# v4 + GEMM phases: one static s_setprio 1 for the lagging wave half (waves 4-7) instead of per-phase priority flips
# speedup vs baseline: 1.0185x; 1.0132x over previous
; __device__ __forceinline__ int opaque_tid(int wv) { int l; asm volatile("v_mbcnt_lo_u32_b32 %0, -1, 0\n\tv_mbcnt_hi_u32_b32 %0, -1, %0" : "=v"(l)); return wv * 64 + l; }
; #define PG8_BAR __builtin_amdgcn_s_barrier()
; template <class Epi>
; __device__ __forceinline__ void gemm_phase(LAS unsigned char* lds, const Gemm g, const StaticOrder& S, const Epi& E, int wv) {
;     const int tid = opaque_tid(wv), wid = __builtin_amdgcn_readfirstlane(tid >> 6), lane = tid & 63, wr = wid >> 2, wc = wid & 3, fr = lane & 15, fq = lane >> 4;
;     const int K = g.K, nt = K / BK;
;     unsigned voffA[2], voffB[2];
; #pragma unroll
;     for (int i = 0; i < 2; ++i) { int R, C; stage_rc(tid * 16 + i * 8192, R, C); const int Rb = Epi::PERM ? ((R & ~31) + perm32(R & 31)) : R;
;         voffA[i] = (unsigned)(R * g.lda + C) * 2u; voffB[i] = (unsigned)(Rb * g.ldb + C) * 2u; }
;     const bool krev = (g.adiag & 2) != 0;
;     const ptrdiff_t kstep = krev ? -(ptrdiff_t)(BK * 2) : (ptrdiff_t)(BK * 2);
;     const size_t kbeg = krev ? (size_t)(nt - 1) * (BK * 2) : 0;
;     const size_t hstepA = (size_t)HALF * g.lda * 2, hstepB = (size_t)HALF * g.ldb * 2;
;     const size_t tstepA = 2 * hstepA, tstepB = 2 * hstepB;
;     const unsigned ldsw = (unsigned)wid * 1024u;
;     const int aoff = lds_byte(wr * 64 + fr, fq * 8), boff = lds_byte(wc * 32 + fr, fq * 8);
;     ...
;     Unit cur, nxt; int ui = 0;
;     if (!S.next(0, cur)) return;
;     f32x4 acc[2][2][4][2];
; #pragma unroll
;     for (int a = 0; a < 2; ++a)
; #pragma unroll
;         for (int b = 0; b < 2; ++b)
; #pragma unroll
;             for (int m = 0; m < 4; ++m)
; #pragma unroll
;                 for (int n = 0; n < 2; ++n) acc[a][b][m][n] = (f32x4){0.f, 0.f, 0.f, 0.f};
;     bf16x8 At[4][2], B0[2][2], B1[2][2];
;     const char* cA = (const char*)g.A + (size_t)cur.pm * tstepA + ((g.adiag & 1) ? (size_t)(cur.pn >> 1) * K * 2 : 0) + kbeg;
;     const char* cB = (const char*)g.Bt + (size_t)cur.pn * tstepB + kbeg;
;     PG8_STAGE(PG8_SB(0, 0), cB, voffB); PG8_STAGE(PG8_SA(0, 0), cA, voffA); PG8_STAGE(PG8_SB(0, 1), cB + hstepB, voffB); PG8_STAGE(PG8_SA(0, 1), cA + hstepA, voffA);
;     if (wr == 1) PG8_BAR;
;     PG8_WAIT_V(4); PG8_BAR;
;     PG8_STAGE(PG8_SB(1, 0), cB + kstep, voffB); PG8_STAGE(PG8_SA(1, 0), cA + kstep, voffA); PG8_STAGE(PG8_SB(1, 1), cB + hstepB + kstep, voffB);
;     PG8_WAIT_V(6); PG8_BAR;
.LBB0_196:
	v_readlane_b32 s6, v255, 14
	v_readlane_b32 s7, v255, 15
	s_and_b64 vcc, exec, s[6:7]
	s_cbranch_vccnz .LBB0_244
	v_ashrrev_i32_e32 v2, 31, v0
	v_lshrrev_b32_e32 v2, 26, v2
	v_lshlrev_b32_e32 v1, 4, v0
	v_add_u32_e32 v2, v0, v2
	v_bfe_i32 v0, v0, 27, 1
	v_lshrrev_b32_e32 v0, 22, v0
	v_add_u32_e32 v0, v1, v0
	v_and_b32_e32 v0, 0xfffffc00, v0
	v_sub_u32_e32 v0, v1, v0
	v_ashrrev_i32_e32 v9, 6, v2
	v_lshrrev_b32_e32 v2, 4, v0
	v_bitop3_b32 v0, v2, v0, 32 bitop3:0x6c
	v_ashrrev_i32_e32 v3, 31, v0
	v_lshrrev_b32_e32 v3, 26, v3
	v_add_u32_e32 v3, v0, v3
	v_lshlrev_b32_e32 v2, 3, v9
	v_ashrrev_i32_e32 v10, 6, v3
	v_and_b32_e32 v3, 0xc0, v3
	v_and_b32_e32 v2, -16, v2
	v_sub_u32_e32 v0, v0, v3
	v_mov_b32_e32 v3, 1
	v_add_u32_e32 v2, v10, v2
	v_ashrrev_i16_sdwa v0, v3, sext(v0) dst_sel:DWORD dst_unused:UNUSED_PAD src0_sel:DWORD src1_sel:BYTE_0
	v_lshlrev_b32_e32 v4, 5, v9
	v_bfe_i32 v11, v0, 0, 16
	v_lshlrev_b32_e32 v0, 1, v2
	v_lshrrev_b32_e32 v5, 2, v2
	v_and_b32_e32 v6, 3, v10
	s_mov_b32 s9, 0xfffe0
	v_and_b32_e32 v4, 32, v4
	v_and_b32_e32 v0, 24, v0
	v_and_b32_e32 v5, 4, v5
	v_and_or_b32 v6, v2, s9, v6
	v_or3_b32 v0, v6, v5, v0
	v_add_lshl_u32 v4, v4, v11, 1
	v_lshl_add_u32 v138, v0, 12, v4
	v_add_u32_e32 v0, 0x2000, v1
	v_ashrrev_i32_e32 v1, 31, v0
	v_lshrrev_b32_e32 v1, 22, v1
	v_add_u32_e32 v1, v0, v1
	v_ashrrev_i32_e32 v12, 10, v1
	v_mul_i32_i24_e32 v1, 0x400, v12
	v_sub_u32_e32 v0, v0, v1
	v_lshrrev_b32_e32 v1, 4, v0
	v_bitop3_b32 v0, v1, v0, 32 bitop3:0x6c
	v_lshl_add_u32 v136, v2, 12, v4
	v_ashrrev_i32_e32 v2, 31, v0
	v_lshrrev_b32_e32 v2, 26, v2
	s_waitcnt lgkmcnt(0)
	s_add_u32 s5, s18, 0x7300000
	v_add_u32_e32 v2, v0, v2
	s_addc_u32 s6, s19, 0
	v_lshlrev_b32_e32 v1, 3, v12
	v_ashrrev_i32_e32 v13, 6, v2
	v_and_b32_e32 v2, 0xc0, v2
	s_add_u32 s7, s56, 0x900000
	v_and_b32_e32 v1, -16, v1
	v_sub_u32_e32 v0, v0, v2
	s_addc_u32 s8, s57, 0
	s_ashr_i32 s15, s4, 6
	v_add_u32_e32 v1, v13, v1
	v_ashrrev_i16_sdwa v0, v3, sext(v0) dst_sel:DWORD dst_unused:UNUSED_PAD src0_sel:DWORD src1_sel:BYTE_0
	v_and_b32_e32 v3, 3, v13
	s_ashr_i32 s21, s20, 31
	s_ashr_i32 s69, s68, 31
	v_and_or_b32 v3, v1, s9, v3
	s_ashr_i32 s18, s4, 8
	s_lshl_b32 s9, s15, 10
	s_lshl_b64 s[12:13], s[20:21], 20
	s_lshl_b64 s[10:11], s[68:69], 20
	s_add_u32 s72, s7, s10
	v_lshlrev_b32_e32 v4, 5, v12
	v_bfe_i32 v14, v0, 0, 16
	v_lshlrev_b32_e32 v0, 1, v1
	v_lshrrev_b32_e32 v2, 2, v1
	s_addc_u32 s73, s8, s11
	s_add_i32 s10, s9, 0
	v_and_b32_e32 v4, 32, v4
	v_and_b32_e32 v0, 24, v0
	v_and_b32_e32 v2, 4, v2
	s_add_i32 m0, s10, 0x10000
	v_or3_b32 v0, v3, v2, v0
	v_add_lshl_u32 v2, v4, v14, 1
	global_load_lds_dwordx4 v138, s[72:73]
	s_add_i32 m0, s10, 0x12000
	v_lshl_add_u32 v142, v0, 12, v2
	s_add_u32 s70, s5, s12
	global_load_lds_dwordx4 v142, s[72:73]
	s_addc_u32 s71, s6, s13
	s_mov_b32 m0, s10
	s_add_i32 s11, s10, 0x2000
	v_lshl_add_u32 v140, v1, 12, v2
	global_load_lds_dwordx4 v136, s[70:71]
	s_mov_b32 m0, s11
	s_add_u32 s12, s72, 0x80000
	global_load_lds_dwordx4 v140, s[70:71]
	s_addc_u32 s13, s73, 0
	s_add_i32 m0, s10, 0x14000
	v_mov_b32_e32 v139, 0
	global_load_lds_dwordx4 v138, s[12:13]
	s_add_i32 m0, s10, 0x16000
	s_add_u32 s22, s70, 0x80000
	global_load_lds_dwordx4 v142, s[12:13]
	s_addc_u32 s23, s71, 0
	s_add_i32 s12, s10, 0x4000
	s_mov_b32 m0, s12
	s_add_i32 s13, s10, 0x6000
	global_load_lds_dwordx4 v136, s[22:23]
	s_mov_b32 m0, s13
	v_mov_b32_e32 v143, v139
	global_load_lds_dwordx4 v140, s[22:23]
	v_mov_b32_e32 v137, v139
	v_mov_b32_e32 v141, v139
	s_mov_b32 s14, 0
	v_lshl_add_u64 v[6:7], s[72:73], 0, v[138:139]
	v_lshl_add_u64 v[4:5], s[72:73], 0, v[142:143]
	v_lshl_add_u64 v[2:3], s[70:71], 0, v[136:137]
	s_cmp_lg_u32 s18, 1
	v_lshl_add_u64 v[0:1], s[70:71], 0, v[140:141]
	s_cbranch_scc1 .LBB0_199
	s_barrier
	s_setprio 1

; #define PG8_STAGE(bufoff, gbase, voff) do { _Pragma("unroll") for (int _i = 0; _i < 2; ++_i) \
;         __builtin_amdgcn_global_load_lds((const unsigned*)((const char*)(gbase) + (voff)[_i]), (LAS unsigned*)(lds + (bufoff) + ldsw + _i * 8192), 16, 0, 0); } while (0)
; #define PG8_LDA(dst, b, h) do { _Pragma("unroll") for (int m = 0; m < 4; ++m) _Pragma("unroll") for (int k = 0; k < 2; ++k) dst[m][k] = *(const LAS bf16x8*)(lds + PG8_SA(b, h) + aoff + m * 2048 + k * 1024); } while (0)
; #define PG8_LDB(dst, b, h) do { _Pragma("unroll") for (int n = 0; n < 2; ++n) _Pragma("unroll") for (int k = 0; k < 2; ++k) dst[n][k] = *(const LAS bf16x8*)(lds + PG8_SB(b, h) + boff + n * 2048 + k * 1024); } while (0)
; #define PG8_MMA(ai, bj, At, Bt) do { __builtin_amdgcn_s_setprio(1); _Pragma("unroll") for (int m = 0; m < 4; ++m) _Pragma("unroll") for (int n = 0; n < 2; ++n) _Pragma("unroll") for (int k = 0; k < 2; ++k) \
;         acc[ai][bj][m][n] = __builtin_amdgcn_mfma_f32_16x16x32_bf16(Bt[n][k], At[m][k], acc[ai][bj][m][n], 0, 0, 0); __builtin_amdgcn_s_setprio(0); } while (0)
; #define PG8_WAIT_V(n) asm volatile("s_waitcnt vmcnt(" #n ")" ::: "memory")
; #define PG8_WAIT_L(n) asm volatile("s_waitcnt lgkmcnt(" #n ")" ::: "memory")
; #define PG8_BAR __builtin_amdgcn_s_barrier()
; template <class Epi>
; __device__ __forceinline__ void gemm_phase(LAS unsigned char* lds, const Gemm g, const StaticOrder& S, const Epi& E, int wv) {
;     ...
;             const bool last = (t == nt - 2);
;             const char* a1 = cA + (ptrdiff_t)(t + 1) * kstep;
;             const char* a2 = last ? nA : cA + (ptrdiff_t)(t + 2) * kstep; const char* b2 = last ? nB : cB + (ptrdiff_t)(t + 2) * kstep;
;             const char* a3 = a2 + kstep; const char* b3 = b2 + kstep;
;             PG8_LDB(B0, 0, 0); PG8_SCHED; PG8_LDA(At, 0, 0); PG8_STAGE(PG8_SA(1, 1), a1 + hstepA, voffA);
;             PG8_WAIT_L(8); PG8_BAR; PG8_WAIT_L(0); PG8_MMA(0, 0, At, B0); PG8_BAR; PG8_SCHED;
;             PG8_LDB(B1, 0, 1); PG8_STAGE(PG8_SB(0, 0), b2, voffB);
;             PG8_BAR; PG8_WAIT_L(0); PG8_MMA(0, 1, At, B1); PG8_BAR;
;             PG8_LDA(At, 0, 1); PG8_STAGE(PG8_SA(0, 0), a2, voffA);
;             PG8_BAR; PG8_WAIT_L(0); PG8_MMA(1, 0, At, B0); PG8_BAR; PG8_SCHED;
;             PG8_STAGE(PG8_SB(0, 1), b2 + hstepB, voffB);
;             PG8_WAIT_V(6); PG8_BAR; PG8_MMA(1, 1, At, B1); PG8_BAR;
.LBB0_208:
	s_add_u32 s39, s70, 0xfff80080
	s_addc_u32 s40, s71, -1
	s_cmp_eq_u32 s38, 28
	s_cselect_b32 s75, s21, s40
	s_cselect_b32 s74, s30, s39
	s_cselect_b32 s73, s31, s35
	s_cselect_b32 s72, s33, s34
	s_add_i32 m0, s10, 0xc000
	ds_read_b128 v[160:163], v191
	ds_read_b128 v[164:167], v191 offset:1024
	ds_read_b128 v[168:171], v191 offset:2048
	ds_read_b128 v[172:175], v191 offset:3072
	ds_read_b128 v[176:179], v191 offset:4096
	ds_read_b128 v[198:201], v191 offset:5120
	ds_read_b128 v[202:205], v191 offset:6144
	ds_read_b128 v[206:209], v191 offset:7168
	global_load_lds_dwordx4 v144, s[70:71]
	s_add_i32 m0, s10, 0xe000
	s_nop 0
	global_load_lds_dwordx4 v146, s[70:71]
	s_waitcnt lgkmcnt(8)
	s_barrier
	s_waitcnt lgkmcnt(0)
	s_waitcnt lgkmcnt(0)
	v_mfma_f32_16x16x32_bf16 v[124:127], v[128:131], v[160:163], v[124:127]
	v_mfma_f32_16x16x32_bf16 v[120:123], v[152:155], v[160:163], v[120:123]
	v_mfma_f32_16x16x32_bf16 v[108:111], v[128:131], v[168:171], v[108:111]
	v_mfma_f32_16x16x32_bf16 v[104:107], v[152:155], v[168:171], v[104:107]
	v_mfma_f32_16x16x32_bf16 v[92:95], v[128:131], v[176:179], v[92:95]
	v_mfma_f32_16x16x32_bf16 v[88:91], v[152:155], v[176:179], v[88:91]
	v_mfma_f32_16x16x32_bf16 v[76:79], v[128:131], v[202:205], v[76:79]
	v_mfma_f32_16x16x32_bf16 v[72:75], v[152:155], v[202:205], v[72:75]
	v_mfma_f32_16x16x32_bf16 v[124:127], v[132:135], v[164:167], v[124:127]
	v_mfma_f32_16x16x32_bf16 v[120:123], v[156:159], v[164:167], v[120:123]
	v_mfma_f32_16x16x32_bf16 v[108:111], v[132:135], v[172:175], v[108:111]
	v_mfma_f32_16x16x32_bf16 v[104:107], v[156:159], v[172:175], v[104:107]
	v_mfma_f32_16x16x32_bf16 v[92:95], v[132:135], v[198:201], v[92:95]
	v_mfma_f32_16x16x32_bf16 v[88:91], v[156:159], v[198:201], v[88:91]
	v_mfma_f32_16x16x32_bf16 v[76:79], v[132:135], v[206:209], v[76:79]
	v_mfma_f32_16x16x32_bf16 v[72:75], v[156:159], v[206:209], v[72:75]
	s_barrier
	s_add_i32 s39, s23, s9
	s_add_u32 s98, s72, s58
	s_addc_u32 s99, s73, s59
	s_mov_b32 m0, s39
	ds_read_b128 v[210:213], v192
	ds_read_b128 v[214:217], v192 offset:1024
	ds_read_b128 v[218:221], v192 offset:2048
	ds_read_b128 v[222:225], v192 offset:3072
	global_load_lds_dwordx4 v138, s[72:73]
	s_add_i32 m0, s39, 0x2000
	s_nop 0
	global_load_lds_dwordx4 v142, s[72:73]
	s_barrier
	s_waitcnt lgkmcnt(0)
	s_waitcnt lgkmcnt(0)
	v_mfma_f32_16x16x32_bf16 v[116:119], v[210:213], v[160:163], v[116:119]
	v_mfma_f32_16x16x32_bf16 v[112:115], v[218:221], v[160:163], v[112:115]
	v_mfma_f32_16x16x32_bf16 v[100:103], v[210:213], v[168:171], v[100:103]
	v_mfma_f32_16x16x32_bf16 v[96:99], v[218:221], v[168:171], v[96:99]
	v_mfma_f32_16x16x32_bf16 v[84:87], v[210:213], v[176:179], v[84:87]
	v_mfma_f32_16x16x32_bf16 v[80:83], v[218:221], v[176:179], v[80:83]
	v_mfma_f32_16x16x32_bf16 v[68:71], v[210:213], v[202:205], v[68:71]
	v_mfma_f32_16x16x32_bf16 v[64:67], v[218:221], v[202:205], v[64:67]
	v_mfma_f32_16x16x32_bf16 v[116:119], v[214:217], v[164:167], v[116:119]
	v_mfma_f32_16x16x32_bf16 v[112:115], v[222:225], v[164:167], v[112:115]
	v_mfma_f32_16x16x32_bf16 v[100:103], v[214:217], v[172:175], v[100:103]
	v_mfma_f32_16x16x32_bf16 v[96:99], v[222:225], v[172:175], v[96:99]
	v_mfma_f32_16x16x32_bf16 v[84:87], v[214:217], v[198:201], v[84:87]
	v_mfma_f32_16x16x32_bf16 v[80:83], v[222:225], v[198:201], v[80:83]
	v_mfma_f32_16x16x32_bf16 v[68:71], v[214:217], v[206:209], v[68:71]
	v_mfma_f32_16x16x32_bf16 v[64:67], v[222:225], v[206:209], v[64:67]
	s_mov_b32 m0, s10
	s_add_u32 s100, s74, s58
	s_addc_u32 s101, s75, s59
	s_barrier
	ds_read_b128 v[160:163], v191 offset:16384
	ds_read_b128 v[164:167], v191 offset:17408
	ds_read_b128 v[168:171], v191 offset:18432
	ds_read_b128 v[172:175], v191 offset:19456
	ds_read_b128 v[176:179], v191 offset:20480
	ds_read_b128 v[198:201], v191 offset:21504
	ds_read_b128 v[202:205], v191 offset:22528
	ds_read_b128 v[206:209], v191 offset:23552
	global_load_lds_dwordx4 v136, s[74:75]
	s_mov_b32 m0, s11
	s_nop 0
	global_load_lds_dwordx4 v140, s[74:75]
	s_waitcnt vmcnt(10)
	s_barrier
	s_waitcnt lgkmcnt(0)
	s_waitcnt lgkmcnt(0)
	v_mfma_f32_16x16x32_bf16 v[60:63], v[128:131], v[160:163], v[60:63]
	v_mfma_f32_16x16x32_bf16 v[56:59], v[152:155], v[160:163], v[56:59]
	v_mfma_f32_16x16x32_bf16 v[44:47], v[128:131], v[168:171], v[44:47]
	v_mfma_f32_16x16x32_bf16 v[40:43], v[152:155], v[168:171], v[40:43]
	v_mfma_f32_16x16x32_bf16 v[28:31], v[128:131], v[176:179], v[28:31]
	v_mfma_f32_16x16x32_bf16 v[24:27], v[152:155], v[176:179], v[24:27]
	v_mfma_f32_16x16x32_bf16 v[12:15], v[128:131], v[202:205], v[12:15]
	v_mfma_f32_16x16x32_bf16 v[8:11], v[152:155], v[202:205], v[8:11]
	v_mfma_f32_16x16x32_bf16 v[60:63], v[132:135], v[164:167], v[60:63]
	v_mfma_f32_16x16x32_bf16 v[56:59], v[156:159], v[164:167], v[56:59]
	v_mfma_f32_16x16x32_bf16 v[44:47], v[132:135], v[172:175], v[44:47]
	v_mfma_f32_16x16x32_bf16 v[40:43], v[156:159], v[172:175], v[40:43]
	v_mfma_f32_16x16x32_bf16 v[28:31], v[132:135], v[198:201], v[28:31]
	v_mfma_f32_16x16x32_bf16 v[24:27], v[156:159], v[198:201], v[24:27]
	v_mfma_f32_16x16x32_bf16 v[12:15], v[132:135], v[206:209], v[12:15]
	v_mfma_f32_16x16x32_bf16 v[8:11], v[156:159], v[206:209], v[8:11]
	s_barrier
	s_add_u32 s40, s72, 0x80000
	s_addc_u32 s41, s73, 0
	s_add_i32 s39, s24, s9
	s_mov_b32 m0, s39
	s_nop 0
	global_load_lds_dwordx4 v138, s[40:41]
	s_add_i32 m0, s39, 0x2000
	s_nop 0
	global_load_lds_dwordx4 v142, s[40:41]
	s_add_i32 s39, 0, 0x18000
	v_add_u32_e32 v156, s39, v184
	ds_read_b128 v[128:131], v156
	ds_read_b128 v[132:135], v156 offset:1024
	ds_read_b128 v[152:155], v156 offset:2048
	ds_read_b128 v[156:159], v156 offset:3072
	s_waitcnt vmcnt(6)
	s_barrier
; #define PG8_STAGE(bufoff, gbase, voff) do { _Pragma("unroll") for (int _i = 0; _i < 2; ++_i) \
;         __builtin_amdgcn_global_load_lds((const unsigned*)((const char*)(gbase) + (voff)[_i]), (LAS unsigned*)(lds + (bufoff) + ldsw + _i * 8192), 16, 0, 0); } while (0)
; #define PG8_LDA(dst, b, h) do { _Pragma("unroll") for (int m = 0; m < 4; ++m) _Pragma("unroll") for (int k = 0; k < 2; ++k) dst[m][k] = *(const LAS bf16x8*)(lds + PG8_SA(b, h) + aoff + m * 2048 + k * 1024); } while (0)
; #define PG8_LDB(dst, b, h) do { _Pragma("unroll") for (int n = 0; n < 2; ++n) _Pragma("unroll") for (int k = 0; k < 2; ++k) dst[n][k] = *(const LAS bf16x8*)(lds + PG8_SB(b, h) + boff + n * 2048 + k * 1024); } while (0)
; #define PG8_MMA(ai, bj, At, Bt) do { __builtin_amdgcn_s_setprio(1); _Pragma("unroll") for (int m = 0; m < 4; ++m) _Pragma("unroll") for (int n = 0; n < 2; ++n) _Pragma("unroll") for (int k = 0; k < 2; ++k) \
;         acc[ai][bj][m][n] = __builtin_amdgcn_mfma_f32_16x16x32_bf16(Bt[n][k], At[m][k], acc[ai][bj][m][n], 0, 0, 0); __builtin_amdgcn_s_setprio(0); } while (0)
; #define PG8_WAIT_V(n) asm volatile("s_waitcnt vmcnt(" #n ")" ::: "memory")
; #define PG8_WAIT_L(n) asm volatile("s_waitcnt lgkmcnt(" #n ")" ::: "memory")
; #define PG8_BAR __builtin_amdgcn_s_barrier()
; #define PG8_SCHED __builtin_amdgcn_sched_barrier(0)
; template <class Epi>
; __device__ __forceinline__ void gemm_phase(LAS unsigned char* lds, const Gemm g, const StaticOrder& S, const Epi& E, int wv) {
;     ...
;             PG8_WAIT_V(6); PG8_BAR; PG8_MMA(1, 1, At, B1); PG8_BAR;
;             PG8_LDB(B0, 1, 0); PG8_SCHED; PG8_LDA(At, 1, 0); PG8_STAGE(PG8_SA(0, 1), a2 + hstepA, voffA);
;             PG8_WAIT_L(8); PG8_BAR; PG8_WAIT_L(0); PG8_MMA(0, 0, At, B0); PG8_BAR; PG8_SCHED;
;             PG8_LDB(B1, 1, 1); PG8_STAGE(PG8_SB(1, 0), b3, voffB);
;             PG8_BAR; PG8_WAIT_L(0); PG8_MMA(0, 1, At, B1); PG8_BAR;
;             PG8_LDA(At, 1, 1); PG8_STAGE(PG8_SA(1, 0), a3, voffA);
;             PG8_BAR; PG8_WAIT_L(0); PG8_MMA(1, 0, At, B0); PG8_BAR; PG8_SCHED;
	v_mfma_f32_16x16x32_bf16 v[52:55], v[210:213], v[160:163], v[52:55]
	v_mfma_f32_16x16x32_bf16 v[48:51], v[218:221], v[160:163], v[48:51]
	v_mfma_f32_16x16x32_bf16 v[36:39], v[210:213], v[168:171], v[36:39]
	v_mfma_f32_16x16x32_bf16 v[32:35], v[218:221], v[168:171], v[32:35]
	v_mfma_f32_16x16x32_bf16 v[20:23], v[210:213], v[176:179], v[20:23]
	v_mfma_f32_16x16x32_bf16 v[16:19], v[218:221], v[176:179], v[16:19]
	v_mfma_f32_16x16x32_bf16 v[4:7], v[210:213], v[202:205], v[4:7]
	v_mfma_f32_16x16x32_bf16 v[0:3], v[218:221], v[202:205], v[0:3]
	v_mfma_f32_16x16x32_bf16 v[52:55], v[214:217], v[164:167], v[52:55]
	v_mfma_f32_16x16x32_bf16 v[48:51], v[222:225], v[164:167], v[48:51]
	v_mfma_f32_16x16x32_bf16 v[36:39], v[214:217], v[172:175], v[36:39]
	v_mfma_f32_16x16x32_bf16 v[32:35], v[222:225], v[172:175], v[32:35]
	v_mfma_f32_16x16x32_bf16 v[20:23], v[214:217], v[198:201], v[20:23]
	v_mfma_f32_16x16x32_bf16 v[16:19], v[222:225], v[198:201], v[16:19]
	v_mfma_f32_16x16x32_bf16 v[4:7], v[214:217], v[206:209], v[4:7]
	v_mfma_f32_16x16x32_bf16 v[0:3], v[222:225], v[206:209], v[0:3]
	s_waitcnt lgkmcnt(0)
	s_barrier
	s_add_u32 s40, s74, 0x80000
	s_addc_u32 s41, s75, 0
	s_mov_b32 m0, s12
	ds_read_b128 v[160:163], v191 offset:32768
	ds_read_b128 v[164:167], v191 offset:33792
	ds_read_b128 v[168:171], v191 offset:34816
	ds_read_b128 v[172:175], v191 offset:35840
	ds_read_b128 v[176:179], v191 offset:36864
	ds_read_b128 v[198:201], v191 offset:37888
	ds_read_b128 v[202:205], v191 offset:38912
	ds_read_b128 v[206:209], v191 offset:39936
	global_load_lds_dwordx4 v136, s[40:41]
	s_mov_b32 m0, s13
	s_nop 0
	global_load_lds_dwordx4 v140, s[40:41]
	s_waitcnt lgkmcnt(8)
	s_barrier
	s_waitcnt lgkmcnt(0)
	s_waitcnt lgkmcnt(0)
	v_mfma_f32_16x16x32_bf16 v[124:127], v[128:131], v[160:163], v[124:127]
	v_mfma_f32_16x16x32_bf16 v[120:123], v[152:155], v[160:163], v[120:123]
	v_mfma_f32_16x16x32_bf16 v[108:111], v[128:131], v[168:171], v[108:111]
	v_mfma_f32_16x16x32_bf16 v[104:107], v[152:155], v[168:171], v[104:107]
	v_mfma_f32_16x16x32_bf16 v[92:95], v[128:131], v[176:179], v[92:95]
	v_mfma_f32_16x16x32_bf16 v[88:91], v[152:155], v[176:179], v[88:91]
	v_mfma_f32_16x16x32_bf16 v[76:79], v[128:131], v[202:205], v[76:79]
	v_mfma_f32_16x16x32_bf16 v[72:75], v[152:155], v[202:205], v[72:75]
	v_mfma_f32_16x16x32_bf16 v[124:127], v[132:135], v[164:167], v[124:127]
	v_mfma_f32_16x16x32_bf16 v[120:123], v[156:159], v[164:167], v[120:123]
	v_mfma_f32_16x16x32_bf16 v[108:111], v[132:135], v[172:175], v[108:111]
	v_mfma_f32_16x16x32_bf16 v[104:107], v[156:159], v[172:175], v[104:107]
	v_mfma_f32_16x16x32_bf16 v[92:95], v[132:135], v[198:201], v[92:95]
	v_mfma_f32_16x16x32_bf16 v[88:91], v[156:159], v[198:201], v[88:91]
	v_mfma_f32_16x16x32_bf16 v[76:79], v[132:135], v[206:209], v[76:79]
	v_mfma_f32_16x16x32_bf16 v[72:75], v[156:159], v[206:209], v[72:75]
	s_barrier
	s_add_i32 s42, 0, 0x1c000
	s_add_i32 s39, s39, s9
	v_add_u32_e32 v197, s42, v184
	s_mov_b32 m0, s39
	ds_read_b128 v[210:213], v197
	ds_read_b128 v[214:217], v197 offset:1024
	ds_read_b128 v[218:221], v197 offset:2048
	ds_read_b128 v[222:225], v197 offset:3072
	global_load_lds_dwordx4 v138, s[98:99]
	s_add_i32 m0, s39, 0x2000
	s_nop 0
	global_load_lds_dwordx4 v142, s[98:99]
	s_barrier
	s_waitcnt lgkmcnt(0)
	s_waitcnt lgkmcnt(0)
	v_mfma_f32_16x16x32_bf16 v[116:119], v[210:213], v[160:163], v[116:119]
	v_mfma_f32_16x16x32_bf16 v[112:115], v[218:221], v[160:163], v[112:115]
	v_mfma_f32_16x16x32_bf16 v[100:103], v[210:213], v[168:171], v[100:103]
	v_mfma_f32_16x16x32_bf16 v[96:99], v[218:221], v[168:171], v[96:99]
	v_mfma_f32_16x16x32_bf16 v[84:87], v[210:213], v[176:179], v[84:87]
	v_mfma_f32_16x16x32_bf16 v[80:83], v[218:221], v[176:179], v[80:83]
	v_mfma_f32_16x16x32_bf16 v[68:71], v[210:213], v[202:205], v[68:71]
	v_mfma_f32_16x16x32_bf16 v[64:67], v[218:221], v[202:205], v[64:67]
	v_mfma_f32_16x16x32_bf16 v[116:119], v[214:217], v[164:167], v[116:119]
	v_mfma_f32_16x16x32_bf16 v[112:115], v[222:225], v[164:167], v[112:115]
	v_mfma_f32_16x16x32_bf16 v[100:103], v[214:217], v[172:175], v[100:103]
	v_mfma_f32_16x16x32_bf16 v[96:99], v[222:225], v[172:175], v[96:99]
	v_mfma_f32_16x16x32_bf16 v[84:87], v[214:217], v[198:201], v[84:87]
	v_mfma_f32_16x16x32_bf16 v[80:83], v[222:225], v[198:201], v[80:83]
	v_mfma_f32_16x16x32_bf16 v[68:71], v[214:217], v[206:209], v[68:71]
	v_mfma_f32_16x16x32_bf16 v[64:67], v[222:225], v[206:209], v[64:67]
	s_mov_b32 m0, s15
	s_barrier
	ds_read_b128 v[160:163], v191 offset:49152
	ds_read_b128 v[164:167], v191 offset:50176
	ds_read_b128 v[168:171], v191 offset:51200
	ds_read_b128 v[172:175], v191 offset:52224
	ds_read_b128 v[176:179], v191 offset:53248
	ds_read_b128 v[198:201], v191 offset:54272
	ds_read_b128 v[202:205], v191 offset:55296
	ds_read_b128 v[206:209], v191 offset:56320
	global_load_lds_dwordx4 v136, s[100:101]
	s_mov_b32 m0, s22
	s_nop 0
	global_load_lds_dwordx4 v140, s[100:101]
	s_waitcnt vmcnt(10)
	s_barrier
; __device__ __forceinline__ float ss_fix(float raw) { return (float)__float_as_uint(raw) * (1.0f / 256.0f); }
; #define PG8_STAGE(bufoff, gbase, voff) do { _Pragma("unroll") for (int _i = 0; _i < 2; ++_i) \
;         __builtin_amdgcn_global_load_lds((const unsigned*)((const char*)(gbase) + (voff)[_i]), (LAS unsigned*)(lds + (bufoff) + ldsw + _i * 8192), 16, 0, 0); } while (0)
; #define PG8_MMA(ai, bj, At, Bt) do { __builtin_amdgcn_s_setprio(1); _Pragma("unroll") for (int m = 0; m < 4; ++m) _Pragma("unroll") for (int n = 0; n < 2; ++n) _Pragma("unroll") for (int k = 0; k < 2; ++k) \
;         acc[ai][bj][m][n] = __builtin_amdgcn_mfma_f32_16x16x32_bf16(Bt[n][k], At[m][k], acc[ai][bj][m][n], 0, 0, 0); __builtin_amdgcn_s_setprio(0); } while (0)
; #define PG8_WAIT_V(n) asm volatile("s_waitcnt vmcnt(" #n ")" ::: "memory")
; template <class Epi>
; __device__ __forceinline__ void gemm_phase(LAS unsigned char* lds, const Gemm g, const StaticOrder& S, const Epi& E, int wv) {
;     ...
;             PG8_STAGE(PG8_SB(1, 1), b3 + hstepB, voffB);
;             PG8_WAIT_V(6); PG8_BAR; PG8_MMA(1, 1, At, B1); PG8_BAR;
;     __device__ __forceinline__ void operator()(const f32x4 (&acc)[2][2][4][2], const Unit& u, int wr, int wc, int fr, int fq) const {
;         const int row0 = u.pm * BM + wr * 64 + fr, col0 = u.pn * BM + wc * 32 + 8 * fq;
;         const bool isq = u.pn < 8;
;         const float* gp = (isq ? gq : gk) + wc * 32 + 8 * fq;
;         const float qs = isq ? 0.08838834764831845f * LOG2E : 1.0f;
;         const f32x4 g0 = *(const f32x4*)gp * qs, g1 = *(const f32x4*)(gp + 4) * qs;
;         float rsv[8];
; #pragma unroll
;         for (int it = 0; it < 8; ++it) rsv[it] = __builtin_amdgcn_rsqf(ss_fix(ss[row0 + (it >> 2) * HALF + (it & 3) * 16]) * (1.0f / DM) + EPS);
; #pragma unroll
;         for (int it = 0; it < 8; ++it) { const int ai = it >> 2, m = it & 3; const float rs = rsv[it];
; #pragma unroll
;             for (int bj = 0; bj < 2; ++bj) { const f32x4 v0 = acc[ai][bj][m][0] * rs, v1 = acc[ai][bj][m][1] * rs;
;                 float sq = (v0[0] * v0[0] + v0[1] * v0[1]) + (v0[2] * v0[2] + v0[3] * v0[3]) + (v1[0] * v1[0] + v1[1] * v1[1]) + (v1[2] * v1[2] + v1[3] * v1[3]);
;                 sq += __shfl_xor(sq, 16); sq += __shfl_xor(sq, 32);
;                 if (fq == 0) P[((ai * HALF + wr * 64 + m * 16 + fr) * 2 + bj) * 4 + wc] = sq; } }
	s_waitcnt lgkmcnt(0)
	s_waitcnt lgkmcnt(0)
	v_mfma_f32_16x16x32_bf16 v[60:63], v[128:131], v[160:163], v[60:63]
	v_mfma_f32_16x16x32_bf16 v[56:59], v[152:155], v[160:163], v[56:59]
	v_mfma_f32_16x16x32_bf16 v[44:47], v[128:131], v[168:171], v[44:47]
	v_mfma_f32_16x16x32_bf16 v[40:43], v[152:155], v[168:171], v[40:43]
	v_mfma_f32_16x16x32_bf16 v[28:31], v[128:131], v[176:179], v[28:31]
	v_mfma_f32_16x16x32_bf16 v[24:27], v[152:155], v[176:179], v[24:27]
	v_mfma_f32_16x16x32_bf16 v[12:15], v[128:131], v[202:205], v[12:15]
	v_mfma_f32_16x16x32_bf16 v[8:11], v[152:155], v[202:205], v[8:11]
	v_mfma_f32_16x16x32_bf16 v[60:63], v[132:135], v[164:167], v[60:63]
	v_mfma_f32_16x16x32_bf16 v[56:59], v[156:159], v[164:167], v[56:59]
	v_mfma_f32_16x16x32_bf16 v[44:47], v[132:135], v[172:175], v[44:47]
	v_mfma_f32_16x16x32_bf16 v[40:43], v[156:159], v[172:175], v[40:43]
	v_mfma_f32_16x16x32_bf16 v[28:31], v[132:135], v[198:201], v[28:31]
	v_mfma_f32_16x16x32_bf16 v[24:27], v[156:159], v[198:201], v[24:27]
	v_mfma_f32_16x16x32_bf16 v[12:15], v[132:135], v[206:209], v[12:15]
	v_mfma_f32_16x16x32_bf16 v[8:11], v[156:159], v[206:209], v[8:11]
	s_barrier
	s_add_u32 s40, s72, 0x80080
	s_addc_u32 s41, s73, 0
	s_add_i32 s39, s42, s9
	s_mov_b32 m0, s39
	s_nop 0
	global_load_lds_dwordx4 v138, s[40:41]
	s_add_i32 m0, s39, 0x2000
	s_nop 0
	global_load_lds_dwordx4 v142, s[40:41]
	ds_read_b128 v[128:131], v190
	ds_read_b128 v[132:135], v190 offset:1024
	ds_read_b128 v[152:155], v190 offset:2048
	ds_read_b128 v[156:159], v190 offset:3072
	s_waitcnt vmcnt(6)
	s_barrier
	v_mfma_f32_16x16x32_bf16 v[52:55], v[210:213], v[160:163], v[52:55]
	v_mfma_f32_16x16x32_bf16 v[48:51], v[218:221], v[160:163], v[48:51]
	v_mfma_f32_16x16x32_bf16 v[36:39], v[210:213], v[168:171], v[36:39]
	v_mfma_f32_16x16x32_bf16 v[32:35], v[218:221], v[168:171], v[32:35]
	v_mfma_f32_16x16x32_bf16 v[20:23], v[210:213], v[176:179], v[20:23]
	v_mfma_f32_16x16x32_bf16 v[16:19], v[218:221], v[176:179], v[16:19]
	v_mfma_f32_16x16x32_bf16 v[4:7], v[210:213], v[202:205], v[4:7]
	v_mfma_f32_16x16x32_bf16 v[0:3], v[218:221], v[202:205], v[0:3]
	v_mfma_f32_16x16x32_bf16 v[52:55], v[214:217], v[164:167], v[52:55]
	v_mfma_f32_16x16x32_bf16 v[48:51], v[222:225], v[164:167], v[48:51]
	v_mfma_f32_16x16x32_bf16 v[36:39], v[214:217], v[172:175], v[36:39]
	v_mfma_f32_16x16x32_bf16 v[32:35], v[222:225], v[172:175], v[32:35]
	v_mfma_f32_16x16x32_bf16 v[20:23], v[214:217], v[198:201], v[20:23]
	v_mfma_f32_16x16x32_bf16 v[16:19], v[222:225], v[198:201], v[16:19]
	v_mfma_f32_16x16x32_bf16 v[4:7], v[214:217], v[206:209], v[4:7]
	v_mfma_f32_16x16x32_bf16 v[0:3], v[222:225], v[206:209], v[0:3]
	s_waitcnt lgkmcnt(0)
	s_add_i32 s38, s38, 2
	s_add_u32 s70, s70, 0x100
	s_addc_u32 s71, s71, 0
	s_add_u32 s34, s34, 0x100
	s_addc_u32 s35, s35, 0
	s_cmp_gt_u32 s38, 29
	s_barrier
	s_cbranch_scc0 .LBB0_208
	v_lshl_add_u32 v168, s20, 8, v183
	v_ashrrev_i32_e32 v169, 31, v168
	v_lshl_add_u64 v[128:129], v[168:169], 2, s[50:51]
	global_load_dword v159, v[128:129], off
	s_cmp_lt_i32 s68, 8
	s_cselect_b64 vcc, -1, 0
	global_load_dword v158, v[128:129], off offset:64
	global_load_dword v157, v[128:129], off offset:128
	global_load_dword v156, v[128:129], off offset:192
	global_load_dword v155, v[128:129], off offset:512
	global_load_dword v154, v[128:129], off offset:576
	global_load_dword v153, v[128:129], off offset:640
	global_load_dword v152, v[128:129], off offset:704
	s_and_b64 s[20:21], vcc, exec
	s_cselect_b32 s20, s52, s54
	s_cselect_b32 s21, s53, s55
	s_add_u32 s20, s20, s25
	s_addc_u32 s21, s21, 0
	global_load_dwordx4 v[128:131], v193, s[20:21] offset:16
	global_load_dwordx4 v[132:135], v193, s[20:21]
	v_and_b32_e32 v161, 64, v195
	v_xor_b32_e32 v160, 16, v195
	v_add_u32_e32 v167, 64, v161
	v_cmp_lt_i32_e64 s[20:21], v160, v167
	s_waitcnt vmcnt(0)
	v_cvt_f32_u32_e32 v159, v159
	v_mul_f32_e32 v159, 0x3b800000, v159
	v_fmamk_f32 v159, v159, 0x3a000000, v194
	v_rsq_f32_e32 v166, v159
	v_cndmask_b32_e64 v159, v195, v160, s[20:21]
	v_lshlrev_b32_e32 v170, 2, v159
	v_pk_mul_f32 v[160:161], v[126:127], v[166:167] op_sel_hi:[1,0]
	v_pk_mul_f32 v[162:163], v[124:125], v[166:167] op_sel_hi:[1,0]
	v_pk_mul_f32 v[172:173], v[120:121], v[166:167] op_sel_hi:[1,0]
	v_mul_f32_e32 v159, v163, v163
	v_mul_f32_e32 v161, v161, v161
	v_pk_mul_f32 v[164:165], v[122:123], v[166:167] op_sel_hi:[1,0]
	v_mul_f32_e32 v163, v173, v173
	v_fmac_f32_e32 v159, v162, v162
	v_fmac_f32_e32 v161, v160, v160
	v_mul_f32_e32 v165, v165, v165
	v_fmac_f32_e32 v163, v172, v172
	v_add_f32_e32 v159, v159, v161
	v_add_f32_e32 v159, v163, v159
	v_fmac_f32_e32 v165, v164, v164
	v_add_f32_e32 v159, v165, v159
	ds_bpermute_b32 v160, v170, v159
	v_xor_b32_e32 v161, 32, v195
	v_cmp_lt_i32_e64 s[20:21], v161, v167
	s_waitcnt lgkmcnt(0)
	v_add_f32_e32 v159, v159, v160
	v_cndmask_b32_e64 v161, v195, v161, s[20:21]
	v_lshlrev_b32_e32 v171, 2, v161
	ds_bpermute_b32 v160, v171, v159
	s_and_saveexec_b64 s[20:21], s[16:17]
	s_cbranch_execz .LBB0_211
	s_waitcnt lgkmcnt(0)
	v_add_f32_e32 v159, v159, v160
	ds_write_b32 v186, v159

; #define PG8_WAIT_V(n) asm volatile("s_waitcnt vmcnt(" #n ")" ::: "memory")
; #define PG8_BAR __builtin_amdgcn_s_barrier()
; template <class Epi>
; __device__ __forceinline__ void gemm_phase(LAS unsigned char* lds, const Gemm g, const StaticOrder& S, const Epi& E, int wv) {
;     ...
;     PG8_WAIT_V(0);
;     if (wr == 0) PG8_BAR;
;     PG8_BAR;
.LBB0_243:
	s_barrier
	s_setprio 0

; __device__ __forceinline__ int opaque_tid(int wv) { int l; asm volatile("v_mbcnt_lo_u32_b32 %0, -1, 0\n\tv_mbcnt_hi_u32_b32 %0, -1, %0" : "=v"(l)); return wv * 64 + l; }
; #define PG8_BAR __builtin_amdgcn_s_barrier()
; template <class Epi>
; __device__ __forceinline__ void gemm_phase(LAS unsigned char* lds, const Gemm g, const StaticOrder& S, const Epi& E, int wv) {
;     const int tid = opaque_tid(wv), wid = __builtin_amdgcn_readfirstlane(tid >> 6), lane = tid & 63, wr = wid >> 2, wc = wid & 3, fr = lane & 15, fq = lane >> 4;
;     const int K = g.K, nt = K / BK;
;     unsigned voffA[2], voffB[2];
; #pragma unroll
;     for (int i = 0; i < 2; ++i) { int R, C; stage_rc(tid * 16 + i * 8192, R, C); const int Rb = Epi::PERM ? ((R & ~31) + perm32(R & 31)) : R;
;         voffA[i] = (unsigned)(R * g.lda + C) * 2u; voffB[i] = (unsigned)(Rb * g.ldb + C) * 2u; }
;     const bool krev = (g.adiag & 2) != 0;
;     const ptrdiff_t kstep = krev ? -(ptrdiff_t)(BK * 2) : (ptrdiff_t)(BK * 2);
;     const size_t kbeg = krev ? (size_t)(nt - 1) * (BK * 2) : 0;
;     const size_t hstepA = (size_t)HALF * g.lda * 2, hstepB = (size_t)HALF * g.ldb * 2;
;     const size_t tstepA = 2 * hstepA, tstepB = 2 * hstepB;
;     const unsigned ldsw = (unsigned)wid * 1024u;
;     const int aoff = lds_byte(wr * 64 + fr, fq * 8), boff = lds_byte(wc * 32 + fr, fq * 8);
;     ...
;     Unit cur, nxt; int ui = 0;
;     if (!S.next(0, cur)) return;
;     f32x4 acc[2][2][4][2];
; #pragma unroll
;     for (int a = 0; a < 2; ++a)
; #pragma unroll
;         for (int b = 0; b < 2; ++b)
; #pragma unroll
;             for (int m = 0; m < 4; ++m)
; #pragma unroll
;                 for (int n = 0; n < 2; ++n) acc[a][b][m][n] = (f32x4){0.f, 0.f, 0.f, 0.f};
;     bf16x8 At[4][2], B0[2][2], B1[2][2];
;     const char* cA = (const char*)g.A + (size_t)cur.pm * tstepA + ((g.adiag & 1) ? (size_t)(cur.pn >> 1) * K * 2 : 0) + kbeg;
;     const char* cB = (const char*)g.Bt + (size_t)cur.pn * tstepB + kbeg;
;     PG8_STAGE(PG8_SB(0, 0), cB, voffB); PG8_STAGE(PG8_SA(0, 0), cA, voffA); PG8_STAGE(PG8_SB(0, 1), cB + hstepB, voffB); PG8_STAGE(PG8_SA(0, 1), cA + hstepA, voffA);
;     if (wr == 1) PG8_BAR;
;     PG8_WAIT_V(4); PG8_BAR;
;     PG8_STAGE(PG8_SB(1, 0), cB + kstep, voffB); PG8_STAGE(PG8_SA(1, 0), cA + kstep, voffA); PG8_STAGE(PG8_SB(1, 1), cB + hstepB + kstep, voffB);
;     PG8_WAIT_V(6); PG8_BAR;
.LBB0_249:
	v_ashrrev_i32_e32 v2, 31, v0
	v_lshrrev_b32_e32 v2, 26, v2
	v_lshlrev_b32_e32 v1, 4, v0
	v_add_u32_e32 v2, v0, v2
	v_bfe_i32 v0, v0, 27, 1
	v_lshrrev_b32_e32 v0, 22, v0
	v_add_u32_e32 v0, v1, v0
	v_and_b32_e32 v0, 0xfffffc00, v0
	v_sub_u32_e32 v0, v1, v0
	v_ashrrev_i32_e32 v9, 6, v2
	v_lshrrev_b32_e32 v2, 4, v0
	v_bitop3_b32 v0, v2, v0, 32 bitop3:0x6c
	v_ashrrev_i32_e32 v3, 31, v0
	v_lshrrev_b32_e32 v3, 26, v3
	v_add_u32_e32 v3, v0, v3
	v_lshlrev_b32_e32 v2, 3, v9
	v_ashrrev_i32_e32 v10, 6, v3
	v_and_b32_e32 v3, 0xc0, v3
	v_and_b32_e32 v2, -16, v2
	v_sub_u32_e32 v0, v0, v3
	v_mov_b32_e32 v3, 1
	v_add_u32_e32 v2, v10, v2
	v_ashrrev_i16_sdwa v0, v3, sext(v0) dst_sel:DWORD dst_unused:UNUSED_PAD src0_sel:DWORD src1_sel:BYTE_0
	s_ashr_i32 s11, s5, 3
	v_lshlrev_b32_e32 v4, 5, v9
	v_bfe_i32 v11, v0, 0, 16
	v_lshlrev_b32_e32 v0, 1, v2
	v_lshrrev_b32_e32 v5, 2, v2
	v_and_b32_e32 v6, 3, v10
	s_mov_b32 s9, 0xfffe0
	s_waitcnt lgkmcnt(0)
	s_add_u32 s5, s50, 0x1900000
	v_and_b32_e32 v4, 32, v4
	v_and_b32_e32 v0, 24, v0
	v_and_b32_e32 v5, 4, v5
	v_and_or_b32 v6, v2, s9, v6
	s_addc_u32 s6, s51, 0
	v_or3_b32 v0, v6, v5, v0
	v_add_lshl_u32 v4, v4, v11, 1
	s_add_u32 s7, s20, 0x7300000
	v_lshl_add_u32 v130, v0, 12, v4
	v_add_u32_e32 v0, 0x2000, v1
	s_addc_u32 s8, s21, 0
	v_ashrrev_i32_e32 v1, 31, v0
	s_add_i32 s10, s10, s11
	v_lshrrev_b32_e32 v1, 22, v1
	s_ashr_i32 s11, s10, 31
	v_add_u32_e32 v1, v0, v1
	s_lshr_b32 s11, s11, 23
	v_ashrrev_i32_e32 v12, 10, v1
	s_add_i32 s11, s10, s11
	v_mul_i32_i24_e32 v1, 0x400, v12
	s_ashr_i32 s12, s11, 9
	s_and_b32 s11, s11, 0xfffffe00
	v_sub_u32_e32 v0, v0, v1
	s_sub_i32 s10, s10, s11
	v_lshrrev_b32_e32 v1, 4, v0
	s_sext_i32_i16 s11, s10
	v_bitop3_b32 v0, v1, v0, 32 bitop3:0x6c
	s_bfe_u32 s11, s11, 0x3001c
	v_lshl_add_u32 v128, v2, 12, v4
	v_ashrrev_i32_e32 v2, 31, v0
	s_add_i32 s11, s10, s11
	v_lshrrev_b32_e32 v2, 26, v2
	s_sext_i32_i16 s13, s11
	s_and_b32 s11, s11, 0xfff8
	v_add_u32_e32 v2, v0, v2
	s_sub_i32 s10, s10, s11
	v_lshlrev_b32_e32 v1, 3, v12
	v_ashrrev_i32_e32 v13, 6, v2
	v_and_b32_e32 v2, 0xc0, v2
	s_lshl_b32 s12, s12, 3
	s_sext_i32_i16 s10, s10
	v_and_b32_e32 v1, -16, v1
	v_sub_u32_e32 v0, v0, v2
	s_lshr_b32 s50, s13, 3
	s_add_i32 s64, s12, s10
	v_add_u32_e32 v1, v13, v1
	v_ashrrev_i16_sdwa v0, v3, sext(v0) dst_sel:DWORD dst_unused:UNUSED_PAD src0_sel:DWORD src1_sel:BYTE_0
	v_and_b32_e32 v3, 3, v13
	s_ashr_i32 s15, s4, 6
	s_ashr_i32 s65, s64, 31
	s_bfe_i64 s[10:11], s[50:51], 0x100000
	s_ashr_i32 s23, s4, 8
	v_and_or_b32 v3, v1, s9, v3
	s_lshl_b32 s9, s15, 10
	s_lshl_b64 s[12:13], s[64:65], 20
	s_lshl_b64 s[10:11], s[10:11], 20
	s_add_u32 s68, s7, s10
	v_lshlrev_b32_e32 v4, 5, v12
	v_bfe_i32 v14, v0, 0, 16
	v_lshlrev_b32_e32 v0, 1, v1
	v_lshrrev_b32_e32 v2, 2, v1
	s_addc_u32 s69, s8, s11
	s_add_i32 s10, s9, 0
	v_and_b32_e32 v4, 32, v4
	v_and_b32_e32 v0, 24, v0
	v_and_b32_e32 v2, 4, v2
	s_add_i32 m0, s10, 0x10000
	v_or3_b32 v0, v3, v2, v0
	v_add_lshl_u32 v2, v4, v14, 1
	global_load_lds_dwordx4 v130, s[68:69]
	s_add_i32 m0, s10, 0x12000
	v_lshl_add_u32 v134, v0, 12, v2
	s_add_u32 s66, s5, s12
	global_load_lds_dwordx4 v134, s[68:69]
	s_addc_u32 s67, s6, s13
	s_mov_b32 m0, s10
	s_add_i32 s11, s10, 0x2000
	v_lshl_add_u32 v132, v1, 12, v2
	global_load_lds_dwordx4 v128, s[66:67]
	s_mov_b32 m0, s11
	s_add_u32 s12, s68, 0x80000
	global_load_lds_dwordx4 v132, s[66:67]
	s_addc_u32 s13, s69, 0
	s_add_i32 m0, s10, 0x14000
	v_mov_b32_e32 v131, 0
	global_load_lds_dwordx4 v130, s[12:13]
	s_add_i32 m0, s10, 0x16000
	s_add_u32 s20, s66, 0x80000
	global_load_lds_dwordx4 v134, s[12:13]
	s_addc_u32 s21, s67, 0
	s_add_i32 s12, s10, 0x4000
	s_mov_b32 m0, s12
	s_add_i32 s13, s10, 0x6000
	global_load_lds_dwordx4 v128, s[20:21]
	s_mov_b32 m0, s13
	v_mov_b32_e32 v135, v131
	global_load_lds_dwordx4 v132, s[20:21]
	v_mov_b32_e32 v129, v131
	v_mov_b32_e32 v133, v131
	s_mov_b32 s14, 0
	v_lshl_add_u64 v[6:7], s[68:69], 0, v[130:131]
	v_lshl_add_u64 v[4:5], s[68:69], 0, v[134:135]
	v_lshl_add_u64 v[2:3], s[66:67], 0, v[128:129]
	s_cmp_lg_u32 s23, 1
	v_lshl_add_u64 v[0:1], s[66:67], 0, v[132:133]
	s_cbranch_scc1 .LBB0_251
	s_barrier
	s_setprio 1

; #define PG8_STAGE(bufoff, gbase, voff) do { _Pragma("unroll") for (int _i = 0; _i < 2; ++_i) \
;         __builtin_amdgcn_global_load_lds((const unsigned*)((const char*)(gbase) + (voff)[_i]), (LAS unsigned*)(lds + (bufoff) + ldsw + _i * 8192), 16, 0, 0); } while (0)
; #define PG8_BAR __builtin_amdgcn_s_barrier()
; template <class Epi>
; __device__ __forceinline__ void gemm_phase(LAS unsigned char* lds, const Gemm g, const StaticOrder& S, const Epi& E, int wv) {
;     ...
;         const bool has_next = S.next(ui + 1, nxt);
;         const char* nA = has_next ? (const char*)g.A + (size_t)nxt.pm * tstepA + ((g.adiag & 1) ? (size_t)(nxt.pn >> 1) * K * 2 : 0) + kbeg : cA;
;         const char* nB = has_next ? (const char*)g.Bt + (size_t)nxt.pn * tstepB + kbeg : cB;
;         for (int t = 0; t < nt; t += 2) {
;             const bool last = (t == nt - 2);
;             const char* a1 = cA + (ptrdiff_t)(t + 1) * kstep;
;             const char* a2 = last ? nA : cA + (ptrdiff_t)(t + 2) * kstep; const char* b2 = last ? nB : cB + (ptrdiff_t)(t + 2) * kstep;
;             const char* a3 = a2 + kstep; const char* b3 = b2 + kstep;
;             PG8_LDB(B0, 0, 0); PG8_SCHED; PG8_LDA(At, 0, 0); PG8_STAGE(PG8_SA(1, 1), a1 + hstepA, voffA);
;             PG8_WAIT_L(8); PG8_BAR; PG8_WAIT_L(0); PG8_MMA(0, 0, At, B0); PG8_BAR; PG8_SCHED;
;             PG8_LDB(B1, 0, 1); PG8_STAGE(PG8_SB(0, 0), b2, voffB);
;             PG8_BAR; PG8_WAIT_L(0); PG8_MMA(0, 1, At, B1); PG8_BAR;
;             PG8_LDA(At, 0, 1); PG8_STAGE(PG8_SA(0, 0), a2, voffA);
;             PG8_BAR; PG8_WAIT_L(0); PG8_MMA(1, 0, At, B0); PG8_BAR; PG8_SCHED;
;             PG8_STAGE(PG8_SB(0, 1), b2 + hstepB, voffB);
;             PG8_WAIT_V(6); PG8_BAR; PG8_MMA(1, 1, At, B1); PG8_BAR;
;             PG8_LDB(B0, 1, 0); PG8_SCHED; PG8_LDA(At, 1, 0); PG8_STAGE(PG8_SA(0, 1), a2 + hstepA, voffA);
;             PG8_WAIT_L(8); PG8_BAR; PG8_WAIT_L(0); PG8_MMA(0, 0, At, B0); PG8_BAR; PG8_SCHED;
;             PG8_LDB(B1, 1, 1); PG8_STAGE(PG8_SB(1, 0), b3, voffB);
;             PG8_BAR; PG8_WAIT_L(0); PG8_MMA(0, 1, At, B1); PG8_BAR;
;             PG8_LDA(At, 1, 1); PG8_STAGE(PG8_SA(1, 0), a3, voffA);
;             PG8_BAR; PG8_WAIT_L(0); PG8_MMA(1, 0, At, B0); PG8_BAR; PG8_SCHED;
;             PG8_STAGE(PG8_SB(1, 1), b3 + hstepB, voffB);
;             PG8_WAIT_V(6); PG8_BAR; PG8_MMA(1, 1, At, B1); PG8_BAR;
.LBB0_259:
	s_add_u32 s43, s66, 0xfff80080
	s_addc_u32 s44, s67, -1
	s_cmp_eq_u32 s42, 28
	s_cselect_b32 s71, s34, s44
	s_cselect_b32 s70, s35, s43
	s_cselect_b32 s69, s38, s41
	s_cselect_b32 s68, s39, s40
	s_add_i32 m0, s10, 0xc000
	ds_read_b128 v[172:175], v168
	ds_read_b128 v[176:179], v168 offset:1024
	ds_read_b128 v[184:187], v168 offset:2048
	ds_read_b128 v[188:191], v168 offset:3072
	ds_read_b128 v[192:195], v168 offset:4096
	ds_read_b128 v[196:199], v168 offset:5120
	ds_read_b128 v[200:203], v168 offset:6144
	ds_read_b128 v[204:207], v168 offset:7168
	global_load_lds_dwordx4 v138, s[66:67]
	s_add_i32 m0, s10, 0xe000
	s_nop 0
	global_load_lds_dwordx4 v140, s[66:67]
	s_waitcnt lgkmcnt(8)
	s_barrier
	s_waitcnt lgkmcnt(0)
	s_waitcnt lgkmcnt(0)
	v_mfma_f32_16x16x32_bf16 v[124:127], v[146:149], v[172:175], v[124:127]
	v_mfma_f32_16x16x32_bf16 v[120:123], v[154:157], v[172:175], v[120:123]
	v_mfma_f32_16x16x32_bf16 v[112:115], v[146:149], v[184:187], v[112:115]
	v_mfma_f32_16x16x32_bf16 v[104:107], v[154:157], v[184:187], v[104:107]
	v_mfma_f32_16x16x32_bf16 v[96:99], v[146:149], v[192:195], v[96:99]
	v_mfma_f32_16x16x32_bf16 v[88:91], v[154:157], v[192:195], v[88:91]
	v_mfma_f32_16x16x32_bf16 v[80:83], v[146:149], v[200:203], v[80:83]
	v_mfma_f32_16x16x32_bf16 v[72:75], v[154:157], v[200:203], v[72:75]
	v_mfma_f32_16x16x32_bf16 v[124:127], v[150:153], v[176:179], v[124:127]
	v_mfma_f32_16x16x32_bf16 v[120:123], v[158:161], v[176:179], v[120:123]
	v_mfma_f32_16x16x32_bf16 v[112:115], v[150:153], v[188:191], v[112:115]
	v_mfma_f32_16x16x32_bf16 v[104:107], v[158:161], v[188:191], v[104:107]
	v_mfma_f32_16x16x32_bf16 v[96:99], v[150:153], v[196:199], v[96:99]
	v_mfma_f32_16x16x32_bf16 v[88:91], v[158:161], v[196:199], v[88:91]
	v_mfma_f32_16x16x32_bf16 v[80:83], v[150:153], v[204:207], v[80:83]
	v_mfma_f32_16x16x32_bf16 v[72:75], v[158:161], v[204:207], v[72:75]
	s_barrier
	s_add_i32 s43, s23, s9
	s_add_u32 s98, s68, s20
	s_addc_u32 s99, s69, s21
	s_mov_b32 m0, s43
	ds_read_b128 v[208:211], v169
	ds_read_b128 v[212:215], v169 offset:1024
	ds_read_b128 v[216:219], v169 offset:2048
	ds_read_b128 v[220:223], v169 offset:3072
	global_load_lds_dwordx4 v130, s[68:69]
	s_add_i32 m0, s43, 0x2000
	s_nop 0
	global_load_lds_dwordx4 v134, s[68:69]
	s_barrier
	s_waitcnt lgkmcnt(0)
	s_waitcnt lgkmcnt(0)
	v_mfma_f32_16x16x32_bf16 v[116:119], v[208:211], v[172:175], v[116:119]
	v_mfma_f32_16x16x32_bf16 v[108:111], v[216:219], v[172:175], v[108:111]
	v_mfma_f32_16x16x32_bf16 v[100:103], v[208:211], v[184:187], v[100:103]
	v_mfma_f32_16x16x32_bf16 v[92:95], v[216:219], v[184:187], v[92:95]
	v_mfma_f32_16x16x32_bf16 v[84:87], v[208:211], v[192:195], v[84:87]
	v_mfma_f32_16x16x32_bf16 v[76:79], v[216:219], v[192:195], v[76:79]
	v_mfma_f32_16x16x32_bf16 v[68:71], v[208:211], v[200:203], v[68:71]
	v_mfma_f32_16x16x32_bf16 v[64:67], v[216:219], v[200:203], v[64:67]
	v_mfma_f32_16x16x32_bf16 v[116:119], v[212:215], v[176:179], v[116:119]
	v_mfma_f32_16x16x32_bf16 v[108:111], v[220:223], v[176:179], v[108:111]
	v_mfma_f32_16x16x32_bf16 v[100:103], v[212:215], v[188:191], v[100:103]
	v_mfma_f32_16x16x32_bf16 v[92:95], v[220:223], v[188:191], v[92:95]
	v_mfma_f32_16x16x32_bf16 v[84:87], v[212:215], v[196:199], v[84:87]
	v_mfma_f32_16x16x32_bf16 v[76:79], v[220:223], v[196:199], v[76:79]
	v_mfma_f32_16x16x32_bf16 v[68:71], v[212:215], v[204:207], v[68:71]
	v_mfma_f32_16x16x32_bf16 v[64:67], v[220:223], v[204:207], v[64:67]
	s_mov_b32 m0, s10
	s_add_u32 s100, s70, s20
	s_addc_u32 s101, s71, s21
	s_barrier
	ds_read_b128 v[172:175], v168 offset:16384
	ds_read_b128 v[176:179], v168 offset:17408
	ds_read_b128 v[184:187], v168 offset:18432
	ds_read_b128 v[188:191], v168 offset:19456
	ds_read_b128 v[192:195], v168 offset:20480
	ds_read_b128 v[196:199], v168 offset:21504
	ds_read_b128 v[200:203], v168 offset:22528
	ds_read_b128 v[204:207], v168 offset:23552
	global_load_lds_dwordx4 v128, s[70:71]
	s_mov_b32 m0, s11
	s_nop 0
	global_load_lds_dwordx4 v132, s[70:71]
	s_waitcnt vmcnt(10)
	s_barrier
	s_waitcnt lgkmcnt(0)
	s_waitcnt lgkmcnt(0)
	v_mfma_f32_16x16x32_bf16 v[60:63], v[146:149], v[172:175], v[60:63]
	v_mfma_f32_16x16x32_bf16 v[56:59], v[154:157], v[172:175], v[56:59]
	v_mfma_f32_16x16x32_bf16 v[52:55], v[146:149], v[184:187], v[52:55]
	v_mfma_f32_16x16x32_bf16 v[44:47], v[154:157], v[184:187], v[44:47]
	v_mfma_f32_16x16x32_bf16 v[36:39], v[146:149], v[192:195], v[36:39]
	v_mfma_f32_16x16x32_bf16 v[28:31], v[154:157], v[192:195], v[28:31]
	v_mfma_f32_16x16x32_bf16 v[20:23], v[146:149], v[200:203], v[20:23]
	v_mfma_f32_16x16x32_bf16 v[12:15], v[154:157], v[200:203], v[12:15]
	v_mfma_f32_16x16x32_bf16 v[60:63], v[150:153], v[176:179], v[60:63]
	v_mfma_f32_16x16x32_bf16 v[56:59], v[158:161], v[176:179], v[56:59]
	v_mfma_f32_16x16x32_bf16 v[52:55], v[150:153], v[188:191], v[52:55]
	v_mfma_f32_16x16x32_bf16 v[44:47], v[158:161], v[188:191], v[44:47]
	v_mfma_f32_16x16x32_bf16 v[36:39], v[150:153], v[196:199], v[36:39]
	v_mfma_f32_16x16x32_bf16 v[28:31], v[158:161], v[196:199], v[28:31]
	v_mfma_f32_16x16x32_bf16 v[20:23], v[150:153], v[204:207], v[20:23]
	v_mfma_f32_16x16x32_bf16 v[12:15], v[158:161], v[204:207], v[12:15]
	s_barrier
	s_add_u32 s44, s68, 0x80000
	s_addc_u32 s45, s69, 0
	s_add_i32 s43, s24, s9
	s_mov_b32 m0, s43
	s_nop 0
	global_load_lds_dwordx4 v130, s[44:45]
	s_add_i32 m0, s43, 0x2000
	s_nop 0
	global_load_lds_dwordx4 v134, s[44:45]
	s_add_i32 s43, 0, 0x18000
	v_add_u32_e32 v158, s43, v165
	ds_read_b128 v[146:149], v158
	ds_read_b128 v[150:153], v158 offset:1024
	ds_read_b128 v[154:157], v158 offset:2048
	ds_read_b128 v[158:161], v158 offset:3072
	s_waitcnt vmcnt(6)
	s_barrier
; #define PG8_STAGE(bufoff, gbase, voff) do { _Pragma("unroll") for (int _i = 0; _i < 2; ++_i) \
;         __builtin_amdgcn_global_load_lds((const unsigned*)((const char*)(gbase) + (voff)[_i]), (LAS unsigned*)(lds + (bufoff) + ldsw + _i * 8192), 16, 0, 0); } while (0)
; #define PG8_LDA(dst, b, h) do { _Pragma("unroll") for (int m = 0; m < 4; ++m) _Pragma("unroll") for (int k = 0; k < 2; ++k) dst[m][k] = *(const LAS bf16x8*)(lds + PG8_SA(b, h) + aoff + m * 2048 + k * 1024); } while (0)
; #define PG8_WAIT_V(n) asm volatile("s_waitcnt vmcnt(" #n ")" ::: "memory")
; #define PG8_BAR __builtin_amdgcn_s_barrier()
; template <class Epi>
; __device__ __forceinline__ void gemm_phase(LAS unsigned char* lds, const Gemm g, const StaticOrder& S, const Epi& E, int wv) {
;     ...
;         for (int t = 0; t < nt; t += 2) {
;             const bool last = (t == nt - 2);
;             const char* a1 = cA + (ptrdiff_t)(t + 1) * kstep;
;             const char* a2 = last ? nA : cA + (ptrdiff_t)(t + 2) * kstep; const char* b2 = last ? nB : cB + (ptrdiff_t)(t + 2) * kstep;
;             const char* a3 = a2 + kstep; const char* b3 = b2 + kstep;
;             PG8_LDB(B0, 0, 0); PG8_SCHED; PG8_LDA(At, 0, 0); PG8_STAGE(PG8_SA(1, 1), a1 + hstepA, voffA);
;             PG8_WAIT_L(8); PG8_BAR; PG8_WAIT_L(0); PG8_MMA(0, 0, At, B0); PG8_BAR; PG8_SCHED;
;             PG8_LDB(B1, 0, 1); PG8_STAGE(PG8_SB(0, 0), b2, voffB);
;             PG8_BAR; PG8_WAIT_L(0); PG8_MMA(0, 1, At, B1); PG8_BAR;
;             PG8_LDA(At, 0, 1); PG8_STAGE(PG8_SA(0, 0), a2, voffA);
;             PG8_BAR; PG8_WAIT_L(0); PG8_MMA(1, 0, At, B0); PG8_BAR; PG8_SCHED;
;             PG8_STAGE(PG8_SB(0, 1), b2 + hstepB, voffB);
;             PG8_WAIT_V(6); PG8_BAR; PG8_MMA(1, 1, At, B1); PG8_BAR;
;             PG8_LDB(B0, 1, 0); PG8_SCHED; PG8_LDA(At, 1, 0); PG8_STAGE(PG8_SA(0, 1), a2 + hstepA, voffA);
;             PG8_WAIT_L(8); PG8_BAR; PG8_WAIT_L(0); PG8_MMA(0, 0, At, B0); PG8_BAR; PG8_SCHED;
;             PG8_LDB(B1, 1, 1); PG8_STAGE(PG8_SB(1, 0), b3, voffB);
;             PG8_BAR; PG8_WAIT_L(0); PG8_MMA(0, 1, At, B1); PG8_BAR;
;             PG8_LDA(At, 1, 1); PG8_STAGE(PG8_SA(1, 0), a3, voffA);
;             PG8_BAR; PG8_WAIT_L(0); PG8_MMA(1, 0, At, B0); PG8_BAR; PG8_SCHED;
;             PG8_STAGE(PG8_SB(1, 1), b3 + hstepB, voffB);
;             PG8_WAIT_V(6); PG8_BAR; PG8_MMA(1, 1, At, B1); PG8_BAR;
	v_mfma_f32_16x16x32_bf16 v[48:51], v[208:211], v[172:175], v[48:51]
	v_mfma_f32_16x16x32_bf16 v[40:43], v[216:219], v[172:175], v[40:43]
	v_mfma_f32_16x16x32_bf16 v[32:35], v[208:211], v[184:187], v[32:35]
	v_mfma_f32_16x16x32_bf16 v[24:27], v[216:219], v[184:187], v[24:27]
	v_mfma_f32_16x16x32_bf16 v[16:19], v[208:211], v[192:195], v[16:19]
	v_mfma_f32_16x16x32_bf16 v[8:11], v[216:219], v[192:195], v[8:11]
	v_mfma_f32_16x16x32_bf16 v[4:7], v[208:211], v[200:203], v[4:7]
	v_mfma_f32_16x16x32_bf16 v[0:3], v[216:219], v[200:203], v[0:3]
	v_mfma_f32_16x16x32_bf16 v[48:51], v[212:215], v[176:179], v[48:51]
	v_mfma_f32_16x16x32_bf16 v[40:43], v[220:223], v[176:179], v[40:43]
	v_mfma_f32_16x16x32_bf16 v[32:35], v[212:215], v[188:191], v[32:35]
	v_mfma_f32_16x16x32_bf16 v[24:27], v[220:223], v[188:191], v[24:27]
	v_mfma_f32_16x16x32_bf16 v[16:19], v[212:215], v[196:199], v[16:19]
	v_mfma_f32_16x16x32_bf16 v[8:11], v[220:223], v[196:199], v[8:11]
	v_mfma_f32_16x16x32_bf16 v[4:7], v[212:215], v[204:207], v[4:7]
	v_mfma_f32_16x16x32_bf16 v[0:3], v[220:223], v[204:207], v[0:3]
	s_waitcnt lgkmcnt(0)
	s_barrier
	s_add_u32 s44, s70, 0x80000
	s_addc_u32 s45, s71, 0
	s_mov_b32 m0, s12
	ds_read_b128 v[172:175], v168 offset:32768
	ds_read_b128 v[176:179], v168 offset:33792
	ds_read_b128 v[184:187], v168 offset:34816
	ds_read_b128 v[188:191], v168 offset:35840
	ds_read_b128 v[192:195], v168 offset:36864
	ds_read_b128 v[196:199], v168 offset:37888
	ds_read_b128 v[200:203], v168 offset:38912
	ds_read_b128 v[204:207], v168 offset:39936
	global_load_lds_dwordx4 v128, s[44:45]
	s_mov_b32 m0, s13
	s_nop 0
	global_load_lds_dwordx4 v132, s[44:45]
	s_waitcnt lgkmcnt(8)
	s_barrier
	s_waitcnt lgkmcnt(0)
	s_waitcnt lgkmcnt(0)
	v_mfma_f32_16x16x32_bf16 v[124:127], v[146:149], v[172:175], v[124:127]
	v_mfma_f32_16x16x32_bf16 v[120:123], v[154:157], v[172:175], v[120:123]
	v_mfma_f32_16x16x32_bf16 v[112:115], v[146:149], v[184:187], v[112:115]
	v_mfma_f32_16x16x32_bf16 v[104:107], v[154:157], v[184:187], v[104:107]
	v_mfma_f32_16x16x32_bf16 v[96:99], v[146:149], v[192:195], v[96:99]
	v_mfma_f32_16x16x32_bf16 v[88:91], v[154:157], v[192:195], v[88:91]
	v_mfma_f32_16x16x32_bf16 v[80:83], v[146:149], v[200:203], v[80:83]
	v_mfma_f32_16x16x32_bf16 v[72:75], v[154:157], v[200:203], v[72:75]
	v_mfma_f32_16x16x32_bf16 v[124:127], v[150:153], v[176:179], v[124:127]
	v_mfma_f32_16x16x32_bf16 v[120:123], v[158:161], v[176:179], v[120:123]
	v_mfma_f32_16x16x32_bf16 v[112:115], v[150:153], v[188:191], v[112:115]
	v_mfma_f32_16x16x32_bf16 v[104:107], v[158:161], v[188:191], v[104:107]
	v_mfma_f32_16x16x32_bf16 v[96:99], v[150:153], v[196:199], v[96:99]
	v_mfma_f32_16x16x32_bf16 v[88:91], v[158:161], v[196:199], v[88:91]
	v_mfma_f32_16x16x32_bf16 v[80:83], v[150:153], v[204:207], v[80:83]
	v_mfma_f32_16x16x32_bf16 v[72:75], v[158:161], v[204:207], v[72:75]
	s_barrier
	s_add_i32 s46, 0, 0x1c000
	s_add_i32 s43, s43, s9
	v_add_u32_e32 v171, s46, v165
	s_mov_b32 m0, s43
	ds_read_b128 v[208:211], v171
	ds_read_b128 v[212:215], v171 offset:1024
	ds_read_b128 v[216:219], v171 offset:2048
	ds_read_b128 v[220:223], v171 offset:3072
	global_load_lds_dwordx4 v130, s[98:99]
	s_add_i32 m0, s43, 0x2000
	s_nop 0
	global_load_lds_dwordx4 v134, s[98:99]
	s_barrier
	s_waitcnt lgkmcnt(0)
	s_waitcnt lgkmcnt(0)
	v_mfma_f32_16x16x32_bf16 v[116:119], v[208:211], v[172:175], v[116:119]
	v_mfma_f32_16x16x32_bf16 v[108:111], v[216:219], v[172:175], v[108:111]
	v_mfma_f32_16x16x32_bf16 v[100:103], v[208:211], v[184:187], v[100:103]
	v_mfma_f32_16x16x32_bf16 v[92:95], v[216:219], v[184:187], v[92:95]
	v_mfma_f32_16x16x32_bf16 v[84:87], v[208:211], v[192:195], v[84:87]
	v_mfma_f32_16x16x32_bf16 v[76:79], v[216:219], v[192:195], v[76:79]
	v_mfma_f32_16x16x32_bf16 v[68:71], v[208:211], v[200:203], v[68:71]
	v_mfma_f32_16x16x32_bf16 v[64:67], v[216:219], v[200:203], v[64:67]
	v_mfma_f32_16x16x32_bf16 v[116:119], v[212:215], v[176:179], v[116:119]
	v_mfma_f32_16x16x32_bf16 v[108:111], v[220:223], v[176:179], v[108:111]
	v_mfma_f32_16x16x32_bf16 v[100:103], v[212:215], v[188:191], v[100:103]
	v_mfma_f32_16x16x32_bf16 v[92:95], v[220:223], v[188:191], v[92:95]
	v_mfma_f32_16x16x32_bf16 v[84:87], v[212:215], v[196:199], v[84:87]
	v_mfma_f32_16x16x32_bf16 v[76:79], v[220:223], v[196:199], v[76:79]
	v_mfma_f32_16x16x32_bf16 v[68:71], v[212:215], v[204:207], v[68:71]
	v_mfma_f32_16x16x32_bf16 v[64:67], v[220:223], v[204:207], v[64:67]
	s_mov_b32 m0, s15
	s_barrier
	ds_read_b128 v[172:175], v168 offset:49152
	ds_read_b128 v[176:179], v168 offset:50176
	ds_read_b128 v[184:187], v168 offset:51200
	ds_read_b128 v[188:191], v168 offset:52224
	ds_read_b128 v[192:195], v168 offset:53248
	ds_read_b128 v[196:199], v168 offset:54272
	ds_read_b128 v[200:203], v168 offset:55296
	ds_read_b128 v[204:207], v168 offset:56320
	global_load_lds_dwordx4 v128, s[100:101]
	s_mov_b32 m0, s22
	s_nop 0
	global_load_lds_dwordx4 v132, s[100:101]
	s_waitcnt vmcnt(10)
	s_barrier
	s_waitcnt lgkmcnt(0)
	s_waitcnt lgkmcnt(0)
	v_mfma_f32_16x16x32_bf16 v[60:63], v[146:149], v[172:175], v[60:63]
	v_mfma_f32_16x16x32_bf16 v[56:59], v[154:157], v[172:175], v[56:59]
	v_mfma_f32_16x16x32_bf16 v[52:55], v[146:149], v[184:187], v[52:55]
	v_mfma_f32_16x16x32_bf16 v[44:47], v[154:157], v[184:187], v[44:47]
	v_mfma_f32_16x16x32_bf16 v[36:39], v[146:149], v[192:195], v[36:39]
	v_mfma_f32_16x16x32_bf16 v[28:31], v[154:157], v[192:195], v[28:31]
	v_mfma_f32_16x16x32_bf16 v[20:23], v[146:149], v[200:203], v[20:23]
	v_mfma_f32_16x16x32_bf16 v[12:15], v[154:157], v[200:203], v[12:15]
	v_mfma_f32_16x16x32_bf16 v[60:63], v[150:153], v[176:179], v[60:63]
	v_mfma_f32_16x16x32_bf16 v[56:59], v[158:161], v[176:179], v[56:59]
	v_mfma_f32_16x16x32_bf16 v[52:55], v[150:153], v[188:191], v[52:55]
	v_mfma_f32_16x16x32_bf16 v[44:47], v[158:161], v[188:191], v[44:47]
	v_mfma_f32_16x16x32_bf16 v[36:39], v[150:153], v[196:199], v[36:39]
	v_mfma_f32_16x16x32_bf16 v[28:31], v[158:161], v[196:199], v[28:31]
	v_mfma_f32_16x16x32_bf16 v[20:23], v[150:153], v[204:207], v[20:23]
	v_mfma_f32_16x16x32_bf16 v[12:15], v[158:161], v[204:207], v[12:15]
	s_barrier
; template <class Epi>
; __device__ __forceinline__ void gemm_phase(LAS unsigned char* lds, const Gemm g, const StaticOrder& S, const Epi& E, int wv) {
;     ...
;             PG8_BAR; PG8_WAIT_L(0); PG8_MMA(1, 0, At, B0); PG8_BAR; PG8_SCHED;
;             PG8_STAGE(PG8_SB(1, 1), b3 + hstepB, voffB);
;             PG8_WAIT_V(6); PG8_BAR; PG8_MMA(1, 1, At, B1); PG8_BAR;
;         }
;         E(acc, cur, wr, wc, fr, fq);
;     __device__ __forceinline__ void operator()(const f32x4 (&acc)[2][2][4][2], const Unit& u, int wr, int wc, int fr, int fq) const {
;     ...
;         if (SM == 2) {
; #pragma unroll
;             for (int bj = 0; bj < 2; ++bj)
; #pragma unroll
;                 for (int n = 0; n < 2; ++n) { const f32x4 s = *(const f32x4*)(ss + u.pn * BM + wc * 32 + 8 * fq + bj * HALF + 4 * n);
; #pragma unroll
;                     for (int j = 0; j < 4; ++j) cs[bj][n][j] = __builtin_amdgcn_rsqf(ss_fix(s[j]) * (1.0f / DM) + EPS); }
;         }
;         float rsv[8];
; #pragma unroll
;         for (int it = 0; it < 8; ++it) rsv[it] = (SM == 1) ? ss[row0 + (it >> 2) * HALF + (it & 3) * 16] : 1.0f;
; #pragma unroll
;         for (int ai = 0; ai < 2; ++ai)
; #pragma unroll
;             for (int m = 0; m < 4; ++m) { const int row = row0 + ai * HALF + m * 16; float rs = 1.0f; if (SM == 1) rs = __builtin_amdgcn_rsqf(ss_fix(rsv[ai * 4 + m]) * (1.0f / DM) + EPS);
;                 bf16_t* rowp = base + (size_t)row * ldc + col0;
; #pragma unroll
;                 for (int bj = 0; bj < 2; ++bj) { f32x4 v0 = acc[ai][bj][m][0], v1 = acc[ai][bj][m][1];
;                     if (SM == 1) { v0 *= rs; v1 *= rs; }
;                     if (SM == 2) { v0 *= cs[bj][0]; v1 *= cs[bj][1]; }
;                     if (ACT == 1) {
; #pragma unroll
;                         for (int j = 0; j < 4; ++j) { const float a = fmaxf(v0[j], 0.f), b = fmaxf(v1[j], 0.f); v0[j] = a * a; v1[j] = b * b; } }
;                     if (ACT == 2) { if (tsel == 0) {
; #pragma unroll
;                         for (int j = 0; j < 4; ++j) { const float a = v0[j], b = v1[j];
;                             v0[j] = a * fast_sigmoid(1.5957691216057308f * (a + 0.044715f * a * a * a)); v1[j] = b * fast_sigmoid(1.5957691216057308f * (b + 0.044715f * b * b * b)); } } }
;                     u32x4 w; w.x = pk_bf16(v0[0], v0[1]); w.y = pk_bf16(v0[2], v0[3]); w.z = pk_bf16(v1[0], v1[1]); w.w = pk_bf16(v1[2], v1[3]);
	s_add_u32 s44, s68, 0x80080
	s_addc_u32 s45, s69, 0
	s_add_i32 s43, s46, s9
	s_mov_b32 m0, s43
	s_nop 0
	global_load_lds_dwordx4 v130, s[44:45]
	s_add_i32 m0, s43, 0x2000
	s_nop 0
	global_load_lds_dwordx4 v134, s[44:45]
	ds_read_b128 v[146:149], v167
	ds_read_b128 v[150:153], v167 offset:1024
	ds_read_b128 v[154:157], v167 offset:2048
	ds_read_b128 v[158:161], v167 offset:3072
	s_waitcnt vmcnt(6)
	s_barrier
	v_mfma_f32_16x16x32_bf16 v[48:51], v[208:211], v[172:175], v[48:51]
	v_mfma_f32_16x16x32_bf16 v[40:43], v[216:219], v[172:175], v[40:43]
	v_mfma_f32_16x16x32_bf16 v[32:35], v[208:211], v[184:187], v[32:35]
	v_mfma_f32_16x16x32_bf16 v[24:27], v[216:219], v[184:187], v[24:27]
	v_mfma_f32_16x16x32_bf16 v[16:19], v[208:211], v[192:195], v[16:19]
	v_mfma_f32_16x16x32_bf16 v[8:11], v[216:219], v[192:195], v[8:11]
	v_mfma_f32_16x16x32_bf16 v[4:7], v[208:211], v[200:203], v[4:7]
	v_mfma_f32_16x16x32_bf16 v[0:3], v[216:219], v[200:203], v[0:3]
	v_mfma_f32_16x16x32_bf16 v[48:51], v[212:215], v[176:179], v[48:51]
	v_mfma_f32_16x16x32_bf16 v[40:43], v[220:223], v[176:179], v[40:43]
	v_mfma_f32_16x16x32_bf16 v[32:35], v[212:215], v[188:191], v[32:35]
	v_mfma_f32_16x16x32_bf16 v[24:27], v[220:223], v[188:191], v[24:27]
	v_mfma_f32_16x16x32_bf16 v[16:19], v[212:215], v[196:199], v[16:19]
	v_mfma_f32_16x16x32_bf16 v[8:11], v[220:223], v[196:199], v[8:11]
	v_mfma_f32_16x16x32_bf16 v[4:7], v[212:215], v[204:207], v[4:7]
	v_mfma_f32_16x16x32_bf16 v[0:3], v[220:223], v[204:207], v[0:3]
	s_waitcnt lgkmcnt(0)
	s_add_i32 s42, s42, 2
	s_add_u32 s66, s66, 0x100
	s_addc_u32 s67, s67, 0
	s_add_u32 s40, s40, 0x100
	s_addc_u32 s41, s41, 0
	s_cmp_gt_u32 s42, 29
	s_barrier
	s_cbranch_scc0 .LBB0_259
	s_lshl_b32 s34, s33, 8
	s_ashr_i32 s35, s34, 31
	v_lshl_add_u64 v[146:147], s[34:35], 2, v[136:137]
	global_load_dwordx4 v[148:151], v[146:147], off
	global_load_dwordx4 v[152:155], v[146:147], off offset:16
	global_load_dwordx4 v[156:159], v[146:147], off offset:512
	global_load_dwordx4 v[160:163], v[146:147], off offset:528
	v_lshl_add_u32 v172, s64, 8, v164
	v_or_b32_e32 v146, s34, v166
	v_ashrrev_i32_e32 v173, 31, v172
	v_ashrrev_i32_e32 v147, 31, v146
	v_lshlrev_b64 v[174:175], 15, v[172:173]
	v_lshl_add_u64 v[176:177], v[146:147], 1, s[18:19]
	v_lshl_add_u64 v[146:147], v[176:177], 0, v[174:175]
	s_mov_b32 s33, 0x400000
	s_mov_b64 s[34:35], 0x400000
	s_mov_b32 s64, s58
	s_mov_b64 s[68:69], s[62:63]
	s_mov_b64 s[66:67], s[60:61]
	s_waitcnt vmcnt(0)
	v_cvt_f32_u32_e32 v148, v148
	v_cvt_f32_u32_e32 v149, v149
	v_cvt_f32_u32_e32 v150, v150
	v_cvt_f32_u32_e32 v151, v151
	v_cvt_f32_u32_e32 v152, v152
	v_cvt_f32_u32_e32 v153, v153
	v_cvt_f32_u32_e32 v154, v154
	v_cvt_f32_u32_e32 v155, v155
	v_cvt_f32_u32_e32 v156, v156
	v_cvt_f32_u32_e32 v157, v157
	v_cvt_f32_u32_e32 v158, v158
	v_cvt_f32_u32_e32 v159, v159
	v_cvt_f32_u32_e32 v160, v160
	v_cvt_f32_u32_e32 v161, v161
	v_cvt_f32_u32_e32 v162, v162
	v_cvt_f32_u32_e32 v163, v163
	v_mul_f32_e32 v148, 0x3b800000, v148
	v_mul_f32_e32 v149, 0x3b800000, v149
	v_mul_f32_e32 v150, 0x3b800000, v150
	v_mul_f32_e32 v151, 0x3b800000, v151
	v_mul_f32_e32 v152, 0x3b800000, v152
	v_mul_f32_e32 v153, 0x3b800000, v153
	v_mul_f32_e32 v154, 0x3b800000, v154
	v_mul_f32_e32 v155, 0x3b800000, v155
	v_mul_f32_e32 v156, 0x3b800000, v156
	v_mul_f32_e32 v157, 0x3b800000, v157
	v_mul_f32_e32 v158, 0x3b800000, v158
	v_mul_f32_e32 v159, 0x3b800000, v159
	v_mul_f32_e32 v160, 0x3b800000, v160
	v_mul_f32_e32 v161, 0x3b800000, v161
	v_mul_f32_e32 v162, 0x3b800000, v162
	v_mul_f32_e32 v163, 0x3b800000, v163
	v_fmamk_f32 v148, v148, 0x3a000000, v170
	v_fmamk_f32 v149, v149, 0x3a000000, v170
	v_fmamk_f32 v150, v150, 0x3a000000, v170
	v_fmamk_f32 v151, v151, 0x3a000000, v170
	v_fmamk_f32 v152, v152, 0x3a000000, v170
	v_fmamk_f32 v153, v153, 0x3a000000, v170
	v_fmamk_f32 v154, v154, 0x3a000000, v170
	v_fmamk_f32 v155, v155, 0x3a000000, v170
	v_fmamk_f32 v171, v156, 0x3a000000, v170
	v_fmamk_f32 v173, v157, 0x3a000000, v170
	v_fmamk_f32 v174, v158, 0x3a000000, v170
	v_fmamk_f32 v175, v159, 0x3a000000, v170
	v_fmamk_f32 v178, v160, 0x3a000000, v170
	v_fmamk_f32 v179, v161, 0x3a000000, v170
	v_fmamk_f32 v180, v162, 0x3a000000, v170
	v_fmamk_f32 v181, v163, 0x3a000000, v170
	v_rsq_f32_e32 v158, v148
	v_rsq_f32_e32 v159, v149
	v_rsq_f32_e32 v162, v150
	v_rsq_f32_e32 v163, v151
	v_rsq_f32_e32 v156, v152
	v_rsq_f32_e32 v157, v153
	v_rsq_f32_e32 v160, v154
	v_rsq_f32_e32 v161, v155
	v_rsq_f32_e32 v150, v171
	v_rsq_f32_e32 v151, v173
	v_rsq_f32_e32 v154, v174
	v_rsq_f32_e32 v155, v175
	v_rsq_f32_e32 v148, v178
	v_rsq_f32_e32 v149, v179
	v_rsq_f32_e32 v152, v180
	v_rsq_f32_e32 v153, v181
	v_pk_mul_f32 v[126:127], v[126:127], v[162:163]
	v_pk_mul_f32 v[124:125], v[124:125], v[158:159]
	v_pk_mul_f32 v[122:123], v[122:123], v[160:161]
	v_pk_mul_f32 v[120:121], v[120:121], v[156:157]
	v_pk_mul_f32 v[118:119], v[118:119], v[154:155]
	v_pk_mul_f32 v[116:117], v[116:117], v[150:151]
	v_pk_mul_f32 v[174:175], v[110:111], v[152:153]
	v_pk_mul_f32 v[178:179], v[108:109], v[148:149]
	v_cvt_pk_bf16_f32 v108, v124, v125
	v_cvt_pk_bf16_f32 v109, v126, v127
	v_cvt_pk_bf16_f32 v110, v120, v121
	v_cvt_pk_bf16_f32 v111, v122, v123
	v_cvt_pk_bf16_f32 v116, v116, v117
	v_cvt_pk_bf16_f32 v117, v118, v119
	v_cvt_pk_bf16_f32 v118, v178, v179
	v_cvt_pk_bf16_f32 v119, v174, v175
	global_store_dwordx4 v[146:147], v[108:111], off
	global_store_dwordx4 v[146:147], v[116:119], off offset:256
	v_pk_mul_f32 v[112:113], v[112:113], v[158:159]
	v_or_b32_e32 v108, 16, v172
	v_ashrrev_i32_e32 v109, 31, v108
	v_lshlrev_b64 v[108:109], 15, v[108:109]
	v_pk_mul_f32 v[110:111], v[114:115], v[162:163]
; __device__ __forceinline__ float fast_sigmoid(float x) { return __builtin_amdgcn_rcpf(1.0f + __builtin_amdgcn_exp2f(-x * LOG2E)); }
; __device__ __forceinline__ float ss_fix(float raw) { return (float)__float_as_uint(raw) * (1.0f / 256.0f); }
; template <class Epi>
; __device__ __forceinline__ void gemm_phase(LAS unsigned char* lds, const Gemm g, const StaticOrder& S, const Epi& E, int wv) {
;     ...
;         if (!has_next) break;
; #pragma unroll
;         for (int a = 0; a < 2; ++a)
; #pragma unroll
;             for (int b = 0; b < 2; ++b)
; #pragma unroll
;                 for (int m = 0; m < 4; ++m)
; #pragma unroll
;                     for (int n = 0; n < 2; ++n) acc[a][b][m][n] = (f32x4){0.f, 0.f, 0.f, 0.f};
;         cur = nxt; cA = nA; cB = nB; ++ui;
;     __device__ __forceinline__ void operator()(const f32x4 (&acc)[2][2][4][2], const Unit& u, int wr, int wc, int fr, int fq) const {
;     ...
;         for (int ai = 0; ai < 2; ++ai)
; #pragma unroll
;             for (int m = 0; m < 4; ++m) { const int row = row0 + ai * HALF + m * 16; float rs = 1.0f; if (SM == 1) rs = __builtin_amdgcn_rsqf(ss_fix(rsv[ai * 4 + m]) * (1.0f / DM) + EPS);
;                 bf16_t* rowp = base + (size_t)row * ldc + col0;
; #pragma unroll
;                 for (int bj = 0; bj < 2; ++bj) { f32x4 v0 = acc[ai][bj][m][0], v1 = acc[ai][bj][m][1];
;                     if (SM == 1) { v0 *= rs; v1 *= rs; }
;                     if (SM == 2) { v0 *= cs[bj][0]; v1 *= cs[bj][1]; }
;                     if (ACT == 1) {
; #pragma unroll
;                         for (int j = 0; j < 4; ++j) { const float a = fmaxf(v0[j], 0.f), b = fmaxf(v1[j], 0.f); v0[j] = a * a; v1[j] = b * b; } }
;                     if (ACT == 2) { if (tsel == 0) {
; #pragma unroll
;                         for (int j = 0; j < 4; ++j) { const float a = v0[j], b = v1[j];
;                             v0[j] = a * fast_sigmoid(1.5957691216057308f * (a + 0.044715f * a * a * a)); v1[j] = b * fast_sigmoid(1.5957691216057308f * (b + 0.044715f * b * b * b)); } } }
;                     u32x4 w; w.x = pk_bf16(v0[0], v0[1]); w.y = pk_bf16(v0[2], v0[3]); w.z = pk_bf16(v1[0], v1[1]); w.w = pk_bf16(v1[2], v1[3]);
;                     *(u32x4*)(rowp + bj * HALF) = w; } }
	v_pk_mul_f32 v[114:115], v[106:107], v[160:161]
	v_pk_mul_f32 v[106:107], v[104:105], v[156:157]
	v_lshl_add_u64 v[108:109], v[176:177], 0, v[108:109]
	v_cvt_pk_bf16_f32 v104, v112, v113
	v_cvt_pk_bf16_f32 v105, v110, v111
	v_cvt_pk_bf16_f32 v106, v106, v107
	v_cvt_pk_bf16_f32 v107, v114, v115
	global_store_dwordx4 v[108:109], v[104:107], off
	v_pk_mul_f32 v[102:103], v[102:103], v[154:155]
	v_pk_mul_f32 v[100:101], v[100:101], v[150:151]
	v_pk_mul_f32 v[104:105], v[94:95], v[152:153]
	v_pk_mul_f32 v[94:95], v[92:93], v[148:149]
	v_cvt_pk_bf16_f32 v92, v100, v101
	v_cvt_pk_bf16_f32 v93, v102, v103
	v_cvt_pk_bf16_f32 v94, v94, v95
	v_cvt_pk_bf16_f32 v95, v104, v105
	global_store_dwordx4 v[108:109], v[92:95], off offset:256
	v_pk_mul_f32 v[96:97], v[96:97], v[158:159]
	v_pk_mul_f32 v[86:87], v[86:87], v[154:155]
	v_or_b32_e32 v92, 32, v172
	v_ashrrev_i32_e32 v93, 31, v92
	v_lshlrev_b64 v[92:93], 15, v[92:93]
	v_pk_mul_f32 v[94:95], v[98:99], v[162:163]
	v_pk_mul_f32 v[98:99], v[90:91], v[160:161]
	v_pk_mul_f32 v[90:91], v[88:89], v[156:157]
	v_lshl_add_u64 v[92:93], v[176:177], 0, v[92:93]
	v_cvt_pk_bf16_f32 v88, v96, v97
	v_cvt_pk_bf16_f32 v89, v94, v95
	v_cvt_pk_bf16_f32 v90, v90, v91
	v_cvt_pk_bf16_f32 v91, v98, v99
	global_store_dwordx4 v[92:93], v[88:91], off
	v_pk_mul_f32 v[84:85], v[84:85], v[150:151]
	v_pk_mul_f32 v[80:81], v[80:81], v[158:159]
	v_pk_mul_f32 v[88:89], v[78:79], v[152:153]
	v_pk_mul_f32 v[78:79], v[76:77], v[148:149]
	v_cvt_pk_bf16_f32 v76, v84, v85
	v_cvt_pk_bf16_f32 v77, v86, v87
	v_cvt_pk_bf16_f32 v78, v78, v79
	v_cvt_pk_bf16_f32 v79, v88, v89
	global_store_dwordx4 v[92:93], v[76:79], off offset:256
	v_pk_mul_f32 v[70:71], v[70:71], v[154:155]
	v_pk_mul_f32 v[68:69], v[68:69], v[150:151]
	v_or_b32_e32 v76, 48, v172
	v_ashrrev_i32_e32 v77, 31, v76
	v_lshlrev_b64 v[76:77], 15, v[76:77]
	v_pk_mul_f32 v[78:79], v[82:83], v[162:163]
	v_pk_mul_f32 v[82:83], v[74:75], v[160:161]
	v_pk_mul_f32 v[74:75], v[72:73], v[156:157]
	v_lshl_add_u64 v[76:77], v[176:177], 0, v[76:77]
	v_cvt_pk_bf16_f32 v72, v80, v81
	v_cvt_pk_bf16_f32 v73, v78, v79
	v_cvt_pk_bf16_f32 v74, v74, v75
	v_cvt_pk_bf16_f32 v75, v82, v83
	global_store_dwordx4 v[76:77], v[72:75], off
	v_pk_mul_f32 v[60:61], v[60:61], v[158:159]
	v_pk_mul_f32 v[62:63], v[62:63], v[162:163]
	v_pk_mul_f32 v[72:73], v[66:67], v[152:153]
	v_pk_mul_f32 v[66:67], v[64:65], v[148:149]
	v_cvt_pk_bf16_f32 v64, v68, v69
	v_cvt_pk_bf16_f32 v65, v70, v71
	v_cvt_pk_bf16_f32 v66, v66, v67
	v_cvt_pk_bf16_f32 v67, v72, v73
	global_store_dwordx4 v[76:77], v[64:67], off offset:256
	v_pk_mul_f32 v[50:51], v[50:51], v[154:155]
	v_pk_mul_f32 v[48:49], v[48:49], v[150:151]
	v_pk_mul_f32 v[66:67], v[58:59], v[160:161]
	v_pk_mul_f32 v[58:59], v[56:57], v[156:157]
	v_cvt_pk_bf16_f32 v56, v60, v61
	v_add_co_u32_e32 v60, vcc, s33, v146
	v_cvt_pk_bf16_f32 v57, v62, v63
	v_cvt_pk_bf16_f32 v58, v58, v59
	v_cvt_pk_bf16_f32 v59, v66, v67
	v_addc_co_u32_e32 v61, vcc, 0, v147, vcc
	global_store_dwordx4 v[60:61], v[56:59], off
	v_lshl_add_u64 v[64:65], v[146:147], 0, s[34:35]
	v_pk_mul_f32 v[44:45], v[44:45], v[156:157]
	v_pk_mul_f32 v[56:57], v[42:43], v[152:153]
	v_pk_mul_f32 v[42:43], v[40:41], v[148:149]
	v_cvt_pk_bf16_f32 v40, v48, v49
	v_cvt_pk_bf16_f32 v41, v50, v51
	v_cvt_pk_bf16_f32 v42, v42, v43
	v_cvt_pk_bf16_f32 v43, v56, v57
	global_store_dwordx4 v[64:65], v[40:43], off offset:256
	v_pk_mul_f32 v[46:47], v[46:47], v[160:161]
	v_pk_mul_f32 v[34:35], v[34:35], v[154:155]
	v_pk_mul_f32 v[42:43], v[54:55], v[162:163]
	v_pk_mul_f32 v[40:41], v[52:53], v[158:159]
	v_pk_mul_f32 v[32:33], v[32:33], v[150:151]
	v_cvt_pk_bf16_f32 v40, v40, v41
	v_cvt_pk_bf16_f32 v41, v42, v43
	v_cvt_pk_bf16_f32 v42, v44, v45
	v_add_co_u32_e32 v44, vcc, s25, v146
	v_cvt_pk_bf16_f32 v43, v46, v47
	s_nop 0
	v_addc_co_u32_e32 v45, vcc, 0, v147, vcc
	global_store_dwordx4 v[44:45], v[40:43], off
	v_lshl_add_u64 v[48:49], v[146:147], 0, s[50:51]
	v_pk_mul_f32 v[28:29], v[28:29], v[156:157]
	v_pk_mul_f32 v[40:41], v[26:27], v[152:153]
	v_pk_mul_f32 v[26:27], v[24:25], v[148:149]
	v_cvt_pk_bf16_f32 v24, v32, v33
	v_cvt_pk_bf16_f32 v25, v34, v35
	v_cvt_pk_bf16_f32 v26, v26, v27
	v_cvt_pk_bf16_f32 v27, v40, v41
	global_store_dwordx4 v[48:49], v[24:27], off offset:256
	v_pk_mul_f32 v[30:31], v[30:31], v[160:161]
	v_pk_mul_f32 v[18:19], v[18:19], v[154:155]
	v_pk_mul_f32 v[26:27], v[38:39], v[162:163]
	v_pk_mul_f32 v[24:25], v[36:37], v[158:159]
	v_pk_mul_f32 v[16:17], v[16:17], v[150:151]
	v_cvt_pk_bf16_f32 v24, v24, v25
	v_cvt_pk_bf16_f32 v25, v26, v27
	v_cvt_pk_bf16_f32 v26, v28, v29
	v_add_co_u32_e32 v28, vcc, s30, v146
	v_cvt_pk_bf16_f32 v27, v30, v31
	s_nop 0
	v_addc_co_u32_e32 v29, vcc, 0, v147, vcc
	global_store_dwordx4 v[28:29], v[24:27], off
	v_lshl_add_u64 v[32:33], v[146:147], 0, s[52:53]
	v_pk_mul_f32 v[12:13], v[12:13], v[156:157]
	v_pk_mul_f32 v[24:25], v[10:11], v[152:153]
	v_pk_mul_f32 v[10:11], v[8:9], v[148:149]
	v_cvt_pk_bf16_f32 v8, v16, v17
	v_cvt_pk_bf16_f32 v9, v18, v19
	v_cvt_pk_bf16_f32 v10, v10, v11
	v_cvt_pk_bf16_f32 v11, v24, v25
	global_store_dwordx4 v[32:33], v[8:11], off offset:256
	v_pk_mul_f32 v[14:15], v[14:15], v[160:161]
	v_pk_mul_f32 v[6:7], v[6:7], v[154:155]
	v_pk_mul_f32 v[10:11], v[22:23], v[162:163]
	v_pk_mul_f32 v[8:9], v[20:21], v[158:159]
	v_pk_mul_f32 v[4:5], v[4:5], v[150:151]
	v_cvt_pk_bf16_f32 v8, v8, v9
	v_cvt_pk_bf16_f32 v9, v10, v11
	v_cvt_pk_bf16_f32 v10, v12, v13
	v_add_co_u32_e32 v12, vcc, s31, v146
	v_cvt_pk_bf16_f32 v11, v14, v15
	s_nop 0
	v_addc_co_u32_e32 v13, vcc, 0, v147, vcc
	global_store_dwordx4 v[12:13], v[8:11], off
	v_lshl_add_u64 v[16:17], v[146:147], 0, s[54:55]
	s_and_b64 vcc, exec, s[16:17]
	v_pk_mul_f32 v[8:9], v[2:3], v[152:153]
	v_pk_mul_f32 v[2:3], v[0:1], v[148:149]
	v_cvt_pk_bf16_f32 v0, v4, v5
	v_cvt_pk_bf16_f32 v1, v6, v7
	v_cvt_pk_bf16_f32 v2, v2, v3
	v_cvt_pk_bf16_f32 v3, v8, v9
	s_mov_b32 s33, s56
	global_store_dwordx4 v[16:17], v[0:3], off offset:256
	s_cbranch_vccz .LBB0_252
	s_waitcnt vmcnt(0)
	s_cmpk_gt_u32 s4, 0xff
	s_cbranch_scc1 .LBB0_263
	s_barrier

; __device__ __forceinline__ int opaque_tid(int wv) { int l; asm volatile("v_mbcnt_lo_u32_b32 %0, -1, 0\n\tv_mbcnt_hi_u32_b32 %0, -1, %0" : "=v"(l)); return wv * 64 + l; }
; #define PG8_BAR __builtin_amdgcn_s_barrier()
; template <class Epi>
; __device__ __forceinline__ void gemm_phase(LAS unsigned char* lds, const Gemm g, const StaticOrder& S, const Epi& E, int wv) {
;     const int tid = opaque_tid(wv), wid = __builtin_amdgcn_readfirstlane(tid >> 6), lane = tid & 63, wr = wid >> 2, wc = wid & 3, fr = lane & 15, fq = lane >> 4;
;     const int K = g.K, nt = K / BK;
;     unsigned voffA[2], voffB[2];
; #pragma unroll
;     for (int i = 0; i < 2; ++i) { int R, C; stage_rc(tid * 16 + i * 8192, R, C); const int Rb = Epi::PERM ? ((R & ~31) + perm32(R & 31)) : R;
;         voffA[i] = (unsigned)(R * g.lda + C) * 2u; voffB[i] = (unsigned)(Rb * g.ldb + C) * 2u; }
;     const bool krev = (g.adiag & 2) != 0;
;     const ptrdiff_t kstep = krev ? -(ptrdiff_t)(BK * 2) : (ptrdiff_t)(BK * 2);
;     const size_t kbeg = krev ? (size_t)(nt - 1) * (BK * 2) : 0;
;     const size_t hstepA = (size_t)HALF * g.lda * 2, hstepB = (size_t)HALF * g.ldb * 2;
;     const size_t tstepA = 2 * hstepA, tstepB = 2 * hstepB;
;     const unsigned ldsw = (unsigned)wid * 1024u;
;     const int aoff = lds_byte(wr * 64 + fr, fq * 8), boff = lds_byte(wc * 32 + fr, fq * 8);
;     ...
;     Unit cur, nxt; int ui = 0;
;     if (!S.next(0, cur)) return;
;     f32x4 acc[2][2][4][2];
; #pragma unroll
;     for (int a = 0; a < 2; ++a)
; #pragma unroll
;         for (int b = 0; b < 2; ++b)
; #pragma unroll
;             for (int m = 0; m < 4; ++m)
; #pragma unroll
;                 for (int n = 0; n < 2; ++n) acc[a][b][m][n] = (f32x4){0.f, 0.f, 0.f, 0.f};
;     bf16x8 At[4][2], B0[2][2], B1[2][2];
;     const char* cA = (const char*)g.A + (size_t)cur.pm * tstepA + ((g.adiag & 1) ? (size_t)(cur.pn >> 1) * K * 2 : 0) + kbeg;
;     const char* cB = (const char*)g.Bt + (size_t)cur.pn * tstepB + kbeg;
;     PG8_STAGE(PG8_SB(0, 0), cB, voffB); PG8_STAGE(PG8_SA(0, 0), cA, voffA); PG8_STAGE(PG8_SB(0, 1), cB + hstepB, voffB); PG8_STAGE(PG8_SA(0, 1), cA + hstepA, voffA);
;     if (wr == 1) PG8_BAR;
;     PG8_WAIT_V(4); PG8_BAR;
;     PG8_STAGE(PG8_SB(1, 0), cB + kstep, voffB); PG8_STAGE(PG8_SA(1, 0), cA + kstep, voffA); PG8_STAGE(PG8_SB(1, 1), cB + hstepB + kstep, voffB);
;     PG8_WAIT_V(6); PG8_BAR;
.LBB0_431:
	v_readlane_b32 s6, v255, 10
	v_readlane_b32 s7, v255, 11
	s_and_b64 vcc, exec, s[6:7]
	s_cbranch_vccnz .LBB0_463
	v_ashrrev_i32_e32 v2, 31, v0
	v_lshrrev_b32_e32 v2, 26, v2
	v_lshlrev_b32_e32 v1, 4, v0
	v_add_u32_e32 v2, v0, v2
	v_bfe_i32 v0, v0, 27, 1
	v_lshrrev_b32_e32 v0, 22, v0
	v_add_u32_e32 v0, v1, v0
	v_and_b32_e32 v0, 0xfffffc00, v0
	v_sub_u32_e32 v0, v1, v0
	v_ashrrev_i32_e32 v9, 6, v2
	v_lshrrev_b32_e32 v2, 4, v0
	v_bitop3_b32 v0, v2, v0, 32 bitop3:0x6c
	v_ashrrev_i32_e32 v3, 31, v0
	v_lshrrev_b32_e32 v3, 26, v3
	v_add_u32_e32 v3, v0, v3
	v_lshlrev_b32_e32 v2, 3, v9
	v_ashrrev_i32_e32 v10, 6, v3
	v_and_b32_e32 v3, 0xc0, v3
	v_and_b32_e32 v2, -16, v2
	v_sub_u32_e32 v0, v0, v3
	v_mov_b32_e32 v3, 1
	v_add_u32_e32 v2, v10, v2
	v_ashrrev_i16_sdwa v0, v3, sext(v0) dst_sel:DWORD dst_unused:UNUSED_PAD src0_sel:DWORD src1_sel:BYTE_0
	v_lshlrev_b32_e32 v4, 5, v9
	v_bfe_i32 v11, v0, 0, 16
	v_lshlrev_b32_e32 v0, 1, v2
	v_lshrrev_b32_e32 v5, 2, v2
	v_and_b32_e32 v6, 3, v10
	s_mov_b32 s9, 0xfffe0
	v_and_b32_e32 v4, 32, v4
	v_and_b32_e32 v0, 24, v0
	v_and_b32_e32 v5, 4, v5
	v_and_or_b32 v6, v2, s9, v6
	v_or3_b32 v0, v6, v5, v0
	v_add_lshl_u32 v4, v4, v11, 1
	v_lshl_add_u32 v146, v0, 12, v4
	v_add_u32_e32 v0, 0x2000, v1
	v_ashrrev_i32_e32 v1, 31, v0
	v_lshrrev_b32_e32 v1, 22, v1
	v_add_u32_e32 v1, v0, v1
	v_ashrrev_i32_e32 v12, 10, v1
	v_mul_i32_i24_e32 v1, 0x400, v12
	v_sub_u32_e32 v0, v0, v1
	v_lshrrev_b32_e32 v1, 4, v0
	v_bitop3_b32 v0, v1, v0, 32 bitop3:0x6c
	v_lshl_add_u32 v144, v2, 12, v4
	v_ashrrev_i32_e32 v2, 31, v0
	v_lshrrev_b32_e32 v2, 26, v2
	s_waitcnt lgkmcnt(0)
	s_add_u32 s5, s30, 0x1b300000
	v_add_u32_e32 v2, v0, v2
	s_addc_u32 s6, s31, 0
	v_lshlrev_b32_e32 v1, 3, v12
	v_ashrrev_i32_e32 v13, 6, v2
	v_and_b32_e32 v2, 0xc0, v2
	s_add_u32 s7, s50, 0x2100000
	v_and_b32_e32 v1, -16, v1
	v_sub_u32_e32 v0, v0, v2
	s_addc_u32 s8, s51, 0
	v_add_u32_e32 v1, v13, v1
	v_ashrrev_i16_sdwa v0, v3, sext(v0) dst_sel:DWORD dst_unused:UNUSED_PAD src0_sel:DWORD src1_sel:BYTE_0
	v_and_b32_e32 v3, 3, v13
	s_ashr_i32 s15, s4, 6
	s_ashr_i32 s67, s66, 31
	s_ashr_i32 s23, s4, 8
	v_and_or_b32 v3, v1, s9, v3
	s_lshl_b32 s9, s15, 10
	s_lshl_b64 s[10:11], s[66:67], 20
	s_add_u32 s70, s5, s10
	s_addc_u32 s71, s6, s11
	s_ashr_i32 s69, s68, 31
	s_lshl_b64 s[10:11], s[68:69], 20
	v_lshlrev_b32_e32 v4, 5, v12
	v_bfe_i32 v14, v0, 0, 16
	v_lshlrev_b32_e32 v0, 1, v1
	v_lshrrev_b32_e32 v2, 2, v1
	s_add_u32 s72, s7, s10
	v_and_b32_e32 v4, 32, v4
	v_and_b32_e32 v0, 24, v0
	v_and_b32_e32 v2, 4, v2
	s_addc_u32 s73, s8, s11
	s_add_i32 s10, s9, 0
	v_or3_b32 v0, v3, v2, v0
	v_add_lshl_u32 v2, v4, v14, 1
	s_add_i32 m0, s10, 0x10000
	v_lshl_add_u32 v150, v0, 12, v2
	global_load_lds_dwordx4 v146, s[72:73]
	s_add_i32 m0, s10, 0x12000
	s_add_i32 s11, s10, 0x2000
	global_load_lds_dwordx4 v150, s[72:73]
	s_mov_b32 m0, s10
	v_lshl_add_u32 v148, v1, 12, v2
	global_load_lds_dwordx4 v144, s[70:71]
	s_mov_b32 m0, s11
	s_add_u32 s12, s72, 0x80000
	global_load_lds_dwordx4 v148, s[70:71]
	s_addc_u32 s13, s73, 0
	s_add_i32 m0, s10, 0x14000
	v_mov_b32_e32 v147, 0
	global_load_lds_dwordx4 v146, s[12:13]
	s_add_i32 m0, s10, 0x16000
	s_add_u32 s24, s70, 0x80000
	global_load_lds_dwordx4 v150, s[12:13]
	s_addc_u32 s25, s71, 0
	s_add_i32 s12, s10, 0x4000
	s_mov_b32 m0, s12
	s_add_i32 s13, s10, 0x6000
	global_load_lds_dwordx4 v144, s[24:25]
	s_mov_b32 m0, s13
	v_mov_b32_e32 v151, v147
	global_load_lds_dwordx4 v148, s[24:25]
	v_mov_b32_e32 v145, v147
	v_mov_b32_e32 v149, v147
	s_mov_b32 s14, 0
	v_lshl_add_u64 v[6:7], s[72:73], 0, v[146:147]
	v_lshl_add_u64 v[4:5], s[72:73], 0, v[150:151]
	v_lshl_add_u64 v[2:3], s[70:71], 0, v[144:145]
	s_cmp_lg_u32 s23, 1
	v_lshl_add_u64 v[0:1], s[70:71], 0, v[148:149]
	s_cbranch_scc1 .LBB0_434
	s_barrier
	s_setprio 1

; #define PG8_STAGE(bufoff, gbase, voff) do { _Pragma("unroll") for (int _i = 0; _i < 2; ++_i) \
;         __builtin_amdgcn_global_load_lds((const unsigned*)((const char*)(gbase) + (voff)[_i]), (LAS unsigned*)(lds + (bufoff) + ldsw + _i * 8192), 16, 0, 0); } while (0)
; #define PG8_BAR __builtin_amdgcn_s_barrier()
; template <class Epi>
; __device__ __forceinline__ void gemm_phase(LAS unsigned char* lds, const Gemm g, const StaticOrder& S, const Epi& E, int wv) {
;     ...
;         const bool has_next = S.next(ui + 1, nxt);
;         const char* nA = has_next ? (const char*)g.A + (size_t)nxt.pm * tstepA + ((g.adiag & 1) ? (size_t)(nxt.pn >> 1) * K * 2 : 0) + kbeg : cA;
;         const char* nB = has_next ? (const char*)g.Bt + (size_t)nxt.pn * tstepB + kbeg : cB;
;         for (int t = 0; t < nt; t += 2) {
;             const bool last = (t == nt - 2);
;             const char* a1 = cA + (ptrdiff_t)(t + 1) * kstep;
;             const char* a2 = last ? nA : cA + (ptrdiff_t)(t + 2) * kstep; const char* b2 = last ? nB : cB + (ptrdiff_t)(t + 2) * kstep;
;             const char* a3 = a2 + kstep; const char* b3 = b2 + kstep;
;             PG8_LDB(B0, 0, 0); PG8_SCHED; PG8_LDA(At, 0, 0); PG8_STAGE(PG8_SA(1, 1), a1 + hstepA, voffA);
;             PG8_WAIT_L(8); PG8_BAR; PG8_WAIT_L(0); PG8_MMA(0, 0, At, B0); PG8_BAR; PG8_SCHED;
;             PG8_LDB(B1, 0, 1); PG8_STAGE(PG8_SB(0, 0), b2, voffB);
;             PG8_BAR; PG8_WAIT_L(0); PG8_MMA(0, 1, At, B1); PG8_BAR;
;             PG8_LDA(At, 0, 1); PG8_STAGE(PG8_SA(0, 0), a2, voffA);
;             PG8_BAR; PG8_WAIT_L(0); PG8_MMA(1, 0, At, B0); PG8_BAR; PG8_SCHED;
;             PG8_STAGE(PG8_SB(0, 1), b2 + hstepB, voffB);
;             PG8_WAIT_V(6); PG8_BAR; PG8_MMA(1, 1, At, B1); PG8_BAR;
;             PG8_LDB(B0, 1, 0); PG8_SCHED; PG8_LDA(At, 1, 0); PG8_STAGE(PG8_SA(0, 1), a2 + hstepA, voffA);
;             PG8_WAIT_L(8); PG8_BAR; PG8_WAIT_L(0); PG8_MMA(0, 0, At, B0); PG8_BAR; PG8_SCHED;
;             PG8_LDB(B1, 1, 1); PG8_STAGE(PG8_SB(1, 0), b3, voffB);
;             PG8_BAR; PG8_WAIT_L(0); PG8_MMA(0, 1, At, B1); PG8_BAR;
;             PG8_LDA(At, 1, 1); PG8_STAGE(PG8_SA(1, 0), a3, voffA);
;             PG8_BAR; PG8_WAIT_L(0); PG8_MMA(1, 0, At, B0); PG8_BAR; PG8_SCHED;
;             PG8_STAGE(PG8_SB(1, 1), b3 + hstepB, voffB);
;             PG8_WAIT_V(6); PG8_BAR; PG8_MMA(1, 1, At, B1); PG8_BAR;
.LBB0_443:
	s_add_u32 s42, s70, 0xfff80080
	s_addc_u32 s43, s71, -1
	s_cmp_eq_u32 s41, 28
	s_cselect_b32 s75, s33, s43
	s_cselect_b32 s74, s34, s42
	s_cselect_b32 s73, s35, s40
	s_cselect_b32 s72, s38, s39
	s_add_i32 m0, s10, 0xc000
	ds_read_b128 v[160:163], v180
	ds_read_b128 v[164:167], v180 offset:1024
	ds_read_b128 v[168:171], v180 offset:2048
	ds_read_b128 v[172:175], v180 offset:3072
	ds_read_b128 v[182:185], v180 offset:4096
	ds_read_b128 v[186:189], v180 offset:5120
	ds_read_b128 v[190:193], v180 offset:6144
	ds_read_b128 v[194:197], v180 offset:7168
	global_load_lds_dwordx4 v154, s[70:71]
	s_add_i32 m0, s10, 0xe000
	s_nop 0
	global_load_lds_dwordx4 v152, s[70:71]
	s_waitcnt lgkmcnt(8)
	s_barrier
	s_waitcnt lgkmcnt(0)
	s_waitcnt lgkmcnt(0)
	v_mfma_f32_16x16x32_bf16 v[124:127], v[128:131], v[160:163], v[124:127]
	v_mfma_f32_16x16x32_bf16 v[120:123], v[136:139], v[160:163], v[120:123]
	v_mfma_f32_16x16x32_bf16 v[108:111], v[128:131], v[168:171], v[108:111]
	v_mfma_f32_16x16x32_bf16 v[104:107], v[136:139], v[168:171], v[104:107]
	v_mfma_f32_16x16x32_bf16 v[92:95], v[128:131], v[182:185], v[92:95]
	v_mfma_f32_16x16x32_bf16 v[88:91], v[136:139], v[182:185], v[88:91]
	v_mfma_f32_16x16x32_bf16 v[76:79], v[128:131], v[190:193], v[76:79]
	v_mfma_f32_16x16x32_bf16 v[72:75], v[136:139], v[190:193], v[72:75]
	v_mfma_f32_16x16x32_bf16 v[124:127], v[132:135], v[164:167], v[124:127]
	v_mfma_f32_16x16x32_bf16 v[120:123], v[140:143], v[164:167], v[120:123]
	v_mfma_f32_16x16x32_bf16 v[108:111], v[132:135], v[172:175], v[108:111]
	v_mfma_f32_16x16x32_bf16 v[104:107], v[140:143], v[172:175], v[104:107]
	v_mfma_f32_16x16x32_bf16 v[92:95], v[132:135], v[186:189], v[92:95]
	v_mfma_f32_16x16x32_bf16 v[88:91], v[140:143], v[186:189], v[88:91]
	v_mfma_f32_16x16x32_bf16 v[76:79], v[132:135], v[194:197], v[76:79]
	v_mfma_f32_16x16x32_bf16 v[72:75], v[140:143], v[194:197], v[72:75]
	s_barrier
	s_add_i32 s42, s23, s9
	s_add_u32 s98, s72, s54
	s_addc_u32 s99, s73, s55
	s_mov_b32 m0, s42
	ds_read_b128 v[198:201], v181
	ds_read_b128 v[202:205], v181 offset:1024
	ds_read_b128 v[206:209], v181 offset:2048
	ds_read_b128 v[210:213], v181 offset:3072
	global_load_lds_dwordx4 v146, s[72:73]
	s_add_i32 m0, s42, 0x2000
	s_nop 0
	global_load_lds_dwordx4 v150, s[72:73]
	s_barrier
	s_waitcnt lgkmcnt(0)
	s_waitcnt lgkmcnt(0)
	v_mfma_f32_16x16x32_bf16 v[116:119], v[198:201], v[160:163], v[116:119]
	v_mfma_f32_16x16x32_bf16 v[112:115], v[206:209], v[160:163], v[112:115]
	v_mfma_f32_16x16x32_bf16 v[100:103], v[198:201], v[168:171], v[100:103]
	v_mfma_f32_16x16x32_bf16 v[96:99], v[206:209], v[168:171], v[96:99]
	v_mfma_f32_16x16x32_bf16 v[84:87], v[198:201], v[182:185], v[84:87]
	v_mfma_f32_16x16x32_bf16 v[80:83], v[206:209], v[182:185], v[80:83]
	v_mfma_f32_16x16x32_bf16 v[68:71], v[198:201], v[190:193], v[68:71]
	v_mfma_f32_16x16x32_bf16 v[64:67], v[206:209], v[190:193], v[64:67]
	v_mfma_f32_16x16x32_bf16 v[116:119], v[202:205], v[164:167], v[116:119]
	v_mfma_f32_16x16x32_bf16 v[112:115], v[210:213], v[164:167], v[112:115]
	v_mfma_f32_16x16x32_bf16 v[100:103], v[202:205], v[172:175], v[100:103]
	v_mfma_f32_16x16x32_bf16 v[96:99], v[210:213], v[172:175], v[96:99]
	v_mfma_f32_16x16x32_bf16 v[84:87], v[202:205], v[186:189], v[84:87]
	v_mfma_f32_16x16x32_bf16 v[80:83], v[210:213], v[186:189], v[80:83]
	v_mfma_f32_16x16x32_bf16 v[68:71], v[202:205], v[194:197], v[68:71]
	v_mfma_f32_16x16x32_bf16 v[64:67], v[210:213], v[194:197], v[64:67]
	s_mov_b32 m0, s10
	s_add_u32 s100, s74, s54
	s_addc_u32 s101, s75, s55
	s_barrier
	ds_read_b128 v[160:163], v180 offset:16384
	ds_read_b128 v[164:167], v180 offset:17408
	ds_read_b128 v[168:171], v180 offset:18432
	ds_read_b128 v[172:175], v180 offset:19456
	ds_read_b128 v[182:185], v180 offset:20480
	ds_read_b128 v[186:189], v180 offset:21504
	ds_read_b128 v[190:193], v180 offset:22528
	ds_read_b128 v[194:197], v180 offset:23552
	global_load_lds_dwordx4 v144, s[74:75]
	s_mov_b32 m0, s11
	s_nop 0
	global_load_lds_dwordx4 v148, s[74:75]
	s_waitcnt vmcnt(10)
	s_barrier
	s_waitcnt lgkmcnt(0)
	s_waitcnt lgkmcnt(0)
	v_mfma_f32_16x16x32_bf16 v[60:63], v[128:131], v[160:163], v[60:63]
	v_mfma_f32_16x16x32_bf16 v[56:59], v[136:139], v[160:163], v[56:59]
	v_mfma_f32_16x16x32_bf16 v[44:47], v[128:131], v[168:171], v[44:47]
	v_mfma_f32_16x16x32_bf16 v[40:43], v[136:139], v[168:171], v[40:43]
	v_mfma_f32_16x16x32_bf16 v[28:31], v[128:131], v[182:185], v[28:31]
	v_mfma_f32_16x16x32_bf16 v[24:27], v[136:139], v[182:185], v[24:27]
	v_mfma_f32_16x16x32_bf16 v[12:15], v[128:131], v[190:193], v[12:15]
	v_mfma_f32_16x16x32_bf16 v[8:11], v[136:139], v[190:193], v[8:11]
	v_mfma_f32_16x16x32_bf16 v[60:63], v[132:135], v[164:167], v[60:63]
	v_mfma_f32_16x16x32_bf16 v[56:59], v[140:143], v[164:167], v[56:59]
	v_mfma_f32_16x16x32_bf16 v[44:47], v[132:135], v[172:175], v[44:47]
	v_mfma_f32_16x16x32_bf16 v[40:43], v[140:143], v[172:175], v[40:43]
	v_mfma_f32_16x16x32_bf16 v[28:31], v[132:135], v[186:189], v[28:31]
	v_mfma_f32_16x16x32_bf16 v[24:27], v[140:143], v[186:189], v[24:27]
	v_mfma_f32_16x16x32_bf16 v[12:15], v[132:135], v[194:197], v[12:15]
	v_mfma_f32_16x16x32_bf16 v[8:11], v[140:143], v[194:197], v[8:11]
	s_barrier
	s_add_u32 s42, s72, 0x80000
	s_addc_u32 s43, s73, 0
	s_add_i32 s44, s24, s9
	s_mov_b32 m0, s44
	s_nop 0
	global_load_lds_dwordx4 v146, s[42:43]
	s_add_i32 m0, s44, 0x2000
	s_nop 0
	global_load_lds_dwordx4 v150, s[42:43]
	s_add_i32 s44, 0, 0x18000
	v_add_u32_e32 v140, s44, v177
	ds_read_b128 v[128:131], v140
	ds_read_b128 v[132:135], v140 offset:1024
	ds_read_b128 v[136:139], v140 offset:2048
	ds_read_b128 v[140:143], v140 offset:3072
	s_waitcnt vmcnt(6)
	s_barrier
; #define PG8_STAGE(bufoff, gbase, voff) do { _Pragma("unroll") for (int _i = 0; _i < 2; ++_i) \
;         __builtin_amdgcn_global_load_lds((const unsigned*)((const char*)(gbase) + (voff)[_i]), (LAS unsigned*)(lds + (bufoff) + ldsw + _i * 8192), 16, 0, 0); } while (0)
; #define PG8_LDA(dst, b, h) do { _Pragma("unroll") for (int m = 0; m < 4; ++m) _Pragma("unroll") for (int k = 0; k < 2; ++k) dst[m][k] = *(const LAS bf16x8*)(lds + PG8_SA(b, h) + aoff + m * 2048 + k * 1024); } while (0)
; #define PG8_WAIT_V(n) asm volatile("s_waitcnt vmcnt(" #n ")" ::: "memory")
; #define PG8_BAR __builtin_amdgcn_s_barrier()
; template <class Epi>
; __device__ __forceinline__ void gemm_phase(LAS unsigned char* lds, const Gemm g, const StaticOrder& S, const Epi& E, int wv) {
;     ...
;         for (int t = 0; t < nt; t += 2) {
;             const bool last = (t == nt - 2);
;             const char* a1 = cA + (ptrdiff_t)(t + 1) * kstep;
;             const char* a2 = last ? nA : cA + (ptrdiff_t)(t + 2) * kstep; const char* b2 = last ? nB : cB + (ptrdiff_t)(t + 2) * kstep;
;             const char* a3 = a2 + kstep; const char* b3 = b2 + kstep;
;             PG8_LDB(B0, 0, 0); PG8_SCHED; PG8_LDA(At, 0, 0); PG8_STAGE(PG8_SA(1, 1), a1 + hstepA, voffA);
;             PG8_WAIT_L(8); PG8_BAR; PG8_WAIT_L(0); PG8_MMA(0, 0, At, B0); PG8_BAR; PG8_SCHED;
;             PG8_LDB(B1, 0, 1); PG8_STAGE(PG8_SB(0, 0), b2, voffB);
;             PG8_BAR; PG8_WAIT_L(0); PG8_MMA(0, 1, At, B1); PG8_BAR;
;             PG8_LDA(At, 0, 1); PG8_STAGE(PG8_SA(0, 0), a2, voffA);
;             PG8_BAR; PG8_WAIT_L(0); PG8_MMA(1, 0, At, B0); PG8_BAR; PG8_SCHED;
;             PG8_STAGE(PG8_SB(0, 1), b2 + hstepB, voffB);
;             PG8_WAIT_V(6); PG8_BAR; PG8_MMA(1, 1, At, B1); PG8_BAR;
;             PG8_LDB(B0, 1, 0); PG8_SCHED; PG8_LDA(At, 1, 0); PG8_STAGE(PG8_SA(0, 1), a2 + hstepA, voffA);
;             PG8_WAIT_L(8); PG8_BAR; PG8_WAIT_L(0); PG8_MMA(0, 0, At, B0); PG8_BAR; PG8_SCHED;
;             PG8_LDB(B1, 1, 1); PG8_STAGE(PG8_SB(1, 0), b3, voffB);
;             PG8_BAR; PG8_WAIT_L(0); PG8_MMA(0, 1, At, B1); PG8_BAR;
;             PG8_LDA(At, 1, 1); PG8_STAGE(PG8_SA(1, 0), a3, voffA);
;             PG8_BAR; PG8_WAIT_L(0); PG8_MMA(1, 0, At, B0); PG8_BAR; PG8_SCHED;
;             PG8_STAGE(PG8_SB(1, 1), b3 + hstepB, voffB);
;             PG8_WAIT_V(6); PG8_BAR; PG8_MMA(1, 1, At, B1); PG8_BAR;
	v_mfma_f32_16x16x32_bf16 v[52:55], v[198:201], v[160:163], v[52:55]
	v_mfma_f32_16x16x32_bf16 v[48:51], v[206:209], v[160:163], v[48:51]
	v_mfma_f32_16x16x32_bf16 v[36:39], v[198:201], v[168:171], v[36:39]
	v_mfma_f32_16x16x32_bf16 v[32:35], v[206:209], v[168:171], v[32:35]
	v_mfma_f32_16x16x32_bf16 v[20:23], v[198:201], v[182:185], v[20:23]
	v_mfma_f32_16x16x32_bf16 v[16:19], v[206:209], v[182:185], v[16:19]
	v_mfma_f32_16x16x32_bf16 v[4:7], v[198:201], v[190:193], v[4:7]
	v_mfma_f32_16x16x32_bf16 v[0:3], v[206:209], v[190:193], v[0:3]
	v_mfma_f32_16x16x32_bf16 v[52:55], v[202:205], v[164:167], v[52:55]
	v_mfma_f32_16x16x32_bf16 v[48:51], v[210:213], v[164:167], v[48:51]
	v_mfma_f32_16x16x32_bf16 v[36:39], v[202:205], v[172:175], v[36:39]
	v_mfma_f32_16x16x32_bf16 v[32:35], v[210:213], v[172:175], v[32:35]
	v_mfma_f32_16x16x32_bf16 v[20:23], v[202:205], v[186:189], v[20:23]
	v_mfma_f32_16x16x32_bf16 v[16:19], v[210:213], v[186:189], v[16:19]
	v_mfma_f32_16x16x32_bf16 v[4:7], v[202:205], v[194:197], v[4:7]
	v_mfma_f32_16x16x32_bf16 v[0:3], v[210:213], v[194:197], v[0:3]
	s_waitcnt lgkmcnt(0)
	s_barrier
	s_add_u32 s42, s74, 0x80000
	s_addc_u32 s43, s75, 0
	s_mov_b32 m0, s12
	ds_read_b128 v[160:163], v180 offset:32768
	ds_read_b128 v[164:167], v180 offset:33792
	ds_read_b128 v[168:171], v180 offset:34816
	ds_read_b128 v[172:175], v180 offset:35840
	ds_read_b128 v[182:185], v180 offset:36864
	ds_read_b128 v[186:189], v180 offset:37888
	ds_read_b128 v[190:193], v180 offset:38912
	ds_read_b128 v[194:197], v180 offset:39936
	global_load_lds_dwordx4 v144, s[42:43]
	s_mov_b32 m0, s13
	s_nop 0
	global_load_lds_dwordx4 v148, s[42:43]
	s_waitcnt lgkmcnt(8)
	s_barrier
	s_waitcnt lgkmcnt(0)
	s_waitcnt lgkmcnt(0)
	v_mfma_f32_16x16x32_bf16 v[124:127], v[128:131], v[160:163], v[124:127]
	v_mfma_f32_16x16x32_bf16 v[120:123], v[136:139], v[160:163], v[120:123]
	v_mfma_f32_16x16x32_bf16 v[108:111], v[128:131], v[168:171], v[108:111]
	v_mfma_f32_16x16x32_bf16 v[104:107], v[136:139], v[168:171], v[104:107]
	v_mfma_f32_16x16x32_bf16 v[92:95], v[128:131], v[182:185], v[92:95]
	v_mfma_f32_16x16x32_bf16 v[88:91], v[136:139], v[182:185], v[88:91]
	v_mfma_f32_16x16x32_bf16 v[76:79], v[128:131], v[190:193], v[76:79]
	v_mfma_f32_16x16x32_bf16 v[72:75], v[136:139], v[190:193], v[72:75]
	v_mfma_f32_16x16x32_bf16 v[124:127], v[132:135], v[164:167], v[124:127]
	v_mfma_f32_16x16x32_bf16 v[120:123], v[140:143], v[164:167], v[120:123]
	v_mfma_f32_16x16x32_bf16 v[108:111], v[132:135], v[172:175], v[108:111]
	v_mfma_f32_16x16x32_bf16 v[104:107], v[140:143], v[172:175], v[104:107]
	v_mfma_f32_16x16x32_bf16 v[92:95], v[132:135], v[186:189], v[92:95]
	v_mfma_f32_16x16x32_bf16 v[88:91], v[140:143], v[186:189], v[88:91]
	v_mfma_f32_16x16x32_bf16 v[76:79], v[132:135], v[194:197], v[76:79]
	v_mfma_f32_16x16x32_bf16 v[72:75], v[140:143], v[194:197], v[72:75]
	s_barrier
	s_add_i32 s45, 0, 0x1c000
	s_add_i32 s42, s44, s9
	v_add_u32_e32 v210, s45, v177
	s_mov_b32 m0, s42
	ds_read_b128 v[198:201], v210
	ds_read_b128 v[202:205], v210 offset:1024
	ds_read_b128 v[206:209], v210 offset:2048
	ds_read_b128 v[210:213], v210 offset:3072
	global_load_lds_dwordx4 v146, s[98:99]
	s_add_i32 m0, s42, 0x2000
	s_nop 0
	global_load_lds_dwordx4 v150, s[98:99]
	s_barrier
	s_waitcnt lgkmcnt(0)
	s_waitcnt lgkmcnt(0)
	v_mfma_f32_16x16x32_bf16 v[116:119], v[198:201], v[160:163], v[116:119]
	v_mfma_f32_16x16x32_bf16 v[112:115], v[206:209], v[160:163], v[112:115]
	v_mfma_f32_16x16x32_bf16 v[100:103], v[198:201], v[168:171], v[100:103]
	v_mfma_f32_16x16x32_bf16 v[96:99], v[206:209], v[168:171], v[96:99]
	v_mfma_f32_16x16x32_bf16 v[84:87], v[198:201], v[182:185], v[84:87]
	v_mfma_f32_16x16x32_bf16 v[80:83], v[206:209], v[182:185], v[80:83]
	v_mfma_f32_16x16x32_bf16 v[68:71], v[198:201], v[190:193], v[68:71]
	v_mfma_f32_16x16x32_bf16 v[64:67], v[206:209], v[190:193], v[64:67]
	v_mfma_f32_16x16x32_bf16 v[116:119], v[202:205], v[164:167], v[116:119]
	v_mfma_f32_16x16x32_bf16 v[112:115], v[210:213], v[164:167], v[112:115]
	v_mfma_f32_16x16x32_bf16 v[100:103], v[202:205], v[172:175], v[100:103]
	v_mfma_f32_16x16x32_bf16 v[96:99], v[210:213], v[172:175], v[96:99]
	v_mfma_f32_16x16x32_bf16 v[84:87], v[202:205], v[186:189], v[84:87]
	v_mfma_f32_16x16x32_bf16 v[80:83], v[210:213], v[186:189], v[80:83]
	v_mfma_f32_16x16x32_bf16 v[68:71], v[202:205], v[194:197], v[68:71]
	v_mfma_f32_16x16x32_bf16 v[64:67], v[210:213], v[194:197], v[64:67]
	s_mov_b32 m0, s15
	s_barrier
	ds_read_b128 v[160:163], v180 offset:49152
	ds_read_b128 v[164:167], v180 offset:50176
	ds_read_b128 v[168:171], v180 offset:51200
	ds_read_b128 v[172:175], v180 offset:52224
	ds_read_b128 v[182:185], v180 offset:53248
	ds_read_b128 v[186:189], v180 offset:54272
	ds_read_b128 v[190:193], v180 offset:55296
	ds_read_b128 v[194:197], v180 offset:56320
	global_load_lds_dwordx4 v144, s[100:101]
	s_mov_b32 m0, s22
	s_nop 0
	global_load_lds_dwordx4 v148, s[100:101]
	s_waitcnt vmcnt(10)
	s_barrier
	s_waitcnt lgkmcnt(0)
	s_waitcnt lgkmcnt(0)
	v_mfma_f32_16x16x32_bf16 v[60:63], v[128:131], v[160:163], v[60:63]
	v_mfma_f32_16x16x32_bf16 v[56:59], v[136:139], v[160:163], v[56:59]
	v_mfma_f32_16x16x32_bf16 v[44:47], v[128:131], v[168:171], v[44:47]
	v_mfma_f32_16x16x32_bf16 v[40:43], v[136:139], v[168:171], v[40:43]
	v_mfma_f32_16x16x32_bf16 v[28:31], v[128:131], v[182:185], v[28:31]
	v_mfma_f32_16x16x32_bf16 v[24:27], v[136:139], v[182:185], v[24:27]
	v_mfma_f32_16x16x32_bf16 v[12:15], v[128:131], v[190:193], v[12:15]
	v_mfma_f32_16x16x32_bf16 v[8:11], v[136:139], v[190:193], v[8:11]
	v_mfma_f32_16x16x32_bf16 v[60:63], v[132:135], v[164:167], v[60:63]
	v_mfma_f32_16x16x32_bf16 v[56:59], v[140:143], v[164:167], v[56:59]
	v_mfma_f32_16x16x32_bf16 v[44:47], v[132:135], v[172:175], v[44:47]
	v_mfma_f32_16x16x32_bf16 v[40:43], v[140:143], v[172:175], v[40:43]
	v_mfma_f32_16x16x32_bf16 v[28:31], v[132:135], v[186:189], v[28:31]
	v_mfma_f32_16x16x32_bf16 v[24:27], v[140:143], v[186:189], v[24:27]
	v_mfma_f32_16x16x32_bf16 v[12:15], v[132:135], v[194:197], v[12:15]
	v_mfma_f32_16x16x32_bf16 v[8:11], v[140:143], v[194:197], v[8:11]
	s_barrier
; template <class Epi>
; __device__ __forceinline__ void gemm_phase(LAS unsigned char* lds, const Gemm g, const StaticOrder& S, const Epi& E, int wv) {
;     ...
;             PG8_WAIT_V(6); PG8_BAR; PG8_MMA(1, 1, At, B1); PG8_BAR;
;         }
;     __device__ __forceinline__ void operator()(const f32x4 (&acc)[2][2][4][2], const Unit& u, int wr, int wc, int fr, int fq) const {
;         const int row0 = u.pm * BM + wr * 64 + fr, col0 = u.pn * BM + wc * 32 + 8 * fq;
;         constexpr int RD = 3;
;         f32x4 hbuf[RD][4]; u32x4 hraw[RD][2]; u32x4 pbuf[RD][2]; float rsb[RD];
;     ...
;         RES_LOAD(0, 0); RES_LOAD(1, 1);
; #pragma unroll
;         for (int it = 0; it < 8; ++it) { const int ai = it >> 2, m = it & 3, sc = it % RD;
;             if (it + RD - 1 < 8) RES_LOAD((it + RD - 1) % RD, it + RD - 1);
;             asm volatile("" ::: "memory");
;             const int row = row0 + ai * HALF + m * 16; const size_t ro = (size_t)row * DM + col0;
;             float rs = 1.0f; if (MODE == 1) rs = __builtin_amdgcn_rsqf(ss_fix(rsb[sc]) * (1.0f / DM) + EPS);
;             float sq = 0.f;
; #pragma unroll
;             for (int bj = 0; bj < 2; ++bj) { const size_t off = ro + bj * HALF;
;                 f32x4 v0 = acc[ai][bj][m][0], v1 = acc[ai][bj][m][1];
;                 if (MODE == 1) { const u32x4 pw = pbuf[sc][bj];
;                     v0[0] = fast_sigmoid(rs * v0[0]) * bf_lo(pw.x); v0[1] = fast_sigmoid(rs * v0[1]) * bf_hi(pw.x); v0[2] = fast_sigmoid(rs * v0[2]) * bf_lo(pw.y); v0[3] = fast_sigmoid(rs * v0[3]) * bf_hi(pw.y);
;                     v1[0] = fast_sigmoid(rs * v1[0]) * bf_lo(pw.z); v1[1] = fast_sigmoid(rs * v1[1]) * bf_hi(pw.z); v1[2] = fast_sigmoid(rs * v1[2]) * bf_lo(pw.w); v1[3] = fast_sigmoid(rs * v1[3]) * bf_hi(pw.w); }
;                 f32x4 h0, h1;
;                 if (IN16) { const u32x4 hw = hraw[sc][bj]; h0 = (f32x4){bf_lo(hw.x), bf_hi(hw.x), bf_lo(hw.y), bf_hi(hw.y)}; h1 = (f32x4){bf_lo(hw.z), bf_hi(hw.z), bf_lo(hw.w), bf_hi(hw.w)}; }
;                 else { h0 = hbuf[sc][2 * bj]; h1 = hbuf[sc][2 * bj + 1]; }
;                 const f32x4 o0 = h0 + v0, o1 = h1 + v1;
;                 if (OUT32) { *(f32x4*)(hout + off) = o0; *(f32x4*)(hout + off + 4) = o1; }
;                 if (hb) { u32x4 w; w.x = pk_bf16(o0[0], o0[1]); w.y = pk_bf16(o0[2], o0[3]); w.z = pk_bf16(o1[0], o1[1]); w.w = pk_bf16(o1[2], o1[3]); *(u32x4*)(hb + off) = w; }
	s_add_u32 s42, s72, 0x80080
	s_addc_u32 s43, s73, 0
	s_add_i32 s44, s45, s9
	s_mov_b32 m0, s44
	s_nop 0
	global_load_lds_dwordx4 v146, s[42:43]
	s_add_i32 m0, s44, 0x2000
	s_nop 0
	global_load_lds_dwordx4 v150, s[42:43]
	ds_read_b128 v[128:131], v179
	ds_read_b128 v[132:135], v179 offset:1024
	ds_read_b128 v[136:139], v179 offset:2048
	ds_read_b128 v[140:143], v179 offset:3072
	s_waitcnt vmcnt(6)
	s_barrier
	v_mfma_f32_16x16x32_bf16 v[52:55], v[198:201], v[160:163], v[52:55]
	v_mfma_f32_16x16x32_bf16 v[48:51], v[206:209], v[160:163], v[48:51]
	v_mfma_f32_16x16x32_bf16 v[36:39], v[198:201], v[168:171], v[36:39]
	v_mfma_f32_16x16x32_bf16 v[32:35], v[206:209], v[168:171], v[32:35]
	v_mfma_f32_16x16x32_bf16 v[20:23], v[198:201], v[182:185], v[20:23]
	v_mfma_f32_16x16x32_bf16 v[16:19], v[206:209], v[182:185], v[16:19]
	v_mfma_f32_16x16x32_bf16 v[4:7], v[198:201], v[190:193], v[4:7]
	v_mfma_f32_16x16x32_bf16 v[0:3], v[206:209], v[190:193], v[0:3]
	v_mfma_f32_16x16x32_bf16 v[52:55], v[202:205], v[164:167], v[52:55]
	v_mfma_f32_16x16x32_bf16 v[48:51], v[210:213], v[164:167], v[48:51]
	v_mfma_f32_16x16x32_bf16 v[36:39], v[202:205], v[172:175], v[36:39]
	v_mfma_f32_16x16x32_bf16 v[32:35], v[210:213], v[172:175], v[32:35]
	v_mfma_f32_16x16x32_bf16 v[20:23], v[202:205], v[186:189], v[20:23]
	v_mfma_f32_16x16x32_bf16 v[16:19], v[210:213], v[186:189], v[16:19]
	v_mfma_f32_16x16x32_bf16 v[4:7], v[202:205], v[194:197], v[4:7]
	v_mfma_f32_16x16x32_bf16 v[0:3], v[210:213], v[194:197], v[0:3]
	s_waitcnt lgkmcnt(0)
	s_add_i32 s41, s41, 2
	s_add_u32 s39, s39, 0x100
	s_addc_u32 s40, s40, 0
	s_add_u32 s70, s70, 0x100
	s_addc_u32 s71, s71, 0
	s_cmp_gt_u32 s41, 29
	s_barrier
	s_cbranch_scc0 .LBB0_443
	v_lshl_add_u32 v170, s66, 8, v176
	v_lshl_or_b32 v160, s68, 8, v178
	v_ashrrev_i32_e32 v171, 31, v170
	v_ashrrev_i32_e32 v161, 31, v160
	v_lshlrev_b64 v[190:191], 12, v[170:171]
	v_lshl_add_u64 v[128:129], s[30:31], 0, v[190:191]
	v_lshlrev_b64 v[162:163], 1, v[160:161]
	v_lshl_add_u64 v[164:165], v[128:129], 0, v[162:163]
	global_load_dwordx4 v[182:185], v[164:165], off
	global_load_dwordx4 v[186:189], v[164:165], off offset:256
	v_or_b32_e32 v172, 16, v170
	v_or_b32_e32 v166, 32, v170
	v_ashrrev_i32_e32 v173, 31, v172
	v_ashrrev_i32_e32 v167, 31, v166
	v_lshlrev_b64 v[174:175], 12, v[172:173]
	v_lshlrev_b64 v[168:169], 12, v[166:167]
	v_lshl_add_u64 v[128:129], s[30:31], 0, v[174:175]
	v_lshl_add_u64 v[130:131], s[30:31], 0, v[168:169]
	v_lshl_add_u64 v[128:129], v[128:129], 0, v[162:163]
	v_lshl_add_u64 v[130:131], v[130:131], 0, v[162:163]
	global_load_dwordx4 v[140:143], v[128:129], off
	global_load_dwordx4 v[136:139], v[128:129], off offset:256
	global_load_dwordx4 v[132:135], v[130:131], off
	s_nop 0
	global_load_dwordx4 v[128:131], v[130:131], off offset:256
	s_waitcnt vmcnt(0)
	v_lshlrev_b32_e32 v192, 16, v182
	v_and_b32_e32 v193, 0xffff0000, v182
	v_lshlrev_b32_e32 v182, 16, v183
	v_and_b32_e32 v183, 0xffff0000, v183
	v_lshlrev_b32_e32 v194, 16, v184
	v_and_b32_e32 v195, 0xffff0000, v184
	v_lshlrev_b32_e32 v184, 16, v185
	v_and_b32_e32 v185, 0xffff0000, v185
	v_lshlrev_b32_e32 v196, 16, v186
	v_and_b32_e32 v197, 0xffff0000, v186
	v_lshlrev_b32_e32 v186, 16, v187
	v_and_b32_e32 v187, 0xffff0000, v187
	v_lshlrev_b32_e32 v198, 16, v188
	v_and_b32_e32 v199, 0xffff0000, v188
	v_lshlrev_b32_e32 v188, 16, v189
	v_and_b32_e32 v189, 0xffff0000, v189
	v_pk_add_f32 v[126:127], v[126:127], v[182:183]
	v_pk_add_f32 v[124:125], v[124:125], v[192:193]
	v_pk_add_f32 v[122:123], v[122:123], v[184:185]
	v_pk_add_f32 v[120:121], v[120:121], v[194:195]
	v_pk_add_f32 v[118:119], v[118:119], v[186:187]
	v_pk_add_f32 v[116:117], v[116:117], v[196:197]
	v_pk_add_f32 v[182:183], v[114:115], v[188:189]
	v_pk_add_f32 v[184:185], v[112:113], v[198:199]
	v_cvt_pk_bf16_f32 v112, v124, v125
	v_cvt_pk_bf16_f32 v113, v126, v127
	v_cvt_pk_bf16_f32 v114, v120, v121
	v_cvt_pk_bf16_f32 v115, v122, v123
	v_mul_f32_e32 v125, v125, v125
	v_mul_f32_e32 v127, v127, v127
	v_mul_f32_e32 v121, v121, v121
	v_mul_f32_e32 v123, v123, v123
	v_mul_f32_e32 v186, v117, v117
	v_mul_f32_e32 v187, v119, v119
	v_mul_f32_e32 v188, v185, v185
	v_mul_f32_e32 v189, v183, v183
	v_fmac_f32_e32 v125, v124, v124
	v_fmac_f32_e32 v127, v126, v126
	v_fmac_f32_e32 v121, v120, v120
	v_fmac_f32_e32 v123, v122, v122
	v_fmac_f32_e32 v186, v116, v116
	v_fmac_f32_e32 v187, v118, v118
	v_fmac_f32_e32 v188, v184, v184
	v_fmac_f32_e32 v189, v182, v182
	v_add_f32_e32 v120, v125, v127
	v_add_f32_e32 v121, v121, v123
	v_add_f32_e32 v122, v186, v187
	v_add_f32_e32 v123, v188, v189
	v_add_f32_e32 v120, v120, v121
	v_add_f32_e32 v121, v122, v123
	v_add_f32_e32 v122, v120, v121
	ds_bpermute_b32 v123, v245, v122
	v_lshl_add_u64 v[120:121], s[50:51], 0, v[190:191]
	v_lshl_add_u64 v[120:121], v[120:121], 0, v[162:163]
	global_store_dwordx4 v[120:121], v[112:115], off
	s_waitcnt lgkmcnt(0)
	s_nop 0
	v_add_f32_e32 v112, v122, v123
	ds_bpermute_b32 v113, v244, v112
	v_cvt_pk_bf16_f32 v114, v116, v117
	v_cvt_pk_bf16_f32 v115, v118, v119
	v_cvt_pk_bf16_f32 v116, v184, v185
	v_cvt_pk_bf16_f32 v117, v182, v183
	global_store_dwordx4 v[120:121], v[114:117], off offset:256
	s_and_saveexec_b64 s[66:67], s[16:17]
	s_cbranch_execz .LBB0_446
	s_waitcnt lgkmcnt(0)
	v_add_f32_e32 v112, v112, v113
	v_fma_f32 v112, v112, s25, 0.5
	v_cvt_u32_f32_e32 v114, v112
	v_lshl_add_u64 v[112:113], v[170:171], 2, s[52:53]
	global_atomic_add v[112:113], v114, off

; __device__ __forceinline__ int opaque_tid(int wv) { int l; asm volatile("v_mbcnt_lo_u32_b32 %0, -1, 0\n\tv_mbcnt_hi_u32_b32 %0, -1, %0" : "=v"(l)); return wv * 64 + l; }
; #define PG8_BAR __builtin_amdgcn_s_barrier()
; template <class Epi>
; __device__ __forceinline__ void gemm_phase(LAS unsigned char* lds, const Gemm g, const StaticOrder& S, const Epi& E, int wv) {
;     const int tid = opaque_tid(wv), wid = __builtin_amdgcn_readfirstlane(tid >> 6), lane = tid & 63, wr = wid >> 2, wc = wid & 3, fr = lane & 15, fq = lane >> 4;
;     const int K = g.K, nt = K / BK;
;     unsigned voffA[2], voffB[2];
; #pragma unroll
;     for (int i = 0; i < 2; ++i) { int R, C; stage_rc(tid * 16 + i * 8192, R, C); const int Rb = Epi::PERM ? ((R & ~31) + perm32(R & 31)) : R;
;         voffA[i] = (unsigned)(R * g.lda + C) * 2u; voffB[i] = (unsigned)(Rb * g.ldb + C) * 2u; }
;     const bool krev = (g.adiag & 2) != 0;
;     const ptrdiff_t kstep = krev ? -(ptrdiff_t)(BK * 2) : (ptrdiff_t)(BK * 2);
;     const size_t kbeg = krev ? (size_t)(nt - 1) * (BK * 2) : 0;
;     const size_t hstepA = (size_t)HALF * g.lda * 2, hstepB = (size_t)HALF * g.ldb * 2;
;     const size_t tstepA = 2 * hstepA, tstepB = 2 * hstepB;
;     const unsigned ldsw = (unsigned)wid * 1024u;
;     const int aoff = lds_byte(wr * 64 + fr, fq * 8), boff = lds_byte(wc * 32 + fr, fq * 8);
;     ...
;     Unit cur, nxt; int ui = 0;
;     if (!S.next(0, cur)) return;
;     f32x4 acc[2][2][4][2];
; #pragma unroll
;     for (int a = 0; a < 2; ++a)
; #pragma unroll
;         for (int b = 0; b < 2; ++b)
; #pragma unroll
;             for (int m = 0; m < 4; ++m)
; #pragma unroll
;                 for (int n = 0; n < 2; ++n) acc[a][b][m][n] = (f32x4){0.f, 0.f, 0.f, 0.f};
;     bf16x8 At[4][2], B0[2][2], B1[2][2];
;     const char* cA = (const char*)g.A + (size_t)cur.pm * tstepA + ((g.adiag & 1) ? (size_t)(cur.pn >> 1) * K * 2 : 0) + kbeg;
;     const char* cB = (const char*)g.Bt + (size_t)cur.pn * tstepB + kbeg;
;     PG8_STAGE(PG8_SB(0, 0), cB, voffB); PG8_STAGE(PG8_SA(0, 0), cA, voffA); PG8_STAGE(PG8_SB(0, 1), cB + hstepB, voffB); PG8_STAGE(PG8_SA(0, 1), cA + hstepA, voffA);
;     if (wr == 1) PG8_BAR;
;     PG8_WAIT_V(4); PG8_BAR;
;     PG8_STAGE(PG8_SB(1, 0), cB + kstep, voffB); PG8_STAGE(PG8_SA(1, 0), cA + kstep, voffA); PG8_STAGE(PG8_SB(1, 1), cB + hstepB + kstep, voffB);
;     PG8_WAIT_V(6); PG8_BAR;
.LBB0_520:
	v_ashrrev_i32_e32 v2, 31, v0
	v_lshrrev_b32_e32 v2, 26, v2
	v_lshlrev_b32_e32 v1, 4, v0
	v_add_u32_e32 v2, v0, v2
	v_bfe_i32 v0, v0, 27, 1
	v_lshrrev_b32_e32 v0, 22, v0
	v_add_u32_e32 v0, v1, v0
	v_and_b32_e32 v0, 0xfffffc00, v0
	v_sub_u32_e32 v0, v1, v0
	v_ashrrev_i32_e32 v9, 6, v2
	v_lshrrev_b32_e32 v2, 4, v0
	v_bitop3_b32 v0, v2, v0, 32 bitop3:0x6c
	v_ashrrev_i32_e32 v3, 31, v0
	v_lshrrev_b32_e32 v3, 26, v3
	v_add_u32_e32 v3, v0, v3
	v_lshlrev_b32_e32 v2, 3, v9
	v_ashrrev_i32_e32 v10, 6, v3
	v_and_b32_e32 v3, 0xc0, v3
	v_and_b32_e32 v2, -16, v2
	v_sub_u32_e32 v0, v0, v3
	v_mov_b32_e32 v3, 1
	v_add_u32_e32 v2, v10, v2
	v_ashrrev_i16_sdwa v0, v3, sext(v0) dst_sel:DWORD dst_unused:UNUSED_PAD src0_sel:DWORD src1_sel:BYTE_0
	s_ashr_i32 s11, s5, 3
	v_lshlrev_b32_e32 v4, 5, v9
	v_bfe_i32 v11, v0, 0, 16
	v_lshlrev_b32_e32 v0, 1, v2
	v_lshrrev_b32_e32 v5, 2, v2
	v_and_b32_e32 v6, 3, v10
	s_mov_b32 s9, 0xfffe0
	s_waitcnt lgkmcnt(0)
	s_add_u32 s5, s52, 0xb300000
	v_and_b32_e32 v4, 32, v4
	v_and_b32_e32 v0, 24, v0
	v_and_b32_e32 v5, 4, v5
	v_and_or_b32 v6, v2, s9, v6
	s_addc_u32 s6, s53, 0
	v_or3_b32 v0, v6, v5, v0
	v_add_lshl_u32 v4, v4, v11, 1
	s_add_u32 s7, s50, 0x2900000
	v_lshl_add_u32 v130, v0, 12, v4
	v_add_u32_e32 v0, 0x2000, v1
	s_addc_u32 s8, s51, 0
	v_ashrrev_i32_e32 v1, 31, v0
	s_add_i32 s10, s10, s11
	v_lshrrev_b32_e32 v1, 22, v1
	s_ashr_i32 s11, s10, 31
	v_add_u32_e32 v1, v0, v1
	s_lshr_b32 s11, s11, 24
	v_ashrrev_i32_e32 v12, 10, v1
	s_add_i32 s11, s10, s11
	v_mul_i32_i24_e32 v1, 0x400, v12
	s_ashr_i32 s12, s11, 8
	s_and_b32 s11, s11, 0xffffff00
	v_sub_u32_e32 v0, v0, v1
	s_sub_i32 s10, s10, s11
	v_lshrrev_b32_e32 v1, 4, v0
	s_sext_i32_i16 s11, s10
	v_bitop3_b32 v0, v1, v0, 32 bitop3:0x6c
	s_bfe_u32 s11, s11, 0x3001c
	v_lshl_add_u32 v128, v2, 12, v4
	v_ashrrev_i32_e32 v2, 31, v0
	s_add_i32 s11, s10, s11
	v_lshrrev_b32_e32 v2, 26, v2
	s_sext_i32_i16 s13, s11
	s_and_b32 s11, s11, 0xfff8
	v_add_u32_e32 v2, v0, v2
	s_sub_i32 s10, s10, s11
	v_lshlrev_b32_e32 v1, 3, v12
	v_ashrrev_i32_e32 v13, 6, v2
	v_and_b32_e32 v2, 0xc0, v2
	s_lshl_b32 s12, s12, 3
	s_sext_i32_i16 s10, s10
	v_and_b32_e32 v1, -16, v1
	v_sub_u32_e32 v0, v0, v2
	s_lshr_b32 s54, s13, 3
	s_add_i32 s64, s12, s10
	v_add_u32_e32 v1, v13, v1
	v_ashrrev_i16_sdwa v0, v3, sext(v0) dst_sel:DWORD dst_unused:UNUSED_PAD src0_sel:DWORD src1_sel:BYTE_0
	v_and_b32_e32 v3, 3, v13
	s_ashr_i32 s15, s4, 6
	s_ashr_i32 s65, s64, 31
	s_bfe_i64 s[10:11], s[54:55], 0x100000
	s_ashr_i32 s23, s4, 8
	v_and_or_b32 v3, v1, s9, v3
	s_lshl_b32 s9, s15, 10
	s_lshl_b64 s[12:13], s[64:65], 20
	s_lshl_b64 s[10:11], s[10:11], 20
	s_add_u32 s66, s7, s10
	v_lshlrev_b32_e32 v4, 5, v12
	v_bfe_i32 v14, v0, 0, 16
	v_lshlrev_b32_e32 v0, 1, v1
	v_lshrrev_b32_e32 v2, 2, v1
	s_addc_u32 s67, s8, s11
	s_add_i32 s10, s9, 0
	v_and_b32_e32 v4, 32, v4
	v_and_b32_e32 v0, 24, v0
	v_and_b32_e32 v2, 4, v2
	s_add_i32 m0, s10, 0x10000
	v_or3_b32 v0, v3, v2, v0
	v_add_lshl_u32 v2, v4, v14, 1
	global_load_lds_dwordx4 v130, s[66:67]
	s_add_i32 m0, s10, 0x12000
	v_lshl_add_u32 v134, v0, 12, v2
	s_add_u32 s68, s5, s12
	global_load_lds_dwordx4 v134, s[66:67]
	s_addc_u32 s69, s6, s13
	s_mov_b32 m0, s10
	s_add_i32 s11, s10, 0x2000
	v_lshl_add_u32 v132, v1, 12, v2
	global_load_lds_dwordx4 v128, s[68:69]
	s_mov_b32 m0, s11
	s_add_u32 s12, s66, 0x80000
	global_load_lds_dwordx4 v132, s[68:69]
	s_addc_u32 s13, s67, 0
	s_add_i32 m0, s10, 0x14000
	v_mov_b32_e32 v131, 0
	global_load_lds_dwordx4 v130, s[12:13]
	s_add_i32 m0, s10, 0x16000
	s_add_u32 s24, s68, 0x80000
	global_load_lds_dwordx4 v134, s[12:13]
	s_addc_u32 s25, s69, 0
	s_add_i32 s12, s10, 0x4000
	s_mov_b32 m0, s12
	s_add_i32 s13, s10, 0x6000
	global_load_lds_dwordx4 v128, s[24:25]
	s_mov_b32 m0, s13
	v_mov_b32_e32 v135, v131
	global_load_lds_dwordx4 v132, s[24:25]
	v_mov_b32_e32 v129, v131
	v_mov_b32_e32 v133, v131
	s_mov_b32 s14, 0
	v_lshl_add_u64 v[6:7], s[66:67], 0, v[130:131]
	v_lshl_add_u64 v[4:5], s[66:67], 0, v[134:135]
	v_lshl_add_u64 v[2:3], s[68:69], 0, v[128:129]
	s_cmp_lg_u32 s23, 1
	v_lshl_add_u64 v[0:1], s[68:69], 0, v[132:133]
	s_cbranch_scc1 .LBB0_522
	s_barrier
	s_setprio 1

; #define PG8_STAGE(bufoff, gbase, voff) do { _Pragma("unroll") for (int _i = 0; _i < 2; ++_i) \
;         __builtin_amdgcn_global_load_lds((const unsigned*)((const char*)(gbase) + (voff)[_i]), (LAS unsigned*)(lds + (bufoff) + ldsw + _i * 8192), 16, 0, 0); } while (0)
; #define PG8_BAR __builtin_amdgcn_s_barrier()
; template <class Epi>
; __device__ __forceinline__ void gemm_phase(LAS unsigned char* lds, const Gemm g, const StaticOrder& S, const Epi& E, int wv) {
;     ...
;         const bool has_next = S.next(ui + 1, nxt);
;         const char* nA = has_next ? (const char*)g.A + (size_t)nxt.pm * tstepA + ((g.adiag & 1) ? (size_t)(nxt.pn >> 1) * K * 2 : 0) + kbeg : cA;
;         const char* nB = has_next ? (const char*)g.Bt + (size_t)nxt.pn * tstepB + kbeg : cB;
;         for (int t = 0; t < nt; t += 2) {
;             const bool last = (t == nt - 2);
;             const char* a1 = cA + (ptrdiff_t)(t + 1) * kstep;
;             const char* a2 = last ? nA : cA + (ptrdiff_t)(t + 2) * kstep; const char* b2 = last ? nB : cB + (ptrdiff_t)(t + 2) * kstep;
;             const char* a3 = a2 + kstep; const char* b3 = b2 + kstep;
;             PG8_LDB(B0, 0, 0); PG8_SCHED; PG8_LDA(At, 0, 0); PG8_STAGE(PG8_SA(1, 1), a1 + hstepA, voffA);
;             PG8_WAIT_L(8); PG8_BAR; PG8_WAIT_L(0); PG8_MMA(0, 0, At, B0); PG8_BAR; PG8_SCHED;
;             PG8_LDB(B1, 0, 1); PG8_STAGE(PG8_SB(0, 0), b2, voffB);
;             PG8_BAR; PG8_WAIT_L(0); PG8_MMA(0, 1, At, B1); PG8_BAR;
;             PG8_LDA(At, 0, 1); PG8_STAGE(PG8_SA(0, 0), a2, voffA);
;             PG8_BAR; PG8_WAIT_L(0); PG8_MMA(1, 0, At, B0); PG8_BAR; PG8_SCHED;
;             PG8_STAGE(PG8_SB(0, 1), b2 + hstepB, voffB);
;             PG8_WAIT_V(6); PG8_BAR; PG8_MMA(1, 1, At, B1); PG8_BAR;
;             PG8_LDB(B0, 1, 0); PG8_SCHED; PG8_LDA(At, 1, 0); PG8_STAGE(PG8_SA(0, 1), a2 + hstepA, voffA);
;             PG8_WAIT_L(8); PG8_BAR; PG8_WAIT_L(0); PG8_MMA(0, 0, At, B0); PG8_BAR; PG8_SCHED;
;             PG8_LDB(B1, 1, 1); PG8_STAGE(PG8_SB(1, 0), b3, voffB);
;             PG8_BAR; PG8_WAIT_L(0); PG8_MMA(0, 1, At, B1); PG8_BAR;
;             PG8_LDA(At, 1, 1); PG8_STAGE(PG8_SA(1, 0), a3, voffA);
;             PG8_BAR; PG8_WAIT_L(0); PG8_MMA(1, 0, At, B0); PG8_BAR; PG8_SCHED;
;             PG8_STAGE(PG8_SB(1, 1), b3 + hstepB, voffB);
;             PG8_WAIT_V(6); PG8_BAR; PG8_MMA(1, 1, At, B1); PG8_BAR;
.LBB0_530:
	s_add_u32 s44, s66, 0xfff80080
	s_addc_u32 s45, s67, -1
	s_cmp_eq_u32 s43, 28
	s_cselect_b32 s71, s35, s45
	s_cselect_b32 s70, s38, s44
	s_cselect_b32 s69, s39, s42
	s_cselect_b32 s68, s40, s41
	s_add_i32 m0, s10, 0xc000
	ds_read_b128 v[170:173], v154
	ds_read_b128 v[174:177], v154 offset:1024
	ds_read_b128 v[178:181], v154 offset:2048
	ds_read_b128 v[182:185], v154 offset:3072
	ds_read_b128 v[186:189], v154 offset:4096
	ds_read_b128 v[190:193], v154 offset:5120
	ds_read_b128 v[194:197], v154 offset:6144
	ds_read_b128 v[198:201], v154 offset:7168
	global_load_lds_dwordx4 v138, s[66:67]
	s_add_i32 m0, s10, 0xe000
	s_nop 0
	global_load_lds_dwordx4 v136, s[66:67]
	s_waitcnt lgkmcnt(8)
	s_barrier
	s_waitcnt lgkmcnt(0)
	s_waitcnt lgkmcnt(0)
	v_mfma_f32_16x16x32_bf16 v[124:127], v[144:147], v[170:173], v[124:127]
	v_mfma_f32_16x16x32_bf16 v[120:123], v[162:165], v[170:173], v[120:123]
	v_mfma_f32_16x16x32_bf16 v[116:119], v[144:147], v[178:181], v[116:119]
	v_mfma_f32_16x16x32_bf16 v[112:115], v[162:165], v[178:181], v[112:115]
	v_mfma_f32_16x16x32_bf16 v[92:95], v[144:147], v[186:189], v[92:95]
	v_mfma_f32_16x16x32_bf16 v[88:91], v[162:165], v[186:189], v[88:91]
	v_mfma_f32_16x16x32_bf16 v[76:79], v[144:147], v[194:197], v[76:79]
	v_mfma_f32_16x16x32_bf16 v[72:75], v[162:165], v[194:197], v[72:75]
	v_mfma_f32_16x16x32_bf16 v[124:127], v[158:161], v[174:177], v[124:127]
	v_mfma_f32_16x16x32_bf16 v[120:123], v[166:169], v[174:177], v[120:123]
	v_mfma_f32_16x16x32_bf16 v[116:119], v[158:161], v[182:185], v[116:119]
	v_mfma_f32_16x16x32_bf16 v[112:115], v[166:169], v[182:185], v[112:115]
	v_mfma_f32_16x16x32_bf16 v[92:95], v[158:161], v[190:193], v[92:95]
	v_mfma_f32_16x16x32_bf16 v[88:91], v[166:169], v[190:193], v[88:91]
	v_mfma_f32_16x16x32_bf16 v[76:79], v[158:161], v[198:201], v[76:79]
	v_mfma_f32_16x16x32_bf16 v[72:75], v[166:169], v[198:201], v[72:75]
	s_barrier
	s_add_i32 s44, s23, s9
	s_add_u32 s98, s68, s52
	s_addc_u32 s99, s69, s53
	s_mov_b32 m0, s44
	ds_read_b128 v[202:205], v155
	ds_read_b128 v[206:209], v155 offset:1024
	ds_read_b128 v[210:213], v155 offset:2048
	ds_read_b128 v[214:217], v155 offset:3072
	global_load_lds_dwordx4 v130, s[68:69]
	s_add_i32 m0, s44, 0x2000
	s_nop 0
	global_load_lds_dwordx4 v134, s[68:69]
	s_barrier
	s_waitcnt lgkmcnt(0)
	s_waitcnt lgkmcnt(0)
	v_mfma_f32_16x16x32_bf16 v[108:111], v[202:205], v[170:173], v[108:111]
	v_mfma_f32_16x16x32_bf16 v[104:107], v[210:213], v[170:173], v[104:107]
	v_mfma_f32_16x16x32_bf16 v[100:103], v[202:205], v[178:181], v[100:103]
	v_mfma_f32_16x16x32_bf16 v[96:99], v[210:213], v[178:181], v[96:99]
	v_mfma_f32_16x16x32_bf16 v[84:87], v[202:205], v[186:189], v[84:87]
	v_mfma_f32_16x16x32_bf16 v[80:83], v[210:213], v[186:189], v[80:83]
	v_mfma_f32_16x16x32_bf16 v[68:71], v[202:205], v[194:197], v[68:71]
	v_mfma_f32_16x16x32_bf16 v[64:67], v[210:213], v[194:197], v[64:67]
	v_mfma_f32_16x16x32_bf16 v[108:111], v[206:209], v[174:177], v[108:111]
	v_mfma_f32_16x16x32_bf16 v[104:107], v[214:217], v[174:177], v[104:107]
	v_mfma_f32_16x16x32_bf16 v[100:103], v[206:209], v[182:185], v[100:103]
	v_mfma_f32_16x16x32_bf16 v[96:99], v[214:217], v[182:185], v[96:99]
	v_mfma_f32_16x16x32_bf16 v[84:87], v[206:209], v[190:193], v[84:87]
	v_mfma_f32_16x16x32_bf16 v[80:83], v[214:217], v[190:193], v[80:83]
	v_mfma_f32_16x16x32_bf16 v[68:71], v[206:209], v[198:201], v[68:71]
	v_mfma_f32_16x16x32_bf16 v[64:67], v[214:217], v[198:201], v[64:67]
	s_mov_b32 m0, s10
	s_add_u32 s100, s70, s52
	s_addc_u32 s101, s71, s53
	s_barrier
	ds_read_b128 v[170:173], v154 offset:16384
	ds_read_b128 v[174:177], v154 offset:17408
	ds_read_b128 v[178:181], v154 offset:18432
	ds_read_b128 v[182:185], v154 offset:19456
	ds_read_b128 v[186:189], v154 offset:20480
	ds_read_b128 v[190:193], v154 offset:21504
	ds_read_b128 v[194:197], v154 offset:22528
	ds_read_b128 v[198:201], v154 offset:23552
	global_load_lds_dwordx4 v128, s[70:71]
	s_mov_b32 m0, s11
	s_nop 0
	global_load_lds_dwordx4 v132, s[70:71]
	s_waitcnt vmcnt(10)
	s_barrier
	s_waitcnt lgkmcnt(0)
	s_waitcnt lgkmcnt(0)
	v_mfma_f32_16x16x32_bf16 v[60:63], v[144:147], v[170:173], v[60:63]
	v_mfma_f32_16x16x32_bf16 v[56:59], v[162:165], v[170:173], v[56:59]
	v_mfma_f32_16x16x32_bf16 v[44:47], v[144:147], v[178:181], v[44:47]
	v_mfma_f32_16x16x32_bf16 v[40:43], v[162:165], v[178:181], v[40:43]
	v_mfma_f32_16x16x32_bf16 v[28:31], v[144:147], v[186:189], v[28:31]
	v_mfma_f32_16x16x32_bf16 v[24:27], v[162:165], v[186:189], v[24:27]
	v_mfma_f32_16x16x32_bf16 v[12:15], v[144:147], v[194:197], v[12:15]
	v_mfma_f32_16x16x32_bf16 v[8:11], v[162:165], v[194:197], v[8:11]
	v_mfma_f32_16x16x32_bf16 v[60:63], v[158:161], v[174:177], v[60:63]
	v_mfma_f32_16x16x32_bf16 v[56:59], v[166:169], v[174:177], v[56:59]
	v_mfma_f32_16x16x32_bf16 v[44:47], v[158:161], v[182:185], v[44:47]
	v_mfma_f32_16x16x32_bf16 v[40:43], v[166:169], v[182:185], v[40:43]
	v_mfma_f32_16x16x32_bf16 v[28:31], v[158:161], v[190:193], v[28:31]
	v_mfma_f32_16x16x32_bf16 v[24:27], v[166:169], v[190:193], v[24:27]
	v_mfma_f32_16x16x32_bf16 v[12:15], v[158:161], v[198:201], v[12:15]
	v_mfma_f32_16x16x32_bf16 v[8:11], v[166:169], v[198:201], v[8:11]
	s_barrier
	s_add_u32 s44, s68, 0x80000
	s_addc_u32 s45, s69, 0
	s_add_i32 s46, s24, s9
	s_mov_b32 m0, s46
	s_nop 0
	global_load_lds_dwordx4 v130, s[44:45]
	s_add_i32 m0, s46, 0x2000
	s_nop 0
	global_load_lds_dwordx4 v134, s[44:45]
	s_add_i32 s46, 0, 0x18000
	v_add_u32_e32 v157, s46, v151
	ds_read_b128 v[144:147], v157
	ds_read_b128 v[158:161], v157 offset:1024
	ds_read_b128 v[162:165], v157 offset:2048
	ds_read_b128 v[166:169], v157 offset:3072
	s_waitcnt vmcnt(6)
	s_barrier
; #define PG8_STAGE(bufoff, gbase, voff) do { _Pragma("unroll") for (int _i = 0; _i < 2; ++_i) \
;         __builtin_amdgcn_global_load_lds((const unsigned*)((const char*)(gbase) + (voff)[_i]), (LAS unsigned*)(lds + (bufoff) + ldsw + _i * 8192), 16, 0, 0); } while (0)
; #define PG8_LDA(dst, b, h) do { _Pragma("unroll") for (int m = 0; m < 4; ++m) _Pragma("unroll") for (int k = 0; k < 2; ++k) dst[m][k] = *(const LAS bf16x8*)(lds + PG8_SA(b, h) + aoff + m * 2048 + k * 1024); } while (0)
; #define PG8_WAIT_V(n) asm volatile("s_waitcnt vmcnt(" #n ")" ::: "memory")
; #define PG8_BAR __builtin_amdgcn_s_barrier()
; template <class Epi>
; __device__ __forceinline__ void gemm_phase(LAS unsigned char* lds, const Gemm g, const StaticOrder& S, const Epi& E, int wv) {
;     ...
;         for (int t = 0; t < nt; t += 2) {
;             const bool last = (t == nt - 2);
;             const char* a1 = cA + (ptrdiff_t)(t + 1) * kstep;
;             const char* a2 = last ? nA : cA + (ptrdiff_t)(t + 2) * kstep; const char* b2 = last ? nB : cB + (ptrdiff_t)(t + 2) * kstep;
;             const char* a3 = a2 + kstep; const char* b3 = b2 + kstep;
;             PG8_LDB(B0, 0, 0); PG8_SCHED; PG8_LDA(At, 0, 0); PG8_STAGE(PG8_SA(1, 1), a1 + hstepA, voffA);
;             PG8_WAIT_L(8); PG8_BAR; PG8_WAIT_L(0); PG8_MMA(0, 0, At, B0); PG8_BAR; PG8_SCHED;
;             PG8_LDB(B1, 0, 1); PG8_STAGE(PG8_SB(0, 0), b2, voffB);
;             PG8_BAR; PG8_WAIT_L(0); PG8_MMA(0, 1, At, B1); PG8_BAR;
;             PG8_LDA(At, 0, 1); PG8_STAGE(PG8_SA(0, 0), a2, voffA);
;             PG8_BAR; PG8_WAIT_L(0); PG8_MMA(1, 0, At, B0); PG8_BAR; PG8_SCHED;
;             PG8_STAGE(PG8_SB(0, 1), b2 + hstepB, voffB);
;             PG8_WAIT_V(6); PG8_BAR; PG8_MMA(1, 1, At, B1); PG8_BAR;
;             PG8_LDB(B0, 1, 0); PG8_SCHED; PG8_LDA(At, 1, 0); PG8_STAGE(PG8_SA(0, 1), a2 + hstepA, voffA);
;             PG8_WAIT_L(8); PG8_BAR; PG8_WAIT_L(0); PG8_MMA(0, 0, At, B0); PG8_BAR; PG8_SCHED;
;             PG8_LDB(B1, 1, 1); PG8_STAGE(PG8_SB(1, 0), b3, voffB);
;             PG8_BAR; PG8_WAIT_L(0); PG8_MMA(0, 1, At, B1); PG8_BAR;
;             PG8_LDA(At, 1, 1); PG8_STAGE(PG8_SA(1, 0), a3, voffA);
;             PG8_BAR; PG8_WAIT_L(0); PG8_MMA(1, 0, At, B0); PG8_BAR; PG8_SCHED;
;             PG8_STAGE(PG8_SB(1, 1), b3 + hstepB, voffB);
;             PG8_WAIT_V(6); PG8_BAR; PG8_MMA(1, 1, At, B1); PG8_BAR;
	v_mfma_f32_16x16x32_bf16 v[52:55], v[202:205], v[170:173], v[52:55]
	v_mfma_f32_16x16x32_bf16 v[48:51], v[210:213], v[170:173], v[48:51]
	v_mfma_f32_16x16x32_bf16 v[36:39], v[202:205], v[178:181], v[36:39]
	v_mfma_f32_16x16x32_bf16 v[32:35], v[210:213], v[178:181], v[32:35]
	v_mfma_f32_16x16x32_bf16 v[20:23], v[202:205], v[186:189], v[20:23]
	v_mfma_f32_16x16x32_bf16 v[16:19], v[210:213], v[186:189], v[16:19]
	v_mfma_f32_16x16x32_bf16 v[4:7], v[202:205], v[194:197], v[4:7]
	v_mfma_f32_16x16x32_bf16 v[0:3], v[210:213], v[194:197], v[0:3]
	v_mfma_f32_16x16x32_bf16 v[52:55], v[206:209], v[174:177], v[52:55]
	v_mfma_f32_16x16x32_bf16 v[48:51], v[214:217], v[174:177], v[48:51]
	v_mfma_f32_16x16x32_bf16 v[36:39], v[206:209], v[182:185], v[36:39]
	v_mfma_f32_16x16x32_bf16 v[32:35], v[214:217], v[182:185], v[32:35]
	v_mfma_f32_16x16x32_bf16 v[20:23], v[206:209], v[190:193], v[20:23]
	v_mfma_f32_16x16x32_bf16 v[16:19], v[214:217], v[190:193], v[16:19]
	v_mfma_f32_16x16x32_bf16 v[4:7], v[206:209], v[198:201], v[4:7]
	v_mfma_f32_16x16x32_bf16 v[0:3], v[214:217], v[198:201], v[0:3]
	s_waitcnt lgkmcnt(0)
	s_barrier
	s_add_u32 s44, s70, 0x80000
	s_addc_u32 s45, s71, 0
	s_mov_b32 m0, s12
	ds_read_b128 v[170:173], v154 offset:32768
	ds_read_b128 v[174:177], v154 offset:33792
	ds_read_b128 v[178:181], v154 offset:34816
	ds_read_b128 v[182:185], v154 offset:35840
	ds_read_b128 v[186:189], v154 offset:36864
	ds_read_b128 v[190:193], v154 offset:37888
	ds_read_b128 v[194:197], v154 offset:38912
	ds_read_b128 v[198:201], v154 offset:39936
	global_load_lds_dwordx4 v128, s[44:45]
	s_mov_b32 m0, s13
	s_nop 0
	global_load_lds_dwordx4 v132, s[44:45]
	s_waitcnt lgkmcnt(8)
	s_barrier
	s_waitcnt lgkmcnt(0)
	s_waitcnt lgkmcnt(0)
	v_mfma_f32_16x16x32_bf16 v[124:127], v[144:147], v[170:173], v[124:127]
	v_mfma_f32_16x16x32_bf16 v[120:123], v[162:165], v[170:173], v[120:123]
	v_mfma_f32_16x16x32_bf16 v[116:119], v[144:147], v[178:181], v[116:119]
	v_mfma_f32_16x16x32_bf16 v[112:115], v[162:165], v[178:181], v[112:115]
	v_mfma_f32_16x16x32_bf16 v[92:95], v[144:147], v[186:189], v[92:95]
	v_mfma_f32_16x16x32_bf16 v[88:91], v[162:165], v[186:189], v[88:91]
	v_mfma_f32_16x16x32_bf16 v[76:79], v[144:147], v[194:197], v[76:79]
	v_mfma_f32_16x16x32_bf16 v[72:75], v[162:165], v[194:197], v[72:75]
	v_mfma_f32_16x16x32_bf16 v[124:127], v[158:161], v[174:177], v[124:127]
	v_mfma_f32_16x16x32_bf16 v[120:123], v[166:169], v[174:177], v[120:123]
	v_mfma_f32_16x16x32_bf16 v[116:119], v[158:161], v[182:185], v[116:119]
	v_mfma_f32_16x16x32_bf16 v[112:115], v[166:169], v[182:185], v[112:115]
	v_mfma_f32_16x16x32_bf16 v[92:95], v[158:161], v[190:193], v[92:95]
	v_mfma_f32_16x16x32_bf16 v[88:91], v[166:169], v[190:193], v[88:91]
	v_mfma_f32_16x16x32_bf16 v[76:79], v[158:161], v[198:201], v[76:79]
	v_mfma_f32_16x16x32_bf16 v[72:75], v[166:169], v[198:201], v[72:75]
	s_barrier
	s_add_i32 s47, 0, 0x1c000
	s_add_i32 s44, s46, s9
	v_add_u32_e32 v157, s47, v151
	s_mov_b32 m0, s44
	ds_read_b128 v[202:205], v157
	ds_read_b128 v[206:209], v157 offset:1024
	ds_read_b128 v[210:213], v157 offset:2048
	ds_read_b128 v[214:217], v157 offset:3072
	global_load_lds_dwordx4 v130, s[98:99]
	s_add_i32 m0, s44, 0x2000
	s_nop 0
	global_load_lds_dwordx4 v134, s[98:99]
	s_barrier
	s_waitcnt lgkmcnt(0)
	s_waitcnt lgkmcnt(0)
	v_mfma_f32_16x16x32_bf16 v[108:111], v[202:205], v[170:173], v[108:111]
	v_mfma_f32_16x16x32_bf16 v[104:107], v[210:213], v[170:173], v[104:107]
	v_mfma_f32_16x16x32_bf16 v[100:103], v[202:205], v[178:181], v[100:103]
	v_mfma_f32_16x16x32_bf16 v[96:99], v[210:213], v[178:181], v[96:99]
	v_mfma_f32_16x16x32_bf16 v[84:87], v[202:205], v[186:189], v[84:87]
	v_mfma_f32_16x16x32_bf16 v[80:83], v[210:213], v[186:189], v[80:83]
	v_mfma_f32_16x16x32_bf16 v[68:71], v[202:205], v[194:197], v[68:71]
	v_mfma_f32_16x16x32_bf16 v[64:67], v[210:213], v[194:197], v[64:67]
	v_mfma_f32_16x16x32_bf16 v[108:111], v[206:209], v[174:177], v[108:111]
	v_mfma_f32_16x16x32_bf16 v[104:107], v[214:217], v[174:177], v[104:107]
	v_mfma_f32_16x16x32_bf16 v[100:103], v[206:209], v[182:185], v[100:103]
	v_mfma_f32_16x16x32_bf16 v[96:99], v[214:217], v[182:185], v[96:99]
	v_mfma_f32_16x16x32_bf16 v[84:87], v[206:209], v[190:193], v[84:87]
	v_mfma_f32_16x16x32_bf16 v[80:83], v[214:217], v[190:193], v[80:83]
	v_mfma_f32_16x16x32_bf16 v[68:71], v[206:209], v[198:201], v[68:71]
	v_mfma_f32_16x16x32_bf16 v[64:67], v[214:217], v[198:201], v[64:67]
	s_mov_b32 m0, s15
	s_barrier
	ds_read_b128 v[170:173], v154 offset:49152
	ds_read_b128 v[174:177], v154 offset:50176
	ds_read_b128 v[178:181], v154 offset:51200
	ds_read_b128 v[182:185], v154 offset:52224
	ds_read_b128 v[186:189], v154 offset:53248
	ds_read_b128 v[190:193], v154 offset:54272
	ds_read_b128 v[194:197], v154 offset:55296
	ds_read_b128 v[198:201], v154 offset:56320
	global_load_lds_dwordx4 v128, s[100:101]
	s_mov_b32 m0, s22
	s_nop 0
	global_load_lds_dwordx4 v132, s[100:101]
	s_waitcnt vmcnt(10)
	s_barrier
	s_waitcnt lgkmcnt(0)
	s_waitcnt lgkmcnt(0)
	v_mfma_f32_16x16x32_bf16 v[60:63], v[144:147], v[170:173], v[60:63]
	v_mfma_f32_16x16x32_bf16 v[56:59], v[162:165], v[170:173], v[56:59]
	v_mfma_f32_16x16x32_bf16 v[44:47], v[144:147], v[178:181], v[44:47]
	v_mfma_f32_16x16x32_bf16 v[40:43], v[162:165], v[178:181], v[40:43]
	v_mfma_f32_16x16x32_bf16 v[28:31], v[144:147], v[186:189], v[28:31]
	v_mfma_f32_16x16x32_bf16 v[24:27], v[162:165], v[186:189], v[24:27]
	v_mfma_f32_16x16x32_bf16 v[12:15], v[144:147], v[194:197], v[12:15]
	v_mfma_f32_16x16x32_bf16 v[8:11], v[162:165], v[194:197], v[8:11]
	v_mfma_f32_16x16x32_bf16 v[60:63], v[158:161], v[174:177], v[60:63]
	v_mfma_f32_16x16x32_bf16 v[56:59], v[166:169], v[174:177], v[56:59]
	v_mfma_f32_16x16x32_bf16 v[44:47], v[158:161], v[182:185], v[44:47]
	v_mfma_f32_16x16x32_bf16 v[40:43], v[166:169], v[182:185], v[40:43]
	v_mfma_f32_16x16x32_bf16 v[28:31], v[158:161], v[190:193], v[28:31]
	v_mfma_f32_16x16x32_bf16 v[24:27], v[166:169], v[190:193], v[24:27]
	v_mfma_f32_16x16x32_bf16 v[12:15], v[158:161], v[198:201], v[12:15]
	v_mfma_f32_16x16x32_bf16 v[8:11], v[166:169], v[198:201], v[8:11]
	s_barrier
;     __device__ __forceinline__ void operator()(const f32x4 (&acc)[2][2][4][2], const Unit& u, int wr, int wc, int fr, int fq) const {
;         const int row0 = u.pm * BM + wr * 64 + fr; int colt = u.pn * BM; bf16_t* base = O; int tsel = 0;
;         if (split_cols) { tsel = colt / split_cols; base += (size_t)tsel * split_stride; colt -= tsel * split_cols; }
;         const int col0 = colt + wc * 32 + 8 * fq;
;         f32x4 cs[2][2];
;         if (SM == 2) {
; #pragma unroll
;             for (int bj = 0; bj < 2; ++bj)
; #pragma unroll
;                 for (int n = 0; n < 2; ++n) { const f32x4 s = *(const f32x4*)(ss + u.pn * BM + wc * 32 + 8 * fq + bj * HALF + 4 * n);
; #pragma unroll
;                     for (int j = 0; j < 4; ++j) cs[bj][n][j] = __builtin_amdgcn_rsqf(ss_fix(s[j]) * (1.0f / DM) + EPS); }
;         }
;         float rsv[8];
; #pragma unroll
;         for (int it = 0; it < 8; ++it) rsv[it] = (SM == 1) ? ss[row0 + (it >> 2) * HALF + (it & 3) * 16] : 1.0f;
; #pragma unroll
;         for (int ai = 0; ai < 2; ++ai)
; #pragma unroll
;             for (int m = 0; m < 4; ++m) { const int row = row0 + ai * HALF + m * 16; float rs = 1.0f; if (SM == 1) rs = __builtin_amdgcn_rsqf(ss_fix(rsv[ai * 4 + m]) * (1.0f / DM) + EPS);
;                 bf16_t* rowp = base + (size_t)row * ldc + col0;
; #pragma unroll
;                 for (int bj = 0; bj < 2; ++bj) { f32x4 v0 = acc[ai][bj][m][0], v1 = acc[ai][bj][m][1];
;                     if (SM == 1) { v0 *= rs; v1 *= rs; }
;                     if (SM == 2) { v0 *= cs[bj][0]; v1 *= cs[bj][1]; }
;                     if (ACT == 1) {
; #pragma unroll
;                         for (int j = 0; j < 4; ++j) { const float a = fmaxf(v0[j], 0.f), b = fmaxf(v1[j], 0.f); v0[j] = a * a; v1[j] = b * b; } }
;                     if (ACT == 2) { if (tsel == 0) {
; #pragma unroll
;                         for (int j = 0; j < 4; ++j) { const float a = v0[j], b = v1[j];
;                             v0[j] = a * fast_sigmoid(1.5957691216057308f * (a + 0.044715f * a * a * a)); v1[j] = b * fast_sigmoid(1.5957691216057308f * (b + 0.044715f * b * b * b)); } } }
;                     u32x4 w; w.x = pk_bf16(v0[0], v0[1]); w.y = pk_bf16(v0[2], v0[3]); w.z = pk_bf16(v1[0], v1[1]); w.w = pk_bf16(v1[2], v1[3]);
;                     *(u32x4*)(rowp + bj * HALF) = w; } }
	s_add_u32 s44, s68, 0x80080
	s_addc_u32 s45, s69, 0
	s_add_i32 s46, s47, s9
	s_mov_b32 m0, s46
	s_nop 0
	global_load_lds_dwordx4 v130, s[44:45]
	s_add_i32 m0, s46, 0x2000
	s_nop 0
	global_load_lds_dwordx4 v134, s[44:45]
	ds_read_b128 v[144:147], v153
	ds_read_b128 v[158:161], v153 offset:1024
	ds_read_b128 v[162:165], v153 offset:2048
	ds_read_b128 v[166:169], v153 offset:3072
	s_waitcnt vmcnt(6)
	s_barrier
	v_mfma_f32_16x16x32_bf16 v[52:55], v[202:205], v[170:173], v[52:55]
	v_mfma_f32_16x16x32_bf16 v[48:51], v[210:213], v[170:173], v[48:51]
	v_mfma_f32_16x16x32_bf16 v[36:39], v[202:205], v[178:181], v[36:39]
	v_mfma_f32_16x16x32_bf16 v[32:35], v[210:213], v[178:181], v[32:35]
	v_mfma_f32_16x16x32_bf16 v[20:23], v[202:205], v[186:189], v[20:23]
	v_mfma_f32_16x16x32_bf16 v[16:19], v[210:213], v[186:189], v[16:19]
	v_mfma_f32_16x16x32_bf16 v[4:7], v[202:205], v[194:197], v[4:7]
	v_mfma_f32_16x16x32_bf16 v[0:3], v[210:213], v[194:197], v[0:3]
	v_mfma_f32_16x16x32_bf16 v[52:55], v[206:209], v[174:177], v[52:55]
	v_mfma_f32_16x16x32_bf16 v[48:51], v[214:217], v[174:177], v[48:51]
	v_mfma_f32_16x16x32_bf16 v[36:39], v[206:209], v[182:185], v[36:39]
	v_mfma_f32_16x16x32_bf16 v[32:35], v[214:217], v[182:185], v[32:35]
	v_mfma_f32_16x16x32_bf16 v[20:23], v[206:209], v[190:193], v[20:23]
	v_mfma_f32_16x16x32_bf16 v[16:19], v[214:217], v[190:193], v[16:19]
	v_mfma_f32_16x16x32_bf16 v[4:7], v[206:209], v[198:201], v[4:7]
	v_mfma_f32_16x16x32_bf16 v[0:3], v[214:217], v[198:201], v[0:3]
	s_waitcnt lgkmcnt(0)
	s_add_i32 s43, s43, 2
	s_add_u32 s41, s41, 0x100
	s_addc_u32 s42, s42, 0
	s_add_u32 s66, s66, 0x100
	s_addc_u32 s67, s67, 0
	s_cmp_gt_u32 s43, 29
	s_barrier
	s_cbranch_scc0 .LBB0_530
	v_lshl_add_u32 v146, s64, 8, v150
	v_ashrrev_i32_e32 v147, 31, v146
	v_lshl_add_u64 v[144:145], v[146:147], 2, s[50:51]
	global_load_dword v157, v[144:145], off
	global_load_dword v162, v[144:145], off offset:64
	v_lshlrev_b64 v[160:161], 14, v[146:147]
	global_load_dword v166, v[144:145], off offset:128
	global_load_dword v167, v[144:145], off offset:192
	global_load_dword v168, v[144:145], off offset:512
	global_load_dword v169, v[144:145], off offset:576
	global_load_dword v170, v[144:145], off offset:640
	global_load_dword v147, v[144:145], off offset:704
	v_lshl_or_b32 v148, s34, 8, v152
	v_ashrrev_i32_e32 v149, 31, v148
	v_lshl_add_u64 v[148:149], v[148:149], 1, s[18:19]
	v_lshl_add_u64 v[144:145], v[148:149], 0, v[160:161]
	v_or_b32_e32 v158, 16, v146
	v_ashrrev_i32_e32 v159, 31, v158
	v_lshlrev_b64 v[158:159], 14, v[158:159]
	v_lshl_add_u64 v[158:159], v[148:149], 0, v[158:159]
	s_mov_b64 s[34:35], 0x200000
	s_mov_b32 s64, s58
	s_mov_b64 s[66:67], s[62:63]
	s_mov_b64 s[68:69], s[60:61]
	s_waitcnt vmcnt(0)
	v_cvt_f32_u32_e32 v157, v157
	v_cvt_f32_u32_e32 v161, v162
	v_mul_f32_e32 v157, 0x3b800000, v157
	v_fmamk_f32 v157, v157, 0x3a000000, v156
	v_rsq_f32_e32 v160, v157
	v_mul_f32_e32 v157, 0x3b800000, v161
	v_fmamk_f32 v157, v157, 0x3a000000, v156
	v_rsq_f32_e32 v162, v157
	v_pk_mul_f32 v[126:127], v[126:127], v[160:161] op_sel_hi:[1,0]
	v_pk_mul_f32 v[124:125], v[124:125], v[160:161] op_sel_hi:[1,0]
	v_pk_mul_f32 v[122:123], v[122:123], v[160:161] op_sel_hi:[1,0]
	v_pk_mul_f32 v[120:121], v[120:121], v[160:161] op_sel_hi:[1,0]
	v_pk_mul_f32 v[110:111], v[110:111], v[160:161] op_sel_hi:[1,0]
	v_pk_mul_f32 v[108:109], v[108:109], v[160:161] op_sel_hi:[1,0]
	v_pk_mul_f32 v[106:107], v[106:107], v[160:161] op_sel_hi:[1,0]
	v_pk_mul_f32 v[104:105], v[104:105], v[160:161] op_sel_hi:[1,0]
	v_pk_mul_f32 v[118:119], v[118:119], v[162:163] op_sel_hi:[1,0]
	v_pk_mul_f32 v[116:117], v[116:117], v[162:163] op_sel_hi:[1,0]
	v_pk_mul_f32 v[114:115], v[114:115], v[162:163] op_sel_hi:[1,0]
	v_pk_mul_f32 v[112:113], v[112:113], v[162:163] op_sel_hi:[1,0]
	v_pk_mul_f32 v[160:161], v[102:103], v[162:163] op_sel_hi:[1,0]
	v_pk_mul_f32 v[100:101], v[100:101], v[162:163] op_sel_hi:[1,0]
	v_pk_mul_f32 v[164:165], v[98:99], v[162:163] op_sel_hi:[1,0]
	v_pk_mul_f32 v[162:163], v[96:97], v[162:163] op_sel_hi:[1,0]
	v_max_f32_e32 v96, 0, v124
	v_max_f32_e32 v98, 0, v120
	v_max_f32_e32 v97, 0, v125
	v_max_f32_e32 v99, 0, v121
	v_max_f32_e32 v102, 0, v126
	v_max_f32_e32 v120, 0, v122
	v_max_f32_e32 v103, 0, v127
	v_max_f32_e32 v121, 0, v123
	v_max_f32_e32 v108, 0, v108
	v_max_f32_e32 v109, 0, v109
	v_max_f32_e32 v110, 0, v110
	v_max_f32_e32 v111, 0, v111
	v_max_f32_e32 v104, 0, v104
	v_max_f32_e32 v105, 0, v105
	v_max_f32_e32 v106, 0, v106
	v_max_f32_e32 v107, 0, v107
	v_max_f32_e32 v116, 0, v116
	v_max_f32_e32 v112, 0, v112
	v_max_f32_e32 v117, 0, v117
	v_max_f32_e32 v113, 0, v113
	v_max_f32_e32 v118, 0, v118
	v_max_f32_e32 v114, 0, v114
	v_max_f32_e32 v119, 0, v119
	v_max_f32_e32 v115, 0, v115
	v_max_f32_e32 v122, 0, v100
	v_max_f32_e32 v123, 0, v101
	v_pk_mul_f32 v[96:97], v[96:97], v[96:97]
	v_pk_mul_f32 v[98:99], v[98:99], v[98:99]
	v_pk_mul_f32 v[100:101], v[102:103], v[102:103]
	v_pk_mul_f32 v[102:103], v[120:121], v[120:121]
	v_pk_mul_f32 v[108:109], v[108:109], v[108:109]
	v_pk_mul_f32 v[110:111], v[110:111], v[110:111]
	v_pk_mul_f32 v[104:105], v[104:105], v[104:105]
	v_pk_mul_f32 v[106:107], v[106:107], v[106:107]
	v_pk_mul_f32 v[116:117], v[116:117], v[116:117]
	v_pk_mul_f32 v[112:113], v[112:113], v[112:113]
	v_pk_mul_f32 v[118:119], v[118:119], v[118:119]
	v_pk_mul_f32 v[114:115], v[114:115], v[114:115]
	v_cvt_pk_bf16_f32 v96, v96, v97
	v_cvt_pk_bf16_f32 v97, v100, v101
	v_cvt_pk_bf16_f32 v98, v98, v99
	v_cvt_pk_bf16_f32 v99, v102, v103
	v_cvt_pk_bf16_f32 v100, v108, v109
	v_cvt_pk_bf16_f32 v101, v110, v111
	v_cvt_pk_bf16_f32 v102, v104, v105
	v_cvt_pk_bf16_f32 v103, v106, v107
; __device__ __forceinline__ float fast_sigmoid(float x) { return __builtin_amdgcn_rcpf(1.0f + __builtin_amdgcn_exp2f(-x * LOG2E)); }
; __device__ __forceinline__ float ss_fix(float raw) { return (float)__float_as_uint(raw) * (1.0f / 256.0f); }
;     __device__ __forceinline__ const CAS char* base() const { const CAS char* ka = (const CAS char*)__builtin_amdgcn_kernarg_segment_ptr(); asm volatile("" : "+s"(ka)); return ka; }
;     __device__ __forceinline__ void operator()(const f32x4 (&acc)[2][2][4][2], const Unit& u, int wr, int wc, int fr, int fq) const {
;     ...
;         for (int ai = 0; ai < 2; ++ai)
; #pragma unroll
;             for (int m = 0; m < 4; ++m) { const int row = row0 + ai * HALF + m * 16; float rs = 1.0f; if (SM == 1) rs = __builtin_amdgcn_rsqf(ss_fix(rsv[ai * 4 + m]) * (1.0f / DM) + EPS);
;                 bf16_t* rowp = base + (size_t)row * ldc + col0;
; #pragma unroll
;                 for (int bj = 0; bj < 2; ++bj) { f32x4 v0 = acc[ai][bj][m][0], v1 = acc[ai][bj][m][1];
;                     if (SM == 1) { v0 *= rs; v1 *= rs; }
;                     if (SM == 2) { v0 *= cs[bj][0]; v1 *= cs[bj][1]; }
;                     if (ACT == 1) {
; #pragma unroll
;                         for (int j = 0; j < 4; ++j) { const float a = fmaxf(v0[j], 0.f), b = fmaxf(v1[j], 0.f); v0[j] = a * a; v1[j] = b * b; } }
;                     if (ACT == 2) { if (tsel == 0) {
; #pragma unroll
;                         for (int j = 0; j < 4; ++j) { const float a = v0[j], b = v1[j];
;                             v0[j] = a * fast_sigmoid(1.5957691216057308f * (a + 0.044715f * a * a * a)); v1[j] = b * fast_sigmoid(1.5957691216057308f * (b + 0.044715f * b * b * b)); } } }
;                     u32x4 w; w.x = pk_bf16(v0[0], v0[1]); w.y = pk_bf16(v0[2], v0[3]); w.z = pk_bf16(v1[0], v1[1]); w.w = pk_bf16(v1[2], v1[3]);
;                     *(u32x4*)(rowp + bj * HALF) = w; } }
	v_cvt_pk_bf16_f32 v104, v116, v117
	v_cvt_pk_bf16_f32 v105, v118, v119
	v_cvt_pk_bf16_f32 v106, v112, v113
	v_cvt_pk_bf16_f32 v107, v114, v115
	global_store_dwordx4 v[144:145], v[96:99], off
	global_store_dwordx4 v[144:145], v[100:103], off offset:256
	global_store_dwordx4 v[158:159], v[104:107], off
	v_pk_mul_f32 v[96:97], v[122:123], v[122:123]
	v_max_f32_e32 v100, 0, v160
	v_max_f32_e32 v101, 0, v161
	v_pk_mul_f32 v[100:101], v[100:101], v[100:101]
	v_cvt_pk_bf16_f32 v96, v96, v97
	v_cvt_pk_bf16_f32 v97, v100, v101
	v_cvt_f32_u32_e32 v100, v166
	v_max_f32_e32 v124, 0, v162
	v_max_f32_e32 v125, 0, v163
	v_max_f32_e32 v102, 0, v164
	v_max_f32_e32 v103, 0, v165
	v_pk_mul_f32 v[98:99], v[124:125], v[124:125]
	v_pk_mul_f32 v[102:103], v[102:103], v[102:103]
	v_cvt_pk_bf16_f32 v98, v98, v99
	v_cvt_pk_bf16_f32 v99, v102, v103
	global_store_dwordx4 v[158:159], v[96:99], off offset:256
	s_nop 1
	v_mul_f32_e32 v97, 0x3b800000, v100
	v_fmamk_f32 v97, v97, 0x3a000000, v156
	v_rsq_f32_e32 v98, v97
	v_or_b32_e32 v96, 32, v146
	v_ashrrev_i32_e32 v97, 31, v96
	v_lshlrev_b64 v[96:97], 14, v[96:97]
	v_pk_mul_f32 v[88:89], v[88:89], v[98:99] op_sel_hi:[1,0]
	v_pk_mul_f32 v[94:95], v[94:95], v[98:99] op_sel_hi:[1,0]
	v_pk_mul_f32 v[92:93], v[92:93], v[98:99] op_sel_hi:[1,0]
	v_pk_mul_f32 v[90:91], v[90:91], v[98:99] op_sel_hi:[1,0]
	v_max_f32_e32 v88, 0, v88
	v_max_f32_e32 v89, 0, v89
	v_max_f32_e32 v92, 0, v92
	v_max_f32_e32 v93, 0, v93
	v_pk_mul_f32 v[100:101], v[88:89], v[88:89]
	v_max_f32_e32 v88, 0, v94
	v_max_f32_e32 v90, 0, v90
	v_max_f32_e32 v89, 0, v95
	v_max_f32_e32 v91, 0, v91
	v_pk_mul_f32 v[92:93], v[92:93], v[92:93]
	v_pk_mul_f32 v[94:95], v[88:89], v[88:89]
	v_pk_mul_f32 v[102:103], v[90:91], v[90:91]
	v_pk_mul_f32 v[84:85], v[84:85], v[98:99] op_sel_hi:[1,0]
	v_pk_mul_f32 v[80:81], v[80:81], v[98:99] op_sel_hi:[1,0]
	v_lshl_add_u64 v[96:97], v[148:149], 0, v[96:97]
	v_cvt_pk_bf16_f32 v88, v92, v93
	v_cvt_pk_bf16_f32 v89, v94, v95
	v_cvt_pk_bf16_f32 v90, v100, v101
	v_cvt_pk_bf16_f32 v91, v102, v103
	v_pk_mul_f32 v[86:87], v[86:87], v[98:99] op_sel_hi:[1,0]
	v_max_f32_e32 v84, 0, v84
	v_max_f32_e32 v80, 0, v80
	v_max_f32_e32 v85, 0, v85
	v_max_f32_e32 v81, 0, v81
	global_store_dwordx4 v[96:97], v[88:91], off
	v_pk_mul_f32 v[84:85], v[84:85], v[84:85]
	v_pk_mul_f32 v[82:83], v[82:83], v[98:99] op_sel_hi:[1,0]
	v_pk_mul_f32 v[88:89], v[80:81], v[80:81]
	v_max_f32_e32 v80, 0, v86
	v_max_f32_e32 v81, 0, v87
	v_pk_mul_f32 v[86:87], v[80:81], v[80:81]
	v_cvt_pk_bf16_f32 v80, v84, v85
	v_cvt_f32_u32_e32 v84, v167
	v_max_f32_e32 v82, 0, v82
	v_max_f32_e32 v83, 0, v83
	v_pk_mul_f32 v[90:91], v[82:83], v[82:83]
	v_cvt_pk_bf16_f32 v81, v86, v87
	v_cvt_pk_bf16_f32 v82, v88, v89
	v_cvt_pk_bf16_f32 v83, v90, v91
	global_store_dwordx4 v[96:97], v[80:83], off offset:256
	s_nop 1
	v_mul_f32_e32 v81, 0x3b800000, v84
	v_fmamk_f32 v81, v81, 0x3a000000, v156
	v_rsq_f32_e32 v82, v81
	v_or_b32_e32 v80, 48, v146
	v_ashrrev_i32_e32 v81, 31, v80
	v_lshlrev_b64 v[80:81], 14, v[80:81]
	v_pk_mul_f32 v[72:73], v[72:73], v[82:83] op_sel_hi:[1,0]
	v_pk_mul_f32 v[78:79], v[78:79], v[82:83] op_sel_hi:[1,0]
	v_pk_mul_f32 v[76:77], v[76:77], v[82:83] op_sel_hi:[1,0]
	v_pk_mul_f32 v[74:75], v[74:75], v[82:83] op_sel_hi:[1,0]
	v_max_f32_e32 v72, 0, v72
	v_max_f32_e32 v73, 0, v73
	v_max_f32_e32 v76, 0, v76
	v_max_f32_e32 v77, 0, v77
	v_pk_mul_f32 v[84:85], v[72:73], v[72:73]
	v_max_f32_e32 v72, 0, v78
	v_max_f32_e32 v74, 0, v74
	v_max_f32_e32 v73, 0, v79
	v_max_f32_e32 v75, 0, v75
	v_pk_mul_f32 v[76:77], v[76:77], v[76:77]
	v_pk_mul_f32 v[78:79], v[72:73], v[72:73]
	v_pk_mul_f32 v[86:87], v[74:75], v[74:75]
	v_pk_mul_f32 v[66:67], v[66:67], v[82:83] op_sel_hi:[1,0]
	v_lshl_add_u64 v[80:81], v[148:149], 0, v[80:81]
	v_cvt_pk_bf16_f32 v72, v76, v77
	v_cvt_pk_bf16_f32 v73, v78, v79
	v_cvt_pk_bf16_f32 v74, v84, v85
	v_cvt_pk_bf16_f32 v75, v86, v87
	v_max_f32_e32 v66, 0, v66
	v_max_f32_e32 v67, 0, v67
	global_store_dwordx4 v[80:81], v[72:75], off
	v_pk_mul_f32 v[68:69], v[68:69], v[82:83] op_sel_hi:[1,0]
	v_pk_mul_f32 v[64:65], v[64:65], v[82:83] op_sel_hi:[1,0]
	v_pk_mul_f32 v[74:75], v[66:67], v[66:67]
	v_cvt_f32_u32_e32 v67, v168
	v_pk_mul_f32 v[70:71], v[70:71], v[82:83] op_sel_hi:[1,0]
	v_max_f32_e32 v68, 0, v68
	v_max_f32_e32 v64, 0, v64
	v_max_f32_e32 v69, 0, v69
	v_max_f32_e32 v65, 0, v65
	v_mul_f32_e32 v67, 0x3b800000, v67
	v_pk_mul_f32 v[68:69], v[68:69], v[68:69]
	v_pk_mul_f32 v[72:73], v[64:65], v[64:65]
	v_max_f32_e32 v64, 0, v70
	v_max_f32_e32 v65, 0, v71
	v_fmamk_f32 v67, v67, 0x3a000000, v156
	v_pk_mul_f32 v[70:71], v[64:65], v[64:65]
	v_cvt_pk_bf16_f32 v64, v68, v69
	v_rsq_f32_e32 v68, v67
	v_cvt_pk_bf16_f32 v65, v70, v71
	v_cvt_pk_bf16_f32 v66, v72, v73
	v_cvt_pk_bf16_f32 v67, v74, v75
	v_pk_mul_f32 v[60:61], v[60:61], v[68:69] op_sel_hi:[1,0]
	v_pk_mul_f32 v[56:57], v[56:57], v[68:69] op_sel_hi:[1,0]
	v_pk_mul_f32 v[62:63], v[62:63], v[68:69] op_sel_hi:[1,0]
	v_pk_mul_f32 v[58:59], v[58:59], v[68:69] op_sel_hi:[1,0]
	v_max_f32_e32 v60, 0, v60
	v_max_f32_e32 v56, 0, v56
	v_max_f32_e32 v61, 0, v61
	v_max_f32_e32 v57, 0, v57
	global_store_dwordx4 v[80:81], v[64:67], off offset:256
	v_pk_mul_f32 v[60:61], v[60:61], v[60:61]
	v_max_f32_e32 v58, 0, v58
	v_lshl_add_u64 v[64:65], v[144:145], 0, s[34:35]
	v_pk_mul_f32 v[66:67], v[56:57], v[56:57]
	v_max_f32_e32 v56, 0, v62
	v_max_f32_e32 v57, 0, v63
	v_max_f32_e32 v59, 0, v59
	s_mov_b32 s34, 0x200000
	v_pk_mul_f32 v[62:63], v[56:57], v[56:57]
	v_pk_mul_f32 v[70:71], v[58:59], v[58:59]
	v_cvt_pk_bf16_f32 v56, v60, v61
	v_add_co_u32_e32 v60, vcc, s34, v144
	v_pk_mul_f32 v[50:51], v[50:51], v[68:69] op_sel_hi:[1,0]
; __device__ __forceinline__ float fast_sigmoid(float x) { return __builtin_amdgcn_rcpf(1.0f + __builtin_amdgcn_exp2f(-x * LOG2E)); }
; __device__ __forceinline__ float ss_fix(float raw) { return (float)__float_as_uint(raw) * (1.0f / 256.0f); }
; template <class Epi>
; __device__ __forceinline__ void gemm_phase(LAS unsigned char* lds, const Gemm g, const StaticOrder& S, const Epi& E, int wv) {
;     ...
;         if (!has_next) break;
; #pragma unroll
;         for (int a = 0; a < 2; ++a)
; #pragma unroll
;             for (int b = 0; b < 2; ++b)
; #pragma unroll
;                 for (int m = 0; m < 4; ++m)
; #pragma unroll
;                     for (int n = 0; n < 2; ++n) acc[a][b][m][n] = (f32x4){0.f, 0.f, 0.f, 0.f};
;         cur = nxt; cA = nA; cB = nB; ++ui;
;     __device__ __forceinline__ void operator()(const f32x4 (&acc)[2][2][4][2], const Unit& u, int wr, int wc, int fr, int fq) const {
;     ...
;         for (int ai = 0; ai < 2; ++ai)
; #pragma unroll
;             for (int m = 0; m < 4; ++m) { const int row = row0 + ai * HALF + m * 16; float rs = 1.0f; if (SM == 1) rs = __builtin_amdgcn_rsqf(ss_fix(rsv[ai * 4 + m]) * (1.0f / DM) + EPS);
;                 bf16_t* rowp = base + (size_t)row * ldc + col0;
; #pragma unroll
;                 for (int bj = 0; bj < 2; ++bj) { f32x4 v0 = acc[ai][bj][m][0], v1 = acc[ai][bj][m][1];
;                     if (SM == 1) { v0 *= rs; v1 *= rs; }
;                     if (SM == 2) { v0 *= cs[bj][0]; v1 *= cs[bj][1]; }
;                     if (ACT == 1) {
; #pragma unroll
;                         for (int j = 0; j < 4; ++j) { const float a = fmaxf(v0[j], 0.f), b = fmaxf(v1[j], 0.f); v0[j] = a * a; v1[j] = b * b; } }
;                     if (ACT == 2) { if (tsel == 0) {
; #pragma unroll
;                         for (int j = 0; j < 4; ++j) { const float a = v0[j], b = v1[j];
;                             v0[j] = a * fast_sigmoid(1.5957691216057308f * (a + 0.044715f * a * a * a)); v1[j] = b * fast_sigmoid(1.5957691216057308f * (b + 0.044715f * b * b * b)); } } }
;                     u32x4 w; w.x = pk_bf16(v0[0], v0[1]); w.y = pk_bf16(v0[2], v0[3]); w.z = pk_bf16(v1[0], v1[1]); w.w = pk_bf16(v1[2], v1[3]);
;                     *(u32x4*)(rowp + bj * HALF) = w; } }
	v_cvt_pk_bf16_f32 v57, v62, v63
	v_cvt_pk_bf16_f32 v58, v66, v67
	v_cvt_pk_bf16_f32 v59, v70, v71
	v_addc_co_u32_e32 v61, vcc, 0, v145, vcc
	v_max_f32_e32 v50, 0, v50
	v_max_f32_e32 v51, 0, v51
	global_store_dwordx4 v[60:61], v[56:59], off
	v_pk_mul_f32 v[52:53], v[52:53], v[68:69] op_sel_hi:[1,0]
	v_pk_mul_f32 v[48:49], v[48:49], v[68:69] op_sel_hi:[1,0]
	v_pk_mul_f32 v[58:59], v[50:51], v[50:51]
	v_cvt_f32_u32_e32 v51, v169
	v_pk_mul_f32 v[54:55], v[54:55], v[68:69] op_sel_hi:[1,0]
	v_max_f32_e32 v52, 0, v52
	v_max_f32_e32 v48, 0, v48
	v_max_f32_e32 v53, 0, v53
	v_max_f32_e32 v49, 0, v49
	v_mul_f32_e32 v51, 0x3b800000, v51
	v_pk_mul_f32 v[52:53], v[52:53], v[52:53]
	v_pk_mul_f32 v[56:57], v[48:49], v[48:49]
	v_max_f32_e32 v48, 0, v54
	v_max_f32_e32 v49, 0, v55
	v_fmamk_f32 v51, v51, 0x3a000000, v156
	v_pk_mul_f32 v[54:55], v[48:49], v[48:49]
	v_cvt_pk_bf16_f32 v48, v52, v53
	v_rsq_f32_e32 v52, v51
	v_cvt_pk_bf16_f32 v49, v54, v55
	v_cvt_pk_bf16_f32 v50, v56, v57
	v_cvt_pk_bf16_f32 v51, v58, v59
	v_pk_mul_f32 v[44:45], v[44:45], v[52:53] op_sel_hi:[1,0]
	v_pk_mul_f32 v[40:41], v[40:41], v[52:53] op_sel_hi:[1,0]
	s_mov_b64 s[34:35], 0x240000
	v_pk_mul_f32 v[46:47], v[46:47], v[52:53] op_sel_hi:[1,0]
	v_pk_mul_f32 v[42:43], v[42:43], v[52:53] op_sel_hi:[1,0]
	v_max_f32_e32 v44, 0, v44
	v_max_f32_e32 v40, 0, v40
	v_max_f32_e32 v45, 0, v45
	v_max_f32_e32 v41, 0, v41
	global_store_dwordx4 v[64:65], v[48:51], off offset:256
	v_pk_mul_f32 v[44:45], v[44:45], v[44:45]
	v_max_f32_e32 v42, 0, v42
	v_lshl_add_u64 v[48:49], v[144:145], 0, s[34:35]
	v_pk_mul_f32 v[50:51], v[40:41], v[40:41]
	v_max_f32_e32 v40, 0, v46
	v_max_f32_e32 v41, 0, v47
	v_max_f32_e32 v43, 0, v43
	s_mov_b32 s34, 0x240000
	v_pk_mul_f32 v[46:47], v[40:41], v[40:41]
	v_pk_mul_f32 v[54:55], v[42:43], v[42:43]
	v_cvt_pk_bf16_f32 v40, v44, v45
	v_add_co_u32_e32 v44, vcc, s34, v144
	v_pk_mul_f32 v[34:35], v[34:35], v[52:53] op_sel_hi:[1,0]
	v_cvt_pk_bf16_f32 v41, v46, v47
	v_cvt_pk_bf16_f32 v42, v50, v51
	v_cvt_pk_bf16_f32 v43, v54, v55
	v_addc_co_u32_e32 v45, vcc, 0, v145, vcc
	v_max_f32_e32 v34, 0, v34
	v_max_f32_e32 v35, 0, v35
	global_store_dwordx4 v[44:45], v[40:43], off
	v_pk_mul_f32 v[36:37], v[36:37], v[52:53] op_sel_hi:[1,0]
	v_pk_mul_f32 v[32:33], v[32:33], v[52:53] op_sel_hi:[1,0]
	v_pk_mul_f32 v[42:43], v[34:35], v[34:35]
	v_cvt_f32_u32_e32 v35, v170
	v_pk_mul_f32 v[38:39], v[38:39], v[52:53] op_sel_hi:[1,0]
	v_max_f32_e32 v36, 0, v36
	v_max_f32_e32 v32, 0, v32
	v_max_f32_e32 v37, 0, v37
	v_max_f32_e32 v33, 0, v33
	v_mul_f32_e32 v35, 0x3b800000, v35
	v_pk_mul_f32 v[36:37], v[36:37], v[36:37]
	v_pk_mul_f32 v[40:41], v[32:33], v[32:33]
	v_max_f32_e32 v32, 0, v38
	v_max_f32_e32 v33, 0, v39
	v_fmamk_f32 v35, v35, 0x3a000000, v156
	v_pk_mul_f32 v[38:39], v[32:33], v[32:33]
	v_cvt_pk_bf16_f32 v32, v36, v37
	v_rsq_f32_e32 v36, v35
	v_cvt_pk_bf16_f32 v33, v38, v39
	v_cvt_pk_bf16_f32 v34, v40, v41
	v_cvt_pk_bf16_f32 v35, v42, v43
	v_pk_mul_f32 v[28:29], v[28:29], v[36:37] op_sel_hi:[1,0]
	v_pk_mul_f32 v[24:25], v[24:25], v[36:37] op_sel_hi:[1,0]
	v_pk_mul_f32 v[30:31], v[30:31], v[36:37] op_sel_hi:[1,0]
	v_pk_mul_f32 v[26:27], v[26:27], v[36:37] op_sel_hi:[1,0]
	v_max_f32_e32 v28, 0, v28
	v_max_f32_e32 v24, 0, v24
	v_max_f32_e32 v29, 0, v29
	v_max_f32_e32 v25, 0, v25
	global_store_dwordx4 v[48:49], v[32:35], off offset:256
	v_pk_mul_f32 v[28:29], v[28:29], v[28:29]
	v_max_f32_e32 v26, 0, v26
	v_pk_mul_f32 v[34:35], v[24:25], v[24:25]
	v_max_f32_e32 v24, 0, v30
	v_max_f32_e32 v25, 0, v31
	v_max_f32_e32 v27, 0, v27
	v_pk_mul_f32 v[30:31], v[24:25], v[24:25]
	v_pk_mul_f32 v[38:39], v[26:27], v[26:27]
	v_cvt_pk_bf16_f32 v24, v28, v29
	v_add_co_u32_e32 v28, vcc, s25, v144
	v_pk_mul_f32 v[18:19], v[18:19], v[36:37] op_sel_hi:[1,0]
	v_cvt_pk_bf16_f32 v25, v30, v31
	v_cvt_pk_bf16_f32 v26, v34, v35
	v_cvt_pk_bf16_f32 v27, v38, v39
	v_addc_co_u32_e32 v29, vcc, 0, v145, vcc
	v_max_f32_e32 v18, 0, v18
	v_max_f32_e32 v19, 0, v19
	global_store_dwordx4 v[28:29], v[24:27], off
	v_pk_mul_f32 v[20:21], v[20:21], v[36:37] op_sel_hi:[1,0]
	v_pk_mul_f32 v[16:17], v[16:17], v[36:37] op_sel_hi:[1,0]
	v_pk_mul_f32 v[26:27], v[18:19], v[18:19]
	v_cvt_f32_u32_e32 v19, v147
	v_pk_mul_f32 v[22:23], v[22:23], v[36:37] op_sel_hi:[1,0]
	v_max_f32_e32 v20, 0, v20
	v_max_f32_e32 v16, 0, v16
	v_max_f32_e32 v21, 0, v21
	v_max_f32_e32 v17, 0, v17
	v_mul_f32_e32 v19, 0x3b800000, v19
	v_pk_mul_f32 v[20:21], v[20:21], v[20:21]
	v_pk_mul_f32 v[24:25], v[16:17], v[16:17]
	v_max_f32_e32 v16, 0, v22
	v_max_f32_e32 v17, 0, v23
	v_fmamk_f32 v19, v19, 0x3a000000, v156
	v_pk_mul_f32 v[22:23], v[16:17], v[16:17]
	v_cvt_pk_bf16_f32 v16, v20, v21
	v_rsq_f32_e32 v20, v19
	s_mov_b64 s[34:35], 0x280000
	v_lshl_add_u64 v[32:33], v[144:145], 0, s[34:35]
	v_cvt_pk_bf16_f32 v17, v22, v23
	v_pk_mul_f32 v[12:13], v[12:13], v[20:21] op_sel_hi:[1,0]
	v_pk_mul_f32 v[8:9], v[8:9], v[20:21] op_sel_hi:[1,0]
	v_cvt_pk_bf16_f32 v18, v24, v25
	v_cvt_pk_bf16_f32 v19, v26, v27
	v_pk_mul_f32 v[14:15], v[14:15], v[20:21] op_sel_hi:[1,0]
	v_pk_mul_f32 v[10:11], v[10:11], v[20:21] op_sel_hi:[1,0]
	v_max_f32_e32 v12, 0, v12
	v_max_f32_e32 v8, 0, v8
	v_max_f32_e32 v13, 0, v13
	v_max_f32_e32 v9, 0, v9
	global_store_dwordx4 v[32:33], v[16:19], off offset:256
	v_pk_mul_f32 v[12:13], v[12:13], v[12:13]
	v_max_f32_e32 v10, 0, v10
	v_pk_mul_f32 v[18:19], v[8:9], v[8:9]
	v_max_f32_e32 v8, 0, v14
	v_max_f32_e32 v9, 0, v15
	v_max_f32_e32 v11, 0, v11
	v_pk_mul_f32 v[14:15], v[8:9], v[8:9]
	v_pk_mul_f32 v[22:23], v[10:11], v[10:11]
	v_cvt_pk_bf16_f32 v8, v12, v13
	v_add_co_u32_e32 v12, vcc, s33, v144
	v_pk_mul_f32 v[0:1], v[0:1], v[20:21] op_sel_hi:[1,0]
	v_cvt_pk_bf16_f32 v9, v14, v15
	v_cvt_pk_bf16_f32 v10, v18, v19
	v_cvt_pk_bf16_f32 v11, v22, v23
	v_addc_co_u32_e32 v13, vcc, 0, v145, vcc
	v_pk_mul_f32 v[6:7], v[6:7], v[20:21] op_sel_hi:[1,0]
	v_pk_mul_f32 v[4:5], v[4:5], v[20:21] op_sel_hi:[1,0]
	v_pk_mul_f32 v[2:3], v[2:3], v[20:21] op_sel_hi:[1,0]
	v_max_f32_e32 v0, 0, v0
	v_max_f32_e32 v1, 0, v1
	global_store_dwordx4 v[12:13], v[8:11], off
	v_max_f32_e32 v4, 0, v4
	v_max_f32_e32 v5, 0, v5
	v_pk_mul_f32 v[8:9], v[0:1], v[0:1]
	v_max_f32_e32 v0, 0, v6
	v_max_f32_e32 v2, 0, v2
	v_max_f32_e32 v1, 0, v7
	v_max_f32_e32 v3, 0, v3
	v_pk_mul_f32 v[4:5], v[4:5], v[4:5]
	v_pk_mul_f32 v[6:7], v[0:1], v[0:1]
	v_pk_mul_f32 v[10:11], v[2:3], v[2:3]
	v_lshl_add_u64 v[16:17], v[144:145], 0, s[54:55]
	v_cvt_pk_bf16_f32 v0, v4, v5
	v_cvt_pk_bf16_f32 v1, v6, v7
	v_cvt_pk_bf16_f32 v2, v8, v9
	v_cvt_pk_bf16_f32 v3, v10, v11
	s_and_b64 vcc, exec, s[16:17]
	s_mov_b32 s34, s56
	global_store_dwordx4 v[16:17], v[0:3], off offset:256
	s_cbranch_vccz .LBB0_523
	s_waitcnt vmcnt(0)
	s_cmpk_gt_u32 s4, 0xff
	s_cbranch_scc1 .LBB0_534
	s_barrier

; __device__ __forceinline__ int opaque_tid(int wv) { int l; asm volatile("v_mbcnt_lo_u32_b32 %0, -1, 0\n\tv_mbcnt_hi_u32_b32 %0, -1, %0" : "=v"(l)); return wv * 64 + l; }
; #define PG8_BAR __builtin_amdgcn_s_barrier()
; template <class Epi>
; __device__ __forceinline__ void gemm_phase(LAS unsigned char* lds, const Gemm g, const StaticOrder& S, const Epi& E, int wv) {
;     const int tid = opaque_tid(wv), wid = __builtin_amdgcn_readfirstlane(tid >> 6), lane = tid & 63, wr = wid >> 2, wc = wid & 3, fr = lane & 15, fq = lane >> 4;
;     const int K = g.K, nt = K / BK;
;     unsigned voffA[2], voffB[2];
; #pragma unroll
;     for (int i = 0; i < 2; ++i) { int R, C; stage_rc(tid * 16 + i * 8192, R, C); const int Rb = Epi::PERM ? ((R & ~31) + perm32(R & 31)) : R;
;         voffA[i] = (unsigned)(R * g.lda + C) * 2u; voffB[i] = (unsigned)(Rb * g.ldb + C) * 2u; }
;     const bool krev = (g.adiag & 2) != 0;
;     const ptrdiff_t kstep = krev ? -(ptrdiff_t)(BK * 2) : (ptrdiff_t)(BK * 2);
;     const size_t kbeg = krev ? (size_t)(nt - 1) * (BK * 2) : 0;
;     const size_t hstepA = (size_t)HALF * g.lda * 2, hstepB = (size_t)HALF * g.ldb * 2;
;     const size_t tstepA = 2 * hstepA, tstepB = 2 * hstepB;
;     const unsigned ldsw = (unsigned)wid * 1024u;
;     const int aoff = lds_byte(wr * 64 + fr, fq * 8), boff = lds_byte(wc * 32 + fr, fq * 8);
;     ...
;     Unit cur, nxt; int ui = 0;
;     if (!S.next(0, cur)) return;
;     f32x4 acc[2][2][4][2];
; #pragma unroll
;     for (int a = 0; a < 2; ++a)
; #pragma unroll
;         for (int b = 0; b < 2; ++b)
; #pragma unroll
;             for (int m = 0; m < 4; ++m)
; #pragma unroll
;                 for (int n = 0; n < 2; ++n) acc[a][b][m][n] = (f32x4){0.f, 0.f, 0.f, 0.f};
;     bf16x8 At[4][2], B0[2][2], B1[2][2];
;     const char* cA = (const char*)g.A + (size_t)cur.pm * tstepA + ((g.adiag & 1) ? (size_t)(cur.pn >> 1) * K * 2 : 0) + kbeg;
;     const char* cB = (const char*)g.Bt + (size_t)cur.pn * tstepB + kbeg;
;     PG8_STAGE(PG8_SB(0, 0), cB, voffB); PG8_STAGE(PG8_SA(0, 0), cA, voffA); PG8_STAGE(PG8_SB(0, 1), cB + hstepB, voffB); PG8_STAGE(PG8_SA(0, 1), cA + hstepA, voffA);
;     if (wr == 1) PG8_BAR;
;     PG8_WAIT_V(4); PG8_BAR;
;     PG8_STAGE(PG8_SB(1, 0), cB + kstep, voffB); PG8_STAGE(PG8_SA(1, 0), cA + kstep, voffA); PG8_STAGE(PG8_SB(1, 1), cB + hstepB + kstep, voffB);
;     PG8_WAIT_V(6); PG8_BAR;
.LBB0_593:
	v_readlane_b32 s6, v255, 10
	v_readlane_b32 s7, v255, 11
	s_and_b64 vcc, exec, s[6:7]
	s_cbranch_vccnz .LBB0_629
	v_ashrrev_i32_e32 v3, 31, v1
	v_lshrrev_b32_e32 v3, 26, v3
	v_lshlrev_b32_e32 v2, 4, v1
	v_add_u32_e32 v3, v1, v3
	v_bfe_i32 v1, v1, 27, 1
	v_lshrrev_b32_e32 v1, 22, v1
	v_add_u32_e32 v1, v2, v1
	v_and_b32_e32 v1, 0xfffffc00, v1
	v_sub_u32_e32 v1, v2, v1
	v_lshrrev_b32_e32 v4, 4, v1
	v_bitop3_b32 v1, v4, v1, 32 bitop3:0x6c
	v_ashrrev_i32_e32 v5, 31, v1
	v_ashrrev_i32_e32 v3, 6, v3
	v_lshrrev_b32_e32 v5, 26, v5
	v_lshlrev_b32_e32 v4, 3, v3
	v_add_u32_e32 v5, v1, v5
	v_and_b32_e32 v4, -16, v4
	v_ashrrev_i32_e32 v6, 6, v5
	v_and_b32_e32 v5, 0xc0, v5
	v_add_u32_e32 v4, v6, v4
	v_sub_u32_e32 v1, v1, v5
	v_mov_b32_e32 v5, 1
	v_lshlrev_b32_e32 v3, 5, v3
	v_ashrrev_i16_sdwa v1, v5, sext(v1) dst_sel:DWORD dst_unused:UNUSED_PAD src0_sel:DWORD src1_sel:BYTE_0
	v_lshlrev_b32_e32 v7, 1, v4
	v_lshrrev_b32_e32 v8, 2, v4
	v_and_b32_e32 v6, 3, v6
	s_mov_b32 s7, 0x3ffe0
	v_and_b32_e32 v3, 32, v3
	v_bfe_i32 v1, v1, 0, 16
	v_and_b32_e32 v7, 24, v7
	v_and_b32_e32 v8, 4, v8
	v_and_or_b32 v6, v4, s7, v6
	v_or3_b32 v6, v6, v8, v7
	v_add_lshl_u32 v1, v3, v1, 1
	v_lshl_add_u32 v144, v4, 14, v1
	v_lshl_add_u32 v146, v6, 14, v1
	v_add_u32_e32 v1, 0x2000, v2
	v_ashrrev_i32_e32 v2, 31, v1
	v_lshrrev_b32_e32 v2, 22, v2
	v_add_u32_e32 v2, v1, v2
	v_ashrrev_i32_e32 v2, 10, v2
	v_mul_i32_i24_e32 v3, 0x400, v2
	v_sub_u32_e32 v1, v1, v3
	v_lshrrev_b32_e32 v3, 4, v1
	v_bitop3_b32 v1, v3, v1, 32 bitop3:0x6c
	v_ashrrev_i32_e32 v4, 31, v1
	v_lshrrev_b32_e32 v4, 26, v4
	v_lshlrev_b32_e32 v3, 3, v2
	v_add_u32_e32 v4, v1, v4
	s_waitcnt lgkmcnt(0)
	s_add_u32 s5, s50, 0xf300000
	v_and_b32_e32 v3, -16, v3
	v_ashrrev_i32_e32 v6, 6, v4
	s_addc_u32 s6, s51, 0
	v_add_u32_e32 v3, v6, v3
	v_and_b32_e32 v6, 3, v6
	s_ashr_i32 s23, s4, 6
	s_ashr_i32 s69, s68, 31
	s_ashr_i32 s14, s4, 8
	v_and_or_b32 v6, v3, s7, v6
	s_lshl_b32 s7, s23, 10
	s_lshl_b64 s[8:9], s[68:69], 22
	s_add_u32 s12, s5, s8
	s_addc_u32 s13, s6, s9
	s_ashr_i32 s71, s70, 31
	s_lshl_b64 s[8:9], s[70:71], 22
	s_add_u32 s10, s16, s8
	s_addc_u32 s11, s17, s9
	s_add_u32 s15, s10, 0x4900000
	v_and_b32_e32 v4, 0xc0, v4
	s_addc_u32 s22, s11, 0
	v_sub_u32_e32 v1, v1, v4
	s_add_u32 s72, s10, 0x4903f80
	v_lshlrev_b32_e32 v2, 5, v2
	v_ashrrev_i16_sdwa v1, v5, sext(v1) dst_sel:DWORD dst_unused:UNUSED_PAD src0_sel:DWORD src1_sel:BYTE_0
	v_lshlrev_b32_e32 v4, 1, v3
	v_lshrrev_b32_e32 v5, 2, v3
	s_addc_u32 s73, s11, 0
	s_add_i32 s8, s7, 0
	v_and_b32_e32 v2, 32, v2
	v_bfe_i32 v1, v1, 0, 16
	v_and_b32_e32 v4, 24, v4
	v_and_b32_e32 v5, 4, v5
	s_add_i32 m0, s8, 0x10000
	v_or3_b32 v4, v6, v5, v4
	v_add_lshl_u32 v1, v2, v1, 1
	global_load_lds_dwordx4 v146, s[72:73]
	s_add_i32 m0, s8, 0x12000
	v_lshl_add_u32 v150, v4, 14, v1
	s_add_u32 s74, s12, 0x3f80
	global_load_lds_dwordx4 v150, s[72:73]
	s_addc_u32 s75, s13, 0
	s_mov_b32 m0, s8
	s_add_i32 s9, s8, 0x2000
	v_lshl_add_u32 v148, v3, 14, v1
	global_load_lds_dwordx4 v144, s[74:75]
	s_mov_b32 m0, s9
	s_add_u32 s10, s10, 0x4b03f80
	global_load_lds_dwordx4 v148, s[74:75]
	s_addc_u32 s11, s11, 0
	s_add_i32 m0, s8, 0x14000
	v_mov_b32_e32 v147, 0
	global_load_lds_dwordx4 v146, s[10:11]
	s_add_i32 m0, s8, 0x16000
	s_add_u32 s24, s12, 0x203f80
	global_load_lds_dwordx4 v150, s[10:11]
	s_addc_u32 s25, s13, 0
	s_add_i32 s10, s8, 0x4000
	s_mov_b32 m0, s10
	s_add_i32 s11, s8, 0x6000
	global_load_lds_dwordx4 v144, s[24:25]
	s_mov_b32 m0, s11
	s_mov_b32 s51, 0
	global_load_lds_dwordx4 v148, s[24:25]
	v_mov_b32_e32 v151, v147
	v_mov_b32_e32 v145, v147
	s_cmp_lg_u32 s14, 1
	v_mov_b32_e32 v149, v147
	s_cbranch_scc1 .LBB0_596
	s_barrier
	s_setprio 1

; #define PG8_STAGE(bufoff, gbase, voff) do { _Pragma("unroll") for (int _i = 0; _i < 2; ++_i) \
;         __builtin_amdgcn_global_load_lds((const unsigned*)((const char*)(gbase) + (voff)[_i]), (LAS unsigned*)(lds + (bufoff) + ldsw + _i * 8192), 16, 0, 0); } while (0)
; #define PG8_BAR __builtin_amdgcn_s_barrier()
; template <class Epi>
; __device__ __forceinline__ void gemm_phase(LAS unsigned char* lds, const Gemm g, const StaticOrder& S, const Epi& E, int wv) {
;     ...
;         const bool has_next = S.next(ui + 1, nxt);
;         const char* nA = has_next ? (const char*)g.A + (size_t)nxt.pm * tstepA + ((g.adiag & 1) ? (size_t)(nxt.pn >> 1) * K * 2 : 0) + kbeg : cA;
;         const char* nB = has_next ? (const char*)g.Bt + (size_t)nxt.pn * tstepB + kbeg : cB;
;         for (int t = 0; t < nt; t += 2) {
;             const bool last = (t == nt - 2);
;             const char* a1 = cA + (ptrdiff_t)(t + 1) * kstep;
;             const char* a2 = last ? nA : cA + (ptrdiff_t)(t + 2) * kstep; const char* b2 = last ? nB : cB + (ptrdiff_t)(t + 2) * kstep;
;             const char* a3 = a2 + kstep; const char* b3 = b2 + kstep;
;             PG8_LDB(B0, 0, 0); PG8_SCHED; PG8_LDA(At, 0, 0); PG8_STAGE(PG8_SA(1, 1), a1 + hstepA, voffA);
;             PG8_WAIT_L(8); PG8_BAR; PG8_WAIT_L(0); PG8_MMA(0, 0, At, B0); PG8_BAR; PG8_SCHED;
;             PG8_LDB(B1, 0, 1); PG8_STAGE(PG8_SB(0, 0), b2, voffB);
;             PG8_BAR; PG8_WAIT_L(0); PG8_MMA(0, 1, At, B1); PG8_BAR;
;             PG8_LDA(At, 0, 1); PG8_STAGE(PG8_SA(0, 0), a2, voffA);
;             PG8_BAR; PG8_WAIT_L(0); PG8_MMA(1, 0, At, B0); PG8_BAR; PG8_SCHED;
;             PG8_STAGE(PG8_SB(0, 1), b2 + hstepB, voffB);
;             PG8_WAIT_V(6); PG8_BAR; PG8_MMA(1, 1, At, B1); PG8_BAR;
;             PG8_LDB(B0, 1, 0); PG8_SCHED; PG8_LDA(At, 1, 0); PG8_STAGE(PG8_SA(0, 1), a2 + hstepA, voffA);
;             PG8_WAIT_L(8); PG8_BAR; PG8_WAIT_L(0); PG8_MMA(0, 0, At, B0); PG8_BAR; PG8_SCHED;
;             PG8_LDB(B1, 1, 1); PG8_STAGE(PG8_SB(1, 0), b3, voffB);
;             PG8_BAR; PG8_WAIT_L(0); PG8_MMA(0, 1, At, B1); PG8_BAR;
;             PG8_LDA(At, 1, 1); PG8_STAGE(PG8_SA(1, 0), a3, voffA);
;             PG8_BAR; PG8_WAIT_L(0); PG8_MMA(1, 0, At, B0); PG8_BAR; PG8_SCHED;
;             PG8_STAGE(PG8_SB(1, 1), b3 + hstepB, voffB);
;             PG8_WAIT_V(6); PG8_BAR; PG8_MMA(1, 1, At, B1); PG8_BAR;
.LBB0_605:
	s_or_b32 s50, s35, 1
	s_lshl_b64 s[38:39], s[50:51], 7
	s_sub_u32 s38, 0, s38
	s_subb_u32 s39, 0, s39
	s_add_u32 s38, s33, s38
	s_addc_u32 s39, s34, s39
	s_add_i32 m0, s8, 0xc000
	ds_read_b128 v[156:159], v175
	ds_read_b128 v[160:163], v175 offset:1024
	ds_read_b128 v[164:167], v175 offset:2048
	ds_read_b128 v[168:171], v175 offset:3072
	ds_read_b128 v[176:179], v175 offset:4096
	ds_read_b128 v[180:183], v175 offset:5120
	ds_read_b128 v[184:187], v175 offset:6144
	ds_read_b128 v[188:191], v175 offset:7168
	global_load_lds_dwordx4 v144, s[38:39]
	s_add_i32 m0, s8, 0xe000
	s_nop 0
	global_load_lds_dwordx4 v148, s[38:39]
	s_waitcnt lgkmcnt(8)
	s_barrier
	s_waitcnt lgkmcnt(0)
	s_waitcnt lgkmcnt(0)
	v_mfma_f32_16x16x32_bf16 v[124:127], v[128:131], v[156:159], v[124:127]
	v_mfma_f32_16x16x32_bf16 v[120:123], v[136:139], v[156:159], v[120:123]
	v_mfma_f32_16x16x32_bf16 v[108:111], v[128:131], v[164:167], v[108:111]
	v_mfma_f32_16x16x32_bf16 v[104:107], v[136:139], v[164:167], v[104:107]
	v_mfma_f32_16x16x32_bf16 v[92:95], v[128:131], v[176:179], v[92:95]
	v_mfma_f32_16x16x32_bf16 v[88:91], v[136:139], v[176:179], v[88:91]
	v_mfma_f32_16x16x32_bf16 v[76:79], v[128:131], v[184:187], v[76:79]
	v_mfma_f32_16x16x32_bf16 v[72:75], v[136:139], v[184:187], v[72:75]
	v_mfma_f32_16x16x32_bf16 v[124:127], v[132:135], v[160:163], v[124:127]
	v_mfma_f32_16x16x32_bf16 v[120:123], v[140:143], v[160:163], v[120:123]
	v_mfma_f32_16x16x32_bf16 v[108:111], v[132:135], v[168:171], v[108:111]
	v_mfma_f32_16x16x32_bf16 v[104:107], v[140:143], v[168:171], v[104:107]
	v_mfma_f32_16x16x32_bf16 v[92:95], v[132:135], v[180:183], v[92:95]
	v_mfma_f32_16x16x32_bf16 v[88:91], v[140:143], v[180:183], v[88:91]
	v_mfma_f32_16x16x32_bf16 v[76:79], v[132:135], v[188:191], v[76:79]
	v_mfma_f32_16x16x32_bf16 v[72:75], v[140:143], v[188:191], v[72:75]
	s_barrier
	s_add_i32 s38, s22, s7
	v_add_u32_e32 v204, s23, v173
	s_add_u32 s98, s82, s58
	s_addc_u32 s99, s83, s59
	s_mov_b32 m0, s38
	ds_read_b128 v[192:195], v204
	ds_read_b128 v[196:199], v204 offset:1024
	ds_read_b128 v[200:203], v204 offset:2048
	ds_read_b128 v[204:207], v204 offset:3072
	global_load_lds_dwordx4 v146, s[82:83]
	s_add_i32 m0, s38, 0x2000
	s_nop 0
	global_load_lds_dwordx4 v150, s[82:83]
	s_barrier
	s_waitcnt lgkmcnt(0)
	s_waitcnt lgkmcnt(0)
	v_mfma_f32_16x16x32_bf16 v[116:119], v[192:195], v[156:159], v[116:119]
	v_mfma_f32_16x16x32_bf16 v[112:115], v[200:203], v[156:159], v[112:115]
	v_mfma_f32_16x16x32_bf16 v[100:103], v[192:195], v[164:167], v[100:103]
	v_mfma_f32_16x16x32_bf16 v[96:99], v[200:203], v[164:167], v[96:99]
	v_mfma_f32_16x16x32_bf16 v[84:87], v[192:195], v[176:179], v[84:87]
	v_mfma_f32_16x16x32_bf16 v[80:83], v[200:203], v[176:179], v[80:83]
	v_mfma_f32_16x16x32_bf16 v[68:71], v[192:195], v[184:187], v[68:71]
	v_mfma_f32_16x16x32_bf16 v[64:67], v[200:203], v[184:187], v[64:67]
	v_mfma_f32_16x16x32_bf16 v[116:119], v[196:199], v[160:163], v[116:119]
	v_mfma_f32_16x16x32_bf16 v[112:115], v[204:207], v[160:163], v[112:115]
	v_mfma_f32_16x16x32_bf16 v[100:103], v[196:199], v[168:171], v[100:103]
	v_mfma_f32_16x16x32_bf16 v[96:99], v[204:207], v[168:171], v[96:99]
	v_mfma_f32_16x16x32_bf16 v[84:87], v[196:199], v[180:183], v[84:87]
	v_mfma_f32_16x16x32_bf16 v[80:83], v[204:207], v[180:183], v[80:83]
	v_mfma_f32_16x16x32_bf16 v[68:71], v[196:199], v[188:191], v[68:71]
	v_mfma_f32_16x16x32_bf16 v[64:67], v[204:207], v[188:191], v[64:67]
	s_mov_b32 m0, s8
	s_add_u32 s100, s84, s58
	s_addc_u32 s101, s85, s59
	s_barrier
	ds_read_b128 v[156:159], v175 offset:16384
	ds_read_b128 v[160:163], v175 offset:17408
	ds_read_b128 v[164:167], v175 offset:18432
	ds_read_b128 v[168:171], v175 offset:19456
	ds_read_b128 v[176:179], v175 offset:20480
	ds_read_b128 v[180:183], v175 offset:21504
	ds_read_b128 v[184:187], v175 offset:22528
	ds_read_b128 v[188:191], v175 offset:23552
	global_load_lds_dwordx4 v144, s[84:85]
	s_mov_b32 m0, s9
	s_nop 0
	global_load_lds_dwordx4 v148, s[84:85]
	s_waitcnt vmcnt(10)
	s_barrier
	s_waitcnt lgkmcnt(0)
	s_waitcnt lgkmcnt(0)
	v_mfma_f32_16x16x32_bf16 v[60:63], v[128:131], v[156:159], v[60:63]
	v_mfma_f32_16x16x32_bf16 v[56:59], v[136:139], v[156:159], v[56:59]
	v_mfma_f32_16x16x32_bf16 v[44:47], v[128:131], v[164:167], v[44:47]
	v_mfma_f32_16x16x32_bf16 v[40:43], v[136:139], v[164:167], v[40:43]
	v_mfma_f32_16x16x32_bf16 v[28:31], v[128:131], v[176:179], v[28:31]
	v_mfma_f32_16x16x32_bf16 v[24:27], v[136:139], v[176:179], v[24:27]
	v_mfma_f32_16x16x32_bf16 v[12:15], v[128:131], v[184:187], v[12:15]
	v_mfma_f32_16x16x32_bf16 v[8:11], v[136:139], v[184:187], v[8:11]
	v_mfma_f32_16x16x32_bf16 v[60:63], v[132:135], v[160:163], v[60:63]
	v_mfma_f32_16x16x32_bf16 v[56:59], v[140:143], v[160:163], v[56:59]
	v_mfma_f32_16x16x32_bf16 v[44:47], v[132:135], v[168:171], v[44:47]
	v_mfma_f32_16x16x32_bf16 v[40:43], v[140:143], v[168:171], v[40:43]
	v_mfma_f32_16x16x32_bf16 v[28:31], v[132:135], v[180:183], v[28:31]
	v_mfma_f32_16x16x32_bf16 v[24:27], v[140:143], v[180:183], v[24:27]
	v_mfma_f32_16x16x32_bf16 v[12:15], v[132:135], v[188:191], v[12:15]
	v_mfma_f32_16x16x32_bf16 v[8:11], v[140:143], v[188:191], v[8:11]
	s_barrier
	s_add_u32 s38, s82, 0x200000
	s_addc_u32 s39, s83, 0
	s_add_i32 s40, s23, s7
	s_mov_b32 m0, s40
	s_nop 0
	global_load_lds_dwordx4 v146, s[38:39]
	s_add_i32 m0, s40, 0x2000
	s_nop 0
	global_load_lds_dwordx4 v150, s[38:39]
	s_add_i32 s40, 0, 0x18000
	v_add_u32_e32 v140, s40, v173
	ds_read_b128 v[128:131], v140
	ds_read_b128 v[132:135], v140 offset:1024
	ds_read_b128 v[136:139], v140 offset:2048
	ds_read_b128 v[140:143], v140 offset:3072
	s_waitcnt vmcnt(6)
	s_barrier
; #define PG8_STAGE(bufoff, gbase, voff) do { _Pragma("unroll") for (int _i = 0; _i < 2; ++_i) \
;         __builtin_amdgcn_global_load_lds((const unsigned*)((const char*)(gbase) + (voff)[_i]), (LAS unsigned*)(lds + (bufoff) + ldsw + _i * 8192), 16, 0, 0); } while (0)
; #define PG8_LDA(dst, b, h) do { _Pragma("unroll") for (int m = 0; m < 4; ++m) _Pragma("unroll") for (int k = 0; k < 2; ++k) dst[m][k] = *(const LAS bf16x8*)(lds + PG8_SA(b, h) + aoff + m * 2048 + k * 1024); } while (0)
; #define PG8_WAIT_V(n) asm volatile("s_waitcnt vmcnt(" #n ")" ::: "memory")
; #define PG8_BAR __builtin_amdgcn_s_barrier()
; template <class Epi>
; __device__ __forceinline__ void gemm_phase(LAS unsigned char* lds, const Gemm g, const StaticOrder& S, const Epi& E, int wv) {
;     ...
;         for (int t = 0; t < nt; t += 2) {
;             const bool last = (t == nt - 2);
;             const char* a1 = cA + (ptrdiff_t)(t + 1) * kstep;
;             const char* a2 = last ? nA : cA + (ptrdiff_t)(t + 2) * kstep; const char* b2 = last ? nB : cB + (ptrdiff_t)(t + 2) * kstep;
;             const char* a3 = a2 + kstep; const char* b3 = b2 + kstep;
;             PG8_LDB(B0, 0, 0); PG8_SCHED; PG8_LDA(At, 0, 0); PG8_STAGE(PG8_SA(1, 1), a1 + hstepA, voffA);
;             PG8_WAIT_L(8); PG8_BAR; PG8_WAIT_L(0); PG8_MMA(0, 0, At, B0); PG8_BAR; PG8_SCHED;
;             PG8_LDB(B1, 0, 1); PG8_STAGE(PG8_SB(0, 0), b2, voffB);
;             PG8_BAR; PG8_WAIT_L(0); PG8_MMA(0, 1, At, B1); PG8_BAR;
;             PG8_LDA(At, 0, 1); PG8_STAGE(PG8_SA(0, 0), a2, voffA);
;             PG8_BAR; PG8_WAIT_L(0); PG8_MMA(1, 0, At, B0); PG8_BAR; PG8_SCHED;
;             PG8_STAGE(PG8_SB(0, 1), b2 + hstepB, voffB);
;             PG8_WAIT_V(6); PG8_BAR; PG8_MMA(1, 1, At, B1); PG8_BAR;
;             PG8_LDB(B0, 1, 0); PG8_SCHED; PG8_LDA(At, 1, 0); PG8_STAGE(PG8_SA(0, 1), a2 + hstepA, voffA);
;             PG8_WAIT_L(8); PG8_BAR; PG8_WAIT_L(0); PG8_MMA(0, 0, At, B0); PG8_BAR; PG8_SCHED;
;             PG8_LDB(B1, 1, 1); PG8_STAGE(PG8_SB(1, 0), b3, voffB);
;             PG8_BAR; PG8_WAIT_L(0); PG8_MMA(0, 1, At, B1); PG8_BAR;
;             PG8_LDA(At, 1, 1); PG8_STAGE(PG8_SA(1, 0), a3, voffA);
;             PG8_BAR; PG8_WAIT_L(0); PG8_MMA(1, 0, At, B0); PG8_BAR; PG8_SCHED;
;             PG8_STAGE(PG8_SB(1, 1), b3 + hstepB, voffB);
;             PG8_WAIT_V(6); PG8_BAR; PG8_MMA(1, 1, At, B1); PG8_BAR;
	v_mfma_f32_16x16x32_bf16 v[52:55], v[192:195], v[156:159], v[52:55]
	v_mfma_f32_16x16x32_bf16 v[48:51], v[200:203], v[156:159], v[48:51]
	v_mfma_f32_16x16x32_bf16 v[36:39], v[192:195], v[164:167], v[36:39]
	v_mfma_f32_16x16x32_bf16 v[32:35], v[200:203], v[164:167], v[32:35]
	v_mfma_f32_16x16x32_bf16 v[20:23], v[192:195], v[176:179], v[20:23]
	v_mfma_f32_16x16x32_bf16 v[16:19], v[200:203], v[176:179], v[16:19]
	v_mfma_f32_16x16x32_bf16 v[4:7], v[192:195], v[184:187], v[4:7]
	v_mfma_f32_16x16x32_bf16 v[0:3], v[200:203], v[184:187], v[0:3]
	v_mfma_f32_16x16x32_bf16 v[52:55], v[196:199], v[160:163], v[52:55]
	v_mfma_f32_16x16x32_bf16 v[48:51], v[204:207], v[160:163], v[48:51]
	v_mfma_f32_16x16x32_bf16 v[36:39], v[196:199], v[168:171], v[36:39]
	v_mfma_f32_16x16x32_bf16 v[32:35], v[204:207], v[168:171], v[32:35]
	v_mfma_f32_16x16x32_bf16 v[20:23], v[196:199], v[180:183], v[20:23]
	v_mfma_f32_16x16x32_bf16 v[16:19], v[204:207], v[180:183], v[16:19]
	v_mfma_f32_16x16x32_bf16 v[4:7], v[196:199], v[188:191], v[4:7]
	v_mfma_f32_16x16x32_bf16 v[0:3], v[204:207], v[188:191], v[0:3]
	s_waitcnt lgkmcnt(0)
	s_barrier
	s_add_u32 s38, s84, 0x200000
	s_addc_u32 s39, s85, 0
	s_mov_b32 m0, s10
	ds_read_b128 v[156:159], v175 offset:32768
	ds_read_b128 v[160:163], v175 offset:33792
	ds_read_b128 v[164:167], v175 offset:34816
	ds_read_b128 v[168:171], v175 offset:35840
	ds_read_b128 v[176:179], v175 offset:36864
	ds_read_b128 v[180:183], v175 offset:37888
	ds_read_b128 v[184:187], v175 offset:38912
	ds_read_b128 v[188:191], v175 offset:39936
	global_load_lds_dwordx4 v144, s[38:39]
	s_mov_b32 m0, s11
	s_nop 0
	global_load_lds_dwordx4 v148, s[38:39]
	s_waitcnt lgkmcnt(8)
	s_barrier
	s_waitcnt lgkmcnt(0)
	s_waitcnt lgkmcnt(0)
	v_mfma_f32_16x16x32_bf16 v[124:127], v[128:131], v[156:159], v[124:127]
	v_mfma_f32_16x16x32_bf16 v[120:123], v[136:139], v[156:159], v[120:123]
	v_mfma_f32_16x16x32_bf16 v[108:111], v[128:131], v[164:167], v[108:111]
	v_mfma_f32_16x16x32_bf16 v[104:107], v[136:139], v[164:167], v[104:107]
	v_mfma_f32_16x16x32_bf16 v[92:95], v[128:131], v[176:179], v[92:95]
	v_mfma_f32_16x16x32_bf16 v[88:91], v[136:139], v[176:179], v[88:91]
	v_mfma_f32_16x16x32_bf16 v[76:79], v[128:131], v[184:187], v[76:79]
	v_mfma_f32_16x16x32_bf16 v[72:75], v[136:139], v[184:187], v[72:75]
	v_mfma_f32_16x16x32_bf16 v[124:127], v[132:135], v[160:163], v[124:127]
	v_mfma_f32_16x16x32_bf16 v[120:123], v[140:143], v[160:163], v[120:123]
	v_mfma_f32_16x16x32_bf16 v[108:111], v[132:135], v[168:171], v[108:111]
	v_mfma_f32_16x16x32_bf16 v[104:107], v[140:143], v[168:171], v[104:107]
	v_mfma_f32_16x16x32_bf16 v[92:95], v[132:135], v[180:183], v[92:95]
	v_mfma_f32_16x16x32_bf16 v[88:91], v[140:143], v[180:183], v[88:91]
	v_mfma_f32_16x16x32_bf16 v[76:79], v[132:135], v[188:191], v[76:79]
	v_mfma_f32_16x16x32_bf16 v[72:75], v[140:143], v[188:191], v[72:75]
	s_barrier
	s_add_i32 s41, 0, 0x1c000
	s_add_i32 s38, s40, s7
	v_add_u32_e32 v204, s41, v173
	s_mov_b32 m0, s38
	ds_read_b128 v[192:195], v204
	ds_read_b128 v[196:199], v204 offset:1024
	ds_read_b128 v[200:203], v204 offset:2048
	ds_read_b128 v[204:207], v204 offset:3072
	global_load_lds_dwordx4 v146, s[98:99]
	s_add_i32 m0, s38, 0x2000
	s_nop 0
	global_load_lds_dwordx4 v150, s[98:99]
	s_barrier
	s_waitcnt lgkmcnt(0)
	s_waitcnt lgkmcnt(0)
	v_mfma_f32_16x16x32_bf16 v[116:119], v[192:195], v[156:159], v[116:119]
	v_mfma_f32_16x16x32_bf16 v[112:115], v[200:203], v[156:159], v[112:115]
	v_mfma_f32_16x16x32_bf16 v[100:103], v[192:195], v[164:167], v[100:103]
	v_mfma_f32_16x16x32_bf16 v[96:99], v[200:203], v[164:167], v[96:99]
	v_mfma_f32_16x16x32_bf16 v[84:87], v[192:195], v[176:179], v[84:87]
	v_mfma_f32_16x16x32_bf16 v[80:83], v[200:203], v[176:179], v[80:83]
	v_mfma_f32_16x16x32_bf16 v[68:71], v[192:195], v[184:187], v[68:71]
	v_mfma_f32_16x16x32_bf16 v[64:67], v[200:203], v[184:187], v[64:67]
	v_mfma_f32_16x16x32_bf16 v[116:119], v[196:199], v[160:163], v[116:119]
	v_mfma_f32_16x16x32_bf16 v[112:115], v[204:207], v[160:163], v[112:115]
	v_mfma_f32_16x16x32_bf16 v[100:103], v[196:199], v[168:171], v[100:103]
	v_mfma_f32_16x16x32_bf16 v[96:99], v[204:207], v[168:171], v[96:99]
	v_mfma_f32_16x16x32_bf16 v[84:87], v[196:199], v[180:183], v[84:87]
	v_mfma_f32_16x16x32_bf16 v[80:83], v[204:207], v[180:183], v[80:83]
	v_mfma_f32_16x16x32_bf16 v[68:71], v[196:199], v[188:191], v[68:71]
	v_mfma_f32_16x16x32_bf16 v[64:67], v[204:207], v[188:191], v[64:67]
	s_mov_b32 m0, s12
	s_barrier
; #define PG8_STAGE(bufoff, gbase, voff) do { _Pragma("unroll") for (int _i = 0; _i < 2; ++_i) \
;         __builtin_amdgcn_global_load_lds((const unsigned*)((const char*)(gbase) + (voff)[_i]), (LAS unsigned*)(lds + (bufoff) + ldsw + _i * 8192), 16, 0, 0); } while (0)
; #define PG8_LDA(dst, b, h) do { _Pragma("unroll") for (int m = 0; m < 4; ++m) _Pragma("unroll") for (int k = 0; k < 2; ++k) dst[m][k] = *(const LAS bf16x8*)(lds + PG8_SA(b, h) + aoff + m * 2048 + k * 1024); } while (0)
; #define PG8_WAIT_V(n) asm volatile("s_waitcnt vmcnt(" #n ")" ::: "memory")
; #define PG8_BAR __builtin_amdgcn_s_barrier()
; template <class Epi>
; __device__ __forceinline__ void gemm_phase(LAS unsigned char* lds, const Gemm g, const StaticOrder& S, const Epi& E, int wv) {
;     ...
;         for (int t = 0; t < nt; t += 2) {
;             const bool last = (t == nt - 2);
;             const char* a1 = cA + (ptrdiff_t)(t + 1) * kstep;
;             const char* a2 = last ? nA : cA + (ptrdiff_t)(t + 2) * kstep; const char* b2 = last ? nB : cB + (ptrdiff_t)(t + 2) * kstep;
;             const char* a3 = a2 + kstep; const char* b3 = b2 + kstep;
;             PG8_LDB(B0, 0, 0); PG8_SCHED; PG8_LDA(At, 0, 0); PG8_STAGE(PG8_SA(1, 1), a1 + hstepA, voffA);
;             PG8_WAIT_L(8); PG8_BAR; PG8_WAIT_L(0); PG8_MMA(0, 0, At, B0); PG8_BAR; PG8_SCHED;
;             PG8_LDB(B1, 0, 1); PG8_STAGE(PG8_SB(0, 0), b2, voffB);
;             PG8_BAR; PG8_WAIT_L(0); PG8_MMA(0, 1, At, B1); PG8_BAR;
;             PG8_LDA(At, 0, 1); PG8_STAGE(PG8_SA(0, 0), a2, voffA);
;             PG8_BAR; PG8_WAIT_L(0); PG8_MMA(1, 0, At, B0); PG8_BAR; PG8_SCHED;
;             PG8_STAGE(PG8_SB(0, 1), b2 + hstepB, voffB);
;             PG8_WAIT_V(6); PG8_BAR; PG8_MMA(1, 1, At, B1); PG8_BAR;
;             PG8_LDB(B0, 1, 0); PG8_SCHED; PG8_LDA(At, 1, 0); PG8_STAGE(PG8_SA(0, 1), a2 + hstepA, voffA);
;             PG8_WAIT_L(8); PG8_BAR; PG8_WAIT_L(0); PG8_MMA(0, 0, At, B0); PG8_BAR; PG8_SCHED;
;             PG8_LDB(B1, 1, 1); PG8_STAGE(PG8_SB(1, 0), b3, voffB);
;             PG8_BAR; PG8_WAIT_L(0); PG8_MMA(0, 1, At, B1); PG8_BAR;
;             PG8_LDA(At, 1, 1); PG8_STAGE(PG8_SA(1, 0), a3, voffA);
;             PG8_BAR; PG8_WAIT_L(0); PG8_MMA(1, 0, At, B0); PG8_BAR; PG8_SCHED;
;             PG8_STAGE(PG8_SB(1, 1), b3 + hstepB, voffB);
;             PG8_WAIT_V(6); PG8_BAR; PG8_MMA(1, 1, At, B1); PG8_BAR;
	ds_read_b128 v[156:159], v175 offset:49152
	ds_read_b128 v[160:163], v175 offset:50176
	ds_read_b128 v[164:167], v175 offset:51200
	ds_read_b128 v[168:171], v175 offset:52224
	ds_read_b128 v[176:179], v175 offset:53248
	ds_read_b128 v[180:183], v175 offset:54272
	ds_read_b128 v[184:187], v175 offset:55296
	ds_read_b128 v[188:191], v175 offset:56320
	global_load_lds_dwordx4 v144, s[100:101]
	s_mov_b32 m0, s13
	s_nop 0
	global_load_lds_dwordx4 v148, s[100:101]
	s_waitcnt vmcnt(10)
	s_barrier
	s_waitcnt lgkmcnt(0)
	s_waitcnt lgkmcnt(0)
	v_mfma_f32_16x16x32_bf16 v[60:63], v[128:131], v[156:159], v[60:63]
	v_mfma_f32_16x16x32_bf16 v[56:59], v[136:139], v[156:159], v[56:59]
	v_mfma_f32_16x16x32_bf16 v[44:47], v[128:131], v[164:167], v[44:47]
	v_mfma_f32_16x16x32_bf16 v[40:43], v[136:139], v[164:167], v[40:43]
	v_mfma_f32_16x16x32_bf16 v[28:31], v[128:131], v[176:179], v[28:31]
	v_mfma_f32_16x16x32_bf16 v[24:27], v[136:139], v[176:179], v[24:27]
	v_mfma_f32_16x16x32_bf16 v[12:15], v[128:131], v[184:187], v[12:15]
	v_mfma_f32_16x16x32_bf16 v[8:11], v[136:139], v[184:187], v[8:11]
	v_mfma_f32_16x16x32_bf16 v[60:63], v[132:135], v[160:163], v[60:63]
	v_mfma_f32_16x16x32_bf16 v[56:59], v[140:143], v[160:163], v[56:59]
	v_mfma_f32_16x16x32_bf16 v[44:47], v[132:135], v[168:171], v[44:47]
	v_mfma_f32_16x16x32_bf16 v[40:43], v[140:143], v[168:171], v[40:43]
	v_mfma_f32_16x16x32_bf16 v[28:31], v[132:135], v[180:183], v[28:31]
	v_mfma_f32_16x16x32_bf16 v[24:27], v[140:143], v[180:183], v[24:27]
	v_mfma_f32_16x16x32_bf16 v[12:15], v[132:135], v[188:191], v[12:15]
	v_mfma_f32_16x16x32_bf16 v[8:11], v[140:143], v[188:191], v[8:11]
	s_barrier
	s_add_u32 s38, s82, 0x1fff80
	s_addc_u32 s39, s83, 0
	s_add_i32 s40, s41, s7
	s_mov_b32 m0, s40
	s_nop 0
	global_load_lds_dwordx4 v146, s[38:39]
	s_add_i32 m0, s40, 0x2000
	s_nop 0
	global_load_lds_dwordx4 v150, s[38:39]
	v_add_u32_e32 v140, s22, v173
	ds_read_b128 v[128:131], v140
	ds_read_b128 v[132:135], v140 offset:1024
	ds_read_b128 v[136:139], v140 offset:2048
	ds_read_b128 v[140:143], v140 offset:3072
	s_waitcnt vmcnt(6)
	s_barrier
	v_mfma_f32_16x16x32_bf16 v[52:55], v[192:195], v[156:159], v[52:55]
	v_mfma_f32_16x16x32_bf16 v[48:51], v[200:203], v[156:159], v[48:51]
	v_mfma_f32_16x16x32_bf16 v[36:39], v[192:195], v[164:167], v[36:39]
	v_mfma_f32_16x16x32_bf16 v[32:35], v[200:203], v[164:167], v[32:35]
	v_mfma_f32_16x16x32_bf16 v[20:23], v[192:195], v[176:179], v[20:23]
	v_mfma_f32_16x16x32_bf16 v[16:19], v[200:203], v[176:179], v[16:19]
	v_mfma_f32_16x16x32_bf16 v[4:7], v[192:195], v[184:187], v[4:7]
	v_mfma_f32_16x16x32_bf16 v[0:3], v[200:203], v[184:187], v[0:3]
	v_mfma_f32_16x16x32_bf16 v[52:55], v[196:199], v[160:163], v[52:55]
	v_mfma_f32_16x16x32_bf16 v[48:51], v[204:207], v[160:163], v[48:51]
	v_mfma_f32_16x16x32_bf16 v[36:39], v[196:199], v[168:171], v[36:39]
	v_mfma_f32_16x16x32_bf16 v[32:35], v[204:207], v[168:171], v[32:35]
	v_mfma_f32_16x16x32_bf16 v[20:23], v[196:199], v[180:183], v[20:23]
	v_mfma_f32_16x16x32_bf16 v[16:19], v[204:207], v[180:183], v[16:19]
	v_mfma_f32_16x16x32_bf16 v[4:7], v[196:199], v[188:191], v[4:7]
	v_mfma_f32_16x16x32_bf16 v[0:3], v[204:207], v[188:191], v[0:3]
	s_waitcnt lgkmcnt(0)
	s_cmpk_gt_u32 s35, 0x7d
	s_mov_b32 s35, s80
	s_barrier
	s_cbranch_scc1 .LBB0_610

; __device__ __forceinline__ int opaque_tid(int wv) { int l; asm volatile("v_mbcnt_lo_u32_b32 %0, -1, 0\n\tv_mbcnt_hi_u32_b32 %0, -1, %0" : "=v"(l)); return wv * 64 + l; }
; #define PG8_BAR __builtin_amdgcn_s_barrier()
; template <class Epi>
; __device__ __forceinline__ void gemm_phase(LAS unsigned char* lds, const Gemm g, const StaticOrder& S, const Epi& E, int wv) {
;     const int tid = opaque_tid(wv), wid = __builtin_amdgcn_readfirstlane(tid >> 6), lane = tid & 63, wr = wid >> 2, wc = wid & 3, fr = lane & 15, fq = lane >> 4;
;     const int K = g.K, nt = K / BK;
;     unsigned voffA[2], voffB[2];
; #pragma unroll
;     for (int i = 0; i < 2; ++i) { int R, C; stage_rc(tid * 16 + i * 8192, R, C); const int Rb = Epi::PERM ? ((R & ~31) + perm32(R & 31)) : R;
;         voffA[i] = (unsigned)(R * g.lda + C) * 2u; voffB[i] = (unsigned)(Rb * g.ldb + C) * 2u; }
;     const bool krev = (g.adiag & 2) != 0;
;     const ptrdiff_t kstep = krev ? -(ptrdiff_t)(BK * 2) : (ptrdiff_t)(BK * 2);
;     const size_t kbeg = krev ? (size_t)(nt - 1) * (BK * 2) : 0;
;     const size_t hstepA = (size_t)HALF * g.lda * 2, hstepB = (size_t)HALF * g.ldb * 2;
;     const size_t tstepA = 2 * hstepA, tstepB = 2 * hstepB;
;     const unsigned ldsw = (unsigned)wid * 1024u;
;     const int aoff = lds_byte(wr * 64 + fr, fq * 8), boff = lds_byte(wc * 32 + fr, fq * 8);
;     ...
;     Unit cur, nxt; int ui = 0;
;     if (!S.next(0, cur)) return;
;     f32x4 acc[2][2][4][2];
; #pragma unroll
;     for (int a = 0; a < 2; ++a)
; #pragma unroll
;         for (int b = 0; b < 2; ++b)
; #pragma unroll
;             for (int m = 0; m < 4; ++m)
; #pragma unroll
;                 for (int n = 0; n < 2; ++n) acc[a][b][m][n] = (f32x4){0.f, 0.f, 0.f, 0.f};
;     bf16x8 At[4][2], B0[2][2], B1[2][2];
;     const char* cA = (const char*)g.A + (size_t)cur.pm * tstepA + ((g.adiag & 1) ? (size_t)(cur.pn >> 1) * K * 2 : 0) + kbeg;
;     const char* cB = (const char*)g.Bt + (size_t)cur.pn * tstepB + kbeg;
;     PG8_STAGE(PG8_SB(0, 0), cB, voffB); PG8_STAGE(PG8_SA(0, 0), cA, voffA); PG8_STAGE(PG8_SB(0, 1), cB + hstepB, voffB); PG8_STAGE(PG8_SA(0, 1), cA + hstepA, voffA);
;     if (wr == 1) PG8_BAR;
;     PG8_WAIT_V(4); PG8_BAR;
;     PG8_STAGE(PG8_SB(1, 0), cB + kstep, voffB); PG8_STAGE(PG8_SA(1, 0), cA + kstep, voffA); PG8_STAGE(PG8_SB(1, 1), cB + hstepB + kstep, voffB);
;     PG8_WAIT_V(6); PG8_BAR;
.LBB0_634:
	v_ashrrev_i32_e32 v2, 31, v0
	v_lshrrev_b32_e32 v2, 26, v2
	v_lshlrev_b32_e32 v1, 4, v0
	v_add_u32_e32 v2, v0, v2
	v_bfe_i32 v0, v0, 27, 1
	v_lshrrev_b32_e32 v0, 22, v0
	v_add_u32_e32 v0, v1, v0
	v_and_b32_e32 v0, 0xfffffc00, v0
	v_sub_u32_e32 v0, v1, v0
	v_lshrrev_b32_e32 v3, 4, v0
	v_bitop3_b32 v0, v3, v0, 32 bitop3:0x6c
	v_ashrrev_i32_e32 v4, 31, v0
	v_lshrrev_b32_e32 v4, 26, v4
	v_add_u32_e32 v4, v0, v4
	s_ashr_i32 s11, s5, 3
	v_ashrrev_i32_e32 v5, 6, v4
	v_and_b32_e32 v4, 0xc0, v4
	s_waitcnt lgkmcnt(0)
	s_add_u32 s5, s50, 0x100000
	v_ashrrev_i32_e32 v2, 6, v2
	v_sub_u32_e32 v0, v0, v4
	v_mov_b32_e32 v4, 1
	s_addc_u32 s6, s51, 0
	v_lshlrev_b32_e32 v3, 3, v2
	v_lshlrev_b32_e32 v2, 5, v2
	v_ashrrev_i16_sdwa v0, v4, sext(v0) dst_sel:DWORD dst_unused:UNUSED_PAD src0_sel:DWORD src1_sel:BYTE_0
	s_add_u32 s7, s18, 0x7100000
	v_and_b32_e32 v3, -16, v3
	v_and_b32_e32 v2, 32, v2
	v_bfe_i32 v0, v0, 0, 16
	s_addc_u32 s8, s19, 0
	v_add_u32_e32 v3, v5, v3
	v_and_b32_e32 v5, 3, v5
	s_mov_b32 s9, 0x7fffe0
	v_add_lshl_u32 v2, v2, v0, 1
	v_add_u32_e32 v1, 0x2000, v1
	s_add_i32 s10, s10, s11
	v_lshlrev_b32_e32 v6, 1, v3
	v_lshrrev_b32_e32 v7, 2, v3
	v_and_or_b32 v5, v3, s9, v5
	v_lshl_add_u32 v0, v3, 9, v2
	v_ashrrev_i32_e32 v3, 31, v1
	s_ashr_i32 s11, s10, 31
	v_lshrrev_b32_e32 v3, 22, v3
	s_lshr_b32 s11, s11, 27
	v_and_b32_e32 v6, 24, v6
	v_and_b32_e32 v7, 4, v7
	v_add_u32_e32 v3, v1, v3
	s_add_i32 s11, s10, s11
	v_or3_b32 v5, v5, v7, v6
	v_ashrrev_i32_e32 v3, 10, v3
	s_ashr_i32 s12, s11, 5
	s_andn2_b32 s11, s11, 31
	v_lshl_add_u32 v2, v5, 9, v2
	v_mul_i32_i24_e32 v5, 0x400, v3
	s_sub_i32 s10, s10, s11
	v_sub_u32_e32 v1, v1, v5
	s_bfe_i32 s11, s10, 0x80000
	v_lshrrev_b32_e32 v5, 4, v1
	s_bfe_u32 s11, s11, 0x2000d
	v_bitop3_b32 v1, v5, v1, 32 bitop3:0x6c
	s_add_i32 s11, s10, s11
	v_ashrrev_i32_e32 v6, 31, v1
	s_bfe_i32 s13, s11, 0x80000
	s_and_b32 s11, s11, 0xfc
	v_lshrrev_b32_e32 v6, 26, v6
	s_sub_i32 s10, s10, s11
	v_lshlrev_b32_e32 v5, 3, v3
	v_add_u32_e32 v6, v1, v6
	s_lshl_b32 s12, s12, 2
	s_sext_i32_i16 s13, s13
	s_sext_i32_i8 s10, s10
	v_and_b32_e32 v5, -16, v5
	v_ashrrev_i32_e32 v7, 6, v6
	s_lshr_b32 s52, s13, 2
	s_add_i32 s58, s12, s10
	v_add_u32_e32 v5, v7, v5
	v_and_b32_e32 v7, 3, v7
	s_ashr_i32 s14, s4, 6
	s_ashr_i32 s59, s58, 31
	s_bfe_i64 s[10:11], s[52:53], 0x100000
	s_ashr_i32 s22, s4, 8
	v_and_b32_e32 v6, 0xc0, v6
	v_and_or_b32 v7, v5, s9, v7
	s_lshl_b32 s9, s14, 10
	s_lshl_b64 s[12:13], s[58:59], 17
	s_lshl_b64 s[10:11], s[10:11], 17
	v_sub_u32_e32 v1, v1, v6
	s_add_u32 s70, s7, s10
	v_lshlrev_b32_e32 v3, 5, v3
	v_ashrrev_i16_sdwa v1, v4, sext(v1) dst_sel:DWORD dst_unused:UNUSED_PAD src0_sel:DWORD src1_sel:BYTE_0
	v_lshlrev_b32_e32 v4, 1, v5
	v_lshrrev_b32_e32 v6, 2, v5
	s_addc_u32 s71, s8, s11
	s_add_i32 s10, s9, 0
	v_and_b32_e32 v3, 32, v3
	v_bfe_i32 v1, v1, 0, 16
	v_and_b32_e32 v4, 24, v4
	v_and_b32_e32 v6, 4, v6
	s_add_i32 m0, s10, 0x10000
	v_or3_b32 v6, v7, v6, v4
	v_add_lshl_u32 v1, v3, v1, 1
	global_load_lds_dwordx4 v2, s[70:71]
	s_add_i32 m0, s10, 0x12000
	v_lshl_add_u32 v6, v6, 9, v1
	s_add_u32 s68, s5, s12
	global_load_lds_dwordx4 v6, s[70:71]
	s_addc_u32 s69, s6, s13
	s_mov_b32 m0, s10
	s_add_i32 s11, s10, 0x2000
	v_lshl_add_u32 v4, v5, 9, v1
	global_load_lds_dwordx4 v0, s[68:69]
	s_mov_b32 m0, s11
	s_add_u32 s12, s70, 0x10000
	global_load_lds_dwordx4 v4, s[68:69]
	s_addc_u32 s13, s71, 0
	s_add_i32 m0, s10, 0x14000
	v_mov_b32_e32 v3, 0
	global_load_lds_dwordx4 v2, s[12:13]
	s_add_i32 m0, s10, 0x16000
	s_add_u32 s18, s68, 0x10000
	global_load_lds_dwordx4 v6, s[12:13]
	s_addc_u32 s19, s69, 0
	s_add_i32 s12, s10, 0x4000
	s_mov_b32 m0, s12
	s_add_i32 s13, s10, 0x6000
	global_load_lds_dwordx4 v0, s[18:19]
	s_mov_b32 m0, s13
	v_mov_b32_e32 v7, v3
	global_load_lds_dwordx4 v4, s[18:19]
	v_mov_b32_e32 v1, v3
	v_mov_b32_e32 v5, v3
	v_lshl_add_u64 v[14:15], s[70:71], 0, v[2:3]
	v_lshl_add_u64 v[12:13], s[70:71], 0, v[6:7]
	v_lshl_add_u64 v[10:11], s[68:69], 0, v[0:1]
	s_cmp_lg_u32 s22, 1
	v_lshl_add_u64 v[8:9], s[68:69], 0, v[4:5]
	s_cbranch_scc1 .LBB0_636
	s_barrier
	s_setprio 1

; #define PG8_STAGE(bufoff, gbase, voff) do { _Pragma("unroll") for (int _i = 0; _i < 2; ++_i) \
;         __builtin_amdgcn_global_load_lds((const unsigned*)((const char*)(gbase) + (voff)[_i]), (LAS unsigned*)(lds + (bufoff) + ldsw + _i * 8192), 16, 0, 0); } while (0)
; #define PG8_BAR __builtin_amdgcn_s_barrier()
; template <class Epi>
; __device__ __forceinline__ void gemm_phase(LAS unsigned char* lds, const Gemm g, const StaticOrder& S, const Epi& E, int wv) {
;     ...
;         const bool has_next = S.next(ui + 1, nxt);
;         const char* nA = has_next ? (const char*)g.A + (size_t)nxt.pm * tstepA + ((g.adiag & 1) ? (size_t)(nxt.pn >> 1) * K * 2 : 0) + kbeg : cA;
;         const char* nB = has_next ? (const char*)g.Bt + (size_t)nxt.pn * tstepB + kbeg : cB;
;         for (int t = 0; t < nt; t += 2) {
;             const bool last = (t == nt - 2);
;             const char* a1 = cA + (ptrdiff_t)(t + 1) * kstep;
;             const char* a2 = last ? nA : cA + (ptrdiff_t)(t + 2) * kstep; const char* b2 = last ? nB : cB + (ptrdiff_t)(t + 2) * kstep;
;             const char* a3 = a2 + kstep; const char* b3 = b2 + kstep;
;             PG8_LDB(B0, 0, 0); PG8_SCHED; PG8_LDA(At, 0, 0); PG8_STAGE(PG8_SA(1, 1), a1 + hstepA, voffA);
;             PG8_WAIT_L(8); PG8_BAR; PG8_WAIT_L(0); PG8_MMA(0, 0, At, B0); PG8_BAR; PG8_SCHED;
;             PG8_LDB(B1, 0, 1); PG8_STAGE(PG8_SB(0, 0), b2, voffB);
;             PG8_BAR; PG8_WAIT_L(0); PG8_MMA(0, 1, At, B1); PG8_BAR;
;             PG8_LDA(At, 0, 1); PG8_STAGE(PG8_SA(0, 0), a2, voffA);
;             PG8_BAR; PG8_WAIT_L(0); PG8_MMA(1, 0, At, B0); PG8_BAR; PG8_SCHED;
;             PG8_STAGE(PG8_SB(0, 1), b2 + hstepB, voffB);
;             PG8_WAIT_V(6); PG8_BAR; PG8_MMA(1, 1, At, B1); PG8_BAR;
;             PG8_LDB(B0, 1, 0); PG8_SCHED; PG8_LDA(At, 1, 0); PG8_STAGE(PG8_SA(0, 1), a2 + hstepA, voffA);
;             PG8_WAIT_L(8); PG8_BAR; PG8_WAIT_L(0); PG8_MMA(0, 0, At, B0); PG8_BAR; PG8_SCHED;
;             PG8_LDB(B1, 1, 1); PG8_STAGE(PG8_SB(1, 0), b3, voffB);
;             PG8_BAR; PG8_WAIT_L(0); PG8_MMA(0, 1, At, B1); PG8_BAR;
;             PG8_LDA(At, 1, 1); PG8_STAGE(PG8_SA(1, 0), a3, voffA);
;             PG8_BAR; PG8_WAIT_L(0); PG8_MMA(1, 0, At, B0); PG8_BAR; PG8_SCHED;
;             PG8_STAGE(PG8_SB(1, 1), b3 + hstepB, voffB);
;             PG8_WAIT_V(6); PG8_BAR; PG8_MMA(1, 1, At, B1); PG8_BAR;
.LBB0_638:
	s_ashr_i32 s63, s62, 31
	s_lshl_b64 s[38:39], s[62:63], 17
	s_add_u32 s64, s5, s38
	v_cmp_lt_i64_e32 vcc, s[56:57], v[8:9]
	s_addc_u32 s65, s6, s39
	ds_read_b128 v[18:21], v15
	ds_read_b128 v[22:25], v15 offset:1024
	ds_read_b128 v[26:29], v15 offset:2048
	ds_read_b128 v[30:33], v15 offset:3072
	s_and_b64 s[38:39], vcc, exec
	s_cselect_b32 s75, s65, s69
	s_cselect_b32 s74, s64, s68
	s_ashr_i32 s61, s60, 31
	s_lshl_b64 s[38:39], s[60:61], 17
	s_add_u32 s66, s7, s38
	s_addc_u32 s67, s8, s39
	s_and_b64 s[38:39], vcc, exec
	s_cselect_b32 s73, s67, s71
	s_cselect_b32 s72, s66, s70
	s_add_u32 s38, s68, 0x10080
	s_addc_u32 s39, s69, 0
	s_mov_b32 m0, s23
	v_lshl_add_u64 v[66:67], s[38:39], 0, v[0:1]
	ds_read_b128 v[34:37], v16
	ds_read_b128 v[38:41], v16 offset:1024
	ds_read_b128 v[42:45], v16 offset:2048
	ds_read_b128 v[46:49], v16 offset:3072
	ds_read_b128 v[50:53], v16 offset:4096
	ds_read_b128 v[54:57], v16 offset:5120
	ds_read_b128 v[58:61], v16 offset:6144
	ds_read_b128 v[62:65], v16 offset:7168
	global_load_lds_dwordx4 v[66:67], off
	v_lshl_add_u64 v[66:67], s[38:39], 0, v[4:5]
	s_mov_b32 m0, s24
	s_nop 0
	global_load_lds_dwordx4 v[66:67], off
	s_waitcnt lgkmcnt(8)
	s_barrier
	s_waitcnt lgkmcnt(0)
	s_waitcnt lgkmcnt(0)
	v_mfma_f32_16x16x32_bf16 v[66:69], v[18:21], v[34:37], 0
	v_mfma_f32_16x16x32_bf16 v[70:73], v[26:29], v[34:37], 0
	v_mfma_f32_16x16x32_bf16 v[74:77], v[18:21], v[42:45], 0
	v_mfma_f32_16x16x32_bf16 v[78:81], v[26:29], v[42:45], 0
	v_mfma_f32_16x16x32_bf16 v[82:85], v[18:21], v[50:53], 0
	v_mfma_f32_16x16x32_bf16 v[86:89], v[26:29], v[50:53], 0
	v_mfma_f32_16x16x32_bf16 v[90:93], v[18:21], v[58:61], 0
	v_mfma_f32_16x16x32_bf16 v[94:97], v[26:29], v[58:61], 0
	v_mfma_f32_16x16x32_bf16 v[66:69], v[22:25], v[38:41], v[66:69]
	v_mfma_f32_16x16x32_bf16 v[70:73], v[30:33], v[38:41], v[70:73]
	v_mfma_f32_16x16x32_bf16 v[74:77], v[22:25], v[46:49], v[74:77]
	v_mfma_f32_16x16x32_bf16 v[78:81], v[30:33], v[46:49], v[78:81]
	v_mfma_f32_16x16x32_bf16 v[82:85], v[22:25], v[54:57], v[82:85]
	v_mfma_f32_16x16x32_bf16 v[86:89], v[30:33], v[54:57], v[86:89]
	v_mfma_f32_16x16x32_bf16 v[90:93], v[22:25], v[62:65], v[90:93]
	v_mfma_f32_16x16x32_bf16 v[94:97], v[30:33], v[62:65], v[94:97]
	s_barrier
	v_lshl_add_u64 v[210:211], s[70:71], 0, v[2:3]
	s_add_i32 s39, s22, s9
	v_lshl_add_u64 v[114:115], v[210:211], 0, s[52:53]
	s_mov_b32 m0, s39
	v_lshl_add_u64 v[212:213], s[70:71], 0, v[6:7]
	s_add_i32 s35, s39, 0x2000
	ds_read_b128 v[98:101], v17
	ds_read_b128 v[102:105], v17 offset:1024
	ds_read_b128 v[106:109], v17 offset:2048
	ds_read_b128 v[110:113], v17 offset:3072
	global_load_lds_dwordx4 v[114:115], off
	v_lshl_add_u64 v[114:115], v[212:213], 0, s[52:53]
	s_mov_b32 m0, s35
	s_nop 0
	global_load_lds_dwordx4 v[114:115], off
	s_barrier
	s_waitcnt lgkmcnt(0)
	s_waitcnt lgkmcnt(0)
	v_mfma_f32_16x16x32_bf16 v[114:117], v[98:101], v[34:37], 0
	v_mfma_f32_16x16x32_bf16 v[34:37], v[106:109], v[34:37], 0
	v_mfma_f32_16x16x32_bf16 v[114:117], v[102:105], v[38:41], v[114:117]
	v_mfma_f32_16x16x32_bf16 v[34:37], v[110:113], v[38:41], v[34:37]
	v_mfma_f32_16x16x32_bf16 v[38:41], v[98:101], v[42:45], 0
	v_mfma_f32_16x16x32_bf16 v[42:45], v[106:109], v[42:45], 0
	v_mfma_f32_16x16x32_bf16 v[38:41], v[102:105], v[46:49], v[38:41]
	v_mfma_f32_16x16x32_bf16 v[42:45], v[110:113], v[46:49], v[42:45]
	v_mfma_f32_16x16x32_bf16 v[46:49], v[98:101], v[50:53], 0
	v_mfma_f32_16x16x32_bf16 v[50:53], v[106:109], v[50:53], 0
	v_mfma_f32_16x16x32_bf16 v[46:49], v[102:105], v[54:57], v[46:49]
	v_mfma_f32_16x16x32_bf16 v[50:53], v[110:113], v[54:57], v[50:53]
	v_mfma_f32_16x16x32_bf16 v[54:57], v[98:101], v[58:61], 0
	v_mfma_f32_16x16x32_bf16 v[58:61], v[106:109], v[58:61], 0
	v_mfma_f32_16x16x32_bf16 v[54:57], v[102:105], v[62:65], v[54:57]
	v_mfma_f32_16x16x32_bf16 v[58:61], v[110:113], v[62:65], v[58:61]
	v_lshl_add_u64 v[214:215], s[68:69], 0, v[0:1]
	s_mov_b32 m0, s10
	v_lshl_add_u64 v[146:147], v[214:215], 0, s[52:53]
	v_lshl_add_u64 v[216:217], s[68:69], 0, v[4:5]
	s_barrier
	ds_read_b128 v[62:65], v16 offset:16384
	ds_read_b128 v[118:121], v16 offset:17408
	ds_read_b128 v[122:125], v16 offset:18432
	ds_read_b128 v[126:129], v16 offset:19456
	ds_read_b128 v[130:133], v16 offset:20480
	ds_read_b128 v[134:137], v16 offset:21504
	ds_read_b128 v[138:141], v16 offset:22528
	ds_read_b128 v[142:145], v16 offset:23552
	global_load_lds_dwordx4 v[146:147], off
	v_lshl_add_u64 v[146:147], v[216:217], 0, s[52:53]
	s_mov_b32 m0, s11
	s_nop 0
	global_load_lds_dwordx4 v[146:147], off
	s_barrier
	s_waitcnt lgkmcnt(0)
	s_waitcnt lgkmcnt(0)
	v_mfma_f32_16x16x32_bf16 v[146:149], v[18:21], v[62:65], 0
	v_mfma_f32_16x16x32_bf16 v[154:157], v[18:21], v[122:125], 0
	v_mfma_f32_16x16x32_bf16 v[162:165], v[18:21], v[130:133], 0
	v_mfma_f32_16x16x32_bf16 v[18:21], v[18:21], v[138:141], 0
	v_mfma_f32_16x16x32_bf16 v[146:149], v[22:25], v[118:121], v[146:149]
	v_mfma_f32_16x16x32_bf16 v[150:153], v[26:29], v[62:65], 0
	v_mfma_f32_16x16x32_bf16 v[154:157], v[22:25], v[126:129], v[154:157]
	v_mfma_f32_16x16x32_bf16 v[158:161], v[26:29], v[122:125], 0
	v_mfma_f32_16x16x32_bf16 v[162:165], v[22:25], v[134:137], v[162:165]
	v_mfma_f32_16x16x32_bf16 v[166:169], v[26:29], v[130:133], 0
	v_mfma_f32_16x16x32_bf16 v[18:21], v[22:25], v[142:145], v[18:21]
	v_mfma_f32_16x16x32_bf16 v[22:25], v[26:29], v[138:141], 0
	v_mfma_f32_16x16x32_bf16 v[150:153], v[30:33], v[118:121], v[150:153]
	v_mfma_f32_16x16x32_bf16 v[158:161], v[30:33], v[126:129], v[158:161]
	v_mfma_f32_16x16x32_bf16 v[166:169], v[30:33], v[134:137], v[166:169]
	v_mfma_f32_16x16x32_bf16 v[22:25], v[30:33], v[142:145], v[22:25]
	s_barrier
; #define PG8_STAGE(bufoff, gbase, voff) do { _Pragma("unroll") for (int _i = 0; _i < 2; ++_i) \
;         __builtin_amdgcn_global_load_lds((const unsigned*)((const char*)(gbase) + (voff)[_i]), (LAS unsigned*)(lds + (bufoff) + ldsw + _i * 8192), 16, 0, 0); } while (0)
; #define PG8_LDA(dst, b, h) do { _Pragma("unroll") for (int m = 0; m < 4; ++m) _Pragma("unroll") for (int k = 0; k < 2; ++k) dst[m][k] = *(const LAS bf16x8*)(lds + PG8_SA(b, h) + aoff + m * 2048 + k * 1024); } while (0)
; #define PG8_WAIT_V(n) asm volatile("s_waitcnt vmcnt(" #n ")" ::: "memory")
; #define PG8_BAR __builtin_amdgcn_s_barrier()
; template <class Epi>
; __device__ __forceinline__ void gemm_phase(LAS unsigned char* lds, const Gemm g, const StaticOrder& S, const Epi& E, int wv) {
;     ...
;         for (int t = 0; t < nt; t += 2) {
;             const bool last = (t == nt - 2);
;             const char* a1 = cA + (ptrdiff_t)(t + 1) * kstep;
;             const char* a2 = last ? nA : cA + (ptrdiff_t)(t + 2) * kstep; const char* b2 = last ? nB : cB + (ptrdiff_t)(t + 2) * kstep;
;             const char* a3 = a2 + kstep; const char* b3 = b2 + kstep;
;             PG8_LDB(B0, 0, 0); PG8_SCHED; PG8_LDA(At, 0, 0); PG8_STAGE(PG8_SA(1, 1), a1 + hstepA, voffA);
;             PG8_WAIT_L(8); PG8_BAR; PG8_WAIT_L(0); PG8_MMA(0, 0, At, B0); PG8_BAR; PG8_SCHED;
;             PG8_LDB(B1, 0, 1); PG8_STAGE(PG8_SB(0, 0), b2, voffB);
;             PG8_BAR; PG8_WAIT_L(0); PG8_MMA(0, 1, At, B1); PG8_BAR;
;             PG8_LDA(At, 0, 1); PG8_STAGE(PG8_SA(0, 0), a2, voffA);
;             PG8_BAR; PG8_WAIT_L(0); PG8_MMA(1, 0, At, B0); PG8_BAR; PG8_SCHED;
;             PG8_STAGE(PG8_SB(0, 1), b2 + hstepB, voffB);
;             PG8_WAIT_V(6); PG8_BAR; PG8_MMA(1, 1, At, B1); PG8_BAR;
;             PG8_LDB(B0, 1, 0); PG8_SCHED; PG8_LDA(At, 1, 0); PG8_STAGE(PG8_SA(0, 1), a2 + hstepA, voffA);
;             PG8_WAIT_L(8); PG8_BAR; PG8_WAIT_L(0); PG8_MMA(0, 0, At, B0); PG8_BAR; PG8_SCHED;
;             PG8_LDB(B1, 1, 1); PG8_STAGE(PG8_SB(1, 0), b3, voffB);
;             PG8_BAR; PG8_WAIT_L(0); PG8_MMA(0, 1, At, B1); PG8_BAR;
;             PG8_LDA(At, 1, 1); PG8_STAGE(PG8_SA(1, 0), a3, voffA);
;             PG8_BAR; PG8_WAIT_L(0); PG8_MMA(1, 0, At, B0); PG8_BAR; PG8_SCHED;
;             PG8_STAGE(PG8_SB(1, 1), b3 + hstepB, voffB);
;             PG8_WAIT_V(6); PG8_BAR; PG8_MMA(1, 1, At, B1); PG8_BAR;
	s_add_u32 s42, s70, 0x10100
	s_addc_u32 s43, s71, 0
	s_add_i32 s40, s25, s9
	v_lshl_add_u64 v[26:27], s[42:43], 0, v[2:3]
	s_mov_b32 m0, s40
	s_add_i32 s38, s40, 0x2000
	global_load_lds_dwordx4 v[26:27], off
	v_lshl_add_u64 v[26:27], s[42:43], 0, v[6:7]
	s_mov_b32 m0, s38
	s_nop 0
	global_load_lds_dwordx4 v[26:27], off
	s_waitcnt vmcnt(6)
	s_barrier
	v_mfma_f32_16x16x32_bf16 v[26:29], v[98:101], v[62:65], 0
	v_mfma_f32_16x16x32_bf16 v[30:33], v[106:109], v[62:65], 0
	v_mfma_f32_16x16x32_bf16 v[26:29], v[102:105], v[118:121], v[26:29]
	v_mfma_f32_16x16x32_bf16 v[30:33], v[110:113], v[118:121], v[30:33]
	v_mfma_f32_16x16x32_bf16 v[62:65], v[98:101], v[122:125], 0
	v_mfma_f32_16x16x32_bf16 v[118:121], v[106:109], v[122:125], 0
	v_mfma_f32_16x16x32_bf16 v[122:125], v[98:101], v[130:133], 0
	v_mfma_f32_16x16x32_bf16 v[98:101], v[98:101], v[138:141], 0
	v_mfma_f32_16x16x32_bf16 v[62:65], v[102:105], v[126:129], v[62:65]
	v_mfma_f32_16x16x32_bf16 v[118:121], v[110:113], v[126:129], v[118:121]
	v_mfma_f32_16x16x32_bf16 v[122:125], v[102:105], v[134:137], v[122:125]
	v_mfma_f32_16x16x32_bf16 v[126:129], v[106:109], v[130:133], 0
	v_mfma_f32_16x16x32_bf16 v[98:101], v[102:105], v[142:145], v[98:101]
	v_mfma_f32_16x16x32_bf16 v[102:105], v[106:109], v[138:141], 0
	v_mfma_f32_16x16x32_bf16 v[126:129], v[110:113], v[134:137], v[126:129]
	v_mfma_f32_16x16x32_bf16 v[102:105], v[110:113], v[142:145], v[102:105]
	s_add_i32 s41, 0, 0x18000
	v_add_u32_e32 v218, s41, v13
	s_barrier
	ds_read_b128 v[106:109], v218
	ds_read_b128 v[110:113], v218 offset:1024
	ds_read_b128 v[130:133], v218 offset:2048
	ds_read_b128 v[134:137], v218 offset:3072
	s_add_u32 s42, s68, 0x10100
	s_addc_u32 s43, s69, 0
	s_mov_b32 m0, s12
	v_lshl_add_u64 v[194:195], s[42:43], 0, v[0:1]
	ds_read_b128 v[138:141], v16 offset:32768
	ds_read_b128 v[142:145], v16 offset:33792
	ds_read_b128 v[170:173], v16 offset:34816
	ds_read_b128 v[174:177], v16 offset:35840
	ds_read_b128 v[178:181], v16 offset:36864
	ds_read_b128 v[182:185], v16 offset:37888
	ds_read_b128 v[186:189], v16 offset:38912
	ds_read_b128 v[190:193], v16 offset:39936
	global_load_lds_dwordx4 v[194:195], off
	v_lshl_add_u64 v[194:195], s[42:43], 0, v[4:5]
	s_mov_b32 m0, s13
	s_nop 0
	global_load_lds_dwordx4 v[194:195], off
	s_waitcnt lgkmcnt(8)
	s_barrier
	s_waitcnt lgkmcnt(0)
	s_waitcnt lgkmcnt(0)
	v_mfma_f32_16x16x32_bf16 v[66:69], v[106:109], v[138:141], v[66:69]
	v_mfma_f32_16x16x32_bf16 v[70:73], v[130:133], v[138:141], v[70:73]
	v_mfma_f32_16x16x32_bf16 v[74:77], v[106:109], v[170:173], v[74:77]
	v_mfma_f32_16x16x32_bf16 v[78:81], v[130:133], v[170:173], v[78:81]
	v_mfma_f32_16x16x32_bf16 v[82:85], v[106:109], v[178:181], v[82:85]
	v_mfma_f32_16x16x32_bf16 v[86:89], v[130:133], v[178:181], v[86:89]
	v_mfma_f32_16x16x32_bf16 v[90:93], v[106:109], v[186:189], v[90:93]
	v_mfma_f32_16x16x32_bf16 v[94:97], v[130:133], v[186:189], v[94:97]
	v_mfma_f32_16x16x32_bf16 v[66:69], v[110:113], v[142:145], v[66:69]
	v_mfma_f32_16x16x32_bf16 v[70:73], v[134:137], v[142:145], v[70:73]
	v_mfma_f32_16x16x32_bf16 v[74:77], v[110:113], v[174:177], v[74:77]
	v_mfma_f32_16x16x32_bf16 v[78:81], v[134:137], v[174:177], v[78:81]
	v_mfma_f32_16x16x32_bf16 v[82:85], v[110:113], v[182:185], v[82:85]
	v_mfma_f32_16x16x32_bf16 v[86:89], v[134:137], v[182:185], v[86:89]
	v_mfma_f32_16x16x32_bf16 v[90:93], v[110:113], v[190:193], v[90:93]
	v_mfma_f32_16x16x32_bf16 v[94:97], v[134:137], v[190:193], v[94:97]
	s_barrier
	s_add_i32 s44, 0, 0x1c000
	s_add_i32 s43, s41, s9
	v_add_u32_e32 v219, s44, v13
	v_lshl_add_u64 v[210:211], v[210:211], 0, s[54:55]
	s_mov_b32 m0, s43
	s_add_i32 s41, s43, 0x2000
	ds_read_b128 v[194:197], v219
	ds_read_b128 v[198:201], v219 offset:1024
	ds_read_b128 v[202:205], v219 offset:2048
	ds_read_b128 v[206:209], v219 offset:3072
	global_load_lds_dwordx4 v[210:211], off
	v_lshl_add_u64 v[210:211], v[212:213], 0, s[54:55]
	s_mov_b32 m0, s41
	s_nop 0
	global_load_lds_dwordx4 v[210:211], off
	s_barrier
	s_waitcnt lgkmcnt(0)
	s_waitcnt lgkmcnt(0)
	v_mfma_f32_16x16x32_bf16 v[114:117], v[194:197], v[138:141], v[114:117]
	v_mfma_f32_16x16x32_bf16 v[34:37], v[202:205], v[138:141], v[34:37]
	v_mfma_f32_16x16x32_bf16 v[38:41], v[194:197], v[170:173], v[38:41]
	v_mfma_f32_16x16x32_bf16 v[42:45], v[202:205], v[170:173], v[42:45]
	v_mfma_f32_16x16x32_bf16 v[46:49], v[194:197], v[178:181], v[46:49]
	v_mfma_f32_16x16x32_bf16 v[50:53], v[202:205], v[178:181], v[50:53]
	v_mfma_f32_16x16x32_bf16 v[54:57], v[194:197], v[186:189], v[54:57]
	v_mfma_f32_16x16x32_bf16 v[58:61], v[202:205], v[186:189], v[58:61]
	v_mfma_f32_16x16x32_bf16 v[114:117], v[198:201], v[142:145], v[114:117]
	v_mfma_f32_16x16x32_bf16 v[34:37], v[206:209], v[142:145], v[34:37]
	v_mfma_f32_16x16x32_bf16 v[38:41], v[198:201], v[174:177], v[38:41]
	v_mfma_f32_16x16x32_bf16 v[42:45], v[206:209], v[174:177], v[42:45]
	v_mfma_f32_16x16x32_bf16 v[46:49], v[198:201], v[182:185], v[46:49]
	v_mfma_f32_16x16x32_bf16 v[50:53], v[206:209], v[182:185], v[50:53]
	v_mfma_f32_16x16x32_bf16 v[54:57], v[198:201], v[190:193], v[54:57]
	v_mfma_f32_16x16x32_bf16 v[58:61], v[206:209], v[190:193], v[58:61]
	s_mov_b32 m0, s14
	v_lshl_add_u64 v[210:211], v[214:215], 0, s[54:55]
	s_barrier
	ds_read_b128 v[138:141], v16 offset:49152
	ds_read_b128 v[142:145], v16 offset:50176
	ds_read_b128 v[170:173], v16 offset:51200
	ds_read_b128 v[174:177], v16 offset:52224
	ds_read_b128 v[178:181], v16 offset:53248
	ds_read_b128 v[182:185], v16 offset:54272
	ds_read_b128 v[186:189], v16 offset:55296
	ds_read_b128 v[190:193], v16 offset:56320
	global_load_lds_dwordx4 v[210:211], off
	v_lshl_add_u64 v[210:211], v[216:217], 0, s[54:55]
	s_mov_b32 m0, s15
	s_nop 0
	global_load_lds_dwordx4 v[210:211], off
	s_barrier
; #define PG8_STAGE(bufoff, gbase, voff) do { _Pragma("unroll") for (int _i = 0; _i < 2; ++_i) \
;         __builtin_amdgcn_global_load_lds((const unsigned*)((const char*)(gbase) + (voff)[_i]), (LAS unsigned*)(lds + (bufoff) + ldsw + _i * 8192), 16, 0, 0); } while (0)
; #define PG8_LDA(dst, b, h) do { _Pragma("unroll") for (int m = 0; m < 4; ++m) _Pragma("unroll") for (int k = 0; k < 2; ++k) dst[m][k] = *(const LAS bf16x8*)(lds + PG8_SA(b, h) + aoff + m * 2048 + k * 1024); } while (0)
; #define PG8_WAIT_V(n) asm volatile("s_waitcnt vmcnt(" #n ")" ::: "memory")
; #define PG8_BAR __builtin_amdgcn_s_barrier()
; template <class Epi>
; __device__ __forceinline__ void gemm_phase(LAS unsigned char* lds, const Gemm g, const StaticOrder& S, const Epi& E, int wv) {
;     ...
;         for (int t = 0; t < nt; t += 2) {
;             const bool last = (t == nt - 2);
;             const char* a1 = cA + (ptrdiff_t)(t + 1) * kstep;
;             const char* a2 = last ? nA : cA + (ptrdiff_t)(t + 2) * kstep; const char* b2 = last ? nB : cB + (ptrdiff_t)(t + 2) * kstep;
;             const char* a3 = a2 + kstep; const char* b3 = b2 + kstep;
;             PG8_LDB(B0, 0, 0); PG8_SCHED; PG8_LDA(At, 0, 0); PG8_STAGE(PG8_SA(1, 1), a1 + hstepA, voffA);
;             PG8_WAIT_L(8); PG8_BAR; PG8_WAIT_L(0); PG8_MMA(0, 0, At, B0); PG8_BAR; PG8_SCHED;
;             PG8_LDB(B1, 0, 1); PG8_STAGE(PG8_SB(0, 0), b2, voffB);
;             PG8_BAR; PG8_WAIT_L(0); PG8_MMA(0, 1, At, B1); PG8_BAR;
;             PG8_LDA(At, 0, 1); PG8_STAGE(PG8_SA(0, 0), a2, voffA);
;             PG8_BAR; PG8_WAIT_L(0); PG8_MMA(1, 0, At, B0); PG8_BAR; PG8_SCHED;
;             PG8_STAGE(PG8_SB(0, 1), b2 + hstepB, voffB);
;             PG8_WAIT_V(6); PG8_BAR; PG8_MMA(1, 1, At, B1); PG8_BAR;
;             PG8_LDB(B0, 1, 0); PG8_SCHED; PG8_LDA(At, 1, 0); PG8_STAGE(PG8_SA(0, 1), a2 + hstepA, voffA);
;             PG8_WAIT_L(8); PG8_BAR; PG8_WAIT_L(0); PG8_MMA(0, 0, At, B0); PG8_BAR; PG8_SCHED;
;             PG8_LDB(B1, 1, 1); PG8_STAGE(PG8_SB(1, 0), b3, voffB);
;             PG8_BAR; PG8_WAIT_L(0); PG8_MMA(0, 1, At, B1); PG8_BAR;
;             PG8_LDA(At, 1, 1); PG8_STAGE(PG8_SA(1, 0), a3, voffA);
;             PG8_BAR; PG8_WAIT_L(0); PG8_MMA(1, 0, At, B0); PG8_BAR; PG8_SCHED;
;             PG8_STAGE(PG8_SB(1, 1), b3 + hstepB, voffB);
;             PG8_WAIT_V(6); PG8_BAR; PG8_MMA(1, 1, At, B1); PG8_BAR;
	s_waitcnt lgkmcnt(0)
	s_waitcnt lgkmcnt(0)
	v_mfma_f32_16x16x32_bf16 v[146:149], v[106:109], v[138:141], v[146:149]
	v_mfma_f32_16x16x32_bf16 v[150:153], v[130:133], v[138:141], v[150:153]
	v_mfma_f32_16x16x32_bf16 v[154:157], v[106:109], v[170:173], v[154:157]
	v_mfma_f32_16x16x32_bf16 v[158:161], v[130:133], v[170:173], v[158:161]
	v_mfma_f32_16x16x32_bf16 v[162:165], v[106:109], v[178:181], v[162:165]
	v_mfma_f32_16x16x32_bf16 v[166:169], v[130:133], v[178:181], v[166:169]
	v_mfma_f32_16x16x32_bf16 v[18:21], v[106:109], v[186:189], v[18:21]
	v_mfma_f32_16x16x32_bf16 v[22:25], v[130:133], v[186:189], v[22:25]
	v_mfma_f32_16x16x32_bf16 v[146:149], v[110:113], v[142:145], v[146:149]
	v_mfma_f32_16x16x32_bf16 v[150:153], v[134:137], v[142:145], v[150:153]
	v_mfma_f32_16x16x32_bf16 v[154:157], v[110:113], v[174:177], v[154:157]
	v_mfma_f32_16x16x32_bf16 v[158:161], v[134:137], v[174:177], v[158:161]
	v_mfma_f32_16x16x32_bf16 v[162:165], v[110:113], v[182:185], v[162:165]
	v_mfma_f32_16x16x32_bf16 v[166:169], v[134:137], v[182:185], v[166:169]
	v_mfma_f32_16x16x32_bf16 v[18:21], v[110:113], v[190:193], v[18:21]
	v_mfma_f32_16x16x32_bf16 v[22:25], v[134:137], v[190:193], v[22:25]
	s_barrier
	s_add_u32 s46, s70, 0x10180
	s_addc_u32 s47, s71, 0
	s_add_i32 s44, s44, s9
	v_lshl_add_u64 v[106:107], s[46:47], 0, v[2:3]
	s_mov_b32 m0, s44
	s_add_i32 s42, s44, 0x2000
	global_load_lds_dwordx4 v[106:107], off
	v_lshl_add_u64 v[106:107], s[46:47], 0, v[6:7]
	s_mov_b32 m0, s42
	s_nop 0
	global_load_lds_dwordx4 v[106:107], off
	s_waitcnt vmcnt(6)
	s_barrier
	v_mfma_f32_16x16x32_bf16 v[26:29], v[194:197], v[138:141], v[26:29]
	v_mfma_f32_16x16x32_bf16 v[30:33], v[202:205], v[138:141], v[30:33]
	v_mfma_f32_16x16x32_bf16 v[62:65], v[194:197], v[170:173], v[62:65]
	v_mfma_f32_16x16x32_bf16 v[106:109], v[202:205], v[170:173], v[118:121]
	v_mfma_f32_16x16x32_bf16 v[110:113], v[194:197], v[178:181], v[122:125]
	v_mfma_f32_16x16x32_bf16 v[118:121], v[202:205], v[178:181], v[126:129]
	v_mfma_f32_16x16x32_bf16 v[98:101], v[194:197], v[186:189], v[98:101]
	v_mfma_f32_16x16x32_bf16 v[102:105], v[202:205], v[186:189], v[102:105]
	v_mfma_f32_16x16x32_bf16 v[26:29], v[198:201], v[142:145], v[26:29]
	v_mfma_f32_16x16x32_bf16 v[30:33], v[206:209], v[142:145], v[30:33]
	v_mfma_f32_16x16x32_bf16 v[62:65], v[198:201], v[174:177], v[62:65]
	v_mfma_f32_16x16x32_bf16 v[106:109], v[206:209], v[174:177], v[106:109]
	v_mfma_f32_16x16x32_bf16 v[110:113], v[198:201], v[182:185], v[110:113]
	v_mfma_f32_16x16x32_bf16 v[118:121], v[206:209], v[182:185], v[118:121]
	v_mfma_f32_16x16x32_bf16 v[98:101], v[198:201], v[190:193], v[98:101]
	v_mfma_f32_16x16x32_bf16 v[102:105], v[206:209], v[190:193], v[102:105]
	s_barrier
	ds_read_b128 v[122:125], v15
	ds_read_b128 v[126:129], v15 offset:1024
	ds_read_b128 v[130:133], v15 offset:2048
	ds_read_b128 v[134:137], v15 offset:3072
	s_add_u32 s46, s68, 0x10180
	s_addc_u32 s47, s69, 0
	s_mov_b32 m0, s23
	v_lshl_add_u64 v[194:195], s[46:47], 0, v[0:1]
	ds_read_b128 v[138:141], v16
	ds_read_b128 v[142:145], v16 offset:1024
	ds_read_b128 v[170:173], v16 offset:2048
	ds_read_b128 v[174:177], v16 offset:3072
	ds_read_b128 v[178:181], v16 offset:4096
	ds_read_b128 v[182:185], v16 offset:5120
	ds_read_b128 v[186:189], v16 offset:6144
	ds_read_b128 v[190:193], v16 offset:7168
	global_load_lds_dwordx4 v[194:195], off
	v_lshl_add_u64 v[194:195], s[46:47], 0, v[4:5]
	s_mov_b32 m0, s24
	s_nop 0
	global_load_lds_dwordx4 v[194:195], off
	s_waitcnt lgkmcnt(8)
	s_barrier
	s_waitcnt lgkmcnt(0)
	s_waitcnt lgkmcnt(0)
	v_mfma_f32_16x16x32_bf16 v[66:69], v[122:125], v[138:141], v[66:69]
	v_mfma_f32_16x16x32_bf16 v[70:73], v[130:133], v[138:141], v[70:73]
	v_mfma_f32_16x16x32_bf16 v[74:77], v[122:125], v[170:173], v[74:77]
	v_mfma_f32_16x16x32_bf16 v[78:81], v[130:133], v[170:173], v[78:81]
	v_mfma_f32_16x16x32_bf16 v[82:85], v[122:125], v[178:181], v[82:85]
	v_mfma_f32_16x16x32_bf16 v[86:89], v[130:133], v[178:181], v[86:89]
	v_mfma_f32_16x16x32_bf16 v[90:93], v[122:125], v[186:189], v[90:93]
	v_mfma_f32_16x16x32_bf16 v[94:97], v[130:133], v[186:189], v[94:97]
	v_mfma_f32_16x16x32_bf16 v[66:69], v[126:129], v[142:145], v[66:69]
	v_mfma_f32_16x16x32_bf16 v[70:73], v[134:137], v[142:145], v[70:73]
	v_mfma_f32_16x16x32_bf16 v[74:77], v[126:129], v[174:177], v[74:77]
	v_mfma_f32_16x16x32_bf16 v[78:81], v[134:137], v[174:177], v[78:81]
	v_mfma_f32_16x16x32_bf16 v[82:85], v[126:129], v[182:185], v[82:85]
	v_mfma_f32_16x16x32_bf16 v[86:89], v[134:137], v[182:185], v[86:89]
	v_mfma_f32_16x16x32_bf16 v[90:93], v[126:129], v[190:193], v[90:93]
	v_mfma_f32_16x16x32_bf16 v[94:97], v[134:137], v[190:193], v[94:97]
	s_barrier
	s_mov_b32 m0, s39
	v_lshl_add_u64 v[210:211], s[72:73], 0, v[2:3]
	ds_read_b128 v[194:197], v17
	ds_read_b128 v[198:201], v17 offset:1024
	ds_read_b128 v[202:205], v17 offset:2048
	ds_read_b128 v[206:209], v17 offset:3072
	global_load_lds_dwordx4 v[210:211], off
	v_lshl_add_u64 v[212:213], s[72:73], 0, v[6:7]
	s_mov_b32 m0, s35
	s_nop 0
	global_load_lds_dwordx4 v[212:213], off
	s_barrier
; #define PG8_STAGE(bufoff, gbase, voff) do { _Pragma("unroll") for (int _i = 0; _i < 2; ++_i) \
;         __builtin_amdgcn_global_load_lds((const unsigned*)((const char*)(gbase) + (voff)[_i]), (LAS unsigned*)(lds + (bufoff) + ldsw + _i * 8192), 16, 0, 0); } while (0)
; #define PG8_LDA(dst, b, h) do { _Pragma("unroll") for (int m = 0; m < 4; ++m) _Pragma("unroll") for (int k = 0; k < 2; ++k) dst[m][k] = *(const LAS bf16x8*)(lds + PG8_SA(b, h) + aoff + m * 2048 + k * 1024); } while (0)
; #define PG8_LDB(dst, b, h) do { _Pragma("unroll") for (int n = 0; n < 2; ++n) _Pragma("unroll") for (int k = 0; k < 2; ++k) dst[n][k] = *(const LAS bf16x8*)(lds + PG8_SB(b, h) + boff + n * 2048 + k * 1024); } while (0)
; #define PG8_MMA(ai, bj, At, Bt) do { __builtin_amdgcn_s_setprio(1); _Pragma("unroll") for (int m = 0; m < 4; ++m) _Pragma("unroll") for (int n = 0; n < 2; ++n) _Pragma("unroll") for (int k = 0; k < 2; ++k) \
;         acc[ai][bj][m][n] = __builtin_amdgcn_mfma_f32_16x16x32_bf16(Bt[n][k], At[m][k], acc[ai][bj][m][n], 0, 0, 0); __builtin_amdgcn_s_setprio(0); } while (0)
; #define PG8_WAIT_V(n) asm volatile("s_waitcnt vmcnt(" #n ")" ::: "memory")
; #define PG8_WAIT_L(n) asm volatile("s_waitcnt lgkmcnt(" #n ")" ::: "memory")
; #define PG8_BAR __builtin_amdgcn_s_barrier()
; #define PG8_SCHED __builtin_amdgcn_sched_barrier(0)
; template <class Epi>
; __device__ __forceinline__ void gemm_phase(LAS unsigned char* lds, const Gemm g, const StaticOrder& S, const Epi& E, int wv) {
;     ...
;             PG8_BAR; PG8_WAIT_L(0); PG8_MMA(0, 1, At, B1); PG8_BAR;
;             PG8_LDA(At, 0, 1); PG8_STAGE(PG8_SA(0, 0), a2, voffA);
;             PG8_BAR; PG8_WAIT_L(0); PG8_MMA(1, 0, At, B0); PG8_BAR; PG8_SCHED;
;             PG8_STAGE(PG8_SB(0, 1), b2 + hstepB, voffB);
;             PG8_WAIT_V(6); PG8_BAR; PG8_MMA(1, 1, At, B1); PG8_BAR;
;             PG8_LDB(B0, 1, 0); PG8_SCHED; PG8_LDA(At, 1, 0); PG8_STAGE(PG8_SA(0, 1), a2 + hstepA, voffA);
;             PG8_WAIT_L(8); PG8_BAR; PG8_WAIT_L(0); PG8_MMA(0, 0, At, B0); PG8_BAR; PG8_SCHED;
	s_waitcnt lgkmcnt(0)
	s_waitcnt lgkmcnt(0)
	v_mfma_f32_16x16x32_bf16 v[114:117], v[194:197], v[138:141], v[114:117]
	v_mfma_f32_16x16x32_bf16 v[34:37], v[202:205], v[138:141], v[34:37]
	v_mfma_f32_16x16x32_bf16 v[38:41], v[194:197], v[170:173], v[38:41]
	v_mfma_f32_16x16x32_bf16 v[42:45], v[202:205], v[170:173], v[42:45]
	v_mfma_f32_16x16x32_bf16 v[46:49], v[194:197], v[178:181], v[46:49]
	v_mfma_f32_16x16x32_bf16 v[50:53], v[202:205], v[178:181], v[50:53]
	v_mfma_f32_16x16x32_bf16 v[54:57], v[194:197], v[186:189], v[54:57]
	v_mfma_f32_16x16x32_bf16 v[58:61], v[202:205], v[186:189], v[58:61]
	v_mfma_f32_16x16x32_bf16 v[114:117], v[198:201], v[142:145], v[114:117]
	v_mfma_f32_16x16x32_bf16 v[34:37], v[206:209], v[142:145], v[34:37]
	v_mfma_f32_16x16x32_bf16 v[38:41], v[198:201], v[174:177], v[38:41]
	v_mfma_f32_16x16x32_bf16 v[42:45], v[206:209], v[174:177], v[42:45]
	v_mfma_f32_16x16x32_bf16 v[46:49], v[198:201], v[182:185], v[46:49]
	v_mfma_f32_16x16x32_bf16 v[50:53], v[206:209], v[182:185], v[50:53]
	v_mfma_f32_16x16x32_bf16 v[54:57], v[198:201], v[190:193], v[54:57]
	v_mfma_f32_16x16x32_bf16 v[58:61], v[206:209], v[190:193], v[58:61]
	s_mov_b32 m0, s10
	v_lshl_add_u64 v[214:215], s[74:75], 0, v[0:1]
	s_barrier
	ds_read_b128 v[138:141], v16 offset:16384
	ds_read_b128 v[142:145], v16 offset:17408
	ds_read_b128 v[170:173], v16 offset:18432
	ds_read_b128 v[174:177], v16 offset:19456
	ds_read_b128 v[178:181], v16 offset:20480
	ds_read_b128 v[182:185], v16 offset:21504
	ds_read_b128 v[186:189], v16 offset:22528
	ds_read_b128 v[190:193], v16 offset:23552
	global_load_lds_dwordx4 v[214:215], off
	v_lshl_add_u64 v[216:217], s[74:75], 0, v[4:5]
	s_mov_b32 m0, s11
	s_nop 0
	global_load_lds_dwordx4 v[216:217], off
	s_barrier
	s_waitcnt lgkmcnt(0)
	s_waitcnt lgkmcnt(0)
	v_mfma_f32_16x16x32_bf16 v[146:149], v[122:125], v[138:141], v[146:149]
	v_mfma_f32_16x16x32_bf16 v[150:153], v[130:133], v[138:141], v[150:153]
	v_mfma_f32_16x16x32_bf16 v[154:157], v[122:125], v[170:173], v[154:157]
	v_mfma_f32_16x16x32_bf16 v[158:161], v[130:133], v[170:173], v[158:161]
	v_mfma_f32_16x16x32_bf16 v[162:165], v[122:125], v[178:181], v[162:165]
	v_mfma_f32_16x16x32_bf16 v[166:169], v[130:133], v[178:181], v[166:169]
	v_mfma_f32_16x16x32_bf16 v[18:21], v[122:125], v[186:189], v[18:21]
	v_mfma_f32_16x16x32_bf16 v[22:25], v[130:133], v[186:189], v[22:25]
	v_mfma_f32_16x16x32_bf16 v[146:149], v[126:129], v[142:145], v[146:149]
	v_mfma_f32_16x16x32_bf16 v[150:153], v[134:137], v[142:145], v[150:153]
	v_mfma_f32_16x16x32_bf16 v[154:157], v[126:129], v[174:177], v[154:157]
	v_mfma_f32_16x16x32_bf16 v[158:161], v[134:137], v[174:177], v[158:161]
	v_mfma_f32_16x16x32_bf16 v[162:165], v[126:129], v[182:185], v[162:165]
	v_mfma_f32_16x16x32_bf16 v[166:169], v[134:137], v[182:185], v[166:169]
	v_mfma_f32_16x16x32_bf16 v[18:21], v[126:129], v[190:193], v[18:21]
	v_mfma_f32_16x16x32_bf16 v[22:25], v[134:137], v[190:193], v[22:25]
	s_barrier
	s_add_u32 s46, s72, 0x10000
	s_addc_u32 s47, s73, 0
	s_mov_b32 m0, s40
	v_lshl_add_u64 v[122:123], s[46:47], 0, v[2:3]
	global_load_lds_dwordx4 v[122:123], off
	v_lshl_add_u64 v[122:123], s[46:47], 0, v[6:7]
	s_mov_b32 m0, s38
	s_nop 0
	global_load_lds_dwordx4 v[122:123], off
	s_waitcnt vmcnt(6)
	s_barrier
	v_mfma_f32_16x16x32_bf16 v[26:29], v[194:197], v[138:141], v[26:29]
	v_mfma_f32_16x16x32_bf16 v[30:33], v[202:205], v[138:141], v[30:33]
	v_mfma_f32_16x16x32_bf16 v[62:65], v[194:197], v[170:173], v[62:65]
	v_mfma_f32_16x16x32_bf16 v[106:109], v[202:205], v[170:173], v[106:109]
	v_mfma_f32_16x16x32_bf16 v[110:113], v[194:197], v[178:181], v[110:113]
	v_mfma_f32_16x16x32_bf16 v[118:121], v[202:205], v[178:181], v[118:121]
	v_mfma_f32_16x16x32_bf16 v[98:101], v[194:197], v[186:189], v[98:101]
	v_mfma_f32_16x16x32_bf16 v[102:105], v[202:205], v[186:189], v[102:105]
	v_mfma_f32_16x16x32_bf16 v[26:29], v[198:201], v[142:145], v[26:29]
	v_mfma_f32_16x16x32_bf16 v[30:33], v[206:209], v[142:145], v[30:33]
	v_mfma_f32_16x16x32_bf16 v[62:65], v[198:201], v[174:177], v[62:65]
	v_mfma_f32_16x16x32_bf16 v[106:109], v[206:209], v[174:177], v[106:109]
	v_mfma_f32_16x16x32_bf16 v[110:113], v[198:201], v[182:185], v[110:113]
	v_mfma_f32_16x16x32_bf16 v[118:121], v[206:209], v[182:185], v[118:121]
	v_mfma_f32_16x16x32_bf16 v[98:101], v[198:201], v[190:193], v[98:101]
	v_mfma_f32_16x16x32_bf16 v[102:105], v[206:209], v[190:193], v[102:105]
	s_barrier
	ds_read_b128 v[122:125], v218
	ds_read_b128 v[126:129], v218 offset:1024
	ds_read_b128 v[130:133], v218 offset:2048
	ds_read_b128 v[134:137], v218 offset:3072
	s_add_u32 s38, s74, 0x10000
	s_addc_u32 s39, s75, 0
	s_mov_b32 m0, s12
	v_lshl_add_u64 v[194:195], s[38:39], 0, v[0:1]
	ds_read_b128 v[138:141], v16 offset:32768
	ds_read_b128 v[142:145], v16 offset:33792
	ds_read_b128 v[170:173], v16 offset:34816
	ds_read_b128 v[174:177], v16 offset:35840
	ds_read_b128 v[178:181], v16 offset:36864
	ds_read_b128 v[182:185], v16 offset:37888
	ds_read_b128 v[186:189], v16 offset:38912
	ds_read_b128 v[190:193], v16 offset:39936
	global_load_lds_dwordx4 v[194:195], off
	v_lshl_add_u64 v[194:195], s[38:39], 0, v[4:5]
	s_mov_b32 m0, s13
	s_nop 0
	global_load_lds_dwordx4 v[194:195], off
	s_waitcnt lgkmcnt(8)
	s_barrier
; #define PG8_STAGE(bufoff, gbase, voff) do { _Pragma("unroll") for (int _i = 0; _i < 2; ++_i) \
;         __builtin_amdgcn_global_load_lds((const unsigned*)((const char*)(gbase) + (voff)[_i]), (LAS unsigned*)(lds + (bufoff) + ldsw + _i * 8192), 16, 0, 0); } while (0)
; #define PG8_LDA(dst, b, h) do { _Pragma("unroll") for (int m = 0; m < 4; ++m) _Pragma("unroll") for (int k = 0; k < 2; ++k) dst[m][k] = *(const LAS bf16x8*)(lds + PG8_SA(b, h) + aoff + m * 2048 + k * 1024); } while (0)
; #define PG8_LDB(dst, b, h) do { _Pragma("unroll") for (int n = 0; n < 2; ++n) _Pragma("unroll") for (int k = 0; k < 2; ++k) dst[n][k] = *(const LAS bf16x8*)(lds + PG8_SB(b, h) + boff + n * 2048 + k * 1024); } while (0)
; #define PG8_MMA(ai, bj, At, Bt) do { __builtin_amdgcn_s_setprio(1); _Pragma("unroll") for (int m = 0; m < 4; ++m) _Pragma("unroll") for (int n = 0; n < 2; ++n) _Pragma("unroll") for (int k = 0; k < 2; ++k) \
;         acc[ai][bj][m][n] = __builtin_amdgcn_mfma_f32_16x16x32_bf16(Bt[n][k], At[m][k], acc[ai][bj][m][n], 0, 0, 0); __builtin_amdgcn_s_setprio(0); } while (0)
; #define PG8_WAIT_V(n) asm volatile("s_waitcnt vmcnt(" #n ")" ::: "memory")
; #define PG8_WAIT_L(n) asm volatile("s_waitcnt lgkmcnt(" #n ")" ::: "memory")
; #define PG8_BAR __builtin_amdgcn_s_barrier()
; #define PG8_SCHED __builtin_amdgcn_sched_barrier(0)
; template <class Epi>
; __device__ __forceinline__ void gemm_phase(LAS unsigned char* lds, const Gemm g, const StaticOrder& S, const Epi& E, int wv) {
;     ...
;             PG8_WAIT_L(8); PG8_BAR; PG8_WAIT_L(0); PG8_MMA(0, 0, At, B0); PG8_BAR; PG8_SCHED;
;             PG8_LDB(B1, 1, 1); PG8_STAGE(PG8_SB(1, 0), b3, voffB);
;             PG8_BAR; PG8_WAIT_L(0); PG8_MMA(0, 1, At, B1); PG8_BAR;
;             PG8_LDA(At, 1, 1); PG8_STAGE(PG8_SA(1, 0), a3, voffA);
;             PG8_BAR; PG8_WAIT_L(0); PG8_MMA(1, 0, At, B0); PG8_BAR; PG8_SCHED;
;             PG8_STAGE(PG8_SB(1, 1), b3 + hstepB, voffB);
;             PG8_WAIT_V(6); PG8_BAR; PG8_MMA(1, 1, At, B1); PG8_BAR;
	s_waitcnt lgkmcnt(0)
	s_waitcnt lgkmcnt(0)
	v_mfma_f32_16x16x32_bf16 v[66:69], v[122:125], v[138:141], v[66:69]
	v_mfma_f32_16x16x32_bf16 v[70:73], v[130:133], v[138:141], v[70:73]
	v_mfma_f32_16x16x32_bf16 v[74:77], v[122:125], v[170:173], v[74:77]
	v_mfma_f32_16x16x32_bf16 v[78:81], v[130:133], v[170:173], v[78:81]
	v_mfma_f32_16x16x32_bf16 v[82:85], v[122:125], v[178:181], v[82:85]
	v_mfma_f32_16x16x32_bf16 v[86:89], v[130:133], v[178:181], v[86:89]
	v_mfma_f32_16x16x32_bf16 v[90:93], v[122:125], v[186:189], v[90:93]
	v_mfma_f32_16x16x32_bf16 v[94:97], v[130:133], v[186:189], v[94:97]
	v_mfma_f32_16x16x32_bf16 v[66:69], v[126:129], v[142:145], v[66:69]
	v_mfma_f32_16x16x32_bf16 v[70:73], v[134:137], v[142:145], v[70:73]
	v_mfma_f32_16x16x32_bf16 v[74:77], v[126:129], v[174:177], v[74:77]
	v_mfma_f32_16x16x32_bf16 v[78:81], v[134:137], v[174:177], v[78:81]
	v_mfma_f32_16x16x32_bf16 v[82:85], v[126:129], v[182:185], v[82:85]
	v_mfma_f32_16x16x32_bf16 v[86:89], v[134:137], v[182:185], v[86:89]
	v_mfma_f32_16x16x32_bf16 v[90:93], v[126:129], v[190:193], v[90:93]
	v_mfma_f32_16x16x32_bf16 v[94:97], v[134:137], v[190:193], v[94:97]
	s_barrier
	s_mov_b32 m0, s43
	v_lshl_add_u64 v[210:211], v[210:211], 0, s[50:51]
	ds_read_b128 v[194:197], v219
	ds_read_b128 v[198:201], v219 offset:1024
	ds_read_b128 v[202:205], v219 offset:2048
	ds_read_b128 v[206:209], v219 offset:3072
	global_load_lds_dwordx4 v[210:211], off
	v_lshl_add_u64 v[210:211], v[212:213], 0, s[50:51]
	s_mov_b32 m0, s41
	s_nop 0
	global_load_lds_dwordx4 v[210:211], off
	s_barrier
	s_waitcnt lgkmcnt(0)
	s_waitcnt lgkmcnt(0)
	v_mfma_f32_16x16x32_bf16 v[114:117], v[194:197], v[138:141], v[114:117]
	v_mfma_f32_16x16x32_bf16 v[34:37], v[202:205], v[138:141], v[34:37]
	v_mfma_f32_16x16x32_bf16 v[38:41], v[194:197], v[170:173], v[38:41]
	v_mfma_f32_16x16x32_bf16 v[42:45], v[202:205], v[170:173], v[42:45]
	v_mfma_f32_16x16x32_bf16 v[46:49], v[194:197], v[178:181], v[46:49]
	v_mfma_f32_16x16x32_bf16 v[50:53], v[202:205], v[178:181], v[50:53]
	v_mfma_f32_16x16x32_bf16 v[54:57], v[194:197], v[186:189], v[54:57]
	v_mfma_f32_16x16x32_bf16 v[58:61], v[202:205], v[186:189], v[58:61]
	v_mfma_f32_16x16x32_bf16 v[114:117], v[198:201], v[142:145], v[114:117]
	v_mfma_f32_16x16x32_bf16 v[34:37], v[206:209], v[142:145], v[34:37]
	v_mfma_f32_16x16x32_bf16 v[38:41], v[198:201], v[174:177], v[38:41]
	v_mfma_f32_16x16x32_bf16 v[42:45], v[206:209], v[174:177], v[42:45]
	v_mfma_f32_16x16x32_bf16 v[46:49], v[198:201], v[182:185], v[46:49]
	v_mfma_f32_16x16x32_bf16 v[50:53], v[206:209], v[182:185], v[50:53]
	v_mfma_f32_16x16x32_bf16 v[54:57], v[198:201], v[190:193], v[54:57]
	v_mfma_f32_16x16x32_bf16 v[58:61], v[206:209], v[190:193], v[58:61]
	s_mov_b32 m0, s14
	v_lshl_add_u64 v[210:211], v[214:215], 0, s[50:51]
	s_barrier
	ds_read_b128 v[138:141], v16 offset:49152
	ds_read_b128 v[142:145], v16 offset:50176
	ds_read_b128 v[170:173], v16 offset:51200
	ds_read_b128 v[174:177], v16 offset:52224
	ds_read_b128 v[178:181], v16 offset:53248
	ds_read_b128 v[182:185], v16 offset:54272
	ds_read_b128 v[186:189], v16 offset:55296
	ds_read_b128 v[190:193], v16 offset:56320
	global_load_lds_dwordx4 v[210:211], off
	v_lshl_add_u64 v[210:211], v[216:217], 0, s[50:51]
	s_mov_b32 m0, s15
	s_nop 0
	global_load_lds_dwordx4 v[210:211], off
	s_barrier
	s_waitcnt lgkmcnt(0)
	s_waitcnt lgkmcnt(0)
	v_mfma_f32_16x16x32_bf16 v[146:149], v[122:125], v[138:141], v[146:149]
	v_mfma_f32_16x16x32_bf16 v[150:153], v[130:133], v[138:141], v[150:153]
	v_mfma_f32_16x16x32_bf16 v[154:157], v[122:125], v[170:173], v[154:157]
	v_mfma_f32_16x16x32_bf16 v[158:161], v[130:133], v[170:173], v[158:161]
	v_mfma_f32_16x16x32_bf16 v[162:165], v[122:125], v[178:181], v[162:165]
	v_mfma_f32_16x16x32_bf16 v[166:169], v[130:133], v[178:181], v[166:169]
	v_mfma_f32_16x16x32_bf16 v[18:21], v[122:125], v[186:189], v[18:21]
	v_mfma_f32_16x16x32_bf16 v[22:25], v[130:133], v[186:189], v[22:25]
	v_mfma_f32_16x16x32_bf16 v[146:149], v[126:129], v[142:145], v[146:149]
	v_mfma_f32_16x16x32_bf16 v[150:153], v[134:137], v[142:145], v[150:153]
	v_mfma_f32_16x16x32_bf16 v[154:157], v[126:129], v[174:177], v[154:157]
	v_mfma_f32_16x16x32_bf16 v[158:161], v[134:137], v[174:177], v[158:161]
	v_mfma_f32_16x16x32_bf16 v[162:165], v[126:129], v[182:185], v[162:165]
	v_mfma_f32_16x16x32_bf16 v[166:169], v[134:137], v[182:185], v[166:169]
	v_mfma_f32_16x16x32_bf16 v[18:21], v[126:129], v[190:193], v[18:21]
	v_mfma_f32_16x16x32_bf16 v[22:25], v[134:137], v[190:193], v[22:25]
	s_barrier
	s_add_u32 s38, s72, 0x10080
	s_addc_u32 s39, s73, 0
	s_mov_b32 m0, s44
	v_lshl_add_u64 v[122:123], s[38:39], 0, v[2:3]
	global_load_lds_dwordx4 v[122:123], off
	v_lshl_add_u64 v[122:123], s[38:39], 0, v[6:7]
	s_mov_b32 m0, s42
	s_nop 0
	global_load_lds_dwordx4 v[122:123], off
	s_waitcnt vmcnt(6)
	s_barrier
; #define PG8_BAR __builtin_amdgcn_s_barrier()
; template <class Epi>
; __device__ __forceinline__ void gemm_phase(LAS unsigned char* lds, const Gemm g, const StaticOrder& S, const Epi& E, int wv) {
;     ...
;             PG8_WAIT_V(6); PG8_BAR; PG8_MMA(1, 1, At, B1); PG8_BAR;
;     __device__ __forceinline__ void operator()(const f32x4 (&acc)[2][2][4][2], const Unit& u, int wr, int wc, int fr, int fq) const {
;         const int row0 = u.pm * BM + wr * 64 + fr; int colt = u.pn * BM; bf16_t* base = O; int tsel = 0;
;         if (split_cols) { tsel = colt / split_cols; base += (size_t)tsel * split_stride; colt -= tsel * split_cols; }
;         const int col0 = colt + wc * 32 + 8 * fq;
;         f32x4 cs[2][2];
;         if (SM == 2) {
; #pragma unroll
;             for (int bj = 0; bj < 2; ++bj)
; #pragma unroll
;                 for (int n = 0; n < 2; ++n) { const f32x4 s = *(const f32x4*)(ss + u.pn * BM + wc * 32 + 8 * fq + bj * HALF + 4 * n);
; #pragma unroll
;                     for (int j = 0; j < 4; ++j) cs[bj][n][j] = __builtin_amdgcn_rsqf(ss_fix(s[j]) * (1.0f / DM) + EPS); }
;         }
;         float rsv[8];
; #pragma unroll
;         for (int it = 0; it < 8; ++it) rsv[it] = (SM == 1) ? ss[row0 + (it >> 2) * HALF + (it & 3) * 16] : 1.0f;
; #pragma unroll
;         for (int ai = 0; ai < 2; ++ai)
; #pragma unroll
;             for (int m = 0; m < 4; ++m) { const int row = row0 + ai * HALF + m * 16; float rs = 1.0f; if (SM == 1) rs = __builtin_amdgcn_rsqf(ss_fix(rsv[ai * 4 + m]) * (1.0f / DM) + EPS);
;                 bf16_t* rowp = base + (size_t)row * ldc + col0;
; #pragma unroll
;                 for (int bj = 0; bj < 2; ++bj) { f32x4 v0 = acc[ai][bj][m][0], v1 = acc[ai][bj][m][1];
;                     if (SM == 1) { v0 *= rs; v1 *= rs; }
;                     if (SM == 2) { v0 *= cs[bj][0]; v1 *= cs[bj][1]; }
;                     if (ACT == 1) {
; #pragma unroll
;                         for (int j = 0; j < 4; ++j) { const float a = fmaxf(v0[j], 0.f), b = fmaxf(v1[j], 0.f); v0[j] = a * a; v1[j] = b * b; } }
;                     if (ACT == 2) { if (tsel == 0) {
; #pragma unroll
;                         for (int j = 0; j < 4; ++j) { const float a = v0[j], b = v1[j];
;                             v0[j] = a * fast_sigmoid(1.5957691216057308f * (a + 0.044715f * a * a * a)); v1[j] = b * fast_sigmoid(1.5957691216057308f * (b + 0.044715f * b * b * b)); } } }
	v_mfma_f32_16x16x32_bf16 v[26:29], v[194:197], v[138:141], v[26:29]
	v_mfma_f32_16x16x32_bf16 v[30:33], v[202:205], v[138:141], v[30:33]
	v_mfma_f32_16x16x32_bf16 v[62:65], v[194:197], v[170:173], v[62:65]
	v_mfma_f32_16x16x32_bf16 v[106:109], v[202:205], v[170:173], v[106:109]
	v_mfma_f32_16x16x32_bf16 v[110:113], v[194:197], v[178:181], v[110:113]
	v_mfma_f32_16x16x32_bf16 v[118:121], v[202:205], v[178:181], v[118:121]
	v_mfma_f32_16x16x32_bf16 v[98:101], v[194:197], v[186:189], v[98:101]
	v_mfma_f32_16x16x32_bf16 v[102:105], v[202:205], v[186:189], v[102:105]
	v_mfma_f32_16x16x32_bf16 v[26:29], v[198:201], v[142:145], v[26:29]
	v_mfma_f32_16x16x32_bf16 v[30:33], v[206:209], v[142:145], v[30:33]
	v_mfma_f32_16x16x32_bf16 v[62:65], v[198:201], v[174:177], v[62:65]
	v_mfma_f32_16x16x32_bf16 v[106:109], v[206:209], v[174:177], v[106:109]
	v_mfma_f32_16x16x32_bf16 v[110:113], v[198:201], v[182:185], v[110:113]
	v_mfma_f32_16x16x32_bf16 v[118:121], v[206:209], v[182:185], v[118:121]
	v_mfma_f32_16x16x32_bf16 v[98:101], v[198:201], v[190:193], v[98:101]
	v_mfma_f32_16x16x32_bf16 v[102:105], v[206:209], v[190:193], v[102:105]
	v_lshl_add_u32 v122, s58, 8, v12
	v_lshl_or_b32 v124, s34, 8, v14
	v_ashrrev_i32_e32 v125, 31, v124
	v_ashrrev_i32_e32 v123, 31, v122
	v_lshl_add_u64 v[124:125], v[124:125], 1, s[18:19]
	v_lshlrev_b64 v[126:127], 12, v[122:123]
	v_lshl_add_u64 v[126:127], v[124:125], 0, v[126:127]
	v_cvt_pk_bf16_f32 v66, v66, v67
	v_cvt_pk_bf16_f32 v67, v68, v69
	v_cvt_pk_bf16_f32 v68, v70, v71
	v_cvt_pk_bf16_f32 v69, v72, v73
	s_barrier
	global_store_dwordx4 v[126:127], v[66:69], off
	s_mov_b64 s[34:35], 0x80000
	v_cvt_pk_bf16_f32 v26, v26, v27
	v_cvt_pk_bf16_f32 v68, v34, v35
	v_or_b32_e32 v34, 16, v122
	v_ashrrev_i32_e32 v35, 31, v34
	v_cvt_pk_bf16_f32 v66, v114, v115
	v_cvt_pk_bf16_f32 v67, v116, v117
	v_cvt_pk_bf16_f32 v69, v36, v37
	v_lshlrev_b64 v[34:35], 12, v[34:35]
	global_store_dwordx4 v[126:127], v[66:69], off offset:256
	v_cvt_pk_bf16_f32 v36, v78, v79
	v_cvt_pk_bf16_f32 v37, v80, v81
	v_lshl_add_u64 v[66:67], v[124:125], 0, v[34:35]
	v_cvt_pk_bf16_f32 v34, v74, v75
	v_cvt_pk_bf16_f32 v35, v76, v77
	global_store_dwordx4 v[66:67], v[34:37], off
	v_cvt_pk_bf16_f32 v27, v28, v29
	v_cvt_pk_bf16_f32 v28, v30, v31
	v_cvt_pk_bf16_f32 v34, v38, v39
	v_cvt_pk_bf16_f32 v35, v40, v41
	v_cvt_pk_bf16_f32 v36, v42, v43
	v_cvt_pk_bf16_f32 v37, v44, v45
	global_store_dwordx4 v[66:67], v[34:37], off offset:256
	v_cvt_pk_bf16_f32 v29, v32, v33
	v_cvt_pk_bf16_f32 v18, v18, v19
	v_or_b32_e32 v34, 32, v122
	v_ashrrev_i32_e32 v35, 31, v34
	v_lshlrev_b64 v[34:35], 12, v[34:35]
	v_lshl_add_u64 v[38:39], v[124:125], 0, v[34:35]
	v_cvt_pk_bf16_f32 v34, v82, v83
	v_cvt_pk_bf16_f32 v35, v84, v85
	v_cvt_pk_bf16_f32 v36, v86, v87
	v_cvt_pk_bf16_f32 v37, v88, v89
	global_store_dwordx4 v[38:39], v[34:37], off
	v_cvt_pk_bf16_f32 v19, v20, v21
	v_cvt_pk_bf16_f32 v20, v22, v23
	v_cvt_pk_bf16_f32 v34, v46, v47
	v_cvt_pk_bf16_f32 v35, v48, v49
	v_cvt_pk_bf16_f32 v36, v50, v51
	v_cvt_pk_bf16_f32 v37, v52, v53
	global_store_dwordx4 v[38:39], v[34:37], off offset:256
	v_cvt_pk_bf16_f32 v21, v24, v25
	s_add_i32 s33, s33, s28
	v_or_b32_e32 v34, 48, v122
	v_ashrrev_i32_e32 v35, 31, v34
	v_lshlrev_b64 v[34:35], 12, v[34:35]
	v_lshl_add_u64 v[38:39], v[124:125], 0, v[34:35]
	v_cvt_pk_bf16_f32 v34, v90, v91
	v_cvt_pk_bf16_f32 v35, v92, v93
	v_cvt_pk_bf16_f32 v36, v94, v95
	v_cvt_pk_bf16_f32 v37, v96, v97
	global_store_dwordx4 v[38:39], v[34:37], off
	s_mov_b32 s58, s62
	s_mov_b64 s[70:71], s[66:67]
	v_cvt_pk_bf16_f32 v34, v54, v55
	v_cvt_pk_bf16_f32 v35, v56, v57
	v_cvt_pk_bf16_f32 v36, v58, v59
	v_cvt_pk_bf16_f32 v37, v60, v61
	global_store_dwordx4 v[38:39], v[34:37], off offset:256
	v_lshl_add_u64 v[38:39], v[126:127], 0, s[34:35]
	s_mov_b32 s34, 0x80000
	v_add_co_u32_e32 v40, vcc, s34, v126
	s_mov_b64 s[34:35], 0x90000
	s_nop 0
	v_addc_co_u32_e32 v41, vcc, 0, v127, vcc
	v_lshl_add_u64 v[30:31], v[126:127], 0, s[34:35]
	s_mov_b32 s34, 0x90000
	v_add_co_u32_e32 v32, vcc, s34, v126
	global_store_dwordx4 v[38:39], v[26:29], off offset:256
	s_nop 0
	v_addc_co_u32_e32 v33, vcc, 0, v127, vcc
	v_cvt_pk_bf16_f32 v26, v154, v155
	v_cvt_pk_bf16_f32 v27, v156, v157
	v_cvt_pk_bf16_f32 v28, v158, v159
	v_cvt_pk_bf16_f32 v29, v160, v161
	global_store_dwordx4 v[32:33], v[26:29], off
	s_mov_b64 s[34:35], 0xa0000
	v_cvt_pk_bf16_f32 v34, v146, v147
	v_cvt_pk_bf16_f32 v26, v62, v63
	v_cvt_pk_bf16_f32 v27, v64, v65
	v_cvt_pk_bf16_f32 v28, v106, v107
	v_cvt_pk_bf16_f32 v29, v108, v109
	global_store_dwordx4 v[30:31], v[26:29], off offset:256
	v_lshl_add_u64 v[30:31], v[126:127], 0, s[34:35]
	s_mov_b32 s34, 0xa0000
	v_add_co_u32_e32 v32, vcc, s34, v126
	v_cvt_pk_bf16_f32 v26, v162, v163
	v_cvt_pk_bf16_f32 v27, v164, v165
	v_cvt_pk_bf16_f32 v28, v166, v167
	v_cvt_pk_bf16_f32 v29, v168, v169
	v_addc_co_u32_e32 v33, vcc, 0, v127, vcc
	global_store_dwordx4 v[32:33], v[26:29], off
	s_mov_b64 s[34:35], 0xb0000
	v_cvt_pk_bf16_f32 v35, v148, v149
	v_cvt_pk_bf16_f32 v26, v110, v111
	v_cvt_pk_bf16_f32 v27, v112, v113
	v_cvt_pk_bf16_f32 v28, v118, v119
	v_cvt_pk_bf16_f32 v29, v120, v121
	global_store_dwordx4 v[30:31], v[26:29], off offset:256
	v_cvt_pk_bf16_f32 v36, v150, v151
	v_cvt_pk_bf16_f32 v37, v152, v153
	v_lshl_add_u64 v[26:27], v[126:127], 0, s[34:35]
	s_mov_b32 s34, 0xb0000
	v_add_co_u32_e32 v22, vcc, s34, v126
	s_mov_b32 s34, s60
	s_nop 0
	v_addc_co_u32_e32 v23, vcc, 0, v127, vcc
	global_store_dwordx4 v[22:23], v[18:21], off
	s_andn2_b64 vcc, exec, s[16:17]
	s_mov_b64 s[68:69], s[64:65]
	v_cvt_pk_bf16_f32 v18, v98, v99
	v_cvt_pk_bf16_f32 v19, v100, v101
	v_cvt_pk_bf16_f32 v20, v102, v103
	v_cvt_pk_bf16_f32 v21, v104, v105
	global_store_dwordx4 v[40:41], v[34:37], off
	global_store_dwordx4 v[26:27], v[18:21], off offset:256
	s_cbranch_vccz .LBB0_644

; #define PG8_STAGE(bufoff, gbase, voff) do { _Pragma("unroll") for (int _i = 0; _i < 2; ++_i) \
;         __builtin_amdgcn_global_load_lds((const unsigned*)((const char*)(gbase) + (voff)[_i]), (LAS unsigned*)(lds + (bufoff) + ldsw + _i * 8192), 16, 0, 0); } while (0)
; #define PG8_WAIT_V(n) asm volatile("s_waitcnt vmcnt(" #n ")" ::: "memory")
; #define PG8_BAR __builtin_amdgcn_s_barrier()
; template <class Epi>
; __device__ __forceinline__ void gemm_phase(LAS unsigned char* lds, const Gemm g, const StaticOrder& S, const Epi& E, int wv) {
;     ...
;     for (int i = 0; i < 2; ++i) { int R, C; stage_rc(tid * 16 + i * 8192, R, C); const int Rb = Epi::PERM ? ((R & ~31) + perm32(R & 31)) : R;
;         voffA[i] = (unsigned)(R * g.lda + C) * 2u; voffB[i] = (unsigned)(Rb * g.ldb + C) * 2u; }
;     const bool krev = (g.adiag & 2) != 0;
;     const ptrdiff_t kstep = krev ? -(ptrdiff_t)(BK * 2) : (ptrdiff_t)(BK * 2);
;     const size_t kbeg = krev ? (size_t)(nt - 1) * (BK * 2) : 0;
;     const size_t hstepA = (size_t)HALF * g.lda * 2, hstepB = (size_t)HALF * g.ldb * 2;
;     const size_t tstepA = 2 * hstepA, tstepB = 2 * hstepB;
;     const unsigned ldsw = (unsigned)wid * 1024u;
;     const int aoff = lds_byte(wr * 64 + fr, fq * 8), boff = lds_byte(wc * 32 + fr, fq * 8);
;     ...
;     Unit cur, nxt; int ui = 0;
;     if (!S.next(0, cur)) return;
;     f32x4 acc[2][2][4][2];
; #pragma unroll
;     for (int a = 0; a < 2; ++a)
; #pragma unroll
;         for (int b = 0; b < 2; ++b)
; #pragma unroll
;             for (int m = 0; m < 4; ++m)
; #pragma unroll
;                 for (int n = 0; n < 2; ++n) acc[a][b][m][n] = (f32x4){0.f, 0.f, 0.f, 0.f};
;     bf16x8 At[4][2], B0[2][2], B1[2][2];
;     const char* cA = (const char*)g.A + (size_t)cur.pm * tstepA + ((g.adiag & 1) ? (size_t)(cur.pn >> 1) * K * 2 : 0) + kbeg;
;     const char* cB = (const char*)g.Bt + (size_t)cur.pn * tstepB + kbeg;
;     PG8_STAGE(PG8_SB(0, 0), cB, voffB); PG8_STAGE(PG8_SA(0, 0), cA, voffA); PG8_STAGE(PG8_SB(0, 1), cB + hstepB, voffB); PG8_STAGE(PG8_SA(0, 1), cA + hstepA, voffA);
;     if (wr == 1) PG8_BAR;
;     PG8_WAIT_V(4); PG8_BAR;
;     PG8_STAGE(PG8_SB(1, 0), cB + kstep, voffB); PG8_STAGE(PG8_SA(1, 0), cA + kstep, voffA); PG8_STAGE(PG8_SB(1, 1), cB + hstepB + kstep, voffB);
;     PG8_WAIT_V(6); PG8_BAR;
.LBB0_705:
	v_readlane_b32 s6, v255, 10
	v_readlane_b32 s7, v255, 11
	s_and_b64 vcc, exec, s[6:7]
	s_cbranch_vccnz .LBB0_737
	v_ashrrev_i32_e32 v2, 31, v0
	v_lshrrev_b32_e32 v2, 26, v2
	v_lshlrev_b32_e32 v1, 4, v0
	v_add_u32_e32 v2, v0, v2
	v_bfe_i32 v0, v0, 27, 1
	v_lshrrev_b32_e32 v0, 22, v0
	v_add_u32_e32 v0, v1, v0
	v_and_b32_e32 v0, 0xfffffc00, v0
	v_sub_u32_e32 v0, v1, v0
	v_ashrrev_i32_e32 v9, 6, v2
	v_lshrrev_b32_e32 v2, 4, v0
	v_bitop3_b32 v0, v2, v0, 32 bitop3:0x6c
	v_ashrrev_i32_e32 v3, 31, v0
	v_lshrrev_b32_e32 v3, 26, v3
	v_add_u32_e32 v3, v0, v3
	v_lshlrev_b32_e32 v2, 3, v9
	v_ashrrev_i32_e32 v10, 6, v3
	v_and_b32_e32 v3, 0xc0, v3
	v_and_b32_e32 v2, -16, v2
	v_sub_u32_e32 v0, v0, v3
	v_mov_b32_e32 v3, 1
	v_add_u32_e32 v2, v10, v2
	v_ashrrev_i16_sdwa v0, v3, sext(v0) dst_sel:DWORD dst_unused:UNUSED_PAD src0_sel:DWORD src1_sel:BYTE_0
	v_lshlrev_b32_e32 v4, 5, v9
	v_bfe_i32 v11, v0, 0, 16
	v_lshlrev_b32_e32 v0, 1, v2
	v_lshrrev_b32_e32 v5, 2, v2
	v_and_b32_e32 v6, 3, v10
	s_mov_b32 s9, 0xfffe0
	v_and_b32_e32 v4, 32, v4
	v_and_b32_e32 v0, 24, v0
	v_and_b32_e32 v5, 4, v5
	v_and_or_b32 v6, v2, s9, v6
	v_or3_b32 v0, v6, v5, v0
	v_add_lshl_u32 v4, v4, v11, 1
	v_lshl_add_u32 v162, v0, 12, v4
	v_add_u32_e32 v0, 0x2000, v1
	v_ashrrev_i32_e32 v1, 31, v0
	v_lshrrev_b32_e32 v1, 22, v1
	v_add_u32_e32 v1, v0, v1
	v_ashrrev_i32_e32 v12, 10, v1
	v_mul_i32_i24_e32 v1, 0x400, v12
	v_sub_u32_e32 v0, v0, v1
	v_lshrrev_b32_e32 v1, 4, v0
	v_bitop3_b32 v0, v1, v0, 32 bitop3:0x6c
	v_lshl_add_u32 v160, v2, 12, v4
	v_ashrrev_i32_e32 v2, 31, v0
	v_lshrrev_b32_e32 v2, 26, v2
	s_waitcnt lgkmcnt(0)
	s_add_u32 s5, s50, 0x7300000
	v_add_u32_e32 v2, v0, v2
	s_addc_u32 s6, s51, 0
	v_lshlrev_b32_e32 v1, 3, v12
	v_ashrrev_i32_e32 v13, 6, v2
	v_and_b32_e32 v2, 0xc0, v2
	s_add_u32 s7, s52, 0x6900000
	v_and_b32_e32 v1, -16, v1
	v_sub_u32_e32 v0, v0, v2
	s_addc_u32 s8, s53, 0
	v_add_u32_e32 v1, v13, v1
	v_ashrrev_i16_sdwa v0, v3, sext(v0) dst_sel:DWORD dst_unused:UNUSED_PAD src0_sel:DWORD src1_sel:BYTE_0
	v_and_b32_e32 v3, 3, v13
	s_ashr_i32 s15, s4, 6
	s_ashr_i32 s71, s70, 31
	s_ashr_i32 s73, s72, 31
	s_ashr_i32 s23, s4, 8
	v_and_or_b32 v3, v1, s9, v3
	s_lshl_b32 s9, s15, 10
	s_lshl_b64 s[12:13], s[70:71], 20
	s_lshl_b64 s[10:11], s[72:73], 20
	s_add_u32 s74, s7, s10
	v_lshlrev_b32_e32 v4, 5, v12
	v_bfe_i32 v14, v0, 0, 16
	v_lshlrev_b32_e32 v0, 1, v1
	v_lshrrev_b32_e32 v2, 2, v1
	s_addc_u32 s75, s8, s11
	s_add_i32 s10, s9, 0
	v_and_b32_e32 v4, 32, v4
	v_and_b32_e32 v0, 24, v0
	v_and_b32_e32 v2, 4, v2
	s_add_i32 m0, s10, 0x10000
	v_or3_b32 v0, v3, v2, v0
	v_add_lshl_u32 v2, v4, v14, 1
	global_load_lds_dwordx4 v162, s[74:75]
	s_add_i32 m0, s10, 0x12000
	v_lshl_add_u32 v166, v0, 12, v2
	s_add_u32 s76, s5, s12
	global_load_lds_dwordx4 v166, s[74:75]
	s_addc_u32 s77, s6, s13
	s_mov_b32 m0, s10
	s_add_i32 s11, s10, 0x2000
	v_lshl_add_u32 v164, v1, 12, v2
	global_load_lds_dwordx4 v160, s[76:77]
	s_mov_b32 m0, s11
	s_add_u32 s12, s74, 0x80000
	global_load_lds_dwordx4 v164, s[76:77]
	s_addc_u32 s13, s75, 0
	s_add_i32 m0, s10, 0x14000
	v_mov_b32_e32 v163, 0
	global_load_lds_dwordx4 v162, s[12:13]
	s_add_i32 m0, s10, 0x16000
	s_add_u32 s24, s76, 0x80000
	global_load_lds_dwordx4 v166, s[12:13]
	s_addc_u32 s25, s77, 0
	s_add_i32 s12, s10, 0x4000
	s_mov_b32 m0, s12
	s_add_i32 s13, s10, 0x6000
	global_load_lds_dwordx4 v160, s[24:25]
	s_mov_b32 m0, s13
	v_mov_b32_e32 v167, v163
	global_load_lds_dwordx4 v164, s[24:25]
	v_mov_b32_e32 v161, v163
	v_mov_b32_e32 v165, v163
	s_mov_b32 s14, 0
	v_lshl_add_u64 v[6:7], s[74:75], 0, v[162:163]
	v_lshl_add_u64 v[4:5], s[74:75], 0, v[166:167]
	v_lshl_add_u64 v[2:3], s[76:77], 0, v[160:161]
	s_cmp_lg_u32 s23, 1
	v_lshl_add_u64 v[0:1], s[76:77], 0, v[164:165]
	s_cbranch_scc1 .LBB0_708
	s_barrier
	s_setprio 1

; #define PG8_STAGE(bufoff, gbase, voff) do { _Pragma("unroll") for (int _i = 0; _i < 2; ++_i) \
;         __builtin_amdgcn_global_load_lds((const unsigned*)((const char*)(gbase) + (voff)[_i]), (LAS unsigned*)(lds + (bufoff) + ldsw + _i * 8192), 16, 0, 0); } while (0)
; #define PG8_LDA(dst, b, h) do { _Pragma("unroll") for (int m = 0; m < 4; ++m) _Pragma("unroll") for (int k = 0; k < 2; ++k) dst[m][k] = *(const LAS bf16x8*)(lds + PG8_SA(b, h) + aoff + m * 2048 + k * 1024); } while (0)
; #define PG8_LDB(dst, b, h) do { _Pragma("unroll") for (int n = 0; n < 2; ++n) _Pragma("unroll") for (int k = 0; k < 2; ++k) dst[n][k] = *(const LAS bf16x8*)(lds + PG8_SB(b, h) + boff + n * 2048 + k * 1024); } while (0)
; #define PG8_MMA(ai, bj, At, Bt) do { __builtin_amdgcn_s_setprio(1); _Pragma("unroll") for (int m = 0; m < 4; ++m) _Pragma("unroll") for (int n = 0; n < 2; ++n) _Pragma("unroll") for (int k = 0; k < 2; ++k) \
;         acc[ai][bj][m][n] = __builtin_amdgcn_mfma_f32_16x16x32_bf16(Bt[n][k], At[m][k], acc[ai][bj][m][n], 0, 0, 0); __builtin_amdgcn_s_setprio(0); } while (0)
; #define PG8_WAIT_V(n) asm volatile("s_waitcnt vmcnt(" #n ")" ::: "memory")
; #define PG8_WAIT_L(n) asm volatile("s_waitcnt lgkmcnt(" #n ")" ::: "memory")
; #define PG8_BAR __builtin_amdgcn_s_barrier()
; template <class Epi>
; __device__ __forceinline__ void gemm_phase(LAS unsigned char* lds, const Gemm g, const StaticOrder& S, const Epi& E, int wv) {
;     ...
;             const bool last = (t == nt - 2);
;             const char* a1 = cA + (ptrdiff_t)(t + 1) * kstep;
;             const char* a2 = last ? nA : cA + (ptrdiff_t)(t + 2) * kstep; const char* b2 = last ? nB : cB + (ptrdiff_t)(t + 2) * kstep;
;             const char* a3 = a2 + kstep; const char* b3 = b2 + kstep;
;             PG8_LDB(B0, 0, 0); PG8_SCHED; PG8_LDA(At, 0, 0); PG8_STAGE(PG8_SA(1, 1), a1 + hstepA, voffA);
;             PG8_WAIT_L(8); PG8_BAR; PG8_WAIT_L(0); PG8_MMA(0, 0, At, B0); PG8_BAR; PG8_SCHED;
;             PG8_LDB(B1, 0, 1); PG8_STAGE(PG8_SB(0, 0), b2, voffB);
;             PG8_BAR; PG8_WAIT_L(0); PG8_MMA(0, 1, At, B1); PG8_BAR;
;             PG8_LDA(At, 0, 1); PG8_STAGE(PG8_SA(0, 0), a2, voffA);
;             PG8_BAR; PG8_WAIT_L(0); PG8_MMA(1, 0, At, B0); PG8_BAR; PG8_SCHED;
;             PG8_STAGE(PG8_SB(0, 1), b2 + hstepB, voffB);
;             PG8_WAIT_V(6); PG8_BAR; PG8_MMA(1, 1, At, B1); PG8_BAR;
.LBB0_717:
	s_add_u32 s42, s74, 0xfff80080
	s_addc_u32 s43, s75, -1
	s_cmp_eq_u32 s41, 28
	s_cselect_b32 s79, s33, s43
	s_cselect_b32 s78, s34, s42
	s_cselect_b32 s77, s35, s40
	s_cselect_b32 s76, s38, s39
	s_add_i32 m0, s10, 0xc000
	ds_read_b128 v[144:147], v194
	ds_read_b128 v[148:151], v194 offset:1024
	ds_read_b128 v[152:155], v194 offset:2048
	ds_read_b128 v[156:159], v194 offset:3072
	ds_read_b128 v[176:179], v194 offset:4096
	ds_read_b128 v[180:183], v194 offset:5120
	ds_read_b128 v[184:187], v194 offset:6144
	ds_read_b128 v[198:201], v194 offset:7168
	global_load_lds_dwordx4 v170, s[74:75]
	s_add_i32 m0, s10, 0xe000
	s_nop 0
	global_load_lds_dwordx4 v168, s[74:75]
	s_waitcnt lgkmcnt(8)
	s_barrier
	s_waitcnt lgkmcnt(0)
	s_waitcnt lgkmcnt(0)
	v_mfma_f32_16x16x32_bf16 v[124:127], v[128:131], v[144:147], v[124:127]
	v_mfma_f32_16x16x32_bf16 v[120:123], v[136:139], v[144:147], v[120:123]
	v_mfma_f32_16x16x32_bf16 v[108:111], v[128:131], v[152:155], v[108:111]
	v_mfma_f32_16x16x32_bf16 v[104:107], v[136:139], v[152:155], v[104:107]
	v_mfma_f32_16x16x32_bf16 v[92:95], v[128:131], v[176:179], v[92:95]
	v_mfma_f32_16x16x32_bf16 v[88:91], v[136:139], v[176:179], v[88:91]
	v_mfma_f32_16x16x32_bf16 v[76:79], v[128:131], v[184:187], v[76:79]
	v_mfma_f32_16x16x32_bf16 v[72:75], v[136:139], v[184:187], v[72:75]
	v_mfma_f32_16x16x32_bf16 v[124:127], v[132:135], v[148:151], v[124:127]
	v_mfma_f32_16x16x32_bf16 v[120:123], v[140:143], v[148:151], v[120:123]
	v_mfma_f32_16x16x32_bf16 v[108:111], v[132:135], v[156:159], v[108:111]
	v_mfma_f32_16x16x32_bf16 v[104:107], v[140:143], v[156:159], v[104:107]
	v_mfma_f32_16x16x32_bf16 v[92:95], v[132:135], v[180:183], v[92:95]
	v_mfma_f32_16x16x32_bf16 v[88:91], v[140:143], v[180:183], v[88:91]
	v_mfma_f32_16x16x32_bf16 v[76:79], v[132:135], v[198:201], v[76:79]
	v_mfma_f32_16x16x32_bf16 v[72:75], v[140:143], v[198:201], v[72:75]
	s_barrier
	s_add_i32 s42, s23, s9
	s_add_u32 s98, s76, s60
	s_addc_u32 s99, s77, s61
	s_mov_b32 m0, s42
	ds_read_b128 v[202:205], v195
	ds_read_b128 v[206:209], v195 offset:1024
	ds_read_b128 v[210:213], v195 offset:2048
	ds_read_b128 v[214:217], v195 offset:3072
	global_load_lds_dwordx4 v162, s[76:77]
	s_add_i32 m0, s42, 0x2000
	s_nop 0
	global_load_lds_dwordx4 v166, s[76:77]
	s_barrier
	s_waitcnt lgkmcnt(0)
	s_waitcnt lgkmcnt(0)
	v_mfma_f32_16x16x32_bf16 v[116:119], v[202:205], v[144:147], v[116:119]
	v_mfma_f32_16x16x32_bf16 v[112:115], v[210:213], v[144:147], v[112:115]
	v_mfma_f32_16x16x32_bf16 v[100:103], v[202:205], v[152:155], v[100:103]
	v_mfma_f32_16x16x32_bf16 v[96:99], v[210:213], v[152:155], v[96:99]
	v_mfma_f32_16x16x32_bf16 v[84:87], v[202:205], v[176:179], v[84:87]
	v_mfma_f32_16x16x32_bf16 v[80:83], v[210:213], v[176:179], v[80:83]
	v_mfma_f32_16x16x32_bf16 v[68:71], v[202:205], v[184:187], v[68:71]
	v_mfma_f32_16x16x32_bf16 v[64:67], v[210:213], v[184:187], v[64:67]
	v_mfma_f32_16x16x32_bf16 v[116:119], v[206:209], v[148:151], v[116:119]
	v_mfma_f32_16x16x32_bf16 v[112:115], v[214:217], v[148:151], v[112:115]
	v_mfma_f32_16x16x32_bf16 v[100:103], v[206:209], v[156:159], v[100:103]
	v_mfma_f32_16x16x32_bf16 v[96:99], v[214:217], v[156:159], v[96:99]
	v_mfma_f32_16x16x32_bf16 v[84:87], v[206:209], v[180:183], v[84:87]
	v_mfma_f32_16x16x32_bf16 v[80:83], v[214:217], v[180:183], v[80:83]
	v_mfma_f32_16x16x32_bf16 v[68:71], v[206:209], v[198:201], v[68:71]
	v_mfma_f32_16x16x32_bf16 v[64:67], v[214:217], v[198:201], v[64:67]
	s_mov_b32 m0, s10
	s_add_u32 s100, s78, s60
	s_addc_u32 s101, s79, s61
	s_barrier
	ds_read_b128 v[144:147], v194 offset:16384
	ds_read_b128 v[148:151], v194 offset:17408
	ds_read_b128 v[152:155], v194 offset:18432
	ds_read_b128 v[156:159], v194 offset:19456
	ds_read_b128 v[176:179], v194 offset:20480
	ds_read_b128 v[180:183], v194 offset:21504
	ds_read_b128 v[184:187], v194 offset:22528
	ds_read_b128 v[198:201], v194 offset:23552
	global_load_lds_dwordx4 v160, s[78:79]
	s_mov_b32 m0, s11
	s_nop 0
	global_load_lds_dwordx4 v164, s[78:79]
	s_waitcnt vmcnt(10)
	s_barrier
	s_waitcnt lgkmcnt(0)
	s_waitcnt lgkmcnt(0)
	v_mfma_f32_16x16x32_bf16 v[60:63], v[128:131], v[144:147], v[60:63]
	v_mfma_f32_16x16x32_bf16 v[56:59], v[136:139], v[144:147], v[56:59]
	v_mfma_f32_16x16x32_bf16 v[44:47], v[128:131], v[152:155], v[44:47]
	v_mfma_f32_16x16x32_bf16 v[40:43], v[136:139], v[152:155], v[40:43]
	v_mfma_f32_16x16x32_bf16 v[28:31], v[128:131], v[176:179], v[28:31]
	v_mfma_f32_16x16x32_bf16 v[24:27], v[136:139], v[176:179], v[24:27]
	v_mfma_f32_16x16x32_bf16 v[12:15], v[128:131], v[184:187], v[12:15]
	v_mfma_f32_16x16x32_bf16 v[8:11], v[136:139], v[184:187], v[8:11]
	v_mfma_f32_16x16x32_bf16 v[60:63], v[132:135], v[148:151], v[60:63]
	v_mfma_f32_16x16x32_bf16 v[56:59], v[140:143], v[148:151], v[56:59]
	v_mfma_f32_16x16x32_bf16 v[44:47], v[132:135], v[156:159], v[44:47]
	v_mfma_f32_16x16x32_bf16 v[40:43], v[140:143], v[156:159], v[40:43]
	v_mfma_f32_16x16x32_bf16 v[28:31], v[132:135], v[180:183], v[28:31]
	v_mfma_f32_16x16x32_bf16 v[24:27], v[140:143], v[180:183], v[24:27]
	v_mfma_f32_16x16x32_bf16 v[12:15], v[132:135], v[198:201], v[12:15]
	v_mfma_f32_16x16x32_bf16 v[8:11], v[140:143], v[198:201], v[8:11]
	s_barrier
	s_add_u32 s42, s76, 0x80000
	s_addc_u32 s43, s77, 0
	s_add_i32 s44, s24, s9
	s_mov_b32 m0, s44
	s_nop 0
	global_load_lds_dwordx4 v162, s[42:43]
	s_add_i32 m0, s44, 0x2000
	s_nop 0
	global_load_lds_dwordx4 v166, s[42:43]
	s_add_i32 s44, 0, 0x18000
	v_add_u32_e32 v140, s44, v191
	ds_read_b128 v[128:131], v140
	ds_read_b128 v[132:135], v140 offset:1024
	ds_read_b128 v[136:139], v140 offset:2048
	ds_read_b128 v[140:143], v140 offset:3072
	s_waitcnt vmcnt(6)
	s_barrier
; #define PG8_STAGE(bufoff, gbase, voff) do { _Pragma("unroll") for (int _i = 0; _i < 2; ++_i) \
;         __builtin_amdgcn_global_load_lds((const unsigned*)((const char*)(gbase) + (voff)[_i]), (LAS unsigned*)(lds + (bufoff) + ldsw + _i * 8192), 16, 0, 0); } while (0)
; #define PG8_LDA(dst, b, h) do { _Pragma("unroll") for (int m = 0; m < 4; ++m) _Pragma("unroll") for (int k = 0; k < 2; ++k) dst[m][k] = *(const LAS bf16x8*)(lds + PG8_SA(b, h) + aoff + m * 2048 + k * 1024); } while (0)
; #define PG8_LDB(dst, b, h) do { _Pragma("unroll") for (int n = 0; n < 2; ++n) _Pragma("unroll") for (int k = 0; k < 2; ++k) dst[n][k] = *(const LAS bf16x8*)(lds + PG8_SB(b, h) + boff + n * 2048 + k * 1024); } while (0)
; #define PG8_MMA(ai, bj, At, Bt) do { __builtin_amdgcn_s_setprio(1); _Pragma("unroll") for (int m = 0; m < 4; ++m) _Pragma("unroll") for (int n = 0; n < 2; ++n) _Pragma("unroll") for (int k = 0; k < 2; ++k) \
;         acc[ai][bj][m][n] = __builtin_amdgcn_mfma_f32_16x16x32_bf16(Bt[n][k], At[m][k], acc[ai][bj][m][n], 0, 0, 0); __builtin_amdgcn_s_setprio(0); } while (0)
; #define PG8_WAIT_V(n) asm volatile("s_waitcnt vmcnt(" #n ")" ::: "memory")
; #define PG8_WAIT_L(n) asm volatile("s_waitcnt lgkmcnt(" #n ")" ::: "memory")
; #define PG8_BAR __builtin_amdgcn_s_barrier()
; #define PG8_SCHED __builtin_amdgcn_sched_barrier(0)
; template <class Epi>
; __device__ __forceinline__ void gemm_phase(LAS unsigned char* lds, const Gemm g, const StaticOrder& S, const Epi& E, int wv) {
;     ...
;             PG8_WAIT_V(6); PG8_BAR; PG8_MMA(1, 1, At, B1); PG8_BAR;
;             PG8_LDB(B0, 1, 0); PG8_SCHED; PG8_LDA(At, 1, 0); PG8_STAGE(PG8_SA(0, 1), a2 + hstepA, voffA);
;             PG8_WAIT_L(8); PG8_BAR; PG8_WAIT_L(0); PG8_MMA(0, 0, At, B0); PG8_BAR; PG8_SCHED;
;             PG8_LDB(B1, 1, 1); PG8_STAGE(PG8_SB(1, 0), b3, voffB);
;             PG8_BAR; PG8_WAIT_L(0); PG8_MMA(0, 1, At, B1); PG8_BAR;
;             PG8_LDA(At, 1, 1); PG8_STAGE(PG8_SA(1, 0), a3, voffA);
;             PG8_BAR; PG8_WAIT_L(0); PG8_MMA(1, 0, At, B0); PG8_BAR; PG8_SCHED;
	v_mfma_f32_16x16x32_bf16 v[52:55], v[202:205], v[144:147], v[52:55]
	v_mfma_f32_16x16x32_bf16 v[48:51], v[210:213], v[144:147], v[48:51]
	v_mfma_f32_16x16x32_bf16 v[36:39], v[202:205], v[152:155], v[36:39]
	v_mfma_f32_16x16x32_bf16 v[32:35], v[210:213], v[152:155], v[32:35]
	v_mfma_f32_16x16x32_bf16 v[20:23], v[202:205], v[176:179], v[20:23]
	v_mfma_f32_16x16x32_bf16 v[16:19], v[210:213], v[176:179], v[16:19]
	v_mfma_f32_16x16x32_bf16 v[4:7], v[202:205], v[184:187], v[4:7]
	v_mfma_f32_16x16x32_bf16 v[0:3], v[210:213], v[184:187], v[0:3]
	v_mfma_f32_16x16x32_bf16 v[52:55], v[206:209], v[148:151], v[52:55]
	v_mfma_f32_16x16x32_bf16 v[48:51], v[214:217], v[148:151], v[48:51]
	v_mfma_f32_16x16x32_bf16 v[36:39], v[206:209], v[156:159], v[36:39]
	v_mfma_f32_16x16x32_bf16 v[32:35], v[214:217], v[156:159], v[32:35]
	v_mfma_f32_16x16x32_bf16 v[20:23], v[206:209], v[180:183], v[20:23]
	v_mfma_f32_16x16x32_bf16 v[16:19], v[214:217], v[180:183], v[16:19]
	v_mfma_f32_16x16x32_bf16 v[4:7], v[206:209], v[198:201], v[4:7]
	v_mfma_f32_16x16x32_bf16 v[0:3], v[214:217], v[198:201], v[0:3]
	s_waitcnt lgkmcnt(0)
	s_barrier
	s_add_u32 s42, s78, 0x80000
	s_addc_u32 s43, s79, 0
	s_mov_b32 m0, s12
	ds_read_b128 v[144:147], v194 offset:32768
	ds_read_b128 v[148:151], v194 offset:33792
	ds_read_b128 v[152:155], v194 offset:34816
	ds_read_b128 v[156:159], v194 offset:35840
	ds_read_b128 v[176:179], v194 offset:36864
	ds_read_b128 v[180:183], v194 offset:37888
	ds_read_b128 v[184:187], v194 offset:38912
	ds_read_b128 v[198:201], v194 offset:39936
	global_load_lds_dwordx4 v160, s[42:43]
	s_mov_b32 m0, s13
	s_nop 0
	global_load_lds_dwordx4 v164, s[42:43]
	s_waitcnt lgkmcnt(8)
	s_barrier
	s_waitcnt lgkmcnt(0)
	s_waitcnt lgkmcnt(0)
	v_mfma_f32_16x16x32_bf16 v[124:127], v[128:131], v[144:147], v[124:127]
	v_mfma_f32_16x16x32_bf16 v[120:123], v[136:139], v[144:147], v[120:123]
	v_mfma_f32_16x16x32_bf16 v[108:111], v[128:131], v[152:155], v[108:111]
	v_mfma_f32_16x16x32_bf16 v[104:107], v[136:139], v[152:155], v[104:107]
	v_mfma_f32_16x16x32_bf16 v[92:95], v[128:131], v[176:179], v[92:95]
	v_mfma_f32_16x16x32_bf16 v[88:91], v[136:139], v[176:179], v[88:91]
	v_mfma_f32_16x16x32_bf16 v[76:79], v[128:131], v[184:187], v[76:79]
	v_mfma_f32_16x16x32_bf16 v[72:75], v[136:139], v[184:187], v[72:75]
	v_mfma_f32_16x16x32_bf16 v[124:127], v[132:135], v[148:151], v[124:127]
	v_mfma_f32_16x16x32_bf16 v[120:123], v[140:143], v[148:151], v[120:123]
	v_mfma_f32_16x16x32_bf16 v[108:111], v[132:135], v[156:159], v[108:111]
	v_mfma_f32_16x16x32_bf16 v[104:107], v[140:143], v[156:159], v[104:107]
	v_mfma_f32_16x16x32_bf16 v[92:95], v[132:135], v[180:183], v[92:95]
	v_mfma_f32_16x16x32_bf16 v[88:91], v[140:143], v[180:183], v[88:91]
	v_mfma_f32_16x16x32_bf16 v[76:79], v[132:135], v[198:201], v[76:79]
	v_mfma_f32_16x16x32_bf16 v[72:75], v[140:143], v[198:201], v[72:75]
	s_barrier
	s_add_i32 s45, 0, 0x1c000
	s_add_i32 s42, s44, s9
	v_add_u32_e32 v197, s45, v191
	s_mov_b32 m0, s42
	ds_read_b128 v[202:205], v197
	ds_read_b128 v[206:209], v197 offset:1024
	ds_read_b128 v[210:213], v197 offset:2048
	ds_read_b128 v[214:217], v197 offset:3072
	global_load_lds_dwordx4 v162, s[98:99]
	s_add_i32 m0, s42, 0x2000
	s_nop 0
	global_load_lds_dwordx4 v166, s[98:99]
	s_barrier
	s_waitcnt lgkmcnt(0)
	s_waitcnt lgkmcnt(0)
	v_mfma_f32_16x16x32_bf16 v[116:119], v[202:205], v[144:147], v[116:119]
	v_mfma_f32_16x16x32_bf16 v[112:115], v[210:213], v[144:147], v[112:115]
	v_mfma_f32_16x16x32_bf16 v[100:103], v[202:205], v[152:155], v[100:103]
	v_mfma_f32_16x16x32_bf16 v[96:99], v[210:213], v[152:155], v[96:99]
	v_mfma_f32_16x16x32_bf16 v[84:87], v[202:205], v[176:179], v[84:87]
	v_mfma_f32_16x16x32_bf16 v[80:83], v[210:213], v[176:179], v[80:83]
	v_mfma_f32_16x16x32_bf16 v[68:71], v[202:205], v[184:187], v[68:71]
	v_mfma_f32_16x16x32_bf16 v[64:67], v[210:213], v[184:187], v[64:67]
	v_mfma_f32_16x16x32_bf16 v[116:119], v[206:209], v[148:151], v[116:119]
	v_mfma_f32_16x16x32_bf16 v[112:115], v[214:217], v[148:151], v[112:115]
	v_mfma_f32_16x16x32_bf16 v[100:103], v[206:209], v[156:159], v[100:103]
	v_mfma_f32_16x16x32_bf16 v[96:99], v[214:217], v[156:159], v[96:99]
	v_mfma_f32_16x16x32_bf16 v[84:87], v[206:209], v[180:183], v[84:87]
	v_mfma_f32_16x16x32_bf16 v[80:83], v[214:217], v[180:183], v[80:83]
	v_mfma_f32_16x16x32_bf16 v[68:71], v[206:209], v[198:201], v[68:71]
	v_mfma_f32_16x16x32_bf16 v[64:67], v[214:217], v[198:201], v[64:67]
	s_mov_b32 m0, s15
	s_barrier
	ds_read_b128 v[144:147], v194 offset:49152
	ds_read_b128 v[148:151], v194 offset:50176
	ds_read_b128 v[152:155], v194 offset:51200
	ds_read_b128 v[156:159], v194 offset:52224
	ds_read_b128 v[176:179], v194 offset:53248
	ds_read_b128 v[180:183], v194 offset:54272
	ds_read_b128 v[184:187], v194 offset:55296
	ds_read_b128 v[198:201], v194 offset:56320
	global_load_lds_dwordx4 v160, s[100:101]
	s_mov_b32 m0, s22
	s_nop 0
	global_load_lds_dwordx4 v164, s[100:101]
	s_waitcnt vmcnt(10)
	s_barrier
	s_waitcnt lgkmcnt(0)
	s_waitcnt lgkmcnt(0)
	v_mfma_f32_16x16x32_bf16 v[60:63], v[128:131], v[144:147], v[60:63]
	v_mfma_f32_16x16x32_bf16 v[56:59], v[136:139], v[144:147], v[56:59]
	v_mfma_f32_16x16x32_bf16 v[44:47], v[128:131], v[152:155], v[44:47]
	v_mfma_f32_16x16x32_bf16 v[40:43], v[136:139], v[152:155], v[40:43]
	v_mfma_f32_16x16x32_bf16 v[28:31], v[128:131], v[176:179], v[28:31]
	v_mfma_f32_16x16x32_bf16 v[24:27], v[136:139], v[176:179], v[24:27]
	v_mfma_f32_16x16x32_bf16 v[12:15], v[128:131], v[184:187], v[12:15]
	v_mfma_f32_16x16x32_bf16 v[8:11], v[136:139], v[184:187], v[8:11]
	v_mfma_f32_16x16x32_bf16 v[60:63], v[132:135], v[148:151], v[60:63]
	v_mfma_f32_16x16x32_bf16 v[56:59], v[140:143], v[148:151], v[56:59]
	v_mfma_f32_16x16x32_bf16 v[44:47], v[132:135], v[156:159], v[44:47]
	v_mfma_f32_16x16x32_bf16 v[40:43], v[140:143], v[156:159], v[40:43]
	v_mfma_f32_16x16x32_bf16 v[28:31], v[132:135], v[180:183], v[28:31]
	v_mfma_f32_16x16x32_bf16 v[24:27], v[140:143], v[180:183], v[24:27]
	v_mfma_f32_16x16x32_bf16 v[12:15], v[132:135], v[198:201], v[12:15]
	v_mfma_f32_16x16x32_bf16 v[8:11], v[140:143], v[198:201], v[8:11]
	s_barrier
; #define PG8_STAGE(bufoff, gbase, voff) do { _Pragma("unroll") for (int _i = 0; _i < 2; ++_i) \
;         __builtin_amdgcn_global_load_lds((const unsigned*)((const char*)(gbase) + (voff)[_i]), (LAS unsigned*)(lds + (bufoff) + ldsw + _i * 8192), 16, 0, 0); } while (0)
; #define PG8_MMA(ai, bj, At, Bt) do { __builtin_amdgcn_s_setprio(1); _Pragma("unroll") for (int m = 0; m < 4; ++m) _Pragma("unroll") for (int n = 0; n < 2; ++n) _Pragma("unroll") for (int k = 0; k < 2; ++k) \
;         acc[ai][bj][m][n] = __builtin_amdgcn_mfma_f32_16x16x32_bf16(Bt[n][k], At[m][k], acc[ai][bj][m][n], 0, 0, 0); __builtin_amdgcn_s_setprio(0); } while (0)
; #define PG8_WAIT_V(n) asm volatile("s_waitcnt vmcnt(" #n ")" ::: "memory")
; #define PG8_BAR __builtin_amdgcn_s_barrier()
; template <class Epi>
; __device__ __forceinline__ void gemm_phase(LAS unsigned char* lds, const Gemm g, const StaticOrder& S, const Epi& E, int wv) {
;     ...
;             PG8_STAGE(PG8_SB(1, 1), b3 + hstepB, voffB);
;             PG8_WAIT_V(6); PG8_BAR; PG8_MMA(1, 1, At, B1); PG8_BAR;
;         }
;     __device__ __forceinline__ void operator()(const f32x4 (&acc)[2][2][4][2], const Unit& u, int wr, int wc, int fr, int fq) const {
;         const int row0 = u.pm * BM + wr * 64 + fr, col0 = u.pn * BM + wc * 32 + 8 * fq;
;         constexpr int RD = 3;
;         f32x4 hbuf[RD][4]; u32x4 hraw[RD][2]; u32x4 pbuf[RD][2]; float rsb[RD];
;     ...
;         RES_LOAD(0, 0); RES_LOAD(1, 1);
	s_add_u32 s42, s76, 0x80080
	s_addc_u32 s43, s77, 0
	s_add_i32 s44, s45, s9
	s_mov_b32 m0, s44
	s_nop 0
	global_load_lds_dwordx4 v162, s[42:43]
	s_add_i32 m0, s44, 0x2000
	s_nop 0
	global_load_lds_dwordx4 v166, s[42:43]
	ds_read_b128 v[128:131], v193
	ds_read_b128 v[132:135], v193 offset:1024
	ds_read_b128 v[136:139], v193 offset:2048
	ds_read_b128 v[140:143], v193 offset:3072
	s_waitcnt vmcnt(6)
	s_barrier
	v_mfma_f32_16x16x32_bf16 v[52:55], v[202:205], v[144:147], v[52:55]
	v_mfma_f32_16x16x32_bf16 v[48:51], v[210:213], v[144:147], v[48:51]
	v_mfma_f32_16x16x32_bf16 v[36:39], v[202:205], v[152:155], v[36:39]
	v_mfma_f32_16x16x32_bf16 v[32:35], v[210:213], v[152:155], v[32:35]
	v_mfma_f32_16x16x32_bf16 v[20:23], v[202:205], v[176:179], v[20:23]
	v_mfma_f32_16x16x32_bf16 v[16:19], v[210:213], v[176:179], v[16:19]
	v_mfma_f32_16x16x32_bf16 v[4:7], v[202:205], v[184:187], v[4:7]
	v_mfma_f32_16x16x32_bf16 v[0:3], v[210:213], v[184:187], v[0:3]
	v_mfma_f32_16x16x32_bf16 v[52:55], v[206:209], v[148:151], v[52:55]
	v_mfma_f32_16x16x32_bf16 v[48:51], v[214:217], v[148:151], v[48:51]
	v_mfma_f32_16x16x32_bf16 v[36:39], v[206:209], v[156:159], v[36:39]
	v_mfma_f32_16x16x32_bf16 v[32:35], v[214:217], v[156:159], v[32:35]
	v_mfma_f32_16x16x32_bf16 v[20:23], v[206:209], v[180:183], v[20:23]
	v_mfma_f32_16x16x32_bf16 v[16:19], v[214:217], v[180:183], v[16:19]
	v_mfma_f32_16x16x32_bf16 v[4:7], v[206:209], v[198:201], v[4:7]
	v_mfma_f32_16x16x32_bf16 v[0:3], v[214:217], v[198:201], v[0:3]
	s_waitcnt lgkmcnt(0)
	s_add_i32 s41, s41, 2
	s_add_u32 s39, s39, 0x100
	s_addc_u32 s40, s40, 0
	s_add_u32 s74, s74, 0x100
	s_addc_u32 s75, s75, 0
	s_cmp_gt_u32 s41, 29
	s_barrier
	s_cbranch_scc0 .LBB0_717
	v_lshl_add_u32 v186, s70, 8, v190
	v_lshl_or_b32 v176, s72, 8, v192
	v_ashrrev_i32_e32 v187, 31, v186
	v_lshlrev_b64 v[128:129], 11, v[186:187]
	v_ashrrev_i32_e32 v177, 31, v176
	v_lshl_add_u64 v[128:129], v[128:129], 0, v[176:177]
	v_lshlrev_b64 v[178:179], 1, v[128:129]
	v_lshl_add_u64 v[180:181], v[186:187], 2, s[56:57]
	v_lshl_add_u64 v[128:129], s[58:59], 0, v[178:179]
	global_load_dword v199, v[180:181], off
	global_load_dwordx4 v[200:203], v[128:129], off
	v_or_b32_e32 v188, 16, v186
	v_or_b32_e32 v182, 32, v186
	v_ashrrev_i32_e32 v189, 31, v188
	v_ashrrev_i32_e32 v183, 31, v182
	v_lshl_add_u64 v[130:131], v[188:189], 2, s[56:57]
	v_lshlrev_b64 v[132:133], 11, v[182:183]
	v_lshl_add_u64 v[134:135], v[182:183], 2, s[56:57]
	global_load_dword v198, v[130:131], off
	global_load_dword v197, v[134:135], off
	v_lshl_add_u64 v[130:131], v[132:133], 0, v[176:177]
	v_lshl_add_u64 v[132:133], s[50:51], 0, v[178:179]
	global_load_dwordx4 v[204:207], v[132:133], off
	v_lshlrev_b64 v[128:129], 11, v[188:189]
	v_lshl_add_u64 v[128:129], v[128:129], 0, v[176:177]
	v_or_b32_e32 v132, 0x100, v178
	v_mov_b32_e32 v133, v179
	v_lshlrev_b64 v[128:129], 1, v[128:129]
	v_lshl_add_u64 v[134:135], s[50:51], 0, v[132:133]
	v_lshl_add_u64 v[132:133], s[58:59], 0, v[132:133]
	v_lshl_add_u64 v[136:137], s[50:51], 0, v[128:129]
	v_lshl_add_u64 v[138:139], s[58:59], 0, v[128:129]
	global_load_dwordx4 v[208:211], v[134:135], off
	global_load_dwordx4 v[212:215], v[132:133], off
	global_load_dwordx4 v[152:155], v[136:137], off
	global_load_dwordx4 v[156:159], v[138:139], off
	v_lshlrev_b64 v[130:131], 1, v[130:131]
	v_or_b32_e32 v128, 0x100, v128
	v_lshl_add_u64 v[140:141], s[50:51], 0, v[130:131]
	v_lshl_add_u64 v[142:143], s[58:59], 0, v[130:131]
	v_or_b32_e32 v130, 0x100, v130
	v_lshl_add_u64 v[132:133], s[50:51], 0, v[128:129]
	v_lshl_add_u64 v[128:129], s[58:59], 0, v[128:129]
	v_lshl_add_u64 v[134:135], s[50:51], 0, v[130:131]
	global_load_dwordx4 v[136:139], v[140:141], off
	s_nop 0
	global_load_dwordx4 v[140:143], v[142:143], off
	v_lshl_add_u64 v[216:217], s[58:59], 0, v[130:131]
	global_load_dwordx4 v[144:147], v[132:133], off
	global_load_dwordx4 v[148:151], v[128:129], off
	s_nop 0
	global_load_dwordx4 v[128:131], v[134:135], off
	s_nop 0
	global_load_dwordx4 v[132:135], v[216:217], off
	v_lshlrev_b64 v[184:185], 12, v[186:187]
	s_waitcnt vmcnt(0)
; __device__ __forceinline__ float bf_lo(unsigned w) { return __uint_as_float(w << 16); }
; __device__ __forceinline__ float bf_hi(unsigned w) { return __uint_as_float(w & 0xffff0000u); }
;     __device__ __forceinline__ void operator()(const f32x4 (&acc)[2][2][4][2], const Unit& u, int wr, int wc, int fr, int fq) const {
;     ...
;         for (int it = 0; it < 8; ++it) { const int ai = it >> 2, m = it & 3, sc = it % RD;
;             if (it + RD - 1 < 8) RES_LOAD((it + RD - 1) % RD, it + RD - 1);
;             asm volatile("" ::: "memory");
;             const int row = row0 + ai * HALF + m * 16; const size_t ro = (size_t)row * DM + col0;
;             float rs = 1.0f; if (MODE == 1) rs = __builtin_amdgcn_rsqf(ss_fix(rsb[sc]) * (1.0f / DM) + EPS);
;             float sq = 0.f;
; #pragma unroll
;             for (int bj = 0; bj < 2; ++bj) { const size_t off = ro + bj * HALF;
;                 f32x4 v0 = acc[ai][bj][m][0], v1 = acc[ai][bj][m][1];
;                 if (MODE == 1) { const u32x4 pw = pbuf[sc][bj];
;                     v0[0] = fast_sigmoid(rs * v0[0]) * bf_lo(pw.x); v0[1] = fast_sigmoid(rs * v0[1]) * bf_hi(pw.x); v0[2] = fast_sigmoid(rs * v0[2]) * bf_lo(pw.y); v0[3] = fast_sigmoid(rs * v0[3]) * bf_hi(pw.y);
;                     v1[0] = fast_sigmoid(rs * v1[0]) * bf_lo(pw.z); v1[1] = fast_sigmoid(rs * v1[1]) * bf_hi(pw.z); v1[2] = fast_sigmoid(rs * v1[2]) * bf_lo(pw.w); v1[3] = fast_sigmoid(rs * v1[3]) * bf_hi(pw.w); }
;                 f32x4 h0, h1;
;                 if (IN16) { const u32x4 hw = hraw[sc][bj]; h0 = (f32x4){bf_lo(hw.x), bf_hi(hw.x), bf_lo(hw.y), bf_hi(hw.y)}; h1 = (f32x4){bf_lo(hw.z), bf_hi(hw.z), bf_lo(hw.w), bf_hi(hw.w)}; }
;                 else { h0 = hbuf[sc][2 * bj]; h1 = hbuf[sc][2 * bj + 1]; }
;                 const f32x4 o0 = h0 + v0, o1 = h1 + v1;
;                 if (OUT32) { *(f32x4*)(hout + off) = o0; *(f32x4*)(hout + off + 4) = o1; }
;                 if (hb) { u32x4 w; w.x = pk_bf16(o0[0], o0[1]); w.y = pk_bf16(o0[2], o0[3]); w.z = pk_bf16(o1[0], o1[1]); w.w = pk_bf16(o1[2], o1[3]); *(u32x4*)(hb + off) = w; }
;                 sq += ((o0[0] * o0[0] + o0[1] * o0[1]) + (o0[2] * o0[2] + o0[3] * o0[3])) + ((o1[0] * o1[0] + o1[1] * o1[1]) + (o1[2] * o1[2] + o1[3] * o1[3])); }
;             if (ss_out) { sq += __shfl_xor(sq, 16); sq += __shfl_xor(sq, 32); if (fq == 0) atomicAdd((unsigned*)(ss_out + row), ss_enc(sq)); }
	v_cvt_f32_u32_e32 v199, v199
	v_lshlrev_b32_e32 v218, 16, v202
	v_and_b32_e32 v219, 0xffff0000, v202
	v_lshlrev_b32_e32 v216, 16, v200
	v_mul_f32_e32 v199, 0x3b800000, v199
	v_fmamk_f32 v199, v199, 0x3a000000, v196
	v_rsq_f32_e32 v199, v199
	v_and_b32_e32 v217, 0xffff0000, v200
	v_lshlrev_b32_e32 v200, 16, v201
	v_and_b32_e32 v201, 0xffff0000, v201
	v_mul_f32_e32 v124, v124, v199
	v_mul_f32_e32 v125, v125, v199
	v_mul_f32_e32 v126, v126, v199
	v_mul_f32_e32 v127, v127, v199
	v_mul_f32_e32 v120, v120, v199
	v_mul_f32_e32 v121, v121, v199
	v_mul_f32_e32 v122, v122, v199
	v_mul_f32_e32 v123, v123, v199
	v_mul_f32_e32 v124, 0xbfb8aa3b, v124
	v_mul_f32_e32 v125, 0xbfb8aa3b, v125
	v_mul_f32_e32 v126, 0xbfb8aa3b, v126
	v_mul_f32_e32 v127, 0xbfb8aa3b, v127
	v_mul_f32_e32 v120, 0xbfb8aa3b, v120
	v_mul_f32_e32 v121, 0xbfb8aa3b, v121
	v_mul_f32_e32 v122, 0xbfb8aa3b, v122
	v_mul_f32_e32 v123, 0xbfb8aa3b, v123
	v_exp_f32_e32 v124, v124
	v_exp_f32_e32 v125, v125
	v_exp_f32_e32 v126, v126
	v_exp_f32_e32 v127, v127
	v_exp_f32_e32 v120, v120
	v_exp_f32_e32 v121, v121
	v_exp_f32_e32 v122, v122
	v_exp_f32_e32 v202, v123
	v_add_f32_e32 v123, 1.0, v124
	v_add_f32_e32 v124, 1.0, v125
	v_add_f32_e32 v125, 1.0, v126
	v_add_f32_e32 v126, 1.0, v127
	v_add_f32_e32 v127, 1.0, v120
	v_add_f32_e32 v220, 1.0, v121
	v_mul_f32_e32 v116, v116, v199
	v_mul_f32_e32 v117, v117, v199
	v_mul_f32_e32 v118, v118, v199
	v_mul_f32_e32 v119, v119, v199
	v_add_f32_e32 v221, 1.0, v122
	v_rcp_f32_e32 v121, v124
	v_rcp_f32_e32 v122, v125
	v_rcp_f32_e32 v124, v127
	v_rcp_f32_e32 v125, v220
	v_add_f32_e32 v127, 1.0, v202
	v_mul_f32_e32 v116, 0xbfb8aa3b, v116
	v_mul_f32_e32 v117, 0xbfb8aa3b, v117
	v_mul_f32_e32 v118, 0xbfb8aa3b, v118
	v_mul_f32_e32 v119, 0xbfb8aa3b, v119
	v_mul_f32_e32 v112, v112, v199
	v_mul_f32_e32 v113, v113, v199
	v_rcp_f32_e32 v120, v123
	v_rcp_f32_e32 v123, v126
	v_rcp_f32_e32 v126, v221
	v_rcp_f32_e32 v127, v127
	v_exp_f32_e32 v116, v116
	v_exp_f32_e32 v117, v117
	v_exp_f32_e32 v118, v118
	v_exp_f32_e32 v119, v119
	v_mul_f32_e32 v112, 0xbfb8aa3b, v112
	v_mul_f32_e32 v113, 0xbfb8aa3b, v113
	v_mul_f32_e32 v114, v114, v199
	v_mul_f32_e32 v115, v115, v199
	v_exp_f32_e32 v112, v112
	v_exp_f32_e32 v113, v113
	v_mul_f32_e32 v114, 0xbfb8aa3b, v114
	v_mul_f32_e32 v115, 0xbfb8aa3b, v115
	v_lshlrev_b32_e32 v222, 16, v206
	v_and_b32_e32 v223, 0xffff0000, v206
	v_exp_f32_e32 v114, v114
	v_exp_f32_e32 v115, v115
	v_lshlrev_b32_e32 v202, 16, v203
	v_and_b32_e32 v203, 0xffff0000, v203
	v_lshlrev_b32_e32 v220, 16, v204
	v_and_b32_e32 v221, 0xffff0000, v204
	v_lshlrev_b32_e32 v204, 16, v205
	v_and_b32_e32 v205, 0xffff0000, v205
	v_lshlrev_b32_e32 v206, 16, v207
	v_and_b32_e32 v207, 0xffff0000, v207
	v_pk_fma_f32 v[124:125], v[124:125], v[218:219], v[222:223]
	v_pk_fma_f32 v[200:201], v[122:123], v[200:201], v[204:205]
	v_pk_fma_f32 v[204:205], v[120:121], v[216:217], v[220:221]
	v_pk_fma_f32 v[126:127], v[126:127], v[202:203], v[206:207]
	v_cvt_pk_bf16_f32 v122, v124, v125
	v_mul_f32_e32 v125, v125, v125
	v_add_f32_e32 v116, 1.0, v116
	v_add_f32_e32 v117, 1.0, v117
	v_add_f32_e32 v118, 1.0, v118
	v_add_f32_e32 v119, 1.0, v119
	v_cvt_pk_bf16_f32 v121, v200, v201
	v_mul_f32_e32 v202, v205, v205
	v_mul_f32_e32 v201, v201, v201
	v_fmac_f32_e32 v125, v124, v124
	v_mul_f32_e32 v124, v127, v127
	v_rcp_f32_e32 v116, v116
	v_rcp_f32_e32 v117, v117
	v_rcp_f32_e32 v118, v118
	v_rcp_f32_e32 v119, v119
	v_add_f32_e32 v112, 1.0, v112
	v_add_f32_e32 v113, 1.0, v113
	v_fmac_f32_e32 v202, v204, v204
	v_fmac_f32_e32 v201, v200, v200
	v_fmac_f32_e32 v124, v126, v126
	v_rcp_f32_e32 v112, v112
	v_rcp_f32_e32 v113, v113
	v_add_f32_e32 v114, 1.0, v114
	v_add_f32_e32 v115, 1.0, v115
	v_add_f32_e32 v200, v202, v201
	v_add_f32_e32 v124, v125, v124
	v_rcp_f32_e32 v114, v114
	v_rcp_f32_e32 v115, v115
	v_cvt_pk_bf16_f32 v120, v204, v205
	v_cvt_pk_bf16_f32 v123, v126, v127
	v_add_f32_e32 v216, v200, v124
	v_lshlrev_b32_e32 v124, 16, v212
	v_and_b32_e32 v125, 0xffff0000, v212
	v_lshlrev_b32_e32 v126, 16, v213
	v_and_b32_e32 v127, 0xffff0000, v213
	v_lshlrev_b32_e32 v204, 16, v208
	v_and_b32_e32 v205, 0xffff0000, v208
	v_lshlrev_b32_e32 v206, 16, v209
	v_and_b32_e32 v207, 0xffff0000, v209
	v_lshlrev_b32_e32 v200, 16, v214
	v_and_b32_e32 v201, 0xffff0000, v214
	v_lshlrev_b32_e32 v208, 16, v210
	v_and_b32_e32 v209, 0xffff0000, v210
	v_pk_fma_f32 v[118:119], v[118:119], v[126:127], v[206:207]
	v_pk_fma_f32 v[116:117], v[116:117], v[124:125], v[204:205]
	v_lshlrev_b32_e32 v202, 16, v215
	v_and_b32_e32 v203, 0xffff0000, v215
	v_lshlrev_b32_e32 v210, 16, v211
	v_and_b32_e32 v211, 0xffff0000, v211
	v_pk_fma_f32 v[126:127], v[112:113], v[200:201], v[208:209]
	v_mul_f32_e32 v112, v117, v117
	v_mul_f32_e32 v113, v119, v119
	v_pk_fma_f32 v[124:125], v[114:115], v[202:203], v[210:211]
	v_fmac_f32_e32 v112, v116, v116
	v_fmac_f32_e32 v113, v118, v118
	v_add_f32_e32 v112, v112, v113
	v_mul_f32_e32 v113, v127, v127
	v_mul_f32_e32 v114, v125, v125
	v_fmac_f32_e32 v113, v126, v126
	v_fmac_f32_e32 v114, v124, v124
	v_add_f32_e32 v113, v113, v114
	v_add_f32_e32 v112, v112, v113
	v_add_f32_e32 v115, v216, v112
	ds_bpermute_b32 v199, v245, v115
	v_lshl_add_u64 v[112:113], s[52:53], 0, v[184:185]
	v_lshl_add_u64 v[184:185], v[176:177], 1, v[112:113]
	v_cvt_pk_bf16_f32 v114, v116, v117
	v_cvt_pk_bf16_f32 v116, v126, v127
	s_waitcnt lgkmcnt(0)
	v_add_f32_e32 v112, v115, v199
	ds_bpermute_b32 v113, v244, v112
	v_cvt_pk_bf16_f32 v115, v118, v119
	v_cvt_pk_bf16_f32 v117, v124, v125
	global_store_dwordx4 v[184:185], v[120:123], off
	global_store_dwordx4 v[184:185], v[114:117], off offset:256
	s_and_saveexec_b64 s[70:71], s[16:17]
	s_cbranch_execz .LBB0_720
	s_waitcnt lgkmcnt(0)
	v_add_f32_e32 v112, v112, v113
	v_fma_f32 v112, v112, s25, 0.5
	v_cvt_u32_f32_e32 v114, v112
	v_lshl_add_u64 v[112:113], v[186:187], 2, s[54:55]
	global_atomic_add v[112:113], v114, off

; #define PG8_STAGE(bufoff, gbase, voff) do { _Pragma("unroll") for (int _i = 0; _i < 2; ++_i) \
;         __builtin_amdgcn_global_load_lds((const unsigned*)((const char*)(gbase) + (voff)[_i]), (LAS unsigned*)(lds + (bufoff) + ldsw + _i * 8192), 16, 0, 0); } while (0)
; #define PG8_WAIT_V(n) asm volatile("s_waitcnt vmcnt(" #n ")" ::: "memory")
; #define PG8_BAR __builtin_amdgcn_s_barrier()
; template <class Epi>
; __device__ __forceinline__ void gemm_phase(LAS unsigned char* lds, const Gemm g, const StaticOrder& S, const Epi& E, int wv) {
;     ...
;     for (int i = 0; i < 2; ++i) { int R, C; stage_rc(tid * 16 + i * 8192, R, C); const int Rb = Epi::PERM ? ((R & ~31) + perm32(R & 31)) : R;
;         voffA[i] = (unsigned)(R * g.lda + C) * 2u; voffB[i] = (unsigned)(Rb * g.ldb + C) * 2u; }
;     const bool krev = (g.adiag & 2) != 0;
;     const ptrdiff_t kstep = krev ? -(ptrdiff_t)(BK * 2) : (ptrdiff_t)(BK * 2);
;     const size_t kbeg = krev ? (size_t)(nt - 1) * (BK * 2) : 0;
;     const size_t hstepA = (size_t)HALF * g.lda * 2, hstepB = (size_t)HALF * g.ldb * 2;
;     const size_t tstepA = 2 * hstepA, tstepB = 2 * hstepB;
;     const unsigned ldsw = (unsigned)wid * 1024u;
;     const int aoff = lds_byte(wr * 64 + fr, fq * 8), boff = lds_byte(wc * 32 + fr, fq * 8);
;     ...
;     Unit cur, nxt; int ui = 0;
;     if (!S.next(0, cur)) return;
;     f32x4 acc[2][2][4][2];
; #pragma unroll
;     for (int a = 0; a < 2; ++a)
; #pragma unroll
;         for (int b = 0; b < 2; ++b)
; #pragma unroll
;             for (int m = 0; m < 4; ++m)
; #pragma unroll
;                 for (int n = 0; n < 2; ++n) acc[a][b][m][n] = (f32x4){0.f, 0.f, 0.f, 0.f};
;     bf16x8 At[4][2], B0[2][2], B1[2][2];
;     const char* cA = (const char*)g.A + (size_t)cur.pm * tstepA + ((g.adiag & 1) ? (size_t)(cur.pn >> 1) * K * 2 : 0) + kbeg;
;     const char* cB = (const char*)g.Bt + (size_t)cur.pn * tstepB + kbeg;
;     PG8_STAGE(PG8_SB(0, 0), cB, voffB); PG8_STAGE(PG8_SA(0, 0), cA, voffA); PG8_STAGE(PG8_SB(0, 1), cB + hstepB, voffB); PG8_STAGE(PG8_SA(0, 1), cA + hstepA, voffA);
;     if (wr == 1) PG8_BAR;
;     PG8_WAIT_V(4); PG8_BAR;
;     PG8_STAGE(PG8_SB(1, 0), cB + kstep, voffB); PG8_STAGE(PG8_SA(1, 0), cA + kstep, voffA); PG8_STAGE(PG8_SB(1, 1), cB + hstepB + kstep, voffB);
;     PG8_WAIT_V(6); PG8_BAR;
.LBB0_946:
	v_readlane_b32 s6, v255, 14
	v_readlane_b32 s7, v255, 15
	s_and_b64 vcc, exec, s[6:7]
	s_cbranch_vccnz .LBB0_994
	v_ashrrev_i32_e32 v2, 31, v0
	v_lshrrev_b32_e32 v2, 26, v2
	v_lshlrev_b32_e32 v1, 4, v0
	v_add_u32_e32 v2, v0, v2
	v_bfe_i32 v0, v0, 27, 1
	v_lshrrev_b32_e32 v0, 22, v0
	v_add_u32_e32 v0, v1, v0
	v_and_b32_e32 v0, 0xfffffc00, v0
	v_sub_u32_e32 v0, v1, v0
	v_ashrrev_i32_e32 v9, 6, v2
	v_lshrrev_b32_e32 v2, 4, v0
	v_bitop3_b32 v0, v2, v0, 32 bitop3:0x6c
	v_ashrrev_i32_e32 v3, 31, v0
	v_lshrrev_b32_e32 v3, 26, v3
	v_add_u32_e32 v3, v0, v3
	v_lshlrev_b32_e32 v2, 3, v9
	v_ashrrev_i32_e32 v10, 6, v3
	v_and_b32_e32 v3, 0xc0, v3
	v_and_b32_e32 v2, -16, v2
	v_sub_u32_e32 v0, v0, v3
	v_mov_b32_e32 v3, 1
	v_add_u32_e32 v2, v10, v2
	v_ashrrev_i16_sdwa v0, v3, sext(v0) dst_sel:DWORD dst_unused:UNUSED_PAD src0_sel:DWORD src1_sel:BYTE_0
	v_lshlrev_b32_e32 v4, 5, v9
	v_bfe_i32 v11, v0, 0, 16
	v_lshlrev_b32_e32 v0, 1, v2
	v_lshrrev_b32_e32 v5, 2, v2
	v_and_b32_e32 v6, 3, v10
	s_mov_b32 s11, 0xfffe0
	v_and_b32_e32 v4, 32, v4
	v_and_b32_e32 v0, 24, v0
	v_and_b32_e32 v5, 4, v5
	v_and_or_b32 v6, v2, s11, v6
	v_or3_b32 v0, v6, v5, v0
	v_add_lshl_u32 v4, v4, v11, 1
	v_lshl_add_u32 v130, v0, 12, v4
	v_add_u32_e32 v0, 0x2000, v1
	v_ashrrev_i32_e32 v1, 31, v0
	v_lshrrev_b32_e32 v1, 22, v1
	v_add_u32_e32 v1, v0, v1
	v_ashrrev_i32_e32 v12, 10, v1
	v_mul_i32_i24_e32 v1, 0x400, v12
	v_sub_u32_e32 v0, v0, v1
	v_lshrrev_b32_e32 v1, 4, v0
	v_bitop3_b32 v0, v1, v0, 32 bitop3:0x6c
	v_lshl_add_u32 v128, v2, 12, v4
	v_ashrrev_i32_e32 v2, 31, v0
	v_lshrrev_b32_e32 v2, 26, v2
	v_add_u32_e32 v2, v0, v2
	s_waitcnt lgkmcnt(0)
	s_add_u32 s5, s12, 0xb300000
	v_lshlrev_b32_e32 v1, 3, v12
	v_ashrrev_i32_e32 v13, 6, v2
	v_and_b32_e32 v2, 0xc0, v2
	s_addc_u32 s6, s13, 0
	v_and_b32_e32 v1, -16, v1
	v_sub_u32_e32 v0, v0, v2
	s_add_u32 s7, s16, 0x900000
	v_add_u32_e32 v1, v13, v1
	v_ashrrev_i16_sdwa v0, v3, sext(v0) dst_sel:DWORD dst_unused:UNUSED_PAD src0_sel:DWORD src1_sel:BYTE_0
	v_and_b32_e32 v3, 3, v13
	s_addc_u32 s22, s17, 0
	v_and_or_b32 v3, v1, s11, v3
	s_ashr_i32 s16, s4, 6
	s_ashr_i32 s47, s46, 31
	s_ashr_i32 s11, s10, 31
	s_ashr_i32 s18, s4, 8
	s_lshl_b32 s23, s16, 10
	s_lshl_b64 s[12:13], s[46:47], 20
	s_lshl_b64 s[24:25], s[10:11], 20
	s_add_u32 s48, s7, s24
	v_lshlrev_b32_e32 v4, 5, v12
	v_bfe_i32 v14, v0, 0, 16
	v_lshlrev_b32_e32 v0, 1, v1
	v_lshrrev_b32_e32 v2, 2, v1
	s_addc_u32 s49, s22, s25
	s_add_i32 s24, s23, 0
	v_and_b32_e32 v4, 32, v4
	v_and_b32_e32 v0, 24, v0
	v_and_b32_e32 v2, 4, v2
	s_add_i32 m0, s24, 0x10000
	v_or3_b32 v0, v3, v2, v0
	v_add_lshl_u32 v2, v4, v14, 1
	global_load_lds_dwordx4 v130, s[48:49]
	s_add_i32 m0, s24, 0x12000
	v_lshl_add_u32 v134, v0, 12, v2
	s_add_u32 s50, s5, s12
	global_load_lds_dwordx4 v134, s[48:49]
	s_addc_u32 s51, s6, s13
	s_mov_b32 m0, s24
	s_add_i32 s25, s24, 0x2000
	v_lshl_add_u32 v132, v1, 12, v2
	global_load_lds_dwordx4 v128, s[50:51]
	s_mov_b32 m0, s25
	s_add_u32 s12, s48, 0x80000
	global_load_lds_dwordx4 v132, s[50:51]
	s_addc_u32 s13, s49, 0
	s_add_i32 m0, s24, 0x14000
	v_mov_b32_e32 v131, 0
	global_load_lds_dwordx4 v130, s[12:13]
	s_add_i32 m0, s24, 0x16000
	v_mov_b32_e32 v135, v131
	global_load_lds_dwordx4 v134, s[12:13]
	s_add_u32 s12, s50, 0x80000
	s_addc_u32 s13, s51, 0
	s_add_i32 s33, s24, 0x4000
	s_mov_b32 m0, s33
	s_add_i32 s54, s24, 0x6000
	global_load_lds_dwordx4 v128, s[12:13]
	s_mov_b32 m0, s54
	v_mov_b32_e32 v129, v131
	global_load_lds_dwordx4 v132, s[12:13]
	v_mov_b32_e32 v133, v131
	s_mov_b32 s55, 0
	v_lshl_add_u64 v[6:7], s[48:49], 0, v[130:131]
	v_lshl_add_u64 v[4:5], s[48:49], 0, v[134:135]
	v_lshl_add_u64 v[2:3], s[50:51], 0, v[128:129]
	v_lshl_add_u64 v[0:1], s[50:51], 0, v[132:133]
	s_cmp_lg_u32 s18, 1
	s_mov_b64 s[12:13], 0x80000
	s_cbranch_scc1 .LBB0_949
	s_barrier
	s_setprio 1

; #define PG8_STAGE(bufoff, gbase, voff) do { _Pragma("unroll") for (int _i = 0; _i < 2; ++_i) \
;         __builtin_amdgcn_global_load_lds((const unsigned*)((const char*)(gbase) + (voff)[_i]), (LAS unsigned*)(lds + (bufoff) + ldsw + _i * 8192), 16, 0, 0); } while (0)
; #define PG8_LDA(dst, b, h) do { _Pragma("unroll") for (int m = 0; m < 4; ++m) _Pragma("unroll") for (int k = 0; k < 2; ++k) dst[m][k] = *(const LAS bf16x8*)(lds + PG8_SA(b, h) + aoff + m * 2048 + k * 1024); } while (0)
; #define PG8_LDB(dst, b, h) do { _Pragma("unroll") for (int n = 0; n < 2; ++n) _Pragma("unroll") for (int k = 0; k < 2; ++k) dst[n][k] = *(const LAS bf16x8*)(lds + PG8_SB(b, h) + boff + n * 2048 + k * 1024); } while (0)
; #define PG8_MMA(ai, bj, At, Bt) do { __builtin_amdgcn_s_setprio(1); _Pragma("unroll") for (int m = 0; m < 4; ++m) _Pragma("unroll") for (int n = 0; n < 2; ++n) _Pragma("unroll") for (int k = 0; k < 2; ++k) \
;         acc[ai][bj][m][n] = __builtin_amdgcn_mfma_f32_16x16x32_bf16(Bt[n][k], At[m][k], acc[ai][bj][m][n], 0, 0, 0); __builtin_amdgcn_s_setprio(0); } while (0)
; #define PG8_WAIT_V(n) asm volatile("s_waitcnt vmcnt(" #n ")" ::: "memory")
; #define PG8_WAIT_L(n) asm volatile("s_waitcnt lgkmcnt(" #n ")" ::: "memory")
; #define PG8_BAR __builtin_amdgcn_s_barrier()
; template <class Epi>
; __device__ __forceinline__ void gemm_phase(LAS unsigned char* lds, const Gemm g, const StaticOrder& S, const Epi& E, int wv) {
;     ...
;             const bool last = (t == nt - 2);
;             const char* a1 = cA + (ptrdiff_t)(t + 1) * kstep;
;             const char* a2 = last ? nA : cA + (ptrdiff_t)(t + 2) * kstep; const char* b2 = last ? nB : cB + (ptrdiff_t)(t + 2) * kstep;
;             const char* a3 = a2 + kstep; const char* b3 = b2 + kstep;
;             PG8_LDB(B0, 0, 0); PG8_SCHED; PG8_LDA(At, 0, 0); PG8_STAGE(PG8_SA(1, 1), a1 + hstepA, voffA);
;             PG8_WAIT_L(8); PG8_BAR; PG8_WAIT_L(0); PG8_MMA(0, 0, At, B0); PG8_BAR; PG8_SCHED;
;             PG8_LDB(B1, 0, 1); PG8_STAGE(PG8_SB(0, 0), b2, voffB);
;             PG8_BAR; PG8_WAIT_L(0); PG8_MMA(0, 1, At, B1); PG8_BAR;
;             PG8_LDA(At, 0, 1); PG8_STAGE(PG8_SA(0, 0), a2, voffA);
;             PG8_BAR; PG8_WAIT_L(0); PG8_MMA(1, 0, At, B0); PG8_BAR; PG8_SCHED;
;             PG8_STAGE(PG8_SB(0, 1), b2 + hstepB, voffB);
;             PG8_WAIT_V(6); PG8_BAR; PG8_MMA(1, 1, At, B1); PG8_BAR;
.LBB0_958:
	s_add_u32 s50, s48, 0xfff80080
	s_addc_u32 s51, s49, -1
	s_cmp_eq_u32 s70, 28
	s_cselect_b32 s53, s11, s51
	s_cselect_b32 s52, s41, s50
	s_cselect_b32 s51, s39, s69
	s_cselect_b32 s50, s47, s68
	s_add_i32 m0, s24, 0xc000
	ds_read_b128 v[168:171], v156
	ds_read_b128 v[172:175], v156 offset:1024
	ds_read_b128 v[176:179], v156 offset:2048
	ds_read_b128 v[180:183], v156 offset:3072
	ds_read_b128 v[184:187], v156 offset:4096
	ds_read_b128 v[188:191], v156 offset:5120
	ds_read_b128 v[192:195], v156 offset:6144
	ds_read_b128 v[196:199], v156 offset:7168
	global_load_lds_dwordx4 v138, s[48:49]
	s_add_i32 m0, s24, 0xe000
	s_nop 0
	global_load_lds_dwordx4 v136, s[48:49]
	s_waitcnt lgkmcnt(8)
	s_barrier
	s_waitcnt lgkmcnt(0)
	s_waitcnt lgkmcnt(0)
	v_mfma_f32_16x16x32_bf16 v[124:127], v[144:147], v[168:171], v[124:127]
	v_mfma_f32_16x16x32_bf16 v[120:123], v[160:163], v[168:171], v[120:123]
	v_mfma_f32_16x16x32_bf16 v[108:111], v[144:147], v[176:179], v[108:111]
	v_mfma_f32_16x16x32_bf16 v[104:107], v[160:163], v[176:179], v[104:107]
	v_mfma_f32_16x16x32_bf16 v[92:95], v[144:147], v[184:187], v[92:95]
	v_mfma_f32_16x16x32_bf16 v[88:91], v[160:163], v[184:187], v[88:91]
	v_mfma_f32_16x16x32_bf16 v[76:79], v[144:147], v[192:195], v[76:79]
	v_mfma_f32_16x16x32_bf16 v[72:75], v[160:163], v[192:195], v[72:75]
	v_mfma_f32_16x16x32_bf16 v[124:127], v[148:151], v[172:175], v[124:127]
	v_mfma_f32_16x16x32_bf16 v[120:123], v[164:167], v[172:175], v[120:123]
	v_mfma_f32_16x16x32_bf16 v[108:111], v[148:151], v[180:183], v[108:111]
	v_mfma_f32_16x16x32_bf16 v[104:107], v[164:167], v[180:183], v[104:107]
	v_mfma_f32_16x16x32_bf16 v[92:95], v[148:151], v[188:191], v[92:95]
	v_mfma_f32_16x16x32_bf16 v[88:91], v[164:167], v[188:191], v[88:91]
	v_mfma_f32_16x16x32_bf16 v[76:79], v[148:151], v[196:199], v[76:79]
	v_mfma_f32_16x16x32_bf16 v[72:75], v[164:167], v[196:199], v[72:75]
	s_barrier
	s_add_i32 s71, s60, s23
	s_add_u32 s98, s50, s16
	s_addc_u32 s99, s51, s17
	s_mov_b32 m0, s71
	ds_read_b128 v[200:203], v157
	ds_read_b128 v[204:207], v157 offset:1024
	ds_read_b128 v[208:211], v157 offset:2048
	ds_read_b128 v[212:215], v157 offset:3072
	global_load_lds_dwordx4 v130, s[50:51]
	s_add_i32 m0, s71, 0x2000
	s_nop 0
	global_load_lds_dwordx4 v134, s[50:51]
	s_barrier
	s_waitcnt lgkmcnt(0)
	s_waitcnt lgkmcnt(0)
	v_mfma_f32_16x16x32_bf16 v[116:119], v[200:203], v[168:171], v[116:119]
	v_mfma_f32_16x16x32_bf16 v[112:115], v[208:211], v[168:171], v[112:115]
	v_mfma_f32_16x16x32_bf16 v[100:103], v[200:203], v[176:179], v[100:103]
	v_mfma_f32_16x16x32_bf16 v[96:99], v[208:211], v[176:179], v[96:99]
	v_mfma_f32_16x16x32_bf16 v[84:87], v[200:203], v[184:187], v[84:87]
	v_mfma_f32_16x16x32_bf16 v[80:83], v[208:211], v[184:187], v[80:83]
	v_mfma_f32_16x16x32_bf16 v[68:71], v[200:203], v[192:195], v[68:71]
	v_mfma_f32_16x16x32_bf16 v[64:67], v[208:211], v[192:195], v[64:67]
	v_mfma_f32_16x16x32_bf16 v[116:119], v[204:207], v[172:175], v[116:119]
	v_mfma_f32_16x16x32_bf16 v[112:115], v[212:215], v[172:175], v[112:115]
	v_mfma_f32_16x16x32_bf16 v[100:103], v[204:207], v[180:183], v[100:103]
	v_mfma_f32_16x16x32_bf16 v[96:99], v[212:215], v[180:183], v[96:99]
	v_mfma_f32_16x16x32_bf16 v[84:87], v[204:207], v[188:191], v[84:87]
	v_mfma_f32_16x16x32_bf16 v[80:83], v[212:215], v[188:191], v[80:83]
	v_mfma_f32_16x16x32_bf16 v[68:71], v[204:207], v[196:199], v[68:71]
	v_mfma_f32_16x16x32_bf16 v[64:67], v[212:215], v[196:199], v[64:67]
	s_mov_b32 m0, s24
	s_add_u32 s100, s52, s16
	s_addc_u32 s101, s53, s17
	s_barrier
	ds_read_b128 v[168:171], v156 offset:16384
	ds_read_b128 v[172:175], v156 offset:17408
	ds_read_b128 v[176:179], v156 offset:18432
	ds_read_b128 v[180:183], v156 offset:19456
	ds_read_b128 v[184:187], v156 offset:20480
	ds_read_b128 v[188:191], v156 offset:21504
	ds_read_b128 v[192:195], v156 offset:22528
	ds_read_b128 v[196:199], v156 offset:23552
	global_load_lds_dwordx4 v128, s[52:53]
	s_mov_b32 m0, s25
	s_nop 0
	global_load_lds_dwordx4 v132, s[52:53]
	s_waitcnt vmcnt(10)
	s_barrier
	s_waitcnt lgkmcnt(0)
	s_waitcnt lgkmcnt(0)
	v_mfma_f32_16x16x32_bf16 v[60:63], v[144:147], v[168:171], v[60:63]
	v_mfma_f32_16x16x32_bf16 v[56:59], v[160:163], v[168:171], v[56:59]
	v_mfma_f32_16x16x32_bf16 v[44:47], v[144:147], v[176:179], v[44:47]
	v_mfma_f32_16x16x32_bf16 v[40:43], v[160:163], v[176:179], v[40:43]
	v_mfma_f32_16x16x32_bf16 v[28:31], v[144:147], v[184:187], v[28:31]
	v_mfma_f32_16x16x32_bf16 v[24:27], v[160:163], v[184:187], v[24:27]
	v_mfma_f32_16x16x32_bf16 v[12:15], v[144:147], v[192:195], v[12:15]
	v_mfma_f32_16x16x32_bf16 v[8:11], v[160:163], v[192:195], v[8:11]
	v_mfma_f32_16x16x32_bf16 v[60:63], v[148:151], v[172:175], v[60:63]
	v_mfma_f32_16x16x32_bf16 v[56:59], v[164:167], v[172:175], v[56:59]
	v_mfma_f32_16x16x32_bf16 v[44:47], v[148:151], v[180:183], v[44:47]
	v_mfma_f32_16x16x32_bf16 v[40:43], v[164:167], v[180:183], v[40:43]
	v_mfma_f32_16x16x32_bf16 v[28:31], v[148:151], v[188:191], v[28:31]
	v_mfma_f32_16x16x32_bf16 v[24:27], v[164:167], v[188:191], v[24:27]
	v_mfma_f32_16x16x32_bf16 v[12:15], v[148:151], v[196:199], v[12:15]
	v_mfma_f32_16x16x32_bf16 v[8:11], v[164:167], v[196:199], v[8:11]
	s_barrier
	s_add_u32 s72, s50, 0x80000
	s_addc_u32 s73, s51, 0
	s_add_i32 s71, s61, s23
	s_mov_b32 m0, s71
	s_nop 0
	global_load_lds_dwordx4 v130, s[72:73]
	s_add_i32 m0, s71, 0x2000
	s_nop 0
	global_load_lds_dwordx4 v134, s[72:73]
	s_add_i32 s71, 0, 0x18000
	v_add_u32_e32 v159, s71, v153
	ds_read_b128 v[144:147], v159
	ds_read_b128 v[148:151], v159 offset:1024
	ds_read_b128 v[160:163], v159 offset:2048
	ds_read_b128 v[164:167], v159 offset:3072
	s_waitcnt vmcnt(6)
	s_barrier
; #define PG8_STAGE(bufoff, gbase, voff) do { _Pragma("unroll") for (int _i = 0; _i < 2; ++_i) \
;         __builtin_amdgcn_global_load_lds((const unsigned*)((const char*)(gbase) + (voff)[_i]), (LAS unsigned*)(lds + (bufoff) + ldsw + _i * 8192), 16, 0, 0); } while (0)
; #define PG8_LDA(dst, b, h) do { _Pragma("unroll") for (int m = 0; m < 4; ++m) _Pragma("unroll") for (int k = 0; k < 2; ++k) dst[m][k] = *(const LAS bf16x8*)(lds + PG8_SA(b, h) + aoff + m * 2048 + k * 1024); } while (0)
; #define PG8_LDB(dst, b, h) do { _Pragma("unroll") for (int n = 0; n < 2; ++n) _Pragma("unroll") for (int k = 0; k < 2; ++k) dst[n][k] = *(const LAS bf16x8*)(lds + PG8_SB(b, h) + boff + n * 2048 + k * 1024); } while (0)
; #define PG8_MMA(ai, bj, At, Bt) do { __builtin_amdgcn_s_setprio(1); _Pragma("unroll") for (int m = 0; m < 4; ++m) _Pragma("unroll") for (int n = 0; n < 2; ++n) _Pragma("unroll") for (int k = 0; k < 2; ++k) \
;         acc[ai][bj][m][n] = __builtin_amdgcn_mfma_f32_16x16x32_bf16(Bt[n][k], At[m][k], acc[ai][bj][m][n], 0, 0, 0); __builtin_amdgcn_s_setprio(0); } while (0)
; #define PG8_WAIT_V(n) asm volatile("s_waitcnt vmcnt(" #n ")" ::: "memory")
; #define PG8_WAIT_L(n) asm volatile("s_waitcnt lgkmcnt(" #n ")" ::: "memory")
; #define PG8_BAR __builtin_amdgcn_s_barrier()
; #define PG8_SCHED __builtin_amdgcn_sched_barrier(0)
; template <class Epi>
; __device__ __forceinline__ void gemm_phase(LAS unsigned char* lds, const Gemm g, const StaticOrder& S, const Epi& E, int wv) {
;     ...
;             PG8_WAIT_V(6); PG8_BAR; PG8_MMA(1, 1, At, B1); PG8_BAR;
;             PG8_LDB(B0, 1, 0); PG8_SCHED; PG8_LDA(At, 1, 0); PG8_STAGE(PG8_SA(0, 1), a2 + hstepA, voffA);
;             PG8_WAIT_L(8); PG8_BAR; PG8_WAIT_L(0); PG8_MMA(0, 0, At, B0); PG8_BAR; PG8_SCHED;
;             PG8_LDB(B1, 1, 1); PG8_STAGE(PG8_SB(1, 0), b3, voffB);
;             PG8_BAR; PG8_WAIT_L(0); PG8_MMA(0, 1, At, B1); PG8_BAR;
;             PG8_LDA(At, 1, 1); PG8_STAGE(PG8_SA(1, 0), a3, voffA);
;             PG8_BAR; PG8_WAIT_L(0); PG8_MMA(1, 0, At, B0); PG8_BAR; PG8_SCHED;
	v_mfma_f32_16x16x32_bf16 v[52:55], v[200:203], v[168:171], v[52:55]
	v_mfma_f32_16x16x32_bf16 v[48:51], v[208:211], v[168:171], v[48:51]
	v_mfma_f32_16x16x32_bf16 v[36:39], v[200:203], v[176:179], v[36:39]
	v_mfma_f32_16x16x32_bf16 v[32:35], v[208:211], v[176:179], v[32:35]
	v_mfma_f32_16x16x32_bf16 v[20:23], v[200:203], v[184:187], v[20:23]
	v_mfma_f32_16x16x32_bf16 v[16:19], v[208:211], v[184:187], v[16:19]
	v_mfma_f32_16x16x32_bf16 v[4:7], v[200:203], v[192:195], v[4:7]
	v_mfma_f32_16x16x32_bf16 v[0:3], v[208:211], v[192:195], v[0:3]
	v_mfma_f32_16x16x32_bf16 v[52:55], v[204:207], v[172:175], v[52:55]
	v_mfma_f32_16x16x32_bf16 v[48:51], v[212:215], v[172:175], v[48:51]
	v_mfma_f32_16x16x32_bf16 v[36:39], v[204:207], v[180:183], v[36:39]
	v_mfma_f32_16x16x32_bf16 v[32:35], v[212:215], v[180:183], v[32:35]
	v_mfma_f32_16x16x32_bf16 v[20:23], v[204:207], v[188:191], v[20:23]
	v_mfma_f32_16x16x32_bf16 v[16:19], v[212:215], v[188:191], v[16:19]
	v_mfma_f32_16x16x32_bf16 v[4:7], v[204:207], v[196:199], v[4:7]
	v_mfma_f32_16x16x32_bf16 v[0:3], v[212:215], v[196:199], v[0:3]
	s_waitcnt lgkmcnt(0)
	s_barrier
	s_add_u32 s52, s52, 0x80000
	s_addc_u32 s53, s53, 0
	s_mov_b32 m0, s33
	ds_read_b128 v[168:171], v156 offset:32768
	ds_read_b128 v[172:175], v156 offset:33792
	ds_read_b128 v[176:179], v156 offset:34816
	ds_read_b128 v[180:183], v156 offset:35840
	ds_read_b128 v[184:187], v156 offset:36864
	ds_read_b128 v[188:191], v156 offset:37888
	ds_read_b128 v[192:195], v156 offset:38912
	ds_read_b128 v[196:199], v156 offset:39936
	global_load_lds_dwordx4 v128, s[52:53]
	s_mov_b32 m0, s54
	s_nop 0
	global_load_lds_dwordx4 v132, s[52:53]
	s_waitcnt lgkmcnt(8)
	s_barrier
	s_waitcnt lgkmcnt(0)
	s_waitcnt lgkmcnt(0)
	v_mfma_f32_16x16x32_bf16 v[124:127], v[144:147], v[168:171], v[124:127]
	v_mfma_f32_16x16x32_bf16 v[120:123], v[160:163], v[168:171], v[120:123]
	v_mfma_f32_16x16x32_bf16 v[108:111], v[144:147], v[176:179], v[108:111]
	v_mfma_f32_16x16x32_bf16 v[104:107], v[160:163], v[176:179], v[104:107]
	v_mfma_f32_16x16x32_bf16 v[92:95], v[144:147], v[184:187], v[92:95]
	v_mfma_f32_16x16x32_bf16 v[88:91], v[160:163], v[184:187], v[88:91]
	v_mfma_f32_16x16x32_bf16 v[76:79], v[144:147], v[192:195], v[76:79]
	v_mfma_f32_16x16x32_bf16 v[72:75], v[160:163], v[192:195], v[72:75]
	v_mfma_f32_16x16x32_bf16 v[124:127], v[148:151], v[172:175], v[124:127]
	v_mfma_f32_16x16x32_bf16 v[120:123], v[164:167], v[172:175], v[120:123]
	v_mfma_f32_16x16x32_bf16 v[108:111], v[148:151], v[180:183], v[108:111]
	v_mfma_f32_16x16x32_bf16 v[104:107], v[164:167], v[180:183], v[104:107]
	v_mfma_f32_16x16x32_bf16 v[92:95], v[148:151], v[188:191], v[92:95]
	v_mfma_f32_16x16x32_bf16 v[88:91], v[164:167], v[188:191], v[88:91]
	v_mfma_f32_16x16x32_bf16 v[76:79], v[148:151], v[196:199], v[76:79]
	v_mfma_f32_16x16x32_bf16 v[72:75], v[164:167], v[196:199], v[72:75]
	s_barrier
	s_add_i32 s52, 0, 0x1c000
	s_add_i32 s53, s71, s23
	v_add_u32_e32 v159, s52, v153
	s_mov_b32 m0, s53
	ds_read_b128 v[200:203], v159
	ds_read_b128 v[204:207], v159 offset:1024
	ds_read_b128 v[208:211], v159 offset:2048
	ds_read_b128 v[212:215], v159 offset:3072
	global_load_lds_dwordx4 v130, s[98:99]
	s_add_i32 m0, s53, 0x2000
	s_nop 0
	global_load_lds_dwordx4 v134, s[98:99]
	s_barrier
	s_waitcnt lgkmcnt(0)
	s_waitcnt lgkmcnt(0)
	v_mfma_f32_16x16x32_bf16 v[116:119], v[200:203], v[168:171], v[116:119]
	v_mfma_f32_16x16x32_bf16 v[112:115], v[208:211], v[168:171], v[112:115]
	v_mfma_f32_16x16x32_bf16 v[100:103], v[200:203], v[176:179], v[100:103]
	v_mfma_f32_16x16x32_bf16 v[96:99], v[208:211], v[176:179], v[96:99]
	v_mfma_f32_16x16x32_bf16 v[84:87], v[200:203], v[184:187], v[84:87]
	v_mfma_f32_16x16x32_bf16 v[80:83], v[208:211], v[184:187], v[80:83]
	v_mfma_f32_16x16x32_bf16 v[68:71], v[200:203], v[192:195], v[68:71]
	v_mfma_f32_16x16x32_bf16 v[64:67], v[208:211], v[192:195], v[64:67]
	v_mfma_f32_16x16x32_bf16 v[116:119], v[204:207], v[172:175], v[116:119]
	v_mfma_f32_16x16x32_bf16 v[112:115], v[212:215], v[172:175], v[112:115]
	v_mfma_f32_16x16x32_bf16 v[100:103], v[204:207], v[180:183], v[100:103]
	v_mfma_f32_16x16x32_bf16 v[96:99], v[212:215], v[180:183], v[96:99]
	v_mfma_f32_16x16x32_bf16 v[84:87], v[204:207], v[188:191], v[84:87]
	v_mfma_f32_16x16x32_bf16 v[80:83], v[212:215], v[188:191], v[80:83]
	v_mfma_f32_16x16x32_bf16 v[68:71], v[204:207], v[196:199], v[68:71]
	v_mfma_f32_16x16x32_bf16 v[64:67], v[212:215], v[196:199], v[64:67]
	s_mov_b32 m0, s58
	s_barrier
	ds_read_b128 v[168:171], v156 offset:49152
	ds_read_b128 v[172:175], v156 offset:50176
	ds_read_b128 v[176:179], v156 offset:51200
	ds_read_b128 v[180:183], v156 offset:52224
	ds_read_b128 v[184:187], v156 offset:53248
	ds_read_b128 v[188:191], v156 offset:54272
	ds_read_b128 v[192:195], v156 offset:55296
	ds_read_b128 v[196:199], v156 offset:56320
	global_load_lds_dwordx4 v128, s[100:101]
	s_mov_b32 m0, s59
	s_nop 0
	global_load_lds_dwordx4 v132, s[100:101]
	s_waitcnt vmcnt(10)
	s_barrier
	s_waitcnt lgkmcnt(0)
	s_waitcnt lgkmcnt(0)
	v_mfma_f32_16x16x32_bf16 v[60:63], v[144:147], v[168:171], v[60:63]
	v_mfma_f32_16x16x32_bf16 v[56:59], v[160:163], v[168:171], v[56:59]
	v_mfma_f32_16x16x32_bf16 v[44:47], v[144:147], v[176:179], v[44:47]
	v_mfma_f32_16x16x32_bf16 v[40:43], v[160:163], v[176:179], v[40:43]
	v_mfma_f32_16x16x32_bf16 v[28:31], v[144:147], v[184:187], v[28:31]
	v_mfma_f32_16x16x32_bf16 v[24:27], v[160:163], v[184:187], v[24:27]
	v_mfma_f32_16x16x32_bf16 v[12:15], v[144:147], v[192:195], v[12:15]
	v_mfma_f32_16x16x32_bf16 v[8:11], v[160:163], v[192:195], v[8:11]
	v_mfma_f32_16x16x32_bf16 v[60:63], v[148:151], v[172:175], v[60:63]
	v_mfma_f32_16x16x32_bf16 v[56:59], v[164:167], v[172:175], v[56:59]
	v_mfma_f32_16x16x32_bf16 v[44:47], v[148:151], v[180:183], v[44:47]
	v_mfma_f32_16x16x32_bf16 v[40:43], v[164:167], v[180:183], v[40:43]
	v_mfma_f32_16x16x32_bf16 v[28:31], v[148:151], v[188:191], v[28:31]
	v_mfma_f32_16x16x32_bf16 v[24:27], v[164:167], v[188:191], v[24:27]
	v_mfma_f32_16x16x32_bf16 v[12:15], v[148:151], v[196:199], v[12:15]
	v_mfma_f32_16x16x32_bf16 v[8:11], v[164:167], v[196:199], v[8:11]
	s_barrier
; template <class Epi>
; __device__ __forceinline__ void gemm_phase(LAS unsigned char* lds, const Gemm g, const StaticOrder& S, const Epi& E, int wv) {
;     ...
;             PG8_WAIT_V(6); PG8_BAR; PG8_MMA(1, 1, At, B1); PG8_BAR;
;         }
;     __device__ __forceinline__ void operator()(const f32x4 (&acc)[2][2][4][2], const Unit& u, int wr, int wc, int fr, int fq) const {
;         const int row0 = u.pm * BM + wr * 64 + fr; int colt = u.pn * BM; bf16_t* base = O; int tsel = 0;
;         if (split_cols) { tsel = colt / split_cols; base += (size_t)tsel * split_stride; colt -= tsel * split_cols; }
;         const int col0 = colt + wc * 32 + 8 * fq;
;         f32x4 cs[2][2];
;         if (SM == 2) {
; #pragma unroll
;             for (int bj = 0; bj < 2; ++bj)
; #pragma unroll
;                 for (int n = 0; n < 2; ++n) { const f32x4 s = *(const f32x4*)(ss + u.pn * BM + wc * 32 + 8 * fq + bj * HALF + 4 * n);
; #pragma unroll
;                     for (int j = 0; j < 4; ++j) cs[bj][n][j] = __builtin_amdgcn_rsqf(ss_fix(s[j]) * (1.0f / DM) + EPS); }
;         }
;         float rsv[8];
; #pragma unroll
;         for (int it = 0; it < 8; ++it) rsv[it] = (SM == 1) ? ss[row0 + (it >> 2) * HALF + (it & 3) * 16] : 1.0f;
; #pragma unroll
;         for (int ai = 0; ai < 2; ++ai)
; #pragma unroll
;             for (int m = 0; m < 4; ++m) { const int row = row0 + ai * HALF + m * 16; float rs = 1.0f; if (SM == 1) rs = __builtin_amdgcn_rsqf(ss_fix(rsv[ai * 4 + m]) * (1.0f / DM) + EPS);
;                 bf16_t* rowp = base + (size_t)row * ldc + col0;
; #pragma unroll
;                 for (int bj = 0; bj < 2; ++bj) { f32x4 v0 = acc[ai][bj][m][0], v1 = acc[ai][bj][m][1];
;                     if (SM == 1) { v0 *= rs; v1 *= rs; }
;                     if (SM == 2) { v0 *= cs[bj][0]; v1 *= cs[bj][1]; }
;                     if (ACT == 1) {
; #pragma unroll
;                         for (int j = 0; j < 4; ++j) { const float a = fmaxf(v0[j], 0.f), b = fmaxf(v1[j], 0.f); v0[j] = a * a; v1[j] = b * b; } }
;                     if (ACT == 2) { if (tsel == 0) {
; #pragma unroll
;                         for (int j = 0; j < 4; ++j) { const float a = v0[j], b = v1[j];
;                             v0[j] = a * fast_sigmoid(1.5957691216057308f * (a + 0.044715f * a * a * a)); v1[j] = b * fast_sigmoid(1.5957691216057308f * (b + 0.044715f * b * b * b)); } } }
	s_add_u32 s50, s50, 0x80080
	s_addc_u32 s51, s51, 0
	s_add_i32 s52, s52, s23
	s_mov_b32 m0, s52
	s_nop 0
	global_load_lds_dwordx4 v130, s[50:51]
	s_add_i32 m0, s52, 0x2000
	s_nop 0
	global_load_lds_dwordx4 v134, s[50:51]
	ds_read_b128 v[144:147], v155
	ds_read_b128 v[148:151], v155 offset:1024
	ds_read_b128 v[160:163], v155 offset:2048
	ds_read_b128 v[164:167], v155 offset:3072
	s_waitcnt vmcnt(6)
	s_barrier
	v_mfma_f32_16x16x32_bf16 v[52:55], v[200:203], v[168:171], v[52:55]
	v_mfma_f32_16x16x32_bf16 v[48:51], v[208:211], v[168:171], v[48:51]
	v_mfma_f32_16x16x32_bf16 v[36:39], v[200:203], v[176:179], v[36:39]
	v_mfma_f32_16x16x32_bf16 v[32:35], v[208:211], v[176:179], v[32:35]
	v_mfma_f32_16x16x32_bf16 v[20:23], v[200:203], v[184:187], v[20:23]
	v_mfma_f32_16x16x32_bf16 v[16:19], v[208:211], v[184:187], v[16:19]
	v_mfma_f32_16x16x32_bf16 v[4:7], v[200:203], v[192:195], v[4:7]
	v_mfma_f32_16x16x32_bf16 v[0:3], v[208:211], v[192:195], v[0:3]
	v_mfma_f32_16x16x32_bf16 v[52:55], v[204:207], v[172:175], v[52:55]
	v_mfma_f32_16x16x32_bf16 v[48:51], v[212:215], v[172:175], v[48:51]
	v_mfma_f32_16x16x32_bf16 v[36:39], v[204:207], v[180:183], v[36:39]
	v_mfma_f32_16x16x32_bf16 v[32:35], v[212:215], v[180:183], v[32:35]
	v_mfma_f32_16x16x32_bf16 v[20:23], v[204:207], v[188:191], v[20:23]
	v_mfma_f32_16x16x32_bf16 v[16:19], v[212:215], v[188:191], v[16:19]
	v_mfma_f32_16x16x32_bf16 v[4:7], v[204:207], v[196:199], v[4:7]
	v_mfma_f32_16x16x32_bf16 v[0:3], v[212:215], v[196:199], v[0:3]
	s_waitcnt lgkmcnt(0)
	s_add_i32 s70, s70, 2
	s_add_u32 s68, s68, 0x100
	s_addc_u32 s69, s69, 0
	s_add_u32 s48, s48, 0x100
	s_addc_u32 s49, s49, 0
	s_cmp_gt_u32 s70, 29
	s_barrier
	s_cbranch_scc0 .LBB0_958
	v_lshl_add_u32 v144, s46, 8, v152
	v_ashrrev_i32_e32 v145, 31, v144
	v_lshl_add_u64 v[146:147], v[144:145], 2, s[14:15]
	global_load_dword v148, v[146:147], off
	global_load_dword v165, v[146:147], off offset:64
	global_load_dword v164, v[146:147], off offset:128
	global_load_dword v163, v[146:147], off offset:192
	global_load_dword v162, v[146:147], off offset:512
	global_load_dword v161, v[146:147], off offset:576
	global_load_dword v160, v[146:147], off offset:640
	global_load_dword v159, v[146:147], off offset:704
	s_add_i32 s11, s10, 7
	s_cmp_lt_u32 s11, 15
	s_cselect_b64 s[46:47], -1, 0
	s_cmp_gt_u32 s11, 14
	s_waitcnt vmcnt(0)
	v_cvt_f32_u32_e32 v146, v148
	v_mul_f32_e32 v146, 0x3b800000, v146
	v_fmamk_f32 v146, v146, 0x3a000000, v158
	v_rsq_f32_e32 v146, v146
	s_nop 0
	v_pk_mul_f32 v[126:127], v[126:127], v[146:147] op_sel_hi:[1,0]
	v_pk_mul_f32 v[124:125], v[124:125], v[146:147] op_sel_hi:[1,0]
	v_pk_mul_f32 v[148:149], v[122:123], v[146:147] op_sel_hi:[1,0]
	v_pk_mul_f32 v[150:151], v[120:121], v[146:147] op_sel_hi:[1,0]
	s_cbranch_scc1 .LBB0_961
	v_mul_f32_e32 v121, 0x3d372713, v150
	v_mul_f32_e32 v121, v150, v121
	v_mul_f32_e32 v122, 0x3d372713, v125
	v_fma_f32 v121, v150, v121, v150
	v_mul_f32_e32 v122, v125, v122
	v_mov_b32_e32 v123, v125
	v_mul_f32_e32 v121, 0x3fcc422a, v121
	v_fmac_f32_e32 v123, v123, v122
	v_mul_f32_e32 v121, 0xbfb8aa3b, v121
	v_mul_f32_e32 v122, 0x3fcc422a, v123
	v_exp_f32_e32 v121, v121
	v_mul_f32_e32 v122, 0xbfb8aa3b, v122
	v_exp_f32_e32 v123, v122
	v_mov_b32_e32 v147, v151
	v_add_f32_e32 v121, 1.0, v121
	v_rcp_f32_e32 v122, v121
	v_add_f32_e32 v121, 1.0, v123
	v_mul_f32_e32 v123, 0x3d372713, v151
	v_mul_f32_e32 v123, v151, v123
	v_fmac_f32_e32 v147, v147, v123
	v_mul_f32_e32 v123, 0x3fcc422a, v147
	v_mul_f32_e32 v147, 0x3d372713, v126
	v_mul_f32_e32 v147, v126, v147
	v_mul_f32_e32 v166, 0x3d372713, v148
	v_fma_f32 v147, v126, v147, v126
	v_mul_f32_e32 v166, v148, v166
	v_mul_f32_e32 v147, 0x3fcc422a, v147
	v_fma_f32 v166, v148, v166, v148
	v_mul_f32_e32 v147, 0xbfb8aa3b, v147
	v_mul_f32_e32 v166, 0x3fcc422a, v166
	v_exp_f32_e32 v147, v147
	v_mul_f32_e32 v166, 0xbfb8aa3b, v166
	v_exp_f32_e32 v167, v166
	v_mul_f32_e32 v120, 0x3d372713, v124
	v_add_f32_e32 v147, 1.0, v147
	v_rcp_f32_e32 v166, v147
	v_add_f32_e32 v147, 1.0, v167
	v_mul_f32_e32 v167, 0x3d372713, v127
	v_mul_f32_e32 v167, v127, v167
	v_mul_f32_e32 v168, 0x3d372713, v149
	v_mul_f32_e32 v120, v124, v120
	v_fma_f32 v167, v127, v167, v127
	v_mul_f32_e32 v168, v149, v168
	v_fma_f32 v120, v124, v120, v124
	v_mul_f32_e32 v167, 0x3fcc422a, v167
	v_fma_f32 v168, v149, v168, v149
	v_mul_f32_e32 v120, 0x3fcc422a, v120
	v_mul_f32_e32 v167, 0xbfb8aa3b, v167
	v_mul_f32_e32 v168, 0x3fcc422a, v168
	v_mul_f32_e32 v120, 0xbfb8aa3b, v120
	v_mul_f32_e32 v123, 0xbfb8aa3b, v123
	v_exp_f32_e32 v167, v167
	v_mul_f32_e32 v168, 0xbfb8aa3b, v168
	v_exp_f32_e32 v120, v120
	v_exp_f32_e32 v123, v123
	v_exp_f32_e32 v169, v168
	v_rcp_f32_e32 v168, v147
	v_add_f32_e32 v147, 1.0, v167
	v_add_f32_e32 v120, 1.0, v120
	v_add_f32_e32 v123, 1.0, v123
	v_rcp_f32_e32 v167, v147
	v_add_f32_e32 v147, 1.0, v169
	v_rcp_f32_e32 v120, v120
	v_rcp_f32_e32 v121, v121
	v_rcp_f32_e32 v169, v147
	v_rcp_f32_e32 v123, v123
	v_pk_mul_f32 v[126:127], v[126:127], v[166:167]
	v_pk_mul_f32 v[124:125], v[124:125], v[120:121]
	v_pk_mul_f32 v[148:149], v[148:149], v[168:169]
	v_pk_mul_f32 v[150:151], v[150:151], v[122:123]

; #define PG8_STAGE(bufoff, gbase, voff) do { _Pragma("unroll") for (int _i = 0; _i < 2; ++_i) \
;         __builtin_amdgcn_global_load_lds((const unsigned*)((const char*)(gbase) + (voff)[_i]), (LAS unsigned*)(lds + (bufoff) + ldsw + _i * 8192), 16, 0, 0); } while (0)
; #define PG8_WAIT_V(n) asm volatile("s_waitcnt vmcnt(" #n ")" ::: "memory")
; #define PG8_BAR __builtin_amdgcn_s_barrier()
; template <class Epi>
; __device__ __forceinline__ void gemm_phase(LAS unsigned char* lds, const Gemm g, const StaticOrder& S, const Epi& E, int wv) {
;     ...
;     for (int i = 0; i < 2; ++i) { int R, C; stage_rc(tid * 16 + i * 8192, R, C); const int Rb = Epi::PERM ? ((R & ~31) + perm32(R & 31)) : R;
;         voffA[i] = (unsigned)(R * g.lda + C) * 2u; voffB[i] = (unsigned)(Rb * g.ldb + C) * 2u; }
;     const bool krev = (g.adiag & 2) != 0;
;     const ptrdiff_t kstep = krev ? -(ptrdiff_t)(BK * 2) : (ptrdiff_t)(BK * 2);
;     const size_t kbeg = krev ? (size_t)(nt - 1) * (BK * 2) : 0;
;     const size_t hstepA = (size_t)HALF * g.lda * 2, hstepB = (size_t)HALF * g.ldb * 2;
;     const size_t tstepA = 2 * hstepA, tstepB = 2 * hstepB;
;     const unsigned ldsw = (unsigned)wid * 1024u;
;     const int aoff = lds_byte(wr * 64 + fr, fq * 8), boff = lds_byte(wc * 32 + fr, fq * 8);
;     ...
;     Unit cur, nxt; int ui = 0;
;     if (!S.next(0, cur)) return;
;     f32x4 acc[2][2][4][2];
; #pragma unroll
;     for (int a = 0; a < 2; ++a)
; #pragma unroll
;         for (int b = 0; b < 2; ++b)
; #pragma unroll
;             for (int m = 0; m < 4; ++m)
; #pragma unroll
;                 for (int n = 0; n < 2; ++n) acc[a][b][m][n] = (f32x4){0.f, 0.f, 0.f, 0.f};
;     bf16x8 At[4][2], B0[2][2], B1[2][2];
;     const char* cA = (const char*)g.A + (size_t)cur.pm * tstepA + ((g.adiag & 1) ? (size_t)(cur.pn >> 1) * K * 2 : 0) + kbeg;
;     const char* cB = (const char*)g.Bt + (size_t)cur.pn * tstepB + kbeg;
;     PG8_STAGE(PG8_SB(0, 0), cB, voffB); PG8_STAGE(PG8_SA(0, 0), cA, voffA); PG8_STAGE(PG8_SB(0, 1), cB + hstepB, voffB); PG8_STAGE(PG8_SA(0, 1), cA + hstepA, voffA);
;     if (wr == 1) PG8_BAR;
;     PG8_WAIT_V(4); PG8_BAR;
;     PG8_STAGE(PG8_SB(1, 0), cB + kstep, voffB); PG8_STAGE(PG8_SA(1, 0), cA + kstep, voffA); PG8_STAGE(PG8_SB(1, 1), cB + hstepB + kstep, voffB);
;     PG8_WAIT_V(6); PG8_BAR;
.LBB0_1115:
	s_load_dwordx2 s[8:9], s[38:39], 0x90
	s_load_dwordx2 s[10:11], s[40:41], 0xa0
	v_readlane_b32 s4, v255, 14
	v_readlane_b32 s5, v255, 15
	s_and_b64 vcc, exec, s[4:5]
	s_cbranch_vccnz .LBB0_1385
	v_ashrrev_i32_e32 v2, 31, v0
	v_lshrrev_b32_e32 v2, 26, v2
	v_lshlrev_b32_e32 v1, 4, v0
	v_add_u32_e32 v2, v0, v2
	v_bfe_i32 v0, v0, 27, 1
	v_lshrrev_b32_e32 v0, 22, v0
	v_add_u32_e32 v0, v1, v0
	v_and_b32_e32 v0, 0xfffffc00, v0
	v_sub_u32_e32 v0, v1, v0
	v_lshrrev_b32_e32 v3, 4, v0
	v_bitop3_b32 v0, v3, v0, 32 bitop3:0x6c
	v_ashrrev_i32_e32 v4, 31, v0
	v_lshrrev_b32_e32 v4, 26, v4
	v_ashrrev_i32_e32 v2, 6, v2
	v_add_u32_e32 v4, v0, v4
	v_lshlrev_b32_e32 v3, 3, v2
	v_ashrrev_i32_e32 v5, 6, v4
	v_and_b32_e32 v4, 0xc0, v4
	v_and_b32_e32 v3, -16, v3
	v_lshlrev_b32_e32 v2, 5, v2
	v_sub_u32_e32 v0, v0, v4
	v_mov_b32_e32 v4, 1
	v_add_u32_e32 v3, v5, v3
	v_and_b32_e32 v2, 32, v2
	v_ashrrev_i16_sdwa v0, v4, sext(v0) dst_sel:DWORD dst_unused:UNUSED_PAD src0_sel:DWORD src1_sel:BYTE_0
	v_add_u32_sdwa v0, v2, sext(v0) dst_sel:DWORD dst_unused:UNUSED_PAD src0_sel:DWORD src1_sel:WORD_0
	v_lshlrev_b32_e32 v2, 12, v3
	v_lshl_add_u32 v140, v0, 1, v2
	v_add_u32_e32 v0, 0x2000, v1
	v_ashrrev_i32_e32 v1, 31, v0
	v_lshrrev_b32_e32 v1, 22, v1
	v_add_u32_e32 v1, v0, v1
	v_ashrrev_i32_e32 v1, 10, v1
	v_mul_i32_i24_e32 v2, 0x400, v1
	v_sub_u32_e32 v0, v0, v2
	v_lshrrev_b32_e32 v2, 4, v0
	s_movk_i32 s7, 0xf200
	v_bitop3_b32 v0, v2, v0, 32 bitop3:0x6c
	v_mad_u64_u32 v[142:143], s[4:5], v3, s7, v[140:141]
	v_ashrrev_i32_e32 v3, 31, v0
	v_lshrrev_b32_e32 v3, 26, v3
	v_add_u32_e32 v3, v0, v3
	v_lshlrev_b32_e32 v2, 3, v1
	v_ashrrev_i32_e32 v5, 6, v3
	v_and_b32_e32 v3, 0xc0, v3
	v_and_b32_e32 v2, -16, v2
	v_lshlrev_b32_e32 v1, 5, v1
	v_sub_u32_e32 v0, v0, v3
	v_add_u32_e32 v2, v5, v2
	v_and_b32_e32 v1, 32, v1
	v_ashrrev_i16_sdwa v0, v4, sext(v0) dst_sel:DWORD dst_unused:UNUSED_PAD src0_sel:DWORD src1_sel:BYTE_0
	s_waitcnt lgkmcnt(0)
	s_add_u32 s69, s34, 0x7300000
	v_add_u32_sdwa v0, v1, sext(v0) dst_sel:DWORD dst_unused:UNUSED_PAD src0_sel:DWORD src1_sel:WORD_0
	v_lshlrev_b32_e32 v1, 12, v2
	s_addc_u32 s70, s35, 0
	v_lshl_add_u32 v144, v0, 1, v1
	s_add_u32 s71, s36, 0x1900000
	v_mad_u64_u32 v[146:147], s[4:5], v2, s7, v[144:145]
	s_addc_u32 s72, s37, 0
	s_ashr_i32 s4, s58, 1
	s_ashr_i32 s7, s68, 6
	s_ashr_i32 s57, s56, 31
	s_ashr_i32 s5, s4, 31
	s_ashr_i32 s59, s58, 31
	s_ashr_i32 s6, s68, 8
	s_lshl_b32 s73, s7, 10
	s_lshl_b64 s[22:23], s[56:57], 20
	s_lshl_b64 s[24:25], s[4:5], 9
	s_lshl_b64 s[4:5], s[58:59], 17
	s_add_u32 s62, s71, s4
	s_addc_u32 s63, s72, s5
	s_add_i32 s4, s73, 0
	s_add_i32 m0, s4, 0x10000
	v_mov_b32_e32 v143, 0
	global_load_lds_dwordx4 v142, s[62:63]
	s_add_i32 m0, s4, 0x12000
	s_add_u32 s5, s69, s22
	s_addc_u32 s22, s70, s23
	s_add_u32 s60, s5, s24
	global_load_lds_dwordx4 v146, s[62:63]
	s_addc_u32 s61, s22, s25
	s_mov_b32 m0, s4
	s_add_i32 s5, s4, 0x2000
	global_load_lds_dwordx4 v140, s[60:61]
	s_mov_b32 m0, s5
	s_add_u32 s22, s62, 0x10000
	global_load_lds_dwordx4 v144, s[60:61]
	s_addc_u32 s23, s63, 0
	s_add_i32 m0, s4, 0x14000
	v_mov_b32_e32 v147, v143
	global_load_lds_dwordx4 v142, s[22:23]
	s_add_i32 m0, s4, 0x16000
	s_add_u32 s24, s60, 0x80000
	global_load_lds_dwordx4 v146, s[22:23]
	s_addc_u32 s25, s61, 0
	s_add_i32 s22, s4, 0x4000
	s_mov_b32 m0, s22
	s_add_i32 s23, s4, 0x6000
	global_load_lds_dwordx4 v140, s[24:25]
	s_mov_b32 m0, s23
	v_mov_b32_e32 v141, v143
	global_load_lds_dwordx4 v144, s[24:25]
	v_mov_b32_e32 v145, v143
	v_lshl_add_u64 v[6:7], s[62:63], 0, v[142:143]
	v_lshl_add_u64 v[4:5], s[62:63], 0, v[146:147]
	v_lshl_add_u64 v[2:3], s[60:61], 0, v[140:141]
	s_cmp_lg_u32 s6, 1
	v_lshl_add_u64 v[0:1], s[60:61], 0, v[144:145]
	s_cbranch_scc1 .LBB0_1118
	s_barrier
	s_setprio 1

; #define PG8_STAGE(bufoff, gbase, voff) do { _Pragma("unroll") for (int _i = 0; _i < 2; ++_i) \
;         __builtin_amdgcn_global_load_lds((const unsigned*)((const char*)(gbase) + (voff)[_i]), (LAS unsigned*)(lds + (bufoff) + ldsw + _i * 8192), 16, 0, 0); } while (0)
; #define PG8_LDA(dst, b, h) do { _Pragma("unroll") for (int m = 0; m < 4; ++m) _Pragma("unroll") for (int k = 0; k < 2; ++k) dst[m][k] = *(const LAS bf16x8*)(lds + PG8_SA(b, h) + aoff + m * 2048 + k * 1024); } while (0)
; #define PG8_LDB(dst, b, h) do { _Pragma("unroll") for (int n = 0; n < 2; ++n) _Pragma("unroll") for (int k = 0; k < 2; ++k) dst[n][k] = *(const LAS bf16x8*)(lds + PG8_SB(b, h) + boff + n * 2048 + k * 1024); } while (0)
; #define PG8_MMA(ai, bj, At, Bt) do { __builtin_amdgcn_s_setprio(1); _Pragma("unroll") for (int m = 0; m < 4; ++m) _Pragma("unroll") for (int n = 0; n < 2; ++n) _Pragma("unroll") for (int k = 0; k < 2; ++k) \
;         acc[ai][bj][m][n] = __builtin_amdgcn_mfma_f32_16x16x32_bf16(Bt[n][k], At[m][k], acc[ai][bj][m][n], 0, 0, 0); __builtin_amdgcn_s_setprio(0); } while (0)
; template <class Epi>
; __device__ __forceinline__ void gemm_phase(LAS unsigned char* lds, const Gemm g, const StaticOrder& S, const Epi& E, int wv) {
;     ...
;         const bool has_next = S.next(ui + 1, nxt);
;         const char* nA = has_next ? (const char*)g.A + (size_t)nxt.pm * tstepA + ((g.adiag & 1) ? (size_t)(nxt.pn >> 1) * K * 2 : 0) + kbeg : cA;
;         const char* nB = has_next ? (const char*)g.Bt + (size_t)nxt.pn * tstepB + kbeg : cB;
;         for (int t = 0; t < nt; t += 2) {
;             const bool last = (t == nt - 2);
;             const char* a1 = cA + (ptrdiff_t)(t + 1) * kstep;
;             const char* a2 = last ? nA : cA + (ptrdiff_t)(t + 2) * kstep; const char* b2 = last ? nB : cB + (ptrdiff_t)(t + 2) * kstep;
;             const char* a3 = a2 + kstep; const char* b3 = b2 + kstep;
;             PG8_LDB(B0, 0, 0); PG8_SCHED; PG8_LDA(At, 0, 0); PG8_STAGE(PG8_SA(1, 1), a1 + hstepA, voffA);
;             PG8_WAIT_L(8); PG8_BAR; PG8_WAIT_L(0); PG8_MMA(0, 0, At, B0); PG8_BAR; PG8_SCHED;
;             PG8_LDB(B1, 0, 1); PG8_STAGE(PG8_SB(0, 0), b2, voffB);
;             PG8_BAR; PG8_WAIT_L(0); PG8_MMA(0, 1, At, B1); PG8_BAR;
;             PG8_LDA(At, 0, 1); PG8_STAGE(PG8_SA(0, 0), a2, voffA);
;             PG8_BAR; PG8_WAIT_L(0); PG8_MMA(1, 0, At, B0); PG8_BAR; PG8_SCHED;
.LBB0_1126:
	s_ashr_i32 s51, s50, 31
	s_lshl_b64 s[52:53], s[50:51], 20
	s_add_u32 s49, s69, s52
	s_addc_u32 s51, s70, s53
	s_ashr_i32 s52, s48, 1
	s_ashr_i32 s53, s52, 31
	s_lshl_b64 s[52:53], s[52:53], 9
	s_add_u32 s52, s49, s52
	v_cmp_lt_i64_e32 vcc, s[46:47], v[148:149]
	s_addc_u32 s53, s51, s53
	ds_read_b128 v[0:3], v205
	ds_read_b128 v[4:7], v205 offset:1024
	ds_read_b128 v[8:11], v205 offset:2048
	ds_read_b128 v[12:15], v205 offset:3072
	s_and_b64 s[54:55], vcc, exec
	s_cselect_b32 s67, s53, s61
	s_cselect_b32 s66, s52, s60
	s_ashr_i32 s49, s48, 31
	s_lshl_b64 s[54:55], s[48:49], 17
	s_add_u32 s54, s71, s54
	s_addc_u32 s55, s72, s55
	s_and_b64 s[64:65], vcc, exec
	s_cselect_b32 s65, s55, s63
	s_cselect_b32 s64, s54, s62
	s_add_u32 s76, s60, 0x80080
	s_addc_u32 s77, s61, 0
	s_add_i32 s79, s4, 0xc000
	v_lshl_add_u64 v[48:49], s[76:77], 0, v[140:141]
	s_mov_b32 m0, s79
	s_add_i32 s49, s4, 0xe000
	ds_read_b128 v[16:19], v206
	ds_read_b128 v[20:23], v206 offset:1024
	ds_read_b128 v[24:27], v206 offset:2048
	ds_read_b128 v[28:31], v206 offset:3072
	ds_read_b128 v[32:35], v206 offset:4096
	ds_read_b128 v[36:39], v206 offset:5120
	ds_read_b128 v[40:43], v206 offset:6144
	ds_read_b128 v[44:47], v206 offset:7168
	global_load_lds_dwordx4 v[48:49], off
	v_lshl_add_u64 v[48:49], s[76:77], 0, v[144:145]
	s_mov_b32 m0, s49
	s_nop 0
	global_load_lds_dwordx4 v[48:49], off
	s_waitcnt lgkmcnt(8)
	s_barrier
	s_waitcnt lgkmcnt(0)
	s_waitcnt lgkmcnt(0)
	v_mfma_f32_16x16x32_bf16 v[48:51], v[0:3], v[16:19], 0
	v_mfma_f32_16x16x32_bf16 v[52:55], v[8:11], v[16:19], 0
	v_mfma_f32_16x16x32_bf16 v[56:59], v[0:3], v[24:27], 0
	v_mfma_f32_16x16x32_bf16 v[60:63], v[8:11], v[24:27], 0
	v_mfma_f32_16x16x32_bf16 v[64:67], v[0:3], v[32:35], 0
	v_mfma_f32_16x16x32_bf16 v[68:71], v[8:11], v[32:35], 0
	v_mfma_f32_16x16x32_bf16 v[72:75], v[0:3], v[40:43], 0
	v_mfma_f32_16x16x32_bf16 v[76:79], v[8:11], v[40:43], 0
	v_mfma_f32_16x16x32_bf16 v[48:51], v[4:7], v[20:23], v[48:51]
	v_mfma_f32_16x16x32_bf16 v[52:55], v[12:15], v[20:23], v[52:55]
	v_mfma_f32_16x16x32_bf16 v[56:59], v[4:7], v[28:31], v[56:59]
	v_mfma_f32_16x16x32_bf16 v[60:63], v[12:15], v[28:31], v[60:63]
	v_mfma_f32_16x16x32_bf16 v[64:67], v[4:7], v[36:39], v[64:67]
	v_mfma_f32_16x16x32_bf16 v[68:71], v[12:15], v[36:39], v[68:71]
	v_mfma_f32_16x16x32_bf16 v[72:75], v[4:7], v[44:47], v[72:75]
	v_mfma_f32_16x16x32_bf16 v[76:79], v[12:15], v[44:47], v[76:79]
	s_barrier
	v_lshl_add_u64 v[200:201], s[62:63], 0, v[142:143]
	s_add_i32 s76, s33, s73
	v_lshl_add_u64 v[96:97], v[200:201], 0, s[36:37]
	s_mov_b32 m0, s76
	v_lshl_add_u64 v[214:215], s[62:63], 0, v[146:147]
	s_add_i32 s51, s76, 0x2000
	ds_read_b128 v[80:83], v207
	ds_read_b128 v[84:87], v207 offset:1024
	ds_read_b128 v[88:91], v207 offset:2048
	ds_read_b128 v[92:95], v207 offset:3072
	global_load_lds_dwordx4 v[96:97], off
	v_lshl_add_u64 v[96:97], v[214:215], 0, s[36:37]
	s_mov_b32 m0, s51
	s_nop 0
	global_load_lds_dwordx4 v[96:97], off
	s_barrier
	s_waitcnt lgkmcnt(0)
	s_waitcnt lgkmcnt(0)
	v_mfma_f32_16x16x32_bf16 v[96:99], v[80:83], v[16:19], 0
	v_mfma_f32_16x16x32_bf16 v[16:19], v[88:91], v[16:19], 0
	v_mfma_f32_16x16x32_bf16 v[96:99], v[84:87], v[20:23], v[96:99]
	v_mfma_f32_16x16x32_bf16 v[16:19], v[92:95], v[20:23], v[16:19]
	v_mfma_f32_16x16x32_bf16 v[20:23], v[80:83], v[24:27], 0
	v_mfma_f32_16x16x32_bf16 v[24:27], v[88:91], v[24:27], 0
	v_mfma_f32_16x16x32_bf16 v[20:23], v[84:87], v[28:31], v[20:23]
	v_mfma_f32_16x16x32_bf16 v[24:27], v[92:95], v[28:31], v[24:27]
	v_mfma_f32_16x16x32_bf16 v[28:31], v[80:83], v[32:35], 0
	v_mfma_f32_16x16x32_bf16 v[32:35], v[88:91], v[32:35], 0
	v_mfma_f32_16x16x32_bf16 v[28:31], v[84:87], v[36:39], v[28:31]
	v_mfma_f32_16x16x32_bf16 v[32:35], v[92:95], v[36:39], v[32:35]
	v_mfma_f32_16x16x32_bf16 v[36:39], v[80:83], v[40:43], 0
	v_mfma_f32_16x16x32_bf16 v[40:43], v[88:91], v[40:43], 0
	v_mfma_f32_16x16x32_bf16 v[36:39], v[84:87], v[44:47], v[36:39]
	v_mfma_f32_16x16x32_bf16 v[40:43], v[92:95], v[44:47], v[40:43]
	v_lshl_add_u64 v[216:217], s[60:61], 0, v[140:141]
	s_mov_b32 m0, s4
	v_lshl_add_u64 v[128:129], v[216:217], 0, s[36:37]
	v_lshl_add_u64 v[218:219], s[60:61], 0, v[144:145]
	s_barrier
	ds_read_b128 v[44:47], v206 offset:16384
	ds_read_b128 v[100:103], v206 offset:17408
	ds_read_b128 v[104:107], v206 offset:18432
	ds_read_b128 v[108:111], v206 offset:19456
	ds_read_b128 v[112:115], v206 offset:20480
	ds_read_b128 v[116:119], v206 offset:21504
	ds_read_b128 v[120:123], v206 offset:22528
	ds_read_b128 v[124:127], v206 offset:23552
	global_load_lds_dwordx4 v[128:129], off
	v_lshl_add_u64 v[128:129], v[218:219], 0, s[36:37]
	s_mov_b32 m0, s5
	s_nop 0
	global_load_lds_dwordx4 v[128:129], off
	s_barrier
	s_waitcnt lgkmcnt(0)
	s_waitcnt lgkmcnt(0)
	v_mfma_f32_16x16x32_bf16 v[128:131], v[0:3], v[44:47], 0
	v_mfma_f32_16x16x32_bf16 v[136:139], v[0:3], v[104:107], 0
	v_mfma_f32_16x16x32_bf16 v[156:159], v[0:3], v[112:115], 0
	v_mfma_f32_16x16x32_bf16 v[0:3], v[0:3], v[120:123], 0
	v_mfma_f32_16x16x32_bf16 v[128:131], v[4:7], v[100:103], v[128:131]
	v_mfma_f32_16x16x32_bf16 v[132:135], v[8:11], v[44:47], 0
	v_mfma_f32_16x16x32_bf16 v[136:139], v[4:7], v[108:111], v[136:139]
	v_mfma_f32_16x16x32_bf16 v[152:155], v[8:11], v[104:107], 0
	v_mfma_f32_16x16x32_bf16 v[156:159], v[4:7], v[116:119], v[156:159]
	v_mfma_f32_16x16x32_bf16 v[160:163], v[8:11], v[112:115], 0
	v_mfma_f32_16x16x32_bf16 v[0:3], v[4:7], v[124:127], v[0:3]
	v_mfma_f32_16x16x32_bf16 v[4:7], v[8:11], v[120:123], 0
	v_mfma_f32_16x16x32_bf16 v[132:135], v[12:15], v[100:103], v[132:135]
	v_mfma_f32_16x16x32_bf16 v[152:155], v[12:15], v[108:111], v[152:155]
	v_mfma_f32_16x16x32_bf16 v[160:163], v[12:15], v[116:119], v[160:163]
	v_mfma_f32_16x16x32_bf16 v[4:7], v[12:15], v[124:127], v[4:7]
	s_barrier
; #define PG8_STAGE(bufoff, gbase, voff) do { _Pragma("unroll") for (int _i = 0; _i < 2; ++_i) \
;         __builtin_amdgcn_global_load_lds((const unsigned*)((const char*)(gbase) + (voff)[_i]), (LAS unsigned*)(lds + (bufoff) + ldsw + _i * 8192), 16, 0, 0); } while (0)
; #define PG8_LDA(dst, b, h) do { _Pragma("unroll") for (int m = 0; m < 4; ++m) _Pragma("unroll") for (int k = 0; k < 2; ++k) dst[m][k] = *(const LAS bf16x8*)(lds + PG8_SA(b, h) + aoff + m * 2048 + k * 1024); } while (0)
; #define PG8_LDB(dst, b, h) do { _Pragma("unroll") for (int n = 0; n < 2; ++n) _Pragma("unroll") for (int k = 0; k < 2; ++k) dst[n][k] = *(const LAS bf16x8*)(lds + PG8_SB(b, h) + boff + n * 2048 + k * 1024); } while (0)
; #define PG8_MMA(ai, bj, At, Bt) do { __builtin_amdgcn_s_setprio(1); _Pragma("unroll") for (int m = 0; m < 4; ++m) _Pragma("unroll") for (int n = 0; n < 2; ++n) _Pragma("unroll") for (int k = 0; k < 2; ++k) \
;         acc[ai][bj][m][n] = __builtin_amdgcn_mfma_f32_16x16x32_bf16(Bt[n][k], At[m][k], acc[ai][bj][m][n], 0, 0, 0); __builtin_amdgcn_s_setprio(0); } while (0)
; #define PG8_WAIT_V(n) asm volatile("s_waitcnt vmcnt(" #n ")" ::: "memory")
; #define PG8_WAIT_L(n) asm volatile("s_waitcnt lgkmcnt(" #n ")" ::: "memory")
; #define PG8_BAR __builtin_amdgcn_s_barrier()
; #define PG8_SCHED __builtin_amdgcn_sched_barrier(0)
; template <class Epi>
; __device__ __forceinline__ void gemm_phase(LAS unsigned char* lds, const Gemm g, const StaticOrder& S, const Epi& E, int wv) {
;     ...
;             PG8_BAR; PG8_WAIT_L(0); PG8_MMA(1, 0, At, B0); PG8_BAR; PG8_SCHED;
;             PG8_STAGE(PG8_SB(0, 1), b2 + hstepB, voffB);
;             PG8_WAIT_V(6); PG8_BAR; PG8_MMA(1, 1, At, B1); PG8_BAR;
;             PG8_LDB(B0, 1, 0); PG8_SCHED; PG8_LDA(At, 1, 0); PG8_STAGE(PG8_SA(0, 1), a2 + hstepA, voffA);
;             PG8_WAIT_L(8); PG8_BAR; PG8_WAIT_L(0); PG8_MMA(0, 0, At, B0); PG8_BAR; PG8_SCHED;
;             PG8_LDB(B1, 1, 1); PG8_STAGE(PG8_SB(1, 0), b3, voffB);
;             PG8_BAR; PG8_WAIT_L(0); PG8_MMA(0, 1, At, B1); PG8_BAR;
;             PG8_LDA(At, 1, 1); PG8_STAGE(PG8_SA(1, 0), a3, voffA);
;             PG8_BAR; PG8_WAIT_L(0); PG8_MMA(1, 0, At, B0); PG8_BAR; PG8_SCHED;
	s_add_u32 s80, s62, 0x10100
	s_addc_u32 s81, s63, 0
	s_add_i32 s77, s59, s73
	v_lshl_add_u64 v[8:9], s[80:81], 0, v[142:143]
	s_mov_b32 m0, s77
	s_add_i32 s57, s77, 0x2000
	global_load_lds_dwordx4 v[8:9], off
	v_lshl_add_u64 v[8:9], s[80:81], 0, v[146:147]
	s_mov_b32 m0, s57
	s_nop 0
	global_load_lds_dwordx4 v[8:9], off
	s_waitcnt vmcnt(6)
	s_barrier
	v_mfma_f32_16x16x32_bf16 v[8:11], v[80:83], v[44:47], 0
	v_mfma_f32_16x16x32_bf16 v[12:15], v[88:91], v[44:47], 0
	v_mfma_f32_16x16x32_bf16 v[8:11], v[84:87], v[100:103], v[8:11]
	v_mfma_f32_16x16x32_bf16 v[12:15], v[92:95], v[100:103], v[12:15]
	v_mfma_f32_16x16x32_bf16 v[44:47], v[80:83], v[104:107], 0
	v_mfma_f32_16x16x32_bf16 v[100:103], v[88:91], v[104:107], 0
	v_mfma_f32_16x16x32_bf16 v[104:107], v[80:83], v[112:115], 0
	v_mfma_f32_16x16x32_bf16 v[80:83], v[80:83], v[120:123], 0
	v_mfma_f32_16x16x32_bf16 v[44:47], v[84:87], v[108:111], v[44:47]
	v_mfma_f32_16x16x32_bf16 v[100:103], v[92:95], v[108:111], v[100:103]
	v_mfma_f32_16x16x32_bf16 v[104:107], v[84:87], v[116:119], v[104:107]
	v_mfma_f32_16x16x32_bf16 v[108:111], v[88:91], v[112:115], 0
	v_mfma_f32_16x16x32_bf16 v[80:83], v[84:87], v[124:127], v[80:83]
	v_mfma_f32_16x16x32_bf16 v[84:87], v[88:91], v[120:123], 0
	v_mfma_f32_16x16x32_bf16 v[108:111], v[92:95], v[116:119], v[108:111]
	v_mfma_f32_16x16x32_bf16 v[84:87], v[92:95], v[124:127], v[84:87]
	s_add_i32 s78, 0, 0x18000
	v_add_u32_e32 v209, s78, v203
	s_barrier
	ds_read_b128 v[88:91], v209
	ds_read_b128 v[92:95], v209 offset:1024
	ds_read_b128 v[112:115], v209 offset:2048
	ds_read_b128 v[116:119], v209 offset:3072
	s_add_u32 s80, s60, 0x80100
	s_addc_u32 s81, s61, 0
	s_mov_b32 m0, s22
	v_lshl_add_u64 v[188:189], s[80:81], 0, v[140:141]
	ds_read_b128 v[120:123], v206 offset:32768
	ds_read_b128 v[124:127], v206 offset:33792
	ds_read_b128 v[164:167], v206 offset:34816
	ds_read_b128 v[168:171], v206 offset:35840
	ds_read_b128 v[172:175], v206 offset:36864
	ds_read_b128 v[176:179], v206 offset:37888
	ds_read_b128 v[180:183], v206 offset:38912
	ds_read_b128 v[184:187], v206 offset:39936
	global_load_lds_dwordx4 v[188:189], off
	v_lshl_add_u64 v[188:189], s[80:81], 0, v[144:145]
	s_mov_b32 m0, s23
	s_nop 0
	global_load_lds_dwordx4 v[188:189], off
	s_waitcnt lgkmcnt(8)
	s_barrier
	s_waitcnt lgkmcnt(0)
	s_waitcnt lgkmcnt(0)
	v_mfma_f32_16x16x32_bf16 v[48:51], v[88:91], v[120:123], v[48:51]
	v_mfma_f32_16x16x32_bf16 v[52:55], v[112:115], v[120:123], v[52:55]
	v_mfma_f32_16x16x32_bf16 v[56:59], v[88:91], v[164:167], v[56:59]
	v_mfma_f32_16x16x32_bf16 v[60:63], v[112:115], v[164:167], v[60:63]
	v_mfma_f32_16x16x32_bf16 v[64:67], v[88:91], v[172:175], v[64:67]
	v_mfma_f32_16x16x32_bf16 v[68:71], v[112:115], v[172:175], v[68:71]
	v_mfma_f32_16x16x32_bf16 v[72:75], v[88:91], v[180:183], v[72:75]
	v_mfma_f32_16x16x32_bf16 v[76:79], v[112:115], v[180:183], v[76:79]
	v_mfma_f32_16x16x32_bf16 v[48:51], v[92:95], v[124:127], v[48:51]
	v_mfma_f32_16x16x32_bf16 v[52:55], v[116:119], v[124:127], v[52:55]
	v_mfma_f32_16x16x32_bf16 v[56:59], v[92:95], v[168:171], v[56:59]
	v_mfma_f32_16x16x32_bf16 v[60:63], v[116:119], v[168:171], v[60:63]
	v_mfma_f32_16x16x32_bf16 v[64:67], v[92:95], v[176:179], v[64:67]
	v_mfma_f32_16x16x32_bf16 v[68:71], v[116:119], v[176:179], v[68:71]
	v_mfma_f32_16x16x32_bf16 v[72:75], v[92:95], v[184:187], v[72:75]
	v_mfma_f32_16x16x32_bf16 v[76:79], v[116:119], v[184:187], v[76:79]
	s_barrier
	s_add_i32 s81, 0, 0x1c000
	s_add_i32 s80, s78, s73
	v_add_u32_e32 v250, s81, v203
	v_lshl_add_u64 v[200:201], v[200:201], 0, s[38:39]
	s_mov_b32 m0, s80
	s_add_i32 s78, s80, 0x2000
	ds_read_b128 v[188:191], v250
	ds_read_b128 v[192:195], v250 offset:1024
	ds_read_b128 v[196:199], v250 offset:2048
	ds_read_b128 v[210:213], v250 offset:3072
	global_load_lds_dwordx4 v[200:201], off
	v_lshl_add_u64 v[200:201], v[214:215], 0, s[38:39]
	s_mov_b32 m0, s78
	s_nop 0
	global_load_lds_dwordx4 v[200:201], off
	s_barrier
	s_waitcnt lgkmcnt(0)
	s_waitcnt lgkmcnt(0)
	v_mfma_f32_16x16x32_bf16 v[96:99], v[188:191], v[120:123], v[96:99]
	v_mfma_f32_16x16x32_bf16 v[16:19], v[196:199], v[120:123], v[16:19]
	v_mfma_f32_16x16x32_bf16 v[20:23], v[188:191], v[164:167], v[20:23]
	v_mfma_f32_16x16x32_bf16 v[24:27], v[196:199], v[164:167], v[24:27]
	v_mfma_f32_16x16x32_bf16 v[28:31], v[188:191], v[172:175], v[28:31]
	v_mfma_f32_16x16x32_bf16 v[32:35], v[196:199], v[172:175], v[32:35]
	v_mfma_f32_16x16x32_bf16 v[36:39], v[188:191], v[180:183], v[36:39]
	v_mfma_f32_16x16x32_bf16 v[40:43], v[196:199], v[180:183], v[40:43]
	v_mfma_f32_16x16x32_bf16 v[96:99], v[192:195], v[124:127], v[96:99]
	v_mfma_f32_16x16x32_bf16 v[16:19], v[210:213], v[124:127], v[16:19]
	v_mfma_f32_16x16x32_bf16 v[20:23], v[192:195], v[168:171], v[20:23]
	v_mfma_f32_16x16x32_bf16 v[24:27], v[210:213], v[168:171], v[24:27]
	v_mfma_f32_16x16x32_bf16 v[28:31], v[192:195], v[176:179], v[28:31]
	v_mfma_f32_16x16x32_bf16 v[32:35], v[210:213], v[176:179], v[32:35]
	v_mfma_f32_16x16x32_bf16 v[36:39], v[192:195], v[184:187], v[36:39]
	v_mfma_f32_16x16x32_bf16 v[40:43], v[210:213], v[184:187], v[40:43]
	s_mov_b32 m0, s24
	v_lshl_add_u64 v[200:201], v[216:217], 0, s[38:39]
	s_barrier
	ds_read_b128 v[120:123], v206 offset:49152
	ds_read_b128 v[124:127], v206 offset:50176
	ds_read_b128 v[164:167], v206 offset:51200
	ds_read_b128 v[168:171], v206 offset:52224
	ds_read_b128 v[172:175], v206 offset:53248
	ds_read_b128 v[176:179], v206 offset:54272
	ds_read_b128 v[180:183], v206 offset:55296
	ds_read_b128 v[184:187], v206 offset:56320
	global_load_lds_dwordx4 v[200:201], off
	v_lshl_add_u64 v[200:201], v[218:219], 0, s[38:39]
	s_mov_b32 m0, s25
	s_nop 0
	global_load_lds_dwordx4 v[200:201], off
	s_barrier
; #define PG8_STAGE(bufoff, gbase, voff) do { _Pragma("unroll") for (int _i = 0; _i < 2; ++_i) \
;         __builtin_amdgcn_global_load_lds((const unsigned*)((const char*)(gbase) + (voff)[_i]), (LAS unsigned*)(lds + (bufoff) + ldsw + _i * 8192), 16, 0, 0); } while (0)
; #define PG8_LDA(dst, b, h) do { _Pragma("unroll") for (int m = 0; m < 4; ++m) _Pragma("unroll") for (int k = 0; k < 2; ++k) dst[m][k] = *(const LAS bf16x8*)(lds + PG8_SA(b, h) + aoff + m * 2048 + k * 1024); } while (0)
; #define PG8_LDB(dst, b, h) do { _Pragma("unroll") for (int n = 0; n < 2; ++n) _Pragma("unroll") for (int k = 0; k < 2; ++k) dst[n][k] = *(const LAS bf16x8*)(lds + PG8_SB(b, h) + boff + n * 2048 + k * 1024); } while (0)
; #define PG8_WAIT_V(n) asm volatile("s_waitcnt vmcnt(" #n ")" ::: "memory")
; #define PG8_WAIT_L(n) asm volatile("s_waitcnt lgkmcnt(" #n ")" ::: "memory")
; #define PG8_BAR __builtin_amdgcn_s_barrier()
; #define PG8_SCHED __builtin_amdgcn_sched_barrier(0)
; template <class Epi>
; __device__ __forceinline__ void gemm_phase(LAS unsigned char* lds, const Gemm g, const StaticOrder& S, const Epi& E, int wv) {
;     ...
;             PG8_LDB(B0, 0, 0); PG8_SCHED; PG8_LDA(At, 0, 0); PG8_STAGE(PG8_SA(1, 1), a1 + hstepA, voffA);
;             PG8_WAIT_L(8); PG8_BAR; PG8_WAIT_L(0); PG8_MMA(0, 0, At, B0); PG8_BAR; PG8_SCHED;
;             PG8_LDB(B1, 0, 1); PG8_STAGE(PG8_SB(0, 0), b2, voffB);
;             PG8_BAR; PG8_WAIT_L(0); PG8_MMA(0, 1, At, B1); PG8_BAR;
;             PG8_LDA(At, 0, 1); PG8_STAGE(PG8_SA(0, 0), a2, voffA);
;             PG8_BAR; PG8_WAIT_L(0); PG8_MMA(1, 0, At, B0); PG8_BAR; PG8_SCHED;
;             PG8_STAGE(PG8_SB(0, 1), b2 + hstepB, voffB);
;             PG8_WAIT_V(6); PG8_BAR; PG8_MMA(1, 1, At, B1); PG8_BAR;
;             PG8_LDB(B0, 1, 0); PG8_SCHED; PG8_LDA(At, 1, 0); PG8_STAGE(PG8_SA(0, 1), a2 + hstepA, voffA);
;             PG8_WAIT_L(8); PG8_BAR; PG8_WAIT_L(0); PG8_MMA(0, 0, At, B0); PG8_BAR; PG8_SCHED;
;             PG8_LDB(B1, 1, 1); PG8_STAGE(PG8_SB(1, 0), b3, voffB);
;             PG8_BAR; PG8_WAIT_L(0); PG8_MMA(0, 1, At, B1); PG8_BAR;
;             PG8_LDA(At, 1, 1); PG8_STAGE(PG8_SA(1, 0), a3, voffA);
;             PG8_BAR; PG8_WAIT_L(0); PG8_MMA(1, 0, At, B0); PG8_BAR; PG8_SCHED;
;             PG8_STAGE(PG8_SB(1, 1), b3 + hstepB, voffB);
;             PG8_WAIT_V(6); PG8_BAR; PG8_MMA(1, 1, At, B1); PG8_BAR;
	s_waitcnt lgkmcnt(0)
	s_waitcnt lgkmcnt(0)
	v_mfma_f32_16x16x32_bf16 v[128:131], v[88:91], v[120:123], v[128:131]
	v_mfma_f32_16x16x32_bf16 v[132:135], v[112:115], v[120:123], v[132:135]
	v_mfma_f32_16x16x32_bf16 v[136:139], v[88:91], v[164:167], v[136:139]
	v_mfma_f32_16x16x32_bf16 v[152:155], v[112:115], v[164:167], v[152:155]
	v_mfma_f32_16x16x32_bf16 v[156:159], v[88:91], v[172:175], v[156:159]
	v_mfma_f32_16x16x32_bf16 v[160:163], v[112:115], v[172:175], v[160:163]
	v_mfma_f32_16x16x32_bf16 v[0:3], v[88:91], v[180:183], v[0:3]
	v_mfma_f32_16x16x32_bf16 v[4:7], v[112:115], v[180:183], v[4:7]
	v_mfma_f32_16x16x32_bf16 v[128:131], v[92:95], v[124:127], v[128:131]
	v_mfma_f32_16x16x32_bf16 v[132:135], v[116:119], v[124:127], v[132:135]
	v_mfma_f32_16x16x32_bf16 v[136:139], v[92:95], v[168:171], v[136:139]
	v_mfma_f32_16x16x32_bf16 v[152:155], v[116:119], v[168:171], v[152:155]
	v_mfma_f32_16x16x32_bf16 v[156:159], v[92:95], v[176:179], v[156:159]
	v_mfma_f32_16x16x32_bf16 v[160:163], v[116:119], v[176:179], v[160:163]
	v_mfma_f32_16x16x32_bf16 v[0:3], v[92:95], v[184:187], v[0:3]
	v_mfma_f32_16x16x32_bf16 v[4:7], v[116:119], v[184:187], v[4:7]
	s_barrier
	s_add_u32 s82, s62, 0x10180
	s_addc_u32 s83, s63, 0
	s_add_i32 s63, s81, s73
	v_lshl_add_u64 v[88:89], s[82:83], 0, v[142:143]
	s_mov_b32 m0, s63
	s_add_i32 s62, s63, 0x2000
	global_load_lds_dwordx4 v[88:89], off
	v_lshl_add_u64 v[88:89], s[82:83], 0, v[146:147]
	s_mov_b32 m0, s62
	s_nop 0
	global_load_lds_dwordx4 v[88:89], off
	s_waitcnt vmcnt(6)
	s_barrier
	v_mfma_f32_16x16x32_bf16 v[8:11], v[188:191], v[120:123], v[8:11]
	v_mfma_f32_16x16x32_bf16 v[12:15], v[196:199], v[120:123], v[12:15]
	v_mfma_f32_16x16x32_bf16 v[44:47], v[188:191], v[164:167], v[44:47]
	v_mfma_f32_16x16x32_bf16 v[88:91], v[196:199], v[164:167], v[100:103]
	v_mfma_f32_16x16x32_bf16 v[92:95], v[188:191], v[172:175], v[104:107]
	v_mfma_f32_16x16x32_bf16 v[100:103], v[196:199], v[172:175], v[108:111]
	v_mfma_f32_16x16x32_bf16 v[80:83], v[188:191], v[180:183], v[80:83]
	v_mfma_f32_16x16x32_bf16 v[84:87], v[196:199], v[180:183], v[84:87]
	v_mfma_f32_16x16x32_bf16 v[8:11], v[192:195], v[124:127], v[8:11]
	v_mfma_f32_16x16x32_bf16 v[12:15], v[210:213], v[124:127], v[12:15]
	v_mfma_f32_16x16x32_bf16 v[44:47], v[192:195], v[168:171], v[44:47]
	v_mfma_f32_16x16x32_bf16 v[88:91], v[210:213], v[168:171], v[88:91]
	v_mfma_f32_16x16x32_bf16 v[92:95], v[192:195], v[176:179], v[92:95]
	v_mfma_f32_16x16x32_bf16 v[100:103], v[210:213], v[176:179], v[100:103]
	v_mfma_f32_16x16x32_bf16 v[80:83], v[192:195], v[184:187], v[80:83]
	v_mfma_f32_16x16x32_bf16 v[84:87], v[210:213], v[184:187], v[84:87]
	s_barrier
	ds_read_b128 v[104:107], v205
	ds_read_b128 v[108:111], v205 offset:1024
	ds_read_b128 v[112:115], v205 offset:2048
	ds_read_b128 v[116:119], v205 offset:3072
	s_add_u32 s60, s60, 0x80180
	s_addc_u32 s61, s61, 0
	s_mov_b32 m0, s79
	v_lshl_add_u64 v[188:189], s[60:61], 0, v[140:141]
	ds_read_b128 v[120:123], v206
	ds_read_b128 v[124:127], v206 offset:1024
	ds_read_b128 v[164:167], v206 offset:2048
	ds_read_b128 v[168:171], v206 offset:3072
	ds_read_b128 v[172:175], v206 offset:4096
	ds_read_b128 v[176:179], v206 offset:5120
	ds_read_b128 v[180:183], v206 offset:6144
	ds_read_b128 v[184:187], v206 offset:7168
	global_load_lds_dwordx4 v[188:189], off
	v_lshl_add_u64 v[188:189], s[60:61], 0, v[144:145]
	s_mov_b32 m0, s49
	s_nop 0
	global_load_lds_dwordx4 v[188:189], off
	s_waitcnt lgkmcnt(8)
	s_barrier
	s_waitcnt lgkmcnt(0)
	s_waitcnt lgkmcnt(0)
	v_mfma_f32_16x16x32_bf16 v[60:63], v[112:115], v[164:167], v[60:63]
	v_mfma_f32_16x16x32_bf16 v[188:191], v[116:119], v[168:171], v[60:63]
	v_mfma_f32_16x16x32_bf16 v[60:63], v[104:107], v[172:175], v[64:67]
	v_mfma_f32_16x16x32_bf16 v[64:67], v[108:111], v[176:179], v[60:63]
	v_mfma_f32_16x16x32_bf16 v[60:63], v[112:115], v[172:175], v[68:71]
	v_mfma_f32_16x16x32_bf16 v[68:71], v[116:119], v[176:179], v[60:63]
	v_mfma_f32_16x16x32_bf16 v[60:63], v[104:107], v[180:183], v[72:75]
	v_mfma_f32_16x16x32_bf16 v[48:51], v[104:107], v[120:123], v[48:51]
	v_mfma_f32_16x16x32_bf16 v[52:55], v[112:115], v[120:123], v[52:55]
	v_mfma_f32_16x16x32_bf16 v[56:59], v[104:107], v[164:167], v[56:59]
	v_mfma_f32_16x16x32_bf16 v[72:75], v[108:111], v[184:187], v[60:63]
	v_mfma_f32_16x16x32_bf16 v[60:63], v[112:115], v[180:183], v[76:79]
	v_mfma_f32_16x16x32_bf16 v[48:51], v[108:111], v[124:127], v[48:51]
	v_mfma_f32_16x16x32_bf16 v[52:55], v[116:119], v[124:127], v[52:55]
	v_mfma_f32_16x16x32_bf16 v[56:59], v[108:111], v[168:171], v[56:59]
	v_mfma_f32_16x16x32_bf16 v[76:79], v[116:119], v[184:187], v[60:63]
	s_barrier
	s_mov_b32 m0, s76
	v_lshl_add_u64 v[200:201], s[64:65], 0, v[142:143]
	ds_read_b128 v[60:63], v207
	ds_read_b128 v[192:195], v207 offset:1024
	ds_read_b128 v[196:199], v207 offset:2048
	ds_read_b128 v[210:213], v207 offset:3072
	global_load_lds_dwordx4 v[200:201], off
	v_lshl_add_u64 v[242:243], s[64:65], 0, v[146:147]
	s_mov_b32 m0, s51
	s_nop 0
	global_load_lds_dwordx4 v[242:243], off
	s_barrier
; #define PG8_STAGE(bufoff, gbase, voff) do { _Pragma("unroll") for (int _i = 0; _i < 2; ++_i) \
;         __builtin_amdgcn_global_load_lds((const unsigned*)((const char*)(gbase) + (voff)[_i]), (LAS unsigned*)(lds + (bufoff) + ldsw + _i * 8192), 16, 0, 0); } while (0)
; #define PG8_LDA(dst, b, h) do { _Pragma("unroll") for (int m = 0; m < 4; ++m) _Pragma("unroll") for (int k = 0; k < 2; ++k) dst[m][k] = *(const LAS bf16x8*)(lds + PG8_SA(b, h) + aoff + m * 2048 + k * 1024); } while (0)
; #define PG8_LDB(dst, b, h) do { _Pragma("unroll") for (int n = 0; n < 2; ++n) _Pragma("unroll") for (int k = 0; k < 2; ++k) dst[n][k] = *(const LAS bf16x8*)(lds + PG8_SB(b, h) + boff + n * 2048 + k * 1024); } while (0)
; #define PG8_WAIT_V(n) asm volatile("s_waitcnt vmcnt(" #n ")" ::: "memory")
; #define PG8_WAIT_L(n) asm volatile("s_waitcnt lgkmcnt(" #n ")" ::: "memory")
; #define PG8_BAR __builtin_amdgcn_s_barrier()
; #define PG8_SCHED __builtin_amdgcn_sched_barrier(0)
; template <class Epi>
; __device__ __forceinline__ void gemm_phase(LAS unsigned char* lds, const Gemm g, const StaticOrder& S, const Epi& E, int wv) {
;     ...
;             PG8_LDB(B0, 0, 0); PG8_SCHED; PG8_LDA(At, 0, 0); PG8_STAGE(PG8_SA(1, 1), a1 + hstepA, voffA);
;             PG8_WAIT_L(8); PG8_BAR; PG8_WAIT_L(0); PG8_MMA(0, 0, At, B0); PG8_BAR; PG8_SCHED;
;             PG8_LDB(B1, 0, 1); PG8_STAGE(PG8_SB(0, 0), b2, voffB);
;             PG8_BAR; PG8_WAIT_L(0); PG8_MMA(0, 1, At, B1); PG8_BAR;
;             PG8_LDA(At, 0, 1); PG8_STAGE(PG8_SA(0, 0), a2, voffA);
;             PG8_BAR; PG8_WAIT_L(0); PG8_MMA(1, 0, At, B0); PG8_BAR; PG8_SCHED;
;             PG8_STAGE(PG8_SB(0, 1), b2 + hstepB, voffB);
;             PG8_WAIT_V(6); PG8_BAR; PG8_MMA(1, 1, At, B1); PG8_BAR;
;             PG8_LDB(B0, 1, 0); PG8_SCHED; PG8_LDA(At, 1, 0); PG8_STAGE(PG8_SA(0, 1), a2 + hstepA, voffA);
;             PG8_WAIT_L(8); PG8_BAR; PG8_WAIT_L(0); PG8_MMA(0, 0, At, B0); PG8_BAR; PG8_SCHED;
;             PG8_LDB(B1, 1, 1); PG8_STAGE(PG8_SB(1, 0), b3, voffB);
;             PG8_BAR; PG8_WAIT_L(0); PG8_MMA(0, 1, At, B1); PG8_BAR;
;             PG8_LDA(At, 1, 1); PG8_STAGE(PG8_SA(1, 0), a3, voffA);
;             PG8_BAR; PG8_WAIT_L(0); PG8_MMA(1, 0, At, B0); PG8_BAR; PG8_SCHED;
;             PG8_STAGE(PG8_SB(1, 1), b3 + hstepB, voffB);
;             PG8_WAIT_V(6); PG8_BAR; PG8_MMA(1, 1, At, B1); PG8_BAR;
	s_waitcnt lgkmcnt(0)
	s_waitcnt lgkmcnt(0)
	v_mfma_f32_16x16x32_bf16 v[36:39], v[60:63], v[180:183], v[36:39]
	v_mfma_f32_16x16x32_bf16 v[96:99], v[60:63], v[120:123], v[96:99]
	v_mfma_f32_16x16x32_bf16 v[16:19], v[196:199], v[120:123], v[16:19]
	v_mfma_f32_16x16x32_bf16 v[20:23], v[60:63], v[164:167], v[20:23]
	v_mfma_f32_16x16x32_bf16 v[24:27], v[196:199], v[164:167], v[24:27]
	v_mfma_f32_16x16x32_bf16 v[28:31], v[60:63], v[172:175], v[28:31]
	v_mfma_f32_16x16x32_bf16 v[32:35], v[196:199], v[172:175], v[32:35]
	v_mfma_f32_16x16x32_bf16 v[164:167], v[192:195], v[184:187], v[36:39]
	v_mfma_f32_16x16x32_bf16 v[36:39], v[196:199], v[180:183], v[40:43]
	v_mfma_f32_16x16x32_bf16 v[96:99], v[192:195], v[124:127], v[96:99]
	v_mfma_f32_16x16x32_bf16 v[16:19], v[210:213], v[124:127], v[16:19]
	v_mfma_f32_16x16x32_bf16 v[20:23], v[192:195], v[168:171], v[20:23]
	v_mfma_f32_16x16x32_bf16 v[24:27], v[210:213], v[168:171], v[24:27]
	v_mfma_f32_16x16x32_bf16 v[28:31], v[192:195], v[176:179], v[28:31]
	v_mfma_f32_16x16x32_bf16 v[32:35], v[210:213], v[176:179], v[32:35]
	v_mfma_f32_16x16x32_bf16 v[168:171], v[210:213], v[184:187], v[36:39]
	s_mov_b32 m0, s4
	v_lshl_add_u64 v[246:247], s[66:67], 0, v[140:141]
	s_barrier
	ds_read_b128 v[36:39], v206 offset:16384
	ds_read_b128 v[40:43], v206 offset:17408
	ds_read_b128 v[120:123], v206 offset:18432
	ds_read_b128 v[124:127], v206 offset:19456
	ds_read_b128 v[172:175], v206 offset:20480
	ds_read_b128 v[176:179], v206 offset:21504
	ds_read_b128 v[180:183], v206 offset:22528
	ds_read_b128 v[184:187], v206 offset:23552
	global_load_lds_dwordx4 v[246:247], off
	v_lshl_add_u64 v[248:249], s[66:67], 0, v[144:145]
	s_mov_b32 m0, s5
	s_nop 0
	global_load_lds_dwordx4 v[248:249], off
	s_barrier
	s_waitcnt lgkmcnt(0)
	s_waitcnt lgkmcnt(0)
	v_mfma_f32_16x16x32_bf16 v[128:131], v[104:107], v[36:39], v[128:131]
	v_mfma_f32_16x16x32_bf16 v[214:217], v[108:111], v[40:43], v[128:131]
	v_mfma_f32_16x16x32_bf16 v[128:131], v[112:115], v[36:39], v[132:135]
	v_mfma_f32_16x16x32_bf16 v[218:221], v[116:119], v[40:43], v[128:131]
	v_mfma_f32_16x16x32_bf16 v[128:131], v[104:107], v[120:123], v[136:139]
	v_mfma_f32_16x16x32_bf16 v[222:225], v[108:111], v[124:127], v[128:131]
	v_mfma_f32_16x16x32_bf16 v[128:131], v[112:115], v[120:123], v[152:155]
	v_mfma_f32_16x16x32_bf16 v[152:155], v[116:119], v[124:127], v[128:131]
	v_mfma_f32_16x16x32_bf16 v[128:131], v[104:107], v[172:175], v[156:159]
	v_mfma_f32_16x16x32_bf16 v[156:159], v[108:111], v[176:179], v[128:131]
	v_mfma_f32_16x16x32_bf16 v[128:131], v[112:115], v[172:175], v[160:163]
	v_mfma_f32_16x16x32_bf16 v[0:3], v[104:107], v[180:183], v[0:3]
	v_mfma_f32_16x16x32_bf16 v[4:7], v[112:115], v[180:183], v[4:7]
	v_mfma_f32_16x16x32_bf16 v[160:163], v[116:119], v[176:179], v[128:131]
	v_mfma_f32_16x16x32_bf16 v[0:3], v[108:111], v[184:187], v[0:3]
	v_mfma_f32_16x16x32_bf16 v[4:7], v[116:119], v[184:187], v[4:7]
	s_barrier
	s_add_u32 s60, s64, 0x10000
	s_addc_u32 s61, s65, 0
	s_mov_b32 m0, s77
	v_lshl_add_u64 v[104:105], s[60:61], 0, v[142:143]
	global_load_lds_dwordx4 v[104:105], off
	v_lshl_add_u64 v[104:105], s[60:61], 0, v[146:147]
	s_mov_b32 m0, s57
	s_nop 0
	global_load_lds_dwordx4 v[104:105], off
	s_waitcnt vmcnt(6)
	s_barrier
	v_mfma_f32_16x16x32_bf16 v[12:15], v[196:199], v[36:39], v[12:15]
	v_mfma_f32_16x16x32_bf16 v[226:229], v[210:213], v[40:43], v[12:15]
	v_mfma_f32_16x16x32_bf16 v[12:15], v[60:63], v[120:123], v[44:47]
	v_mfma_f32_16x16x32_bf16 v[230:233], v[192:195], v[124:127], v[12:15]
	v_mfma_f32_16x16x32_bf16 v[12:15], v[196:199], v[120:123], v[88:91]
	v_mfma_f32_16x16x32_bf16 v[234:237], v[210:213], v[124:127], v[12:15]
	v_mfma_f32_16x16x32_bf16 v[12:15], v[60:63], v[172:175], v[92:95]
	v_mfma_f32_16x16x32_bf16 v[238:241], v[192:195], v[176:179], v[12:15]
	v_mfma_f32_16x16x32_bf16 v[12:15], v[196:199], v[172:175], v[100:103]
	v_mfma_f32_16x16x32_bf16 v[172:175], v[210:213], v[176:179], v[12:15]
	v_mfma_f32_16x16x32_bf16 v[12:15], v[60:63], v[180:183], v[80:83]
	v_mfma_f32_16x16x32_bf16 v[8:11], v[60:63], v[36:39], v[8:11]
	v_mfma_f32_16x16x32_bf16 v[80:83], v[192:195], v[184:187], v[12:15]
	v_mfma_f32_16x16x32_bf16 v[12:15], v[196:199], v[180:183], v[84:87]
	v_mfma_f32_16x16x32_bf16 v[8:11], v[192:195], v[40:43], v[8:11]
	v_mfma_f32_16x16x32_bf16 v[176:179], v[210:213], v[184:187], v[12:15]
	s_barrier
	ds_read_b128 v[84:87], v209
	ds_read_b128 v[92:95], v209 offset:1024
	ds_read_b128 v[100:103], v209 offset:2048
	ds_read_b128 v[180:183], v209 offset:3072
	s_add_u32 s60, s66, 0x80000
	s_addc_u32 s61, s67, 0
	s_mov_b32 m0, s22
	v_lshl_add_u64 v[36:37], s[60:61], 0, v[140:141]
	ds_read_b128 v[12:15], v206 offset:32768
	ds_read_b128 v[40:43], v206 offset:33792
	ds_read_b128 v[88:91], v206 offset:34816
	ds_read_b128 v[104:107], v206 offset:35840
	ds_read_b128 v[108:111], v206 offset:36864
	ds_read_b128 v[184:187], v206 offset:37888
	ds_read_b128 v[192:195], v206 offset:38912
	ds_read_b128 v[196:199], v206 offset:39936
	global_load_lds_dwordx4 v[36:37], off
	v_lshl_add_u64 v[36:37], s[60:61], 0, v[144:145]
	s_mov_b32 m0, s23
	s_nop 0
	global_load_lds_dwordx4 v[36:37], off
	s_waitcnt lgkmcnt(8)
	s_barrier
; #define PG8_STAGE(bufoff, gbase, voff) do { _Pragma("unroll") for (int _i = 0; _i < 2; ++_i) \
;         __builtin_amdgcn_global_load_lds((const unsigned*)((const char*)(gbase) + (voff)[_i]), (LAS unsigned*)(lds + (bufoff) + ldsw + _i * 8192), 16, 0, 0); } while (0)
; #define PG8_LDA(dst, b, h) do { _Pragma("unroll") for (int m = 0; m < 4; ++m) _Pragma("unroll") for (int k = 0; k < 2; ++k) dst[m][k] = *(const LAS bf16x8*)(lds + PG8_SA(b, h) + aoff + m * 2048 + k * 1024); } while (0)
; #define PG8_LDB(dst, b, h) do { _Pragma("unroll") for (int n = 0; n < 2; ++n) _Pragma("unroll") for (int k = 0; k < 2; ++k) dst[n][k] = *(const LAS bf16x8*)(lds + PG8_SB(b, h) + boff + n * 2048 + k * 1024); } while (0)
; #define PG8_MMA(ai, bj, At, Bt) do { __builtin_amdgcn_s_setprio(1); _Pragma("unroll") for (int m = 0; m < 4; ++m) _Pragma("unroll") for (int n = 0; n < 2; ++n) _Pragma("unroll") for (int k = 0; k < 2; ++k) \
;         acc[ai][bj][m][n] = __builtin_amdgcn_mfma_f32_16x16x32_bf16(Bt[n][k], At[m][k], acc[ai][bj][m][n], 0, 0, 0); __builtin_amdgcn_s_setprio(0); } while (0)
; template <class Epi>
; __device__ __forceinline__ void gemm_phase(LAS unsigned char* lds, const Gemm g, const StaticOrder& S, const Epi& E, int wv) {
;     ...
;             PG8_WAIT_V(6); PG8_BAR; PG8_MMA(1, 1, At, B1); PG8_BAR;
;             PG8_LDB(B0, 1, 0); PG8_SCHED; PG8_LDA(At, 1, 0); PG8_STAGE(PG8_SA(0, 1), a2 + hstepA, voffA);
;             PG8_WAIT_L(8); PG8_BAR; PG8_WAIT_L(0); PG8_MMA(0, 0, At, B0); PG8_BAR; PG8_SCHED;
;             PG8_LDB(B1, 1, 1); PG8_STAGE(PG8_SB(1, 0), b3, voffB);
;             PG8_BAR; PG8_WAIT_L(0); PG8_MMA(0, 1, At, B1); PG8_BAR;
;             PG8_LDA(At, 1, 1); PG8_STAGE(PG8_SA(1, 0), a3, voffA);
;             PG8_BAR; PG8_WAIT_L(0); PG8_MMA(1, 0, At, B0); PG8_BAR; PG8_SCHED;
;             PG8_STAGE(PG8_SB(1, 1), b3 + hstepB, voffB);
;             PG8_WAIT_V(6); PG8_BAR; PG8_MMA(1, 1, At, B1); PG8_BAR;
;     __device__ __forceinline__ void operator()(const f32x4 (&acc)[2][2][4][2], const Unit& u, int wr, int wc, int fr, int fq) const {
;         const int row0 = u.pm * BM + wr * 64 + fr, ch0 = u.pn * HALF + wc * 32 + 4 * fq;
; #pragma unroll
;         for (int n = 0; n < 2; ++n) {
;             const f32x4 ba = *(const f32x4*)(b_ga + ch0 + n * 16), bx = *(const f32x4*)(b_gx + ch0 + n * 16), sp = *(const f32x4*)(lam + ch0 + n * 16);
	s_waitcnt lgkmcnt(0)
	s_waitcnt lgkmcnt(0)
	v_mfma_f32_16x16x32_bf16 v[36:39], v[84:87], v[12:15], v[48:51]
	v_mfma_f32_16x16x32_bf16 v[136:139], v[92:95], v[40:43], v[36:39]
	v_mfma_f32_16x16x32_bf16 v[36:39], v[100:103], v[12:15], v[52:55]
	v_mfma_f32_16x16x32_bf16 v[60:63], v[180:183], v[40:43], v[36:39]
	v_mfma_f32_16x16x32_bf16 v[36:39], v[84:87], v[88:91], v[56:59]
	v_mfma_f32_16x16x32_bf16 v[128:131], v[92:95], v[104:107], v[36:39]
	v_mfma_f32_16x16x32_bf16 v[36:39], v[100:103], v[88:91], v[188:191]
	v_mfma_f32_16x16x32_bf16 v[52:55], v[180:183], v[104:107], v[36:39]
	v_mfma_f32_16x16x32_bf16 v[36:39], v[84:87], v[108:111], v[64:67]
	v_mfma_f32_16x16x32_bf16 v[120:123], v[92:95], v[184:187], v[36:39]
	v_mfma_f32_16x16x32_bf16 v[36:39], v[100:103], v[108:111], v[68:71]
	v_mfma_f32_16x16x32_bf16 v[44:47], v[180:183], v[184:187], v[36:39]
	v_mfma_f32_16x16x32_bf16 v[36:39], v[84:87], v[192:195], v[72:75]
	v_mfma_f32_16x16x32_bf16 v[112:115], v[92:95], v[196:199], v[36:39]
	v_mfma_f32_16x16x32_bf16 v[36:39], v[100:103], v[192:195], v[76:79]
	v_mfma_f32_16x16x32_bf16 v[36:39], v[180:183], v[196:199], v[36:39]
	s_barrier
	s_mov_b32 m0, s80
	v_lshl_add_u64 v[48:49], v[200:201], 0, s[34:35]
	ds_read_b128 v[64:67], v250
	ds_read_b128 v[68:71], v250 offset:1024
	ds_read_b128 v[76:79], v250 offset:2048
	ds_read_b128 v[188:191], v250 offset:3072
	global_load_lds_dwordx4 v[48:49], off
	v_lshl_add_u64 v[48:49], v[242:243], 0, s[34:35]
	s_mov_b32 m0, s78
	s_nop 0
	global_load_lds_dwordx4 v[48:49], off
	s_barrier
	s_waitcnt lgkmcnt(0)
	s_waitcnt lgkmcnt(0)
	v_mfma_f32_16x16x32_bf16 v[48:51], v[64:67], v[12:15], v[96:99]
	v_mfma_f32_16x16x32_bf16 v[12:15], v[76:79], v[12:15], v[16:19]
	v_mfma_f32_16x16x32_bf16 v[56:59], v[188:191], v[40:43], v[12:15]
	v_mfma_f32_16x16x32_bf16 v[12:15], v[64:67], v[88:91], v[20:23]
	v_mfma_f32_16x16x32_bf16 v[124:127], v[68:71], v[104:107], v[12:15]
	v_mfma_f32_16x16x32_bf16 v[12:15], v[76:79], v[88:91], v[24:27]
	v_mfma_f32_16x16x32_bf16 v[132:135], v[68:71], v[40:43], v[48:51]
	v_mfma_f32_16x16x32_bf16 v[48:51], v[188:191], v[104:107], v[12:15]
	v_mfma_f32_16x16x32_bf16 v[12:15], v[64:67], v[108:111], v[28:31]
	v_mfma_f32_16x16x32_bf16 v[116:119], v[68:71], v[184:187], v[12:15]
	v_mfma_f32_16x16x32_bf16 v[12:15], v[76:79], v[108:111], v[32:35]
	v_mfma_f32_16x16x32_bf16 v[40:43], v[188:191], v[184:187], v[12:15]
	v_mfma_f32_16x16x32_bf16 v[12:15], v[64:67], v[192:195], v[164:167]
	v_mfma_f32_16x16x32_bf16 v[108:111], v[68:71], v[196:199], v[12:15]
	v_mfma_f32_16x16x32_bf16 v[12:15], v[76:79], v[192:195], v[168:171]
	v_mfma_f32_16x16x32_bf16 v[32:35], v[188:191], v[196:199], v[12:15]
	s_mov_b32 m0, s24
	s_nop 4
	v_lshl_add_u64 v[12:13], v[246:247], 0, s[34:35]
	s_barrier
	ds_read_b128 v[16:19], v206 offset:49152
	ds_read_b128 v[24:27], v206 offset:50176
	ds_read_b128 v[164:167], v206 offset:51200
	ds_read_b128 v[168:171], v206 offset:52224
	ds_read_b128 v[184:187], v206 offset:53248
	ds_read_b128 v[192:195], v206 offset:54272
	ds_read_b128 v[196:199], v206 offset:55296
	ds_read_b128 v[210:213], v206 offset:56320
	global_load_lds_dwordx4 v[12:13], off
	v_lshl_add_u64 v[12:13], v[248:249], 0, s[34:35]
	s_mov_b32 m0, s25
	s_nop 0
	global_load_lds_dwordx4 v[12:13], off
	s_barrier
	s_waitcnt lgkmcnt(0)
	s_waitcnt lgkmcnt(0)
	v_mfma_f32_16x16x32_bf16 v[12:15], v[84:87], v[16:19], v[214:217]
	v_mfma_f32_16x16x32_bf16 v[104:107], v[92:95], v[24:27], v[12:15]
	v_mfma_f32_16x16x32_bf16 v[12:15], v[100:103], v[16:19], v[218:221]
	v_mfma_f32_16x16x32_bf16 v[28:31], v[180:183], v[24:27], v[12:15]
	v_mfma_f32_16x16x32_bf16 v[12:15], v[84:87], v[164:167], v[222:225]
	v_mfma_f32_16x16x32_bf16 v[96:99], v[92:95], v[168:171], v[12:15]
	v_mfma_f32_16x16x32_bf16 v[12:15], v[100:103], v[164:167], v[152:155]
	v_mfma_f32_16x16x32_bf16 v[20:23], v[180:183], v[168:171], v[12:15]
	v_mfma_f32_16x16x32_bf16 v[12:15], v[84:87], v[184:187], v[156:159]
	v_mfma_f32_16x16x32_bf16 v[0:3], v[84:87], v[196:199], v[0:3]
	v_mfma_f32_16x16x32_bf16 v[88:91], v[92:95], v[192:195], v[12:15]
	v_mfma_f32_16x16x32_bf16 v[12:15], v[100:103], v[184:187], v[160:163]
	v_mfma_f32_16x16x32_bf16 v[72:75], v[92:95], v[210:213], v[0:3]
	v_mfma_f32_16x16x32_bf16 v[0:3], v[100:103], v[196:199], v[4:7]
	v_mfma_f32_16x16x32_bf16 v[12:15], v[180:183], v[192:195], v[12:15]
	v_mfma_f32_16x16x32_bf16 v[4:7], v[180:183], v[210:213], v[0:3]
	s_barrier
	s_add_u32 s60, s64, 0x10080
	s_addc_u32 s61, s65, 0
	s_mov_b32 m0, s63
	s_nop 0
	v_lshl_add_u64 v[0:1], s[60:61], 0, v[142:143]
	global_load_lds_dwordx4 v[0:1], off
	v_lshl_add_u64 v[0:1], s[60:61], 0, v[146:147]
	s_mov_b32 m0, s62
	s_nop 0
	global_load_lds_dwordx4 v[0:1], off
	s_waitcnt vmcnt(6)
	s_barrier
	v_mfma_f32_16x16x32_bf16 v[0:3], v[64:67], v[16:19], v[8:11]
	v_mfma_f32_16x16x32_bf16 v[100:103], v[68:71], v[24:27], v[0:3]
	v_mfma_f32_16x16x32_bf16 v[0:3], v[76:79], v[16:19], v[226:229]
	v_mfma_f32_16x16x32_bf16 v[24:27], v[188:191], v[24:27], v[0:3]
	v_mfma_f32_16x16x32_bf16 v[0:3], v[64:67], v[164:167], v[230:233]
	v_mfma_f32_16x16x32_bf16 v[92:95], v[68:71], v[168:171], v[0:3]
	v_mfma_f32_16x16x32_bf16 v[0:3], v[76:79], v[164:167], v[234:237]
	v_mfma_f32_16x16x32_bf16 v[16:19], v[188:191], v[168:171], v[0:3]
	v_mfma_f32_16x16x32_bf16 v[0:3], v[64:67], v[184:187], v[238:241]
	v_mfma_f32_16x16x32_bf16 v[84:87], v[68:71], v[192:195], v[0:3]
	v_mfma_f32_16x16x32_bf16 v[0:3], v[76:79], v[184:187], v[172:175]
	v_mfma_f32_16x16x32_bf16 v[8:11], v[188:191], v[192:195], v[0:3]
	v_mfma_f32_16x16x32_bf16 v[0:3], v[64:67], v[196:199], v[80:83]
	v_mfma_f32_16x16x32_bf16 v[64:67], v[68:71], v[210:213], v[0:3]
	v_mfma_f32_16x16x32_bf16 v[0:3], v[76:79], v[196:199], v[176:179]
	v_mfma_f32_16x16x32_bf16 v[0:3], v[188:191], v[210:213], v[0:3]
	v_lshl_or_b32 v152, s58, 7, v204
	v_ashrrev_i32_e32 v153, 31, v152
	v_lshlrev_b64 v[76:77], 2, v[152:153]
	v_lshl_add_u64 v[154:155], s[8:9], 0, v[76:77]
	s_barrier
; __device__ __forceinline__ float bf_lo(unsigned w) { return __uint_as_float(w << 16); }
; __device__ __forceinline__ float bf_hi(unsigned w) { return __uint_as_float(w & 0xffff0000u); }
; __device__ __forceinline__ float fast_sigmoid(float x) { return __builtin_amdgcn_rcpf(1.0f + __builtin_amdgcn_exp2f(-x * LOG2E)); }
;     __device__ __forceinline__ void operator()(const f32x4 (&acc)[2][2][4][2], const Unit& u, int wr, int wc, int fr, int fq) const {
;     ...
;             const f32x4 ba = *(const f32x4*)(b_ga + ch0 + n * 16), bx = *(const f32x4*)(b_gx + ch0 + n * 16), sp = *(const f32x4*)(lam + ch0 + n * 16);
;             u32x2 xall[8];
; #pragma unroll
;             for (int it = 0; it < 8; ++it) xall[it] = *(const u32x2*)(xc + (size_t)(row0 + (it >> 2) * HALF + (it & 3) * 16) * DM + ch0 + n * 16);
;             asm volatile("" ::: "memory");
; #pragma unroll
;             for (int ai = 0; ai < 2; ++ai)
; #pragma unroll
;                 for (int m = 0; m < 4; ++m) { const int row = row0 + ai * HALF + m * 16; const size_t off = (size_t)row * DM + ch0 + n * 16;
;                     const u32x2 xw = xall[ai * 4 + m];
;                     const float xv[4] = {bf_lo(xw.x), bf_hi(xw.x), bf_lo(xw.y), bf_hi(xw.y)};
;                     f32x4 av; float bv[4];
; #pragma unroll
;                     for (int j = 0; j < 4; ++j) { const float r = fast_sigmoid(acc[ai][0][m][n][j] + ba[j]), ig = fast_sigmoid(acc[ai][1][m][n][j] + bx[j]);
;                         const float la = sp[j] * r; const float la2 = __uint_as_float(pk_bf16(la * LOG2E, 0.f) << 16);
;                         const float a = __builtin_amdgcn_exp2f(la2); const float x2 = 2.0f * la2 * 0.6931471805599453f; av[j] = la2;
;                         const float om = (x2 > -0.03f) ? -(x2 * (1.0f + x2 * (0.5f + x2 * (1.0f / 6.0f + x2 * (1.0f / 24.0f))))) : (1.0f - a * a);
;                         bv[j] = __builtin_amdgcn_sqrtf(om) * (ig * xv[j]); }
	global_load_dwordx4 v[80:83], v[154:155], off
	v_lshl_add_u64 v[158:159], s[14:15], 0, v[76:77]
	v_lshl_add_u32 v164, s56, 8, v202
	v_lshl_add_u64 v[156:157], s[10:11], 0, v[76:77]
	global_load_dwordx4 v[76:79], v[158:159], off
	v_add_u32_e32 v184, 0x80, v164
	v_ashrrev_i32_e32 v165, 31, v164
	v_or_b32_e32 v196, 16, v164
	v_or_b32_e32 v192, 32, v164
	v_or_b32_e32 v188, 48, v164
	v_ashrrev_i32_e32 v185, 31, v184
	v_add_u32_e32 v172, 0x90, v164
	v_add_u32_e32 v174, 0xa0, v164
	v_add_u32_e32 v178, 0xb0, v164
	v_lshl_add_u64 v[176:177], v[152:153], 1, s[12:13]
	v_lshlrev_b64 v[160:161], 12, v[164:165]
	v_ashrrev_i32_e32 v197, 31, v196
	v_ashrrev_i32_e32 v193, 31, v192
	v_ashrrev_i32_e32 v189, 31, v188
	v_lshlrev_b64 v[170:171], 12, v[184:185]
	v_ashrrev_i32_e32 v173, 31, v172
	v_ashrrev_i32_e32 v175, 31, v174
	v_ashrrev_i32_e32 v179, 31, v178
	v_lshl_add_u64 v[160:161], v[176:177], 0, v[160:161]
	v_lshlrev_b64 v[162:163], 12, v[196:197]
	v_lshlrev_b64 v[166:167], 12, v[192:193]
	v_lshlrev_b64 v[168:169], 12, v[188:189]
	v_lshl_add_u64 v[170:171], v[176:177], 0, v[170:171]
	v_lshlrev_b64 v[172:173], 12, v[172:173]
	v_lshlrev_b64 v[174:175], 12, v[174:175]
	v_lshlrev_b64 v[178:179], 12, v[178:179]
	global_load_dwordx4 v[68:71], v[156:157], off
	v_lshl_add_u64 v[162:163], v[176:177], 0, v[162:163]
	v_lshl_add_u64 v[166:167], v[176:177], 0, v[166:167]
	v_lshl_add_u64 v[168:169], v[176:177], 0, v[168:169]
	global_load_dwordx2 v[200:201], v[160:161], off
	global_load_dwordx2 v[198:199], v[162:163], off
	global_load_dwordx2 v[194:195], v[166:167], off
	global_load_dwordx2 v[190:191], v[168:169], off
	v_lshl_add_u64 v[172:173], v[176:177], 0, v[172:173]
	v_lshl_add_u64 v[174:175], v[176:177], 0, v[174:175]
	v_lshl_add_u64 v[176:177], v[176:177], 0, v[178:179]
	global_load_dwordx2 v[186:187], v[170:171], off
	global_load_dwordx2 v[182:183], v[172:173], off
	global_load_dwordx2 v[180:181], v[174:175], off
	global_load_dwordx2 v[178:179], v[176:177], off
	s_waitcnt vmcnt(0)
	v_add_f32_e32 v136, v136, v80
	v_mul_f32_e32 v136, 0xbfb8aa3b, v136
	v_exp_f32_e32 v136, v136
	s_nop 0
	v_add_f32_e32 v136, 1.0, v136
	v_rcp_f32_e32 v136, v136
	s_nop 0
	v_mul_f32_e32 v136, v76, v136
	v_mul_f32_e32 v136, 0x3fb8aa3b, v136
	v_cvt_pk_bf16_f32 v136, v136, 0
	v_lshlrev_b32_e32 v136, 16, v136
	v_add_f32_e32 v209, v136, v136
	v_mul_f32_e32 v210, 0x3f317218, v209
	v_cmp_nlt_f32_e32 vcc, s74, v210
	s_and_saveexec_b64 s[56:57], vcc
	s_xor_b64 s[56:57], exec, s[56:57]
	v_exp_f32_e32 v209, v136
	s_nop 0
	v_fma_f32 v209, -v209, v209, 1.0
	s_andn2_saveexec_b64 s[56:57], s[56:57]
	v_fmamk_f32 v209, v210, 0x3d2aaaab, v208
	v_fma_f32 v209, v210, v209, 0.5
	v_fma_f32 v209, v210, v209, 1.0
	v_mul_f32_e64 v209, v210, -v209
	s_or_b64 exec, exec, s[56:57]
	v_add_f32_e32 v137, v137, v81
	v_mul_f32_e32 v137, 0xbfb8aa3b, v137
	v_exp_f32_e32 v137, v137
	s_nop 0
	v_add_f32_e32 v137, 1.0, v137
	v_rcp_f32_e32 v137, v137
	s_nop 0
	v_mul_f32_e32 v137, v77, v137
	v_mul_f32_e32 v137, 0x3fb8aa3b, v137
	v_cvt_pk_bf16_f32 v137, v137, 0
	v_lshlrev_b32_e32 v137, 16, v137
	v_add_f32_e32 v210, v137, v137
	v_mul_f32_e32 v211, 0x3f317218, v210
	v_cmp_nlt_f32_e32 vcc, s74, v211
	s_and_saveexec_b64 s[56:57], vcc
	s_xor_b64 s[56:57], exec, s[56:57]
	v_exp_f32_e32 v210, v137
	s_nop 0
	v_fma_f32 v210, -v210, v210, 1.0
	s_andn2_saveexec_b64 s[56:57], s[56:57]
	v_fmamk_f32 v210, v211, 0x3d2aaaab, v208
	v_fma_f32 v210, v211, v210, 0.5
	v_fma_f32 v210, v211, v210, 1.0
	v_mul_f32_e64 v210, v211, -v210
	s_or_b64 exec, exec, s[56:57]
	v_add_f32_e32 v138, v138, v82
	v_mul_f32_e32 v138, 0xbfb8aa3b, v138
	v_exp_f32_e32 v138, v138
	s_nop 0
	v_add_f32_e32 v138, 1.0, v138
	v_rcp_f32_e32 v138, v138
	s_nop 0
	v_mul_f32_e32 v138, v78, v138
	v_mul_f32_e32 v138, 0x3fb8aa3b, v138
	v_cvt_pk_bf16_f32 v138, v138, 0
	v_lshlrev_b32_e32 v138, 16, v138
	v_add_f32_e32 v211, v138, v138
	v_mul_f32_e32 v212, 0x3f317218, v211
	v_cmp_nlt_f32_e32 vcc, s74, v212
	s_and_saveexec_b64 s[56:57], vcc
	s_xor_b64 s[56:57], exec, s[56:57]
	v_exp_f32_e32 v211, v138
	s_nop 0
	v_fma_f32 v211, -v211, v211, 1.0
	s_andn2_saveexec_b64 s[56:57], s[56:57]
	v_fmamk_f32 v211, v212, 0x3d2aaaab, v208
	v_fma_f32 v211, v212, v211, 0.5
	v_fma_f32 v211, v212, v211, 1.0
	v_mul_f32_e64 v211, v212, -v211
	s_or_b64 exec, exec, s[56:57]
	v_add_f32_e32 v139, v139, v83
	v_mul_f32_e32 v139, 0xbfb8aa3b, v139
	v_exp_f32_e32 v139, v139
	s_nop 0
	v_add_f32_e32 v139, 1.0, v139
	v_rcp_f32_e32 v139, v139
	s_nop 0
	v_mul_f32_e32 v139, v79, v139
	v_mul_f32_e32 v139, 0x3fb8aa3b, v139
	v_cvt_pk_bf16_f32 v139, v139, 0
	v_lshlrev_b32_e32 v139, 16, v139
	v_add_f32_e32 v212, v139, v139
	v_mul_f32_e32 v213, 0x3f317218, v212
	v_cmp_nlt_f32_e32 vcc, s74, v213
	s_and_saveexec_b64 s[56:57], vcc
	s_xor_b64 s[56:57], exec, s[56:57]
	v_exp_f32_e32 v212, v139
	s_nop 0
	v_fma_f32 v212, -v212, v212, 1.0
	s_andn2_saveexec_b64 s[56:57], s[56:57]
	v_fmamk_f32 v212, v213, 0x3d2aaaab, v208
	v_fma_f32 v212, v213, v212, 0.5
	v_fma_f32 v212, v213, v212, 1.0
	v_mul_f32_e64 v212, v213, -v212
	s_or_b64 exec, exec, s[56:57]
	v_add_f32_e32 v134, v134, v70
	v_mul_f32_e32 v134, 0xbfb8aa3b, v134
	v_exp_f32_e32 v134, v134
	v_add_f32_e32 v132, v132, v68
	v_mul_f32_e32 v132, 0xbfb8aa3b, v132
	v_exp_f32_e32 v132, v132
	v_add_f32_e32 v133, v133, v69
	v_add_f32_e32 v135, v135, v71
	v_add_f32_e32 v134, 1.0, v134
	v_mul_f32_e32 v133, 0xbfb8aa3b, v133
	v_rcp_f32_e32 v134, v134
	v_mul_f32_e32 v135, 0xbfb8aa3b, v135
	v_exp_f32_e32 v133, v133
	v_sqrt_f32_e32 v211, v211
	v_exp_f32_e32 v135, v135
	v_add_f32_e32 v132, 1.0, v132
	v_rcp_f32_e32 v132, v132
	v_lshlrev_b32_e32 v213, 16, v201
	v_add_f32_e32 v128, v128, v80
; __device__ __forceinline__ float bf_lo(unsigned w) { return __uint_as_float(w << 16); }
; __device__ __forceinline__ float bf_hi(unsigned w) { return __uint_as_float(w & 0xffff0000u); }
; __device__ __forceinline__ float fast_sigmoid(float x) { return __builtin_amdgcn_rcpf(1.0f + __builtin_amdgcn_exp2f(-x * LOG2E)); }
;     __device__ __forceinline__ void operator()(const f32x4 (&acc)[2][2][4][2], const Unit& u, int wr, int wc, int fr, int fq) const {
;     ...
;                 for (int m = 0; m < 4; ++m) { const int row = row0 + ai * HALF + m * 16; const size_t off = (size_t)row * DM + ch0 + n * 16;
;                     const u32x2 xw = xall[ai * 4 + m];
;                     const float xv[4] = {bf_lo(xw.x), bf_hi(xw.x), bf_lo(xw.y), bf_hi(xw.y)};
;                     f32x4 av; float bv[4];
; #pragma unroll
;                     for (int j = 0; j < 4; ++j) { const float r = fast_sigmoid(acc[ai][0][m][n][j] + ba[j]), ig = fast_sigmoid(acc[ai][1][m][n][j] + bx[j]);
;                         const float la = sp[j] * r; const float la2 = __uint_as_float(pk_bf16(la * LOG2E, 0.f) << 16);
;                         const float a = __builtin_amdgcn_exp2f(la2); const float x2 = 2.0f * la2 * 0.6931471805599453f; av[j] = la2;
;                         const float om = (x2 > -0.03f) ? -(x2 * (1.0f + x2 * (0.5f + x2 * (1.0f / 6.0f + x2 * (1.0f / 24.0f))))) : (1.0f - a * a);
;                         bv[j] = __builtin_amdgcn_sqrtf(om) * (ig * xv[j]); }
;                     { u32x2 wa; wa.x = pk_bf16(av[0], av[1]); wa.y = pk_bf16(av[2], av[3]); *(u32x2*)(aout + off) = wa; }
;                     u32x2 w; w.x = pk_bf16(bv[0], bv[1]); w.y = pk_bf16(bv[2], bv[3]); *(u32x2*)(bout + off) = w; }
	v_mul_f32_e32 v134, v134, v213
	v_sqrt_f32_e32 v209, v209
	v_add_f32_e32 v133, 1.0, v133
	v_mul_f32_e32 v128, 0xbfb8aa3b, v128
	v_mul_f32_e32 v211, v134, v211
	v_add_f32_e32 v134, 1.0, v135
	v_lshlrev_b32_e32 v135, 16, v200
	v_rcp_f32_e32 v133, v133
	v_exp_f32_e32 v128, v128
	v_mul_f32_e32 v132, v132, v135
	v_sqrt_f32_e32 v135, v210
	v_mul_f32_e32 v209, v132, v209
	v_and_b32_e32 v132, 0xffff0000, v200
	v_rcp_f32_e32 v134, v134
	v_mul_f32_e32 v132, v133, v132
	v_add_f32_e32 v128, 1.0, v128
	v_mul_f32_e32 v200, v132, v135
	v_sqrt_f32_e32 v135, v212
	v_rcp_f32_e32 v128, v128
	v_and_b32_e32 v201, 0xffff0000, v201
	v_lshlrev_b64 v[132:133], 11, v[164:165]
	v_mul_f32_e32 v134, v134, v201
	v_mul_f32_e32 v201, v134, v135
	v_lshl_add_u64 v[134:135], v[132:133], 0, v[152:153]
	v_mul_f32_e32 v128, v76, v128
	v_lshlrev_b64 v[134:135], 1, v[134:135]
	v_mul_f32_e32 v128, 0x3fb8aa3b, v128
	v_cvt_pk_bf16_f32 v136, v136, v137
	v_cvt_pk_bf16_f32 v137, v138, v139
	v_lshl_add_u64 v[138:139], s[16:17], 0, v[134:135]
	v_cvt_pk_bf16_f32 v128, v128, 0
	global_store_dwordx2 v[138:139], v[136:137], off
	v_cvt_pk_bf16_f32 v136, v209, v200
	v_cvt_pk_bf16_f32 v137, v211, v201
	v_lshl_add_u64 v[134:135], s[18:19], 0, v[134:135]
	v_lshlrev_b32_e32 v128, 16, v128
	global_store_dwordx2 v[134:135], v[136:137], off
	v_add_f32_e32 v134, v128, v128
	v_mul_f32_e32 v135, 0x3f317218, v134
	v_cmp_nlt_f32_e32 vcc, s74, v135
	s_and_saveexec_b64 s[56:57], vcc
	s_xor_b64 s[56:57], exec, s[56:57]
	v_exp_f32_e32 v134, v128
	s_nop 0
	v_fma_f32 v134, -v134, v134, 1.0
	s_andn2_saveexec_b64 s[56:57], s[56:57]
	v_fmamk_f32 v134, v135, 0x3d2aaaab, v208
	v_fma_f32 v134, v135, v134, 0.5
	v_fma_f32 v134, v135, v134, 1.0
	v_mul_f32_e64 v134, v135, -v134
	s_or_b64 exec, exec, s[56:57]
	v_add_f32_e32 v129, v129, v81
	v_mul_f32_e32 v129, 0xbfb8aa3b, v129
	v_exp_f32_e32 v129, v129
	s_nop 0
	v_add_f32_e32 v129, 1.0, v129
	v_rcp_f32_e32 v129, v129
	s_nop 0
	v_mul_f32_e32 v129, v77, v129
	v_mul_f32_e32 v129, 0x3fb8aa3b, v129
	v_cvt_pk_bf16_f32 v129, v129, 0
	v_lshlrev_b32_e32 v129, 16, v129
	v_add_f32_e32 v135, v129, v129
	v_mul_f32_e32 v136, 0x3f317218, v135
	v_cmp_nlt_f32_e32 vcc, s74, v136
	s_and_saveexec_b64 s[56:57], vcc
	s_xor_b64 s[56:57], exec, s[56:57]
	v_exp_f32_e32 v135, v129
	s_nop 0
	v_fma_f32 v135, -v135, v135, 1.0
	s_andn2_saveexec_b64 s[56:57], s[56:57]
	v_fmamk_f32 v135, v136, 0x3d2aaaab, v208
	v_fma_f32 v135, v136, v135, 0.5
	v_fma_f32 v135, v136, v135, 1.0
	v_mul_f32_e64 v135, v136, -v135
	s_or_b64 exec, exec, s[56:57]
	v_add_f32_e32 v130, v130, v82
	v_mul_f32_e32 v130, 0xbfb8aa3b, v130
	v_exp_f32_e32 v130, v130
	s_nop 0
	v_add_f32_e32 v130, 1.0, v130
	v_rcp_f32_e32 v130, v130
	s_nop 0
	v_mul_f32_e32 v130, v78, v130
	v_mul_f32_e32 v130, 0x3fb8aa3b, v130
	v_cvt_pk_bf16_f32 v130, v130, 0
	v_lshlrev_b32_e32 v130, 16, v130
	v_add_f32_e32 v136, v130, v130
	v_mul_f32_e32 v137, 0x3f317218, v136
	v_cmp_nlt_f32_e32 vcc, s74, v137
	s_and_saveexec_b64 s[56:57], vcc
	s_xor_b64 s[56:57], exec, s[56:57]
	v_exp_f32_e32 v136, v130
	s_nop 0
	v_fma_f32 v136, -v136, v136, 1.0
	s_andn2_saveexec_b64 s[56:57], s[56:57]
	v_fmamk_f32 v136, v137, 0x3d2aaaab, v208
	v_fma_f32 v136, v137, v136, 0.5
	v_fma_f32 v136, v137, v136, 1.0
	v_mul_f32_e64 v136, v137, -v136
	s_or_b64 exec, exec, s[56:57]
	v_add_f32_e32 v131, v131, v83
	v_mul_f32_e32 v131, 0xbfb8aa3b, v131
	v_exp_f32_e32 v131, v131
	s_nop 0
	v_add_f32_e32 v131, 1.0, v131
	v_rcp_f32_e32 v131, v131
	s_nop 0
	v_mul_f32_e32 v131, v79, v131
	v_mul_f32_e32 v131, 0x3fb8aa3b, v131
	v_cvt_pk_bf16_f32 v131, v131, 0
	v_lshlrev_b32_e32 v131, 16, v131
	v_add_f32_e32 v137, v131, v131
	v_mul_f32_e32 v138, 0x3f317218, v137
	v_cmp_nlt_f32_e32 vcc, s74, v138
	s_and_saveexec_b64 s[56:57], vcc
	s_xor_b64 s[56:57], exec, s[56:57]
	v_exp_f32_e32 v137, v131
	s_nop 0
	v_fma_f32 v137, -v137, v137, 1.0
	s_andn2_saveexec_b64 s[56:57], s[56:57]
	v_fmamk_f32 v137, v138, 0x3d2aaaab, v208
	v_fma_f32 v137, v138, v137, 0.5
	v_fma_f32 v137, v138, v137, 1.0
	v_mul_f32_e64 v137, v138, -v137
	s_or_b64 exec, exec, s[56:57]
	v_add_f32_e32 v126, v126, v70
	v_mul_f32_e32 v126, 0xbfb8aa3b, v126
	v_exp_f32_e32 v126, v126
	v_add_f32_e32 v124, v124, v68
	v_mul_f32_e32 v124, 0xbfb8aa3b, v124
	v_exp_f32_e32 v124, v124
	v_add_f32_e32 v125, v125, v69
	v_add_f32_e32 v127, v127, v71
	v_add_f32_e32 v126, 1.0, v126
	v_mul_f32_e32 v125, 0xbfb8aa3b, v125
	v_rcp_f32_e32 v126, v126
	v_mul_f32_e32 v127, 0xbfb8aa3b, v127
	v_exp_f32_e32 v125, v125
	v_sqrt_f32_e32 v136, v136
	v_exp_f32_e32 v127, v127
	v_add_f32_e32 v124, 1.0, v124
	v_rcp_f32_e32 v124, v124
	v_lshlrev_b32_e32 v138, 16, v199
	v_add_f32_e32 v120, v120, v80
	v_mul_f32_e32 v126, v126, v138
	v_sqrt_f32_e32 v134, v134
	v_add_f32_e32 v125, 1.0, v125
	v_mul_f32_e32 v120, 0xbfb8aa3b, v120
	v_mul_f32_e32 v136, v126, v136
	v_add_f32_e32 v126, 1.0, v127
	v_lshlrev_b32_e32 v127, 16, v198
	v_rcp_f32_e32 v125, v125
	v_exp_f32_e32 v120, v120
	v_mul_f32_e32 v124, v124, v127
	v_sqrt_f32_e32 v127, v135
	v_mul_f32_e32 v134, v124, v134
	v_and_b32_e32 v124, 0xffff0000, v198
	v_rcp_f32_e32 v126, v126
	v_mul_f32_e32 v124, v125, v124
	v_add_f32_e32 v120, 1.0, v120
	v_mul_f32_e32 v135, v124, v127
	v_sqrt_f32_e32 v127, v137
	v_rcp_f32_e32 v120, v120
	v_and_b32_e32 v137, 0xffff0000, v199
	v_lshlrev_b64 v[124:125], 11, v[196:197]
	v_mul_f32_e32 v126, v126, v137
	v_mul_f32_e32 v137, v126, v127
	v_lshl_add_u64 v[126:127], v[124:125], 0, v[152:153]
	v_mul_f32_e32 v120, v76, v120
	v_lshlrev_b64 v[126:127], 1, v[126:127]
	v_mul_f32_e32 v120, 0x3fb8aa3b, v120
	v_cvt_pk_bf16_f32 v128, v128, v129
	v_cvt_pk_bf16_f32 v129, v130, v131
	v_lshl_add_u64 v[130:131], s[16:17], 0, v[126:127]
; __device__ __forceinline__ float bf_lo(unsigned w) { return __uint_as_float(w << 16); }
; __device__ __forceinline__ float bf_hi(unsigned w) { return __uint_as_float(w & 0xffff0000u); }
; __device__ __forceinline__ float fast_sigmoid(float x) { return __builtin_amdgcn_rcpf(1.0f + __builtin_amdgcn_exp2f(-x * LOG2E)); }
;     __device__ __forceinline__ void operator()(const f32x4 (&acc)[2][2][4][2], const Unit& u, int wr, int wc, int fr, int fq) const {
;     ...
;                 for (int m = 0; m < 4; ++m) { const int row = row0 + ai * HALF + m * 16; const size_t off = (size_t)row * DM + ch0 + n * 16;
;                     const u32x2 xw = xall[ai * 4 + m];
;                     const float xv[4] = {bf_lo(xw.x), bf_hi(xw.x), bf_lo(xw.y), bf_hi(xw.y)};
;                     f32x4 av; float bv[4];
; #pragma unroll
;                     for (int j = 0; j < 4; ++j) { const float r = fast_sigmoid(acc[ai][0][m][n][j] + ba[j]), ig = fast_sigmoid(acc[ai][1][m][n][j] + bx[j]);
;                         const float la = sp[j] * r; const float la2 = __uint_as_float(pk_bf16(la * LOG2E, 0.f) << 16);
;                         const float a = __builtin_amdgcn_exp2f(la2); const float x2 = 2.0f * la2 * 0.6931471805599453f; av[j] = la2;
;                         const float om = (x2 > -0.03f) ? -(x2 * (1.0f + x2 * (0.5f + x2 * (1.0f / 6.0f + x2 * (1.0f / 24.0f))))) : (1.0f - a * a);
;                         bv[j] = __builtin_amdgcn_sqrtf(om) * (ig * xv[j]); }
;                     { u32x2 wa; wa.x = pk_bf16(av[0], av[1]); wa.y = pk_bf16(av[2], av[3]); *(u32x2*)(aout + off) = wa; }
;                     u32x2 w; w.x = pk_bf16(bv[0], bv[1]); w.y = pk_bf16(bv[2], bv[3]); *(u32x2*)(bout + off) = w; }
	v_cvt_pk_bf16_f32 v120, v120, 0
	global_store_dwordx2 v[130:131], v[128:129], off
	v_cvt_pk_bf16_f32 v128, v134, v135
	v_cvt_pk_bf16_f32 v129, v136, v137
	v_lshl_add_u64 v[126:127], s[18:19], 0, v[126:127]
	v_lshlrev_b32_e32 v120, 16, v120
	global_store_dwordx2 v[126:127], v[128:129], off
	v_add_f32_e32 v126, v120, v120
	v_mul_f32_e32 v127, 0x3f317218, v126
	v_cmp_nlt_f32_e32 vcc, s74, v127
	s_and_saveexec_b64 s[56:57], vcc
	s_xor_b64 s[56:57], exec, s[56:57]
	v_exp_f32_e32 v126, v120
	s_nop 0
	v_fma_f32 v126, -v126, v126, 1.0
	s_andn2_saveexec_b64 s[56:57], s[56:57]
	v_fmamk_f32 v126, v127, 0x3d2aaaab, v208
	v_fma_f32 v126, v127, v126, 0.5
	v_fma_f32 v126, v127, v126, 1.0
	v_mul_f32_e64 v126, v127, -v126
	s_or_b64 exec, exec, s[56:57]
	v_add_f32_e32 v121, v121, v81
	v_mul_f32_e32 v121, 0xbfb8aa3b, v121
	v_exp_f32_e32 v121, v121
	s_nop 0
	v_add_f32_e32 v121, 1.0, v121
	v_rcp_f32_e32 v121, v121
	s_nop 0
	v_mul_f32_e32 v121, v77, v121
	v_mul_f32_e32 v121, 0x3fb8aa3b, v121
	v_cvt_pk_bf16_f32 v121, v121, 0
	v_lshlrev_b32_e32 v121, 16, v121
	v_add_f32_e32 v127, v121, v121
	v_mul_f32_e32 v128, 0x3f317218, v127
	v_cmp_nlt_f32_e32 vcc, s74, v128
	s_and_saveexec_b64 s[56:57], vcc
	s_xor_b64 s[56:57], exec, s[56:57]
	v_exp_f32_e32 v127, v121
	s_nop 0
	v_fma_f32 v127, -v127, v127, 1.0
	s_andn2_saveexec_b64 s[56:57], s[56:57]
	v_fmamk_f32 v127, v128, 0x3d2aaaab, v208
	v_fma_f32 v127, v128, v127, 0.5
	v_fma_f32 v127, v128, v127, 1.0
	v_mul_f32_e64 v127, v128, -v127
	s_or_b64 exec, exec, s[56:57]
	v_add_f32_e32 v122, v122, v82
	v_mul_f32_e32 v122, 0xbfb8aa3b, v122
	v_exp_f32_e32 v122, v122
	s_nop 0
	v_add_f32_e32 v122, 1.0, v122
	v_rcp_f32_e32 v122, v122
	s_nop 0
	v_mul_f32_e32 v122, v78, v122
	v_mul_f32_e32 v122, 0x3fb8aa3b, v122
	v_cvt_pk_bf16_f32 v122, v122, 0
	v_lshlrev_b32_e32 v122, 16, v122
	v_add_f32_e32 v128, v122, v122
	v_mul_f32_e32 v129, 0x3f317218, v128
	v_cmp_nlt_f32_e32 vcc, s74, v129
	s_and_saveexec_b64 s[56:57], vcc
	s_xor_b64 s[56:57], exec, s[56:57]
	v_exp_f32_e32 v128, v122
	s_nop 0
	v_fma_f32 v128, -v128, v128, 1.0
	s_andn2_saveexec_b64 s[56:57], s[56:57]
	v_fmamk_f32 v128, v129, 0x3d2aaaab, v208
	v_fma_f32 v128, v129, v128, 0.5
	v_fma_f32 v128, v129, v128, 1.0
	v_mul_f32_e64 v128, v129, -v128
	s_or_b64 exec, exec, s[56:57]
	v_add_f32_e32 v123, v123, v83
	v_mul_f32_e32 v123, 0xbfb8aa3b, v123
	v_exp_f32_e32 v123, v123
	s_nop 0
	v_add_f32_e32 v123, 1.0, v123
	v_rcp_f32_e32 v123, v123
	s_nop 0
	v_mul_f32_e32 v123, v79, v123
	v_mul_f32_e32 v123, 0x3fb8aa3b, v123
	v_cvt_pk_bf16_f32 v123, v123, 0
	v_lshlrev_b32_e32 v123, 16, v123
	v_add_f32_e32 v129, v123, v123
	v_mul_f32_e32 v130, 0x3f317218, v129
	v_cmp_nlt_f32_e32 vcc, s74, v130
	s_and_saveexec_b64 s[56:57], vcc
	s_xor_b64 s[56:57], exec, s[56:57]
	v_exp_f32_e32 v129, v123
	s_nop 0
	v_fma_f32 v129, -v129, v129, 1.0
	s_andn2_saveexec_b64 s[56:57], s[56:57]
	v_fmamk_f32 v129, v130, 0x3d2aaaab, v208
	v_fma_f32 v129, v130, v129, 0.5
	v_fma_f32 v129, v130, v129, 1.0
	v_mul_f32_e64 v129, v130, -v129
	s_or_b64 exec, exec, s[56:57]
	v_add_f32_e32 v118, v118, v70
	v_mul_f32_e32 v118, 0xbfb8aa3b, v118
	v_exp_f32_e32 v118, v118
	v_add_f32_e32 v116, v116, v68
	v_mul_f32_e32 v116, 0xbfb8aa3b, v116
	v_exp_f32_e32 v116, v116
	v_add_f32_e32 v117, v117, v69
	v_add_f32_e32 v119, v119, v71
	v_add_f32_e32 v118, 1.0, v118
	v_mul_f32_e32 v117, 0xbfb8aa3b, v117
	v_rcp_f32_e32 v118, v118
	v_mul_f32_e32 v119, 0xbfb8aa3b, v119
	v_exp_f32_e32 v117, v117
	v_sqrt_f32_e32 v128, v128
	v_exp_f32_e32 v119, v119
	v_add_f32_e32 v116, 1.0, v116
	v_rcp_f32_e32 v116, v116
	v_lshlrev_b32_e32 v130, 16, v195
	v_add_f32_e32 v112, v112, v80
	v_mul_f32_e32 v118, v118, v130
	v_sqrt_f32_e32 v126, v126
	v_add_f32_e32 v117, 1.0, v117
	v_mul_f32_e32 v112, 0xbfb8aa3b, v112
	v_mul_f32_e32 v128, v118, v128
	v_add_f32_e32 v118, 1.0, v119
	v_lshlrev_b32_e32 v119, 16, v194
	v_rcp_f32_e32 v117, v117
	v_exp_f32_e32 v112, v112
	v_mul_f32_e32 v116, v116, v119
	v_sqrt_f32_e32 v119, v127
	v_mul_f32_e32 v126, v116, v126
	v_and_b32_e32 v116, 0xffff0000, v194
	v_rcp_f32_e32 v118, v118
	v_mul_f32_e32 v116, v117, v116
	v_add_f32_e32 v112, 1.0, v112
	v_mul_f32_e32 v127, v116, v119
	v_sqrt_f32_e32 v119, v129
	v_rcp_f32_e32 v112, v112
	v_and_b32_e32 v129, 0xffff0000, v195
	v_lshlrev_b64 v[116:117], 11, v[192:193]
	v_mul_f32_e32 v118, v118, v129
	v_mul_f32_e32 v129, v118, v119
	v_lshl_add_u64 v[118:119], v[116:117], 0, v[152:153]
	v_mul_f32_e32 v112, v76, v112
	v_lshlrev_b64 v[118:119], 1, v[118:119]
	v_mul_f32_e32 v112, 0x3fb8aa3b, v112
	v_cvt_pk_bf16_f32 v120, v120, v121
	v_cvt_pk_bf16_f32 v121, v122, v123
	v_lshl_add_u64 v[122:123], s[16:17], 0, v[118:119]
	v_cvt_pk_bf16_f32 v112, v112, 0
	global_store_dwordx2 v[122:123], v[120:121], off
	v_cvt_pk_bf16_f32 v120, v126, v127
	v_cvt_pk_bf16_f32 v121, v128, v129
	v_lshl_add_u64 v[118:119], s[18:19], 0, v[118:119]
	v_lshlrev_b32_e32 v112, 16, v112
	global_store_dwordx2 v[118:119], v[120:121], off
	v_add_f32_e32 v118, v112, v112
	v_mul_f32_e32 v119, 0x3f317218, v118
	v_cmp_nlt_f32_e32 vcc, s74, v119
	s_and_saveexec_b64 s[56:57], vcc
	s_xor_b64 s[56:57], exec, s[56:57]
	v_exp_f32_e32 v118, v112
	s_nop 0
	v_fma_f32 v118, -v118, v118, 1.0
	s_andn2_saveexec_b64 s[56:57], s[56:57]
	v_fmamk_f32 v118, v119, 0x3d2aaaab, v208
	v_fma_f32 v118, v119, v118, 0.5
	v_fma_f32 v118, v119, v118, 1.0
	v_mul_f32_e64 v118, v119, -v118
	s_or_b64 exec, exec, s[56:57]
	v_add_f32_e32 v113, v113, v81
	v_mul_f32_e32 v113, 0xbfb8aa3b, v113
	v_exp_f32_e32 v113, v113
	s_nop 0
	v_add_f32_e32 v113, 1.0, v113
	v_rcp_f32_e32 v113, v113
	s_nop 0
	v_mul_f32_e32 v113, v77, v113
	v_mul_f32_e32 v113, 0x3fb8aa3b, v113
	v_cvt_pk_bf16_f32 v113, v113, 0
; __device__ __forceinline__ float bf_lo(unsigned w) { return __uint_as_float(w << 16); }
; __device__ __forceinline__ float bf_hi(unsigned w) { return __uint_as_float(w & 0xffff0000u); }
; __device__ __forceinline__ float fast_sigmoid(float x) { return __builtin_amdgcn_rcpf(1.0f + __builtin_amdgcn_exp2f(-x * LOG2E)); }
;     __device__ __forceinline__ void operator()(const f32x4 (&acc)[2][2][4][2], const Unit& u, int wr, int wc, int fr, int fq) const {
;     ...
;                 for (int m = 0; m < 4; ++m) { const int row = row0 + ai * HALF + m * 16; const size_t off = (size_t)row * DM + ch0 + n * 16;
;                     const u32x2 xw = xall[ai * 4 + m];
;                     const float xv[4] = {bf_lo(xw.x), bf_hi(xw.x), bf_lo(xw.y), bf_hi(xw.y)};
;                     f32x4 av; float bv[4];
; #pragma unroll
;                     for (int j = 0; j < 4; ++j) { const float r = fast_sigmoid(acc[ai][0][m][n][j] + ba[j]), ig = fast_sigmoid(acc[ai][1][m][n][j] + bx[j]);
;                         const float la = sp[j] * r; const float la2 = __uint_as_float(pk_bf16(la * LOG2E, 0.f) << 16);
;                         const float a = __builtin_amdgcn_exp2f(la2); const float x2 = 2.0f * la2 * 0.6931471805599453f; av[j] = la2;
;                         const float om = (x2 > -0.03f) ? -(x2 * (1.0f + x2 * (0.5f + x2 * (1.0f / 6.0f + x2 * (1.0f / 24.0f))))) : (1.0f - a * a);
;                         bv[j] = __builtin_amdgcn_sqrtf(om) * (ig * xv[j]); }
;                     { u32x2 wa; wa.x = pk_bf16(av[0], av[1]); wa.y = pk_bf16(av[2], av[3]); *(u32x2*)(aout + off) = wa; }
;                     u32x2 w; w.x = pk_bf16(bv[0], bv[1]); w.y = pk_bf16(bv[2], bv[3]); *(u32x2*)(bout + off) = w; }
	v_lshlrev_b32_e32 v113, 16, v113
	v_add_f32_e32 v119, v113, v113
	v_mul_f32_e32 v120, 0x3f317218, v119
	v_cmp_nlt_f32_e32 vcc, s74, v120
	s_and_saveexec_b64 s[56:57], vcc
	s_xor_b64 s[56:57], exec, s[56:57]
	v_exp_f32_e32 v119, v113
	s_nop 0
	v_fma_f32 v119, -v119, v119, 1.0
	s_andn2_saveexec_b64 s[56:57], s[56:57]
	v_fmamk_f32 v119, v120, 0x3d2aaaab, v208
	v_fma_f32 v119, v120, v119, 0.5
	v_fma_f32 v119, v120, v119, 1.0
	v_mul_f32_e64 v119, v120, -v119
	s_or_b64 exec, exec, s[56:57]
	v_add_f32_e32 v114, v114, v82
	v_mul_f32_e32 v114, 0xbfb8aa3b, v114
	v_exp_f32_e32 v114, v114
	s_nop 0
	v_add_f32_e32 v114, 1.0, v114
	v_rcp_f32_e32 v114, v114
	s_nop 0
	v_mul_f32_e32 v114, v78, v114
	v_mul_f32_e32 v114, 0x3fb8aa3b, v114
	v_cvt_pk_bf16_f32 v114, v114, 0
	v_lshlrev_b32_e32 v114, 16, v114
	v_add_f32_e32 v120, v114, v114
	v_mul_f32_e32 v121, 0x3f317218, v120
	v_cmp_nlt_f32_e32 vcc, s74, v121
	s_and_saveexec_b64 s[56:57], vcc
	s_xor_b64 s[56:57], exec, s[56:57]
	v_exp_f32_e32 v120, v114
	s_nop 0
	v_fma_f32 v120, -v120, v120, 1.0
	s_andn2_saveexec_b64 s[56:57], s[56:57]
	v_fmamk_f32 v120, v121, 0x3d2aaaab, v208
	v_fma_f32 v120, v121, v120, 0.5
	v_fma_f32 v120, v121, v120, 1.0
	v_mul_f32_e64 v120, v121, -v120
	s_or_b64 exec, exec, s[56:57]
	v_add_f32_e32 v115, v115, v83
	v_mul_f32_e32 v115, 0xbfb8aa3b, v115
	v_exp_f32_e32 v115, v115
	s_nop 0
	v_add_f32_e32 v115, 1.0, v115
	v_rcp_f32_e32 v115, v115
	s_nop 0
	v_mul_f32_e32 v115, v79, v115
	v_mul_f32_e32 v115, 0x3fb8aa3b, v115
	v_cvt_pk_bf16_f32 v115, v115, 0
	v_lshlrev_b32_e32 v115, 16, v115
	v_add_f32_e32 v121, v115, v115
	v_mul_f32_e32 v122, 0x3f317218, v121
	v_cmp_nlt_f32_e32 vcc, s74, v122
	s_and_saveexec_b64 s[56:57], vcc
	s_xor_b64 s[56:57], exec, s[56:57]
	v_exp_f32_e32 v121, v115
	s_nop 0
	v_fma_f32 v121, -v121, v121, 1.0
	s_andn2_saveexec_b64 s[56:57], s[56:57]
	v_fmamk_f32 v121, v122, 0x3d2aaaab, v208
	v_fma_f32 v121, v122, v121, 0.5
	v_fma_f32 v121, v122, v121, 1.0
	v_mul_f32_e64 v121, v122, -v121
	s_or_b64 exec, exec, s[56:57]
	v_add_f32_e32 v110, v110, v70
	v_mul_f32_e32 v110, 0xbfb8aa3b, v110
	v_exp_f32_e32 v110, v110
	v_add_f32_e32 v108, v108, v68
	v_mul_f32_e32 v108, 0xbfb8aa3b, v108
	v_exp_f32_e32 v108, v108
	v_add_f32_e32 v109, v109, v69
	v_add_f32_e32 v111, v111, v71
	v_add_f32_e32 v110, 1.0, v110
	v_mul_f32_e32 v109, 0xbfb8aa3b, v109
	v_rcp_f32_e32 v110, v110
	v_mul_f32_e32 v111, 0xbfb8aa3b, v111
	v_exp_f32_e32 v109, v109
	v_sqrt_f32_e32 v120, v120
	v_exp_f32_e32 v111, v111
	v_add_f32_e32 v108, 1.0, v108
	v_rcp_f32_e32 v108, v108
	v_lshlrev_b32_e32 v122, 16, v191
	v_add_f32_e32 v104, v104, v80
	v_mul_f32_e32 v110, v110, v122
	v_sqrt_f32_e32 v118, v118
	v_add_f32_e32 v109, 1.0, v109
	v_mul_f32_e32 v104, 0xbfb8aa3b, v104
	v_mul_f32_e32 v120, v110, v120
	v_add_f32_e32 v110, 1.0, v111
	v_lshlrev_b32_e32 v111, 16, v190
	v_rcp_f32_e32 v109, v109
	v_exp_f32_e32 v104, v104
	v_mul_f32_e32 v108, v108, v111
	v_sqrt_f32_e32 v111, v119
	v_mul_f32_e32 v118, v108, v118
	v_and_b32_e32 v108, 0xffff0000, v190
	v_rcp_f32_e32 v110, v110
	v_mul_f32_e32 v108, v109, v108
	v_add_f32_e32 v104, 1.0, v104
	v_mul_f32_e32 v119, v108, v111
	v_sqrt_f32_e32 v111, v121
	v_rcp_f32_e32 v104, v104
	v_and_b32_e32 v121, 0xffff0000, v191
	v_lshlrev_b64 v[108:109], 11, v[188:189]
	v_mul_f32_e32 v110, v110, v121
	v_mul_f32_e32 v121, v110, v111
	v_lshl_add_u64 v[110:111], v[108:109], 0, v[152:153]
	v_mul_f32_e32 v104, v76, v104
	v_lshlrev_b64 v[110:111], 1, v[110:111]
	v_mul_f32_e32 v104, 0x3fb8aa3b, v104
	v_cvt_pk_bf16_f32 v112, v112, v113
	v_cvt_pk_bf16_f32 v113, v114, v115
	v_lshl_add_u64 v[114:115], s[16:17], 0, v[110:111]
	v_cvt_pk_bf16_f32 v104, v104, 0
	global_store_dwordx2 v[114:115], v[112:113], off
	v_cvt_pk_bf16_f32 v112, v118, v119
	v_cvt_pk_bf16_f32 v113, v120, v121
	v_lshl_add_u64 v[110:111], s[18:19], 0, v[110:111]
	v_lshlrev_b32_e32 v104, 16, v104
	global_store_dwordx2 v[110:111], v[112:113], off
	v_add_f32_e32 v110, v104, v104
	v_mul_f32_e32 v111, 0x3f317218, v110
	v_cmp_nlt_f32_e32 vcc, s74, v111
	s_and_saveexec_b64 s[56:57], vcc
	s_xor_b64 s[56:57], exec, s[56:57]
	v_exp_f32_e32 v110, v104
	s_nop 0
	v_fma_f32 v110, -v110, v110, 1.0
	s_andn2_saveexec_b64 s[56:57], s[56:57]
	v_fmamk_f32 v110, v111, 0x3d2aaaab, v208
	v_fma_f32 v110, v111, v110, 0.5
	v_fma_f32 v110, v111, v110, 1.0
	v_mul_f32_e64 v110, v111, -v110
	s_or_b64 exec, exec, s[56:57]
	v_add_f32_e32 v105, v105, v81
	v_mul_f32_e32 v105, 0xbfb8aa3b, v105
	v_exp_f32_e32 v105, v105
	s_nop 0
	v_add_f32_e32 v105, 1.0, v105
	v_rcp_f32_e32 v105, v105
	s_nop 0
	v_mul_f32_e32 v105, v77, v105
	v_mul_f32_e32 v105, 0x3fb8aa3b, v105
	v_cvt_pk_bf16_f32 v105, v105, 0
	v_lshlrev_b32_e32 v105, 16, v105
	v_add_f32_e32 v111, v105, v105
	v_mul_f32_e32 v112, 0x3f317218, v111
	v_cmp_nlt_f32_e32 vcc, s74, v112
	s_and_saveexec_b64 s[56:57], vcc
	s_xor_b64 s[56:57], exec, s[56:57]
	v_exp_f32_e32 v111, v105
	s_nop 0
	v_fma_f32 v111, -v111, v111, 1.0
	s_andn2_saveexec_b64 s[56:57], s[56:57]
	v_fmamk_f32 v111, v112, 0x3d2aaaab, v208
	v_fma_f32 v111, v112, v111, 0.5
	v_fma_f32 v111, v112, v111, 1.0
	v_mul_f32_e64 v111, v112, -v111
	s_or_b64 exec, exec, s[56:57]
	v_add_f32_e32 v106, v106, v82
	v_mul_f32_e32 v106, 0xbfb8aa3b, v106
	v_exp_f32_e32 v106, v106
	s_nop 0
	v_add_f32_e32 v106, 1.0, v106
	v_rcp_f32_e32 v106, v106
	s_nop 0
	v_mul_f32_e32 v106, v78, v106
	v_mul_f32_e32 v106, 0x3fb8aa3b, v106
	v_cvt_pk_bf16_f32 v106, v106, 0
	v_lshlrev_b32_e32 v106, 16, v106
	v_add_f32_e32 v112, v106, v106
	v_mul_f32_e32 v113, 0x3f317218, v112
	v_cmp_nlt_f32_e32 vcc, s74, v113
	s_and_saveexec_b64 s[56:57], vcc
	s_xor_b64 s[56:57], exec, s[56:57]
	v_exp_f32_e32 v112, v106
	s_nop 0
; __device__ __forceinline__ float bf_lo(unsigned w) { return __uint_as_float(w << 16); }
; __device__ __forceinline__ float bf_hi(unsigned w) { return __uint_as_float(w & 0xffff0000u); }
; __device__ __forceinline__ float fast_sigmoid(float x) { return __builtin_amdgcn_rcpf(1.0f + __builtin_amdgcn_exp2f(-x * LOG2E)); }
;     __device__ __forceinline__ void operator()(const f32x4 (&acc)[2][2][4][2], const Unit& u, int wr, int wc, int fr, int fq) const {
;     ...
;                 for (int m = 0; m < 4; ++m) { const int row = row0 + ai * HALF + m * 16; const size_t off = (size_t)row * DM + ch0 + n * 16;
;                     const u32x2 xw = xall[ai * 4 + m];
;                     const float xv[4] = {bf_lo(xw.x), bf_hi(xw.x), bf_lo(xw.y), bf_hi(xw.y)};
;                     f32x4 av; float bv[4];
; #pragma unroll
;                     for (int j = 0; j < 4; ++j) { const float r = fast_sigmoid(acc[ai][0][m][n][j] + ba[j]), ig = fast_sigmoid(acc[ai][1][m][n][j] + bx[j]);
;                         const float la = sp[j] * r; const float la2 = __uint_as_float(pk_bf16(la * LOG2E, 0.f) << 16);
;                         const float a = __builtin_amdgcn_exp2f(la2); const float x2 = 2.0f * la2 * 0.6931471805599453f; av[j] = la2;
;                         const float om = (x2 > -0.03f) ? -(x2 * (1.0f + x2 * (0.5f + x2 * (1.0f / 6.0f + x2 * (1.0f / 24.0f))))) : (1.0f - a * a);
;                         bv[j] = __builtin_amdgcn_sqrtf(om) * (ig * xv[j]); }
;                     { u32x2 wa; wa.x = pk_bf16(av[0], av[1]); wa.y = pk_bf16(av[2], av[3]); *(u32x2*)(aout + off) = wa; }
;                     u32x2 w; w.x = pk_bf16(bv[0], bv[1]); w.y = pk_bf16(bv[2], bv[3]); *(u32x2*)(bout + off) = w; }
	v_fma_f32 v112, -v112, v112, 1.0
	s_andn2_saveexec_b64 s[56:57], s[56:57]
	v_fmamk_f32 v112, v113, 0x3d2aaaab, v208
	v_fma_f32 v112, v113, v112, 0.5
	v_fma_f32 v112, v113, v112, 1.0
	v_mul_f32_e64 v112, v113, -v112
	s_or_b64 exec, exec, s[56:57]
	v_add_f32_e32 v107, v107, v83
	v_mul_f32_e32 v107, 0xbfb8aa3b, v107
	v_exp_f32_e32 v107, v107
	s_nop 0
	v_add_f32_e32 v107, 1.0, v107
	v_rcp_f32_e32 v107, v107
	s_nop 0
	v_mul_f32_e32 v107, v79, v107
	v_mul_f32_e32 v107, 0x3fb8aa3b, v107
	v_cvt_pk_bf16_f32 v107, v107, 0
	v_lshlrev_b32_e32 v107, 16, v107
	v_add_f32_e32 v113, v107, v107
	v_mul_f32_e32 v114, 0x3f317218, v113
	v_cmp_nlt_f32_e32 vcc, s74, v114
	s_and_saveexec_b64 s[56:57], vcc
	s_xor_b64 s[56:57], exec, s[56:57]
	v_exp_f32_e32 v113, v107
	s_nop 0
	v_fma_f32 v113, -v113, v113, 1.0
	s_andn2_saveexec_b64 s[56:57], s[56:57]
	v_fmamk_f32 v113, v114, 0x3d2aaaab, v208
	v_fma_f32 v113, v114, v113, 0.5
	v_fma_f32 v113, v114, v113, 1.0
	v_mul_f32_e64 v113, v114, -v113
	s_or_b64 exec, exec, s[56:57]
	v_add_f32_e32 v102, v102, v70
	v_mul_f32_e32 v102, 0xbfb8aa3b, v102
	v_exp_f32_e32 v102, v102
	v_add_f32_e32 v100, v100, v68
	v_mul_f32_e32 v100, 0xbfb8aa3b, v100
	v_exp_f32_e32 v100, v100
	v_add_f32_e32 v101, v101, v69
	v_add_f32_e32 v103, v103, v71
	v_add_f32_e32 v102, 1.0, v102
	v_mul_f32_e32 v101, 0xbfb8aa3b, v101
	v_rcp_f32_e32 v102, v102
	v_mul_f32_e32 v103, 0xbfb8aa3b, v103
	v_exp_f32_e32 v101, v101
	v_sqrt_f32_e32 v112, v112
	v_exp_f32_e32 v103, v103
	v_add_f32_e32 v100, 1.0, v100
	v_rcp_f32_e32 v100, v100
	v_lshlrev_b32_e32 v114, 16, v187
	v_add_f32_e32 v96, v96, v80
	v_mul_f32_e32 v102, v102, v114
	v_sqrt_f32_e32 v110, v110
	v_add_f32_e32 v101, 1.0, v101
	v_mul_f32_e32 v96, 0xbfb8aa3b, v96
	v_mul_f32_e32 v112, v102, v112
	v_add_f32_e32 v102, 1.0, v103
	v_lshlrev_b32_e32 v103, 16, v186
	v_rcp_f32_e32 v101, v101
	v_exp_f32_e32 v96, v96
	v_mul_f32_e32 v100, v100, v103
	v_sqrt_f32_e32 v103, v111
	v_mul_f32_e32 v110, v100, v110
	v_and_b32_e32 v100, 0xffff0000, v186
	v_rcp_f32_e32 v102, v102
	v_mul_f32_e32 v100, v101, v100
	v_add_f32_e32 v96, 1.0, v96
	v_mul_f32_e32 v111, v100, v103
	v_sqrt_f32_e32 v103, v113
	v_rcp_f32_e32 v96, v96
	v_and_b32_e32 v113, 0xffff0000, v187
	v_lshlrev_b64 v[100:101], 11, v[184:185]
	v_mul_f32_e32 v102, v102, v113
	v_mul_f32_e32 v113, v102, v103
	v_lshl_add_u64 v[102:103], v[100:101], 0, v[152:153]
	v_mul_f32_e32 v96, v76, v96
	v_lshlrev_b64 v[102:103], 1, v[102:103]
	v_mul_f32_e32 v96, 0x3fb8aa3b, v96
	v_cvt_pk_bf16_f32 v104, v104, v105
	v_cvt_pk_bf16_f32 v105, v106, v107
	v_lshl_add_u64 v[106:107], s[16:17], 0, v[102:103]
	v_cvt_pk_bf16_f32 v96, v96, 0
	global_store_dwordx2 v[106:107], v[104:105], off
	v_cvt_pk_bf16_f32 v104, v110, v111
	v_cvt_pk_bf16_f32 v105, v112, v113
	v_lshl_add_u64 v[102:103], s[18:19], 0, v[102:103]
	v_lshlrev_b32_e32 v96, 16, v96
	global_store_dwordx2 v[102:103], v[104:105], off
	v_add_f32_e32 v102, v96, v96
	v_mul_f32_e32 v103, 0x3f317218, v102
	v_cmp_nlt_f32_e32 vcc, s74, v103
	s_and_saveexec_b64 s[56:57], vcc
	s_xor_b64 s[56:57], exec, s[56:57]
	v_exp_f32_e32 v102, v96
	s_nop 0
	v_fma_f32 v102, -v102, v102, 1.0
	s_andn2_saveexec_b64 s[56:57], s[56:57]
	v_fmamk_f32 v102, v103, 0x3d2aaaab, v208
	v_fma_f32 v102, v103, v102, 0.5
	v_fma_f32 v102, v103, v102, 1.0
	v_mul_f32_e64 v102, v103, -v102
	s_or_b64 exec, exec, s[56:57]
	v_add_f32_e32 v97, v97, v81
	v_mul_f32_e32 v97, 0xbfb8aa3b, v97
	v_exp_f32_e32 v97, v97
	s_nop 0
	v_add_f32_e32 v97, 1.0, v97
	v_rcp_f32_e32 v97, v97
	s_nop 0
	v_mul_f32_e32 v97, v77, v97
	v_mul_f32_e32 v97, 0x3fb8aa3b, v97
	v_cvt_pk_bf16_f32 v97, v97, 0
	v_lshlrev_b32_e32 v97, 16, v97
	v_add_f32_e32 v103, v97, v97
	v_mul_f32_e32 v104, 0x3f317218, v103
	v_cmp_nlt_f32_e32 vcc, s74, v104
	s_and_saveexec_b64 s[56:57], vcc
	s_xor_b64 s[56:57], exec, s[56:57]
	v_exp_f32_e32 v103, v97
	s_nop 0
	v_fma_f32 v103, -v103, v103, 1.0
	s_andn2_saveexec_b64 s[56:57], s[56:57]
	v_fmamk_f32 v103, v104, 0x3d2aaaab, v208
	v_fma_f32 v103, v104, v103, 0.5
	v_fma_f32 v103, v104, v103, 1.0
	v_mul_f32_e64 v103, v104, -v103
	s_or_b64 exec, exec, s[56:57]
	v_add_f32_e32 v98, v98, v82
	v_mul_f32_e32 v98, 0xbfb8aa3b, v98
	v_exp_f32_e32 v98, v98
	s_nop 0
	v_add_f32_e32 v98, 1.0, v98
	v_rcp_f32_e32 v98, v98
	s_nop 0
	v_mul_f32_e32 v98, v78, v98
	v_mul_f32_e32 v98, 0x3fb8aa3b, v98
	v_cvt_pk_bf16_f32 v98, v98, 0
	v_lshlrev_b32_e32 v98, 16, v98
	v_add_f32_e32 v104, v98, v98
	v_mul_f32_e32 v104, 0x3f317218, v104
	v_cmp_nlt_f32_e32 vcc, s74, v104
	s_and_saveexec_b64 s[56:57], vcc
	s_xor_b64 s[56:57], exec, s[56:57]
	v_exp_f32_e32 v104, v98
	s_nop 0
	v_fma_f32 v105, -v104, v104, 1.0
	s_andn2_saveexec_b64 s[56:57], s[56:57]
	v_fmamk_f32 v105, v104, 0x3d2aaaab, v208
	v_fma_f32 v105, v104, v105, 0.5
	v_fma_f32 v105, v104, v105, 1.0
	v_mul_f32_e64 v105, v104, -v105
	s_or_b64 exec, exec, s[56:57]
	v_add_f32_e32 v99, v99, v83
	v_mul_f32_e32 v99, 0xbfb8aa3b, v99
	v_exp_f32_e32 v99, v99
	s_nop 0
	v_add_f32_e32 v99, 1.0, v99
	v_rcp_f32_e32 v99, v99
	s_nop 0
	v_mul_f32_e32 v99, v79, v99
	v_mul_f32_e32 v99, 0x3fb8aa3b, v99
	v_cvt_pk_bf16_f32 v99, v99, 0
	v_lshlrev_b32_e32 v99, 16, v99
	v_add_f32_e32 v104, v99, v99
	v_mul_f32_e32 v106, 0x3f317218, v104
	v_cmp_nlt_f32_e32 vcc, s74, v106
	s_and_saveexec_b64 s[56:57], vcc
	s_xor_b64 s[56:57], exec, s[56:57]
	v_exp_f32_e32 v104, v99
	s_nop 0
	v_fma_f32 v104, -v104, v104, 1.0
	s_andn2_saveexec_b64 s[56:57], s[56:57]
	v_fmamk_f32 v104, v106, 0x3d2aaaab, v208
	v_fma_f32 v104, v106, v104, 0.5
	v_fma_f32 v104, v106, v104, 1.0
	v_mul_f32_e64 v104, v106, -v104
	s_or_b64 exec, exec, s[56:57]
	v_add_f32_e32 v94, v94, v70
	v_mul_f32_e32 v94, 0xbfb8aa3b, v94
	v_exp_f32_e32 v94, v94
; __device__ __forceinline__ float bf_lo(unsigned w) { return __uint_as_float(w << 16); }
; __device__ __forceinline__ float bf_hi(unsigned w) { return __uint_as_float(w & 0xffff0000u); }
; __device__ __forceinline__ float fast_sigmoid(float x) { return __builtin_amdgcn_rcpf(1.0f + __builtin_amdgcn_exp2f(-x * LOG2E)); }
;     __device__ __forceinline__ void operator()(const f32x4 (&acc)[2][2][4][2], const Unit& u, int wr, int wc, int fr, int fq) const {
;         const int row0 = u.pm * BM + wr * 64 + fr, ch0 = u.pn * HALF + wc * 32 + 4 * fq;
; #pragma unroll
;         for (int n = 0; n < 2; ++n) {
;             const f32x4 ba = *(const f32x4*)(b_ga + ch0 + n * 16), bx = *(const f32x4*)(b_gx + ch0 + n * 16), sp = *(const f32x4*)(lam + ch0 + n * 16);
;             u32x2 xall[8];
; #pragma unroll
;             for (int it = 0; it < 8; ++it) xall[it] = *(const u32x2*)(xc + (size_t)(row0 + (it >> 2) * HALF + (it & 3) * 16) * DM + ch0 + n * 16);
;             asm volatile("" ::: "memory");
; #pragma unroll
;             for (int ai = 0; ai < 2; ++ai)
; #pragma unroll
;                 for (int m = 0; m < 4; ++m) { const int row = row0 + ai * HALF + m * 16; const size_t off = (size_t)row * DM + ch0 + n * 16;
;                     const u32x2 xw = xall[ai * 4 + m];
;                     const float xv[4] = {bf_lo(xw.x), bf_hi(xw.x), bf_lo(xw.y), bf_hi(xw.y)};
;                     f32x4 av; float bv[4];
; #pragma unroll
;                     for (int j = 0; j < 4; ++j) { const float r = fast_sigmoid(acc[ai][0][m][n][j] + ba[j]), ig = fast_sigmoid(acc[ai][1][m][n][j] + bx[j]);
;                         const float la = sp[j] * r; const float la2 = __uint_as_float(pk_bf16(la * LOG2E, 0.f) << 16);
;                         const float a = __builtin_amdgcn_exp2f(la2); const float x2 = 2.0f * la2 * 0.6931471805599453f; av[j] = la2;
;                         const float om = (x2 > -0.03f) ? -(x2 * (1.0f + x2 * (0.5f + x2 * (1.0f / 6.0f + x2 * (1.0f / 24.0f))))) : (1.0f - a * a);
;                         bv[j] = __builtin_amdgcn_sqrtf(om) * (ig * xv[j]); }
;                     { u32x2 wa; wa.x = pk_bf16(av[0], av[1]); wa.y = pk_bf16(av[2], av[3]); *(u32x2*)(aout + off) = wa; }
;                     u32x2 w; w.x = pk_bf16(bv[0], bv[1]); w.y = pk_bf16(bv[2], bv[3]); *(u32x2*)(bout + off) = w; }
;         }
;     }
	v_add_f32_e32 v92, v92, v68
	v_mul_f32_e32 v92, 0xbfb8aa3b, v92
	v_exp_f32_e32 v92, v92
	v_add_f32_e32 v93, v93, v69
	v_add_f32_e32 v95, v95, v71
	v_add_f32_e32 v94, 1.0, v94
	v_mul_f32_e32 v93, 0xbfb8aa3b, v93
	v_rcp_f32_e32 v94, v94
	v_mul_f32_e32 v95, 0xbfb8aa3b, v95
	v_exp_f32_e32 v93, v93
	v_sqrt_f32_e32 v105, v105
	v_exp_f32_e32 v95, v95
	v_add_f32_e32 v92, 1.0, v92
	v_rcp_f32_e32 v92, v92
	v_lshlrev_b32_e32 v106, 16, v183
	v_add_f32_e32 v88, v88, v80
	v_mul_f32_e32 v94, v94, v106
	v_sqrt_f32_e32 v102, v102
	v_add_f32_e32 v93, 1.0, v93
	v_mul_f32_e32 v88, 0xbfb8aa3b, v88
	v_mul_f32_e32 v105, v94, v105
	v_add_f32_e32 v94, 1.0, v95
	v_lshlrev_b32_e32 v95, 16, v182
	v_rcp_f32_e32 v93, v93
	v_exp_f32_e32 v88, v88
	v_mul_f32_e32 v92, v92, v95
	v_sqrt_f32_e32 v95, v103
	v_mul_f32_e32 v102, v92, v102
	v_and_b32_e32 v92, 0xffff0000, v182
	v_rcp_f32_e32 v94, v94
	v_mul_f32_e32 v92, v93, v92
	v_add_f32_e32 v88, 1.0, v88
	v_mul_f32_e32 v103, v92, v95
	v_sqrt_f32_e32 v95, v104
	v_rcp_f32_e32 v88, v88
	v_lshlrev_b64 v[92:93], 11, v[164:165]
	v_and_b32_e32 v104, 0xffff0000, v183
	v_lshl_add_u64 v[92:93], v[92:93], 0, s[40:41]
	v_mul_f32_e32 v94, v94, v104
	v_mul_f32_e32 v104, v94, v95
	v_lshl_add_u64 v[94:95], v[92:93], 0, v[152:153]
	v_mul_f32_e32 v88, v76, v88
	v_lshlrev_b64 v[94:95], 1, v[94:95]
	v_mul_f32_e32 v88, 0x3fb8aa3b, v88
	v_cvt_pk_bf16_f32 v96, v96, v97
	v_cvt_pk_bf16_f32 v97, v98, v99
	v_lshl_add_u64 v[98:99], s[16:17], 0, v[94:95]
	v_cvt_pk_bf16_f32 v88, v88, 0
	global_store_dwordx2 v[98:99], v[96:97], off
	v_cvt_pk_bf16_f32 v96, v102, v103
	v_cvt_pk_bf16_f32 v97, v105, v104
	v_lshl_add_u64 v[94:95], s[18:19], 0, v[94:95]
	v_lshlrev_b32_e32 v88, 16, v88
	global_store_dwordx2 v[94:95], v[96:97], off
	v_add_f32_e32 v94, v88, v88
	v_mul_f32_e32 v95, 0x3f317218, v94
	v_cmp_nlt_f32_e32 vcc, s74, v95
	s_and_saveexec_b64 s[56:57], vcc
	s_xor_b64 s[56:57], exec, s[56:57]
	v_exp_f32_e32 v94, v88
	s_nop 0
	v_fma_f32 v94, -v94, v94, 1.0
	s_andn2_saveexec_b64 s[56:57], s[56:57]
	v_fmamk_f32 v94, v95, 0x3d2aaaab, v208
	v_fma_f32 v94, v95, v94, 0.5
	v_fma_f32 v94, v95, v94, 1.0
	v_mul_f32_e64 v94, v95, -v94
	s_or_b64 exec, exec, s[56:57]
	v_add_f32_e32 v89, v89, v81
	v_mul_f32_e32 v89, 0xbfb8aa3b, v89
	v_exp_f32_e32 v89, v89
	s_nop 0
	v_add_f32_e32 v89, 1.0, v89
	v_rcp_f32_e32 v89, v89
	s_nop 0
	v_mul_f32_e32 v89, v77, v89
	v_mul_f32_e32 v89, 0x3fb8aa3b, v89
	v_cvt_pk_bf16_f32 v89, v89, 0
	v_lshlrev_b32_e32 v89, 16, v89
	v_add_f32_e32 v95, v89, v89
	v_mul_f32_e32 v96, 0x3f317218, v95
	v_cmp_nlt_f32_e32 vcc, s74, v96
	s_and_saveexec_b64 s[56:57], vcc
	s_xor_b64 s[56:57], exec, s[56:57]
	v_exp_f32_e32 v95, v89
	s_nop 0
	v_fma_f32 v95, -v95, v95, 1.0
	s_andn2_saveexec_b64 s[56:57], s[56:57]
	v_fmamk_f32 v95, v96, 0x3d2aaaab, v208
	v_fma_f32 v95, v96, v95, 0.5
	v_fma_f32 v95, v96, v95, 1.0
	v_mul_f32_e64 v95, v96, -v95
	s_or_b64 exec, exec, s[56:57]
	v_add_f32_e32 v90, v90, v82
	v_mul_f32_e32 v90, 0xbfb8aa3b, v90
	v_exp_f32_e32 v90, v90
	s_nop 0
	v_add_f32_e32 v90, 1.0, v90
	v_rcp_f32_e32 v90, v90
	s_nop 0
	v_mul_f32_e32 v90, v78, v90
	v_mul_f32_e32 v90, 0x3fb8aa3b, v90
	v_cvt_pk_bf16_f32 v90, v90, 0
	v_lshlrev_b32_e32 v90, 16, v90
	v_add_f32_e32 v96, v90, v90
	v_mul_f32_e32 v96, 0x3f317218, v96
	v_cmp_nlt_f32_e32 vcc, s74, v96
	s_and_saveexec_b64 s[56:57], vcc
	s_xor_b64 s[56:57], exec, s[56:57]
	v_exp_f32_e32 v96, v90
	s_nop 0
	v_fma_f32 v97, -v96, v96, 1.0
	s_andn2_saveexec_b64 s[56:57], s[56:57]
	v_fmamk_f32 v97, v96, 0x3d2aaaab, v208
	v_fma_f32 v97, v96, v97, 0.5
	v_fma_f32 v97, v96, v97, 1.0
	v_mul_f32_e64 v97, v96, -v97
	s_or_b64 exec, exec, s[56:57]
	v_add_f32_e32 v91, v91, v83
	v_mul_f32_e32 v91, 0xbfb8aa3b, v91
	v_exp_f32_e32 v91, v91
	s_nop 0
	v_add_f32_e32 v91, 1.0, v91
	v_rcp_f32_e32 v91, v91
	s_nop 0
	v_mul_f32_e32 v91, v79, v91
	v_mul_f32_e32 v91, 0x3fb8aa3b, v91
	v_cvt_pk_bf16_f32 v91, v91, 0
	v_lshlrev_b32_e32 v91, 16, v91
	v_add_f32_e32 v96, v91, v91
	v_mul_f32_e32 v98, 0x3f317218, v96
	v_cmp_nlt_f32_e32 vcc, s74, v98
	s_and_saveexec_b64 s[56:57], vcc
	s_xor_b64 s[56:57], exec, s[56:57]
	v_exp_f32_e32 v96, v91
	s_nop 0
	v_fma_f32 v96, -v96, v96, 1.0
	s_andn2_saveexec_b64 s[56:57], s[56:57]
	v_fmamk_f32 v96, v98, 0x3d2aaaab, v208
	v_fma_f32 v96, v98, v96, 0.5
	v_fma_f32 v96, v98, v96, 1.0
	v_mul_f32_e64 v96, v98, -v96
	s_or_b64 exec, exec, s[56:57]
	v_add_f32_e32 v86, v86, v70
	v_mul_f32_e32 v86, 0xbfb8aa3b, v86
	v_exp_f32_e32 v86, v86
	v_add_f32_e32 v84, v84, v68
	v_mul_f32_e32 v84, 0xbfb8aa3b, v84
	v_exp_f32_e32 v84, v84
	v_add_f32_e32 v85, v85, v69
	v_add_f32_e32 v87, v87, v71
	v_add_f32_e32 v86, 1.0, v86
	v_mul_f32_e32 v85, 0xbfb8aa3b, v85
	v_rcp_f32_e32 v86, v86
	v_mul_f32_e32 v87, 0xbfb8aa3b, v87
	v_exp_f32_e32 v85, v85
	v_add_f32_e32 v72, v72, v80
	v_sqrt_f32_e32 v97, v97
	v_exp_f32_e32 v87, v87
	v_add_f32_e32 v84, 1.0, v84
	v_mul_f32_e32 v72, 0xbfb8aa3b, v72
	v_rcp_f32_e32 v84, v84
	v_exp_f32_e32 v72, v72
	v_lshlrev_b32_e32 v98, 16, v181
	v_mul_f32_e32 v86, v86, v98
	v_sqrt_f32_e32 v94, v94
	v_add_f32_e32 v85, 1.0, v85
	v_mul_f32_e32 v97, v86, v97
	v_add_f32_e32 v86, 1.0, v87
	v_lshlrev_b32_e32 v87, 16, v180
	v_rcp_f32_e32 v85, v85
	v_mul_f32_e32 v84, v84, v87
	v_sqrt_f32_e32 v87, v95
	v_add_f32_e32 v72, 1.0, v72
	v_rcp_f32_e32 v72, v72
	v_mul_f32_e32 v94, v84, v94
	v_and_b32_e32 v84, 0xffff0000, v180
	v_rcp_f32_e32 v86, v86
	v_mul_f32_e32 v84, v85, v84
	v_mul_f32_e32 v95, v84, v87
	v_sqrt_f32_e32 v87, v96
	v_mul_f32_e32 v72, v76, v72
	v_lshlrev_b64 v[84:85], 11, v[164:165]
	v_and_b32_e32 v96, 0xffff0000, v181
	v_mul_f32_e32 v72, 0x3fb8aa3b, v72
	v_lshl_add_u64 v[84:85], v[84:85], 0, s[42:43]
	v_mul_f32_e32 v86, v86, v96
; __device__ __forceinline__ float bf_lo(unsigned w) { return __uint_as_float(w << 16); }
; __device__ __forceinline__ float bf_hi(unsigned w) { return __uint_as_float(w & 0xffff0000u); }
; __device__ __forceinline__ float fast_sigmoid(float x) { return __builtin_amdgcn_rcpf(1.0f + __builtin_amdgcn_exp2f(-x * LOG2E)); }
;     __device__ __forceinline__ void operator()(const f32x4 (&acc)[2][2][4][2], const Unit& u, int wr, int wc, int fr, int fq) const {
;     ...
;             const f32x4 ba = *(const f32x4*)(b_ga + ch0 + n * 16), bx = *(const f32x4*)(b_gx + ch0 + n * 16), sp = *(const f32x4*)(lam + ch0 + n * 16);
;             u32x2 xall[8];
; #pragma unroll
;             for (int it = 0; it < 8; ++it) xall[it] = *(const u32x2*)(xc + (size_t)(row0 + (it >> 2) * HALF + (it & 3) * 16) * DM + ch0 + n * 16);
;             asm volatile("" ::: "memory");
; #pragma unroll
;             for (int ai = 0; ai < 2; ++ai)
; #pragma unroll
;                 for (int m = 0; m < 4; ++m) { const int row = row0 + ai * HALF + m * 16; const size_t off = (size_t)row * DM + ch0 + n * 16;
;                     const u32x2 xw = xall[ai * 4 + m];
;                     const float xv[4] = {bf_lo(xw.x), bf_hi(xw.x), bf_lo(xw.y), bf_hi(xw.y)};
;                     f32x4 av; float bv[4];
; #pragma unroll
;                     for (int j = 0; j < 4; ++j) { const float r = fast_sigmoid(acc[ai][0][m][n][j] + ba[j]), ig = fast_sigmoid(acc[ai][1][m][n][j] + bx[j]);
;                         const float la = sp[j] * r; const float la2 = __uint_as_float(pk_bf16(la * LOG2E, 0.f) << 16);
;                         const float a = __builtin_amdgcn_exp2f(la2); const float x2 = 2.0f * la2 * 0.6931471805599453f; av[j] = la2;
;                         const float om = (x2 > -0.03f) ? -(x2 * (1.0f + x2 * (0.5f + x2 * (1.0f / 6.0f + x2 * (1.0f / 24.0f))))) : (1.0f - a * a);
;                         bv[j] = __builtin_amdgcn_sqrtf(om) * (ig * xv[j]); }
;                     { u32x2 wa; wa.x = pk_bf16(av[0], av[1]); wa.y = pk_bf16(av[2], av[3]); *(u32x2*)(aout + off) = wa; }
;                     u32x2 w; w.x = pk_bf16(bv[0], bv[1]); w.y = pk_bf16(bv[2], bv[3]); *(u32x2*)(bout + off) = w; }
	v_cvt_pk_bf16_f32 v72, v72, 0
	v_mul_f32_e32 v96, v86, v87
	v_lshl_add_u64 v[86:87], v[84:85], 0, v[152:153]
	v_lshlrev_b32_e32 v72, 16, v72
	v_lshlrev_b64 v[86:87], 1, v[86:87]
	v_add_f32_e32 v76, v72, v72
	v_cvt_pk_bf16_f32 v88, v88, v89
	v_cvt_pk_bf16_f32 v89, v90, v91
	v_lshl_add_u64 v[90:91], s[16:17], 0, v[86:87]
	v_mul_f32_e32 v80, 0x3f317218, v76
	global_store_dwordx2 v[90:91], v[88:89], off
	v_cvt_pk_bf16_f32 v88, v94, v95
	v_cvt_pk_bf16_f32 v89, v97, v96
	v_lshl_add_u64 v[86:87], s[18:19], 0, v[86:87]
	v_cmp_nlt_f32_e32 vcc, s74, v80
	global_store_dwordx2 v[86:87], v[88:89], off
	s_and_saveexec_b64 s[56:57], vcc
	s_xor_b64 s[56:57], exec, s[56:57]
	v_exp_f32_e32 v76, v72
	s_nop 0
	v_fma_f32 v76, -v76, v76, 1.0
	s_andn2_saveexec_b64 s[56:57], s[56:57]
	v_fmamk_f32 v76, v80, 0x3d2aaaab, v208
	v_fma_f32 v76, v80, v76, 0.5
	v_fma_f32 v76, v80, v76, 1.0
	v_mul_f32_e64 v76, v80, -v76
	s_or_b64 exec, exec, s[56:57]
	v_add_f32_e32 v73, v73, v81
	v_mul_f32_e32 v73, 0xbfb8aa3b, v73
	v_exp_f32_e32 v73, v73
	s_nop 0
	v_add_f32_e32 v73, 1.0, v73
	v_rcp_f32_e32 v73, v73
	s_nop 0
	v_mul_f32_e32 v73, v77, v73
	v_mul_f32_e32 v73, 0x3fb8aa3b, v73
	v_cvt_pk_bf16_f32 v73, v73, 0
	v_lshlrev_b32_e32 v73, 16, v73
	v_add_f32_e32 v77, v73, v73
	v_mul_f32_e32 v80, 0x3f317218, v77
	v_cmp_nlt_f32_e32 vcc, s74, v80
	s_and_saveexec_b64 s[56:57], vcc
	s_xor_b64 s[56:57], exec, s[56:57]
	v_exp_f32_e32 v77, v73
	s_nop 0
	v_fma_f32 v77, -v77, v77, 1.0
	s_andn2_saveexec_b64 s[56:57], s[56:57]
	v_fmamk_f32 v77, v80, 0x3d2aaaab, v208
	v_fma_f32 v77, v80, v77, 0.5
	v_fma_f32 v77, v80, v77, 1.0
	v_mul_f32_e64 v77, v80, -v77
	s_or_b64 exec, exec, s[56:57]
	v_add_f32_e32 v74, v74, v82
	v_mul_f32_e32 v74, 0xbfb8aa3b, v74
	v_exp_f32_e32 v74, v74
	s_nop 0
	v_add_f32_e32 v74, 1.0, v74
	v_rcp_f32_e32 v74, v74
	s_nop 0
	v_mul_f32_e32 v74, v78, v74
	v_mul_f32_e32 v74, 0x3fb8aa3b, v74
	v_cvt_pk_bf16_f32 v74, v74, 0
	v_lshlrev_b32_e32 v74, 16, v74
	v_add_f32_e32 v78, v74, v74
	v_mul_f32_e32 v78, 0x3f317218, v78
	v_cmp_nlt_f32_e32 vcc, s74, v78
	s_and_saveexec_b64 s[56:57], vcc
	s_xor_b64 s[56:57], exec, s[56:57]
	v_exp_f32_e32 v78, v74
	s_nop 0
	v_fma_f32 v80, -v78, v78, 1.0
	s_andn2_saveexec_b64 s[56:57], s[56:57]
	v_fmamk_f32 v80, v78, 0x3d2aaaab, v208
	v_fma_f32 v80, v78, v80, 0.5
	v_fma_f32 v80, v78, v80, 1.0
	v_mul_f32_e64 v80, v78, -v80
	s_or_b64 exec, exec, s[56:57]
	v_add_f32_e32 v75, v75, v83
	v_mul_f32_e32 v75, 0xbfb8aa3b, v75
	v_exp_f32_e32 v75, v75
	s_nop 0
	v_add_f32_e32 v75, 1.0, v75
	v_rcp_f32_e32 v75, v75
	s_nop 0
	v_mul_f32_e32 v75, v79, v75
	v_mul_f32_e32 v75, 0x3fb8aa3b, v75
	v_cvt_pk_bf16_f32 v75, v75, 0
	v_lshlrev_b32_e32 v75, 16, v75
	v_add_f32_e32 v78, v75, v75
	v_mul_f32_e32 v79, 0x3f317218, v78
	v_cmp_nlt_f32_e32 vcc, s74, v79
	s_and_saveexec_b64 s[56:57], vcc
	s_xor_b64 s[56:57], exec, s[56:57]
	v_exp_f32_e32 v78, v75
	s_nop 0
	v_fma_f32 v78, -v78, v78, 1.0
	s_andn2_saveexec_b64 s[56:57], s[56:57]
	v_fmamk_f32 v78, v79, 0x3d2aaaab, v208
	v_fma_f32 v78, v79, v78, 0.5
	v_fma_f32 v78, v79, v78, 1.0
	v_mul_f32_e64 v78, v79, -v78
	s_or_b64 exec, exec, s[56:57]
	v_add_f32_e32 v66, v66, v70
	v_mul_f32_e32 v66, 0xbfb8aa3b, v66
	v_exp_f32_e32 v66, v66
	v_add_f32_e32 v64, v64, v68
	v_mul_f32_e32 v64, 0xbfb8aa3b, v64
	v_exp_f32_e32 v64, v64
	v_add_f32_e32 v65, v65, v69
	v_add_f32_e32 v67, v67, v71
	v_add_f32_e32 v66, 1.0, v66
	v_mul_f32_e32 v65, 0xbfb8aa3b, v65
	v_rcp_f32_e32 v66, v66
	v_mul_f32_e32 v67, 0xbfb8aa3b, v67
	v_exp_f32_e32 v65, v65
	v_sqrt_f32_e32 v79, v80
	v_exp_f32_e32 v67, v67
	v_add_f32_e32 v64, 1.0, v64
	v_rcp_f32_e32 v64, v64
	v_lshlrev_b32_e32 v70, 16, v179
	v_mul_f32_e32 v66, v66, v70
	v_sqrt_f32_e32 v68, v76
	v_add_f32_e32 v65, 1.0, v65
	v_mul_f32_e32 v70, v66, v79
	v_add_f32_e32 v66, 1.0, v67
	v_lshlrev_b32_e32 v67, 16, v178
	v_rcp_f32_e32 v65, v65
	v_mul_f32_e32 v64, v64, v67
	v_sqrt_f32_e32 v67, v77
	v_mul_f32_e32 v71, v64, v68
	v_and_b32_e32 v64, 0xffff0000, v178
	v_rcp_f32_e32 v66, v66
	v_mul_f32_e32 v64, v65, v64
	v_mul_f32_e32 v79, v64, v67
	v_sqrt_f32_e32 v67, v78
	v_lshlrev_b64 v[64:65], 11, v[164:165]
	v_lshl_add_u64 v[76:77], v[64:65], 0, s[44:45]
	v_and_b32_e32 v64, 0xffff0000, v179
	v_mul_f32_e32 v64, v66, v64
	v_mul_f32_e32 v78, v64, v67
	v_lshl_add_u64 v[64:65], v[76:77], 0, v[152:153]
	v_lshlrev_b64 v[64:65], 1, v[64:65]
	v_cvt_pk_bf16_f32 v66, v72, v73
	v_cvt_pk_bf16_f32 v67, v74, v75
	v_lshl_add_u64 v[68:69], s[16:17], 0, v[64:65]
	global_store_dwordx2 v[68:69], v[66:67], off
	v_cvt_pk_bf16_f32 v66, v71, v79
	v_cvt_pk_bf16_f32 v67, v70, v78
	v_lshl_add_u64 v[64:65], s[18:19], 0, v[64:65]
	global_store_dwordx2 v[64:65], v[66:67], off
	global_load_dwordx4 v[72:75], v[154:155], off offset:64
	s_nop 0
	global_load_dwordx4 v[64:67], v[156:157], off offset:64
	global_load_dwordx4 v[68:71], v[158:159], off offset:64
	global_load_dwordx2 v[96:97], v[160:161], off offset:32
	global_load_dwordx2 v[94:95], v[162:163], off offset:32
	global_load_dwordx2 v[90:91], v[166:167], off offset:32
	global_load_dwordx2 v[88:89], v[168:169], off offset:32
	global_load_dwordx2 v[86:87], v[170:171], off offset:32
	global_load_dwordx2 v[82:83], v[172:173], off offset:32
	global_load_dwordx2 v[80:81], v[174:175], off offset:32
	global_load_dwordx2 v[78:79], v[176:177], off offset:32
	s_waitcnt vmcnt(0)
; __device__ __forceinline__ float bf_lo(unsigned w) { return __uint_as_float(w << 16); }
; __device__ __forceinline__ float bf_hi(unsigned w) { return __uint_as_float(w & 0xffff0000u); }
; __device__ __forceinline__ float fast_sigmoid(float x) { return __builtin_amdgcn_rcpf(1.0f + __builtin_amdgcn_exp2f(-x * LOG2E)); }
;     __device__ __forceinline__ void operator()(const f32x4 (&acc)[2][2][4][2], const Unit& u, int wr, int wc, int fr, int fq) const {
;     ...
;                 for (int m = 0; m < 4; ++m) { const int row = row0 + ai * HALF + m * 16; const size_t off = (size_t)row * DM + ch0 + n * 16;
;                     const u32x2 xw = xall[ai * 4 + m];
;                     const float xv[4] = {bf_lo(xw.x), bf_hi(xw.x), bf_lo(xw.y), bf_hi(xw.y)};
;                     f32x4 av; float bv[4];
; #pragma unroll
;                     for (int j = 0; j < 4; ++j) { const float r = fast_sigmoid(acc[ai][0][m][n][j] + ba[j]), ig = fast_sigmoid(acc[ai][1][m][n][j] + bx[j]);
;                         const float la = sp[j] * r; const float la2 = __uint_as_float(pk_bf16(la * LOG2E, 0.f) << 16);
;                         const float a = __builtin_amdgcn_exp2f(la2); const float x2 = 2.0f * la2 * 0.6931471805599453f; av[j] = la2;
;                         const float om = (x2 > -0.03f) ? -(x2 * (1.0f + x2 * (0.5f + x2 * (1.0f / 6.0f + x2 * (1.0f / 24.0f))))) : (1.0f - a * a);
;                         bv[j] = __builtin_amdgcn_sqrtf(om) * (ig * xv[j]); }
;                     { u32x2 wa; wa.x = pk_bf16(av[0], av[1]); wa.y = pk_bf16(av[2], av[3]); *(u32x2*)(aout + off) = wa; }
;                     u32x2 w; w.x = pk_bf16(bv[0], bv[1]); w.y = pk_bf16(bv[2], bv[3]); *(u32x2*)(bout + off) = w; }
	v_add_f32_e32 v60, v60, v72
	v_mul_f32_e32 v60, 0xbfb8aa3b, v60
	v_exp_f32_e32 v60, v60
	s_nop 0
	v_add_f32_e32 v60, 1.0, v60
	v_rcp_f32_e32 v60, v60
	s_nop 0
	v_mul_f32_e32 v60, v68, v60
	v_mul_f32_e32 v60, 0x3fb8aa3b, v60
	v_cvt_pk_bf16_f32 v60, v60, 0
	v_lshlrev_b32_e32 v60, 16, v60
	v_add_f32_e32 v98, v60, v60
	v_mul_f32_e32 v99, 0x3f317218, v98
	v_cmp_nlt_f32_e32 vcc, s74, v99
	s_and_saveexec_b64 s[56:57], vcc
	s_xor_b64 s[56:57], exec, s[56:57]
	v_exp_f32_e32 v98, v60
	s_nop 0
	v_fma_f32 v98, -v98, v98, 1.0
	s_andn2_saveexec_b64 s[56:57], s[56:57]
	v_fmamk_f32 v98, v99, 0x3d2aaaab, v208
	v_fma_f32 v98, v99, v98, 0.5
	v_fma_f32 v98, v99, v98, 1.0
	v_mul_f32_e64 v98, v99, -v98
	s_or_b64 exec, exec, s[56:57]
	v_add_f32_e32 v61, v61, v73
	v_mul_f32_e32 v61, 0xbfb8aa3b, v61
	v_exp_f32_e32 v61, v61
	s_nop 0
	v_add_f32_e32 v61, 1.0, v61
	v_rcp_f32_e32 v61, v61
	s_nop 0
	v_mul_f32_e32 v61, v69, v61
	v_mul_f32_e32 v61, 0x3fb8aa3b, v61
	v_cvt_pk_bf16_f32 v61, v61, 0
	v_lshlrev_b32_e32 v61, 16, v61
	v_add_f32_e32 v99, v61, v61
	v_mul_f32_e32 v102, 0x3f317218, v99
	v_cmp_nlt_f32_e32 vcc, s74, v102
	s_and_saveexec_b64 s[56:57], vcc
	s_xor_b64 s[56:57], exec, s[56:57]
	v_exp_f32_e32 v99, v61
	s_nop 0
	v_fma_f32 v99, -v99, v99, 1.0
	s_andn2_saveexec_b64 s[56:57], s[56:57]
	v_fmamk_f32 v99, v102, 0x3d2aaaab, v208
	v_fma_f32 v99, v102, v99, 0.5
	v_fma_f32 v99, v102, v99, 1.0
	v_mul_f32_e64 v99, v102, -v99
	s_or_b64 exec, exec, s[56:57]
	v_add_f32_e32 v62, v62, v74
	v_mul_f32_e32 v62, 0xbfb8aa3b, v62
	v_exp_f32_e32 v62, v62
	s_nop 0
	v_add_f32_e32 v62, 1.0, v62
	v_rcp_f32_e32 v62, v62
	s_nop 0
	v_mul_f32_e32 v62, v70, v62
	v_mul_f32_e32 v62, 0x3fb8aa3b, v62
	v_cvt_pk_bf16_f32 v62, v62, 0
	v_lshlrev_b32_e32 v62, 16, v62
	v_add_f32_e32 v102, v62, v62
	v_mul_f32_e32 v103, 0x3f317218, v102
	v_cmp_nlt_f32_e32 vcc, s74, v103
	s_and_saveexec_b64 s[56:57], vcc
	s_xor_b64 s[56:57], exec, s[56:57]
	v_exp_f32_e32 v102, v62
	s_nop 0
	v_fma_f32 v102, -v102, v102, 1.0
	s_andn2_saveexec_b64 s[56:57], s[56:57]
	v_fmamk_f32 v102, v103, 0x3d2aaaab, v208
	v_fma_f32 v102, v103, v102, 0.5
	v_fma_f32 v102, v103, v102, 1.0
	v_mul_f32_e64 v102, v103, -v102
	s_or_b64 exec, exec, s[56:57]
	v_add_f32_e32 v63, v63, v75
	v_mul_f32_e32 v63, 0xbfb8aa3b, v63
	v_exp_f32_e32 v63, v63
	s_nop 0
	v_add_f32_e32 v63, 1.0, v63
	v_rcp_f32_e32 v63, v63
	s_nop 0
	v_mul_f32_e32 v63, v71, v63
	v_mul_f32_e32 v63, 0x3fb8aa3b, v63
	v_cvt_pk_bf16_f32 v63, v63, 0
	v_lshlrev_b32_e32 v63, 16, v63
	v_add_f32_e32 v103, v63, v63
	v_mul_f32_e32 v104, 0x3f317218, v103
	v_cmp_nlt_f32_e32 vcc, s74, v104
	s_and_saveexec_b64 s[56:57], vcc
	s_xor_b64 s[56:57], exec, s[56:57]
	v_exp_f32_e32 v103, v63
	s_nop 0
	v_fma_f32 v103, -v103, v103, 1.0
	s_andn2_saveexec_b64 s[56:57], s[56:57]
	v_fmamk_f32 v103, v104, 0x3d2aaaab, v208
	v_fma_f32 v103, v104, v103, 0.5
	v_fma_f32 v103, v104, v103, 1.0
	v_mul_f32_e64 v103, v104, -v103
	s_or_b64 exec, exec, s[56:57]
	v_add_f32_e32 v58, v58, v66
	v_mul_f32_e32 v58, 0xbfb8aa3b, v58
	v_exp_f32_e32 v58, v58
	v_add_f32_e32 v56, v56, v64
	v_mul_f32_e32 v56, 0xbfb8aa3b, v56
	v_exp_f32_e32 v56, v56
	v_add_f32_e32 v57, v57, v65
	v_add_f32_e32 v59, v59, v67
	v_add_f32_e32 v58, 1.0, v58
	v_mul_f32_e32 v57, 0xbfb8aa3b, v57
	v_rcp_f32_e32 v58, v58
	v_mul_f32_e32 v59, 0xbfb8aa3b, v59
	v_exp_f32_e32 v57, v57
	v_sqrt_f32_e32 v102, v102
	v_exp_f32_e32 v59, v59
	v_add_f32_e32 v56, 1.0, v56
	v_rcp_f32_e32 v56, v56
	v_lshlrev_b32_e32 v104, 16, v97
	v_add_f32_e32 v52, v52, v72
	v_mul_f32_e32 v58, v58, v104
	v_sqrt_f32_e32 v98, v98
	v_add_f32_e32 v57, 1.0, v57
	v_mul_f32_e32 v52, 0xbfb8aa3b, v52
	v_mul_f32_e32 v102, v58, v102
	v_add_f32_e32 v58, 1.0, v59
	v_lshlrev_b32_e32 v59, 16, v96
	v_rcp_f32_e32 v57, v57
	v_exp_f32_e32 v52, v52
	v_mul_f32_e32 v56, v56, v59
	v_sqrt_f32_e32 v59, v99
	v_mul_f32_e32 v98, v56, v98
	v_and_b32_e32 v56, 0xffff0000, v96
	v_rcp_f32_e32 v58, v58
	v_mul_f32_e32 v56, v57, v56
	v_add_f32_e32 v52, 1.0, v52
	v_mul_f32_e32 v96, v56, v59
	v_sqrt_f32_e32 v56, v103
	v_rcp_f32_e32 v52, v52
	v_and_b32_e32 v57, 0xffff0000, v97
	v_or_b32_e32 v152, 16, v152
	v_mul_f32_e32 v57, v58, v57
	v_mul_f32_e32 v97, v57, v56
	v_lshl_add_u64 v[56:57], v[132:133], 0, v[152:153]
	v_mul_f32_e32 v52, v68, v52
	v_lshlrev_b64 v[56:57], 1, v[56:57]
	v_mul_f32_e32 v52, 0x3fb8aa3b, v52
	v_cvt_pk_bf16_f32 v58, v60, v61
	v_cvt_pk_bf16_f32 v59, v62, v63
	v_lshl_add_u64 v[60:61], s[16:17], 0, v[56:57]
	v_cvt_pk_bf16_f32 v52, v52, 0
	global_store_dwordx2 v[60:61], v[58:59], off
	v_cvt_pk_bf16_f32 v58, v98, v96
	v_cvt_pk_bf16_f32 v59, v102, v97
	v_lshl_add_u64 v[56:57], s[18:19], 0, v[56:57]
	v_lshlrev_b32_e32 v52, 16, v52
	global_store_dwordx2 v[56:57], v[58:59], off
	v_add_f32_e32 v56, v52, v52
	v_mul_f32_e32 v57, 0x3f317218, v56
	v_cmp_nlt_f32_e32 vcc, s74, v57
	s_and_saveexec_b64 s[56:57], vcc
	s_xor_b64 s[56:57], exec, s[56:57]
	v_exp_f32_e32 v56, v52
	s_nop 0
	v_fma_f32 v56, -v56, v56, 1.0
	s_andn2_saveexec_b64 s[56:57], s[56:57]
	v_fmamk_f32 v56, v57, 0x3d2aaaab, v208
	v_fma_f32 v56, v57, v56, 0.5
	v_fma_f32 v56, v57, v56, 1.0
	v_mul_f32_e64 v56, v57, -v56
	s_or_b64 exec, exec, s[56:57]
	v_add_f32_e32 v53, v53, v73
	v_mul_f32_e32 v53, 0xbfb8aa3b, v53
	v_exp_f32_e32 v53, v53
	s_nop 0
	v_add_f32_e32 v53, 1.0, v53
	v_rcp_f32_e32 v53, v53
	s_nop 0
	v_mul_f32_e32 v53, v69, v53
	v_mul_f32_e32 v53, 0x3fb8aa3b, v53
	v_cvt_pk_bf16_f32 v53, v53, 0
	v_lshlrev_b32_e32 v53, 16, v53
	v_add_f32_e32 v57, v53, v53
	v_mul_f32_e32 v58, 0x3f317218, v57
	v_cmp_nlt_f32_e32 vcc, s74, v58
	s_and_saveexec_b64 s[56:57], vcc
	s_xor_b64 s[56:57], exec, s[56:57]
	v_exp_f32_e32 v57, v53
	s_nop 0
	v_fma_f32 v57, -v57, v57, 1.0
; __device__ __forceinline__ float bf_lo(unsigned w) { return __uint_as_float(w << 16); }
; __device__ __forceinline__ float bf_hi(unsigned w) { return __uint_as_float(w & 0xffff0000u); }
; __device__ __forceinline__ float fast_sigmoid(float x) { return __builtin_amdgcn_rcpf(1.0f + __builtin_amdgcn_exp2f(-x * LOG2E)); }
;     __device__ __forceinline__ void operator()(const f32x4 (&acc)[2][2][4][2], const Unit& u, int wr, int wc, int fr, int fq) const {
;     ...
;                 for (int m = 0; m < 4; ++m) { const int row = row0 + ai * HALF + m * 16; const size_t off = (size_t)row * DM + ch0 + n * 16;
;                     const u32x2 xw = xall[ai * 4 + m];
;                     const float xv[4] = {bf_lo(xw.x), bf_hi(xw.x), bf_lo(xw.y), bf_hi(xw.y)};
;                     f32x4 av; float bv[4];
; #pragma unroll
;                     for (int j = 0; j < 4; ++j) { const float r = fast_sigmoid(acc[ai][0][m][n][j] + ba[j]), ig = fast_sigmoid(acc[ai][1][m][n][j] + bx[j]);
;                         const float la = sp[j] * r; const float la2 = __uint_as_float(pk_bf16(la * LOG2E, 0.f) << 16);
;                         const float a = __builtin_amdgcn_exp2f(la2); const float x2 = 2.0f * la2 * 0.6931471805599453f; av[j] = la2;
;                         const float om = (x2 > -0.03f) ? -(x2 * (1.0f + x2 * (0.5f + x2 * (1.0f / 6.0f + x2 * (1.0f / 24.0f))))) : (1.0f - a * a);
;                         bv[j] = __builtin_amdgcn_sqrtf(om) * (ig * xv[j]); }
;                     { u32x2 wa; wa.x = pk_bf16(av[0], av[1]); wa.y = pk_bf16(av[2], av[3]); *(u32x2*)(aout + off) = wa; }
;                     u32x2 w; w.x = pk_bf16(bv[0], bv[1]); w.y = pk_bf16(bv[2], bv[3]); *(u32x2*)(bout + off) = w; }
	s_andn2_saveexec_b64 s[56:57], s[56:57]
	v_fmamk_f32 v57, v58, 0x3d2aaaab, v208
	v_fma_f32 v57, v58, v57, 0.5
	v_fma_f32 v57, v58, v57, 1.0
	v_mul_f32_e64 v57, v58, -v57
	s_or_b64 exec, exec, s[56:57]
	v_add_f32_e32 v54, v54, v74
	v_mul_f32_e32 v54, 0xbfb8aa3b, v54
	v_exp_f32_e32 v54, v54
	s_nop 0
	v_add_f32_e32 v54, 1.0, v54
	v_rcp_f32_e32 v54, v54
	s_nop 0
	v_mul_f32_e32 v54, v70, v54
	v_mul_f32_e32 v54, 0x3fb8aa3b, v54
	v_cvt_pk_bf16_f32 v54, v54, 0
	v_lshlrev_b32_e32 v54, 16, v54
	v_add_f32_e32 v58, v54, v54
	v_mul_f32_e32 v59, 0x3f317218, v58
	v_cmp_nlt_f32_e32 vcc, s74, v59
	s_and_saveexec_b64 s[56:57], vcc
	s_xor_b64 s[56:57], exec, s[56:57]
	v_exp_f32_e32 v58, v54
	s_nop 0
	v_fma_f32 v58, -v58, v58, 1.0
	s_andn2_saveexec_b64 s[56:57], s[56:57]
	v_fmamk_f32 v58, v59, 0x3d2aaaab, v208
	v_fma_f32 v58, v59, v58, 0.5
	v_fma_f32 v58, v59, v58, 1.0
	v_mul_f32_e64 v58, v59, -v58
	s_or_b64 exec, exec, s[56:57]
	v_add_f32_e32 v55, v55, v75
	v_mul_f32_e32 v55, 0xbfb8aa3b, v55
	v_exp_f32_e32 v55, v55
	s_nop 0
	v_add_f32_e32 v55, 1.0, v55
	v_rcp_f32_e32 v55, v55
	s_nop 0
	v_mul_f32_e32 v55, v71, v55
	v_mul_f32_e32 v55, 0x3fb8aa3b, v55
	v_cvt_pk_bf16_f32 v55, v55, 0
	v_lshlrev_b32_e32 v55, 16, v55
	v_add_f32_e32 v59, v55, v55
	v_mul_f32_e32 v60, 0x3f317218, v59
	v_cmp_nlt_f32_e32 vcc, s74, v60
	s_and_saveexec_b64 s[56:57], vcc
	s_xor_b64 s[56:57], exec, s[56:57]
	v_exp_f32_e32 v59, v55
	s_nop 0
	v_fma_f32 v59, -v59, v59, 1.0
	s_andn2_saveexec_b64 s[56:57], s[56:57]
	v_fmamk_f32 v59, v60, 0x3d2aaaab, v208
	v_fma_f32 v59, v60, v59, 0.5
	v_fma_f32 v59, v60, v59, 1.0
	v_mul_f32_e64 v59, v60, -v59
	s_or_b64 exec, exec, s[56:57]
	v_add_f32_e32 v50, v50, v66
	v_mul_f32_e32 v50, 0xbfb8aa3b, v50
	v_exp_f32_e32 v50, v50
	v_add_f32_e32 v48, v48, v64
	v_mul_f32_e32 v48, 0xbfb8aa3b, v48
	v_exp_f32_e32 v48, v48
	v_add_f32_e32 v49, v49, v65
	v_add_f32_e32 v51, v51, v67
	v_add_f32_e32 v50, 1.0, v50
	v_mul_f32_e32 v49, 0xbfb8aa3b, v49
	v_rcp_f32_e32 v50, v50
	v_mul_f32_e32 v51, 0xbfb8aa3b, v51
	v_exp_f32_e32 v49, v49
	v_sqrt_f32_e32 v58, v58
	v_exp_f32_e32 v51, v51
	v_add_f32_e32 v48, 1.0, v48
	v_rcp_f32_e32 v48, v48
	v_add_f32_e32 v44, v44, v72
	v_lshlrev_b32_e32 v60, 16, v95
	v_sqrt_f32_e32 v56, v56
	v_mul_f32_e32 v44, 0xbfb8aa3b, v44
	v_mul_f32_e32 v50, v50, v60
	v_add_f32_e32 v49, 1.0, v49
	v_exp_f32_e32 v44, v44
	v_mul_f32_e32 v58, v50, v58
	v_add_f32_e32 v50, 1.0, v51
	v_lshlrev_b32_e32 v51, 16, v94
	v_rcp_f32_e32 v49, v49
	v_mul_f32_e32 v48, v48, v51
	v_mul_f32_e32 v56, v48, v56
	v_sqrt_f32_e32 v48, v57
	v_rcp_f32_e32 v50, v50
	v_and_b32_e32 v51, 0xffff0000, v94
	v_add_f32_e32 v44, 1.0, v44
	v_mul_f32_e32 v49, v49, v51
	v_sqrt_f32_e32 v51, v59
	v_rcp_f32_e32 v44, v44
	v_mul_f32_e32 v57, v49, v48
	v_and_b32_e32 v48, 0xffff0000, v95
	v_mul_f32_e32 v48, v50, v48
	v_mul_f32_e32 v59, v48, v51
	v_lshl_add_u64 v[48:49], v[124:125], 0, v[152:153]
	v_mul_f32_e32 v44, v68, v44
	v_lshlrev_b64 v[48:49], 1, v[48:49]
	v_mul_f32_e32 v44, 0x3fb8aa3b, v44
	v_cvt_pk_bf16_f32 v50, v52, v53
	v_cvt_pk_bf16_f32 v51, v54, v55
	v_lshl_add_u64 v[52:53], s[16:17], 0, v[48:49]
	v_cvt_pk_bf16_f32 v44, v44, 0
	global_store_dwordx2 v[52:53], v[50:51], off
	v_cvt_pk_bf16_f32 v50, v56, v57
	v_cvt_pk_bf16_f32 v51, v58, v59
	v_lshl_add_u64 v[48:49], s[18:19], 0, v[48:49]
	v_lshlrev_b32_e32 v44, 16, v44
	global_store_dwordx2 v[48:49], v[50:51], off
	v_add_f32_e32 v48, v44, v44
	v_mul_f32_e32 v49, 0x3f317218, v48
	v_cmp_nlt_f32_e32 vcc, s74, v49
	s_and_saveexec_b64 s[56:57], vcc
	s_xor_b64 s[56:57], exec, s[56:57]
	v_exp_f32_e32 v48, v44
	s_nop 0
	v_fma_f32 v48, -v48, v48, 1.0
	s_andn2_saveexec_b64 s[56:57], s[56:57]
	v_fmamk_f32 v48, v49, 0x3d2aaaab, v208
	v_fma_f32 v48, v49, v48, 0.5
	v_fma_f32 v48, v49, v48, 1.0
	v_mul_f32_e64 v48, v49, -v48
	s_or_b64 exec, exec, s[56:57]
	v_add_f32_e32 v45, v45, v73
	v_mul_f32_e32 v45, 0xbfb8aa3b, v45
	v_exp_f32_e32 v45, v45
	s_nop 0
	v_add_f32_e32 v45, 1.0, v45
	v_rcp_f32_e32 v45, v45
	s_nop 0
	v_mul_f32_e32 v45, v69, v45
	v_mul_f32_e32 v45, 0x3fb8aa3b, v45
	v_cvt_pk_bf16_f32 v45, v45, 0
	v_lshlrev_b32_e32 v45, 16, v45
	v_add_f32_e32 v49, v45, v45
	v_mul_f32_e32 v50, 0x3f317218, v49
	v_cmp_nlt_f32_e32 vcc, s74, v50
	s_and_saveexec_b64 s[56:57], vcc
	s_xor_b64 s[56:57], exec, s[56:57]
	v_exp_f32_e32 v49, v45
	s_nop 0
	v_fma_f32 v49, -v49, v49, 1.0
	s_andn2_saveexec_b64 s[56:57], s[56:57]
	v_fmamk_f32 v49, v50, 0x3d2aaaab, v208
	v_fma_f32 v49, v50, v49, 0.5
	v_fma_f32 v49, v50, v49, 1.0
	v_mul_f32_e64 v49, v50, -v49
	s_or_b64 exec, exec, s[56:57]
	v_add_f32_e32 v46, v46, v74
	v_mul_f32_e32 v46, 0xbfb8aa3b, v46
	v_exp_f32_e32 v46, v46
	s_nop 0
	v_add_f32_e32 v46, 1.0, v46
	v_rcp_f32_e32 v46, v46
	s_nop 0
	v_mul_f32_e32 v46, v70, v46
	v_mul_f32_e32 v46, 0x3fb8aa3b, v46
	v_cvt_pk_bf16_f32 v46, v46, 0
	v_lshlrev_b32_e32 v46, 16, v46
	v_add_f32_e32 v50, v46, v46
	v_mul_f32_e32 v51, 0x3f317218, v50
	v_cmp_nlt_f32_e32 vcc, s74, v51
	s_and_saveexec_b64 s[56:57], vcc
	s_xor_b64 s[56:57], exec, s[56:57]
	v_exp_f32_e32 v50, v46
	s_nop 0
	v_fma_f32 v50, -v50, v50, 1.0
	s_andn2_saveexec_b64 s[56:57], s[56:57]
	v_fmamk_f32 v50, v51, 0x3d2aaaab, v208
	v_fma_f32 v50, v51, v50, 0.5
	v_fma_f32 v50, v51, v50, 1.0
	v_mul_f32_e64 v50, v51, -v50
	s_or_b64 exec, exec, s[56:57]
	v_add_f32_e32 v47, v47, v75
	v_mul_f32_e32 v47, 0xbfb8aa3b, v47
	v_exp_f32_e32 v47, v47
	s_nop 0
	v_add_f32_e32 v47, 1.0, v47
	v_rcp_f32_e32 v47, v47
	s_nop 0
	v_mul_f32_e32 v47, v71, v47
	v_mul_f32_e32 v47, 0x3fb8aa3b, v47
	v_cvt_pk_bf16_f32 v47, v47, 0
	v_lshlrev_b32_e32 v47, 16, v47
	v_add_f32_e32 v51, v47, v47
	v_mul_f32_e32 v52, 0x3f317218, v51
	v_cmp_nlt_f32_e32 vcc, s74, v52
; __device__ __forceinline__ float bf_lo(unsigned w) { return __uint_as_float(w << 16); }
; __device__ __forceinline__ float bf_hi(unsigned w) { return __uint_as_float(w & 0xffff0000u); }
; __device__ __forceinline__ float fast_sigmoid(float x) { return __builtin_amdgcn_rcpf(1.0f + __builtin_amdgcn_exp2f(-x * LOG2E)); }
;     __device__ __forceinline__ void operator()(const f32x4 (&acc)[2][2][4][2], const Unit& u, int wr, int wc, int fr, int fq) const {
;     ...
;                 for (int m = 0; m < 4; ++m) { const int row = row0 + ai * HALF + m * 16; const size_t off = (size_t)row * DM + ch0 + n * 16;
;                     const u32x2 xw = xall[ai * 4 + m];
;                     const float xv[4] = {bf_lo(xw.x), bf_hi(xw.x), bf_lo(xw.y), bf_hi(xw.y)};
;                     f32x4 av; float bv[4];
; #pragma unroll
;                     for (int j = 0; j < 4; ++j) { const float r = fast_sigmoid(acc[ai][0][m][n][j] + ba[j]), ig = fast_sigmoid(acc[ai][1][m][n][j] + bx[j]);
;                         const float la = sp[j] * r; const float la2 = __uint_as_float(pk_bf16(la * LOG2E, 0.f) << 16);
;                         const float a = __builtin_amdgcn_exp2f(la2); const float x2 = 2.0f * la2 * 0.6931471805599453f; av[j] = la2;
;                         const float om = (x2 > -0.03f) ? -(x2 * (1.0f + x2 * (0.5f + x2 * (1.0f / 6.0f + x2 * (1.0f / 24.0f))))) : (1.0f - a * a);
;                         bv[j] = __builtin_amdgcn_sqrtf(om) * (ig * xv[j]); }
;                     { u32x2 wa; wa.x = pk_bf16(av[0], av[1]); wa.y = pk_bf16(av[2], av[3]); *(u32x2*)(aout + off) = wa; }
;                     u32x2 w; w.x = pk_bf16(bv[0], bv[1]); w.y = pk_bf16(bv[2], bv[3]); *(u32x2*)(bout + off) = w; }
	s_and_saveexec_b64 s[56:57], vcc
	s_xor_b64 s[56:57], exec, s[56:57]
	v_exp_f32_e32 v51, v47
	s_nop 0
	v_fma_f32 v51, -v51, v51, 1.0
	s_andn2_saveexec_b64 s[56:57], s[56:57]
	v_fmamk_f32 v51, v52, 0x3d2aaaab, v208
	v_fma_f32 v51, v52, v51, 0.5
	v_fma_f32 v51, v52, v51, 1.0
	v_mul_f32_e64 v51, v52, -v51
	s_or_b64 exec, exec, s[56:57]
	v_add_f32_e32 v42, v42, v66
	v_mul_f32_e32 v42, 0xbfb8aa3b, v42
	v_exp_f32_e32 v42, v42
	v_add_f32_e32 v40, v40, v64
	v_mul_f32_e32 v40, 0xbfb8aa3b, v40
	v_exp_f32_e32 v40, v40
	v_add_f32_e32 v41, v41, v65
	v_add_f32_e32 v43, v43, v67
	v_add_f32_e32 v42, 1.0, v42
	v_mul_f32_e32 v41, 0xbfb8aa3b, v41
	v_rcp_f32_e32 v42, v42
	v_mul_f32_e32 v43, 0xbfb8aa3b, v43
	v_exp_f32_e32 v41, v41
	v_sqrt_f32_e32 v50, v50
	v_exp_f32_e32 v43, v43
	v_add_f32_e32 v40, 1.0, v40
	v_rcp_f32_e32 v40, v40
	v_add_f32_e32 v36, v36, v72
	v_lshlrev_b32_e32 v52, 16, v91
	v_sqrt_f32_e32 v48, v48
	v_mul_f32_e32 v36, 0xbfb8aa3b, v36
	v_mul_f32_e32 v42, v42, v52
	v_add_f32_e32 v41, 1.0, v41
	v_exp_f32_e32 v36, v36
	v_mul_f32_e32 v50, v42, v50
	v_add_f32_e32 v42, 1.0, v43
	v_lshlrev_b32_e32 v43, 16, v90
	v_rcp_f32_e32 v41, v41
	v_mul_f32_e32 v40, v40, v43
	v_mul_f32_e32 v48, v40, v48
	v_sqrt_f32_e32 v40, v49
	v_rcp_f32_e32 v42, v42
	v_and_b32_e32 v43, 0xffff0000, v90
	v_add_f32_e32 v36, 1.0, v36
	v_mul_f32_e32 v41, v41, v43
	v_sqrt_f32_e32 v43, v51
	v_rcp_f32_e32 v36, v36
	v_mul_f32_e32 v49, v41, v40
	v_and_b32_e32 v40, 0xffff0000, v91
	v_mul_f32_e32 v40, v42, v40
	v_mul_f32_e32 v51, v40, v43
	v_lshl_add_u64 v[40:41], v[116:117], 0, v[152:153]
	v_mul_f32_e32 v36, v68, v36
	v_lshlrev_b64 v[40:41], 1, v[40:41]
	v_mul_f32_e32 v36, 0x3fb8aa3b, v36
	v_cvt_pk_bf16_f32 v42, v44, v45
	v_cvt_pk_bf16_f32 v43, v46, v47
	v_lshl_add_u64 v[44:45], s[16:17], 0, v[40:41]
	v_cvt_pk_bf16_f32 v36, v36, 0
	global_store_dwordx2 v[44:45], v[42:43], off
	v_cvt_pk_bf16_f32 v42, v48, v49
	v_cvt_pk_bf16_f32 v43, v50, v51
	v_lshl_add_u64 v[40:41], s[18:19], 0, v[40:41]
	v_lshlrev_b32_e32 v36, 16, v36
	global_store_dwordx2 v[40:41], v[42:43], off
	v_add_f32_e32 v40, v36, v36
	v_mul_f32_e32 v41, 0x3f317218, v40
	v_cmp_nlt_f32_e32 vcc, s74, v41
	s_and_saveexec_b64 s[56:57], vcc
	s_xor_b64 s[56:57], exec, s[56:57]
	v_exp_f32_e32 v40, v36
	s_nop 0
	v_fma_f32 v40, -v40, v40, 1.0
	s_andn2_saveexec_b64 s[56:57], s[56:57]
	v_fmamk_f32 v40, v41, 0x3d2aaaab, v208
	v_fma_f32 v40, v41, v40, 0.5
	v_fma_f32 v40, v41, v40, 1.0
	v_mul_f32_e64 v40, v41, -v40
	s_or_b64 exec, exec, s[56:57]
	v_add_f32_e32 v37, v37, v73
	v_mul_f32_e32 v37, 0xbfb8aa3b, v37
	v_exp_f32_e32 v37, v37
	s_nop 0
	v_add_f32_e32 v37, 1.0, v37
	v_rcp_f32_e32 v37, v37
	s_nop 0
	v_mul_f32_e32 v37, v69, v37
	v_mul_f32_e32 v37, 0x3fb8aa3b, v37
	v_cvt_pk_bf16_f32 v37, v37, 0
	v_lshlrev_b32_e32 v37, 16, v37
	v_add_f32_e32 v41, v37, v37
	v_mul_f32_e32 v42, 0x3f317218, v41
	v_cmp_nlt_f32_e32 vcc, s74, v42
	s_and_saveexec_b64 s[56:57], vcc
	s_xor_b64 s[56:57], exec, s[56:57]
	v_exp_f32_e32 v41, v37
	s_nop 0
	v_fma_f32 v41, -v41, v41, 1.0
	s_andn2_saveexec_b64 s[56:57], s[56:57]
	v_fmamk_f32 v41, v42, 0x3d2aaaab, v208
	v_fma_f32 v41, v42, v41, 0.5
	v_fma_f32 v41, v42, v41, 1.0
	v_mul_f32_e64 v41, v42, -v41
	s_or_b64 exec, exec, s[56:57]
	v_add_f32_e32 v38, v38, v74
	v_mul_f32_e32 v38, 0xbfb8aa3b, v38
	v_exp_f32_e32 v38, v38
	s_nop 0
	v_add_f32_e32 v38, 1.0, v38
	v_rcp_f32_e32 v38, v38
	s_nop 0
	v_mul_f32_e32 v38, v70, v38
	v_mul_f32_e32 v38, 0x3fb8aa3b, v38
	v_cvt_pk_bf16_f32 v38, v38, 0
	v_lshlrev_b32_e32 v38, 16, v38
	v_add_f32_e32 v42, v38, v38
	v_mul_f32_e32 v43, 0x3f317218, v42
	v_cmp_nlt_f32_e32 vcc, s74, v43
	s_and_saveexec_b64 s[56:57], vcc
	s_xor_b64 s[56:57], exec, s[56:57]
	v_exp_f32_e32 v42, v38
	s_nop 0
	v_fma_f32 v42, -v42, v42, 1.0
	s_andn2_saveexec_b64 s[56:57], s[56:57]
	v_fmamk_f32 v42, v43, 0x3d2aaaab, v208
	v_fma_f32 v42, v43, v42, 0.5
	v_fma_f32 v42, v43, v42, 1.0
	v_mul_f32_e64 v42, v43, -v42
	s_or_b64 exec, exec, s[56:57]
	v_add_f32_e32 v39, v39, v75
	v_mul_f32_e32 v39, 0xbfb8aa3b, v39
	v_exp_f32_e32 v39, v39
	s_nop 0
	v_add_f32_e32 v39, 1.0, v39
	v_rcp_f32_e32 v39, v39
	s_nop 0
	v_mul_f32_e32 v39, v71, v39
	v_mul_f32_e32 v39, 0x3fb8aa3b, v39
	v_cvt_pk_bf16_f32 v39, v39, 0
	v_lshlrev_b32_e32 v39, 16, v39
	v_add_f32_e32 v43, v39, v39
	v_mul_f32_e32 v44, 0x3f317218, v43
	v_cmp_nlt_f32_e32 vcc, s74, v44
	s_and_saveexec_b64 s[56:57], vcc
	s_xor_b64 s[56:57], exec, s[56:57]
	v_exp_f32_e32 v43, v39
	s_nop 0
	v_fma_f32 v43, -v43, v43, 1.0
	s_andn2_saveexec_b64 s[56:57], s[56:57]
	v_fmamk_f32 v43, v44, 0x3d2aaaab, v208
	v_fma_f32 v43, v44, v43, 0.5
	v_fma_f32 v43, v44, v43, 1.0
	v_mul_f32_e64 v43, v44, -v43
	s_or_b64 exec, exec, s[56:57]
	v_add_f32_e32 v34, v34, v66
	v_mul_f32_e32 v34, 0xbfb8aa3b, v34
	v_exp_f32_e32 v34, v34
	v_add_f32_e32 v32, v32, v64
	v_mul_f32_e32 v32, 0xbfb8aa3b, v32
	v_exp_f32_e32 v32, v32
	v_add_f32_e32 v33, v33, v65
	v_add_f32_e32 v35, v35, v67
	v_add_f32_e32 v34, 1.0, v34
	v_mul_f32_e32 v33, 0xbfb8aa3b, v33
	v_rcp_f32_e32 v34, v34
	v_mul_f32_e32 v35, 0xbfb8aa3b, v35
	v_exp_f32_e32 v33, v33
	v_sqrt_f32_e32 v42, v42
	v_exp_f32_e32 v35, v35
	v_add_f32_e32 v32, 1.0, v32
	v_rcp_f32_e32 v32, v32
	v_add_f32_e32 v28, v28, v72
	v_lshlrev_b32_e32 v44, 16, v89
	v_sqrt_f32_e32 v40, v40
	v_mul_f32_e32 v28, 0xbfb8aa3b, v28
	v_mul_f32_e32 v34, v34, v44
	v_add_f32_e32 v33, 1.0, v33
	v_exp_f32_e32 v28, v28
	v_mul_f32_e32 v42, v34, v42
	v_add_f32_e32 v34, 1.0, v35
	v_lshlrev_b32_e32 v35, 16, v88
	v_rcp_f32_e32 v33, v33
	v_mul_f32_e32 v32, v32, v35
	v_mul_f32_e32 v40, v32, v40
	v_sqrt_f32_e32 v32, v41
	v_rcp_f32_e32 v34, v34
	v_and_b32_e32 v35, 0xffff0000, v88
	v_add_f32_e32 v28, 1.0, v28
; __device__ __forceinline__ float bf_lo(unsigned w) { return __uint_as_float(w << 16); }
; __device__ __forceinline__ float bf_hi(unsigned w) { return __uint_as_float(w & 0xffff0000u); }
; __device__ __forceinline__ float fast_sigmoid(float x) { return __builtin_amdgcn_rcpf(1.0f + __builtin_amdgcn_exp2f(-x * LOG2E)); }
;     __device__ __forceinline__ void operator()(const f32x4 (&acc)[2][2][4][2], const Unit& u, int wr, int wc, int fr, int fq) const {
;     ...
;                 for (int m = 0; m < 4; ++m) { const int row = row0 + ai * HALF + m * 16; const size_t off = (size_t)row * DM + ch0 + n * 16;
;                     const u32x2 xw = xall[ai * 4 + m];
;                     const float xv[4] = {bf_lo(xw.x), bf_hi(xw.x), bf_lo(xw.y), bf_hi(xw.y)};
;                     f32x4 av; float bv[4];
; #pragma unroll
;                     for (int j = 0; j < 4; ++j) { const float r = fast_sigmoid(acc[ai][0][m][n][j] + ba[j]), ig = fast_sigmoid(acc[ai][1][m][n][j] + bx[j]);
;                         const float la = sp[j] * r; const float la2 = __uint_as_float(pk_bf16(la * LOG2E, 0.f) << 16);
;                         const float a = __builtin_amdgcn_exp2f(la2); const float x2 = 2.0f * la2 * 0.6931471805599453f; av[j] = la2;
;                         const float om = (x2 > -0.03f) ? -(x2 * (1.0f + x2 * (0.5f + x2 * (1.0f / 6.0f + x2 * (1.0f / 24.0f))))) : (1.0f - a * a);
;                         bv[j] = __builtin_amdgcn_sqrtf(om) * (ig * xv[j]); }
;                     { u32x2 wa; wa.x = pk_bf16(av[0], av[1]); wa.y = pk_bf16(av[2], av[3]); *(u32x2*)(aout + off) = wa; }
;                     u32x2 w; w.x = pk_bf16(bv[0], bv[1]); w.y = pk_bf16(bv[2], bv[3]); *(u32x2*)(bout + off) = w; }
	v_mul_f32_e32 v33, v33, v35
	v_sqrt_f32_e32 v35, v43
	v_rcp_f32_e32 v28, v28
	v_mul_f32_e32 v41, v33, v32
	v_and_b32_e32 v32, 0xffff0000, v89
	v_mul_f32_e32 v32, v34, v32
	v_mul_f32_e32 v43, v32, v35
	v_lshl_add_u64 v[32:33], v[108:109], 0, v[152:153]
	v_mul_f32_e32 v28, v68, v28
	v_lshlrev_b64 v[32:33], 1, v[32:33]
	v_mul_f32_e32 v28, 0x3fb8aa3b, v28
	v_cvt_pk_bf16_f32 v34, v36, v37
	v_cvt_pk_bf16_f32 v35, v38, v39
	v_lshl_add_u64 v[36:37], s[16:17], 0, v[32:33]
	v_cvt_pk_bf16_f32 v28, v28, 0
	global_store_dwordx2 v[36:37], v[34:35], off
	v_cvt_pk_bf16_f32 v34, v40, v41
	v_cvt_pk_bf16_f32 v35, v42, v43
	v_lshl_add_u64 v[32:33], s[18:19], 0, v[32:33]
	v_lshlrev_b32_e32 v28, 16, v28
	global_store_dwordx2 v[32:33], v[34:35], off
	v_add_f32_e32 v32, v28, v28
	v_mul_f32_e32 v33, 0x3f317218, v32
	v_cmp_nlt_f32_e32 vcc, s74, v33
	s_and_saveexec_b64 s[56:57], vcc
	s_xor_b64 s[56:57], exec, s[56:57]
	v_exp_f32_e32 v32, v28
	s_nop 0
	v_fma_f32 v32, -v32, v32, 1.0
	s_andn2_saveexec_b64 s[56:57], s[56:57]
	v_fmamk_f32 v32, v33, 0x3d2aaaab, v208
	v_fma_f32 v32, v33, v32, 0.5
	v_fma_f32 v32, v33, v32, 1.0
	v_mul_f32_e64 v32, v33, -v32
	s_or_b64 exec, exec, s[56:57]
	v_add_f32_e32 v29, v29, v73
	v_mul_f32_e32 v29, 0xbfb8aa3b, v29
	v_exp_f32_e32 v29, v29
	s_nop 0
	v_add_f32_e32 v29, 1.0, v29
	v_rcp_f32_e32 v29, v29
	s_nop 0
	v_mul_f32_e32 v29, v69, v29
	v_mul_f32_e32 v29, 0x3fb8aa3b, v29
	v_cvt_pk_bf16_f32 v29, v29, 0
	v_lshlrev_b32_e32 v29, 16, v29
	v_add_f32_e32 v33, v29, v29
	v_mul_f32_e32 v34, 0x3f317218, v33
	v_cmp_nlt_f32_e32 vcc, s74, v34
	s_and_saveexec_b64 s[56:57], vcc
	s_xor_b64 s[56:57], exec, s[56:57]
	v_exp_f32_e32 v33, v29
	s_nop 0
	v_fma_f32 v33, -v33, v33, 1.0
	s_andn2_saveexec_b64 s[56:57], s[56:57]
	v_fmamk_f32 v33, v34, 0x3d2aaaab, v208
	v_fma_f32 v33, v34, v33, 0.5
	v_fma_f32 v33, v34, v33, 1.0
	v_mul_f32_e64 v33, v34, -v33
	s_or_b64 exec, exec, s[56:57]
	v_add_f32_e32 v30, v30, v74
	v_mul_f32_e32 v30, 0xbfb8aa3b, v30
	v_exp_f32_e32 v30, v30
	s_nop 0
	v_add_f32_e32 v30, 1.0, v30
	v_rcp_f32_e32 v30, v30
	s_nop 0
	v_mul_f32_e32 v30, v70, v30
	v_mul_f32_e32 v30, 0x3fb8aa3b, v30
	v_cvt_pk_bf16_f32 v30, v30, 0
	v_lshlrev_b32_e32 v30, 16, v30
	v_add_f32_e32 v34, v30, v30
	v_mul_f32_e32 v35, 0x3f317218, v34
	v_cmp_nlt_f32_e32 vcc, s74, v35
	s_and_saveexec_b64 s[56:57], vcc
	s_xor_b64 s[56:57], exec, s[56:57]
	v_exp_f32_e32 v34, v30
	s_nop 0
	v_fma_f32 v34, -v34, v34, 1.0
	s_andn2_saveexec_b64 s[56:57], s[56:57]
	v_fmamk_f32 v34, v35, 0x3d2aaaab, v208
	v_fma_f32 v34, v35, v34, 0.5
	v_fma_f32 v34, v35, v34, 1.0
	v_mul_f32_e64 v34, v35, -v34
	s_or_b64 exec, exec, s[56:57]
	v_add_f32_e32 v31, v31, v75
	v_mul_f32_e32 v31, 0xbfb8aa3b, v31
	v_exp_f32_e32 v31, v31
	s_nop 0
	v_add_f32_e32 v31, 1.0, v31
	v_rcp_f32_e32 v31, v31
	s_nop 0
	v_mul_f32_e32 v31, v71, v31
	v_mul_f32_e32 v31, 0x3fb8aa3b, v31
	v_cvt_pk_bf16_f32 v31, v31, 0
	v_lshlrev_b32_e32 v31, 16, v31
	v_add_f32_e32 v35, v31, v31
	v_mul_f32_e32 v36, 0x3f317218, v35
	v_cmp_nlt_f32_e32 vcc, s74, v36
	s_and_saveexec_b64 s[56:57], vcc
	s_xor_b64 s[56:57], exec, s[56:57]
	v_exp_f32_e32 v35, v31
	s_nop 0
	v_fma_f32 v35, -v35, v35, 1.0
	s_andn2_saveexec_b64 s[56:57], s[56:57]
	v_fmamk_f32 v35, v36, 0x3d2aaaab, v208
	v_fma_f32 v35, v36, v35, 0.5
	v_fma_f32 v35, v36, v35, 1.0
	v_mul_f32_e64 v35, v36, -v35
	s_or_b64 exec, exec, s[56:57]
	v_add_f32_e32 v26, v26, v66
	v_mul_f32_e32 v26, 0xbfb8aa3b, v26
	v_exp_f32_e32 v26, v26
	v_add_f32_e32 v24, v24, v64
	v_mul_f32_e32 v24, 0xbfb8aa3b, v24
	v_exp_f32_e32 v24, v24
	v_add_f32_e32 v25, v25, v65
	v_add_f32_e32 v27, v27, v67
	v_add_f32_e32 v26, 1.0, v26
	v_mul_f32_e32 v25, 0xbfb8aa3b, v25
	v_rcp_f32_e32 v26, v26
	v_mul_f32_e32 v27, 0xbfb8aa3b, v27
	v_exp_f32_e32 v25, v25
	v_sqrt_f32_e32 v34, v34
	v_exp_f32_e32 v27, v27
	v_add_f32_e32 v24, 1.0, v24
	v_rcp_f32_e32 v24, v24
	v_add_f32_e32 v20, v20, v72
	v_lshlrev_b32_e32 v36, 16, v87
	v_sqrt_f32_e32 v32, v32
	v_mul_f32_e32 v20, 0xbfb8aa3b, v20
	v_mul_f32_e32 v26, v26, v36
	v_add_f32_e32 v25, 1.0, v25
	v_exp_f32_e32 v20, v20
	v_mul_f32_e32 v34, v26, v34
	v_add_f32_e32 v26, 1.0, v27
	v_lshlrev_b32_e32 v27, 16, v86
	v_rcp_f32_e32 v25, v25
	v_mul_f32_e32 v24, v24, v27
	v_mul_f32_e32 v32, v24, v32
	v_sqrt_f32_e32 v24, v33
	v_rcp_f32_e32 v26, v26
	v_and_b32_e32 v27, 0xffff0000, v86
	v_add_f32_e32 v20, 1.0, v20
	v_mul_f32_e32 v25, v25, v27
	v_sqrt_f32_e32 v27, v35
	v_rcp_f32_e32 v20, v20
	v_mul_f32_e32 v33, v25, v24
	v_and_b32_e32 v24, 0xffff0000, v87
	v_mul_f32_e32 v24, v26, v24
	v_mul_f32_e32 v35, v24, v27
	v_lshl_add_u64 v[24:25], v[100:101], 0, v[152:153]
	v_mul_f32_e32 v20, v68, v20
	v_lshlrev_b64 v[24:25], 1, v[24:25]
	v_mul_f32_e32 v20, 0x3fb8aa3b, v20
	v_cvt_pk_bf16_f32 v26, v28, v29
	v_cvt_pk_bf16_f32 v27, v30, v31
	v_lshl_add_u64 v[28:29], s[16:17], 0, v[24:25]
	v_cvt_pk_bf16_f32 v20, v20, 0
	global_store_dwordx2 v[28:29], v[26:27], off
	v_cvt_pk_bf16_f32 v26, v32, v33
	v_cvt_pk_bf16_f32 v27, v34, v35
	v_lshl_add_u64 v[24:25], s[18:19], 0, v[24:25]
	v_lshlrev_b32_e32 v20, 16, v20
	global_store_dwordx2 v[24:25], v[26:27], off
	v_add_f32_e32 v24, v20, v20
	v_mul_f32_e32 v25, 0x3f317218, v24
	v_cmp_nlt_f32_e32 vcc, s74, v25
	s_and_saveexec_b64 s[56:57], vcc
	s_xor_b64 s[56:57], exec, s[56:57]
	v_exp_f32_e32 v24, v20
	s_nop 0
	v_fma_f32 v24, -v24, v24, 1.0
	s_andn2_saveexec_b64 s[56:57], s[56:57]
	v_fmamk_f32 v24, v25, 0x3d2aaaab, v208
	v_fma_f32 v24, v25, v24, 0.5
	v_fma_f32 v24, v25, v24, 1.0
	v_mul_f32_e64 v24, v25, -v24
	s_or_b64 exec, exec, s[56:57]
	v_add_f32_e32 v21, v21, v73
	v_mul_f32_e32 v21, 0xbfb8aa3b, v21
	v_exp_f32_e32 v21, v21
	s_nop 0
	v_add_f32_e32 v21, 1.0, v21
	v_rcp_f32_e32 v21, v21
; __device__ __forceinline__ float bf_lo(unsigned w) { return __uint_as_float(w << 16); }
; __device__ __forceinline__ float bf_hi(unsigned w) { return __uint_as_float(w & 0xffff0000u); }
; __device__ __forceinline__ float fast_sigmoid(float x) { return __builtin_amdgcn_rcpf(1.0f + __builtin_amdgcn_exp2f(-x * LOG2E)); }
;     __device__ __forceinline__ void operator()(const f32x4 (&acc)[2][2][4][2], const Unit& u, int wr, int wc, int fr, int fq) const {
;     ...
;                 for (int m = 0; m < 4; ++m) { const int row = row0 + ai * HALF + m * 16; const size_t off = (size_t)row * DM + ch0 + n * 16;
;                     const u32x2 xw = xall[ai * 4 + m];
;                     const float xv[4] = {bf_lo(xw.x), bf_hi(xw.x), bf_lo(xw.y), bf_hi(xw.y)};
;                     f32x4 av; float bv[4];
; #pragma unroll
;                     for (int j = 0; j < 4; ++j) { const float r = fast_sigmoid(acc[ai][0][m][n][j] + ba[j]), ig = fast_sigmoid(acc[ai][1][m][n][j] + bx[j]);
;                         const float la = sp[j] * r; const float la2 = __uint_as_float(pk_bf16(la * LOG2E, 0.f) << 16);
;                         const float a = __builtin_amdgcn_exp2f(la2); const float x2 = 2.0f * la2 * 0.6931471805599453f; av[j] = la2;
;                         const float om = (x2 > -0.03f) ? -(x2 * (1.0f + x2 * (0.5f + x2 * (1.0f / 6.0f + x2 * (1.0f / 24.0f))))) : (1.0f - a * a);
;                         bv[j] = __builtin_amdgcn_sqrtf(om) * (ig * xv[j]); }
;                     { u32x2 wa; wa.x = pk_bf16(av[0], av[1]); wa.y = pk_bf16(av[2], av[3]); *(u32x2*)(aout + off) = wa; }
;                     u32x2 w; w.x = pk_bf16(bv[0], bv[1]); w.y = pk_bf16(bv[2], bv[3]); *(u32x2*)(bout + off) = w; }
	s_nop 0
	v_mul_f32_e32 v21, v69, v21
	v_mul_f32_e32 v21, 0x3fb8aa3b, v21
	v_cvt_pk_bf16_f32 v21, v21, 0
	v_lshlrev_b32_e32 v21, 16, v21
	v_add_f32_e32 v25, v21, v21
	v_mul_f32_e32 v26, 0x3f317218, v25
	v_cmp_nlt_f32_e32 vcc, s74, v26
	s_and_saveexec_b64 s[56:57], vcc
	s_xor_b64 s[56:57], exec, s[56:57]
	v_exp_f32_e32 v25, v21
	s_nop 0
	v_fma_f32 v25, -v25, v25, 1.0
	s_andn2_saveexec_b64 s[56:57], s[56:57]
	v_fmamk_f32 v25, v26, 0x3d2aaaab, v208
	v_fma_f32 v25, v26, v25, 0.5
	v_fma_f32 v25, v26, v25, 1.0
	v_mul_f32_e64 v25, v26, -v25
	s_or_b64 exec, exec, s[56:57]
	v_add_f32_e32 v22, v22, v74
	v_mul_f32_e32 v22, 0xbfb8aa3b, v22
	v_exp_f32_e32 v22, v22
	s_nop 0
	v_add_f32_e32 v22, 1.0, v22
	v_rcp_f32_e32 v22, v22
	s_nop 0
	v_mul_f32_e32 v22, v70, v22
	v_mul_f32_e32 v22, 0x3fb8aa3b, v22
	v_cvt_pk_bf16_f32 v22, v22, 0
	v_lshlrev_b32_e32 v22, 16, v22
	v_add_f32_e32 v26, v22, v22
	v_mul_f32_e32 v27, 0x3f317218, v26
	v_cmp_nlt_f32_e32 vcc, s74, v27
	s_and_saveexec_b64 s[56:57], vcc
	s_xor_b64 s[56:57], exec, s[56:57]
	v_exp_f32_e32 v26, v22
	s_nop 0
	v_fma_f32 v26, -v26, v26, 1.0
	s_andn2_saveexec_b64 s[56:57], s[56:57]
	v_fmamk_f32 v26, v27, 0x3d2aaaab, v208
	v_fma_f32 v26, v27, v26, 0.5
	v_fma_f32 v26, v27, v26, 1.0
	v_mul_f32_e64 v26, v27, -v26
	s_or_b64 exec, exec, s[56:57]
	v_add_f32_e32 v23, v23, v75
	v_mul_f32_e32 v23, 0xbfb8aa3b, v23
	v_exp_f32_e32 v23, v23
	s_nop 0
	v_add_f32_e32 v23, 1.0, v23
	v_rcp_f32_e32 v23, v23
	s_nop 0
	v_mul_f32_e32 v23, v71, v23
	v_mul_f32_e32 v23, 0x3fb8aa3b, v23
	v_cvt_pk_bf16_f32 v23, v23, 0
	v_lshlrev_b32_e32 v23, 16, v23
	v_add_f32_e32 v27, v23, v23
	v_mul_f32_e32 v28, 0x3f317218, v27
	v_cmp_nlt_f32_e32 vcc, s74, v28
	s_and_saveexec_b64 s[56:57], vcc
	s_xor_b64 s[56:57], exec, s[56:57]
	v_exp_f32_e32 v27, v23
	s_nop 0
	v_fma_f32 v27, -v27, v27, 1.0
	s_andn2_saveexec_b64 s[56:57], s[56:57]
	v_fmamk_f32 v27, v28, 0x3d2aaaab, v208
	v_fma_f32 v27, v28, v27, 0.5
	v_fma_f32 v27, v28, v27, 1.0
	v_mul_f32_e64 v27, v28, -v27
	s_or_b64 exec, exec, s[56:57]
	v_add_f32_e32 v18, v18, v66
	v_mul_f32_e32 v18, 0xbfb8aa3b, v18
	v_exp_f32_e32 v18, v18
	v_add_f32_e32 v16, v16, v64
	v_mul_f32_e32 v16, 0xbfb8aa3b, v16
	v_exp_f32_e32 v16, v16
	v_add_f32_e32 v17, v17, v65
	v_add_f32_e32 v19, v19, v67
	v_add_f32_e32 v18, 1.0, v18
	v_mul_f32_e32 v17, 0xbfb8aa3b, v17
	v_rcp_f32_e32 v18, v18
	v_mul_f32_e32 v19, 0xbfb8aa3b, v19
	v_exp_f32_e32 v17, v17
	v_sqrt_f32_e32 v26, v26
	v_exp_f32_e32 v19, v19
	v_add_f32_e32 v16, 1.0, v16
	v_rcp_f32_e32 v16, v16
	v_add_f32_e32 v12, v12, v72
	v_lshlrev_b32_e32 v28, 16, v83
	v_sqrt_f32_e32 v24, v24
	v_mul_f32_e32 v12, 0xbfb8aa3b, v12
	v_mul_f32_e32 v18, v18, v28
	v_add_f32_e32 v17, 1.0, v17
	v_exp_f32_e32 v12, v12
	v_mul_f32_e32 v26, v18, v26
	v_add_f32_e32 v18, 1.0, v19
	v_lshlrev_b32_e32 v19, 16, v82
	v_rcp_f32_e32 v17, v17
	v_mul_f32_e32 v16, v16, v19
	v_mul_f32_e32 v24, v16, v24
	v_sqrt_f32_e32 v16, v25
	v_rcp_f32_e32 v18, v18
	v_and_b32_e32 v19, 0xffff0000, v82
	v_add_f32_e32 v12, 1.0, v12
	v_mul_f32_e32 v17, v17, v19
	v_sqrt_f32_e32 v19, v27
	v_rcp_f32_e32 v12, v12
	v_mul_f32_e32 v25, v17, v16
	v_and_b32_e32 v16, 0xffff0000, v83
	v_mul_f32_e32 v16, v18, v16
	v_mul_f32_e32 v27, v16, v19
	v_lshl_add_u64 v[16:17], v[92:93], 0, v[152:153]
	v_mul_f32_e32 v12, v68, v12
	v_lshlrev_b64 v[16:17], 1, v[16:17]
	v_mul_f32_e32 v12, 0x3fb8aa3b, v12
	v_cvt_pk_bf16_f32 v18, v20, v21
	v_cvt_pk_bf16_f32 v19, v22, v23
	v_lshl_add_u64 v[20:21], s[16:17], 0, v[16:17]
	v_cvt_pk_bf16_f32 v12, v12, 0
	global_store_dwordx2 v[20:21], v[18:19], off
	v_cvt_pk_bf16_f32 v18, v24, v25
	v_cvt_pk_bf16_f32 v19, v26, v27
	v_lshl_add_u64 v[16:17], s[18:19], 0, v[16:17]
	v_lshlrev_b32_e32 v12, 16, v12
	global_store_dwordx2 v[16:17], v[18:19], off
	v_add_f32_e32 v16, v12, v12
	v_mul_f32_e32 v17, 0x3f317218, v16
	v_cmp_nlt_f32_e32 vcc, s74, v17
	s_and_saveexec_b64 s[56:57], vcc
	s_xor_b64 s[56:57], exec, s[56:57]
	v_exp_f32_e32 v16, v12
	s_nop 0
	v_fma_f32 v16, -v16, v16, 1.0
	s_andn2_saveexec_b64 s[56:57], s[56:57]
	v_fmamk_f32 v16, v17, 0x3d2aaaab, v208
	v_fma_f32 v16, v17, v16, 0.5
	v_fma_f32 v16, v17, v16, 1.0
	v_mul_f32_e64 v16, v17, -v16
	s_or_b64 exec, exec, s[56:57]
	v_add_f32_e32 v13, v13, v73
	v_mul_f32_e32 v13, 0xbfb8aa3b, v13
	v_exp_f32_e32 v13, v13
	s_nop 0
	v_add_f32_e32 v13, 1.0, v13
	v_rcp_f32_e32 v13, v13
	s_nop 0
	v_mul_f32_e32 v13, v69, v13
	v_mul_f32_e32 v13, 0x3fb8aa3b, v13
	v_cvt_pk_bf16_f32 v13, v13, 0
	v_lshlrev_b32_e32 v13, 16, v13
	v_add_f32_e32 v17, v13, v13
	v_mul_f32_e32 v18, 0x3f317218, v17
	v_cmp_nlt_f32_e32 vcc, s74, v18
	s_and_saveexec_b64 s[56:57], vcc
	s_xor_b64 s[56:57], exec, s[56:57]
	v_exp_f32_e32 v17, v13
	s_nop 0
	v_fma_f32 v17, -v17, v17, 1.0
	s_andn2_saveexec_b64 s[56:57], s[56:57]
	v_fmamk_f32 v17, v18, 0x3d2aaaab, v208
	v_fma_f32 v17, v18, v17, 0.5
	v_fma_f32 v17, v18, v17, 1.0
	v_mul_f32_e64 v17, v18, -v17
	s_or_b64 exec, exec, s[56:57]
	v_add_f32_e32 v14, v14, v74
	v_mul_f32_e32 v14, 0xbfb8aa3b, v14
	v_exp_f32_e32 v14, v14
	s_nop 0
	v_add_f32_e32 v14, 1.0, v14
	v_rcp_f32_e32 v14, v14
	s_nop 0
	v_mul_f32_e32 v14, v70, v14
	v_mul_f32_e32 v14, 0x3fb8aa3b, v14
	v_cvt_pk_bf16_f32 v14, v14, 0
	v_lshlrev_b32_e32 v14, 16, v14
	v_add_f32_e32 v18, v14, v14
	v_mul_f32_e32 v19, 0x3f317218, v18
; __device__ __forceinline__ float bf_lo(unsigned w) { return __uint_as_float(w << 16); }
; __device__ __forceinline__ float bf_hi(unsigned w) { return __uint_as_float(w & 0xffff0000u); }
; __device__ __forceinline__ float fast_sigmoid(float x) { return __builtin_amdgcn_rcpf(1.0f + __builtin_amdgcn_exp2f(-x * LOG2E)); }
;     __device__ __forceinline__ void operator()(const f32x4 (&acc)[2][2][4][2], const Unit& u, int wr, int wc, int fr, int fq) const {
;     ...
;                 for (int m = 0; m < 4; ++m) { const int row = row0 + ai * HALF + m * 16; const size_t off = (size_t)row * DM + ch0 + n * 16;
;                     const u32x2 xw = xall[ai * 4 + m];
;                     const float xv[4] = {bf_lo(xw.x), bf_hi(xw.x), bf_lo(xw.y), bf_hi(xw.y)};
;                     f32x4 av; float bv[4];
; #pragma unroll
;                     for (int j = 0; j < 4; ++j) { const float r = fast_sigmoid(acc[ai][0][m][n][j] + ba[j]), ig = fast_sigmoid(acc[ai][1][m][n][j] + bx[j]);
;                         const float la = sp[j] * r; const float la2 = __uint_as_float(pk_bf16(la * LOG2E, 0.f) << 16);
;                         const float a = __builtin_amdgcn_exp2f(la2); const float x2 = 2.0f * la2 * 0.6931471805599453f; av[j] = la2;
;                         const float om = (x2 > -0.03f) ? -(x2 * (1.0f + x2 * (0.5f + x2 * (1.0f / 6.0f + x2 * (1.0f / 24.0f))))) : (1.0f - a * a);
;                         bv[j] = __builtin_amdgcn_sqrtf(om) * (ig * xv[j]); }
;                     { u32x2 wa; wa.x = pk_bf16(av[0], av[1]); wa.y = pk_bf16(av[2], av[3]); *(u32x2*)(aout + off) = wa; }
;                     u32x2 w; w.x = pk_bf16(bv[0], bv[1]); w.y = pk_bf16(bv[2], bv[3]); *(u32x2*)(bout + off) = w; }
	v_cmp_nlt_f32_e32 vcc, s74, v19
	s_and_saveexec_b64 s[56:57], vcc
	s_xor_b64 s[56:57], exec, s[56:57]
	v_exp_f32_e32 v18, v14
	s_nop 0
	v_fma_f32 v18, -v18, v18, 1.0
	s_andn2_saveexec_b64 s[56:57], s[56:57]
	v_fmamk_f32 v18, v19, 0x3d2aaaab, v208
	v_fma_f32 v18, v19, v18, 0.5
	v_fma_f32 v18, v19, v18, 1.0
	v_mul_f32_e64 v18, v19, -v18
	s_or_b64 exec, exec, s[56:57]
	v_add_f32_e32 v15, v15, v75
	v_mul_f32_e32 v15, 0xbfb8aa3b, v15
	v_exp_f32_e32 v15, v15
	s_nop 0
	v_add_f32_e32 v15, 1.0, v15
	v_rcp_f32_e32 v15, v15
	s_nop 0
	v_mul_f32_e32 v15, v71, v15
	v_mul_f32_e32 v15, 0x3fb8aa3b, v15
	v_cvt_pk_bf16_f32 v15, v15, 0
	v_lshlrev_b32_e32 v15, 16, v15
	v_add_f32_e32 v19, v15, v15
	v_mul_f32_e32 v20, 0x3f317218, v19
	v_cmp_nlt_f32_e32 vcc, s74, v20
	s_and_saveexec_b64 s[56:57], vcc
	s_xor_b64 s[56:57], exec, s[56:57]
	v_exp_f32_e32 v19, v15
	s_nop 0
	v_fma_f32 v19, -v19, v19, 1.0
	s_andn2_saveexec_b64 s[56:57], s[56:57]
	v_fmamk_f32 v19, v20, 0x3d2aaaab, v208
	v_fma_f32 v19, v20, v19, 0.5
	v_fma_f32 v19, v20, v19, 1.0
	v_mul_f32_e64 v19, v20, -v19
	s_or_b64 exec, exec, s[56:57]
	v_add_f32_e32 v10, v10, v66
	v_mul_f32_e32 v10, 0xbfb8aa3b, v10
	v_exp_f32_e32 v10, v10
	v_add_f32_e32 v8, v8, v64
	v_mul_f32_e32 v8, 0xbfb8aa3b, v8
	v_exp_f32_e32 v8, v8
	v_add_f32_e32 v9, v9, v65
	v_add_f32_e32 v11, v11, v67
	v_add_f32_e32 v10, 1.0, v10
	v_mul_f32_e32 v9, 0xbfb8aa3b, v9
	v_rcp_f32_e32 v10, v10
	v_mul_f32_e32 v11, 0xbfb8aa3b, v11
	v_exp_f32_e32 v9, v9
	v_sqrt_f32_e32 v18, v18
	v_exp_f32_e32 v11, v11
	v_add_f32_e32 v8, 1.0, v8
	v_rcp_f32_e32 v8, v8
	v_add_f32_e32 v4, v4, v72
	v_lshlrev_b32_e32 v20, 16, v81
	v_sqrt_f32_e32 v16, v16
	v_mul_f32_e32 v4, 0xbfb8aa3b, v4
	v_mul_f32_e32 v10, v10, v20
	v_add_f32_e32 v9, 1.0, v9
	v_exp_f32_e32 v4, v4
	v_mul_f32_e32 v18, v10, v18
	v_add_f32_e32 v10, 1.0, v11
	v_lshlrev_b32_e32 v11, 16, v80
	v_rcp_f32_e32 v9, v9
	v_mul_f32_e32 v8, v8, v11
	v_mul_f32_e32 v16, v8, v16
	v_sqrt_f32_e32 v8, v17
	v_rcp_f32_e32 v10, v10
	v_and_b32_e32 v11, 0xffff0000, v80
	v_add_f32_e32 v4, 1.0, v4
	v_mul_f32_e32 v9, v9, v11
	v_sqrt_f32_e32 v11, v19
	v_rcp_f32_e32 v4, v4
	v_mul_f32_e32 v17, v9, v8
	v_and_b32_e32 v8, 0xffff0000, v81
	v_mul_f32_e32 v8, v10, v8
	v_mul_f32_e32 v19, v8, v11
	v_lshl_add_u64 v[8:9], v[84:85], 0, v[152:153]
	v_mul_f32_e32 v4, v68, v4
	v_lshlrev_b64 v[8:9], 1, v[8:9]
	v_mul_f32_e32 v4, 0x3fb8aa3b, v4
	v_cvt_pk_bf16_f32 v10, v12, v13
	v_cvt_pk_bf16_f32 v11, v14, v15
	v_lshl_add_u64 v[12:13], s[16:17], 0, v[8:9]
	v_cvt_pk_bf16_f32 v4, v4, 0
	global_store_dwordx2 v[12:13], v[10:11], off
	v_cvt_pk_bf16_f32 v10, v16, v17
	v_cvt_pk_bf16_f32 v11, v18, v19
	v_lshl_add_u64 v[8:9], s[18:19], 0, v[8:9]
	v_lshlrev_b32_e32 v4, 16, v4
	global_store_dwordx2 v[8:9], v[10:11], off
	v_add_f32_e32 v8, v4, v4
	v_mul_f32_e32 v9, 0x3f317218, v8
	v_cmp_nlt_f32_e32 vcc, s74, v9
	s_and_saveexec_b64 s[56:57], vcc
	s_xor_b64 s[56:57], exec, s[56:57]
	v_exp_f32_e32 v8, v4
	s_nop 0
	v_fma_f32 v8, -v8, v8, 1.0
	s_andn2_saveexec_b64 s[56:57], s[56:57]
	v_fmamk_f32 v8, v9, 0x3d2aaaab, v208
	v_fma_f32 v8, v9, v8, 0.5
	v_fma_f32 v8, v9, v8, 1.0
	v_mul_f32_e64 v8, v9, -v8
	s_or_b64 exec, exec, s[56:57]
	v_add_f32_e32 v5, v5, v73
	v_mul_f32_e32 v5, 0xbfb8aa3b, v5
	v_exp_f32_e32 v5, v5
	s_nop 0
	v_add_f32_e32 v5, 1.0, v5
	v_rcp_f32_e32 v5, v5
	s_nop 0
	v_mul_f32_e32 v5, v69, v5
	v_mul_f32_e32 v5, 0x3fb8aa3b, v5
	v_cvt_pk_bf16_f32 v5, v5, 0
	v_lshlrev_b32_e32 v5, 16, v5
	v_add_f32_e32 v9, v5, v5
	v_mul_f32_e32 v10, 0x3f317218, v9
	v_cmp_nlt_f32_e32 vcc, s74, v10
	s_and_saveexec_b64 s[56:57], vcc
	s_xor_b64 s[56:57], exec, s[56:57]
	v_exp_f32_e32 v9, v5
	s_nop 0
	v_fma_f32 v9, -v9, v9, 1.0
	s_andn2_saveexec_b64 s[56:57], s[56:57]
	v_fmamk_f32 v9, v10, 0x3d2aaaab, v208
	v_fma_f32 v9, v10, v9, 0.5
	v_fma_f32 v9, v10, v9, 1.0
	v_mul_f32_e64 v9, v10, -v9
	s_or_b64 exec, exec, s[56:57]
	v_add_f32_e32 v6, v6, v74
	v_mul_f32_e32 v6, 0xbfb8aa3b, v6
	v_exp_f32_e32 v6, v6
	s_nop 0
	v_add_f32_e32 v6, 1.0, v6
	v_rcp_f32_e32 v6, v6
	s_nop 0
	v_mul_f32_e32 v6, v70, v6
	v_mul_f32_e32 v6, 0x3fb8aa3b, v6
	v_cvt_pk_bf16_f32 v6, v6, 0
	v_lshlrev_b32_e32 v6, 16, v6
	v_add_f32_e32 v10, v6, v6
	v_mul_f32_e32 v11, 0x3f317218, v10
	v_cmp_nlt_f32_e32 vcc, s74, v11
	s_and_saveexec_b64 s[56:57], vcc
	s_xor_b64 s[56:57], exec, s[56:57]
	v_exp_f32_e32 v10, v6
	s_nop 0
	v_fma_f32 v10, -v10, v10, 1.0
	s_andn2_saveexec_b64 s[56:57], s[56:57]
	v_fmamk_f32 v10, v11, 0x3d2aaaab, v208
	v_fma_f32 v10, v11, v10, 0.5
	v_fma_f32 v10, v11, v10, 1.0
	v_mul_f32_e64 v10, v11, -v10
	s_or_b64 exec, exec, s[56:57]
	v_add_f32_e32 v7, v7, v75
	v_mul_f32_e32 v7, 0xbfb8aa3b, v7
	v_exp_f32_e32 v7, v7
	s_nop 0
	v_add_f32_e32 v7, 1.0, v7
	v_rcp_f32_e32 v7, v7
	s_nop 0
	v_mul_f32_e32 v7, v71, v7
	v_mul_f32_e32 v7, 0x3fb8aa3b, v7
	v_cvt_pk_bf16_f32 v7, v7, 0
	v_lshlrev_b32_e32 v7, 16, v7
	v_add_f32_e32 v11, v7, v7
	v_mul_f32_e32 v12, 0x3f317218, v11
	v_cmp_nlt_f32_e32 vcc, s74, v12
	s_and_saveexec_b64 s[56:57], vcc
	s_xor_b64 s[56:57], exec, s[56:57]
	v_exp_f32_e32 v11, v7
	s_nop 0
	v_fma_f32 v11, -v11, v11, 1.0
	s_andn2_saveexec_b64 s[56:57], s[56:57]
	s_cbranch_execz .LBB0_1119
	v_fmamk_f32 v11, v12, 0x3d2aaaab, v208
	v_fma_f32 v11, v12, v11, 0.5
	v_fma_f32 v11, v12, v11, 1.0
	v_mul_f32_e64 v11, v12, -v11
	s_branch .LBB0_1119

; __device__ __forceinline__ int opaque_tid(int wv) { int l; asm volatile("v_mbcnt_lo_u32_b32 %0, -1, 0\n\tv_mbcnt_hi_u32_b32 %0, -1, %0" : "=v"(l)); return wv * 64 + l; }
; #define PG8_BAR __builtin_amdgcn_s_barrier()
; template <class Epi>
; __device__ __forceinline__ void gemm_phase(LAS unsigned char* lds, const Gemm g, const StaticOrder& S, const Epi& E, int wv) {
;     const int tid = opaque_tid(wv), wid = __builtin_amdgcn_readfirstlane(tid >> 6), lane = tid & 63, wr = wid >> 2, wc = wid & 3, fr = lane & 15, fq = lane >> 4;
;     const int K = g.K, nt = K / BK;
;     unsigned voffA[2], voffB[2];
; #pragma unroll
;     for (int i = 0; i < 2; ++i) { int R, C; stage_rc(tid * 16 + i * 8192, R, C); const int Rb = Epi::PERM ? ((R & ~31) + perm32(R & 31)) : R;
;         voffA[i] = (unsigned)(R * g.lda + C) * 2u; voffB[i] = (unsigned)(Rb * g.ldb + C) * 2u; }
;     const bool krev = (g.adiag & 2) != 0;
;     const ptrdiff_t kstep = krev ? -(ptrdiff_t)(BK * 2) : (ptrdiff_t)(BK * 2);
;     const size_t kbeg = krev ? (size_t)(nt - 1) * (BK * 2) : 0;
;     const size_t hstepA = (size_t)HALF * g.lda * 2, hstepB = (size_t)HALF * g.ldb * 2;
;     const size_t tstepA = 2 * hstepA, tstepB = 2 * hstepB;
;     const unsigned ldsw = (unsigned)wid * 1024u;
;     const int aoff = lds_byte(wr * 64 + fr, fq * 8), boff = lds_byte(wc * 32 + fr, fq * 8);
;     ...
;     Unit cur, nxt; int ui = 0;
;     if (!S.next(0, cur)) return;
;     f32x4 acc[2][2][4][2];
; #pragma unroll
;     for (int a = 0; a < 2; ++a)
; #pragma unroll
;         for (int b = 0; b < 2; ++b)
; #pragma unroll
;             for (int m = 0; m < 4; ++m)
; #pragma unroll
;                 for (int n = 0; n < 2; ++n) acc[a][b][m][n] = (f32x4){0.f, 0.f, 0.f, 0.f};
;     bf16x8 At[4][2], B0[2][2], B1[2][2];
;     const char* cA = (const char*)g.A + (size_t)cur.pm * tstepA + ((g.adiag & 1) ? (size_t)(cur.pn >> 1) * K * 2 : 0) + kbeg;
;     const char* cB = (const char*)g.Bt + (size_t)cur.pn * tstepB + kbeg;
;     PG8_STAGE(PG8_SB(0, 0), cB, voffB); PG8_STAGE(PG8_SA(0, 0), cA, voffA); PG8_STAGE(PG8_SB(0, 1), cB + hstepB, voffB); PG8_STAGE(PG8_SA(0, 1), cA + hstepA, voffA);
;     if (wr == 1) PG8_BAR;
;     PG8_WAIT_V(4); PG8_BAR;
;     PG8_STAGE(PG8_SB(1, 0), cB + kstep, voffB); PG8_STAGE(PG8_SA(1, 0), cA + kstep, voffA); PG8_STAGE(PG8_SB(1, 1), cB + hstepB + kstep, voffB);
;     PG8_WAIT_V(6); PG8_BAR;
.LBB0_1569:
	v_readlane_b32 s16, v255, 10
	v_readlane_b32 s17, v255, 11
	s_and_b64 vcc, exec, s[16:17]
	s_cbranch_vccnz .LBB0_1601
	v_ashrrev_i32_e32 v2, 31, v0
	v_lshrrev_b32_e32 v2, 26, v2
	v_lshlrev_b32_e32 v1, 4, v0
	v_add_u32_e32 v2, v0, v2
	v_bfe_i32 v0, v0, 27, 1
	v_lshrrev_b32_e32 v0, 22, v0
	v_add_u32_e32 v0, v1, v0
	v_and_b32_e32 v0, 0xfffffc00, v0
	v_sub_u32_e32 v0, v1, v0
	v_ashrrev_i32_e32 v9, 6, v2
	v_lshrrev_b32_e32 v2, 4, v0
	v_bitop3_b32 v0, v2, v0, 32 bitop3:0x6c
	v_ashrrev_i32_e32 v3, 31, v0
	v_lshrrev_b32_e32 v3, 26, v3
	v_add_u32_e32 v3, v0, v3
	v_lshlrev_b32_e32 v2, 3, v9
	v_ashrrev_i32_e32 v10, 6, v3
	v_and_b32_e32 v3, 0xc0, v3
	v_and_b32_e32 v2, -16, v2
	v_sub_u32_e32 v0, v0, v3
	v_mov_b32_e32 v3, 1
	v_add_u32_e32 v2, v10, v2
	v_ashrrev_i16_sdwa v0, v3, sext(v0) dst_sel:DWORD dst_unused:UNUSED_PAD src0_sel:DWORD src1_sel:BYTE_0
	s_waitcnt lgkmcnt(0)
	s_add_u32 s5, s10, 0xf300000
	v_lshlrev_b32_e32 v4, 5, v9
	v_bfe_i32 v11, v0, 0, 16
	v_lshlrev_b32_e32 v0, 1, v2
	v_lshrrev_b32_e32 v5, 2, v2
	v_and_b32_e32 v6, 3, v10
	s_mov_b32 s10, 0xfffe0
	v_and_b32_e32 v4, 32, v4
	v_and_b32_e32 v0, 24, v0
	v_and_b32_e32 v5, 4, v5
	v_and_or_b32 v6, v2, s10, v6
	v_or3_b32 v0, v6, v5, v0
	v_add_lshl_u32 v4, v4, v11, 1
	v_lshl_add_u32 v146, v0, 12, v4
	v_add_u32_e32 v0, 0x2000, v1
	v_ashrrev_i32_e32 v1, 31, v0
	v_lshrrev_b32_e32 v1, 22, v1
	v_add_u32_e32 v1, v0, v1
	v_ashrrev_i32_e32 v12, 10, v1
	v_mul_i32_i24_e32 v1, 0x400, v12
	v_sub_u32_e32 v0, v0, v1
	v_lshrrev_b32_e32 v1, 4, v0
	v_bitop3_b32 v0, v1, v0, 32 bitop3:0x6c
	v_lshl_add_u32 v144, v2, 12, v4
	v_ashrrev_i32_e32 v2, 31, v0
	v_lshrrev_b32_e32 v2, 26, v2
	v_add_u32_e32 v2, v0, v2
	s_addc_u32 s22, s11, 0
	v_lshlrev_b32_e32 v1, 3, v12
	v_ashrrev_i32_e32 v13, 6, v2
	v_and_b32_e32 v2, 0xc0, v2
	s_add_u32 s23, s12, 0x2100000
	v_and_b32_e32 v1, -16, v1
	v_sub_u32_e32 v0, v0, v2
	s_addc_u32 s24, s13, 0
	v_add_u32_e32 v1, v13, v1
	v_ashrrev_i16_sdwa v0, v3, sext(v0) dst_sel:DWORD dst_unused:UNUSED_PAD src0_sel:DWORD src1_sel:BYTE_0
	v_and_b32_e32 v3, 3, v13
	s_ashr_i32 s16, s4, 6
	s_ashr_i32 s43, s42, 31
	s_ashr_i32 s18, s4, 8
	v_and_or_b32 v3, v1, s10, v3
	s_lshl_b32 s25, s16, 10
	s_lshl_b64 s[10:11], s[42:43], 20
	s_add_u32 s46, s5, s10
	s_addc_u32 s47, s22, s11
	s_ashr_i32 s45, s44, 31
	s_lshl_b64 s[10:11], s[44:45], 20
	v_lshlrev_b32_e32 v4, 5, v12
	v_bfe_i32 v14, v0, 0, 16
	v_lshlrev_b32_e32 v0, 1, v1
	v_lshrrev_b32_e32 v2, 2, v1
	s_add_u32 s48, s23, s10
	v_and_b32_e32 v4, 32, v4
	v_and_b32_e32 v0, 24, v0
	v_and_b32_e32 v2, 4, v2
	s_addc_u32 s49, s24, s11
	s_add_i32 s33, s25, 0
	v_or3_b32 v0, v3, v2, v0
	v_add_lshl_u32 v2, v4, v14, 1
	s_add_i32 m0, s33, 0x10000
	v_lshl_add_u32 v150, v0, 12, v2
	global_load_lds_dwordx4 v146, s[48:49]
	s_add_i32 m0, s33, 0x12000
	s_add_i32 s45, s33, 0x2000
	global_load_lds_dwordx4 v150, s[48:49]
	s_mov_b32 m0, s33
	v_lshl_add_u32 v148, v1, 12, v2
	global_load_lds_dwordx4 v144, s[46:47]
	s_mov_b32 m0, s45
	s_add_u32 s10, s48, 0x80000
	global_load_lds_dwordx4 v148, s[46:47]
	s_addc_u32 s11, s49, 0
	s_add_i32 m0, s33, 0x14000
	v_mov_b32_e32 v147, 0
	global_load_lds_dwordx4 v146, s[10:11]
	s_add_i32 m0, s33, 0x16000
	v_mov_b32_e32 v151, v147
	global_load_lds_dwordx4 v150, s[10:11]
	s_add_u32 s10, s46, 0x80000
	s_addc_u32 s11, s47, 0
	s_add_i32 s52, s33, 0x4000
	s_mov_b32 m0, s52
	s_add_i32 s53, s33, 0x6000
	global_load_lds_dwordx4 v144, s[10:11]
	s_mov_b32 m0, s53
	v_mov_b32_e32 v145, v147
	global_load_lds_dwordx4 v148, s[10:11]
	v_mov_b32_e32 v149, v147
	s_mov_b32 s54, 0
	v_lshl_add_u64 v[6:7], s[48:49], 0, v[146:147]
	v_lshl_add_u64 v[4:5], s[48:49], 0, v[150:151]
	v_lshl_add_u64 v[2:3], s[46:47], 0, v[144:145]
	s_cmp_lg_u32 s18, 1
	v_lshl_add_u64 v[0:1], s[46:47], 0, v[148:149]
	s_cbranch_scc1 .LBB0_1572
	s_barrier
	s_setprio 1

; #define PG8_STAGE(bufoff, gbase, voff) do { _Pragma("unroll") for (int _i = 0; _i < 2; ++_i) \
;         __builtin_amdgcn_global_load_lds((const unsigned*)((const char*)(gbase) + (voff)[_i]), (LAS unsigned*)(lds + (bufoff) + ldsw + _i * 8192), 16, 0, 0); } while (0)
; #define PG8_LDA(dst, b, h) do { _Pragma("unroll") for (int m = 0; m < 4; ++m) _Pragma("unroll") for (int k = 0; k < 2; ++k) dst[m][k] = *(const LAS bf16x8*)(lds + PG8_SA(b, h) + aoff + m * 2048 + k * 1024); } while (0)
; #define PG8_LDB(dst, b, h) do { _Pragma("unroll") for (int n = 0; n < 2; ++n) _Pragma("unroll") for (int k = 0; k < 2; ++k) dst[n][k] = *(const LAS bf16x8*)(lds + PG8_SB(b, h) + boff + n * 2048 + k * 1024); } while (0)
; #define PG8_MMA(ai, bj, At, Bt) do { __builtin_amdgcn_s_setprio(1); _Pragma("unroll") for (int m = 0; m < 4; ++m) _Pragma("unroll") for (int n = 0; n < 2; ++n) _Pragma("unroll") for (int k = 0; k < 2; ++k) \
;         acc[ai][bj][m][n] = __builtin_amdgcn_mfma_f32_16x16x32_bf16(Bt[n][k], At[m][k], acc[ai][bj][m][n], 0, 0, 0); __builtin_amdgcn_s_setprio(0); } while (0)
; #define PG8_WAIT_V(n) asm volatile("s_waitcnt vmcnt(" #n ")" ::: "memory")
; #define PG8_WAIT_L(n) asm volatile("s_waitcnt lgkmcnt(" #n ")" ::: "memory")
; #define PG8_BAR __builtin_amdgcn_s_barrier()
; #define PG8_SCHED __builtin_amdgcn_sched_barrier(0)
; template <class Epi>
; __device__ __forceinline__ void gemm_phase(LAS unsigned char* lds, const Gemm g, const StaticOrder& S, const Epi& E, int wv) {
;     ...
;             PG8_LDB(B0, 0, 0); PG8_SCHED; PG8_LDA(At, 0, 0); PG8_STAGE(PG8_SA(1, 1), a1 + hstepA, voffA);
;             PG8_WAIT_L(8); PG8_BAR; PG8_WAIT_L(0); PG8_MMA(0, 0, At, B0); PG8_BAR; PG8_SCHED;
;             PG8_LDB(B1, 0, 1); PG8_STAGE(PG8_SB(0, 0), b2, voffB);
;             PG8_BAR; PG8_WAIT_L(0); PG8_MMA(0, 1, At, B1); PG8_BAR;
;             PG8_LDA(At, 0, 1); PG8_STAGE(PG8_SA(0, 0), a2, voffA);
;             PG8_BAR; PG8_WAIT_L(0); PG8_MMA(1, 0, At, B0); PG8_BAR; PG8_SCHED;
;             PG8_STAGE(PG8_SB(0, 1), b2 + hstepB, voffB);
;             PG8_WAIT_V(6); PG8_BAR; PG8_MMA(1, 1, At, B1); PG8_BAR;
.LBB0_1581:
	s_add_u32 s48, s46, 0xfff80080
	s_addc_u32 s49, s47, -1
	s_cmp_eq_u32 s63, 28
	s_cselect_b32 s51, s37, s49
	s_cselect_b32 s50, s43, s48
	s_cselect_b32 s49, s35, s62
	s_cselect_b32 s48, s60, s61
	s_add_i32 m0, s33, 0xc000
	ds_read_b128 v[160:163], v180
	ds_read_b128 v[164:167], v180 offset:1024
	ds_read_b128 v[168:171], v180 offset:2048
	ds_read_b128 v[172:175], v180 offset:3072
	ds_read_b128 v[182:185], v180 offset:4096
	ds_read_b128 v[186:189], v180 offset:5120
	ds_read_b128 v[190:193], v180 offset:6144
	ds_read_b128 v[194:197], v180 offset:7168
	global_load_lds_dwordx4 v154, s[46:47]
	s_add_i32 m0, s33, 0xe000
	s_nop 0
	global_load_lds_dwordx4 v152, s[46:47]
	s_waitcnt lgkmcnt(8)
	s_barrier
	s_waitcnt lgkmcnt(0)
	s_waitcnt lgkmcnt(0)
	v_mfma_f32_16x16x32_bf16 v[124:127], v[128:131], v[160:163], v[124:127]
	v_mfma_f32_16x16x32_bf16 v[120:123], v[136:139], v[160:163], v[120:123]
	v_mfma_f32_16x16x32_bf16 v[108:111], v[128:131], v[168:171], v[108:111]
	v_mfma_f32_16x16x32_bf16 v[104:107], v[136:139], v[168:171], v[104:107]
	v_mfma_f32_16x16x32_bf16 v[92:95], v[128:131], v[182:185], v[92:95]
	v_mfma_f32_16x16x32_bf16 v[88:91], v[136:139], v[182:185], v[88:91]
	v_mfma_f32_16x16x32_bf16 v[76:79], v[128:131], v[190:193], v[76:79]
	v_mfma_f32_16x16x32_bf16 v[72:75], v[136:139], v[190:193], v[72:75]
	v_mfma_f32_16x16x32_bf16 v[124:127], v[132:135], v[164:167], v[124:127]
	v_mfma_f32_16x16x32_bf16 v[120:123], v[140:143], v[164:167], v[120:123]
	v_mfma_f32_16x16x32_bf16 v[108:111], v[132:135], v[172:175], v[108:111]
	v_mfma_f32_16x16x32_bf16 v[104:107], v[140:143], v[172:175], v[104:107]
	v_mfma_f32_16x16x32_bf16 v[92:95], v[132:135], v[186:189], v[92:95]
	v_mfma_f32_16x16x32_bf16 v[88:91], v[140:143], v[186:189], v[88:91]
	v_mfma_f32_16x16x32_bf16 v[76:79], v[132:135], v[194:197], v[76:79]
	v_mfma_f32_16x16x32_bf16 v[72:75], v[140:143], v[194:197], v[72:75]
	s_barrier
	s_add_i32 s64, s57, s25
	s_add_u32 s98, s48, s16
	s_addc_u32 s99, s49, s17
	s_mov_b32 m0, s64
	ds_read_b128 v[198:201], v181
	ds_read_b128 v[202:205], v181 offset:1024
	ds_read_b128 v[206:209], v181 offset:2048
	ds_read_b128 v[210:213], v181 offset:3072
	global_load_lds_dwordx4 v146, s[48:49]
	s_add_i32 m0, s64, 0x2000
	s_nop 0
	global_load_lds_dwordx4 v150, s[48:49]
	s_barrier
	s_waitcnt lgkmcnt(0)
	s_waitcnt lgkmcnt(0)
	v_mfma_f32_16x16x32_bf16 v[116:119], v[198:201], v[160:163], v[116:119]
	v_mfma_f32_16x16x32_bf16 v[112:115], v[206:209], v[160:163], v[112:115]
	v_mfma_f32_16x16x32_bf16 v[100:103], v[198:201], v[168:171], v[100:103]
	v_mfma_f32_16x16x32_bf16 v[96:99], v[206:209], v[168:171], v[96:99]
	v_mfma_f32_16x16x32_bf16 v[84:87], v[198:201], v[182:185], v[84:87]
	v_mfma_f32_16x16x32_bf16 v[80:83], v[206:209], v[182:185], v[80:83]
	v_mfma_f32_16x16x32_bf16 v[68:71], v[198:201], v[190:193], v[68:71]
	v_mfma_f32_16x16x32_bf16 v[64:67], v[206:209], v[190:193], v[64:67]
	v_mfma_f32_16x16x32_bf16 v[116:119], v[202:205], v[164:167], v[116:119]
	v_mfma_f32_16x16x32_bf16 v[112:115], v[210:213], v[164:167], v[112:115]
	v_mfma_f32_16x16x32_bf16 v[100:103], v[202:205], v[172:175], v[100:103]
	v_mfma_f32_16x16x32_bf16 v[96:99], v[210:213], v[172:175], v[96:99]
	v_mfma_f32_16x16x32_bf16 v[84:87], v[202:205], v[186:189], v[84:87]
	v_mfma_f32_16x16x32_bf16 v[80:83], v[210:213], v[186:189], v[80:83]
	v_mfma_f32_16x16x32_bf16 v[68:71], v[202:205], v[194:197], v[68:71]
	v_mfma_f32_16x16x32_bf16 v[64:67], v[210:213], v[194:197], v[64:67]
	s_mov_b32 m0, s33
	s_add_u32 s100, s50, s16
	s_addc_u32 s101, s51, s17
	s_barrier
	ds_read_b128 v[160:163], v180 offset:16384
	ds_read_b128 v[164:167], v180 offset:17408
	ds_read_b128 v[168:171], v180 offset:18432
	ds_read_b128 v[172:175], v180 offset:19456
	ds_read_b128 v[182:185], v180 offset:20480
	ds_read_b128 v[186:189], v180 offset:21504
	ds_read_b128 v[190:193], v180 offset:22528
	ds_read_b128 v[194:197], v180 offset:23552
	global_load_lds_dwordx4 v144, s[50:51]
	s_mov_b32 m0, s45
	s_nop 0
	global_load_lds_dwordx4 v148, s[50:51]
	s_waitcnt vmcnt(10)
	s_barrier
	s_waitcnt lgkmcnt(0)
	s_waitcnt lgkmcnt(0)
	v_mfma_f32_16x16x32_bf16 v[60:63], v[128:131], v[160:163], v[60:63]
	v_mfma_f32_16x16x32_bf16 v[56:59], v[136:139], v[160:163], v[56:59]
	v_mfma_f32_16x16x32_bf16 v[44:47], v[128:131], v[168:171], v[44:47]
	v_mfma_f32_16x16x32_bf16 v[40:43], v[136:139], v[168:171], v[40:43]
	v_mfma_f32_16x16x32_bf16 v[28:31], v[128:131], v[182:185], v[28:31]
	v_mfma_f32_16x16x32_bf16 v[24:27], v[136:139], v[182:185], v[24:27]
	v_mfma_f32_16x16x32_bf16 v[12:15], v[128:131], v[190:193], v[12:15]
	v_mfma_f32_16x16x32_bf16 v[8:11], v[136:139], v[190:193], v[8:11]
	v_mfma_f32_16x16x32_bf16 v[60:63], v[132:135], v[164:167], v[60:63]
	v_mfma_f32_16x16x32_bf16 v[56:59], v[140:143], v[164:167], v[56:59]
	v_mfma_f32_16x16x32_bf16 v[44:47], v[132:135], v[172:175], v[44:47]
	v_mfma_f32_16x16x32_bf16 v[40:43], v[140:143], v[172:175], v[40:43]
	v_mfma_f32_16x16x32_bf16 v[28:31], v[132:135], v[186:189], v[28:31]
	v_mfma_f32_16x16x32_bf16 v[24:27], v[140:143], v[186:189], v[24:27]
	v_mfma_f32_16x16x32_bf16 v[12:15], v[132:135], v[194:197], v[12:15]
	v_mfma_f32_16x16x32_bf16 v[8:11], v[140:143], v[194:197], v[8:11]
	s_barrier
	s_add_u32 s64, s48, 0x80000
	s_addc_u32 s65, s49, 0
	s_add_i32 s66, s58, s25
	s_mov_b32 m0, s66
	s_nop 0
	global_load_lds_dwordx4 v146, s[64:65]
	s_add_i32 m0, s66, 0x2000
	s_nop 0
	global_load_lds_dwordx4 v150, s[64:65]
	s_add_i32 s64, 0, 0x18000
	v_add_u32_e32 v140, s64, v177
	ds_read_b128 v[128:131], v140
	ds_read_b128 v[132:135], v140 offset:1024
	ds_read_b128 v[136:139], v140 offset:2048
	ds_read_b128 v[140:143], v140 offset:3072
	s_waitcnt vmcnt(6)
	s_barrier
; #define PG8_STAGE(bufoff, gbase, voff) do { _Pragma("unroll") for (int _i = 0; _i < 2; ++_i) \
;         __builtin_amdgcn_global_load_lds((const unsigned*)((const char*)(gbase) + (voff)[_i]), (LAS unsigned*)(lds + (bufoff) + ldsw + _i * 8192), 16, 0, 0); } while (0)
; #define PG8_LDA(dst, b, h) do { _Pragma("unroll") for (int m = 0; m < 4; ++m) _Pragma("unroll") for (int k = 0; k < 2; ++k) dst[m][k] = *(const LAS bf16x8*)(lds + PG8_SA(b, h) + aoff + m * 2048 + k * 1024); } while (0)
; #define PG8_LDB(dst, b, h) do { _Pragma("unroll") for (int n = 0; n < 2; ++n) _Pragma("unroll") for (int k = 0; k < 2; ++k) dst[n][k] = *(const LAS bf16x8*)(lds + PG8_SB(b, h) + boff + n * 2048 + k * 1024); } while (0)
; #define PG8_MMA(ai, bj, At, Bt) do { __builtin_amdgcn_s_setprio(1); _Pragma("unroll") for (int m = 0; m < 4; ++m) _Pragma("unroll") for (int n = 0; n < 2; ++n) _Pragma("unroll") for (int k = 0; k < 2; ++k) \
;         acc[ai][bj][m][n] = __builtin_amdgcn_mfma_f32_16x16x32_bf16(Bt[n][k], At[m][k], acc[ai][bj][m][n], 0, 0, 0); __builtin_amdgcn_s_setprio(0); } while (0)
; #define PG8_WAIT_V(n) asm volatile("s_waitcnt vmcnt(" #n ")" ::: "memory")
; #define PG8_WAIT_L(n) asm volatile("s_waitcnt lgkmcnt(" #n ")" ::: "memory")
; #define PG8_BAR __builtin_amdgcn_s_barrier()
; #define PG8_SCHED __builtin_amdgcn_sched_barrier(0)
; template <class Epi>
; __device__ __forceinline__ void gemm_phase(LAS unsigned char* lds, const Gemm g, const StaticOrder& S, const Epi& E, int wv) {
;     ...
;             PG8_WAIT_V(6); PG8_BAR; PG8_MMA(1, 1, At, B1); PG8_BAR;
;             PG8_LDB(B0, 1, 0); PG8_SCHED; PG8_LDA(At, 1, 0); PG8_STAGE(PG8_SA(0, 1), a2 + hstepA, voffA);
;             PG8_WAIT_L(8); PG8_BAR; PG8_WAIT_L(0); PG8_MMA(0, 0, At, B0); PG8_BAR; PG8_SCHED;
;             PG8_LDB(B1, 1, 1); PG8_STAGE(PG8_SB(1, 0), b3, voffB);
;             PG8_BAR; PG8_WAIT_L(0); PG8_MMA(0, 1, At, B1); PG8_BAR;
;             PG8_LDA(At, 1, 1); PG8_STAGE(PG8_SA(1, 0), a3, voffA);
;             PG8_BAR; PG8_WAIT_L(0); PG8_MMA(1, 0, At, B0); PG8_BAR; PG8_SCHED;
	v_mfma_f32_16x16x32_bf16 v[52:55], v[198:201], v[160:163], v[52:55]
	v_mfma_f32_16x16x32_bf16 v[48:51], v[206:209], v[160:163], v[48:51]
	v_mfma_f32_16x16x32_bf16 v[36:39], v[198:201], v[168:171], v[36:39]
	v_mfma_f32_16x16x32_bf16 v[32:35], v[206:209], v[168:171], v[32:35]
	v_mfma_f32_16x16x32_bf16 v[20:23], v[198:201], v[182:185], v[20:23]
	v_mfma_f32_16x16x32_bf16 v[16:19], v[206:209], v[182:185], v[16:19]
	v_mfma_f32_16x16x32_bf16 v[4:7], v[198:201], v[190:193], v[4:7]
	v_mfma_f32_16x16x32_bf16 v[0:3], v[206:209], v[190:193], v[0:3]
	v_mfma_f32_16x16x32_bf16 v[52:55], v[202:205], v[164:167], v[52:55]
	v_mfma_f32_16x16x32_bf16 v[48:51], v[210:213], v[164:167], v[48:51]
	v_mfma_f32_16x16x32_bf16 v[36:39], v[202:205], v[172:175], v[36:39]
	v_mfma_f32_16x16x32_bf16 v[32:35], v[210:213], v[172:175], v[32:35]
	v_mfma_f32_16x16x32_bf16 v[20:23], v[202:205], v[186:189], v[20:23]
	v_mfma_f32_16x16x32_bf16 v[16:19], v[210:213], v[186:189], v[16:19]
	v_mfma_f32_16x16x32_bf16 v[4:7], v[202:205], v[194:197], v[4:7]
	v_mfma_f32_16x16x32_bf16 v[0:3], v[210:213], v[194:197], v[0:3]
	s_waitcnt lgkmcnt(0)
	s_barrier
	s_add_u32 s50, s50, 0x80000
	s_addc_u32 s51, s51, 0
	s_mov_b32 m0, s52
	ds_read_b128 v[160:163], v180 offset:32768
	ds_read_b128 v[164:167], v180 offset:33792
	ds_read_b128 v[168:171], v180 offset:34816
	ds_read_b128 v[172:175], v180 offset:35840
	ds_read_b128 v[182:185], v180 offset:36864
	ds_read_b128 v[186:189], v180 offset:37888
	ds_read_b128 v[190:193], v180 offset:38912
	ds_read_b128 v[194:197], v180 offset:39936
	global_load_lds_dwordx4 v144, s[50:51]
	s_mov_b32 m0, s53
	s_nop 0
	global_load_lds_dwordx4 v148, s[50:51]
	s_waitcnt lgkmcnt(8)
	s_barrier
	s_waitcnt lgkmcnt(0)
	s_waitcnt lgkmcnt(0)
	v_mfma_f32_16x16x32_bf16 v[124:127], v[128:131], v[160:163], v[124:127]
	v_mfma_f32_16x16x32_bf16 v[120:123], v[136:139], v[160:163], v[120:123]
	v_mfma_f32_16x16x32_bf16 v[108:111], v[128:131], v[168:171], v[108:111]
	v_mfma_f32_16x16x32_bf16 v[104:107], v[136:139], v[168:171], v[104:107]
	v_mfma_f32_16x16x32_bf16 v[92:95], v[128:131], v[182:185], v[92:95]
	v_mfma_f32_16x16x32_bf16 v[88:91], v[136:139], v[182:185], v[88:91]
	v_mfma_f32_16x16x32_bf16 v[76:79], v[128:131], v[190:193], v[76:79]
	v_mfma_f32_16x16x32_bf16 v[72:75], v[136:139], v[190:193], v[72:75]
	v_mfma_f32_16x16x32_bf16 v[124:127], v[132:135], v[164:167], v[124:127]
	v_mfma_f32_16x16x32_bf16 v[120:123], v[140:143], v[164:167], v[120:123]
	v_mfma_f32_16x16x32_bf16 v[108:111], v[132:135], v[172:175], v[108:111]
	v_mfma_f32_16x16x32_bf16 v[104:107], v[140:143], v[172:175], v[104:107]
	v_mfma_f32_16x16x32_bf16 v[92:95], v[132:135], v[186:189], v[92:95]
	v_mfma_f32_16x16x32_bf16 v[88:91], v[140:143], v[186:189], v[88:91]
	v_mfma_f32_16x16x32_bf16 v[76:79], v[132:135], v[194:197], v[76:79]
	v_mfma_f32_16x16x32_bf16 v[72:75], v[140:143], v[194:197], v[72:75]
	s_barrier
	s_add_i32 s50, 0, 0x1c000
	s_add_i32 s51, s64, s25
	v_add_u32_e32 v210, s50, v177
	s_mov_b32 m0, s51
	ds_read_b128 v[198:201], v210
	ds_read_b128 v[202:205], v210 offset:1024
	ds_read_b128 v[206:209], v210 offset:2048
	ds_read_b128 v[210:213], v210 offset:3072
	global_load_lds_dwordx4 v146, s[98:99]
	s_add_i32 m0, s51, 0x2000
	s_nop 0
	global_load_lds_dwordx4 v150, s[98:99]
	s_barrier
	s_waitcnt lgkmcnt(0)
	s_waitcnt lgkmcnt(0)
	v_mfma_f32_16x16x32_bf16 v[116:119], v[198:201], v[160:163], v[116:119]
	v_mfma_f32_16x16x32_bf16 v[112:115], v[206:209], v[160:163], v[112:115]
	v_mfma_f32_16x16x32_bf16 v[100:103], v[198:201], v[168:171], v[100:103]
	v_mfma_f32_16x16x32_bf16 v[96:99], v[206:209], v[168:171], v[96:99]
	v_mfma_f32_16x16x32_bf16 v[84:87], v[198:201], v[182:185], v[84:87]
	v_mfma_f32_16x16x32_bf16 v[80:83], v[206:209], v[182:185], v[80:83]
	v_mfma_f32_16x16x32_bf16 v[68:71], v[198:201], v[190:193], v[68:71]
	v_mfma_f32_16x16x32_bf16 v[64:67], v[206:209], v[190:193], v[64:67]
	v_mfma_f32_16x16x32_bf16 v[116:119], v[202:205], v[164:167], v[116:119]
	v_mfma_f32_16x16x32_bf16 v[112:115], v[210:213], v[164:167], v[112:115]
	v_mfma_f32_16x16x32_bf16 v[100:103], v[202:205], v[172:175], v[100:103]
	v_mfma_f32_16x16x32_bf16 v[96:99], v[210:213], v[172:175], v[96:99]
	v_mfma_f32_16x16x32_bf16 v[84:87], v[202:205], v[186:189], v[84:87]
	v_mfma_f32_16x16x32_bf16 v[80:83], v[210:213], v[186:189], v[80:83]
	v_mfma_f32_16x16x32_bf16 v[68:71], v[202:205], v[194:197], v[68:71]
	v_mfma_f32_16x16x32_bf16 v[64:67], v[210:213], v[194:197], v[64:67]
	s_mov_b32 m0, s55
	s_barrier
	ds_read_b128 v[160:163], v180 offset:49152
	ds_read_b128 v[164:167], v180 offset:50176
	ds_read_b128 v[168:171], v180 offset:51200
	ds_read_b128 v[172:175], v180 offset:52224
	ds_read_b128 v[182:185], v180 offset:53248
	ds_read_b128 v[186:189], v180 offset:54272
	ds_read_b128 v[190:193], v180 offset:55296
	ds_read_b128 v[194:197], v180 offset:56320
	global_load_lds_dwordx4 v144, s[100:101]
	s_mov_b32 m0, s56
	s_nop 0
	global_load_lds_dwordx4 v148, s[100:101]
	s_waitcnt vmcnt(10)
	s_barrier
	s_waitcnt lgkmcnt(0)
	s_waitcnt lgkmcnt(0)
	v_mfma_f32_16x16x32_bf16 v[60:63], v[128:131], v[160:163], v[60:63]
	v_mfma_f32_16x16x32_bf16 v[56:59], v[136:139], v[160:163], v[56:59]
	v_mfma_f32_16x16x32_bf16 v[44:47], v[128:131], v[168:171], v[44:47]
	v_mfma_f32_16x16x32_bf16 v[40:43], v[136:139], v[168:171], v[40:43]
	v_mfma_f32_16x16x32_bf16 v[28:31], v[128:131], v[182:185], v[28:31]
	v_mfma_f32_16x16x32_bf16 v[24:27], v[136:139], v[182:185], v[24:27]
	v_mfma_f32_16x16x32_bf16 v[12:15], v[128:131], v[190:193], v[12:15]
	v_mfma_f32_16x16x32_bf16 v[8:11], v[136:139], v[190:193], v[8:11]
	v_mfma_f32_16x16x32_bf16 v[60:63], v[132:135], v[164:167], v[60:63]
	v_mfma_f32_16x16x32_bf16 v[56:59], v[140:143], v[164:167], v[56:59]
	v_mfma_f32_16x16x32_bf16 v[44:47], v[132:135], v[172:175], v[44:47]
	v_mfma_f32_16x16x32_bf16 v[40:43], v[140:143], v[172:175], v[40:43]
	v_mfma_f32_16x16x32_bf16 v[28:31], v[132:135], v[186:189], v[28:31]
	v_mfma_f32_16x16x32_bf16 v[24:27], v[140:143], v[186:189], v[24:27]
	v_mfma_f32_16x16x32_bf16 v[12:15], v[132:135], v[194:197], v[12:15]
	v_mfma_f32_16x16x32_bf16 v[8:11], v[140:143], v[194:197], v[8:11]
	s_barrier
; #define PG8_BAR __builtin_amdgcn_s_barrier()
; template <class Epi>
; __device__ __forceinline__ void gemm_phase(LAS unsigned char* lds, const Gemm g, const StaticOrder& S, const Epi& E, int wv) {
;     ...
;             PG8_BAR; PG8_WAIT_L(0); PG8_MMA(1, 0, At, B0); PG8_BAR; PG8_SCHED;
;             PG8_STAGE(PG8_SB(1, 1), b3 + hstepB, voffB);
;             PG8_WAIT_V(6); PG8_BAR; PG8_MMA(1, 1, At, B1); PG8_BAR;
;     __device__ __forceinline__ void operator()(const f32x4 (&acc)[2][2][4][2], const Unit& u, int wr, int wc, int fr, int fq) const {
;         const int row0 = u.pm * BM + wr * 64 + fr, col0 = u.pn * BM + wc * 32 + 8 * fq;
;         constexpr int RD = 3;
;         f32x4 hbuf[RD][4]; u32x4 hraw[RD][2]; u32x4 pbuf[RD][2]; float rsb[RD];
;     ...
;         RES_LOAD(0, 0); RES_LOAD(1, 1);
; #pragma unroll
;         for (int it = 0; it < 8; ++it) { const int ai = it >> 2, m = it & 3, sc = it % RD;
;             if (it + RD - 1 < 8) RES_LOAD((it + RD - 1) % RD, it + RD - 1);
;             asm volatile("" ::: "memory");
;             const int row = row0 + ai * HALF + m * 16; const size_t ro = (size_t)row * DM + col0;
;             float rs = 1.0f; if (MODE == 1) rs = __builtin_amdgcn_rsqf(ss_fix(rsb[sc]) * (1.0f / DM) + EPS);
;             float sq = 0.f;
; #pragma unroll
;             for (int bj = 0; bj < 2; ++bj) { const size_t off = ro + bj * HALF;
;                 f32x4 v0 = acc[ai][bj][m][0], v1 = acc[ai][bj][m][1];
;                 if (MODE == 1) { const u32x4 pw = pbuf[sc][bj];
;                     v0[0] = fast_sigmoid(rs * v0[0]) * bf_lo(pw.x); v0[1] = fast_sigmoid(rs * v0[1]) * bf_hi(pw.x); v0[2] = fast_sigmoid(rs * v0[2]) * bf_lo(pw.y); v0[3] = fast_sigmoid(rs * v0[3]) * bf_hi(pw.y);
;                     v1[0] = fast_sigmoid(rs * v1[0]) * bf_lo(pw.z); v1[1] = fast_sigmoid(rs * v1[1]) * bf_hi(pw.z); v1[2] = fast_sigmoid(rs * v1[2]) * bf_lo(pw.w); v1[3] = fast_sigmoid(rs * v1[3]) * bf_hi(pw.w); }
;                 f32x4 h0, h1;
;                 if (IN16) { const u32x4 hw = hraw[sc][bj]; h0 = (f32x4){bf_lo(hw.x), bf_hi(hw.x), bf_lo(hw.y), bf_hi(hw.y)}; h1 = (f32x4){bf_lo(hw.z), bf_hi(hw.z), bf_lo(hw.w), bf_hi(hw.w)}; }
;                 else { h0 = hbuf[sc][2 * bj]; h1 = hbuf[sc][2 * bj + 1]; }
;                 const f32x4 o0 = h0 + v0, o1 = h1 + v1;
;                 if (OUT32) { *(f32x4*)(hout + off) = o0; *(f32x4*)(hout + off + 4) = o1; }
	s_add_u32 s48, s48, 0x80080
	s_addc_u32 s49, s49, 0
	s_add_i32 s50, s50, s25
	s_mov_b32 m0, s50
	s_nop 0
	global_load_lds_dwordx4 v146, s[48:49]
	s_add_i32 m0, s50, 0x2000
	s_nop 0
	global_load_lds_dwordx4 v150, s[48:49]
	ds_read_b128 v[128:131], v179
	ds_read_b128 v[132:135], v179 offset:1024
	ds_read_b128 v[136:139], v179 offset:2048
	ds_read_b128 v[140:143], v179 offset:3072
	s_waitcnt vmcnt(6)
	s_barrier
	v_mfma_f32_16x16x32_bf16 v[52:55], v[198:201], v[160:163], v[52:55]
	v_mfma_f32_16x16x32_bf16 v[48:51], v[206:209], v[160:163], v[48:51]
	v_mfma_f32_16x16x32_bf16 v[36:39], v[198:201], v[168:171], v[36:39]
	v_mfma_f32_16x16x32_bf16 v[32:35], v[206:209], v[168:171], v[32:35]
	v_mfma_f32_16x16x32_bf16 v[20:23], v[198:201], v[182:185], v[20:23]
	v_mfma_f32_16x16x32_bf16 v[16:19], v[206:209], v[182:185], v[16:19]
	v_mfma_f32_16x16x32_bf16 v[4:7], v[198:201], v[190:193], v[4:7]
	v_mfma_f32_16x16x32_bf16 v[0:3], v[206:209], v[190:193], v[0:3]
	v_mfma_f32_16x16x32_bf16 v[52:55], v[202:205], v[164:167], v[52:55]
	v_mfma_f32_16x16x32_bf16 v[48:51], v[210:213], v[164:167], v[48:51]
	v_mfma_f32_16x16x32_bf16 v[36:39], v[202:205], v[172:175], v[36:39]
	v_mfma_f32_16x16x32_bf16 v[32:35], v[210:213], v[172:175], v[32:35]
	v_mfma_f32_16x16x32_bf16 v[20:23], v[202:205], v[186:189], v[20:23]
	v_mfma_f32_16x16x32_bf16 v[16:19], v[210:213], v[186:189], v[16:19]
	v_mfma_f32_16x16x32_bf16 v[4:7], v[202:205], v[194:197], v[4:7]
	v_mfma_f32_16x16x32_bf16 v[0:3], v[210:213], v[194:197], v[0:3]
	s_waitcnt lgkmcnt(0)
	s_add_i32 s63, s63, 2
	s_add_u32 s61, s61, 0x100
	s_addc_u32 s62, s62, 0
	s_add_u32 s46, s46, 0x100
	s_addc_u32 s47, s47, 0
	s_cmp_gt_u32 s63, 29
	s_barrier
	s_cbranch_scc0 .LBB0_1581
	v_lshl_add_u32 v170, s42, 8, v176
	v_lshl_or_b32 v160, s44, 8, v178
	v_ashrrev_i32_e32 v171, 31, v170
	v_ashrrev_i32_e32 v161, 31, v160
	v_lshlrev_b64 v[190:191], 12, v[170:171]
	v_lshl_add_u64 v[128:129], s[10:11], 0, v[190:191]
	v_lshlrev_b64 v[162:163], 1, v[160:161]
	v_lshl_add_u64 v[164:165], v[128:129], 0, v[162:163]
	global_load_dwordx4 v[182:185], v[164:165], off
	global_load_dwordx4 v[186:189], v[164:165], off offset:256
	v_or_b32_e32 v172, 16, v170
	v_or_b32_e32 v166, 32, v170
	v_ashrrev_i32_e32 v173, 31, v172
	v_ashrrev_i32_e32 v167, 31, v166
	v_lshlrev_b64 v[174:175], 12, v[172:173]
	v_lshlrev_b64 v[168:169], 12, v[166:167]
	v_lshl_add_u64 v[128:129], s[10:11], 0, v[174:175]
	v_lshl_add_u64 v[130:131], s[10:11], 0, v[168:169]
	v_lshl_add_u64 v[128:129], v[128:129], 0, v[162:163]
	v_lshl_add_u64 v[130:131], v[130:131], 0, v[162:163]
	global_load_dwordx4 v[140:143], v[128:129], off
	global_load_dwordx4 v[136:139], v[128:129], off offset:256
	global_load_dwordx4 v[132:135], v[130:131], off
	s_nop 0
	global_load_dwordx4 v[128:131], v[130:131], off offset:256
	s_waitcnt vmcnt(0)
	v_lshlrev_b32_e32 v192, 16, v182
	v_and_b32_e32 v193, 0xffff0000, v182
	v_lshlrev_b32_e32 v182, 16, v183
	v_and_b32_e32 v183, 0xffff0000, v183
	v_lshlrev_b32_e32 v194, 16, v184
	v_and_b32_e32 v195, 0xffff0000, v184
	v_lshlrev_b32_e32 v184, 16, v185
	v_and_b32_e32 v185, 0xffff0000, v185
	v_lshlrev_b32_e32 v196, 16, v186
	v_and_b32_e32 v197, 0xffff0000, v186
	v_lshlrev_b32_e32 v186, 16, v187
	v_and_b32_e32 v187, 0xffff0000, v187
	v_lshlrev_b32_e32 v198, 16, v188
	v_and_b32_e32 v199, 0xffff0000, v188
	v_lshlrev_b32_e32 v188, 16, v189
	v_and_b32_e32 v189, 0xffff0000, v189
	v_pk_add_f32 v[126:127], v[126:127], v[182:183]
	v_pk_add_f32 v[124:125], v[124:125], v[192:193]
	v_pk_add_f32 v[122:123], v[122:123], v[184:185]
	v_pk_add_f32 v[120:121], v[120:121], v[194:195]
	v_pk_add_f32 v[118:119], v[118:119], v[186:187]
	v_pk_add_f32 v[116:117], v[116:117], v[196:197]
	v_pk_add_f32 v[182:183], v[114:115], v[188:189]
	v_pk_add_f32 v[184:185], v[112:113], v[198:199]
	v_cvt_pk_bf16_f32 v112, v124, v125
	v_cvt_pk_bf16_f32 v113, v126, v127
	v_cvt_pk_bf16_f32 v114, v120, v121
	v_cvt_pk_bf16_f32 v115, v122, v123
	v_mul_f32_e32 v125, v125, v125
	v_mul_f32_e32 v127, v127, v127
	v_mul_f32_e32 v121, v121, v121
	v_mul_f32_e32 v123, v123, v123
	v_mul_f32_e32 v186, v117, v117
	v_mul_f32_e32 v187, v119, v119
	v_mul_f32_e32 v188, v185, v185
	v_mul_f32_e32 v189, v183, v183
	v_fmac_f32_e32 v125, v124, v124
	v_fmac_f32_e32 v127, v126, v126
	v_fmac_f32_e32 v121, v120, v120
	v_fmac_f32_e32 v123, v122, v122
	v_fmac_f32_e32 v186, v116, v116
	v_fmac_f32_e32 v187, v118, v118
	v_fmac_f32_e32 v188, v184, v184
	v_fmac_f32_e32 v189, v182, v182
	v_add_f32_e32 v120, v125, v127
	v_add_f32_e32 v121, v121, v123
	v_add_f32_e32 v122, v186, v187
	v_add_f32_e32 v123, v188, v189
	v_add_f32_e32 v120, v120, v121
	v_add_f32_e32 v121, v122, v123
	v_add_f32_e32 v122, v120, v121
	ds_bpermute_b32 v123, v245, v122
	v_lshl_add_u64 v[120:121], s[12:13], 0, v[190:191]
	v_lshl_add_u64 v[120:121], v[120:121], 0, v[162:163]
	global_store_dwordx4 v[120:121], v[112:115], off
	s_waitcnt lgkmcnt(0)
	s_nop 0
	v_add_f32_e32 v112, v122, v123
	ds_bpermute_b32 v113, v244, v112
	v_cvt_pk_bf16_f32 v114, v116, v117
	v_cvt_pk_bf16_f32 v115, v118, v119
	v_cvt_pk_bf16_f32 v116, v184, v185
	v_cvt_pk_bf16_f32 v117, v182, v183
	global_store_dwordx4 v[120:121], v[114:117], off offset:256
	s_and_saveexec_b64 s[42:43], s[6:7]
	s_cbranch_execz .LBB0_1584
	s_waitcnt lgkmcnt(0)
	v_add_f32_e32 v112, v112, v113
	v_fma_f32 v112, v112, s59, 0.5
	v_cvt_u32_f32_e32 v114, v112
	v_lshl_add_u64 v[112:113], v[170:171], 2, s[14:15]
	global_atomic_add v[112:113], v114, off

;     __device__ bool next(int i, Unit& u) const {
;         const long L = (long)i * G + c; if (L >= nwg) return false;
;         int wgid = (int)L; { const int q = nwg / NXCD, r = nwg % NXCD, xcd = wgid % NXCD, off = wgid / NXCD; wgid = (xcd < r ? xcd * (q + 1) : r * (q + 1) + (xcd - r) * q) + off; }
;         const int nig = wgm * nN, gid = wgid / nig, fm = gid * wgm, gsz = (nM - fm) < wgm ? (nM - fm) : wgm;
;         u.pm = fm + ((wgid % nig) % gsz); u.pn = (wgid % nig) / gsz; return true;
; template <class Epi>
; __device__ __forceinline__ void gemm_phase(LAS unsigned char* lds, const Gemm g, const StaticOrder& S, const Epi& E, int wv) {
;     const int tid = opaque_tid(wv), wid = __builtin_amdgcn_readfirstlane(tid >> 6), lane = tid & 63, wr = wid >> 2, wc = wid & 3, fr = lane & 15, fq = lane >> 4;
;     const int K = g.K, nt = K / BK;
;     unsigned voffA[2], voffB[2];
; #pragma unroll
;     for (int i = 0; i < 2; ++i) { int R, C; stage_rc(tid * 16 + i * 8192, R, C); const int Rb = Epi::PERM ? ((R & ~31) + perm32(R & 31)) : R;
;         voffA[i] = (unsigned)(R * g.lda + C) * 2u; voffB[i] = (unsigned)(Rb * g.ldb + C) * 2u; }
;     const bool krev = (g.adiag & 2) != 0;
;     const ptrdiff_t kstep = krev ? -(ptrdiff_t)(BK * 2) : (ptrdiff_t)(BK * 2);
;     const size_t kbeg = krev ? (size_t)(nt - 1) * (BK * 2) : 0;
;     const size_t hstepA = (size_t)HALF * g.lda * 2, hstepB = (size_t)HALF * g.ldb * 2;
;     const size_t tstepA = 2 * hstepA, tstepB = 2 * hstepB;
;     const unsigned ldsw = (unsigned)wid * 1024u;
;     const int aoff = lds_byte(wr * 64 + fr, fq * 8), boff = lds_byte(wc * 32 + fr, fq * 8);
;     ...
;     Unit cur, nxt; int ui = 0;
;     if (!S.next(0, cur)) return;
;     f32x4 acc[2][2][4][2];
; #pragma unroll
;     for (int a = 0; a < 2; ++a)
; #pragma unroll
;         for (int b = 0; b < 2; ++b)
; #pragma unroll
;             for (int m = 0; m < 4; ++m)
; #pragma unroll
;                 for (int n = 0; n < 2; ++n) acc[a][b][m][n] = (f32x4){0.f, 0.f, 0.f, 0.f};
;     bf16x8 At[4][2], B0[2][2], B1[2][2];
;     const char* cA = (const char*)g.A + (size_t)cur.pm * tstepA + ((g.adiag & 1) ? (size_t)(cur.pn >> 1) * K * 2 : 0) + kbeg;
;     const char* cB = (const char*)g.Bt + (size_t)cur.pn * tstepB + kbeg;
.LBB0_1658:
	v_ashrrev_i32_e32 v2, 31, v0
	v_lshrrev_b32_e32 v2, 26, v2
	v_lshlrev_b32_e32 v1, 4, v0
	v_add_u32_e32 v2, v0, v2
	v_bfe_i32 v0, v0, 27, 1
	v_lshrrev_b32_e32 v0, 22, v0
	v_add_u32_e32 v0, v1, v0
	v_and_b32_e32 v0, 0xfffffc00, v0
	v_sub_u32_e32 v0, v1, v0
	v_ashrrev_i32_e32 v9, 6, v2
	v_lshrrev_b32_e32 v2, 4, v0
	v_bitop3_b32 v0, v2, v0, 32 bitop3:0x6c
	v_ashrrev_i32_e32 v3, 31, v0
	v_lshrrev_b32_e32 v3, 26, v3
	v_add_u32_e32 v3, v0, v3
	s_ashr_i32 s14, s5, 3
	v_lshlrev_b32_e32 v2, 3, v9
	v_ashrrev_i32_e32 v10, 6, v3
	v_and_b32_e32 v3, 0xc0, v3
	s_waitcnt lgkmcnt(0)
	s_add_u32 s5, s12, 0xb300000
	v_and_b32_e32 v2, -16, v2
	v_sub_u32_e32 v0, v0, v3
	v_mov_b32_e32 v3, 1
	s_addc_u32 s22, s13, 0
	v_add_u32_e32 v2, v10, v2
	v_ashrrev_i16_sdwa v0, v3, sext(v0) dst_sel:DWORD dst_unused:UNUSED_PAD src0_sel:DWORD src1_sel:BYTE_0
	s_add_u32 s23, s10, 0x2900000
	v_lshlrev_b32_e32 v4, 5, v9
	v_bfe_i32 v11, v0, 0, 16
	v_lshlrev_b32_e32 v0, 1, v2
	v_lshrrev_b32_e32 v5, 2, v2
	v_and_b32_e32 v6, 3, v10
	s_mov_b32 s10, 0xfffe0
	v_and_b32_e32 v4, 32, v4
	v_and_b32_e32 v0, 24, v0
	v_and_b32_e32 v5, 4, v5
	v_and_or_b32 v6, v2, s10, v6
	v_or3_b32 v0, v6, v5, v0
	v_add_lshl_u32 v4, v4, v11, 1
	v_lshl_add_u32 v130, v0, 12, v4
	v_add_u32_e32 v0, 0x2000, v1
	v_ashrrev_i32_e32 v1, 31, v0
	v_lshrrev_b32_e32 v1, 22, v1
	v_add_u32_e32 v1, v0, v1
	v_ashrrev_i32_e32 v12, 10, v1
	v_mul_i32_i24_e32 v1, 0x400, v12
	v_sub_u32_e32 v0, v0, v1
	v_lshrrev_b32_e32 v1, 4, v0
	v_bitop3_b32 v0, v1, v0, 32 bitop3:0x6c
	v_lshl_add_u32 v128, v2, 12, v4
	v_ashrrev_i32_e32 v2, 31, v0
	v_lshrrev_b32_e32 v2, 26, v2
	v_add_u32_e32 v2, v0, v2
	v_lshlrev_b32_e32 v1, 3, v12
	v_ashrrev_i32_e32 v13, 6, v2
	v_and_b32_e32 v2, 0xc0, v2
	v_and_b32_e32 v1, -16, v1
	v_sub_u32_e32 v0, v0, v2
	v_add_u32_e32 v1, v13, v1
	v_ashrrev_i16_sdwa v0, v3, sext(v0) dst_sel:DWORD dst_unused:UNUSED_PAD src0_sel:DWORD src1_sel:BYTE_0
	v_and_b32_e32 v3, 3, v13
	s_addc_u32 s24, s11, 0
	v_and_or_b32 v3, v1, s10, v3
	s_add_i32 s10, s30, s14
	s_ashr_i32 s11, s10, 31
	s_lshr_b32 s11, s11, 24
	s_add_i32 s11, s10, s11
	s_ashr_i32 s13, s11, 8
	s_and_b32 s11, s11, 0xffffff00
	s_sub_i32 s10, s10, s11
	s_sext_i32_i16 s11, s10
	s_bfe_u32 s11, s11, 0x3001c
	s_add_i32 s11, s10, s11
	s_sext_i32_i16 s14, s11
	s_and_b32 s11, s11, 0xfff8
	s_sub_i32 s10, s10, s11
	s_lshl_b32 s13, s13, 3
	s_sext_i32_i16 s10, s10
	s_ashr_i32 s15, s4, 8
	s_lshr_b32 s14, s14, 3
	s_add_i32 s42, s13, s10
	s_ashr_i32 s12, s4, 6
	s_ashr_i32 s43, s42, 31
	s_bfe_i64 s[16:17], s[14:15], 0x100000
	s_lshl_b32 s25, s12, 10
	s_lshl_b64 s[10:11], s[42:43], 20
	s_lshl_b64 s[16:17], s[16:17], 20
	s_add_u32 s44, s23, s16
	v_lshlrev_b32_e32 v4, 5, v12
	v_bfe_i32 v14, v0, 0, 16
	v_lshlrev_b32_e32 v0, 1, v1
	v_lshrrev_b32_e32 v2, 2, v1
	s_addc_u32 s45, s24, s17
	s_add_i32 s33, s25, 0
	v_and_b32_e32 v4, 32, v4
	v_and_b32_e32 v0, 24, v0
	v_and_b32_e32 v2, 4, v2
	s_add_i32 m0, s33, 0x10000
	v_or3_b32 v0, v3, v2, v0
	v_add_lshl_u32 v2, v4, v14, 1
	global_load_lds_dwordx4 v130, s[44:45]
	s_add_i32 m0, s33, 0x12000
	v_lshl_add_u32 v134, v0, 12, v2
	s_add_u32 s46, s5, s10
	global_load_lds_dwordx4 v134, s[44:45]
	s_addc_u32 s47, s22, s11
	s_mov_b32 m0, s33
	s_add_i32 s43, s33, 0x2000
	v_lshl_add_u32 v132, v1, 12, v2
	global_load_lds_dwordx4 v128, s[46:47]
	s_mov_b32 m0, s43
	s_add_u32 s10, s44, 0x80000
	global_load_lds_dwordx4 v132, s[46:47]
	s_addc_u32 s11, s45, 0
	s_add_i32 m0, s33, 0x14000
	v_mov_b32_e32 v131, 0
	global_load_lds_dwordx4 v130, s[10:11]
	s_add_i32 m0, s33, 0x16000
	v_mov_b32_e32 v135, v131
	global_load_lds_dwordx4 v134, s[10:11]
	s_add_u32 s10, s46, 0x80000
	s_addc_u32 s11, s47, 0
	s_add_i32 s50, s33, 0x4000
	s_mov_b32 m0, s50
	s_add_i32 s51, s33, 0x6000
	global_load_lds_dwordx4 v128, s[10:11]
	s_mov_b32 m0, s51
	v_mov_b32_e32 v129, v131
	global_load_lds_dwordx4 v132, s[10:11]
	v_mov_b32_e32 v133, v131
	s_mov_b32 s52, 0
	v_lshl_add_u64 v[6:7], s[44:45], 0, v[130:131]
	v_lshl_add_u64 v[4:5], s[44:45], 0, v[134:135]
	v_lshl_add_u64 v[2:3], s[46:47], 0, v[128:129]
	s_cmp_lg_u32 s15, 1
	v_lshl_add_u64 v[0:1], s[46:47], 0, v[132:133]
	s_cbranch_scc1 .LBB0_1660
	s_barrier
	s_setprio 1

; #define PG8_STAGE(bufoff, gbase, voff) do { _Pragma("unroll") for (int _i = 0; _i < 2; ++_i) \
;         __builtin_amdgcn_global_load_lds((const unsigned*)((const char*)(gbase) + (voff)[_i]), (LAS unsigned*)(lds + (bufoff) + ldsw + _i * 8192), 16, 0, 0); } while (0)
; #define PG8_LDA(dst, b, h) do { _Pragma("unroll") for (int m = 0; m < 4; ++m) _Pragma("unroll") for (int k = 0; k < 2; ++k) dst[m][k] = *(const LAS bf16x8*)(lds + PG8_SA(b, h) + aoff + m * 2048 + k * 1024); } while (0)
; #define PG8_LDB(dst, b, h) do { _Pragma("unroll") for (int n = 0; n < 2; ++n) _Pragma("unroll") for (int k = 0; k < 2; ++k) dst[n][k] = *(const LAS bf16x8*)(lds + PG8_SB(b, h) + boff + n * 2048 + k * 1024); } while (0)
; #define PG8_MMA(ai, bj, At, Bt) do { __builtin_amdgcn_s_setprio(1); _Pragma("unroll") for (int m = 0; m < 4; ++m) _Pragma("unroll") for (int n = 0; n < 2; ++n) _Pragma("unroll") for (int k = 0; k < 2; ++k) \
;         acc[ai][bj][m][n] = __builtin_amdgcn_mfma_f32_16x16x32_bf16(Bt[n][k], At[m][k], acc[ai][bj][m][n], 0, 0, 0); __builtin_amdgcn_s_setprio(0); } while (0)
; #define PG8_WAIT_V(n) asm volatile("s_waitcnt vmcnt(" #n ")" ::: "memory")
; #define PG8_WAIT_L(n) asm volatile("s_waitcnt lgkmcnt(" #n ")" ::: "memory")
; #define PG8_BAR __builtin_amdgcn_s_barrier()
; #define PG8_SCHED __builtin_amdgcn_sched_barrier(0)
; template <class Epi>
; __device__ __forceinline__ void gemm_phase(LAS unsigned char* lds, const Gemm g, const StaticOrder& S, const Epi& E, int wv) {
;     ...
;             PG8_LDB(B0, 0, 0); PG8_SCHED; PG8_LDA(At, 0, 0); PG8_STAGE(PG8_SA(1, 1), a1 + hstepA, voffA);
;             PG8_WAIT_L(8); PG8_BAR; PG8_WAIT_L(0); PG8_MMA(0, 0, At, B0); PG8_BAR; PG8_SCHED;
;             PG8_LDB(B1, 0, 1); PG8_STAGE(PG8_SB(0, 0), b2, voffB);
;             PG8_BAR; PG8_WAIT_L(0); PG8_MMA(0, 1, At, B1); PG8_BAR;
;             PG8_LDA(At, 0, 1); PG8_STAGE(PG8_SA(0, 0), a2, voffA);
;             PG8_BAR; PG8_WAIT_L(0); PG8_MMA(1, 0, At, B0); PG8_BAR; PG8_SCHED;
;             PG8_STAGE(PG8_SB(0, 1), b2 + hstepB, voffB);
;             PG8_WAIT_V(6); PG8_BAR; PG8_MMA(1, 1, At, B1); PG8_BAR;
.LBB0_1668:
	s_add_u32 s46, s44, 0xfff80080
	s_addc_u32 s47, s45, -1
	s_cmp_eq_u32 s66, 28
	s_cselect_b32 s49, s37, s47
	s_cselect_b32 s48, s62, s46
	s_cselect_b32 s47, s35, s65
	s_cselect_b32 s46, s63, s64
	s_add_i32 m0, s33, 0xc000
	ds_read_b128 v[170:173], v154
	ds_read_b128 v[174:177], v154 offset:1024
	ds_read_b128 v[178:181], v154 offset:2048
	ds_read_b128 v[182:185], v154 offset:3072
	ds_read_b128 v[186:189], v154 offset:4096
	ds_read_b128 v[190:193], v154 offset:5120
	ds_read_b128 v[194:197], v154 offset:6144
	ds_read_b128 v[198:201], v154 offset:7168
	global_load_lds_dwordx4 v138, s[44:45]
	s_add_i32 m0, s33, 0xe000
	s_nop 0
	global_load_lds_dwordx4 v136, s[44:45]
	s_waitcnt lgkmcnt(8)
	s_barrier
	s_waitcnt lgkmcnt(0)
	s_waitcnt lgkmcnt(0)
	v_mfma_f32_16x16x32_bf16 v[124:127], v[144:147], v[170:173], v[124:127]
	v_mfma_f32_16x16x32_bf16 v[120:123], v[162:165], v[170:173], v[120:123]
	v_mfma_f32_16x16x32_bf16 v[116:119], v[144:147], v[178:181], v[116:119]
	v_mfma_f32_16x16x32_bf16 v[112:115], v[162:165], v[178:181], v[112:115]
	v_mfma_f32_16x16x32_bf16 v[92:95], v[144:147], v[186:189], v[92:95]
	v_mfma_f32_16x16x32_bf16 v[88:91], v[162:165], v[186:189], v[88:91]
	v_mfma_f32_16x16x32_bf16 v[76:79], v[144:147], v[194:197], v[76:79]
	v_mfma_f32_16x16x32_bf16 v[72:75], v[162:165], v[194:197], v[72:75]
	v_mfma_f32_16x16x32_bf16 v[124:127], v[158:161], v[174:177], v[124:127]
	v_mfma_f32_16x16x32_bf16 v[120:123], v[166:169], v[174:177], v[120:123]
	v_mfma_f32_16x16x32_bf16 v[116:119], v[158:161], v[182:185], v[116:119]
	v_mfma_f32_16x16x32_bf16 v[112:115], v[166:169], v[182:185], v[112:115]
	v_mfma_f32_16x16x32_bf16 v[92:95], v[158:161], v[190:193], v[92:95]
	v_mfma_f32_16x16x32_bf16 v[88:91], v[166:169], v[190:193], v[88:91]
	v_mfma_f32_16x16x32_bf16 v[76:79], v[158:161], v[198:201], v[76:79]
	v_mfma_f32_16x16x32_bf16 v[72:75], v[166:169], v[198:201], v[72:75]
	s_barrier
	s_add_i32 s67, s55, s25
	s_add_u32 s98, s46, s12
	s_addc_u32 s99, s47, s13
	s_mov_b32 m0, s67
	ds_read_b128 v[202:205], v155
	ds_read_b128 v[206:209], v155 offset:1024
	ds_read_b128 v[210:213], v155 offset:2048
	ds_read_b128 v[214:217], v155 offset:3072
	global_load_lds_dwordx4 v130, s[46:47]
	s_add_i32 m0, s67, 0x2000
	s_nop 0
	global_load_lds_dwordx4 v134, s[46:47]
	s_barrier
	s_waitcnt lgkmcnt(0)
	s_waitcnt lgkmcnt(0)
	v_mfma_f32_16x16x32_bf16 v[108:111], v[202:205], v[170:173], v[108:111]
	v_mfma_f32_16x16x32_bf16 v[104:107], v[210:213], v[170:173], v[104:107]
	v_mfma_f32_16x16x32_bf16 v[100:103], v[202:205], v[178:181], v[100:103]
	v_mfma_f32_16x16x32_bf16 v[96:99], v[210:213], v[178:181], v[96:99]
	v_mfma_f32_16x16x32_bf16 v[84:87], v[202:205], v[186:189], v[84:87]
	v_mfma_f32_16x16x32_bf16 v[80:83], v[210:213], v[186:189], v[80:83]
	v_mfma_f32_16x16x32_bf16 v[68:71], v[202:205], v[194:197], v[68:71]
	v_mfma_f32_16x16x32_bf16 v[64:67], v[210:213], v[194:197], v[64:67]
	v_mfma_f32_16x16x32_bf16 v[108:111], v[206:209], v[174:177], v[108:111]
	v_mfma_f32_16x16x32_bf16 v[104:107], v[214:217], v[174:177], v[104:107]
	v_mfma_f32_16x16x32_bf16 v[100:103], v[206:209], v[182:185], v[100:103]
	v_mfma_f32_16x16x32_bf16 v[96:99], v[214:217], v[182:185], v[96:99]
	v_mfma_f32_16x16x32_bf16 v[84:87], v[206:209], v[190:193], v[84:87]
	v_mfma_f32_16x16x32_bf16 v[80:83], v[214:217], v[190:193], v[80:83]
	v_mfma_f32_16x16x32_bf16 v[68:71], v[206:209], v[198:201], v[68:71]
	v_mfma_f32_16x16x32_bf16 v[64:67], v[214:217], v[198:201], v[64:67]
	s_mov_b32 m0, s33
	s_add_u32 s100, s48, s12
	s_addc_u32 s101, s49, s13
	s_barrier
	ds_read_b128 v[170:173], v154 offset:16384
	ds_read_b128 v[174:177], v154 offset:17408
	ds_read_b128 v[178:181], v154 offset:18432
	ds_read_b128 v[182:185], v154 offset:19456
	ds_read_b128 v[186:189], v154 offset:20480
	ds_read_b128 v[190:193], v154 offset:21504
	ds_read_b128 v[194:197], v154 offset:22528
	ds_read_b128 v[198:201], v154 offset:23552
	global_load_lds_dwordx4 v128, s[48:49]
	s_mov_b32 m0, s43
	s_nop 0
	global_load_lds_dwordx4 v132, s[48:49]
	s_waitcnt vmcnt(10)
	s_barrier
	s_waitcnt lgkmcnt(0)
	s_waitcnt lgkmcnt(0)
	v_mfma_f32_16x16x32_bf16 v[60:63], v[144:147], v[170:173], v[60:63]
	v_mfma_f32_16x16x32_bf16 v[56:59], v[162:165], v[170:173], v[56:59]
	v_mfma_f32_16x16x32_bf16 v[44:47], v[144:147], v[178:181], v[44:47]
	v_mfma_f32_16x16x32_bf16 v[40:43], v[162:165], v[178:181], v[40:43]
	v_mfma_f32_16x16x32_bf16 v[28:31], v[144:147], v[186:189], v[28:31]
	v_mfma_f32_16x16x32_bf16 v[24:27], v[162:165], v[186:189], v[24:27]
	v_mfma_f32_16x16x32_bf16 v[12:15], v[144:147], v[194:197], v[12:15]
	v_mfma_f32_16x16x32_bf16 v[8:11], v[162:165], v[194:197], v[8:11]
	v_mfma_f32_16x16x32_bf16 v[60:63], v[158:161], v[174:177], v[60:63]
	v_mfma_f32_16x16x32_bf16 v[56:59], v[166:169], v[174:177], v[56:59]
	v_mfma_f32_16x16x32_bf16 v[44:47], v[158:161], v[182:185], v[44:47]
	v_mfma_f32_16x16x32_bf16 v[40:43], v[166:169], v[182:185], v[40:43]
	v_mfma_f32_16x16x32_bf16 v[28:31], v[158:161], v[190:193], v[28:31]
	v_mfma_f32_16x16x32_bf16 v[24:27], v[166:169], v[190:193], v[24:27]
	v_mfma_f32_16x16x32_bf16 v[12:15], v[158:161], v[198:201], v[12:15]
	v_mfma_f32_16x16x32_bf16 v[8:11], v[166:169], v[198:201], v[8:11]
	s_barrier
	s_add_u32 s68, s46, 0x80000
	s_addc_u32 s69, s47, 0
	s_add_i32 s67, s56, s25
	s_mov_b32 m0, s67
	s_nop 0
	global_load_lds_dwordx4 v130, s[68:69]
	s_add_i32 m0, s67, 0x2000
	s_nop 0
	global_load_lds_dwordx4 v134, s[68:69]
	s_add_i32 s67, 0, 0x18000
	v_add_u32_e32 v157, s67, v151
	ds_read_b128 v[144:147], v157
	ds_read_b128 v[158:161], v157 offset:1024
	ds_read_b128 v[162:165], v157 offset:2048
	ds_read_b128 v[166:169], v157 offset:3072
	s_waitcnt vmcnt(6)
	s_barrier
; #define PG8_STAGE(bufoff, gbase, voff) do { _Pragma("unroll") for (int _i = 0; _i < 2; ++_i) \
;         __builtin_amdgcn_global_load_lds((const unsigned*)((const char*)(gbase) + (voff)[_i]), (LAS unsigned*)(lds + (bufoff) + ldsw + _i * 8192), 16, 0, 0); } while (0)
; #define PG8_LDA(dst, b, h) do { _Pragma("unroll") for (int m = 0; m < 4; ++m) _Pragma("unroll") for (int k = 0; k < 2; ++k) dst[m][k] = *(const LAS bf16x8*)(lds + PG8_SA(b, h) + aoff + m * 2048 + k * 1024); } while (0)
; #define PG8_LDB(dst, b, h) do { _Pragma("unroll") for (int n = 0; n < 2; ++n) _Pragma("unroll") for (int k = 0; k < 2; ++k) dst[n][k] = *(const LAS bf16x8*)(lds + PG8_SB(b, h) + boff + n * 2048 + k * 1024); } while (0)
; #define PG8_MMA(ai, bj, At, Bt) do { __builtin_amdgcn_s_setprio(1); _Pragma("unroll") for (int m = 0; m < 4; ++m) _Pragma("unroll") for (int n = 0; n < 2; ++n) _Pragma("unroll") for (int k = 0; k < 2; ++k) \
;         acc[ai][bj][m][n] = __builtin_amdgcn_mfma_f32_16x16x32_bf16(Bt[n][k], At[m][k], acc[ai][bj][m][n], 0, 0, 0); __builtin_amdgcn_s_setprio(0); } while (0)
; #define PG8_WAIT_V(n) asm volatile("s_waitcnt vmcnt(" #n ")" ::: "memory")
; #define PG8_WAIT_L(n) asm volatile("s_waitcnt lgkmcnt(" #n ")" ::: "memory")
; #define PG8_BAR __builtin_amdgcn_s_barrier()
; #define PG8_SCHED __builtin_amdgcn_sched_barrier(0)
; template <class Epi>
; __device__ __forceinline__ void gemm_phase(LAS unsigned char* lds, const Gemm g, const StaticOrder& S, const Epi& E, int wv) {
;     ...
;             PG8_WAIT_V(6); PG8_BAR; PG8_MMA(1, 1, At, B1); PG8_BAR;
;             PG8_LDB(B0, 1, 0); PG8_SCHED; PG8_LDA(At, 1, 0); PG8_STAGE(PG8_SA(0, 1), a2 + hstepA, voffA);
;             PG8_WAIT_L(8); PG8_BAR; PG8_WAIT_L(0); PG8_MMA(0, 0, At, B0); PG8_BAR; PG8_SCHED;
;             PG8_LDB(B1, 1, 1); PG8_STAGE(PG8_SB(1, 0), b3, voffB);
;             PG8_BAR; PG8_WAIT_L(0); PG8_MMA(0, 1, At, B1); PG8_BAR;
;             PG8_LDA(At, 1, 1); PG8_STAGE(PG8_SA(1, 0), a3, voffA);
;             PG8_BAR; PG8_WAIT_L(0); PG8_MMA(1, 0, At, B0); PG8_BAR; PG8_SCHED;
	v_mfma_f32_16x16x32_bf16 v[52:55], v[202:205], v[170:173], v[52:55]
	v_mfma_f32_16x16x32_bf16 v[48:51], v[210:213], v[170:173], v[48:51]
	v_mfma_f32_16x16x32_bf16 v[36:39], v[202:205], v[178:181], v[36:39]
	v_mfma_f32_16x16x32_bf16 v[32:35], v[210:213], v[178:181], v[32:35]
	v_mfma_f32_16x16x32_bf16 v[20:23], v[202:205], v[186:189], v[20:23]
	v_mfma_f32_16x16x32_bf16 v[16:19], v[210:213], v[186:189], v[16:19]
	v_mfma_f32_16x16x32_bf16 v[4:7], v[202:205], v[194:197], v[4:7]
	v_mfma_f32_16x16x32_bf16 v[0:3], v[210:213], v[194:197], v[0:3]
	v_mfma_f32_16x16x32_bf16 v[52:55], v[206:209], v[174:177], v[52:55]
	v_mfma_f32_16x16x32_bf16 v[48:51], v[214:217], v[174:177], v[48:51]
	v_mfma_f32_16x16x32_bf16 v[36:39], v[206:209], v[182:185], v[36:39]
	v_mfma_f32_16x16x32_bf16 v[32:35], v[214:217], v[182:185], v[32:35]
	v_mfma_f32_16x16x32_bf16 v[20:23], v[206:209], v[190:193], v[20:23]
	v_mfma_f32_16x16x32_bf16 v[16:19], v[214:217], v[190:193], v[16:19]
	v_mfma_f32_16x16x32_bf16 v[4:7], v[206:209], v[198:201], v[4:7]
	v_mfma_f32_16x16x32_bf16 v[0:3], v[214:217], v[198:201], v[0:3]
	s_waitcnt lgkmcnt(0)
	s_barrier
	s_add_u32 s48, s48, 0x80000
	s_addc_u32 s49, s49, 0
	s_mov_b32 m0, s50
	ds_read_b128 v[170:173], v154 offset:32768
	ds_read_b128 v[174:177], v154 offset:33792
	ds_read_b128 v[178:181], v154 offset:34816
	ds_read_b128 v[182:185], v154 offset:35840
	ds_read_b128 v[186:189], v154 offset:36864
	ds_read_b128 v[190:193], v154 offset:37888
	ds_read_b128 v[194:197], v154 offset:38912
	ds_read_b128 v[198:201], v154 offset:39936
	global_load_lds_dwordx4 v128, s[48:49]
	s_mov_b32 m0, s51
	s_nop 0
	global_load_lds_dwordx4 v132, s[48:49]
	s_waitcnt lgkmcnt(8)
	s_barrier
	s_waitcnt lgkmcnt(0)
	s_waitcnt lgkmcnt(0)
	v_mfma_f32_16x16x32_bf16 v[124:127], v[144:147], v[170:173], v[124:127]
	v_mfma_f32_16x16x32_bf16 v[120:123], v[162:165], v[170:173], v[120:123]
	v_mfma_f32_16x16x32_bf16 v[116:119], v[144:147], v[178:181], v[116:119]
	v_mfma_f32_16x16x32_bf16 v[112:115], v[162:165], v[178:181], v[112:115]
	v_mfma_f32_16x16x32_bf16 v[92:95], v[144:147], v[186:189], v[92:95]
	v_mfma_f32_16x16x32_bf16 v[88:91], v[162:165], v[186:189], v[88:91]
	v_mfma_f32_16x16x32_bf16 v[76:79], v[144:147], v[194:197], v[76:79]
	v_mfma_f32_16x16x32_bf16 v[72:75], v[162:165], v[194:197], v[72:75]
	v_mfma_f32_16x16x32_bf16 v[124:127], v[158:161], v[174:177], v[124:127]
	v_mfma_f32_16x16x32_bf16 v[120:123], v[166:169], v[174:177], v[120:123]
	v_mfma_f32_16x16x32_bf16 v[116:119], v[158:161], v[182:185], v[116:119]
	v_mfma_f32_16x16x32_bf16 v[112:115], v[166:169], v[182:185], v[112:115]
	v_mfma_f32_16x16x32_bf16 v[92:95], v[158:161], v[190:193], v[92:95]
	v_mfma_f32_16x16x32_bf16 v[88:91], v[166:169], v[190:193], v[88:91]
	v_mfma_f32_16x16x32_bf16 v[76:79], v[158:161], v[198:201], v[76:79]
	v_mfma_f32_16x16x32_bf16 v[72:75], v[166:169], v[198:201], v[72:75]
	s_barrier
	s_add_i32 s48, 0, 0x1c000
	s_add_i32 s49, s67, s25
	v_add_u32_e32 v157, s48, v151
	s_mov_b32 m0, s49
	ds_read_b128 v[202:205], v157
	ds_read_b128 v[206:209], v157 offset:1024
	ds_read_b128 v[210:213], v157 offset:2048
	ds_read_b128 v[214:217], v157 offset:3072
	global_load_lds_dwordx4 v130, s[98:99]
	s_add_i32 m0, s49, 0x2000
	s_nop 0
	global_load_lds_dwordx4 v134, s[98:99]
	s_barrier
	s_waitcnt lgkmcnt(0)
	s_waitcnt lgkmcnt(0)
	v_mfma_f32_16x16x32_bf16 v[108:111], v[202:205], v[170:173], v[108:111]
	v_mfma_f32_16x16x32_bf16 v[104:107], v[210:213], v[170:173], v[104:107]
	v_mfma_f32_16x16x32_bf16 v[100:103], v[202:205], v[178:181], v[100:103]
	v_mfma_f32_16x16x32_bf16 v[96:99], v[210:213], v[178:181], v[96:99]
	v_mfma_f32_16x16x32_bf16 v[84:87], v[202:205], v[186:189], v[84:87]
	v_mfma_f32_16x16x32_bf16 v[80:83], v[210:213], v[186:189], v[80:83]
	v_mfma_f32_16x16x32_bf16 v[68:71], v[202:205], v[194:197], v[68:71]
	v_mfma_f32_16x16x32_bf16 v[64:67], v[210:213], v[194:197], v[64:67]
	v_mfma_f32_16x16x32_bf16 v[108:111], v[206:209], v[174:177], v[108:111]
	v_mfma_f32_16x16x32_bf16 v[104:107], v[214:217], v[174:177], v[104:107]
	v_mfma_f32_16x16x32_bf16 v[100:103], v[206:209], v[182:185], v[100:103]
	v_mfma_f32_16x16x32_bf16 v[96:99], v[214:217], v[182:185], v[96:99]
	v_mfma_f32_16x16x32_bf16 v[84:87], v[206:209], v[190:193], v[84:87]
	v_mfma_f32_16x16x32_bf16 v[80:83], v[214:217], v[190:193], v[80:83]
	v_mfma_f32_16x16x32_bf16 v[68:71], v[206:209], v[198:201], v[68:71]
	v_mfma_f32_16x16x32_bf16 v[64:67], v[214:217], v[198:201], v[64:67]
	s_mov_b32 m0, s53
	s_barrier
	ds_read_b128 v[170:173], v154 offset:49152
	ds_read_b128 v[174:177], v154 offset:50176
	ds_read_b128 v[178:181], v154 offset:51200
	ds_read_b128 v[182:185], v154 offset:52224
	ds_read_b128 v[186:189], v154 offset:53248
	ds_read_b128 v[190:193], v154 offset:54272
	ds_read_b128 v[194:197], v154 offset:55296
	ds_read_b128 v[198:201], v154 offset:56320
	global_load_lds_dwordx4 v128, s[100:101]
	s_mov_b32 m0, s54
	s_nop 0
	global_load_lds_dwordx4 v132, s[100:101]
	s_waitcnt vmcnt(10)
	s_barrier
	s_waitcnt lgkmcnt(0)
	s_waitcnt lgkmcnt(0)
	v_mfma_f32_16x16x32_bf16 v[60:63], v[144:147], v[170:173], v[60:63]
	v_mfma_f32_16x16x32_bf16 v[56:59], v[162:165], v[170:173], v[56:59]
	v_mfma_f32_16x16x32_bf16 v[44:47], v[144:147], v[178:181], v[44:47]
	v_mfma_f32_16x16x32_bf16 v[40:43], v[162:165], v[178:181], v[40:43]
	v_mfma_f32_16x16x32_bf16 v[28:31], v[144:147], v[186:189], v[28:31]
	v_mfma_f32_16x16x32_bf16 v[24:27], v[162:165], v[186:189], v[24:27]
	v_mfma_f32_16x16x32_bf16 v[12:15], v[144:147], v[194:197], v[12:15]
	v_mfma_f32_16x16x32_bf16 v[8:11], v[162:165], v[194:197], v[8:11]
	v_mfma_f32_16x16x32_bf16 v[60:63], v[158:161], v[174:177], v[60:63]
	v_mfma_f32_16x16x32_bf16 v[56:59], v[166:169], v[174:177], v[56:59]
	v_mfma_f32_16x16x32_bf16 v[44:47], v[158:161], v[182:185], v[44:47]
	v_mfma_f32_16x16x32_bf16 v[40:43], v[166:169], v[182:185], v[40:43]
	v_mfma_f32_16x16x32_bf16 v[28:31], v[158:161], v[190:193], v[28:31]
	v_mfma_f32_16x16x32_bf16 v[24:27], v[166:169], v[190:193], v[24:27]
	v_mfma_f32_16x16x32_bf16 v[12:15], v[158:161], v[198:201], v[12:15]
	v_mfma_f32_16x16x32_bf16 v[8:11], v[166:169], v[198:201], v[8:11]
	s_barrier
; __device__ __forceinline__ float ss_fix(float raw) { return (float)__float_as_uint(raw) * (1.0f / 256.0f); }
; #define PG8_WAIT_V(n) asm volatile("s_waitcnt vmcnt(" #n ")" ::: "memory")
; #define PG8_BAR __builtin_amdgcn_s_barrier()
; template <class Epi>
; __device__ __forceinline__ void gemm_phase(LAS unsigned char* lds, const Gemm g, const StaticOrder& S, const Epi& E, int wv) {
;     ...
;             PG8_BAR; PG8_WAIT_L(0); PG8_MMA(1, 0, At, B0); PG8_BAR; PG8_SCHED;
;             PG8_STAGE(PG8_SB(1, 1), b3 + hstepB, voffB);
;             PG8_WAIT_V(6); PG8_BAR; PG8_MMA(1, 1, At, B1); PG8_BAR;
;     __device__ __forceinline__ void operator()(const f32x4 (&acc)[2][2][4][2], const Unit& u, int wr, int wc, int fr, int fq) const {
;         const int row0 = u.pm * BM + wr * 64 + fr; int colt = u.pn * BM; bf16_t* base = O; int tsel = 0;
;         if (split_cols) { tsel = colt / split_cols; base += (size_t)tsel * split_stride; colt -= tsel * split_cols; }
;         const int col0 = colt + wc * 32 + 8 * fq;
;         f32x4 cs[2][2];
;         if (SM == 2) {
; #pragma unroll
;             for (int bj = 0; bj < 2; ++bj)
; #pragma unroll
;                 for (int n = 0; n < 2; ++n) { const f32x4 s = *(const f32x4*)(ss + u.pn * BM + wc * 32 + 8 * fq + bj * HALF + 4 * n);
; #pragma unroll
;                     for (int j = 0; j < 4; ++j) cs[bj][n][j] = __builtin_amdgcn_rsqf(ss_fix(s[j]) * (1.0f / DM) + EPS); }
;         }
;         float rsv[8];
; #pragma unroll
;         for (int it = 0; it < 8; ++it) rsv[it] = (SM == 1) ? ss[row0 + (it >> 2) * HALF + (it & 3) * 16] : 1.0f;
; #pragma unroll
;         for (int ai = 0; ai < 2; ++ai)
; #pragma unroll
;             for (int m = 0; m < 4; ++m) { const int row = row0 + ai * HALF + m * 16; float rs = 1.0f; if (SM == 1) rs = __builtin_amdgcn_rsqf(ss_fix(rsv[ai * 4 + m]) * (1.0f / DM) + EPS);
;                 bf16_t* rowp = base + (size_t)row * ldc + col0;
; #pragma unroll
;                 for (int bj = 0; bj < 2; ++bj) { f32x4 v0 = acc[ai][bj][m][0], v1 = acc[ai][bj][m][1];
;                     if (SM == 1) { v0 *= rs; v1 *= rs; }
;                     if (SM == 2) { v0 *= cs[bj][0]; v1 *= cs[bj][1]; }
;                     if (ACT == 1) {
; #pragma unroll
;                         for (int j = 0; j < 4; ++j) { const float a = fmaxf(v0[j], 0.f), b = fmaxf(v1[j], 0.f); v0[j] = a * a; v1[j] = b * b; } }
	s_add_u32 s46, s46, 0x80080
	s_addc_u32 s47, s47, 0
	s_add_i32 s48, s48, s25
	s_mov_b32 m0, s48
	s_nop 0
	global_load_lds_dwordx4 v130, s[46:47]
	s_add_i32 m0, s48, 0x2000
	s_nop 0
	global_load_lds_dwordx4 v134, s[46:47]
	ds_read_b128 v[144:147], v153
	ds_read_b128 v[158:161], v153 offset:1024
	ds_read_b128 v[162:165], v153 offset:2048
	ds_read_b128 v[166:169], v153 offset:3072
	s_waitcnt vmcnt(6)
	s_barrier
	v_mfma_f32_16x16x32_bf16 v[52:55], v[202:205], v[170:173], v[52:55]
	v_mfma_f32_16x16x32_bf16 v[48:51], v[210:213], v[170:173], v[48:51]
	v_mfma_f32_16x16x32_bf16 v[36:39], v[202:205], v[178:181], v[36:39]
	v_mfma_f32_16x16x32_bf16 v[32:35], v[210:213], v[178:181], v[32:35]
	v_mfma_f32_16x16x32_bf16 v[20:23], v[202:205], v[186:189], v[20:23]
	v_mfma_f32_16x16x32_bf16 v[16:19], v[210:213], v[186:189], v[16:19]
	v_mfma_f32_16x16x32_bf16 v[4:7], v[202:205], v[194:197], v[4:7]
	v_mfma_f32_16x16x32_bf16 v[0:3], v[210:213], v[194:197], v[0:3]
	v_mfma_f32_16x16x32_bf16 v[52:55], v[206:209], v[174:177], v[52:55]
	v_mfma_f32_16x16x32_bf16 v[48:51], v[214:217], v[174:177], v[48:51]
	v_mfma_f32_16x16x32_bf16 v[36:39], v[206:209], v[182:185], v[36:39]
	v_mfma_f32_16x16x32_bf16 v[32:35], v[214:217], v[182:185], v[32:35]
	v_mfma_f32_16x16x32_bf16 v[20:23], v[206:209], v[190:193], v[20:23]
	v_mfma_f32_16x16x32_bf16 v[16:19], v[214:217], v[190:193], v[16:19]
	v_mfma_f32_16x16x32_bf16 v[4:7], v[206:209], v[198:201], v[4:7]
	v_mfma_f32_16x16x32_bf16 v[0:3], v[214:217], v[198:201], v[0:3]
	s_waitcnt lgkmcnt(0)
	s_add_i32 s66, s66, 2
	s_add_u32 s64, s64, 0x100
	s_addc_u32 s65, s65, 0
	s_add_u32 s44, s44, 0x100
	s_addc_u32 s45, s45, 0
	s_cmp_gt_u32 s66, 29
	s_barrier
	s_cbranch_scc0 .LBB0_1668
	v_lshl_add_u32 v146, s42, 8, v150
	v_ashrrev_i32_e32 v147, 31, v146
	v_lshl_add_u64 v[144:145], v[146:147], 2, s[10:11]
	global_load_dword v157, v[144:145], off
	global_load_dword v162, v[144:145], off offset:64
	v_lshlrev_b64 v[160:161], 14, v[146:147]
	global_load_dword v166, v[144:145], off offset:128
	global_load_dword v167, v[144:145], off offset:192
	global_load_dword v168, v[144:145], off offset:512
	global_load_dword v169, v[144:145], off offset:576
	global_load_dword v170, v[144:145], off offset:640
	global_load_dword v147, v[144:145], off offset:704
	v_lshl_or_b32 v148, s61, 8, v152
	v_ashrrev_i32_e32 v149, 31, v148
	v_lshl_add_u64 v[148:149], v[148:149], 1, s[8:9]
	v_lshl_add_u64 v[144:145], v[148:149], 0, v[160:161]
	v_or_b32_e32 v158, 16, v146
	v_ashrrev_i32_e32 v159, 31, v158
	v_lshlrev_b64 v[158:159], 14, v[158:159]
	v_lshl_add_u64 v[158:159], v[148:149], 0, v[158:159]
	s_mov_b32 s61, s34
	s_mov_b32 s42, s36
	s_mov_b64 s[44:45], s[40:41]
	s_mov_b64 s[46:47], s[38:39]
	s_waitcnt vmcnt(0)
	v_cvt_f32_u32_e32 v157, v157
	v_cvt_f32_u32_e32 v161, v162
	v_mul_f32_e32 v157, 0x3b800000, v157
	v_fmamk_f32 v157, v157, 0x3a000000, v156
	v_rsq_f32_e32 v160, v157
	v_mul_f32_e32 v157, 0x3b800000, v161
	v_fmamk_f32 v157, v157, 0x3a000000, v156
	v_rsq_f32_e32 v162, v157
	v_pk_mul_f32 v[126:127], v[126:127], v[160:161] op_sel_hi:[1,0]
	v_pk_mul_f32 v[124:125], v[124:125], v[160:161] op_sel_hi:[1,0]
	v_pk_mul_f32 v[122:123], v[122:123], v[160:161] op_sel_hi:[1,0]
	v_pk_mul_f32 v[120:121], v[120:121], v[160:161] op_sel_hi:[1,0]
	v_pk_mul_f32 v[110:111], v[110:111], v[160:161] op_sel_hi:[1,0]
	v_pk_mul_f32 v[108:109], v[108:109], v[160:161] op_sel_hi:[1,0]
	v_pk_mul_f32 v[106:107], v[106:107], v[160:161] op_sel_hi:[1,0]
	v_pk_mul_f32 v[104:105], v[104:105], v[160:161] op_sel_hi:[1,0]
	v_pk_mul_f32 v[118:119], v[118:119], v[162:163] op_sel_hi:[1,0]
	v_pk_mul_f32 v[116:117], v[116:117], v[162:163] op_sel_hi:[1,0]
	v_pk_mul_f32 v[114:115], v[114:115], v[162:163] op_sel_hi:[1,0]
	v_pk_mul_f32 v[112:113], v[112:113], v[162:163] op_sel_hi:[1,0]
	v_pk_mul_f32 v[160:161], v[102:103], v[162:163] op_sel_hi:[1,0]
	v_pk_mul_f32 v[100:101], v[100:101], v[162:163] op_sel_hi:[1,0]
	v_pk_mul_f32 v[164:165], v[98:99], v[162:163] op_sel_hi:[1,0]
	v_pk_mul_f32 v[162:163], v[96:97], v[162:163] op_sel_hi:[1,0]
	v_max_f32_e32 v96, 0, v124
	v_max_f32_e32 v98, 0, v120
	v_max_f32_e32 v97, 0, v125
	v_max_f32_e32 v99, 0, v121
	v_max_f32_e32 v102, 0, v126
	v_max_f32_e32 v120, 0, v122
	v_max_f32_e32 v103, 0, v127
	v_max_f32_e32 v121, 0, v123
	v_max_f32_e32 v108, 0, v108
	v_max_f32_e32 v109, 0, v109
	v_max_f32_e32 v110, 0, v110
	v_max_f32_e32 v111, 0, v111
	v_max_f32_e32 v104, 0, v104
	v_max_f32_e32 v105, 0, v105
	v_max_f32_e32 v106, 0, v106
	v_max_f32_e32 v107, 0, v107
	v_max_f32_e32 v116, 0, v116
	v_max_f32_e32 v112, 0, v112
	v_max_f32_e32 v117, 0, v117
	v_max_f32_e32 v113, 0, v113
	v_max_f32_e32 v118, 0, v118
	v_max_f32_e32 v114, 0, v114
	v_max_f32_e32 v119, 0, v119
	v_max_f32_e32 v115, 0, v115
	v_max_f32_e32 v122, 0, v100
	v_max_f32_e32 v123, 0, v101
	v_pk_mul_f32 v[96:97], v[96:97], v[96:97]
	v_pk_mul_f32 v[98:99], v[98:99], v[98:99]
	v_pk_mul_f32 v[100:101], v[102:103], v[102:103]
	v_pk_mul_f32 v[102:103], v[120:121], v[120:121]
	v_pk_mul_f32 v[108:109], v[108:109], v[108:109]
	v_pk_mul_f32 v[110:111], v[110:111], v[110:111]
	v_pk_mul_f32 v[104:105], v[104:105], v[104:105]
	v_pk_mul_f32 v[106:107], v[106:107], v[106:107]
	v_pk_mul_f32 v[116:117], v[116:117], v[116:117]
	v_pk_mul_f32 v[112:113], v[112:113], v[112:113]
	v_pk_mul_f32 v[118:119], v[118:119], v[118:119]
	v_pk_mul_f32 v[114:115], v[114:115], v[114:115]
	v_cvt_pk_bf16_f32 v96, v96, v97
	v_cvt_pk_bf16_f32 v97, v100, v101
	v_cvt_pk_bf16_f32 v98, v98, v99
	v_cvt_pk_bf16_f32 v99, v102, v103
	v_cvt_pk_bf16_f32 v100, v108, v109
	v_cvt_pk_bf16_f32 v101, v110, v111
	v_cvt_pk_bf16_f32 v102, v104, v105
	v_cvt_pk_bf16_f32 v103, v106, v107
; __device__ __forceinline__ float fast_sigmoid(float x) { return __builtin_amdgcn_rcpf(1.0f + __builtin_amdgcn_exp2f(-x * LOG2E)); }
; __device__ __forceinline__ float ss_fix(float raw) { return (float)__float_as_uint(raw) * (1.0f / 256.0f); }
;     __device__ __forceinline__ const CAS char* base() const { const CAS char* ka = (const CAS char*)__builtin_amdgcn_kernarg_segment_ptr(); asm volatile("" : "+s"(ka)); return ka; }
;     __device__ __forceinline__ void operator()(const f32x4 (&acc)[2][2][4][2], const Unit& u, int wr, int wc, int fr, int fq) const {
;     ...
; #pragma unroll
;         for (int ai = 0; ai < 2; ++ai)
; #pragma unroll
;             for (int m = 0; m < 4; ++m) { const int row = row0 + ai * HALF + m * 16; float rs = 1.0f; if (SM == 1) rs = __builtin_amdgcn_rsqf(ss_fix(rsv[ai * 4 + m]) * (1.0f / DM) + EPS);
;                 bf16_t* rowp = base + (size_t)row * ldc + col0;
; #pragma unroll
;                 for (int bj = 0; bj < 2; ++bj) { f32x4 v0 = acc[ai][bj][m][0], v1 = acc[ai][bj][m][1];
;                     if (SM == 1) { v0 *= rs; v1 *= rs; }
;                     if (SM == 2) { v0 *= cs[bj][0]; v1 *= cs[bj][1]; }
;                     if (ACT == 1) {
; #pragma unroll
;                         for (int j = 0; j < 4; ++j) { const float a = fmaxf(v0[j], 0.f), b = fmaxf(v1[j], 0.f); v0[j] = a * a; v1[j] = b * b; } }
;                     if (ACT == 2) { if (tsel == 0) {
; #pragma unroll
;                         for (int j = 0; j < 4; ++j) { const float a = v0[j], b = v1[j];
;                             v0[j] = a * fast_sigmoid(1.5957691216057308f * (a + 0.044715f * a * a * a)); v1[j] = b * fast_sigmoid(1.5957691216057308f * (b + 0.044715f * b * b * b)); } } }
;                     u32x4 w; w.x = pk_bf16(v0[0], v0[1]); w.y = pk_bf16(v0[2], v0[3]); w.z = pk_bf16(v1[0], v1[1]); w.w = pk_bf16(v1[2], v1[3]);
;                     *(u32x4*)(rowp + bj * HALF) = w; } }
	v_cvt_pk_bf16_f32 v104, v116, v117
	v_cvt_pk_bf16_f32 v105, v118, v119
	v_cvt_pk_bf16_f32 v106, v112, v113
	v_cvt_pk_bf16_f32 v107, v114, v115
	global_store_dwordx4 v[144:145], v[96:99], off
	global_store_dwordx4 v[144:145], v[100:103], off offset:256
	global_store_dwordx4 v[158:159], v[104:107], off
	v_pk_mul_f32 v[96:97], v[122:123], v[122:123]
	v_max_f32_e32 v100, 0, v160
	v_max_f32_e32 v101, 0, v161
	v_pk_mul_f32 v[100:101], v[100:101], v[100:101]
	v_cvt_pk_bf16_f32 v96, v96, v97
	v_cvt_pk_bf16_f32 v97, v100, v101
	v_cvt_f32_u32_e32 v100, v166
	v_max_f32_e32 v124, 0, v162
	v_max_f32_e32 v125, 0, v163
	v_max_f32_e32 v102, 0, v164
	v_max_f32_e32 v103, 0, v165
	v_pk_mul_f32 v[98:99], v[124:125], v[124:125]
	v_pk_mul_f32 v[102:103], v[102:103], v[102:103]
	v_cvt_pk_bf16_f32 v98, v98, v99
	v_cvt_pk_bf16_f32 v99, v102, v103
	global_store_dwordx4 v[158:159], v[96:99], off offset:256
	s_nop 1
	v_mul_f32_e32 v97, 0x3b800000, v100
	v_fmamk_f32 v97, v97, 0x3a000000, v156
	v_rsq_f32_e32 v98, v97
	v_or_b32_e32 v96, 32, v146
	v_ashrrev_i32_e32 v97, 31, v96
	v_lshlrev_b64 v[96:97], 14, v[96:97]
	v_pk_mul_f32 v[88:89], v[88:89], v[98:99] op_sel_hi:[1,0]
	v_pk_mul_f32 v[94:95], v[94:95], v[98:99] op_sel_hi:[1,0]
	v_pk_mul_f32 v[92:93], v[92:93], v[98:99] op_sel_hi:[1,0]
	v_pk_mul_f32 v[90:91], v[90:91], v[98:99] op_sel_hi:[1,0]
	v_max_f32_e32 v88, 0, v88
	v_max_f32_e32 v89, 0, v89
	v_max_f32_e32 v92, 0, v92
	v_max_f32_e32 v93, 0, v93
	v_pk_mul_f32 v[100:101], v[88:89], v[88:89]
	v_max_f32_e32 v88, 0, v94
	v_max_f32_e32 v90, 0, v90
	v_max_f32_e32 v89, 0, v95
	v_max_f32_e32 v91, 0, v91
	v_pk_mul_f32 v[92:93], v[92:93], v[92:93]
	v_pk_mul_f32 v[94:95], v[88:89], v[88:89]
	v_pk_mul_f32 v[102:103], v[90:91], v[90:91]
	v_pk_mul_f32 v[84:85], v[84:85], v[98:99] op_sel_hi:[1,0]
	v_pk_mul_f32 v[80:81], v[80:81], v[98:99] op_sel_hi:[1,0]
	v_lshl_add_u64 v[96:97], v[148:149], 0, v[96:97]
	v_cvt_pk_bf16_f32 v88, v92, v93
	v_cvt_pk_bf16_f32 v89, v94, v95
	v_cvt_pk_bf16_f32 v90, v100, v101
	v_cvt_pk_bf16_f32 v91, v102, v103
	v_pk_mul_f32 v[86:87], v[86:87], v[98:99] op_sel_hi:[1,0]
	v_max_f32_e32 v84, 0, v84
	v_max_f32_e32 v80, 0, v80
	v_max_f32_e32 v85, 0, v85
	v_max_f32_e32 v81, 0, v81
	global_store_dwordx4 v[96:97], v[88:91], off
	v_pk_mul_f32 v[84:85], v[84:85], v[84:85]
	v_pk_mul_f32 v[82:83], v[82:83], v[98:99] op_sel_hi:[1,0]
	v_pk_mul_f32 v[88:89], v[80:81], v[80:81]
	v_max_f32_e32 v80, 0, v86
	v_max_f32_e32 v81, 0, v87
	v_pk_mul_f32 v[86:87], v[80:81], v[80:81]
	v_cvt_pk_bf16_f32 v80, v84, v85
	v_cvt_f32_u32_e32 v84, v167
	v_max_f32_e32 v82, 0, v82
	v_max_f32_e32 v83, 0, v83
	v_pk_mul_f32 v[90:91], v[82:83], v[82:83]
	v_cvt_pk_bf16_f32 v81, v86, v87
	v_cvt_pk_bf16_f32 v82, v88, v89
	v_cvt_pk_bf16_f32 v83, v90, v91
	global_store_dwordx4 v[96:97], v[80:83], off offset:256
	s_nop 1
	v_mul_f32_e32 v81, 0x3b800000, v84
	v_fmamk_f32 v81, v81, 0x3a000000, v156
	v_rsq_f32_e32 v82, v81
	v_or_b32_e32 v80, 48, v146
	v_ashrrev_i32_e32 v81, 31, v80
	v_lshlrev_b64 v[80:81], 14, v[80:81]
	v_pk_mul_f32 v[72:73], v[72:73], v[82:83] op_sel_hi:[1,0]
	v_pk_mul_f32 v[78:79], v[78:79], v[82:83] op_sel_hi:[1,0]
	v_pk_mul_f32 v[76:77], v[76:77], v[82:83] op_sel_hi:[1,0]
	v_pk_mul_f32 v[74:75], v[74:75], v[82:83] op_sel_hi:[1,0]
	v_max_f32_e32 v72, 0, v72
	v_max_f32_e32 v73, 0, v73
	v_max_f32_e32 v76, 0, v76
	v_max_f32_e32 v77, 0, v77
	v_pk_mul_f32 v[84:85], v[72:73], v[72:73]
	v_max_f32_e32 v72, 0, v78
	v_max_f32_e32 v74, 0, v74
	v_max_f32_e32 v73, 0, v79
	v_max_f32_e32 v75, 0, v75
	v_pk_mul_f32 v[76:77], v[76:77], v[76:77]
	v_pk_mul_f32 v[78:79], v[72:73], v[72:73]
	v_pk_mul_f32 v[86:87], v[74:75], v[74:75]
	v_pk_mul_f32 v[66:67], v[66:67], v[82:83] op_sel_hi:[1,0]
	v_lshl_add_u64 v[80:81], v[148:149], 0, v[80:81]
	v_cvt_pk_bf16_f32 v72, v76, v77
	v_cvt_pk_bf16_f32 v73, v78, v79
	v_cvt_pk_bf16_f32 v74, v84, v85
	v_cvt_pk_bf16_f32 v75, v86, v87
	v_max_f32_e32 v66, 0, v66
	v_max_f32_e32 v67, 0, v67
	global_store_dwordx4 v[80:81], v[72:75], off
	v_pk_mul_f32 v[68:69], v[68:69], v[82:83] op_sel_hi:[1,0]
	v_pk_mul_f32 v[64:65], v[64:65], v[82:83] op_sel_hi:[1,0]
	v_pk_mul_f32 v[74:75], v[66:67], v[66:67]
	v_cvt_f32_u32_e32 v67, v168
	v_pk_mul_f32 v[70:71], v[70:71], v[82:83] op_sel_hi:[1,0]
	v_max_f32_e32 v68, 0, v68
	v_max_f32_e32 v64, 0, v64
	v_max_f32_e32 v69, 0, v69
	v_max_f32_e32 v65, 0, v65
	v_mul_f32_e32 v67, 0x3b800000, v67
	v_pk_mul_f32 v[68:69], v[68:69], v[68:69]
	v_pk_mul_f32 v[72:73], v[64:65], v[64:65]
	v_max_f32_e32 v64, 0, v70
	v_max_f32_e32 v65, 0, v71
	v_fmamk_f32 v67, v67, 0x3a000000, v156
	v_pk_mul_f32 v[70:71], v[64:65], v[64:65]
	v_cvt_pk_bf16_f32 v64, v68, v69
	v_rsq_f32_e32 v68, v67
	v_cvt_pk_bf16_f32 v65, v70, v71
	v_cvt_pk_bf16_f32 v66, v72, v73
	v_cvt_pk_bf16_f32 v67, v74, v75
	v_pk_mul_f32 v[60:61], v[60:61], v[68:69] op_sel_hi:[1,0]
	v_pk_mul_f32 v[56:57], v[56:57], v[68:69] op_sel_hi:[1,0]
	v_pk_mul_f32 v[62:63], v[62:63], v[68:69] op_sel_hi:[1,0]
	v_pk_mul_f32 v[58:59], v[58:59], v[68:69] op_sel_hi:[1,0]
	v_max_f32_e32 v60, 0, v60
	v_max_f32_e32 v56, 0, v56
	v_max_f32_e32 v61, 0, v61
	v_max_f32_e32 v57, 0, v57
	global_store_dwordx4 v[80:81], v[64:67], off offset:256
	v_pk_mul_f32 v[60:61], v[60:61], v[60:61]
	v_max_f32_e32 v58, 0, v58
	v_pk_mul_f32 v[66:67], v[56:57], v[56:57]
	v_max_f32_e32 v56, 0, v62
	v_max_f32_e32 v57, 0, v63
	v_max_f32_e32 v59, 0, v59
	v_pk_mul_f32 v[62:63], v[56:57], v[56:57]
	v_pk_mul_f32 v[70:71], v[58:59], v[58:59]
	v_cvt_pk_bf16_f32 v56, v60, v61
	v_add_co_u32_e32 v60, vcc, s57, v144
	v_pk_mul_f32 v[50:51], v[50:51], v[68:69] op_sel_hi:[1,0]
	v_cvt_pk_bf16_f32 v57, v62, v63
	v_cvt_pk_bf16_f32 v58, v66, v67
; __device__ __forceinline__ float fast_sigmoid(float x) { return __builtin_amdgcn_rcpf(1.0f + __builtin_amdgcn_exp2f(-x * LOG2E)); }
; __device__ __forceinline__ float ss_fix(float raw) { return (float)__float_as_uint(raw) * (1.0f / 256.0f); }
;     __device__ __forceinline__ const CAS char* base() const { const CAS char* ka = (const CAS char*)__builtin_amdgcn_kernarg_segment_ptr(); asm volatile("" : "+s"(ka)); return ka; }
;     __device__ __forceinline__ void operator()(const f32x4 (&acc)[2][2][4][2], const Unit& u, int wr, int wc, int fr, int fq) const {
;     ...
; #pragma unroll
;         for (int ai = 0; ai < 2; ++ai)
; #pragma unroll
;             for (int m = 0; m < 4; ++m) { const int row = row0 + ai * HALF + m * 16; float rs = 1.0f; if (SM == 1) rs = __builtin_amdgcn_rsqf(ss_fix(rsv[ai * 4 + m]) * (1.0f / DM) + EPS);
;                 bf16_t* rowp = base + (size_t)row * ldc + col0;
; #pragma unroll
;                 for (int bj = 0; bj < 2; ++bj) { f32x4 v0 = acc[ai][bj][m][0], v1 = acc[ai][bj][m][1];
;                     if (SM == 1) { v0 *= rs; v1 *= rs; }
;                     if (SM == 2) { v0 *= cs[bj][0]; v1 *= cs[bj][1]; }
;                     if (ACT == 1) {
; #pragma unroll
;                         for (int j = 0; j < 4; ++j) { const float a = fmaxf(v0[j], 0.f), b = fmaxf(v1[j], 0.f); v0[j] = a * a; v1[j] = b * b; } }
;                     if (ACT == 2) { if (tsel == 0) {
; #pragma unroll
;                         for (int j = 0; j < 4; ++j) { const float a = v0[j], b = v1[j];
;                             v0[j] = a * fast_sigmoid(1.5957691216057308f * (a + 0.044715f * a * a * a)); v1[j] = b * fast_sigmoid(1.5957691216057308f * (b + 0.044715f * b * b * b)); } } }
;                     u32x4 w; w.x = pk_bf16(v0[0], v0[1]); w.y = pk_bf16(v0[2], v0[3]); w.z = pk_bf16(v1[0], v1[1]); w.w = pk_bf16(v1[2], v1[3]);
;                     *(u32x4*)(rowp + bj * HALF) = w; } }
	v_cvt_pk_bf16_f32 v59, v70, v71
	v_addc_co_u32_e32 v61, vcc, 0, v145, vcc
	v_max_f32_e32 v50, 0, v50
	v_max_f32_e32 v51, 0, v51
	global_store_dwordx4 v[60:61], v[56:59], off
	v_pk_mul_f32 v[52:53], v[52:53], v[68:69] op_sel_hi:[1,0]
	v_pk_mul_f32 v[48:49], v[48:49], v[68:69] op_sel_hi:[1,0]
	v_pk_mul_f32 v[58:59], v[50:51], v[50:51]
	v_cvt_f32_u32_e32 v51, v169
	v_pk_mul_f32 v[54:55], v[54:55], v[68:69] op_sel_hi:[1,0]
	v_max_f32_e32 v52, 0, v52
	v_max_f32_e32 v48, 0, v48
	v_max_f32_e32 v53, 0, v53
	v_max_f32_e32 v49, 0, v49
	v_mul_f32_e32 v51, 0x3b800000, v51
	v_pk_mul_f32 v[52:53], v[52:53], v[52:53]
	v_pk_mul_f32 v[56:57], v[48:49], v[48:49]
	v_max_f32_e32 v48, 0, v54
	v_max_f32_e32 v49, 0, v55
	v_fmamk_f32 v51, v51, 0x3a000000, v156
	v_pk_mul_f32 v[54:55], v[48:49], v[48:49]
	v_cvt_pk_bf16_f32 v48, v52, v53
	v_rsq_f32_e32 v52, v51
	v_lshl_add_u64 v[64:65], v[144:145], 0, s[14:15]
	v_cvt_pk_bf16_f32 v49, v54, v55
	v_cvt_pk_bf16_f32 v50, v56, v57
	v_pk_mul_f32 v[44:45], v[44:45], v[52:53] op_sel_hi:[1,0]
	v_pk_mul_f32 v[40:41], v[40:41], v[52:53] op_sel_hi:[1,0]
	v_cvt_pk_bf16_f32 v51, v58, v59
	v_pk_mul_f32 v[46:47], v[46:47], v[52:53] op_sel_hi:[1,0]
	v_pk_mul_f32 v[42:43], v[42:43], v[52:53] op_sel_hi:[1,0]
	v_max_f32_e32 v44, 0, v44
	v_max_f32_e32 v40, 0, v40
	v_max_f32_e32 v45, 0, v45
	v_max_f32_e32 v41, 0, v41
	global_store_dwordx4 v[64:65], v[48:51], off offset:256
	v_pk_mul_f32 v[44:45], v[44:45], v[44:45]
	v_max_f32_e32 v42, 0, v42
	v_pk_mul_f32 v[50:51], v[40:41], v[40:41]
	v_max_f32_e32 v40, 0, v46
	v_max_f32_e32 v41, 0, v47
	v_max_f32_e32 v43, 0, v43
	v_pk_mul_f32 v[46:47], v[40:41], v[40:41]
	v_pk_mul_f32 v[54:55], v[42:43], v[42:43]
	v_cvt_pk_bf16_f32 v40, v44, v45
	v_add_co_u32_e32 v44, vcc, s58, v144
	v_pk_mul_f32 v[34:35], v[34:35], v[52:53] op_sel_hi:[1,0]
	v_cvt_pk_bf16_f32 v41, v46, v47
	v_cvt_pk_bf16_f32 v42, v50, v51
	v_cvt_pk_bf16_f32 v43, v54, v55
	v_addc_co_u32_e32 v45, vcc, 0, v145, vcc
	v_max_f32_e32 v34, 0, v34
	v_max_f32_e32 v35, 0, v35
	global_store_dwordx4 v[44:45], v[40:43], off
	v_pk_mul_f32 v[36:37], v[36:37], v[52:53] op_sel_hi:[1,0]
	v_pk_mul_f32 v[32:33], v[32:33], v[52:53] op_sel_hi:[1,0]
	v_pk_mul_f32 v[42:43], v[34:35], v[34:35]
	v_cvt_f32_u32_e32 v35, v170
	v_pk_mul_f32 v[38:39], v[38:39], v[52:53] op_sel_hi:[1,0]
	v_max_f32_e32 v36, 0, v36
	v_max_f32_e32 v32, 0, v32
	v_max_f32_e32 v37, 0, v37
	v_max_f32_e32 v33, 0, v33
	v_mul_f32_e32 v35, 0x3b800000, v35
	v_pk_mul_f32 v[36:37], v[36:37], v[36:37]
	v_pk_mul_f32 v[40:41], v[32:33], v[32:33]
	v_max_f32_e32 v32, 0, v38
	v_max_f32_e32 v33, 0, v39
	v_fmamk_f32 v35, v35, 0x3a000000, v156
	v_pk_mul_f32 v[38:39], v[32:33], v[32:33]
	v_cvt_pk_bf16_f32 v32, v36, v37
	v_rsq_f32_e32 v36, v35
	v_lshl_add_u64 v[48:49], v[144:145], 0, s[16:17]
	v_cvt_pk_bf16_f32 v33, v38, v39
	v_cvt_pk_bf16_f32 v34, v40, v41
	v_pk_mul_f32 v[28:29], v[28:29], v[36:37] op_sel_hi:[1,0]
	v_pk_mul_f32 v[24:25], v[24:25], v[36:37] op_sel_hi:[1,0]
	v_cvt_pk_bf16_f32 v35, v42, v43
	v_pk_mul_f32 v[30:31], v[30:31], v[36:37] op_sel_hi:[1,0]
	v_pk_mul_f32 v[26:27], v[26:27], v[36:37] op_sel_hi:[1,0]
	v_max_f32_e32 v28, 0, v28
	v_max_f32_e32 v24, 0, v24
	v_max_f32_e32 v29, 0, v29
	v_max_f32_e32 v25, 0, v25
	global_store_dwordx4 v[48:49], v[32:35], off offset:256
	v_pk_mul_f32 v[28:29], v[28:29], v[28:29]
	v_max_f32_e32 v26, 0, v26
	v_pk_mul_f32 v[34:35], v[24:25], v[24:25]
	v_max_f32_e32 v24, 0, v30
	v_max_f32_e32 v25, 0, v31
	v_max_f32_e32 v27, 0, v27
	v_pk_mul_f32 v[30:31], v[24:25], v[24:25]
	v_pk_mul_f32 v[38:39], v[26:27], v[26:27]
	v_cvt_pk_bf16_f32 v24, v28, v29
	v_add_co_u32_e32 v28, vcc, s59, v144
	v_pk_mul_f32 v[18:19], v[18:19], v[36:37] op_sel_hi:[1,0]
	v_cvt_pk_bf16_f32 v25, v30, v31
	v_cvt_pk_bf16_f32 v26, v34, v35
	v_cvt_pk_bf16_f32 v27, v38, v39
	v_addc_co_u32_e32 v29, vcc, 0, v145, vcc
	v_max_f32_e32 v18, 0, v18
	v_max_f32_e32 v19, 0, v19
	global_store_dwordx4 v[28:29], v[24:27], off
	v_pk_mul_f32 v[20:21], v[20:21], v[36:37] op_sel_hi:[1,0]
	v_pk_mul_f32 v[16:17], v[16:17], v[36:37] op_sel_hi:[1,0]
	v_pk_mul_f32 v[26:27], v[18:19], v[18:19]
	v_cvt_f32_u32_e32 v19, v147
	v_pk_mul_f32 v[22:23], v[22:23], v[36:37] op_sel_hi:[1,0]
	v_max_f32_e32 v20, 0, v20
	v_max_f32_e32 v16, 0, v16
	v_max_f32_e32 v21, 0, v21
	v_max_f32_e32 v17, 0, v17
	v_mul_f32_e32 v19, 0x3b800000, v19
	v_pk_mul_f32 v[20:21], v[20:21], v[20:21]
	v_pk_mul_f32 v[24:25], v[16:17], v[16:17]
	v_max_f32_e32 v16, 0, v22
	v_max_f32_e32 v17, 0, v23
	v_fmamk_f32 v19, v19, 0x3a000000, v156
	v_pk_mul_f32 v[22:23], v[16:17], v[16:17]
	v_cvt_pk_bf16_f32 v16, v20, v21
	v_rsq_f32_e32 v20, v19
	v_lshl_add_u64 v[32:33], v[144:145], 0, s[18:19]
	v_cvt_pk_bf16_f32 v17, v22, v23
	v_cvt_pk_bf16_f32 v18, v24, v25
	v_pk_mul_f32 v[12:13], v[12:13], v[20:21] op_sel_hi:[1,0]
	v_pk_mul_f32 v[8:9], v[8:9], v[20:21] op_sel_hi:[1,0]
	v_cvt_pk_bf16_f32 v19, v26, v27
	v_pk_mul_f32 v[14:15], v[14:15], v[20:21] op_sel_hi:[1,0]
	v_pk_mul_f32 v[10:11], v[10:11], v[20:21] op_sel_hi:[1,0]
	v_max_f32_e32 v12, 0, v12
	v_max_f32_e32 v8, 0, v8
	v_max_f32_e32 v13, 0, v13
	v_max_f32_e32 v9, 0, v9
	global_store_dwordx4 v[32:33], v[16:19], off offset:256
	v_pk_mul_f32 v[12:13], v[12:13], v[12:13]
	v_max_f32_e32 v10, 0, v10
	v_pk_mul_f32 v[18:19], v[8:9], v[8:9]
	v_max_f32_e32 v8, 0, v14
	v_max_f32_e32 v9, 0, v15
	v_max_f32_e32 v11, 0, v11
	v_pk_mul_f32 v[14:15], v[8:9], v[8:9]
	v_pk_mul_f32 v[22:23], v[10:11], v[10:11]
	v_cvt_pk_bf16_f32 v8, v12, v13
	v_add_co_u32_e32 v12, vcc, s60, v144
	v_pk_mul_f32 v[0:1], v[0:1], v[20:21] op_sel_hi:[1,0]
	v_cvt_pk_bf16_f32 v9, v14, v15
	v_cvt_pk_bf16_f32 v10, v18, v19
	v_cvt_pk_bf16_f32 v11, v22, v23
	v_addc_co_u32_e32 v13, vcc, 0, v145, vcc
	v_pk_mul_f32 v[6:7], v[6:7], v[20:21] op_sel_hi:[1,0]
	v_pk_mul_f32 v[4:5], v[4:5], v[20:21] op_sel_hi:[1,0]
	v_pk_mul_f32 v[2:3], v[2:3], v[20:21] op_sel_hi:[1,0]
	v_max_f32_e32 v0, 0, v0
	v_max_f32_e32 v1, 0, v1
	global_store_dwordx4 v[12:13], v[8:11], off
	v_max_f32_e32 v4, 0, v4
	v_max_f32_e32 v5, 0, v5
	v_pk_mul_f32 v[8:9], v[0:1], v[0:1]
	v_max_f32_e32 v0, 0, v6
	v_max_f32_e32 v2, 0, v2
	v_max_f32_e32 v1, 0, v7
	v_max_f32_e32 v3, 0, v3
	v_pk_mul_f32 v[4:5], v[4:5], v[4:5]
	v_pk_mul_f32 v[6:7], v[0:1], v[0:1]
	v_pk_mul_f32 v[10:11], v[2:3], v[2:3]
	v_lshl_add_u64 v[16:17], v[144:145], 0, s[30:31]
	v_cvt_pk_bf16_f32 v0, v4, v5
	v_cvt_pk_bf16_f32 v1, v6, v7
	v_cvt_pk_bf16_f32 v2, v8, v9
	v_cvt_pk_bf16_f32 v3, v10, v11
	s_and_b64 vcc, exec, s[6:7]
	global_store_dwordx4 v[16:17], v[0:3], off offset:256
	s_cbranch_vccz .LBB0_1661
	s_waitcnt vmcnt(0)
	s_cmpk_gt_u32 s4, 0xff
	s_cbranch_scc1 .LBB0_1672
	s_barrier

; __device__ __forceinline__ int opaque_tid(int wv) { int l; asm volatile("v_mbcnt_lo_u32_b32 %0, -1, 0\n\tv_mbcnt_hi_u32_b32 %0, -1, %0" : "=v"(l)); return wv * 64 + l; }
; #define PG8_BAR __builtin_amdgcn_s_barrier()
; template <class Epi>
; __device__ __forceinline__ void gemm_phase(LAS unsigned char* lds, const Gemm g, const StaticOrder& S, const Epi& E, int wv) {
;     const int tid = opaque_tid(wv), wid = __builtin_amdgcn_readfirstlane(tid >> 6), lane = tid & 63, wr = wid >> 2, wc = wid & 3, fr = lane & 15, fq = lane >> 4;
;     const int K = g.K, nt = K / BK;
;     unsigned voffA[2], voffB[2];
; #pragma unroll
;     for (int i = 0; i < 2; ++i) { int R, C; stage_rc(tid * 16 + i * 8192, R, C); const int Rb = Epi::PERM ? ((R & ~31) + perm32(R & 31)) : R;
;         voffA[i] = (unsigned)(R * g.lda + C) * 2u; voffB[i] = (unsigned)(Rb * g.ldb + C) * 2u; }
;     const bool krev = (g.adiag & 2) != 0;
;     const ptrdiff_t kstep = krev ? -(ptrdiff_t)(BK * 2) : (ptrdiff_t)(BK * 2);
;     const size_t kbeg = krev ? (size_t)(nt - 1) * (BK * 2) : 0;
;     const size_t hstepA = (size_t)HALF * g.lda * 2, hstepB = (size_t)HALF * g.ldb * 2;
;     const size_t tstepA = 2 * hstepA, tstepB = 2 * hstepB;
;     const unsigned ldsw = (unsigned)wid * 1024u;
;     const int aoff = lds_byte(wr * 64 + fr, fq * 8), boff = lds_byte(wc * 32 + fr, fq * 8);
;     ...
;     Unit cur, nxt; int ui = 0;
;     if (!S.next(0, cur)) return;
;     f32x4 acc[2][2][4][2];
; #pragma unroll
;     for (int a = 0; a < 2; ++a)
; #pragma unroll
;         for (int b = 0; b < 2; ++b)
; #pragma unroll
;             for (int m = 0; m < 4; ++m)
; #pragma unroll
;                 for (int n = 0; n < 2; ++n) acc[a][b][m][n] = (f32x4){0.f, 0.f, 0.f, 0.f};
;     bf16x8 At[4][2], B0[2][2], B1[2][2];
;     const char* cA = (const char*)g.A + (size_t)cur.pm * tstepA + ((g.adiag & 1) ? (size_t)(cur.pn >> 1) * K * 2 : 0) + kbeg;
;     const char* cB = (const char*)g.Bt + (size_t)cur.pn * tstepB + kbeg;
;     PG8_STAGE(PG8_SB(0, 0), cB, voffB); PG8_STAGE(PG8_SA(0, 0), cA, voffA); PG8_STAGE(PG8_SB(0, 1), cB + hstepB, voffB); PG8_STAGE(PG8_SA(0, 1), cA + hstepA, voffA);
;     if (wr == 1) PG8_BAR;
;     PG8_WAIT_V(4); PG8_BAR;
;     PG8_STAGE(PG8_SB(1, 0), cB + kstep, voffB); PG8_STAGE(PG8_SA(1, 0), cA + kstep, voffA); PG8_STAGE(PG8_SB(1, 1), cB + hstepB + kstep, voffB);
;     PG8_WAIT_V(6); PG8_BAR;
.LBB0_1731:
	v_readlane_b32 s12, v255, 10
	v_readlane_b32 s13, v255, 11
	s_and_b64 vcc, exec, s[12:13]
	s_cbranch_vccnz .LBB0_1767
	v_ashrrev_i32_e32 v3, 31, v1
	v_lshrrev_b32_e32 v3, 26, v3
	v_lshlrev_b32_e32 v2, 4, v1
	v_add_u32_e32 v3, v1, v3
	v_bfe_i32 v1, v1, 27, 1
	v_lshrrev_b32_e32 v1, 22, v1
	v_add_u32_e32 v1, v2, v1
	v_and_b32_e32 v1, 0xfffffc00, v1
	v_sub_u32_e32 v1, v2, v1
	v_lshrrev_b32_e32 v4, 4, v1
	v_bitop3_b32 v1, v4, v1, 32 bitop3:0x6c
	v_ashrrev_i32_e32 v5, 31, v1
	v_ashrrev_i32_e32 v3, 6, v3
	v_lshrrev_b32_e32 v5, 26, v5
	v_lshlrev_b32_e32 v4, 3, v3
	v_add_u32_e32 v5, v1, v5
	v_and_b32_e32 v4, -16, v4
	v_ashrrev_i32_e32 v6, 6, v5
	v_and_b32_e32 v5, 0xc0, v5
	s_waitcnt lgkmcnt(0)
	s_add_u32 s5, s10, 0xf300000
	v_add_u32_e32 v4, v6, v4
	v_sub_u32_e32 v1, v1, v5
	v_mov_b32_e32 v5, 1
	s_addc_u32 s22, s11, 0
	v_lshlrev_b32_e32 v3, 5, v3
	v_ashrrev_i16_sdwa v1, v5, sext(v1) dst_sel:DWORD dst_unused:UNUSED_PAD src0_sel:DWORD src1_sel:BYTE_0
	v_lshlrev_b32_e32 v7, 1, v4
	v_lshrrev_b32_e32 v8, 2, v4
	v_and_b32_e32 v6, 3, v6
	s_mov_b32 s11, 0x3ffe0
	v_and_b32_e32 v3, 32, v3
	v_bfe_i32 v1, v1, 0, 16
	v_and_b32_e32 v7, 24, v7
	v_and_b32_e32 v8, 4, v8
	v_and_or_b32 v6, v4, s11, v6
	v_or3_b32 v6, v6, v8, v7
	v_add_lshl_u32 v1, v3, v1, 1
	v_lshl_add_u32 v144, v4, 14, v1
	v_lshl_add_u32 v146, v6, 14, v1
	v_add_u32_e32 v1, 0x2000, v2
	v_ashrrev_i32_e32 v2, 31, v1
	v_lshrrev_b32_e32 v2, 22, v2
	v_add_u32_e32 v2, v1, v2
	v_ashrrev_i32_e32 v2, 10, v2
	v_mul_i32_i24_e32 v3, 0x400, v2
	v_sub_u32_e32 v1, v1, v3
	v_lshrrev_b32_e32 v3, 4, v1
	v_bitop3_b32 v1, v3, v1, 32 bitop3:0x6c
	v_ashrrev_i32_e32 v4, 31, v1
	s_ashr_i32 s34, s4, 6
	s_ashr_i32 s43, s42, 31
	s_ashr_i32 s10, s4, 8
	v_lshrrev_b32_e32 v4, 26, v4
	s_lshl_b32 s23, s34, 10
	s_lshl_b64 s[12:13], s[42:43], 22
	v_lshlrev_b32_e32 v3, 3, v2
	v_add_u32_e32 v4, v1, v4
	s_add_u32 s30, s5, s12
	v_and_b32_e32 v3, -16, v3
	v_ashrrev_i32_e32 v6, 6, v4
	s_addc_u32 s31, s22, s13
	s_ashr_i32 s45, s44, 31
	v_add_u32_e32 v3, v6, v3
	v_and_b32_e32 v6, 3, v6
	s_lshl_b64 s[12:13], s[44:45], 22
	v_and_or_b32 v6, v3, s11, v6
	s_add_u32 s11, s6, s12
	s_addc_u32 s13, s7, s13
	s_add_u32 s18, s11, 0x4900000
	v_and_b32_e32 v4, 0xc0, v4
	s_addc_u32 s19, s13, 0
	v_sub_u32_e32 v1, v1, v4
	s_add_u32 s46, s11, 0x4903f80
	v_lshlrev_b32_e32 v2, 5, v2
	v_ashrrev_i16_sdwa v1, v5, sext(v1) dst_sel:DWORD dst_unused:UNUSED_PAD src0_sel:DWORD src1_sel:BYTE_0
	v_lshlrev_b32_e32 v4, 1, v3
	v_lshrrev_b32_e32 v5, 2, v3
	s_addc_u32 s47, s13, 0
	s_add_i32 s24, s23, 0
	v_and_b32_e32 v2, 32, v2
	v_bfe_i32 v1, v1, 0, 16
	v_and_b32_e32 v4, 24, v4
	v_and_b32_e32 v5, 4, v5
	s_add_i32 m0, s24, 0x10000
	v_or3_b32 v4, v6, v5, v4
	v_add_lshl_u32 v1, v2, v1, 1
	global_load_lds_dwordx4 v146, s[46:47]
	s_add_i32 m0, s24, 0x12000
	v_lshl_add_u32 v150, v4, 14, v1
	s_add_u32 s48, s30, 0x3f80
	global_load_lds_dwordx4 v150, s[46:47]
	s_addc_u32 s49, s31, 0
	s_mov_b32 m0, s24
	s_add_i32 s25, s24, 0x2000
	v_lshl_add_u32 v148, v3, 14, v1
	global_load_lds_dwordx4 v144, s[48:49]
	s_mov_b32 m0, s25
	s_add_u32 s12, s11, 0x4b03f80
	global_load_lds_dwordx4 v148, s[48:49]
	s_addc_u32 s13, s13, 0
	s_add_i32 m0, s24, 0x14000
	v_mov_b32_e32 v147, 0
	global_load_lds_dwordx4 v146, s[12:13]
	s_add_i32 m0, s24, 0x16000
	s_mov_b32 s11, 0
	global_load_lds_dwordx4 v150, s[12:13]
	s_add_u32 s12, s30, 0x203f80
	s_addc_u32 s13, s31, 0
	s_add_i32 s33, s24, 0x4000
	s_mov_b32 m0, s33
	s_add_i32 s45, s24, 0x6000
	global_load_lds_dwordx4 v144, s[12:13]
	s_mov_b32 m0, s45
	v_mov_b32_e32 v151, v147
	global_load_lds_dwordx4 v148, s[12:13]
	v_mov_b32_e32 v145, v147
	s_cmp_lg_u32 s10, 1
	v_mov_b32_e32 v149, v147
	s_cbranch_scc1 .LBB0_1734
	s_barrier
	s_setprio 1

; #define PG8_STAGE(bufoff, gbase, voff) do { _Pragma("unroll") for (int _i = 0; _i < 2; ++_i) \
;         __builtin_amdgcn_global_load_lds((const unsigned*)((const char*)(gbase) + (voff)[_i]), (LAS unsigned*)(lds + (bufoff) + ldsw + _i * 8192), 16, 0, 0); } while (0)
; #define PG8_LDA(dst, b, h) do { _Pragma("unroll") for (int m = 0; m < 4; ++m) _Pragma("unroll") for (int k = 0; k < 2; ++k) dst[m][k] = *(const LAS bf16x8*)(lds + PG8_SA(b, h) + aoff + m * 2048 + k * 1024); } while (0)
; #define PG8_LDB(dst, b, h) do { _Pragma("unroll") for (int n = 0; n < 2; ++n) _Pragma("unroll") for (int k = 0; k < 2; ++k) dst[n][k] = *(const LAS bf16x8*)(lds + PG8_SB(b, h) + boff + n * 2048 + k * 1024); } while (0)
; #define PG8_MMA(ai, bj, At, Bt) do { __builtin_amdgcn_s_setprio(1); _Pragma("unroll") for (int m = 0; m < 4; ++m) _Pragma("unroll") for (int n = 0; n < 2; ++n) _Pragma("unroll") for (int k = 0; k < 2; ++k) \
;         acc[ai][bj][m][n] = __builtin_amdgcn_mfma_f32_16x16x32_bf16(Bt[n][k], At[m][k], acc[ai][bj][m][n], 0, 0, 0); __builtin_amdgcn_s_setprio(0); } while (0)
; #define PG8_WAIT_V(n) asm volatile("s_waitcnt vmcnt(" #n ")" ::: "memory")
; #define PG8_WAIT_L(n) asm volatile("s_waitcnt lgkmcnt(" #n ")" ::: "memory")
; #define PG8_BAR __builtin_amdgcn_s_barrier()
; #define PG8_SCHED __builtin_amdgcn_sched_barrier(0)
; template <class Epi>
; __device__ __forceinline__ void gemm_phase(LAS unsigned char* lds, const Gemm g, const StaticOrder& S, const Epi& E, int wv) {
;     ...
;             PG8_LDB(B0, 0, 0); PG8_SCHED; PG8_LDA(At, 0, 0); PG8_STAGE(PG8_SA(1, 1), a1 + hstepA, voffA);
;             PG8_WAIT_L(8); PG8_BAR; PG8_WAIT_L(0); PG8_MMA(0, 0, At, B0); PG8_BAR; PG8_SCHED;
;             PG8_LDB(B1, 0, 1); PG8_STAGE(PG8_SB(0, 0), b2, voffB);
;             PG8_BAR; PG8_WAIT_L(0); PG8_MMA(0, 1, At, B1); PG8_BAR;
;             PG8_LDA(At, 0, 1); PG8_STAGE(PG8_SA(0, 0), a2, voffA);
;             PG8_BAR; PG8_WAIT_L(0); PG8_MMA(1, 0, At, B0); PG8_BAR; PG8_SCHED;
;             PG8_STAGE(PG8_SB(0, 1), b2 + hstepB, voffB);
;             PG8_WAIT_V(6); PG8_BAR; PG8_MMA(1, 1, At, B1); PG8_BAR;
.LBB0_1743:
	s_or_b32 s10, s43, 1
	s_lshl_b64 s[68:69], s[10:11], 7
	s_sub_u32 s10, 0, s68
	s_subb_u32 s55, 0, s69
	s_add_u32 s68, s35, s10
	s_addc_u32 s69, s37, s55
	s_add_i32 m0, s24, 0xc000
	ds_read_b128 v[156:159], v175
	ds_read_b128 v[160:163], v175 offset:1024
	ds_read_b128 v[164:167], v175 offset:2048
	ds_read_b128 v[168:171], v175 offset:3072
	ds_read_b128 v[176:179], v175 offset:4096
	ds_read_b128 v[180:183], v175 offset:5120
	ds_read_b128 v[184:187], v175 offset:6144
	ds_read_b128 v[188:191], v175 offset:7168
	global_load_lds_dwordx4 v144, s[68:69]
	s_add_i32 m0, s24, 0xe000
	s_nop 0
	global_load_lds_dwordx4 v148, s[68:69]
	s_waitcnt lgkmcnt(8)
	s_barrier
	s_waitcnt lgkmcnt(0)
	s_waitcnt lgkmcnt(0)
	v_mfma_f32_16x16x32_bf16 v[124:127], v[128:131], v[156:159], v[124:127]
	v_mfma_f32_16x16x32_bf16 v[120:123], v[136:139], v[156:159], v[120:123]
	v_mfma_f32_16x16x32_bf16 v[108:111], v[128:131], v[164:167], v[108:111]
	v_mfma_f32_16x16x32_bf16 v[104:107], v[136:139], v[164:167], v[104:107]
	v_mfma_f32_16x16x32_bf16 v[92:95], v[128:131], v[176:179], v[92:95]
	v_mfma_f32_16x16x32_bf16 v[88:91], v[136:139], v[176:179], v[88:91]
	v_mfma_f32_16x16x32_bf16 v[76:79], v[128:131], v[184:187], v[76:79]
	v_mfma_f32_16x16x32_bf16 v[72:75], v[136:139], v[184:187], v[72:75]
	v_mfma_f32_16x16x32_bf16 v[124:127], v[132:135], v[160:163], v[124:127]
	v_mfma_f32_16x16x32_bf16 v[120:123], v[140:143], v[160:163], v[120:123]
	v_mfma_f32_16x16x32_bf16 v[108:111], v[132:135], v[168:171], v[108:111]
	v_mfma_f32_16x16x32_bf16 v[104:107], v[140:143], v[168:171], v[104:107]
	v_mfma_f32_16x16x32_bf16 v[92:95], v[132:135], v[180:183], v[92:95]
	v_mfma_f32_16x16x32_bf16 v[88:91], v[140:143], v[180:183], v[88:91]
	v_mfma_f32_16x16x32_bf16 v[76:79], v[132:135], v[188:191], v[76:79]
	v_mfma_f32_16x16x32_bf16 v[72:75], v[140:143], v[188:191], v[72:75]
	s_barrier
	s_add_i32 s10, s64, s23
	v_add_u32_e32 v204, s65, v173
	s_add_u32 s98, s56, s18
	s_addc_u32 s99, s57, s19
	s_mov_b32 m0, s10
	ds_read_b128 v[192:195], v204
	ds_read_b128 v[196:199], v204 offset:1024
	ds_read_b128 v[200:203], v204 offset:2048
	ds_read_b128 v[204:207], v204 offset:3072
	global_load_lds_dwordx4 v146, s[56:57]
	s_add_i32 m0, s10, 0x2000
	s_nop 0
	global_load_lds_dwordx4 v150, s[56:57]
	s_barrier
	s_waitcnt lgkmcnt(0)
	s_waitcnt lgkmcnt(0)
	v_mfma_f32_16x16x32_bf16 v[116:119], v[192:195], v[156:159], v[116:119]
	v_mfma_f32_16x16x32_bf16 v[112:115], v[200:203], v[156:159], v[112:115]
	v_mfma_f32_16x16x32_bf16 v[100:103], v[192:195], v[164:167], v[100:103]
	v_mfma_f32_16x16x32_bf16 v[96:99], v[200:203], v[164:167], v[96:99]
	v_mfma_f32_16x16x32_bf16 v[84:87], v[192:195], v[176:179], v[84:87]
	v_mfma_f32_16x16x32_bf16 v[80:83], v[200:203], v[176:179], v[80:83]
	v_mfma_f32_16x16x32_bf16 v[68:71], v[192:195], v[184:187], v[68:71]
	v_mfma_f32_16x16x32_bf16 v[64:67], v[200:203], v[184:187], v[64:67]
	v_mfma_f32_16x16x32_bf16 v[116:119], v[196:199], v[160:163], v[116:119]
	v_mfma_f32_16x16x32_bf16 v[112:115], v[204:207], v[160:163], v[112:115]
	v_mfma_f32_16x16x32_bf16 v[100:103], v[196:199], v[168:171], v[100:103]
	v_mfma_f32_16x16x32_bf16 v[96:99], v[204:207], v[168:171], v[96:99]
	v_mfma_f32_16x16x32_bf16 v[84:87], v[196:199], v[180:183], v[84:87]
	v_mfma_f32_16x16x32_bf16 v[80:83], v[204:207], v[180:183], v[80:83]
	v_mfma_f32_16x16x32_bf16 v[68:71], v[196:199], v[188:191], v[68:71]
	v_mfma_f32_16x16x32_bf16 v[64:67], v[204:207], v[188:191], v[64:67]
	s_mov_b32 m0, s24
	s_add_u32 s100, s58, s18
	s_addc_u32 s101, s59, s19
	s_barrier
	ds_read_b128 v[156:159], v175 offset:16384
	ds_read_b128 v[160:163], v175 offset:17408
	ds_read_b128 v[164:167], v175 offset:18432
	ds_read_b128 v[168:171], v175 offset:19456
	ds_read_b128 v[176:179], v175 offset:20480
	ds_read_b128 v[180:183], v175 offset:21504
	ds_read_b128 v[184:187], v175 offset:22528
	ds_read_b128 v[188:191], v175 offset:23552
	global_load_lds_dwordx4 v144, s[58:59]
	s_mov_b32 m0, s25
	s_nop 0
	global_load_lds_dwordx4 v148, s[58:59]
	s_waitcnt vmcnt(10)
	s_barrier
	s_waitcnt lgkmcnt(0)
	s_waitcnt lgkmcnt(0)
	v_mfma_f32_16x16x32_bf16 v[60:63], v[128:131], v[156:159], v[60:63]
	v_mfma_f32_16x16x32_bf16 v[56:59], v[136:139], v[156:159], v[56:59]
	v_mfma_f32_16x16x32_bf16 v[44:47], v[128:131], v[164:167], v[44:47]
	v_mfma_f32_16x16x32_bf16 v[40:43], v[136:139], v[164:167], v[40:43]
	v_mfma_f32_16x16x32_bf16 v[28:31], v[128:131], v[176:179], v[28:31]
	v_mfma_f32_16x16x32_bf16 v[24:27], v[136:139], v[176:179], v[24:27]
	v_mfma_f32_16x16x32_bf16 v[12:15], v[128:131], v[184:187], v[12:15]
	v_mfma_f32_16x16x32_bf16 v[8:11], v[136:139], v[184:187], v[8:11]
	v_mfma_f32_16x16x32_bf16 v[60:63], v[132:135], v[160:163], v[60:63]
	v_mfma_f32_16x16x32_bf16 v[56:59], v[140:143], v[160:163], v[56:59]
	v_mfma_f32_16x16x32_bf16 v[44:47], v[132:135], v[168:171], v[44:47]
	v_mfma_f32_16x16x32_bf16 v[40:43], v[140:143], v[168:171], v[40:43]
	v_mfma_f32_16x16x32_bf16 v[28:31], v[132:135], v[180:183], v[28:31]
	v_mfma_f32_16x16x32_bf16 v[24:27], v[140:143], v[180:183], v[24:27]
	v_mfma_f32_16x16x32_bf16 v[12:15], v[132:135], v[188:191], v[12:15]
	v_mfma_f32_16x16x32_bf16 v[8:11], v[140:143], v[188:191], v[8:11]
	s_barrier
	s_add_u32 s68, s56, 0x200000
	s_addc_u32 s69, s57, 0
	s_add_i32 s10, s65, s23
	s_mov_b32 m0, s10
	s_nop 0
	global_load_lds_dwordx4 v146, s[68:69]
	s_add_i32 m0, s10, 0x2000
	s_nop 0
	global_load_lds_dwordx4 v150, s[68:69]
	s_add_i32 s10, 0, 0x18000
	v_add_u32_e32 v140, s10, v173
	ds_read_b128 v[128:131], v140
	ds_read_b128 v[132:135], v140 offset:1024
	ds_read_b128 v[136:139], v140 offset:2048
	ds_read_b128 v[140:143], v140 offset:3072
	s_waitcnt vmcnt(6)
	s_barrier
; #define PG8_STAGE(bufoff, gbase, voff) do { _Pragma("unroll") for (int _i = 0; _i < 2; ++_i) \
;         __builtin_amdgcn_global_load_lds((const unsigned*)((const char*)(gbase) + (voff)[_i]), (LAS unsigned*)(lds + (bufoff) + ldsw + _i * 8192), 16, 0, 0); } while (0)
; #define PG8_LDA(dst, b, h) do { _Pragma("unroll") for (int m = 0; m < 4; ++m) _Pragma("unroll") for (int k = 0; k < 2; ++k) dst[m][k] = *(const LAS bf16x8*)(lds + PG8_SA(b, h) + aoff + m * 2048 + k * 1024); } while (0)
; #define PG8_LDB(dst, b, h) do { _Pragma("unroll") for (int n = 0; n < 2; ++n) _Pragma("unroll") for (int k = 0; k < 2; ++k) dst[n][k] = *(const LAS bf16x8*)(lds + PG8_SB(b, h) + boff + n * 2048 + k * 1024); } while (0)
; #define PG8_MMA(ai, bj, At, Bt) do { __builtin_amdgcn_s_setprio(1); _Pragma("unroll") for (int m = 0; m < 4; ++m) _Pragma("unroll") for (int n = 0; n < 2; ++n) _Pragma("unroll") for (int k = 0; k < 2; ++k) \
;         acc[ai][bj][m][n] = __builtin_amdgcn_mfma_f32_16x16x32_bf16(Bt[n][k], At[m][k], acc[ai][bj][m][n], 0, 0, 0); __builtin_amdgcn_s_setprio(0); } while (0)
; #define PG8_WAIT_V(n) asm volatile("s_waitcnt vmcnt(" #n ")" ::: "memory")
; #define PG8_WAIT_L(n) asm volatile("s_waitcnt lgkmcnt(" #n ")" ::: "memory")
; #define PG8_BAR __builtin_amdgcn_s_barrier()
; #define PG8_SCHED __builtin_amdgcn_sched_barrier(0)
; template <class Epi>
; __device__ __forceinline__ void gemm_phase(LAS unsigned char* lds, const Gemm g, const StaticOrder& S, const Epi& E, int wv) {
;     ...
;             PG8_WAIT_V(6); PG8_BAR; PG8_MMA(1, 1, At, B1); PG8_BAR;
;             PG8_LDB(B0, 1, 0); PG8_SCHED; PG8_LDA(At, 1, 0); PG8_STAGE(PG8_SA(0, 1), a2 + hstepA, voffA);
;             PG8_WAIT_L(8); PG8_BAR; PG8_WAIT_L(0); PG8_MMA(0, 0, At, B0); PG8_BAR; PG8_SCHED;
;             PG8_LDB(B1, 1, 1); PG8_STAGE(PG8_SB(1, 0), b3, voffB);
;             PG8_BAR; PG8_WAIT_L(0); PG8_MMA(0, 1, At, B1); PG8_BAR;
;             PG8_LDA(At, 1, 1); PG8_STAGE(PG8_SA(1, 0), a3, voffA);
;             PG8_BAR; PG8_WAIT_L(0); PG8_MMA(1, 0, At, B0); PG8_BAR; PG8_SCHED;
	v_mfma_f32_16x16x32_bf16 v[52:55], v[192:195], v[156:159], v[52:55]
	v_mfma_f32_16x16x32_bf16 v[48:51], v[200:203], v[156:159], v[48:51]
	v_mfma_f32_16x16x32_bf16 v[36:39], v[192:195], v[164:167], v[36:39]
	v_mfma_f32_16x16x32_bf16 v[32:35], v[200:203], v[164:167], v[32:35]
	v_mfma_f32_16x16x32_bf16 v[20:23], v[192:195], v[176:179], v[20:23]
	v_mfma_f32_16x16x32_bf16 v[16:19], v[200:203], v[176:179], v[16:19]
	v_mfma_f32_16x16x32_bf16 v[4:7], v[192:195], v[184:187], v[4:7]
	v_mfma_f32_16x16x32_bf16 v[0:3], v[200:203], v[184:187], v[0:3]
	v_mfma_f32_16x16x32_bf16 v[52:55], v[196:199], v[160:163], v[52:55]
	v_mfma_f32_16x16x32_bf16 v[48:51], v[204:207], v[160:163], v[48:51]
	v_mfma_f32_16x16x32_bf16 v[36:39], v[196:199], v[168:171], v[36:39]
	v_mfma_f32_16x16x32_bf16 v[32:35], v[204:207], v[168:171], v[32:35]
	v_mfma_f32_16x16x32_bf16 v[20:23], v[196:199], v[180:183], v[20:23]
	v_mfma_f32_16x16x32_bf16 v[16:19], v[204:207], v[180:183], v[16:19]
	v_mfma_f32_16x16x32_bf16 v[4:7], v[196:199], v[188:191], v[4:7]
	v_mfma_f32_16x16x32_bf16 v[0:3], v[204:207], v[188:191], v[0:3]
	s_waitcnt lgkmcnt(0)
	s_barrier
	s_add_u32 s58, s58, 0x200000
	s_addc_u32 s59, s59, 0
	s_mov_b32 m0, s33
	ds_read_b128 v[156:159], v175 offset:32768
	ds_read_b128 v[160:163], v175 offset:33792
	ds_read_b128 v[164:167], v175 offset:34816
	ds_read_b128 v[168:171], v175 offset:35840
	ds_read_b128 v[176:179], v175 offset:36864
	ds_read_b128 v[180:183], v175 offset:37888
	ds_read_b128 v[184:187], v175 offset:38912
	ds_read_b128 v[188:191], v175 offset:39936
	global_load_lds_dwordx4 v144, s[58:59]
	s_mov_b32 m0, s45
	s_nop 0
	global_load_lds_dwordx4 v148, s[58:59]
	s_waitcnt lgkmcnt(8)
	s_barrier
	s_waitcnt lgkmcnt(0)
	s_waitcnt lgkmcnt(0)
	v_mfma_f32_16x16x32_bf16 v[124:127], v[128:131], v[156:159], v[124:127]
	v_mfma_f32_16x16x32_bf16 v[120:123], v[136:139], v[156:159], v[120:123]
	v_mfma_f32_16x16x32_bf16 v[108:111], v[128:131], v[164:167], v[108:111]
	v_mfma_f32_16x16x32_bf16 v[104:107], v[136:139], v[164:167], v[104:107]
	v_mfma_f32_16x16x32_bf16 v[92:95], v[128:131], v[176:179], v[92:95]
	v_mfma_f32_16x16x32_bf16 v[88:91], v[136:139], v[176:179], v[88:91]
	v_mfma_f32_16x16x32_bf16 v[76:79], v[128:131], v[184:187], v[76:79]
	v_mfma_f32_16x16x32_bf16 v[72:75], v[136:139], v[184:187], v[72:75]
	v_mfma_f32_16x16x32_bf16 v[124:127], v[132:135], v[160:163], v[124:127]
	v_mfma_f32_16x16x32_bf16 v[120:123], v[140:143], v[160:163], v[120:123]
	v_mfma_f32_16x16x32_bf16 v[108:111], v[132:135], v[168:171], v[108:111]
	v_mfma_f32_16x16x32_bf16 v[104:107], v[140:143], v[168:171], v[104:107]
	v_mfma_f32_16x16x32_bf16 v[92:95], v[132:135], v[180:183], v[92:95]
	v_mfma_f32_16x16x32_bf16 v[88:91], v[140:143], v[180:183], v[88:91]
	v_mfma_f32_16x16x32_bf16 v[76:79], v[132:135], v[188:191], v[76:79]
	v_mfma_f32_16x16x32_bf16 v[72:75], v[140:143], v[188:191], v[72:75]
	s_barrier
	s_add_i32 s55, 0, 0x1c000
	s_add_i32 s10, s10, s23
	v_add_u32_e32 v204, s55, v173
	s_mov_b32 m0, s10
	ds_read_b128 v[192:195], v204
	ds_read_b128 v[196:199], v204 offset:1024
	ds_read_b128 v[200:203], v204 offset:2048
	ds_read_b128 v[204:207], v204 offset:3072
	global_load_lds_dwordx4 v146, s[98:99]
	s_add_i32 m0, s10, 0x2000
	s_nop 0
	global_load_lds_dwordx4 v150, s[98:99]
	s_barrier
	s_waitcnt lgkmcnt(0)
	s_waitcnt lgkmcnt(0)
	v_mfma_f32_16x16x32_bf16 v[116:119], v[192:195], v[156:159], v[116:119]
	v_mfma_f32_16x16x32_bf16 v[112:115], v[200:203], v[156:159], v[112:115]
	v_mfma_f32_16x16x32_bf16 v[100:103], v[192:195], v[164:167], v[100:103]
	v_mfma_f32_16x16x32_bf16 v[96:99], v[200:203], v[164:167], v[96:99]
	v_mfma_f32_16x16x32_bf16 v[84:87], v[192:195], v[176:179], v[84:87]
	v_mfma_f32_16x16x32_bf16 v[80:83], v[200:203], v[176:179], v[80:83]
	v_mfma_f32_16x16x32_bf16 v[68:71], v[192:195], v[184:187], v[68:71]
	v_mfma_f32_16x16x32_bf16 v[64:67], v[200:203], v[184:187], v[64:67]
	v_mfma_f32_16x16x32_bf16 v[116:119], v[196:199], v[160:163], v[116:119]
	v_mfma_f32_16x16x32_bf16 v[112:115], v[204:207], v[160:163], v[112:115]
	v_mfma_f32_16x16x32_bf16 v[100:103], v[196:199], v[168:171], v[100:103]
	v_mfma_f32_16x16x32_bf16 v[96:99], v[204:207], v[168:171], v[96:99]
	v_mfma_f32_16x16x32_bf16 v[84:87], v[196:199], v[180:183], v[84:87]
	v_mfma_f32_16x16x32_bf16 v[80:83], v[204:207], v[180:183], v[80:83]
	v_mfma_f32_16x16x32_bf16 v[68:71], v[196:199], v[188:191], v[68:71]
	v_mfma_f32_16x16x32_bf16 v[64:67], v[204:207], v[188:191], v[64:67]
	s_mov_b32 m0, s60
	s_barrier
; #define PG8_STAGE(bufoff, gbase, voff) do { _Pragma("unroll") for (int _i = 0; _i < 2; ++_i) \
;         __builtin_amdgcn_global_load_lds((const unsigned*)((const char*)(gbase) + (voff)[_i]), (LAS unsigned*)(lds + (bufoff) + ldsw + _i * 8192), 16, 0, 0); } while (0)
; #define PG8_MMA(ai, bj, At, Bt) do { __builtin_amdgcn_s_setprio(1); _Pragma("unroll") for (int m = 0; m < 4; ++m) _Pragma("unroll") for (int n = 0; n < 2; ++n) _Pragma("unroll") for (int k = 0; k < 2; ++k) \
;         acc[ai][bj][m][n] = __builtin_amdgcn_mfma_f32_16x16x32_bf16(Bt[n][k], At[m][k], acc[ai][bj][m][n], 0, 0, 0); __builtin_amdgcn_s_setprio(0); } while (0)
; #define PG8_WAIT_V(n) asm volatile("s_waitcnt vmcnt(" #n ")" ::: "memory")
; #define PG8_WAIT_L(n) asm volatile("s_waitcnt lgkmcnt(" #n ")" ::: "memory")
; #define PG8_BAR __builtin_amdgcn_s_barrier()
; #define PG8_SCHED __builtin_amdgcn_sched_barrier(0)
; template <class Epi>
; __device__ __forceinline__ void gemm_phase(LAS unsigned char* lds, const Gemm g, const StaticOrder& S, const Epi& E, int wv) {
;     ...
;             PG8_BAR; PG8_WAIT_L(0); PG8_MMA(1, 0, At, B0); PG8_BAR; PG8_SCHED;
;             PG8_STAGE(PG8_SB(1, 1), b3 + hstepB, voffB);
;             PG8_WAIT_V(6); PG8_BAR; PG8_MMA(1, 1, At, B1); PG8_BAR;
	ds_read_b128 v[156:159], v175 offset:49152
	ds_read_b128 v[160:163], v175 offset:50176
	ds_read_b128 v[164:167], v175 offset:51200
	ds_read_b128 v[168:171], v175 offset:52224
	ds_read_b128 v[176:179], v175 offset:53248
	ds_read_b128 v[180:183], v175 offset:54272
	ds_read_b128 v[184:187], v175 offset:55296
	ds_read_b128 v[188:191], v175 offset:56320
	global_load_lds_dwordx4 v144, s[100:101]
	s_mov_b32 m0, s61
	s_nop 0
	global_load_lds_dwordx4 v148, s[100:101]
	s_waitcnt vmcnt(10)
	s_barrier
	s_waitcnt lgkmcnt(0)
	s_waitcnt lgkmcnt(0)
	v_mfma_f32_16x16x32_bf16 v[60:63], v[128:131], v[156:159], v[60:63]
	v_mfma_f32_16x16x32_bf16 v[56:59], v[136:139], v[156:159], v[56:59]
	v_mfma_f32_16x16x32_bf16 v[44:47], v[128:131], v[164:167], v[44:47]
	v_mfma_f32_16x16x32_bf16 v[40:43], v[136:139], v[164:167], v[40:43]
	v_mfma_f32_16x16x32_bf16 v[28:31], v[128:131], v[176:179], v[28:31]
	v_mfma_f32_16x16x32_bf16 v[24:27], v[136:139], v[176:179], v[24:27]
	v_mfma_f32_16x16x32_bf16 v[12:15], v[128:131], v[184:187], v[12:15]
	v_mfma_f32_16x16x32_bf16 v[8:11], v[136:139], v[184:187], v[8:11]
	v_mfma_f32_16x16x32_bf16 v[60:63], v[132:135], v[160:163], v[60:63]
	v_mfma_f32_16x16x32_bf16 v[56:59], v[140:143], v[160:163], v[56:59]
	v_mfma_f32_16x16x32_bf16 v[44:47], v[132:135], v[168:171], v[44:47]
	v_mfma_f32_16x16x32_bf16 v[40:43], v[140:143], v[168:171], v[40:43]
	v_mfma_f32_16x16x32_bf16 v[28:31], v[132:135], v[180:183], v[28:31]
	v_mfma_f32_16x16x32_bf16 v[24:27], v[140:143], v[180:183], v[24:27]
	v_mfma_f32_16x16x32_bf16 v[12:15], v[132:135], v[188:191], v[12:15]
	v_mfma_f32_16x16x32_bf16 v[8:11], v[140:143], v[188:191], v[8:11]
	s_barrier
	s_add_u32 s56, s56, 0x1fff80
	s_addc_u32 s57, s57, 0
	s_add_i32 s10, s55, s23
	s_mov_b32 m0, s10
	s_nop 0
	global_load_lds_dwordx4 v146, s[56:57]
	s_add_i32 m0, s10, 0x2000
	s_nop 0
	global_load_lds_dwordx4 v150, s[56:57]
	v_add_u32_e32 v140, s64, v173
	ds_read_b128 v[128:131], v140
	ds_read_b128 v[132:135], v140 offset:1024
	ds_read_b128 v[136:139], v140 offset:2048
	ds_read_b128 v[140:143], v140 offset:3072
	s_waitcnt vmcnt(6)
	s_barrier
	v_mfma_f32_16x16x32_bf16 v[52:55], v[192:195], v[156:159], v[52:55]
	v_mfma_f32_16x16x32_bf16 v[48:51], v[200:203], v[156:159], v[48:51]
	v_mfma_f32_16x16x32_bf16 v[36:39], v[192:195], v[164:167], v[36:39]
	v_mfma_f32_16x16x32_bf16 v[32:35], v[200:203], v[164:167], v[32:35]
	v_mfma_f32_16x16x32_bf16 v[20:23], v[192:195], v[176:179], v[20:23]
	v_mfma_f32_16x16x32_bf16 v[16:19], v[200:203], v[176:179], v[16:19]
	v_mfma_f32_16x16x32_bf16 v[4:7], v[192:195], v[184:187], v[4:7]
	v_mfma_f32_16x16x32_bf16 v[0:3], v[200:203], v[184:187], v[0:3]
	v_mfma_f32_16x16x32_bf16 v[52:55], v[196:199], v[160:163], v[52:55]
	v_mfma_f32_16x16x32_bf16 v[48:51], v[204:207], v[160:163], v[48:51]
	v_mfma_f32_16x16x32_bf16 v[36:39], v[196:199], v[168:171], v[36:39]
	v_mfma_f32_16x16x32_bf16 v[32:35], v[204:207], v[168:171], v[32:35]
	v_mfma_f32_16x16x32_bf16 v[20:23], v[196:199], v[180:183], v[20:23]
	v_mfma_f32_16x16x32_bf16 v[16:19], v[204:207], v[180:183], v[16:19]
	v_mfma_f32_16x16x32_bf16 v[4:7], v[196:199], v[188:191], v[4:7]
	v_mfma_f32_16x16x32_bf16 v[0:3], v[204:207], v[188:191], v[0:3]
	s_waitcnt lgkmcnt(0)
	s_cmpk_gt_u32 s43, 0x7d
	s_mov_b32 s43, s54
	s_barrier
	s_cbranch_scc1 .LBB0_1748

;     __device__ bool next(int i, Unit& u) const {
;         const long L = (long)i * G + c; if (L >= nwg) return false;
;         int wgid = (int)L; { const int q = nwg / NXCD, r = nwg % NXCD, xcd = wgid % NXCD, off = wgid / NXCD; wgid = (xcd < r ? xcd * (q + 1) : r * (q + 1) + (xcd - r) * q) + off; }
;         const int nig = wgm * nN, gid = wgid / nig, fm = gid * wgm, gsz = (nM - fm) < wgm ? (nM - fm) : wgm;
;         u.pm = fm + ((wgid % nig) % gsz); u.pn = (wgid % nig) / gsz; return true;
; template <class Epi>
; __device__ __forceinline__ void gemm_phase(LAS unsigned char* lds, const Gemm g, const StaticOrder& S, const Epi& E, int wv) {
;     const int tid = opaque_tid(wv), wid = __builtin_amdgcn_readfirstlane(tid >> 6), lane = tid & 63, wr = wid >> 2, wc = wid & 3, fr = lane & 15, fq = lane >> 4;
;     const int K = g.K, nt = K / BK;
;     unsigned voffA[2], voffB[2];
; #pragma unroll
;     for (int i = 0; i < 2; ++i) { int R, C; stage_rc(tid * 16 + i * 8192, R, C); const int Rb = Epi::PERM ? ((R & ~31) + perm32(R & 31)) : R;
;         voffA[i] = (unsigned)(R * g.lda + C) * 2u; voffB[i] = (unsigned)(Rb * g.ldb + C) * 2u; }
;     const bool krev = (g.adiag & 2) != 0;
;     const ptrdiff_t kstep = krev ? -(ptrdiff_t)(BK * 2) : (ptrdiff_t)(BK * 2);
;     const size_t kbeg = krev ? (size_t)(nt - 1) * (BK * 2) : 0;
;     const size_t hstepA = (size_t)HALF * g.lda * 2, hstepB = (size_t)HALF * g.ldb * 2;
;     const size_t tstepA = 2 * hstepA, tstepB = 2 * hstepB;
;     const unsigned ldsw = (unsigned)wid * 1024u;
;     const int aoff = lds_byte(wr * 64 + fr, fq * 8), boff = lds_byte(wc * 32 + fr, fq * 8);
;     ...
;     Unit cur, nxt; int ui = 0;
;     if (!S.next(0, cur)) return;
;     f32x4 acc[2][2][4][2];
; #pragma unroll
;     for (int a = 0; a < 2; ++a)
; #pragma unroll
;         for (int b = 0; b < 2; ++b)
; #pragma unroll
;             for (int m = 0; m < 4; ++m)
; #pragma unroll
;                 for (int n = 0; n < 2; ++n) acc[a][b][m][n] = (f32x4){0.f, 0.f, 0.f, 0.f};
;     bf16x8 At[4][2], B0[2][2], B1[2][2];
;     const char* cA = (const char*)g.A + (size_t)cur.pm * tstepA + ((g.adiag & 1) ? (size_t)(cur.pn >> 1) * K * 2 : 0) + kbeg;
;     const char* cB = (const char*)g.Bt + (size_t)cur.pn * tstepB + kbeg;
.LBB0_1772:
	v_ashrrev_i32_e32 v2, 31, v0
	v_lshrrev_b32_e32 v2, 26, v2
	v_lshlrev_b32_e32 v1, 4, v0
	v_add_u32_e32 v2, v0, v2
	v_bfe_i32 v0, v0, 27, 1
	v_lshrrev_b32_e32 v0, 22, v0
	v_add_u32_e32 v0, v1, v0
	v_and_b32_e32 v0, 0xfffffc00, v0
	v_sub_u32_e32 v0, v1, v0
	v_lshrrev_b32_e32 v3, 4, v0
	v_bitop3_b32 v0, v3, v0, 32 bitop3:0x6c
	v_ashrrev_i32_e32 v4, 31, v0
	v_lshrrev_b32_e32 v4, 26, v4
	v_add_u32_e32 v4, v0, v4
	v_ashrrev_i32_e32 v5, 6, v4
	v_and_b32_e32 v4, 0xc0, v4
	s_ashr_i32 s12, s5, 3
	v_ashrrev_i32_e32 v2, 6, v2
	v_sub_u32_e32 v0, v0, v4
	v_mov_b32_e32 v4, 1
	s_waitcnt lgkmcnt(0)
	s_add_u32 s5, s10, 0x100000
	v_lshlrev_b32_e32 v3, 3, v2
	v_lshlrev_b32_e32 v2, 5, v2
	v_ashrrev_i16_sdwa v0, v4, sext(v0) dst_sel:DWORD dst_unused:UNUSED_PAD src0_sel:DWORD src1_sel:BYTE_0
	s_addc_u32 s22, s11, 0
	v_and_b32_e32 v3, -16, v3
	v_and_b32_e32 v2, 32, v2
	v_bfe_i32 v0, v0, 0, 16
	s_add_u32 s23, s8, 0x7100000
	v_add_u32_e32 v3, v5, v3
	v_and_b32_e32 v5, 3, v5
	s_mov_b32 s8, 0x7fffe0
	v_add_lshl_u32 v2, v2, v0, 1
	v_add_u32_e32 v1, 0x2000, v1
	v_lshlrev_b32_e32 v6, 1, v3
	v_lshrrev_b32_e32 v7, 2, v3
	v_and_or_b32 v5, v3, s8, v5
	v_lshl_add_u32 v0, v3, 9, v2
	v_ashrrev_i32_e32 v3, 31, v1
	v_lshrrev_b32_e32 v3, 22, v3
	v_and_b32_e32 v6, 24, v6
	v_and_b32_e32 v7, 4, v7
	v_add_u32_e32 v3, v1, v3
	v_or3_b32 v5, v5, v7, v6
	v_ashrrev_i32_e32 v3, 10, v3
	v_lshl_add_u32 v2, v5, 9, v2
	v_mul_i32_i24_e32 v5, 0x400, v3
	v_sub_u32_e32 v1, v1, v5
	v_lshrrev_b32_e32 v5, 4, v1
	v_bitop3_b32 v1, v5, v1, 32 bitop3:0x6c
	v_ashrrev_i32_e32 v6, 31, v1
	v_lshrrev_b32_e32 v6, 26, v6
	v_lshlrev_b32_e32 v5, 3, v3
	v_add_u32_e32 v6, v1, v6
	v_and_b32_e32 v5, -16, v5
	v_ashrrev_i32_e32 v7, 6, v6
	v_add_u32_e32 v5, v7, v5
	v_and_b32_e32 v7, 3, v7
	s_addc_u32 s24, s9, 0
	v_and_or_b32 v7, v5, s8, v7
	s_add_i32 s8, s14, s12
	s_ashr_i32 s9, s8, 31
	s_lshr_b32 s9, s9, 27
	s_add_i32 s9, s8, s9
	s_ashr_i32 s11, s9, 5
	s_andn2_b32 s9, s9, 31
	s_sub_i32 s8, s8, s9
	s_bfe_i32 s9, s8, 0x80000
	s_bfe_u32 s9, s9, 0x2000d
	s_add_i32 s9, s8, s9
	s_bfe_i32 s12, s9, 0x80000
	s_and_b32 s9, s9, 0xfc
	s_sub_i32 s8, s8, s9
	s_lshl_b32 s11, s11, 2
	s_sext_i32_i16 s12, s12
	s_sext_i32_i8 s8, s8
	s_ashr_i32 s13, s4, 8
	s_lshr_b32 s12, s12, 2
	s_add_i32 s38, s11, s8
	s_ashr_i32 s10, s4, 6
	s_ashr_i32 s39, s38, 31
	s_bfe_i64 s[14:15], s[12:13], 0x100000
	v_and_b32_e32 v6, 0xc0, v6
	s_lshl_b32 s25, s10, 10
	s_lshl_b64 s[8:9], s[38:39], 17
	s_lshl_b64 s[14:15], s[14:15], 17
	v_sub_u32_e32 v1, v1, v6
	s_add_u32 s50, s23, s14
	v_lshlrev_b32_e32 v3, 5, v3
	v_ashrrev_i16_sdwa v1, v4, sext(v1) dst_sel:DWORD dst_unused:UNUSED_PAD src0_sel:DWORD src1_sel:BYTE_0
	v_lshlrev_b32_e32 v4, 1, v5
	v_lshrrev_b32_e32 v6, 2, v5
	s_addc_u32 s51, s24, s15
	s_add_i32 s33, s25, 0
	v_and_b32_e32 v3, 32, v3
	v_bfe_i32 v1, v1, 0, 16
	v_and_b32_e32 v4, 24, v4
	v_and_b32_e32 v6, 4, v6
	s_add_i32 m0, s33, 0x10000
	v_or3_b32 v6, v7, v6, v4
	v_add_lshl_u32 v1, v3, v1, 1
	global_load_lds_dwordx4 v2, s[50:51]
	s_add_i32 m0, s33, 0x12000
	v_lshl_add_u32 v6, v6, 9, v1
	s_add_u32 s48, s5, s8
	global_load_lds_dwordx4 v6, s[50:51]
	s_addc_u32 s49, s22, s9
	s_mov_b32 m0, s33
	s_add_i32 s39, s33, 0x2000
	v_lshl_add_u32 v4, v5, 9, v1
	global_load_lds_dwordx4 v0, s[48:49]
	s_mov_b32 m0, s39
	s_add_u32 s8, s50, 0x10000
	global_load_lds_dwordx4 v4, s[48:49]
	s_addc_u32 s9, s51, 0
	s_add_i32 m0, s33, 0x14000
	v_mov_b32_e32 v3, 0
	global_load_lds_dwordx4 v2, s[8:9]
	s_add_i32 m0, s33, 0x16000
	v_mov_b32_e32 v7, v3
	global_load_lds_dwordx4 v6, s[8:9]
	s_add_u32 s8, s48, 0x10000
	s_addc_u32 s9, s49, 0
	s_add_i32 s56, s33, 0x4000
	s_mov_b32 m0, s56
	s_add_i32 s57, s33, 0x6000
	global_load_lds_dwordx4 v0, s[8:9]
	s_mov_b32 m0, s57
	v_mov_b32_e32 v1, v3
	global_load_lds_dwordx4 v4, s[8:9]
	v_mov_b32_e32 v5, v3
	v_lshl_add_u64 v[14:15], s[50:51], 0, v[2:3]
	v_lshl_add_u64 v[12:13], s[50:51], 0, v[6:7]
	v_lshl_add_u64 v[10:11], s[48:49], 0, v[0:1]
	s_cmp_lg_u32 s13, 1
	v_lshl_add_u64 v[8:9], s[48:49], 0, v[4:5]
	s_cbranch_scc1 .LBB0_1774
	s_barrier
	s_setprio 1

; #define PG8_STAGE(bufoff, gbase, voff) do { _Pragma("unroll") for (int _i = 0; _i < 2; ++_i) \
;         __builtin_amdgcn_global_load_lds((const unsigned*)((const char*)(gbase) + (voff)[_i]), (LAS unsigned*)(lds + (bufoff) + ldsw + _i * 8192), 16, 0, 0); } while (0)
; #define PG8_LDA(dst, b, h) do { _Pragma("unroll") for (int m = 0; m < 4; ++m) _Pragma("unroll") for (int k = 0; k < 2; ++k) dst[m][k] = *(const LAS bf16x8*)(lds + PG8_SA(b, h) + aoff + m * 2048 + k * 1024); } while (0)
; #define PG8_LDB(dst, b, h) do { _Pragma("unroll") for (int n = 0; n < 2; ++n) _Pragma("unroll") for (int k = 0; k < 2; ++k) dst[n][k] = *(const LAS bf16x8*)(lds + PG8_SB(b, h) + boff + n * 2048 + k * 1024); } while (0)
; #define PG8_WAIT_V(n) asm volatile("s_waitcnt vmcnt(" #n ")" ::: "memory")
; #define PG8_WAIT_L(n) asm volatile("s_waitcnt lgkmcnt(" #n ")" ::: "memory")
; #define PG8_BAR __builtin_amdgcn_s_barrier()
; template <class Epi>
; __device__ __forceinline__ void gemm_phase(LAS unsigned char* lds, const Gemm g, const StaticOrder& S, const Epi& E, int wv) {
;     ...
;         const bool has_next = S.next(ui + 1, nxt);
;         const char* nA = has_next ? (const char*)g.A + (size_t)nxt.pm * tstepA + ((g.adiag & 1) ? (size_t)(nxt.pn >> 1) * K * 2 : 0) + kbeg : cA;
;         const char* nB = has_next ? (const char*)g.Bt + (size_t)nxt.pn * tstepB + kbeg : cB;
;         for (int t = 0; t < nt; t += 2) {
;             const bool last = (t == nt - 2);
;             const char* a1 = cA + (ptrdiff_t)(t + 1) * kstep;
;             const char* a2 = last ? nA : cA + (ptrdiff_t)(t + 2) * kstep; const char* b2 = last ? nB : cB + (ptrdiff_t)(t + 2) * kstep;
;             const char* a3 = a2 + kstep; const char* b3 = b2 + kstep;
;             PG8_LDB(B0, 0, 0); PG8_SCHED; PG8_LDA(At, 0, 0); PG8_STAGE(PG8_SA(1, 1), a1 + hstepA, voffA);
;             PG8_WAIT_L(8); PG8_BAR; PG8_WAIT_L(0); PG8_MMA(0, 0, At, B0); PG8_BAR; PG8_SCHED;
;             PG8_LDB(B1, 0, 1); PG8_STAGE(PG8_SB(0, 0), b2, voffB);
;             PG8_BAR; PG8_WAIT_L(0); PG8_MMA(0, 1, At, B1); PG8_BAR;
;             PG8_LDA(At, 0, 1); PG8_STAGE(PG8_SA(0, 0), a2, voffA);
;             PG8_BAR; PG8_WAIT_L(0); PG8_MMA(1, 0, At, B0); PG8_BAR; PG8_SCHED;
;             PG8_STAGE(PG8_SB(0, 1), b2 + hstepB, voffB);
;             PG8_WAIT_V(6); PG8_BAR; PG8_MMA(1, 1, At, B1); PG8_BAR;
.LBB0_1776:
	s_ashr_i32 s43, s42, 31
	s_lshl_b64 s[44:45], s[42:43], 17
	s_add_u32 s44, s5, s44
	v_cmp_lt_i64_e32 vcc, s[36:37], v[8:9]
	s_addc_u32 s45, s22, s45
	ds_read_b128 v[18:21], v15
	ds_read_b128 v[22:25], v15 offset:1024
	ds_read_b128 v[26:29], v15 offset:2048
	ds_read_b128 v[30:33], v15 offset:3072
	s_and_b64 s[46:47], vcc, exec
	s_cselect_b32 s55, s45, s49
	s_cselect_b32 s54, s44, s48
	s_ashr_i32 s41, s40, 31
	s_lshl_b64 s[46:47], s[40:41], 17
	s_add_u32 s46, s23, s46
	s_addc_u32 s47, s24, s47
	s_and_b64 s[52:53], vcc, exec
	s_cselect_b32 s53, s47, s51
	s_cselect_b32 s52, s46, s50
	s_add_u32 s70, s48, 0x10080
	s_addc_u32 s71, s49, 0
	s_mov_b32 m0, s61
	v_lshl_add_u64 v[66:67], s[70:71], 0, v[0:1]
	ds_read_b128 v[34:37], v16
	ds_read_b128 v[38:41], v16 offset:1024
	ds_read_b128 v[42:45], v16 offset:2048
	ds_read_b128 v[46:49], v16 offset:3072
	ds_read_b128 v[50:53], v16 offset:4096
	ds_read_b128 v[54:57], v16 offset:5120
	ds_read_b128 v[58:61], v16 offset:6144
	ds_read_b128 v[62:65], v16 offset:7168
	global_load_lds_dwordx4 v[66:67], off
	v_lshl_add_u64 v[66:67], s[70:71], 0, v[4:5]
	s_mov_b32 m0, s62
	s_nop 0
	global_load_lds_dwordx4 v[66:67], off
	s_waitcnt lgkmcnt(8)
	s_barrier
	s_waitcnt lgkmcnt(0)
	s_waitcnt lgkmcnt(0)
	v_mfma_f32_16x16x32_bf16 v[66:69], v[18:21], v[34:37], 0
	v_mfma_f32_16x16x32_bf16 v[70:73], v[26:29], v[34:37], 0
	v_mfma_f32_16x16x32_bf16 v[74:77], v[18:21], v[42:45], 0
	v_mfma_f32_16x16x32_bf16 v[78:81], v[26:29], v[42:45], 0
	v_mfma_f32_16x16x32_bf16 v[82:85], v[18:21], v[50:53], 0
	v_mfma_f32_16x16x32_bf16 v[86:89], v[26:29], v[50:53], 0
	v_mfma_f32_16x16x32_bf16 v[90:93], v[18:21], v[58:61], 0
	v_mfma_f32_16x16x32_bf16 v[94:97], v[26:29], v[58:61], 0
	v_mfma_f32_16x16x32_bf16 v[66:69], v[22:25], v[38:41], v[66:69]
	v_mfma_f32_16x16x32_bf16 v[70:73], v[30:33], v[38:41], v[70:73]
	v_mfma_f32_16x16x32_bf16 v[74:77], v[22:25], v[46:49], v[74:77]
	v_mfma_f32_16x16x32_bf16 v[78:81], v[30:33], v[46:49], v[78:81]
	v_mfma_f32_16x16x32_bf16 v[82:85], v[22:25], v[54:57], v[82:85]
	v_mfma_f32_16x16x32_bf16 v[86:89], v[30:33], v[54:57], v[86:89]
	v_mfma_f32_16x16x32_bf16 v[90:93], v[22:25], v[62:65], v[90:93]
	v_mfma_f32_16x16x32_bf16 v[94:97], v[30:33], v[62:65], v[94:97]
	s_barrier
	v_lshl_add_u64 v[210:211], s[50:51], 0, v[2:3]
	s_add_i32 s69, s60, s25
	v_lshl_add_u64 v[114:115], v[210:211], 0, s[12:13]
	s_mov_b32 m0, s69
	v_lshl_add_u64 v[212:213], s[50:51], 0, v[6:7]
	s_add_i32 s41, s69, 0x2000
	ds_read_b128 v[98:101], v17
	ds_read_b128 v[102:105], v17 offset:1024
	ds_read_b128 v[106:109], v17 offset:2048
	ds_read_b128 v[110:113], v17 offset:3072
	global_load_lds_dwordx4 v[114:115], off
	v_lshl_add_u64 v[114:115], v[212:213], 0, s[12:13]
	s_mov_b32 m0, s41
	s_nop 0
	global_load_lds_dwordx4 v[114:115], off
	s_barrier
	s_waitcnt lgkmcnt(0)
	s_waitcnt lgkmcnt(0)
	v_mfma_f32_16x16x32_bf16 v[114:117], v[98:101], v[34:37], 0
	v_mfma_f32_16x16x32_bf16 v[34:37], v[106:109], v[34:37], 0
	v_mfma_f32_16x16x32_bf16 v[114:117], v[102:105], v[38:41], v[114:117]
	v_mfma_f32_16x16x32_bf16 v[34:37], v[110:113], v[38:41], v[34:37]
	v_mfma_f32_16x16x32_bf16 v[38:41], v[98:101], v[42:45], 0
	v_mfma_f32_16x16x32_bf16 v[42:45], v[106:109], v[42:45], 0
	v_mfma_f32_16x16x32_bf16 v[38:41], v[102:105], v[46:49], v[38:41]
	v_mfma_f32_16x16x32_bf16 v[42:45], v[110:113], v[46:49], v[42:45]
	v_mfma_f32_16x16x32_bf16 v[46:49], v[98:101], v[50:53], 0
	v_mfma_f32_16x16x32_bf16 v[50:53], v[106:109], v[50:53], 0
	v_mfma_f32_16x16x32_bf16 v[46:49], v[102:105], v[54:57], v[46:49]
	v_mfma_f32_16x16x32_bf16 v[50:53], v[110:113], v[54:57], v[50:53]
	v_mfma_f32_16x16x32_bf16 v[54:57], v[98:101], v[58:61], 0
	v_mfma_f32_16x16x32_bf16 v[58:61], v[106:109], v[58:61], 0
	v_mfma_f32_16x16x32_bf16 v[54:57], v[102:105], v[62:65], v[54:57]
	v_mfma_f32_16x16x32_bf16 v[58:61], v[110:113], v[62:65], v[58:61]
	v_lshl_add_u64 v[214:215], s[48:49], 0, v[0:1]
	s_mov_b32 m0, s33
	v_lshl_add_u64 v[146:147], v[214:215], 0, s[12:13]
	v_lshl_add_u64 v[216:217], s[48:49], 0, v[4:5]
	s_barrier
	ds_read_b128 v[62:65], v16 offset:16384
	ds_read_b128 v[118:121], v16 offset:17408
	ds_read_b128 v[122:125], v16 offset:18432
	ds_read_b128 v[126:129], v16 offset:19456
	ds_read_b128 v[130:133], v16 offset:20480
	ds_read_b128 v[134:137], v16 offset:21504
	ds_read_b128 v[138:141], v16 offset:22528
	ds_read_b128 v[142:145], v16 offset:23552
	global_load_lds_dwordx4 v[146:147], off
	v_lshl_add_u64 v[146:147], v[216:217], 0, s[12:13]
	s_mov_b32 m0, s39
	s_nop 0
	global_load_lds_dwordx4 v[146:147], off
	s_barrier
	s_waitcnt lgkmcnt(0)
	s_waitcnt lgkmcnt(0)
	v_mfma_f32_16x16x32_bf16 v[146:149], v[18:21], v[62:65], 0
	v_mfma_f32_16x16x32_bf16 v[154:157], v[18:21], v[122:125], 0
	v_mfma_f32_16x16x32_bf16 v[162:165], v[18:21], v[130:133], 0
	v_mfma_f32_16x16x32_bf16 v[18:21], v[18:21], v[138:141], 0
	v_mfma_f32_16x16x32_bf16 v[146:149], v[22:25], v[118:121], v[146:149]
	v_mfma_f32_16x16x32_bf16 v[150:153], v[26:29], v[62:65], 0
	v_mfma_f32_16x16x32_bf16 v[154:157], v[22:25], v[126:129], v[154:157]
	v_mfma_f32_16x16x32_bf16 v[158:161], v[26:29], v[122:125], 0
	v_mfma_f32_16x16x32_bf16 v[162:165], v[22:25], v[134:137], v[162:165]
	v_mfma_f32_16x16x32_bf16 v[166:169], v[26:29], v[130:133], 0
	v_mfma_f32_16x16x32_bf16 v[18:21], v[22:25], v[142:145], v[18:21]
	v_mfma_f32_16x16x32_bf16 v[22:25], v[26:29], v[138:141], 0
	v_mfma_f32_16x16x32_bf16 v[150:153], v[30:33], v[118:121], v[150:153]
	v_mfma_f32_16x16x32_bf16 v[158:161], v[30:33], v[126:129], v[158:161]
	v_mfma_f32_16x16x32_bf16 v[166:169], v[30:33], v[134:137], v[166:169]
	v_mfma_f32_16x16x32_bf16 v[22:25], v[30:33], v[142:145], v[22:25]
	s_barrier
; #define PG8_STAGE(bufoff, gbase, voff) do { _Pragma("unroll") for (int _i = 0; _i < 2; ++_i) \
;         __builtin_amdgcn_global_load_lds((const unsigned*)((const char*)(gbase) + (voff)[_i]), (LAS unsigned*)(lds + (bufoff) + ldsw + _i * 8192), 16, 0, 0); } while (0)
; #define PG8_LDA(dst, b, h) do { _Pragma("unroll") for (int m = 0; m < 4; ++m) _Pragma("unroll") for (int k = 0; k < 2; ++k) dst[m][k] = *(const LAS bf16x8*)(lds + PG8_SA(b, h) + aoff + m * 2048 + k * 1024); } while (0)
; #define PG8_LDB(dst, b, h) do { _Pragma("unroll") for (int n = 0; n < 2; ++n) _Pragma("unroll") for (int k = 0; k < 2; ++k) dst[n][k] = *(const LAS bf16x8*)(lds + PG8_SB(b, h) + boff + n * 2048 + k * 1024); } while (0)
; #define PG8_WAIT_V(n) asm volatile("s_waitcnt vmcnt(" #n ")" ::: "memory")
; #define PG8_WAIT_L(n) asm volatile("s_waitcnt lgkmcnt(" #n ")" ::: "memory")
; #define PG8_BAR __builtin_amdgcn_s_barrier()
; #define PG8_SCHED __builtin_amdgcn_sched_barrier(0)
; template <class Epi>
; __device__ __forceinline__ void gemm_phase(LAS unsigned char* lds, const Gemm g, const StaticOrder& S, const Epi& E, int wv) {
;     ...
;             PG8_LDB(B0, 0, 0); PG8_SCHED; PG8_LDA(At, 0, 0); PG8_STAGE(PG8_SA(1, 1), a1 + hstepA, voffA);
;             PG8_WAIT_L(8); PG8_BAR; PG8_WAIT_L(0); PG8_MMA(0, 0, At, B0); PG8_BAR; PG8_SCHED;
;             PG8_LDB(B1, 0, 1); PG8_STAGE(PG8_SB(0, 0), b2, voffB);
;             PG8_BAR; PG8_WAIT_L(0); PG8_MMA(0, 1, At, B1); PG8_BAR;
;             PG8_LDA(At, 0, 1); PG8_STAGE(PG8_SA(0, 0), a2, voffA);
;             PG8_BAR; PG8_WAIT_L(0); PG8_MMA(1, 0, At, B0); PG8_BAR; PG8_SCHED;
;             PG8_STAGE(PG8_SB(0, 1), b2 + hstepB, voffB);
;             PG8_WAIT_V(6); PG8_BAR; PG8_MMA(1, 1, At, B1); PG8_BAR;
;             PG8_LDB(B0, 1, 0); PG8_SCHED; PG8_LDA(At, 1, 0); PG8_STAGE(PG8_SA(0, 1), a2 + hstepA, voffA);
;             PG8_WAIT_L(8); PG8_BAR; PG8_WAIT_L(0); PG8_MMA(0, 0, At, B0); PG8_BAR; PG8_SCHED;
;             PG8_LDB(B1, 1, 1); PG8_STAGE(PG8_SB(1, 0), b3, voffB);
;             PG8_BAR; PG8_WAIT_L(0); PG8_MMA(0, 1, At, B1); PG8_BAR;
;             PG8_LDA(At, 1, 1); PG8_STAGE(PG8_SA(1, 0), a3, voffA);
;             PG8_BAR; PG8_WAIT_L(0); PG8_MMA(1, 0, At, B0); PG8_BAR; PG8_SCHED;
;             PG8_STAGE(PG8_SB(1, 1), b3 + hstepB, voffB);
;             PG8_WAIT_V(6); PG8_BAR; PG8_MMA(1, 1, At, B1); PG8_BAR;
	s_add_u32 s72, s50, 0x10100
	s_addc_u32 s73, s51, 0
	s_add_i32 s70, s63, s25
	v_lshl_add_u64 v[26:27], s[72:73], 0, v[2:3]
	s_mov_b32 m0, s70
	s_add_i32 s43, s70, 0x2000
	global_load_lds_dwordx4 v[26:27], off
	v_lshl_add_u64 v[26:27], s[72:73], 0, v[6:7]
	s_mov_b32 m0, s43
	s_nop 0
	global_load_lds_dwordx4 v[26:27], off
	s_waitcnt vmcnt(6)
	s_barrier
	v_mfma_f32_16x16x32_bf16 v[26:29], v[98:101], v[62:65], 0
	v_mfma_f32_16x16x32_bf16 v[30:33], v[106:109], v[62:65], 0
	v_mfma_f32_16x16x32_bf16 v[26:29], v[102:105], v[118:121], v[26:29]
	v_mfma_f32_16x16x32_bf16 v[30:33], v[110:113], v[118:121], v[30:33]
	v_mfma_f32_16x16x32_bf16 v[62:65], v[98:101], v[122:125], 0
	v_mfma_f32_16x16x32_bf16 v[118:121], v[106:109], v[122:125], 0
	v_mfma_f32_16x16x32_bf16 v[122:125], v[98:101], v[130:133], 0
	v_mfma_f32_16x16x32_bf16 v[98:101], v[98:101], v[138:141], 0
	v_mfma_f32_16x16x32_bf16 v[62:65], v[102:105], v[126:129], v[62:65]
	v_mfma_f32_16x16x32_bf16 v[118:121], v[110:113], v[126:129], v[118:121]
	v_mfma_f32_16x16x32_bf16 v[122:125], v[102:105], v[134:137], v[122:125]
	v_mfma_f32_16x16x32_bf16 v[126:129], v[106:109], v[130:133], 0
	v_mfma_f32_16x16x32_bf16 v[98:101], v[102:105], v[142:145], v[98:101]
	v_mfma_f32_16x16x32_bf16 v[102:105], v[106:109], v[138:141], 0
	v_mfma_f32_16x16x32_bf16 v[126:129], v[110:113], v[134:137], v[126:129]
	v_mfma_f32_16x16x32_bf16 v[102:105], v[110:113], v[142:145], v[102:105]
	s_add_i32 s71, 0, 0x18000
	v_add_u32_e32 v218, s71, v13
	s_barrier
	ds_read_b128 v[106:109], v218
	ds_read_b128 v[110:113], v218 offset:1024
	ds_read_b128 v[130:133], v218 offset:2048
	ds_read_b128 v[134:137], v218 offset:3072
	s_add_u32 s72, s48, 0x10100
	s_addc_u32 s73, s49, 0
	s_mov_b32 m0, s56
	v_lshl_add_u64 v[194:195], s[72:73], 0, v[0:1]
	ds_read_b128 v[138:141], v16 offset:32768
	ds_read_b128 v[142:145], v16 offset:33792
	ds_read_b128 v[170:173], v16 offset:34816
	ds_read_b128 v[174:177], v16 offset:35840
	ds_read_b128 v[178:181], v16 offset:36864
	ds_read_b128 v[182:185], v16 offset:37888
	ds_read_b128 v[186:189], v16 offset:38912
	ds_read_b128 v[190:193], v16 offset:39936
	global_load_lds_dwordx4 v[194:195], off
	v_lshl_add_u64 v[194:195], s[72:73], 0, v[4:5]
	s_mov_b32 m0, s57
	s_nop 0
	global_load_lds_dwordx4 v[194:195], off
	s_waitcnt lgkmcnt(8)
	s_barrier
	s_waitcnt lgkmcnt(0)
	s_waitcnt lgkmcnt(0)
	v_mfma_f32_16x16x32_bf16 v[66:69], v[106:109], v[138:141], v[66:69]
	v_mfma_f32_16x16x32_bf16 v[70:73], v[130:133], v[138:141], v[70:73]
	v_mfma_f32_16x16x32_bf16 v[74:77], v[106:109], v[170:173], v[74:77]
	v_mfma_f32_16x16x32_bf16 v[78:81], v[130:133], v[170:173], v[78:81]
	v_mfma_f32_16x16x32_bf16 v[82:85], v[106:109], v[178:181], v[82:85]
	v_mfma_f32_16x16x32_bf16 v[86:89], v[130:133], v[178:181], v[86:89]
	v_mfma_f32_16x16x32_bf16 v[90:93], v[106:109], v[186:189], v[90:93]
	v_mfma_f32_16x16x32_bf16 v[94:97], v[130:133], v[186:189], v[94:97]
	v_mfma_f32_16x16x32_bf16 v[66:69], v[110:113], v[142:145], v[66:69]
	v_mfma_f32_16x16x32_bf16 v[70:73], v[134:137], v[142:145], v[70:73]
	v_mfma_f32_16x16x32_bf16 v[74:77], v[110:113], v[174:177], v[74:77]
	v_mfma_f32_16x16x32_bf16 v[78:81], v[134:137], v[174:177], v[78:81]
	v_mfma_f32_16x16x32_bf16 v[82:85], v[110:113], v[182:185], v[82:85]
	v_mfma_f32_16x16x32_bf16 v[86:89], v[134:137], v[182:185], v[86:89]
	v_mfma_f32_16x16x32_bf16 v[90:93], v[110:113], v[190:193], v[90:93]
	v_mfma_f32_16x16x32_bf16 v[94:97], v[134:137], v[190:193], v[94:97]
	s_barrier
	s_add_i32 s73, 0, 0x1c000
	s_add_i32 s72, s71, s25
	v_add_u32_e32 v219, s73, v13
	v_lshl_add_u64 v[210:211], v[210:211], 0, s[14:15]
	s_mov_b32 m0, s72
	s_add_i32 s71, s72, 0x2000
	ds_read_b128 v[194:197], v219
	ds_read_b128 v[198:201], v219 offset:1024
	ds_read_b128 v[202:205], v219 offset:2048
	ds_read_b128 v[206:209], v219 offset:3072
	global_load_lds_dwordx4 v[210:211], off
	v_lshl_add_u64 v[210:211], v[212:213], 0, s[14:15]
	s_mov_b32 m0, s71
	s_nop 0
	global_load_lds_dwordx4 v[210:211], off
	s_barrier
	s_waitcnt lgkmcnt(0)
	s_waitcnt lgkmcnt(0)
	v_mfma_f32_16x16x32_bf16 v[114:117], v[194:197], v[138:141], v[114:117]
	v_mfma_f32_16x16x32_bf16 v[34:37], v[202:205], v[138:141], v[34:37]
	v_mfma_f32_16x16x32_bf16 v[38:41], v[194:197], v[170:173], v[38:41]
	v_mfma_f32_16x16x32_bf16 v[42:45], v[202:205], v[170:173], v[42:45]
	v_mfma_f32_16x16x32_bf16 v[46:49], v[194:197], v[178:181], v[46:49]
	v_mfma_f32_16x16x32_bf16 v[50:53], v[202:205], v[178:181], v[50:53]
	v_mfma_f32_16x16x32_bf16 v[54:57], v[194:197], v[186:189], v[54:57]
	v_mfma_f32_16x16x32_bf16 v[58:61], v[202:205], v[186:189], v[58:61]
	v_mfma_f32_16x16x32_bf16 v[114:117], v[198:201], v[142:145], v[114:117]
	v_mfma_f32_16x16x32_bf16 v[34:37], v[206:209], v[142:145], v[34:37]
	v_mfma_f32_16x16x32_bf16 v[38:41], v[198:201], v[174:177], v[38:41]
	v_mfma_f32_16x16x32_bf16 v[42:45], v[206:209], v[174:177], v[42:45]
	v_mfma_f32_16x16x32_bf16 v[46:49], v[198:201], v[182:185], v[46:49]
	v_mfma_f32_16x16x32_bf16 v[50:53], v[206:209], v[182:185], v[50:53]
	v_mfma_f32_16x16x32_bf16 v[54:57], v[198:201], v[190:193], v[54:57]
	v_mfma_f32_16x16x32_bf16 v[58:61], v[206:209], v[190:193], v[58:61]
	s_mov_b32 m0, s58
	v_lshl_add_u64 v[210:211], v[214:215], 0, s[14:15]
	s_barrier
	ds_read_b128 v[138:141], v16 offset:49152
	ds_read_b128 v[142:145], v16 offset:50176
	ds_read_b128 v[170:173], v16 offset:51200
	ds_read_b128 v[174:177], v16 offset:52224
	ds_read_b128 v[178:181], v16 offset:53248
	ds_read_b128 v[182:185], v16 offset:54272
	ds_read_b128 v[186:189], v16 offset:55296
	ds_read_b128 v[190:193], v16 offset:56320
	global_load_lds_dwordx4 v[210:211], off
	v_lshl_add_u64 v[210:211], v[216:217], 0, s[14:15]
	s_mov_b32 m0, s59
	s_nop 0
	global_load_lds_dwordx4 v[210:211], off
	s_barrier
; #define PG8_STAGE(bufoff, gbase, voff) do { _Pragma("unroll") for (int _i = 0; _i < 2; ++_i) \
;         __builtin_amdgcn_global_load_lds((const unsigned*)((const char*)(gbase) + (voff)[_i]), (LAS unsigned*)(lds + (bufoff) + ldsw + _i * 8192), 16, 0, 0); } while (0)
; #define PG8_LDA(dst, b, h) do { _Pragma("unroll") for (int m = 0; m < 4; ++m) _Pragma("unroll") for (int k = 0; k < 2; ++k) dst[m][k] = *(const LAS bf16x8*)(lds + PG8_SA(b, h) + aoff + m * 2048 + k * 1024); } while (0)
; #define PG8_LDB(dst, b, h) do { _Pragma("unroll") for (int n = 0; n < 2; ++n) _Pragma("unroll") for (int k = 0; k < 2; ++k) dst[n][k] = *(const LAS bf16x8*)(lds + PG8_SB(b, h) + boff + n * 2048 + k * 1024); } while (0)
; #define PG8_WAIT_V(n) asm volatile("s_waitcnt vmcnt(" #n ")" ::: "memory")
; #define PG8_WAIT_L(n) asm volatile("s_waitcnt lgkmcnt(" #n ")" ::: "memory")
; #define PG8_BAR __builtin_amdgcn_s_barrier()
; #define PG8_SCHED __builtin_amdgcn_sched_barrier(0)
; template <class Epi>
; __device__ __forceinline__ void gemm_phase(LAS unsigned char* lds, const Gemm g, const StaticOrder& S, const Epi& E, int wv) {
;     ...
;             PG8_LDB(B0, 0, 0); PG8_SCHED; PG8_LDA(At, 0, 0); PG8_STAGE(PG8_SA(1, 1), a1 + hstepA, voffA);
;             PG8_WAIT_L(8); PG8_BAR; PG8_WAIT_L(0); PG8_MMA(0, 0, At, B0); PG8_BAR; PG8_SCHED;
;             PG8_LDB(B1, 0, 1); PG8_STAGE(PG8_SB(0, 0), b2, voffB);
;             PG8_BAR; PG8_WAIT_L(0); PG8_MMA(0, 1, At, B1); PG8_BAR;
;             PG8_LDA(At, 0, 1); PG8_STAGE(PG8_SA(0, 0), a2, voffA);
;             PG8_BAR; PG8_WAIT_L(0); PG8_MMA(1, 0, At, B0); PG8_BAR; PG8_SCHED;
;             PG8_STAGE(PG8_SB(0, 1), b2 + hstepB, voffB);
;             PG8_WAIT_V(6); PG8_BAR; PG8_MMA(1, 1, At, B1); PG8_BAR;
;             PG8_LDB(B0, 1, 0); PG8_SCHED; PG8_LDA(At, 1, 0); PG8_STAGE(PG8_SA(0, 1), a2 + hstepA, voffA);
;             PG8_WAIT_L(8); PG8_BAR; PG8_WAIT_L(0); PG8_MMA(0, 0, At, B0); PG8_BAR; PG8_SCHED;
;             PG8_LDB(B1, 1, 1); PG8_STAGE(PG8_SB(1, 0), b3, voffB);
;             PG8_BAR; PG8_WAIT_L(0); PG8_MMA(0, 1, At, B1); PG8_BAR;
;             PG8_LDA(At, 1, 1); PG8_STAGE(PG8_SA(1, 0), a3, voffA);
;             PG8_BAR; PG8_WAIT_L(0); PG8_MMA(1, 0, At, B0); PG8_BAR; PG8_SCHED;
;             PG8_STAGE(PG8_SB(1, 1), b3 + hstepB, voffB);
;             PG8_WAIT_V(6); PG8_BAR; PG8_MMA(1, 1, At, B1); PG8_BAR;
	s_waitcnt lgkmcnt(0)
	s_waitcnt lgkmcnt(0)
	v_mfma_f32_16x16x32_bf16 v[146:149], v[106:109], v[138:141], v[146:149]
	v_mfma_f32_16x16x32_bf16 v[150:153], v[130:133], v[138:141], v[150:153]
	v_mfma_f32_16x16x32_bf16 v[154:157], v[106:109], v[170:173], v[154:157]
	v_mfma_f32_16x16x32_bf16 v[158:161], v[130:133], v[170:173], v[158:161]
	v_mfma_f32_16x16x32_bf16 v[162:165], v[106:109], v[178:181], v[162:165]
	v_mfma_f32_16x16x32_bf16 v[166:169], v[130:133], v[178:181], v[166:169]
	v_mfma_f32_16x16x32_bf16 v[18:21], v[106:109], v[186:189], v[18:21]
	v_mfma_f32_16x16x32_bf16 v[22:25], v[130:133], v[186:189], v[22:25]
	v_mfma_f32_16x16x32_bf16 v[146:149], v[110:113], v[142:145], v[146:149]
	v_mfma_f32_16x16x32_bf16 v[150:153], v[134:137], v[142:145], v[150:153]
	v_mfma_f32_16x16x32_bf16 v[154:157], v[110:113], v[174:177], v[154:157]
	v_mfma_f32_16x16x32_bf16 v[158:161], v[134:137], v[174:177], v[158:161]
	v_mfma_f32_16x16x32_bf16 v[162:165], v[110:113], v[182:185], v[162:165]
	v_mfma_f32_16x16x32_bf16 v[166:169], v[134:137], v[182:185], v[166:169]
	v_mfma_f32_16x16x32_bf16 v[18:21], v[110:113], v[190:193], v[18:21]
	v_mfma_f32_16x16x32_bf16 v[22:25], v[134:137], v[190:193], v[22:25]
	s_barrier
	s_add_u32 s74, s50, 0x10180
	s_addc_u32 s75, s51, 0
	s_add_i32 s51, s73, s25
	v_lshl_add_u64 v[106:107], s[74:75], 0, v[2:3]
	s_mov_b32 m0, s51
	s_add_i32 s50, s51, 0x2000
	global_load_lds_dwordx4 v[106:107], off
	v_lshl_add_u64 v[106:107], s[74:75], 0, v[6:7]
	s_mov_b32 m0, s50
	s_nop 0
	global_load_lds_dwordx4 v[106:107], off
	s_waitcnt vmcnt(6)
	s_barrier
	v_mfma_f32_16x16x32_bf16 v[26:29], v[194:197], v[138:141], v[26:29]
	v_mfma_f32_16x16x32_bf16 v[30:33], v[202:205], v[138:141], v[30:33]
	v_mfma_f32_16x16x32_bf16 v[62:65], v[194:197], v[170:173], v[62:65]
	v_mfma_f32_16x16x32_bf16 v[106:109], v[202:205], v[170:173], v[118:121]
	v_mfma_f32_16x16x32_bf16 v[110:113], v[194:197], v[178:181], v[122:125]
	v_mfma_f32_16x16x32_bf16 v[118:121], v[202:205], v[178:181], v[126:129]
	v_mfma_f32_16x16x32_bf16 v[98:101], v[194:197], v[186:189], v[98:101]
	v_mfma_f32_16x16x32_bf16 v[102:105], v[202:205], v[186:189], v[102:105]
	v_mfma_f32_16x16x32_bf16 v[26:29], v[198:201], v[142:145], v[26:29]
	v_mfma_f32_16x16x32_bf16 v[30:33], v[206:209], v[142:145], v[30:33]
	v_mfma_f32_16x16x32_bf16 v[62:65], v[198:201], v[174:177], v[62:65]
	v_mfma_f32_16x16x32_bf16 v[106:109], v[206:209], v[174:177], v[106:109]
	v_mfma_f32_16x16x32_bf16 v[110:113], v[198:201], v[182:185], v[110:113]
	v_mfma_f32_16x16x32_bf16 v[118:121], v[206:209], v[182:185], v[118:121]
	v_mfma_f32_16x16x32_bf16 v[98:101], v[198:201], v[190:193], v[98:101]
	v_mfma_f32_16x16x32_bf16 v[102:105], v[206:209], v[190:193], v[102:105]
	s_barrier
	ds_read_b128 v[122:125], v15
	ds_read_b128 v[126:129], v15 offset:1024
	ds_read_b128 v[130:133], v15 offset:2048
	ds_read_b128 v[134:137], v15 offset:3072
	s_add_u32 s48, s48, 0x10180
	s_addc_u32 s49, s49, 0
	s_mov_b32 m0, s61
	v_lshl_add_u64 v[194:195], s[48:49], 0, v[0:1]
	ds_read_b128 v[138:141], v16
	ds_read_b128 v[142:145], v16 offset:1024
	ds_read_b128 v[170:173], v16 offset:2048
	ds_read_b128 v[174:177], v16 offset:3072
	ds_read_b128 v[178:181], v16 offset:4096
	ds_read_b128 v[182:185], v16 offset:5120
	ds_read_b128 v[186:189], v16 offset:6144
	ds_read_b128 v[190:193], v16 offset:7168
	global_load_lds_dwordx4 v[194:195], off
	v_lshl_add_u64 v[194:195], s[48:49], 0, v[4:5]
	s_mov_b32 m0, s62
	s_nop 0
	global_load_lds_dwordx4 v[194:195], off
	s_waitcnt lgkmcnt(8)
	s_barrier
	s_waitcnt lgkmcnt(0)
	s_waitcnt lgkmcnt(0)
	v_mfma_f32_16x16x32_bf16 v[66:69], v[122:125], v[138:141], v[66:69]
	v_mfma_f32_16x16x32_bf16 v[70:73], v[130:133], v[138:141], v[70:73]
	v_mfma_f32_16x16x32_bf16 v[74:77], v[122:125], v[170:173], v[74:77]
	v_mfma_f32_16x16x32_bf16 v[78:81], v[130:133], v[170:173], v[78:81]
	v_mfma_f32_16x16x32_bf16 v[82:85], v[122:125], v[178:181], v[82:85]
	v_mfma_f32_16x16x32_bf16 v[86:89], v[130:133], v[178:181], v[86:89]
	v_mfma_f32_16x16x32_bf16 v[90:93], v[122:125], v[186:189], v[90:93]
	v_mfma_f32_16x16x32_bf16 v[94:97], v[130:133], v[186:189], v[94:97]
	v_mfma_f32_16x16x32_bf16 v[66:69], v[126:129], v[142:145], v[66:69]
	v_mfma_f32_16x16x32_bf16 v[70:73], v[134:137], v[142:145], v[70:73]
	v_mfma_f32_16x16x32_bf16 v[74:77], v[126:129], v[174:177], v[74:77]
	v_mfma_f32_16x16x32_bf16 v[78:81], v[134:137], v[174:177], v[78:81]
	v_mfma_f32_16x16x32_bf16 v[82:85], v[126:129], v[182:185], v[82:85]
	v_mfma_f32_16x16x32_bf16 v[86:89], v[134:137], v[182:185], v[86:89]
	v_mfma_f32_16x16x32_bf16 v[90:93], v[126:129], v[190:193], v[90:93]
	v_mfma_f32_16x16x32_bf16 v[94:97], v[134:137], v[190:193], v[94:97]
	s_barrier
	s_mov_b32 m0, s69
	v_lshl_add_u64 v[210:211], s[52:53], 0, v[2:3]
	ds_read_b128 v[194:197], v17
	ds_read_b128 v[198:201], v17 offset:1024
	ds_read_b128 v[202:205], v17 offset:2048
	ds_read_b128 v[206:209], v17 offset:3072
	global_load_lds_dwordx4 v[210:211], off
	v_lshl_add_u64 v[212:213], s[52:53], 0, v[6:7]
	s_mov_b32 m0, s41
	s_nop 0
	global_load_lds_dwordx4 v[212:213], off
	s_barrier
; #define PG8_STAGE(bufoff, gbase, voff) do { _Pragma("unroll") for (int _i = 0; _i < 2; ++_i) \
;         __builtin_amdgcn_global_load_lds((const unsigned*)((const char*)(gbase) + (voff)[_i]), (LAS unsigned*)(lds + (bufoff) + ldsw + _i * 8192), 16, 0, 0); } while (0)
; #define PG8_LDA(dst, b, h) do { _Pragma("unroll") for (int m = 0; m < 4; ++m) _Pragma("unroll") for (int k = 0; k < 2; ++k) dst[m][k] = *(const LAS bf16x8*)(lds + PG8_SA(b, h) + aoff + m * 2048 + k * 1024); } while (0)
; #define PG8_LDB(dst, b, h) do { _Pragma("unroll") for (int n = 0; n < 2; ++n) _Pragma("unroll") for (int k = 0; k < 2; ++k) dst[n][k] = *(const LAS bf16x8*)(lds + PG8_SB(b, h) + boff + n * 2048 + k * 1024); } while (0)
; #define PG8_WAIT_V(n) asm volatile("s_waitcnt vmcnt(" #n ")" ::: "memory")
; #define PG8_WAIT_L(n) asm volatile("s_waitcnt lgkmcnt(" #n ")" ::: "memory")
; #define PG8_BAR __builtin_amdgcn_s_barrier()
; #define PG8_SCHED __builtin_amdgcn_sched_barrier(0)
; template <class Epi>
; __device__ __forceinline__ void gemm_phase(LAS unsigned char* lds, const Gemm g, const StaticOrder& S, const Epi& E, int wv) {
;     ...
;             PG8_LDB(B0, 0, 0); PG8_SCHED; PG8_LDA(At, 0, 0); PG8_STAGE(PG8_SA(1, 1), a1 + hstepA, voffA);
;             PG8_WAIT_L(8); PG8_BAR; PG8_WAIT_L(0); PG8_MMA(0, 0, At, B0); PG8_BAR; PG8_SCHED;
;             PG8_LDB(B1, 0, 1); PG8_STAGE(PG8_SB(0, 0), b2, voffB);
;             PG8_BAR; PG8_WAIT_L(0); PG8_MMA(0, 1, At, B1); PG8_BAR;
;             PG8_LDA(At, 0, 1); PG8_STAGE(PG8_SA(0, 0), a2, voffA);
;             PG8_BAR; PG8_WAIT_L(0); PG8_MMA(1, 0, At, B0); PG8_BAR; PG8_SCHED;
;             PG8_STAGE(PG8_SB(0, 1), b2 + hstepB, voffB);
;             PG8_WAIT_V(6); PG8_BAR; PG8_MMA(1, 1, At, B1); PG8_BAR;
;             PG8_LDB(B0, 1, 0); PG8_SCHED; PG8_LDA(At, 1, 0); PG8_STAGE(PG8_SA(0, 1), a2 + hstepA, voffA);
;             PG8_WAIT_L(8); PG8_BAR; PG8_WAIT_L(0); PG8_MMA(0, 0, At, B0); PG8_BAR; PG8_SCHED;
;             PG8_LDB(B1, 1, 1); PG8_STAGE(PG8_SB(1, 0), b3, voffB);
;             PG8_BAR; PG8_WAIT_L(0); PG8_MMA(0, 1, At, B1); PG8_BAR;
;             PG8_LDA(At, 1, 1); PG8_STAGE(PG8_SA(1, 0), a3, voffA);
;             PG8_BAR; PG8_WAIT_L(0); PG8_MMA(1, 0, At, B0); PG8_BAR; PG8_SCHED;
;             PG8_STAGE(PG8_SB(1, 1), b3 + hstepB, voffB);
;             PG8_WAIT_V(6); PG8_BAR; PG8_MMA(1, 1, At, B1); PG8_BAR;
	s_waitcnt lgkmcnt(0)
	s_waitcnt lgkmcnt(0)
	v_mfma_f32_16x16x32_bf16 v[114:117], v[194:197], v[138:141], v[114:117]
	v_mfma_f32_16x16x32_bf16 v[34:37], v[202:205], v[138:141], v[34:37]
	v_mfma_f32_16x16x32_bf16 v[38:41], v[194:197], v[170:173], v[38:41]
	v_mfma_f32_16x16x32_bf16 v[42:45], v[202:205], v[170:173], v[42:45]
	v_mfma_f32_16x16x32_bf16 v[46:49], v[194:197], v[178:181], v[46:49]
	v_mfma_f32_16x16x32_bf16 v[50:53], v[202:205], v[178:181], v[50:53]
	v_mfma_f32_16x16x32_bf16 v[54:57], v[194:197], v[186:189], v[54:57]
	v_mfma_f32_16x16x32_bf16 v[58:61], v[202:205], v[186:189], v[58:61]
	v_mfma_f32_16x16x32_bf16 v[114:117], v[198:201], v[142:145], v[114:117]
	v_mfma_f32_16x16x32_bf16 v[34:37], v[206:209], v[142:145], v[34:37]
	v_mfma_f32_16x16x32_bf16 v[38:41], v[198:201], v[174:177], v[38:41]
	v_mfma_f32_16x16x32_bf16 v[42:45], v[206:209], v[174:177], v[42:45]
	v_mfma_f32_16x16x32_bf16 v[46:49], v[198:201], v[182:185], v[46:49]
	v_mfma_f32_16x16x32_bf16 v[50:53], v[206:209], v[182:185], v[50:53]
	v_mfma_f32_16x16x32_bf16 v[54:57], v[198:201], v[190:193], v[54:57]
	v_mfma_f32_16x16x32_bf16 v[58:61], v[206:209], v[190:193], v[58:61]
	s_mov_b32 m0, s33
	v_lshl_add_u64 v[214:215], s[54:55], 0, v[0:1]
	s_barrier
	ds_read_b128 v[138:141], v16 offset:16384
	ds_read_b128 v[142:145], v16 offset:17408
	ds_read_b128 v[170:173], v16 offset:18432
	ds_read_b128 v[174:177], v16 offset:19456
	ds_read_b128 v[178:181], v16 offset:20480
	ds_read_b128 v[182:185], v16 offset:21504
	ds_read_b128 v[186:189], v16 offset:22528
	ds_read_b128 v[190:193], v16 offset:23552
	global_load_lds_dwordx4 v[214:215], off
	v_lshl_add_u64 v[216:217], s[54:55], 0, v[4:5]
	s_mov_b32 m0, s39
	s_nop 0
	global_load_lds_dwordx4 v[216:217], off
	s_barrier
	s_waitcnt lgkmcnt(0)
	s_waitcnt lgkmcnt(0)
	v_mfma_f32_16x16x32_bf16 v[146:149], v[122:125], v[138:141], v[146:149]
	v_mfma_f32_16x16x32_bf16 v[150:153], v[130:133], v[138:141], v[150:153]
	v_mfma_f32_16x16x32_bf16 v[154:157], v[122:125], v[170:173], v[154:157]
	v_mfma_f32_16x16x32_bf16 v[158:161], v[130:133], v[170:173], v[158:161]
	v_mfma_f32_16x16x32_bf16 v[162:165], v[122:125], v[178:181], v[162:165]
	v_mfma_f32_16x16x32_bf16 v[166:169], v[130:133], v[178:181], v[166:169]
	v_mfma_f32_16x16x32_bf16 v[18:21], v[122:125], v[186:189], v[18:21]
	v_mfma_f32_16x16x32_bf16 v[22:25], v[130:133], v[186:189], v[22:25]
	v_mfma_f32_16x16x32_bf16 v[146:149], v[126:129], v[142:145], v[146:149]
	v_mfma_f32_16x16x32_bf16 v[150:153], v[134:137], v[142:145], v[150:153]
	v_mfma_f32_16x16x32_bf16 v[154:157], v[126:129], v[174:177], v[154:157]
	v_mfma_f32_16x16x32_bf16 v[158:161], v[134:137], v[174:177], v[158:161]
	v_mfma_f32_16x16x32_bf16 v[162:165], v[126:129], v[182:185], v[162:165]
	v_mfma_f32_16x16x32_bf16 v[166:169], v[134:137], v[182:185], v[166:169]
	v_mfma_f32_16x16x32_bf16 v[18:21], v[126:129], v[190:193], v[18:21]
	v_mfma_f32_16x16x32_bf16 v[22:25], v[134:137], v[190:193], v[22:25]
	s_barrier
	s_add_u32 s48, s52, 0x10000
	s_addc_u32 s49, s53, 0
	s_mov_b32 m0, s70
	v_lshl_add_u64 v[122:123], s[48:49], 0, v[2:3]
	global_load_lds_dwordx4 v[122:123], off
	v_lshl_add_u64 v[122:123], s[48:49], 0, v[6:7]
	s_mov_b32 m0, s43
	s_nop 0
	global_load_lds_dwordx4 v[122:123], off
	s_waitcnt vmcnt(6)
	s_barrier
	v_mfma_f32_16x16x32_bf16 v[26:29], v[194:197], v[138:141], v[26:29]
	v_mfma_f32_16x16x32_bf16 v[30:33], v[202:205], v[138:141], v[30:33]
	v_mfma_f32_16x16x32_bf16 v[62:65], v[194:197], v[170:173], v[62:65]
	v_mfma_f32_16x16x32_bf16 v[106:109], v[202:205], v[170:173], v[106:109]
	v_mfma_f32_16x16x32_bf16 v[110:113], v[194:197], v[178:181], v[110:113]
	v_mfma_f32_16x16x32_bf16 v[118:121], v[202:205], v[178:181], v[118:121]
	v_mfma_f32_16x16x32_bf16 v[98:101], v[194:197], v[186:189], v[98:101]
	v_mfma_f32_16x16x32_bf16 v[102:105], v[202:205], v[186:189], v[102:105]
	v_mfma_f32_16x16x32_bf16 v[26:29], v[198:201], v[142:145], v[26:29]
	v_mfma_f32_16x16x32_bf16 v[30:33], v[206:209], v[142:145], v[30:33]
	v_mfma_f32_16x16x32_bf16 v[62:65], v[198:201], v[174:177], v[62:65]
	v_mfma_f32_16x16x32_bf16 v[106:109], v[206:209], v[174:177], v[106:109]
	v_mfma_f32_16x16x32_bf16 v[110:113], v[198:201], v[182:185], v[110:113]
	v_mfma_f32_16x16x32_bf16 v[118:121], v[206:209], v[182:185], v[118:121]
	v_mfma_f32_16x16x32_bf16 v[98:101], v[198:201], v[190:193], v[98:101]
	v_mfma_f32_16x16x32_bf16 v[102:105], v[206:209], v[190:193], v[102:105]
	s_barrier
	ds_read_b128 v[122:125], v218
	ds_read_b128 v[126:129], v218 offset:1024
	ds_read_b128 v[130:133], v218 offset:2048
	ds_read_b128 v[134:137], v218 offset:3072
	s_add_u32 s48, s54, 0x10000
	s_addc_u32 s49, s55, 0
	s_mov_b32 m0, s56
	v_lshl_add_u64 v[194:195], s[48:49], 0, v[0:1]
	ds_read_b128 v[138:141], v16 offset:32768
	ds_read_b128 v[142:145], v16 offset:33792
	ds_read_b128 v[170:173], v16 offset:34816
	ds_read_b128 v[174:177], v16 offset:35840
	ds_read_b128 v[178:181], v16 offset:36864
	ds_read_b128 v[182:185], v16 offset:37888
	ds_read_b128 v[186:189], v16 offset:38912
	ds_read_b128 v[190:193], v16 offset:39936
	global_load_lds_dwordx4 v[194:195], off
	v_lshl_add_u64 v[194:195], s[48:49], 0, v[4:5]
	s_mov_b32 m0, s57
	s_nop 0
	global_load_lds_dwordx4 v[194:195], off
	s_waitcnt lgkmcnt(8)
	s_barrier
; #define PG8_STAGE(bufoff, gbase, voff) do { _Pragma("unroll") for (int _i = 0; _i < 2; ++_i) \
;         __builtin_amdgcn_global_load_lds((const unsigned*)((const char*)(gbase) + (voff)[_i]), (LAS unsigned*)(lds + (bufoff) + ldsw + _i * 8192), 16, 0, 0); } while (0)
; #define PG8_LDA(dst, b, h) do { _Pragma("unroll") for (int m = 0; m < 4; ++m) _Pragma("unroll") for (int k = 0; k < 2; ++k) dst[m][k] = *(const LAS bf16x8*)(lds + PG8_SA(b, h) + aoff + m * 2048 + k * 1024); } while (0)
; #define PG8_LDB(dst, b, h) do { _Pragma("unroll") for (int n = 0; n < 2; ++n) _Pragma("unroll") for (int k = 0; k < 2; ++k) dst[n][k] = *(const LAS bf16x8*)(lds + PG8_SB(b, h) + boff + n * 2048 + k * 1024); } while (0)
; #define PG8_WAIT_V(n) asm volatile("s_waitcnt vmcnt(" #n ")" ::: "memory")
; #define PG8_WAIT_L(n) asm volatile("s_waitcnt lgkmcnt(" #n ")" ::: "memory")
; #define PG8_BAR __builtin_amdgcn_s_barrier()
; #define PG8_SCHED __builtin_amdgcn_sched_barrier(0)
; template <class Epi>
; __device__ __forceinline__ void gemm_phase(LAS unsigned char* lds, const Gemm g, const StaticOrder& S, const Epi& E, int wv) {
;     ...
;             PG8_LDB(B0, 0, 0); PG8_SCHED; PG8_LDA(At, 0, 0); PG8_STAGE(PG8_SA(1, 1), a1 + hstepA, voffA);
;             PG8_WAIT_L(8); PG8_BAR; PG8_WAIT_L(0); PG8_MMA(0, 0, At, B0); PG8_BAR; PG8_SCHED;
;             PG8_LDB(B1, 0, 1); PG8_STAGE(PG8_SB(0, 0), b2, voffB);
;             PG8_BAR; PG8_WAIT_L(0); PG8_MMA(0, 1, At, B1); PG8_BAR;
;             PG8_LDA(At, 0, 1); PG8_STAGE(PG8_SA(0, 0), a2, voffA);
;             PG8_BAR; PG8_WAIT_L(0); PG8_MMA(1, 0, At, B0); PG8_BAR; PG8_SCHED;
;             PG8_STAGE(PG8_SB(0, 1), b2 + hstepB, voffB);
;             PG8_WAIT_V(6); PG8_BAR; PG8_MMA(1, 1, At, B1); PG8_BAR;
;             PG8_LDB(B0, 1, 0); PG8_SCHED; PG8_LDA(At, 1, 0); PG8_STAGE(PG8_SA(0, 1), a2 + hstepA, voffA);
;             PG8_WAIT_L(8); PG8_BAR; PG8_WAIT_L(0); PG8_MMA(0, 0, At, B0); PG8_BAR; PG8_SCHED;
;             PG8_LDB(B1, 1, 1); PG8_STAGE(PG8_SB(1, 0), b3, voffB);
;             PG8_BAR; PG8_WAIT_L(0); PG8_MMA(0, 1, At, B1); PG8_BAR;
;             PG8_LDA(At, 1, 1); PG8_STAGE(PG8_SA(1, 0), a3, voffA);
;             PG8_BAR; PG8_WAIT_L(0); PG8_MMA(1, 0, At, B0); PG8_BAR; PG8_SCHED;
;             PG8_STAGE(PG8_SB(1, 1), b3 + hstepB, voffB);
;             PG8_WAIT_V(6); PG8_BAR; PG8_MMA(1, 1, At, B1); PG8_BAR;
	s_waitcnt lgkmcnt(0)
	s_waitcnt lgkmcnt(0)
	v_mfma_f32_16x16x32_bf16 v[66:69], v[122:125], v[138:141], v[66:69]
	v_mfma_f32_16x16x32_bf16 v[70:73], v[130:133], v[138:141], v[70:73]
	v_mfma_f32_16x16x32_bf16 v[74:77], v[122:125], v[170:173], v[74:77]
	v_mfma_f32_16x16x32_bf16 v[78:81], v[130:133], v[170:173], v[78:81]
	v_mfma_f32_16x16x32_bf16 v[82:85], v[122:125], v[178:181], v[82:85]
	v_mfma_f32_16x16x32_bf16 v[86:89], v[130:133], v[178:181], v[86:89]
	v_mfma_f32_16x16x32_bf16 v[90:93], v[122:125], v[186:189], v[90:93]
	v_mfma_f32_16x16x32_bf16 v[94:97], v[130:133], v[186:189], v[94:97]
	v_mfma_f32_16x16x32_bf16 v[66:69], v[126:129], v[142:145], v[66:69]
	v_mfma_f32_16x16x32_bf16 v[70:73], v[134:137], v[142:145], v[70:73]
	v_mfma_f32_16x16x32_bf16 v[74:77], v[126:129], v[174:177], v[74:77]
	v_mfma_f32_16x16x32_bf16 v[78:81], v[134:137], v[174:177], v[78:81]
	v_mfma_f32_16x16x32_bf16 v[82:85], v[126:129], v[182:185], v[82:85]
	v_mfma_f32_16x16x32_bf16 v[86:89], v[134:137], v[182:185], v[86:89]
	v_mfma_f32_16x16x32_bf16 v[90:93], v[126:129], v[190:193], v[90:93]
	v_mfma_f32_16x16x32_bf16 v[94:97], v[134:137], v[190:193], v[94:97]
	s_barrier
	s_mov_b32 m0, s72
	v_lshl_add_u64 v[210:211], v[210:211], 0, s[10:11]
	ds_read_b128 v[194:197], v219
	ds_read_b128 v[198:201], v219 offset:1024
	ds_read_b128 v[202:205], v219 offset:2048
	ds_read_b128 v[206:209], v219 offset:3072
	global_load_lds_dwordx4 v[210:211], off
	v_lshl_add_u64 v[210:211], v[212:213], 0, s[10:11]
	s_mov_b32 m0, s71
	s_nop 0
	global_load_lds_dwordx4 v[210:211], off
	s_barrier
	s_waitcnt lgkmcnt(0)
	s_waitcnt lgkmcnt(0)
	v_mfma_f32_16x16x32_bf16 v[114:117], v[194:197], v[138:141], v[114:117]
	v_mfma_f32_16x16x32_bf16 v[34:37], v[202:205], v[138:141], v[34:37]
	v_mfma_f32_16x16x32_bf16 v[38:41], v[194:197], v[170:173], v[38:41]
	v_mfma_f32_16x16x32_bf16 v[42:45], v[202:205], v[170:173], v[42:45]
	v_mfma_f32_16x16x32_bf16 v[46:49], v[194:197], v[178:181], v[46:49]
	v_mfma_f32_16x16x32_bf16 v[50:53], v[202:205], v[178:181], v[50:53]
	v_mfma_f32_16x16x32_bf16 v[54:57], v[194:197], v[186:189], v[54:57]
	v_mfma_f32_16x16x32_bf16 v[58:61], v[202:205], v[186:189], v[58:61]
	v_mfma_f32_16x16x32_bf16 v[114:117], v[198:201], v[142:145], v[114:117]
	v_mfma_f32_16x16x32_bf16 v[34:37], v[206:209], v[142:145], v[34:37]
	v_mfma_f32_16x16x32_bf16 v[38:41], v[198:201], v[174:177], v[38:41]
	v_mfma_f32_16x16x32_bf16 v[42:45], v[206:209], v[174:177], v[42:45]
	v_mfma_f32_16x16x32_bf16 v[46:49], v[198:201], v[182:185], v[46:49]
	v_mfma_f32_16x16x32_bf16 v[50:53], v[206:209], v[182:185], v[50:53]
	v_mfma_f32_16x16x32_bf16 v[54:57], v[198:201], v[190:193], v[54:57]
	v_mfma_f32_16x16x32_bf16 v[58:61], v[206:209], v[190:193], v[58:61]
	s_mov_b32 m0, s58
	v_lshl_add_u64 v[210:211], v[214:215], 0, s[10:11]
	s_barrier
	ds_read_b128 v[138:141], v16 offset:49152
	ds_read_b128 v[142:145], v16 offset:50176
	ds_read_b128 v[170:173], v16 offset:51200
	ds_read_b128 v[174:177], v16 offset:52224
	ds_read_b128 v[178:181], v16 offset:53248
	ds_read_b128 v[182:185], v16 offset:54272
	ds_read_b128 v[186:189], v16 offset:55296
	ds_read_b128 v[190:193], v16 offset:56320
	global_load_lds_dwordx4 v[210:211], off
	v_lshl_add_u64 v[210:211], v[216:217], 0, s[10:11]
	s_mov_b32 m0, s59
	s_nop 0
	global_load_lds_dwordx4 v[210:211], off
	s_barrier
	s_waitcnt lgkmcnt(0)
	s_waitcnt lgkmcnt(0)
	v_mfma_f32_16x16x32_bf16 v[146:149], v[122:125], v[138:141], v[146:149]
	v_mfma_f32_16x16x32_bf16 v[150:153], v[130:133], v[138:141], v[150:153]
	v_mfma_f32_16x16x32_bf16 v[154:157], v[122:125], v[170:173], v[154:157]
	v_mfma_f32_16x16x32_bf16 v[158:161], v[130:133], v[170:173], v[158:161]
	v_mfma_f32_16x16x32_bf16 v[162:165], v[122:125], v[178:181], v[162:165]
	v_mfma_f32_16x16x32_bf16 v[166:169], v[130:133], v[178:181], v[166:169]
	v_mfma_f32_16x16x32_bf16 v[18:21], v[122:125], v[186:189], v[18:21]
	v_mfma_f32_16x16x32_bf16 v[22:25], v[130:133], v[186:189], v[22:25]
	v_mfma_f32_16x16x32_bf16 v[146:149], v[126:129], v[142:145], v[146:149]
	v_mfma_f32_16x16x32_bf16 v[150:153], v[134:137], v[142:145], v[150:153]
	v_mfma_f32_16x16x32_bf16 v[154:157], v[126:129], v[174:177], v[154:157]
	v_mfma_f32_16x16x32_bf16 v[158:161], v[134:137], v[174:177], v[158:161]
	v_mfma_f32_16x16x32_bf16 v[162:165], v[126:129], v[182:185], v[162:165]
	v_mfma_f32_16x16x32_bf16 v[166:169], v[134:137], v[182:185], v[166:169]
	v_mfma_f32_16x16x32_bf16 v[18:21], v[126:129], v[190:193], v[18:21]
	v_mfma_f32_16x16x32_bf16 v[22:25], v[134:137], v[190:193], v[22:25]
	s_barrier
	s_add_u32 s48, s52, 0x10080
	s_addc_u32 s49, s53, 0
	s_mov_b32 m0, s51
	v_lshl_add_u64 v[122:123], s[48:49], 0, v[2:3]
	global_load_lds_dwordx4 v[122:123], off
	v_lshl_add_u64 v[122:123], s[48:49], 0, v[6:7]
	s_mov_b32 m0, s50
	s_nop 0
	global_load_lds_dwordx4 v[122:123], off
	s_waitcnt vmcnt(6)
	s_barrier
; #define PG8_BAR __builtin_amdgcn_s_barrier()
; template <class Epi>
; __device__ __forceinline__ void gemm_phase(LAS unsigned char* lds, const Gemm g, const StaticOrder& S, const Epi& E, int wv) {
;     ...
;             PG8_WAIT_V(6); PG8_BAR; PG8_MMA(1, 1, At, B1); PG8_BAR;
;             PG8_LDB(B0, 1, 0); PG8_SCHED; PG8_LDA(At, 1, 0); PG8_STAGE(PG8_SA(0, 1), a2 + hstepA, voffA);
;             PG8_WAIT_L(8); PG8_BAR; PG8_WAIT_L(0); PG8_MMA(0, 0, At, B0); PG8_BAR; PG8_SCHED;
;             PG8_LDB(B1, 1, 1); PG8_STAGE(PG8_SB(1, 0), b3, voffB);
;             PG8_BAR; PG8_WAIT_L(0); PG8_MMA(0, 1, At, B1); PG8_BAR;
;             PG8_LDA(At, 1, 1); PG8_STAGE(PG8_SA(1, 0), a3, voffA);
;             PG8_BAR; PG8_WAIT_L(0); PG8_MMA(1, 0, At, B0); PG8_BAR; PG8_SCHED;
;             PG8_STAGE(PG8_SB(1, 1), b3 + hstepB, voffB);
;             PG8_WAIT_V(6); PG8_BAR; PG8_MMA(1, 1, At, B1); PG8_BAR;
;     __device__ __forceinline__ void operator()(const f32x4 (&acc)[2][2][4][2], const Unit& u, int wr, int wc, int fr, int fq) const {
;         const int row0 = u.pm * BM + wr * 64 + fr; int colt = u.pn * BM; bf16_t* base = O; int tsel = 0;
;         if (split_cols) { tsel = colt / split_cols; base += (size_t)tsel * split_stride; colt -= tsel * split_cols; }
;         const int col0 = colt + wc * 32 + 8 * fq;
;         f32x4 cs[2][2];
;         if (SM == 2) {
; #pragma unroll
;             for (int bj = 0; bj < 2; ++bj)
; #pragma unroll
;                 for (int n = 0; n < 2; ++n) { const f32x4 s = *(const f32x4*)(ss + u.pn * BM + wc * 32 + 8 * fq + bj * HALF + 4 * n);
; #pragma unroll
;                     for (int j = 0; j < 4; ++j) cs[bj][n][j] = __builtin_amdgcn_rsqf(ss_fix(s[j]) * (1.0f / DM) + EPS); }
;         }
;         float rsv[8];
; #pragma unroll
;         for (int it = 0; it < 8; ++it) rsv[it] = (SM == 1) ? ss[row0 + (it >> 2) * HALF + (it & 3) * 16] : 1.0f;
; #pragma unroll
;         for (int ai = 0; ai < 2; ++ai)
; #pragma unroll
;             for (int m = 0; m < 4; ++m) { const int row = row0 + ai * HALF + m * 16; float rs = 1.0f; if (SM == 1) rs = __builtin_amdgcn_rsqf(ss_fix(rsv[ai * 4 + m]) * (1.0f / DM) + EPS);
;                 bf16_t* rowp = base + (size_t)row * ldc + col0;
; #pragma unroll
;                 for (int bj = 0; bj < 2; ++bj) { f32x4 v0 = acc[ai][bj][m][0], v1 = acc[ai][bj][m][1];
;                     if (SM == 1) { v0 *= rs; v1 *= rs; }
	v_mfma_f32_16x16x32_bf16 v[26:29], v[194:197], v[138:141], v[26:29]
	v_mfma_f32_16x16x32_bf16 v[30:33], v[202:205], v[138:141], v[30:33]
	v_mfma_f32_16x16x32_bf16 v[62:65], v[194:197], v[170:173], v[62:65]
	v_mfma_f32_16x16x32_bf16 v[106:109], v[202:205], v[170:173], v[106:109]
	v_mfma_f32_16x16x32_bf16 v[110:113], v[194:197], v[178:181], v[110:113]
	v_mfma_f32_16x16x32_bf16 v[118:121], v[202:205], v[178:181], v[118:121]
	v_mfma_f32_16x16x32_bf16 v[98:101], v[194:197], v[186:189], v[98:101]
	v_mfma_f32_16x16x32_bf16 v[102:105], v[202:205], v[186:189], v[102:105]
	v_mfma_f32_16x16x32_bf16 v[26:29], v[198:201], v[142:145], v[26:29]
	v_mfma_f32_16x16x32_bf16 v[30:33], v[206:209], v[142:145], v[30:33]
	v_mfma_f32_16x16x32_bf16 v[62:65], v[198:201], v[174:177], v[62:65]
	v_mfma_f32_16x16x32_bf16 v[106:109], v[206:209], v[174:177], v[106:109]
	v_mfma_f32_16x16x32_bf16 v[110:113], v[198:201], v[182:185], v[110:113]
	v_mfma_f32_16x16x32_bf16 v[118:121], v[206:209], v[182:185], v[118:121]
	v_mfma_f32_16x16x32_bf16 v[98:101], v[198:201], v[190:193], v[98:101]
	v_mfma_f32_16x16x32_bf16 v[102:105], v[206:209], v[190:193], v[102:105]
	v_lshl_add_u32 v122, s38, 8, v12
	v_lshl_or_b32 v124, s68, 8, v14
	v_ashrrev_i32_e32 v125, 31, v124
	v_ashrrev_i32_e32 v123, 31, v122
	v_lshl_add_u64 v[124:125], v[124:125], 1, s[8:9]
	v_lshlrev_b64 v[126:127], 12, v[122:123]
	v_lshl_add_u64 v[126:127], v[124:125], 0, v[126:127]
	v_cvt_pk_bf16_f32 v66, v66, v67
	v_cvt_pk_bf16_f32 v67, v68, v69
	v_cvt_pk_bf16_f32 v68, v70, v71
	v_cvt_pk_bf16_f32 v69, v72, v73
	s_barrier
	global_store_dwordx4 v[126:127], v[66:69], off
	v_cvt_pk_bf16_f32 v26, v26, v27
	v_cvt_pk_bf16_f32 v27, v28, v29
	v_cvt_pk_bf16_f32 v68, v34, v35
	v_or_b32_e32 v34, 16, v122
	v_ashrrev_i32_e32 v35, 31, v34
	v_cvt_pk_bf16_f32 v66, v114, v115
	v_cvt_pk_bf16_f32 v67, v116, v117
	v_cvt_pk_bf16_f32 v69, v36, v37
	v_lshlrev_b64 v[34:35], 12, v[34:35]
	global_store_dwordx4 v[126:127], v[66:69], off offset:256
	v_cvt_pk_bf16_f32 v36, v78, v79
	v_cvt_pk_bf16_f32 v37, v80, v81
	v_lshl_add_u64 v[66:67], v[124:125], 0, v[34:35]
	v_cvt_pk_bf16_f32 v34, v74, v75
	v_cvt_pk_bf16_f32 v35, v76, v77
	global_store_dwordx4 v[66:67], v[34:37], off
	v_cvt_pk_bf16_f32 v28, v30, v31
	v_cvt_pk_bf16_f32 v29, v32, v33
	v_cvt_pk_bf16_f32 v34, v38, v39
	v_cvt_pk_bf16_f32 v35, v40, v41
	v_cvt_pk_bf16_f32 v36, v42, v43
	v_cvt_pk_bf16_f32 v37, v44, v45
	global_store_dwordx4 v[66:67], v[34:37], off offset:256
	v_add_co_u32_e32 v40, vcc, s64, v126
	s_nop 0
	v_or_b32_e32 v34, 32, v122
	v_ashrrev_i32_e32 v35, 31, v34
	v_lshlrev_b64 v[34:35], 12, v[34:35]
	v_lshl_add_u64 v[38:39], v[124:125], 0, v[34:35]
	v_cvt_pk_bf16_f32 v34, v82, v83
	v_cvt_pk_bf16_f32 v35, v84, v85
	v_cvt_pk_bf16_f32 v36, v86, v87
	v_cvt_pk_bf16_f32 v37, v88, v89
	global_store_dwordx4 v[38:39], v[34:37], off
	v_addc_co_u32_e32 v41, vcc, 0, v127, vcc
	s_nop 0
	v_cvt_pk_bf16_f32 v34, v46, v47
	v_cvt_pk_bf16_f32 v35, v48, v49
	v_cvt_pk_bf16_f32 v36, v50, v51
	v_cvt_pk_bf16_f32 v37, v52, v53
	global_store_dwordx4 v[38:39], v[34:37], off offset:256
	v_add_co_u32_e32 v32, vcc, s65, v126
	s_nop 0
	v_or_b32_e32 v34, 48, v122
	v_ashrrev_i32_e32 v35, 31, v34
	v_lshlrev_b64 v[34:35], 12, v[34:35]
	v_lshl_add_u64 v[38:39], v[124:125], 0, v[34:35]
	v_cvt_pk_bf16_f32 v34, v90, v91
	v_cvt_pk_bf16_f32 v35, v92, v93
	v_cvt_pk_bf16_f32 v36, v94, v95
	v_cvt_pk_bf16_f32 v37, v96, v97
	global_store_dwordx4 v[38:39], v[34:37], off
	v_addc_co_u32_e32 v33, vcc, 0, v127, vcc
	s_nop 0
	v_cvt_pk_bf16_f32 v34, v54, v55
	v_cvt_pk_bf16_f32 v35, v56, v57
	v_cvt_pk_bf16_f32 v36, v58, v59
	v_cvt_pk_bf16_f32 v37, v60, v61
	global_store_dwordx4 v[38:39], v[34:37], off offset:256
	v_lshl_add_u64 v[38:39], v[126:127], 0, s[16:17]
	global_store_dwordx4 v[38:39], v[26:29], off offset:256
	v_lshl_add_u64 v[30:31], v[126:127], 0, s[18:19]
	v_cvt_pk_bf16_f32 v18, v18, v19
	v_cvt_pk_bf16_f32 v26, v154, v155
	v_cvt_pk_bf16_f32 v27, v156, v157
	v_cvt_pk_bf16_f32 v28, v158, v159
	v_cvt_pk_bf16_f32 v29, v160, v161
	global_store_dwordx4 v[32:33], v[26:29], off
	v_add_co_u32_e32 v32, vcc, s66, v126
	s_nop 0
	v_cvt_pk_bf16_f32 v26, v62, v63
	v_cvt_pk_bf16_f32 v27, v64, v65
	v_cvt_pk_bf16_f32 v28, v106, v107
	v_cvt_pk_bf16_f32 v29, v108, v109
	v_addc_co_u32_e32 v33, vcc, 0, v127, vcc
	global_store_dwordx4 v[30:31], v[26:29], off offset:256
	v_cvt_pk_bf16_f32 v19, v20, v21
	v_cvt_pk_bf16_f32 v20, v22, v23
	v_cvt_pk_bf16_f32 v26, v162, v163
	v_cvt_pk_bf16_f32 v27, v164, v165
	v_cvt_pk_bf16_f32 v28, v166, v167
	v_cvt_pk_bf16_f32 v29, v168, v169
	v_add_co_u32_e32 v22, vcc, s67, v126
	v_readlane_b32 s38, v255, 9
	v_lshl_add_u64 v[30:31], v[126:127], 0, s[30:31]
	global_store_dwordx4 v[32:33], v[26:29], off
	v_cvt_pk_bf16_f32 v21, v24, v25
	v_addc_co_u32_e32 v23, vcc, 0, v127, vcc
	v_cvt_pk_bf16_f32 v26, v110, v111
	v_cvt_pk_bf16_f32 v27, v112, v113
	v_cvt_pk_bf16_f32 v28, v118, v119
	v_cvt_pk_bf16_f32 v29, v120, v121
	s_add_i32 s38, s38, s28
	v_cvt_pk_bf16_f32 v34, v146, v147
	v_cvt_pk_bf16_f32 v35, v148, v149
	v_cvt_pk_bf16_f32 v36, v150, v151
	v_cvt_pk_bf16_f32 v37, v152, v153
	global_store_dwordx4 v[30:31], v[26:29], off offset:256
	global_store_dwordx4 v[22:23], v[18:21], off
	v_writelane_b32 v255, s38, 9
	v_lshl_add_u64 v[26:27], v[126:127], 0, s[34:35]
	v_cvt_pk_bf16_f32 v18, v98, v99
	v_cvt_pk_bf16_f32 v19, v100, v101
	v_cvt_pk_bf16_f32 v20, v102, v103
	v_cvt_pk_bf16_f32 v21, v104, v105
	s_andn2_b64 vcc, exec, s[6:7]
	s_mov_b32 s68, s40
	s_mov_b32 s38, s42
	s_mov_b64 s[50:51], s[46:47]
	s_mov_b64 s[48:49], s[44:45]
	global_store_dwordx4 v[40:41], v[34:37], off
	global_store_dwordx4 v[26:27], v[18:21], off offset:256
	s_cbranch_vccz .LBB0_1782

; __device__ __forceinline__ int opaque_tid(int wv) { int l; asm volatile("v_mbcnt_lo_u32_b32 %0, -1, 0\n\tv_mbcnt_hi_u32_b32 %0, -1, %0" : "=v"(l)); return wv * 64 + l; }
; #define PG8_STAGE(bufoff, gbase, voff) do { _Pragma("unroll") for (int _i = 0; _i < 2; ++_i) \
;         __builtin_amdgcn_global_load_lds((const unsigned*)((const char*)(gbase) + (voff)[_i]), (LAS unsigned*)(lds + (bufoff) + ldsw + _i * 8192), 16, 0, 0); } while (0)
; template <class Epi>
; __device__ __forceinline__ void gemm_phase(LAS unsigned char* lds, const Gemm g, const StaticOrder& S, const Epi& E, int wv) {
;     const int tid = opaque_tid(wv), wid = __builtin_amdgcn_readfirstlane(tid >> 6), lane = tid & 63, wr = wid >> 2, wc = wid & 3, fr = lane & 15, fq = lane >> 4;
;     const int K = g.K, nt = K / BK;
;     unsigned voffA[2], voffB[2];
; #pragma unroll
;     for (int i = 0; i < 2; ++i) { int R, C; stage_rc(tid * 16 + i * 8192, R, C); const int Rb = Epi::PERM ? ((R & ~31) + perm32(R & 31)) : R;
;         voffA[i] = (unsigned)(R * g.lda + C) * 2u; voffB[i] = (unsigned)(Rb * g.ldb + C) * 2u; }
;     const bool krev = (g.adiag & 2) != 0;
;     const ptrdiff_t kstep = krev ? -(ptrdiff_t)(BK * 2) : (ptrdiff_t)(BK * 2);
;     const size_t kbeg = krev ? (size_t)(nt - 1) * (BK * 2) : 0;
;     const size_t hstepA = (size_t)HALF * g.lda * 2, hstepB = (size_t)HALF * g.ldb * 2;
;     const size_t tstepA = 2 * hstepA, tstepB = 2 * hstepB;
;     const unsigned ldsw = (unsigned)wid * 1024u;
;     const int aoff = lds_byte(wr * 64 + fr, fq * 8), boff = lds_byte(wc * 32 + fr, fq * 8);
;     ...
;     Unit cur, nxt; int ui = 0;
;     if (!S.next(0, cur)) return;
;     f32x4 acc[2][2][4][2];
; #pragma unroll
;     for (int a = 0; a < 2; ++a)
; #pragma unroll
;         for (int b = 0; b < 2; ++b)
; #pragma unroll
;             for (int m = 0; m < 4; ++m)
; #pragma unroll
;                 for (int n = 0; n < 2; ++n) acc[a][b][m][n] = (f32x4){0.f, 0.f, 0.f, 0.f};
;     bf16x8 At[4][2], B0[2][2], B1[2][2];
;     const char* cA = (const char*)g.A + (size_t)cur.pm * tstepA + ((g.adiag & 1) ? (size_t)(cur.pn >> 1) * K * 2 : 0) + kbeg;
;     const char* cB = (const char*)g.Bt + (size_t)cur.pn * tstepB + kbeg;
;     PG8_STAGE(PG8_SB(0, 0), cB, voffB); PG8_STAGE(PG8_SA(0, 0), cA, voffA); PG8_STAGE(PG8_SB(0, 1), cB + hstepB, voffB); PG8_STAGE(PG8_SA(0, 1), cA + hstepA, voffA);
;     if (wr == 1) PG8_BAR;
.LBB0_1843:
	v_ashrrev_i32_e32 v2, 31, v0
	v_lshrrev_b32_e32 v2, 26, v2
	v_lshlrev_b32_e32 v1, 4, v0
	v_add_u32_e32 v2, v0, v2
	v_bfe_i32 v0, v0, 27, 1
	v_lshrrev_b32_e32 v0, 22, v0
	v_add_u32_e32 v0, v1, v0
	v_and_b32_e32 v0, 0xfffffc00, v0
	v_sub_u32_e32 v0, v1, v0
	v_ashrrev_i32_e32 v9, 6, v2
	v_lshrrev_b32_e32 v2, 4, v0
	v_bitop3_b32 v0, v2, v0, 32 bitop3:0x6c
	v_ashrrev_i32_e32 v3, 31, v0
	v_lshrrev_b32_e32 v3, 26, v3
	v_add_u32_e32 v3, v0, v3
	v_lshlrev_b32_e32 v2, 3, v9
	v_ashrrev_i32_e32 v10, 6, v3
	v_and_b32_e32 v3, 0xc0, v3
	s_waitcnt lgkmcnt(0)
	s_add_u32 s36, s16, 0x7300000
	v_and_b32_e32 v2, -16, v2
	v_sub_u32_e32 v0, v0, v3
	v_mov_b32_e32 v3, 1
	s_addc_u32 s37, s17, 0
	v_add_u32_e32 v2, v10, v2
	v_ashrrev_i16_sdwa v0, v3, sext(v0) dst_sel:DWORD dst_unused:UNUSED_PAD src0_sel:DWORD src1_sel:BYTE_0
	s_add_u32 s38, s4, 0x6900000
	v_lshlrev_b32_e32 v4, 5, v9
	v_bfe_i32 v11, v0, 0, 16
	v_lshlrev_b32_e32 v0, 1, v2
	v_lshrrev_b32_e32 v5, 2, v2
	v_and_b32_e32 v6, 3, v10
	s_mov_b32 s4, 0xfffe0
	v_and_b32_e32 v4, 32, v4
	v_and_b32_e32 v0, 24, v0
	v_and_b32_e32 v5, 4, v5
	v_and_or_b32 v6, v2, s4, v6
	v_or3_b32 v0, v6, v5, v0
	v_add_lshl_u32 v4, v4, v11, 1
	v_lshl_add_u32 v162, v0, 12, v4
	v_add_u32_e32 v0, 0x2000, v1
	v_ashrrev_i32_e32 v1, 31, v0
	v_lshrrev_b32_e32 v1, 22, v1
	v_add_u32_e32 v1, v0, v1
	v_ashrrev_i32_e32 v12, 10, v1
	v_mul_i32_i24_e32 v1, 0x400, v12
	v_sub_u32_e32 v0, v0, v1
	v_lshrrev_b32_e32 v1, 4, v0
	v_bitop3_b32 v0, v1, v0, 32 bitop3:0x6c
	v_lshl_add_u32 v160, v2, 12, v4
	v_ashrrev_i32_e32 v2, 31, v0
	v_lshrrev_b32_e32 v2, 26, v2
	v_add_u32_e32 v2, v0, v2
	v_lshlrev_b32_e32 v1, 3, v12
	v_ashrrev_i32_e32 v13, 6, v2
	v_and_b32_e32 v2, 0xc0, v2
	v_and_b32_e32 v1, -16, v1
	v_sub_u32_e32 v0, v0, v2
	s_addc_u32 s39, s5, 0
	v_add_u32_e32 v1, v13, v1
	v_ashrrev_i16_sdwa v0, v3, sext(v0) dst_sel:DWORD dst_unused:UNUSED_PAD src0_sel:DWORD src1_sel:BYTE_0
	v_and_b32_e32 v3, 3, v13
	s_add_i32 s0, s22, s0
	v_and_or_b32 v3, v1, s4, v3
	s_ashr_i32 s4, s0, 31
	s_lshr_b32 s4, s4, 27
	s_add_i32 s4, s0, s4
	s_ashr_i32 s5, s4, 5
	s_and_b32 s4, s4, 0xffe0
	s_sub_i32 s4, s0, s4
	s_bfe_i32 s0, s4, 0x80000
	s_bfe_u32 s0, s0, 0x2000d
	s_add_i32 s15, s4, s0
	s_bfe_i32 s0, s15, 0x80000
	s_and_b32 s15, s15, 0xfc
	s_sub_i32 s4, s4, s15
	s_lshl_b32 s5, s5, 2
	s_sext_i32_i16 s0, s0
	s_sext_i32_i8 s4, s4
	s_ashr_i32 s1, s33, 8
	s_lshr_b32 s0, s0, 2
	s_add_i32 s24, s5, s4
	s_ashr_i32 s14, s33, 6
	s_ashr_i32 s25, s24, 31
	s_bfe_i64 s[16:17], s[0:1], 0x100000
	s_lshl_b32 s40, s14, 10
	s_lshl_b64 s[4:5], s[24:25], 20
	s_lshl_b64 s[16:17], s[16:17], 20
	s_add_u32 s28, s38, s16
	v_lshlrev_b32_e32 v4, 5, v12
	v_bfe_i32 v14, v0, 0, 16
	v_lshlrev_b32_e32 v0, 1, v1
	v_lshrrev_b32_e32 v2, 2, v1
	s_addc_u32 s29, s39, s17
	s_add_i32 s25, s40, 0
	v_and_b32_e32 v4, 32, v4
	v_and_b32_e32 v0, 24, v0
	v_and_b32_e32 v2, 4, v2
	s_add_i32 m0, s25, 0x10000
	v_or3_b32 v0, v3, v2, v0
	v_add_lshl_u32 v2, v4, v14, 1
	global_load_lds_dwordx4 v162, s[28:29]
	s_add_i32 m0, s25, 0x12000
	v_lshl_add_u32 v166, v0, 12, v2
	s_add_u32 s30, s36, s4
	global_load_lds_dwordx4 v166, s[28:29]
	s_addc_u32 s31, s37, s5
	s_mov_b32 m0, s25
	s_add_i32 s41, s25, 0x2000
	v_lshl_add_u32 v164, v1, 12, v2
	global_load_lds_dwordx4 v160, s[30:31]
	s_mov_b32 m0, s41
	s_add_u32 s4, s28, 0x80000
	global_load_lds_dwordx4 v164, s[30:31]
	s_addc_u32 s5, s29, 0
	s_add_i32 m0, s25, 0x14000
	v_mov_b32_e32 v163, 0
	global_load_lds_dwordx4 v162, s[4:5]
	s_add_i32 m0, s25, 0x16000
	v_mov_b32_e32 v167, v163
	global_load_lds_dwordx4 v166, s[4:5]
	s_add_u32 s4, s30, 0x80000
	s_addc_u32 s5, s31, 0
	s_add_i32 s42, s25, 0x4000
	s_mov_b32 m0, s42
	s_add_i32 s43, s25, 0x6000
	global_load_lds_dwordx4 v160, s[4:5]
	s_mov_b32 m0, s43
	v_mov_b32_e32 v161, v163
	global_load_lds_dwordx4 v164, s[4:5]
	s_load_dwordx2 s[4:5], s[6:7], 0xd8
	v_mov_b32_e32 v165, v163
	s_mov_b32 s44, 0
	v_lshl_add_u64 v[6:7], s[28:29], 0, v[162:163]
	v_lshl_add_u64 v[4:5], s[28:29], 0, v[166:167]
	v_lshl_add_u64 v[2:3], s[30:31], 0, v[160:161]
	s_cmp_lg_u32 s1, 1
	v_lshl_add_u64 v[0:1], s[30:31], 0, v[164:165]
	s_cbranch_scc1 .LBB0_1845
	s_barrier
	s_setprio 1

; #define PG8_STAGE(bufoff, gbase, voff) do { _Pragma("unroll") for (int _i = 0; _i < 2; ++_i) \
;         __builtin_amdgcn_global_load_lds((const unsigned*)((const char*)(gbase) + (voff)[_i]), (LAS unsigned*)(lds + (bufoff) + ldsw + _i * 8192), 16, 0, 0); } while (0)
; #define PG8_LDA(dst, b, h) do { _Pragma("unroll") for (int m = 0; m < 4; ++m) _Pragma("unroll") for (int k = 0; k < 2; ++k) dst[m][k] = *(const LAS bf16x8*)(lds + PG8_SA(b, h) + aoff + m * 2048 + k * 1024); } while (0)
; #define PG8_WAIT_V(n) asm volatile("s_waitcnt vmcnt(" #n ")" ::: "memory")
; #define PG8_BAR __builtin_amdgcn_s_barrier()
; template <class Epi>
; __device__ __forceinline__ void gemm_phase(LAS unsigned char* lds, const Gemm g, const StaticOrder& S, const Epi& E, int wv) {
;     ...
;         for (int t = 0; t < nt; t += 2) {
;             const bool last = (t == nt - 2);
;             const char* a1 = cA + (ptrdiff_t)(t + 1) * kstep;
;             const char* a2 = last ? nA : cA + (ptrdiff_t)(t + 2) * kstep; const char* b2 = last ? nB : cB + (ptrdiff_t)(t + 2) * kstep;
;             const char* a3 = a2 + kstep; const char* b3 = b2 + kstep;
;             PG8_LDB(B0, 0, 0); PG8_SCHED; PG8_LDA(At, 0, 0); PG8_STAGE(PG8_SA(1, 1), a1 + hstepA, voffA);
;             PG8_WAIT_L(8); PG8_BAR; PG8_WAIT_L(0); PG8_MMA(0, 0, At, B0); PG8_BAR; PG8_SCHED;
;             PG8_LDB(B1, 0, 1); PG8_STAGE(PG8_SB(0, 0), b2, voffB);
;             PG8_BAR; PG8_WAIT_L(0); PG8_MMA(0, 1, At, B1); PG8_BAR;
;             PG8_LDA(At, 0, 1); PG8_STAGE(PG8_SA(0, 0), a2, voffA);
;             PG8_BAR; PG8_WAIT_L(0); PG8_MMA(1, 0, At, B0); PG8_BAR; PG8_SCHED;
;             PG8_STAGE(PG8_SB(0, 1), b2 + hstepB, voffB);
;             PG8_WAIT_V(6); PG8_BAR; PG8_MMA(1, 1, At, B1); PG8_BAR;
;             PG8_LDB(B0, 1, 0); PG8_SCHED; PG8_LDA(At, 1, 0); PG8_STAGE(PG8_SA(0, 1), a2 + hstepA, voffA);
;             PG8_WAIT_L(8); PG8_BAR; PG8_WAIT_L(0); PG8_MMA(0, 0, At, B0); PG8_BAR; PG8_SCHED;
;             PG8_LDB(B1, 1, 1); PG8_STAGE(PG8_SB(1, 0), b3, voffB);
;             PG8_BAR; PG8_WAIT_L(0); PG8_MMA(0, 1, At, B1); PG8_BAR;
;             PG8_LDA(At, 1, 1); PG8_STAGE(PG8_SA(1, 0), a3, voffA);
;             PG8_BAR; PG8_WAIT_L(0); PG8_MMA(1, 0, At, B0); PG8_BAR; PG8_SCHED;
;             PG8_STAGE(PG8_SB(1, 1), b3 + hstepB, voffB);
;             PG8_WAIT_V(6); PG8_BAR; PG8_MMA(1, 1, At, B1); PG8_BAR;
.LBB0_1853:
	s_add_u32 s30, s28, 0xfff80080
	s_addc_u32 s31, s29, -1
	s_cmp_eq_u32 s54, 28
	s_cselect_b32 s35, s19, s31
	s_cselect_b32 s34, s50, s30
	s_cselect_b32 s31, s17, s53
	s_cselect_b32 s30, s51, s52
	s_add_i32 m0, s25, 0xc000
	ds_read_b128 v[144:147], v194
	ds_read_b128 v[148:151], v194 offset:1024
	ds_read_b128 v[152:155], v194 offset:2048
	ds_read_b128 v[156:159], v194 offset:3072
	ds_read_b128 v[176:179], v194 offset:4096
	ds_read_b128 v[180:183], v194 offset:5120
	ds_read_b128 v[184:187], v194 offset:6144
	ds_read_b128 v[198:201], v194 offset:7168
	global_load_lds_dwordx4 v170, s[28:29]
	s_add_i32 m0, s25, 0xe000
	s_nop 0
	global_load_lds_dwordx4 v168, s[28:29]
	s_waitcnt lgkmcnt(8)
	s_barrier
	s_waitcnt lgkmcnt(0)
	s_waitcnt lgkmcnt(0)
	v_mfma_f32_16x16x32_bf16 v[124:127], v[128:131], v[144:147], v[124:127]
	v_mfma_f32_16x16x32_bf16 v[120:123], v[136:139], v[144:147], v[120:123]
	v_mfma_f32_16x16x32_bf16 v[108:111], v[128:131], v[152:155], v[108:111]
	v_mfma_f32_16x16x32_bf16 v[104:107], v[136:139], v[152:155], v[104:107]
	v_mfma_f32_16x16x32_bf16 v[92:95], v[128:131], v[176:179], v[92:95]
	v_mfma_f32_16x16x32_bf16 v[88:91], v[136:139], v[176:179], v[88:91]
	v_mfma_f32_16x16x32_bf16 v[76:79], v[128:131], v[184:187], v[76:79]
	v_mfma_f32_16x16x32_bf16 v[72:75], v[136:139], v[184:187], v[72:75]
	v_mfma_f32_16x16x32_bf16 v[124:127], v[132:135], v[148:151], v[124:127]
	v_mfma_f32_16x16x32_bf16 v[120:123], v[140:143], v[148:151], v[120:123]
	v_mfma_f32_16x16x32_bf16 v[108:111], v[132:135], v[156:159], v[108:111]
	v_mfma_f32_16x16x32_bf16 v[104:107], v[140:143], v[156:159], v[104:107]
	v_mfma_f32_16x16x32_bf16 v[92:95], v[132:135], v[180:183], v[92:95]
	v_mfma_f32_16x16x32_bf16 v[88:91], v[140:143], v[180:183], v[88:91]
	v_mfma_f32_16x16x32_bf16 v[76:79], v[132:135], v[198:201], v[76:79]
	v_mfma_f32_16x16x32_bf16 v[72:75], v[140:143], v[198:201], v[72:75]
	s_barrier
	s_add_i32 s55, s47, s40
	s_add_u32 s98, s30, s12
	s_addc_u32 s99, s31, s13
	s_mov_b32 m0, s55
	ds_read_b128 v[202:205], v195
	ds_read_b128 v[206:209], v195 offset:1024
	ds_read_b128 v[210:213], v195 offset:2048
	ds_read_b128 v[214:217], v195 offset:3072
	global_load_lds_dwordx4 v162, s[30:31]
	s_add_i32 m0, s55, 0x2000
	s_nop 0
	global_load_lds_dwordx4 v166, s[30:31]
	s_barrier
	s_waitcnt lgkmcnt(0)
	s_waitcnt lgkmcnt(0)
	v_mfma_f32_16x16x32_bf16 v[116:119], v[202:205], v[144:147], v[116:119]
	v_mfma_f32_16x16x32_bf16 v[112:115], v[210:213], v[144:147], v[112:115]
	v_mfma_f32_16x16x32_bf16 v[100:103], v[202:205], v[152:155], v[100:103]
	v_mfma_f32_16x16x32_bf16 v[96:99], v[210:213], v[152:155], v[96:99]
	v_mfma_f32_16x16x32_bf16 v[84:87], v[202:205], v[176:179], v[84:87]
	v_mfma_f32_16x16x32_bf16 v[80:83], v[210:213], v[176:179], v[80:83]
	v_mfma_f32_16x16x32_bf16 v[68:71], v[202:205], v[184:187], v[68:71]
	v_mfma_f32_16x16x32_bf16 v[64:67], v[210:213], v[184:187], v[64:67]
	v_mfma_f32_16x16x32_bf16 v[116:119], v[206:209], v[148:151], v[116:119]
	v_mfma_f32_16x16x32_bf16 v[112:115], v[214:217], v[148:151], v[112:115]
	v_mfma_f32_16x16x32_bf16 v[100:103], v[206:209], v[156:159], v[100:103]
	v_mfma_f32_16x16x32_bf16 v[96:99], v[214:217], v[156:159], v[96:99]
	v_mfma_f32_16x16x32_bf16 v[84:87], v[206:209], v[180:183], v[84:87]
	v_mfma_f32_16x16x32_bf16 v[80:83], v[214:217], v[180:183], v[80:83]
	v_mfma_f32_16x16x32_bf16 v[68:71], v[206:209], v[198:201], v[68:71]
	v_mfma_f32_16x16x32_bf16 v[64:67], v[214:217], v[198:201], v[64:67]
	s_mov_b32 m0, s25
	s_add_u32 s100, s34, s12
	s_addc_u32 s101, s35, s13
	s_barrier
	ds_read_b128 v[144:147], v194 offset:16384
	ds_read_b128 v[148:151], v194 offset:17408
	ds_read_b128 v[152:155], v194 offset:18432
	ds_read_b128 v[156:159], v194 offset:19456
	ds_read_b128 v[176:179], v194 offset:20480
	ds_read_b128 v[180:183], v194 offset:21504
	ds_read_b128 v[184:187], v194 offset:22528
	ds_read_b128 v[198:201], v194 offset:23552
	global_load_lds_dwordx4 v160, s[34:35]
	s_mov_b32 m0, s41
	s_nop 0
	global_load_lds_dwordx4 v164, s[34:35]
	s_waitcnt vmcnt(10)
	s_barrier
	s_waitcnt lgkmcnt(0)
	s_waitcnt lgkmcnt(0)
	v_mfma_f32_16x16x32_bf16 v[60:63], v[128:131], v[144:147], v[60:63]
	v_mfma_f32_16x16x32_bf16 v[56:59], v[136:139], v[144:147], v[56:59]
	v_mfma_f32_16x16x32_bf16 v[44:47], v[128:131], v[152:155], v[44:47]
	v_mfma_f32_16x16x32_bf16 v[40:43], v[136:139], v[152:155], v[40:43]
	v_mfma_f32_16x16x32_bf16 v[28:31], v[128:131], v[176:179], v[28:31]
	v_mfma_f32_16x16x32_bf16 v[24:27], v[136:139], v[176:179], v[24:27]
	v_mfma_f32_16x16x32_bf16 v[12:15], v[128:131], v[184:187], v[12:15]
	v_mfma_f32_16x16x32_bf16 v[8:11], v[136:139], v[184:187], v[8:11]
	v_mfma_f32_16x16x32_bf16 v[60:63], v[132:135], v[148:151], v[60:63]
	v_mfma_f32_16x16x32_bf16 v[56:59], v[140:143], v[148:151], v[56:59]
	v_mfma_f32_16x16x32_bf16 v[44:47], v[132:135], v[156:159], v[44:47]
	v_mfma_f32_16x16x32_bf16 v[40:43], v[140:143], v[156:159], v[40:43]
	v_mfma_f32_16x16x32_bf16 v[28:31], v[132:135], v[180:183], v[28:31]
	v_mfma_f32_16x16x32_bf16 v[24:27], v[140:143], v[180:183], v[24:27]
	v_mfma_f32_16x16x32_bf16 v[12:15], v[132:135], v[198:201], v[12:15]
	v_mfma_f32_16x16x32_bf16 v[8:11], v[140:143], v[198:201], v[8:11]
	s_barrier
	s_add_u32 s56, s30, 0x80000
	s_addc_u32 s57, s31, 0
	s_add_i32 s55, s48, s40
	s_mov_b32 m0, s55
	s_nop 0
	global_load_lds_dwordx4 v162, s[56:57]
	s_add_i32 m0, s55, 0x2000
	s_nop 0
	global_load_lds_dwordx4 v166, s[56:57]
	s_add_i32 s55, 0, 0x18000
	v_add_u32_e32 v140, s55, v191
	ds_read_b128 v[128:131], v140
	ds_read_b128 v[132:135], v140 offset:1024
	ds_read_b128 v[136:139], v140 offset:2048
	ds_read_b128 v[140:143], v140 offset:3072
	s_waitcnt vmcnt(6)
	s_barrier
; #define PG8_STAGE(bufoff, gbase, voff) do { _Pragma("unroll") for (int _i = 0; _i < 2; ++_i) \
;         __builtin_amdgcn_global_load_lds((const unsigned*)((const char*)(gbase) + (voff)[_i]), (LAS unsigned*)(lds + (bufoff) + ldsw + _i * 8192), 16, 0, 0); } while (0)
; #define PG8_LDA(dst, b, h) do { _Pragma("unroll") for (int m = 0; m < 4; ++m) _Pragma("unroll") for (int k = 0; k < 2; ++k) dst[m][k] = *(const LAS bf16x8*)(lds + PG8_SA(b, h) + aoff + m * 2048 + k * 1024); } while (0)
; #define PG8_LDB(dst, b, h) do { _Pragma("unroll") for (int n = 0; n < 2; ++n) _Pragma("unroll") for (int k = 0; k < 2; ++k) dst[n][k] = *(const LAS bf16x8*)(lds + PG8_SB(b, h) + boff + n * 2048 + k * 1024); } while (0)
; #define PG8_MMA(ai, bj, At, Bt) do { __builtin_amdgcn_s_setprio(1); _Pragma("unroll") for (int m = 0; m < 4; ++m) _Pragma("unroll") for (int n = 0; n < 2; ++n) _Pragma("unroll") for (int k = 0; k < 2; ++k) \
;         acc[ai][bj][m][n] = __builtin_amdgcn_mfma_f32_16x16x32_bf16(Bt[n][k], At[m][k], acc[ai][bj][m][n], 0, 0, 0); __builtin_amdgcn_s_setprio(0); } while (0)
; #define PG8_WAIT_V(n) asm volatile("s_waitcnt vmcnt(" #n ")" ::: "memory")
; #define PG8_WAIT_L(n) asm volatile("s_waitcnt lgkmcnt(" #n ")" ::: "memory")
; #define PG8_BAR __builtin_amdgcn_s_barrier()
; #define PG8_SCHED __builtin_amdgcn_sched_barrier(0)
; template <class Epi>
; __device__ __forceinline__ void gemm_phase(LAS unsigned char* lds, const Gemm g, const StaticOrder& S, const Epi& E, int wv) {
;     ...
;             PG8_LDB(B0, 1, 0); PG8_SCHED; PG8_LDA(At, 1, 0); PG8_STAGE(PG8_SA(0, 1), a2 + hstepA, voffA);
;             PG8_WAIT_L(8); PG8_BAR; PG8_WAIT_L(0); PG8_MMA(0, 0, At, B0); PG8_BAR; PG8_SCHED;
;             PG8_LDB(B1, 1, 1); PG8_STAGE(PG8_SB(1, 0), b3, voffB);
;             PG8_BAR; PG8_WAIT_L(0); PG8_MMA(0, 1, At, B1); PG8_BAR;
;             PG8_LDA(At, 1, 1); PG8_STAGE(PG8_SA(1, 0), a3, voffA);
;             PG8_BAR; PG8_WAIT_L(0); PG8_MMA(1, 0, At, B0); PG8_BAR; PG8_SCHED;
;             PG8_STAGE(PG8_SB(1, 1), b3 + hstepB, voffB);
;             PG8_WAIT_V(6); PG8_BAR; PG8_MMA(1, 1, At, B1); PG8_BAR;
	v_mfma_f32_16x16x32_bf16 v[52:55], v[202:205], v[144:147], v[52:55]
	v_mfma_f32_16x16x32_bf16 v[48:51], v[210:213], v[144:147], v[48:51]
	v_mfma_f32_16x16x32_bf16 v[36:39], v[202:205], v[152:155], v[36:39]
	v_mfma_f32_16x16x32_bf16 v[32:35], v[210:213], v[152:155], v[32:35]
	v_mfma_f32_16x16x32_bf16 v[20:23], v[202:205], v[176:179], v[20:23]
	v_mfma_f32_16x16x32_bf16 v[16:19], v[210:213], v[176:179], v[16:19]
	v_mfma_f32_16x16x32_bf16 v[4:7], v[202:205], v[184:187], v[4:7]
	v_mfma_f32_16x16x32_bf16 v[0:3], v[210:213], v[184:187], v[0:3]
	v_mfma_f32_16x16x32_bf16 v[52:55], v[206:209], v[148:151], v[52:55]
	v_mfma_f32_16x16x32_bf16 v[48:51], v[214:217], v[148:151], v[48:51]
	v_mfma_f32_16x16x32_bf16 v[36:39], v[206:209], v[156:159], v[36:39]
	v_mfma_f32_16x16x32_bf16 v[32:35], v[214:217], v[156:159], v[32:35]
	v_mfma_f32_16x16x32_bf16 v[20:23], v[206:209], v[180:183], v[20:23]
	v_mfma_f32_16x16x32_bf16 v[16:19], v[214:217], v[180:183], v[16:19]
	v_mfma_f32_16x16x32_bf16 v[4:7], v[206:209], v[198:201], v[4:7]
	v_mfma_f32_16x16x32_bf16 v[0:3], v[214:217], v[198:201], v[0:3]
	s_waitcnt lgkmcnt(0)
	s_barrier
	s_add_u32 s34, s34, 0x80000
	s_addc_u32 s35, s35, 0
	s_mov_b32 m0, s42
	ds_read_b128 v[144:147], v194 offset:32768
	ds_read_b128 v[148:151], v194 offset:33792
	ds_read_b128 v[152:155], v194 offset:34816
	ds_read_b128 v[156:159], v194 offset:35840
	ds_read_b128 v[176:179], v194 offset:36864
	ds_read_b128 v[180:183], v194 offset:37888
	ds_read_b128 v[184:187], v194 offset:38912
	ds_read_b128 v[198:201], v194 offset:39936
	global_load_lds_dwordx4 v160, s[34:35]
	s_mov_b32 m0, s43
	s_nop 0
	global_load_lds_dwordx4 v164, s[34:35]
	s_waitcnt lgkmcnt(8)
	s_barrier
	s_waitcnt lgkmcnt(0)
	s_waitcnt lgkmcnt(0)
	v_mfma_f32_16x16x32_bf16 v[124:127], v[128:131], v[144:147], v[124:127]
	v_mfma_f32_16x16x32_bf16 v[120:123], v[136:139], v[144:147], v[120:123]
	v_mfma_f32_16x16x32_bf16 v[108:111], v[128:131], v[152:155], v[108:111]
	v_mfma_f32_16x16x32_bf16 v[104:107], v[136:139], v[152:155], v[104:107]
	v_mfma_f32_16x16x32_bf16 v[92:95], v[128:131], v[176:179], v[92:95]
	v_mfma_f32_16x16x32_bf16 v[88:91], v[136:139], v[176:179], v[88:91]
	v_mfma_f32_16x16x32_bf16 v[76:79], v[128:131], v[184:187], v[76:79]
	v_mfma_f32_16x16x32_bf16 v[72:75], v[136:139], v[184:187], v[72:75]
	v_mfma_f32_16x16x32_bf16 v[124:127], v[132:135], v[148:151], v[124:127]
	v_mfma_f32_16x16x32_bf16 v[120:123], v[140:143], v[148:151], v[120:123]
	v_mfma_f32_16x16x32_bf16 v[108:111], v[132:135], v[156:159], v[108:111]
	v_mfma_f32_16x16x32_bf16 v[104:107], v[140:143], v[156:159], v[104:107]
	v_mfma_f32_16x16x32_bf16 v[92:95], v[132:135], v[180:183], v[92:95]
	v_mfma_f32_16x16x32_bf16 v[88:91], v[140:143], v[180:183], v[88:91]
	v_mfma_f32_16x16x32_bf16 v[76:79], v[132:135], v[198:201], v[76:79]
	v_mfma_f32_16x16x32_bf16 v[72:75], v[140:143], v[198:201], v[72:75]
	s_barrier
	s_add_i32 s34, 0, 0x1c000
	s_add_i32 s35, s55, s40
	v_add_u32_e32 v197, s34, v191
	s_mov_b32 m0, s35
	ds_read_b128 v[202:205], v197
	ds_read_b128 v[206:209], v197 offset:1024
	ds_read_b128 v[210:213], v197 offset:2048
	ds_read_b128 v[214:217], v197 offset:3072
	global_load_lds_dwordx4 v162, s[98:99]
	s_add_i32 m0, s35, 0x2000
	s_nop 0
	global_load_lds_dwordx4 v166, s[98:99]
	s_barrier
	s_waitcnt lgkmcnt(0)
	s_waitcnt lgkmcnt(0)
	v_mfma_f32_16x16x32_bf16 v[116:119], v[202:205], v[144:147], v[116:119]
	v_mfma_f32_16x16x32_bf16 v[112:115], v[210:213], v[144:147], v[112:115]
	v_mfma_f32_16x16x32_bf16 v[100:103], v[202:205], v[152:155], v[100:103]
	v_mfma_f32_16x16x32_bf16 v[96:99], v[210:213], v[152:155], v[96:99]
	v_mfma_f32_16x16x32_bf16 v[84:87], v[202:205], v[176:179], v[84:87]
	v_mfma_f32_16x16x32_bf16 v[80:83], v[210:213], v[176:179], v[80:83]
	v_mfma_f32_16x16x32_bf16 v[68:71], v[202:205], v[184:187], v[68:71]
	v_mfma_f32_16x16x32_bf16 v[64:67], v[210:213], v[184:187], v[64:67]
	v_mfma_f32_16x16x32_bf16 v[116:119], v[206:209], v[148:151], v[116:119]
	v_mfma_f32_16x16x32_bf16 v[112:115], v[214:217], v[148:151], v[112:115]
	v_mfma_f32_16x16x32_bf16 v[100:103], v[206:209], v[156:159], v[100:103]
	v_mfma_f32_16x16x32_bf16 v[96:99], v[214:217], v[156:159], v[96:99]
	v_mfma_f32_16x16x32_bf16 v[84:87], v[206:209], v[180:183], v[84:87]
	v_mfma_f32_16x16x32_bf16 v[80:83], v[214:217], v[180:183], v[80:83]
	v_mfma_f32_16x16x32_bf16 v[68:71], v[206:209], v[198:201], v[68:71]
	v_mfma_f32_16x16x32_bf16 v[64:67], v[214:217], v[198:201], v[64:67]
	s_mov_b32 m0, s45
	s_barrier
	ds_read_b128 v[144:147], v194 offset:49152
	ds_read_b128 v[148:151], v194 offset:50176
	ds_read_b128 v[152:155], v194 offset:51200
	ds_read_b128 v[156:159], v194 offset:52224
	ds_read_b128 v[176:179], v194 offset:53248
	ds_read_b128 v[180:183], v194 offset:54272
	ds_read_b128 v[184:187], v194 offset:55296
	ds_read_b128 v[198:201], v194 offset:56320
	global_load_lds_dwordx4 v160, s[100:101]
	s_mov_b32 m0, s46
	s_nop 0
	global_load_lds_dwordx4 v164, s[100:101]
	s_waitcnt vmcnt(10)
	s_barrier
	s_waitcnt lgkmcnt(0)
	s_waitcnt lgkmcnt(0)
	v_mfma_f32_16x16x32_bf16 v[60:63], v[128:131], v[144:147], v[60:63]
	v_mfma_f32_16x16x32_bf16 v[56:59], v[136:139], v[144:147], v[56:59]
	v_mfma_f32_16x16x32_bf16 v[44:47], v[128:131], v[152:155], v[44:47]
	v_mfma_f32_16x16x32_bf16 v[40:43], v[136:139], v[152:155], v[40:43]
	v_mfma_f32_16x16x32_bf16 v[28:31], v[128:131], v[176:179], v[28:31]
	v_mfma_f32_16x16x32_bf16 v[24:27], v[136:139], v[176:179], v[24:27]
	v_mfma_f32_16x16x32_bf16 v[12:15], v[128:131], v[184:187], v[12:15]
	v_mfma_f32_16x16x32_bf16 v[8:11], v[136:139], v[184:187], v[8:11]
	v_mfma_f32_16x16x32_bf16 v[60:63], v[132:135], v[148:151], v[60:63]
	v_mfma_f32_16x16x32_bf16 v[56:59], v[140:143], v[148:151], v[56:59]
	v_mfma_f32_16x16x32_bf16 v[44:47], v[132:135], v[156:159], v[44:47]
	v_mfma_f32_16x16x32_bf16 v[40:43], v[140:143], v[156:159], v[40:43]
	v_mfma_f32_16x16x32_bf16 v[28:31], v[132:135], v[180:183], v[28:31]
	v_mfma_f32_16x16x32_bf16 v[24:27], v[140:143], v[180:183], v[24:27]
	v_mfma_f32_16x16x32_bf16 v[12:15], v[132:135], v[198:201], v[12:15]
	v_mfma_f32_16x16x32_bf16 v[8:11], v[140:143], v[198:201], v[8:11]
	s_barrier
; #define PG8_WAIT_V(n) asm volatile("s_waitcnt vmcnt(" #n ")" ::: "memory")
; template <class Epi>
; __device__ __forceinline__ void gemm_phase(LAS unsigned char* lds, const Gemm g, const StaticOrder& S, const Epi& E, int wv) {
;     ...
;             PG8_BAR; PG8_WAIT_L(0); PG8_MMA(1, 0, At, B0); PG8_BAR; PG8_SCHED;
;             PG8_STAGE(PG8_SB(1, 1), b3 + hstepB, voffB);
;             PG8_WAIT_V(6); PG8_BAR; PG8_MMA(1, 1, At, B1); PG8_BAR;
;     __device__ __forceinline__ void operator()(const f32x4 (&acc)[2][2][4][2], const Unit& u, int wr, int wc, int fr, int fq) const {
;     ...
;         RES_LOAD(0, 0); RES_LOAD(1, 1);
; #pragma unroll
;         for (int it = 0; it < 8; ++it) { const int ai = it >> 2, m = it & 3, sc = it % RD;
;             if (it + RD - 1 < 8) RES_LOAD((it + RD - 1) % RD, it + RD - 1);
;             asm volatile("" ::: "memory");
;             const int row = row0 + ai * HALF + m * 16; const size_t ro = (size_t)row * DM + col0;
;             float rs = 1.0f; if (MODE == 1) rs = __builtin_amdgcn_rsqf(ss_fix(rsb[sc]) * (1.0f / DM) + EPS);
;             float sq = 0.f;
; #pragma unroll
;             for (int bj = 0; bj < 2; ++bj) { const size_t off = ro + bj * HALF;
;                 f32x4 v0 = acc[ai][bj][m][0], v1 = acc[ai][bj][m][1];
;                 if (MODE == 1) { const u32x4 pw = pbuf[sc][bj];
;                     v0[0] = fast_sigmoid(rs * v0[0]) * bf_lo(pw.x); v0[1] = fast_sigmoid(rs * v0[1]) * bf_hi(pw.x); v0[2] = fast_sigmoid(rs * v0[2]) * bf_lo(pw.y); v0[3] = fast_sigmoid(rs * v0[3]) * bf_hi(pw.y);
;                     v1[0] = fast_sigmoid(rs * v1[0]) * bf_lo(pw.z); v1[1] = fast_sigmoid(rs * v1[1]) * bf_hi(pw.z); v1[2] = fast_sigmoid(rs * v1[2]) * bf_lo(pw.w); v1[3] = fast_sigmoid(rs * v1[3]) * bf_hi(pw.w); }
;                 f32x4 h0, h1;
;                 if (IN16) { const u32x4 hw = hraw[sc][bj]; h0 = (f32x4){bf_lo(hw.x), bf_hi(hw.x), bf_lo(hw.y), bf_hi(hw.y)}; h1 = (f32x4){bf_lo(hw.z), bf_hi(hw.z), bf_lo(hw.w), bf_hi(hw.w)}; }
;                 else { h0 = hbuf[sc][2 * bj]; h1 = hbuf[sc][2 * bj + 1]; }
;                 const f32x4 o0 = h0 + v0, o1 = h1 + v1;
;                 if (OUT32) { *(f32x4*)(hout + off) = o0; *(f32x4*)(hout + off + 4) = o1; }
;                 if (hb) { u32x4 w; w.x = pk_bf16(o0[0], o0[1]); w.y = pk_bf16(o0[2], o0[3]); w.z = pk_bf16(o1[0], o1[1]); w.w = pk_bf16(o1[2], o1[3]); *(u32x4*)(hb + off) = w; }
	s_add_u32 s30, s30, 0x80080
	s_addc_u32 s31, s31, 0
	s_add_i32 s34, s34, s40
	s_mov_b32 m0, s34
	s_nop 0
	global_load_lds_dwordx4 v162, s[30:31]
	s_add_i32 m0, s34, 0x2000
	s_nop 0
	global_load_lds_dwordx4 v166, s[30:31]
	ds_read_b128 v[128:131], v193
	ds_read_b128 v[132:135], v193 offset:1024
	ds_read_b128 v[136:139], v193 offset:2048
	ds_read_b128 v[140:143], v193 offset:3072
	s_waitcnt vmcnt(6)
	s_barrier
	v_mfma_f32_16x16x32_bf16 v[52:55], v[202:205], v[144:147], v[52:55]
	v_mfma_f32_16x16x32_bf16 v[48:51], v[210:213], v[144:147], v[48:51]
	v_mfma_f32_16x16x32_bf16 v[36:39], v[202:205], v[152:155], v[36:39]
	v_mfma_f32_16x16x32_bf16 v[32:35], v[210:213], v[152:155], v[32:35]
	v_mfma_f32_16x16x32_bf16 v[20:23], v[202:205], v[176:179], v[20:23]
	v_mfma_f32_16x16x32_bf16 v[16:19], v[210:213], v[176:179], v[16:19]
	v_mfma_f32_16x16x32_bf16 v[4:7], v[202:205], v[184:187], v[4:7]
	v_mfma_f32_16x16x32_bf16 v[0:3], v[210:213], v[184:187], v[0:3]
	v_mfma_f32_16x16x32_bf16 v[52:55], v[206:209], v[148:151], v[52:55]
	v_mfma_f32_16x16x32_bf16 v[48:51], v[214:217], v[148:151], v[48:51]
	v_mfma_f32_16x16x32_bf16 v[36:39], v[206:209], v[156:159], v[36:39]
	v_mfma_f32_16x16x32_bf16 v[32:35], v[214:217], v[156:159], v[32:35]
	v_mfma_f32_16x16x32_bf16 v[20:23], v[206:209], v[180:183], v[20:23]
	v_mfma_f32_16x16x32_bf16 v[16:19], v[214:217], v[180:183], v[16:19]
	v_mfma_f32_16x16x32_bf16 v[4:7], v[206:209], v[198:201], v[4:7]
	v_mfma_f32_16x16x32_bf16 v[0:3], v[214:217], v[198:201], v[0:3]
	s_waitcnt lgkmcnt(0)
	s_add_i32 s54, s54, 2
	s_add_u32 s52, s52, 0x100
	s_addc_u32 s53, s53, 0
	s_add_u32 s28, s28, 0x100
	s_addc_u32 s29, s29, 0
	s_cmp_gt_u32 s54, 29
	s_barrier
	s_cbranch_scc0 .LBB0_1853
	v_lshl_add_u32 v178, s24, 8, v190
	v_lshl_or_b32 v176, s49, 8, v192
	v_ashrrev_i32_e32 v179, 31, v178
	v_lshlrev_b64 v[128:129], 11, v[178:179]
	v_ashrrev_i32_e32 v177, 31, v176
	v_lshl_add_u64 v[186:187], v[128:129], 0, v[176:177]
	v_lshlrev_b64 v[128:129], 1, v[186:187]
	v_lshl_add_u64 v[180:181], v[178:179], 2, s[8:9]
	v_lshl_add_u64 v[130:131], s[10:11], 0, v[128:129]
	global_load_dword v184, v[180:181], off
	global_load_dwordx4 v[198:201], v[130:131], off
	v_or_b32_e32 v130, 32, v178
	v_ashrrev_i32_e32 v131, 31, v130
	v_lshl_add_u64 v[132:133], v[130:131], 2, s[8:9]
	global_load_dword v179, v[132:133], off
	v_or_b32_e32 v132, 16, v178
	v_ashrrev_i32_e32 v133, 31, v132
	v_lshlrev_b64 v[134:135], 11, v[132:133]
	v_lshl_add_u64 v[132:133], v[132:133], 2, s[8:9]
	global_load_dword v197, v[132:133], off
	v_lshl_add_u64 v[132:133], s[6:7], 0, v[128:129]
	global_load_dwordx4 v[202:205], v[132:133], off
	v_lshlrev_b64 v[130:131], 11, v[130:131]
	v_lshl_add_u64 v[188:189], v[134:135], 0, v[176:177]
	v_or_b32_e32 v128, 0x100, v128
	v_lshl_add_u64 v[182:183], v[130:131], 0, v[176:177]
	v_lshlrev_b64 v[130:131], 1, v[188:189]
	v_lshl_add_u64 v[134:135], s[6:7], 0, v[128:129]
	v_lshl_add_u64 v[128:129], s[10:11], 0, v[128:129]
	v_lshl_add_u64 v[136:137], s[6:7], 0, v[130:131]
	v_lshl_add_u64 v[138:139], s[10:11], 0, v[130:131]
	global_load_dwordx4 v[206:209], v[134:135], off
	global_load_dwordx4 v[210:213], v[128:129], off
	global_load_dwordx4 v[152:155], v[136:137], off
	global_load_dwordx4 v[156:159], v[138:139], off
	v_lshlrev_b64 v[132:133], 1, v[182:183]
	v_or_b32_e32 v130, 0x100, v130
	v_lshl_add_u64 v[140:141], s[6:7], 0, v[132:133]
	v_lshl_add_u64 v[142:143], s[10:11], 0, v[132:133]
	v_or_b32_e32 v132, 0x100, v132
	v_lshl_add_u64 v[128:129], s[6:7], 0, v[130:131]
	v_lshl_add_u64 v[130:131], s[10:11], 0, v[130:131]
	v_lshl_add_u64 v[134:135], s[6:7], 0, v[132:133]
	v_lshl_add_u64 v[132:133], s[10:11], 0, v[132:133]
	global_load_dwordx4 v[136:139], v[140:141], off
	s_nop 0
	global_load_dwordx4 v[140:143], v[142:143], off
	s_nop 0
	global_load_dwordx4 v[144:147], v[128:129], off
	global_load_dwordx4 v[148:151], v[130:131], off
	s_nop 0
	global_load_dwordx4 v[128:131], v[134:135], off
	s_nop 0
	global_load_dwordx4 v[132:135], v[132:133], off
	s_and_b64 vcc, exec, s[0:1]
	s_mov_b32 s49, s16
	s_mov_b32 s24, s18
	s_mov_b64 s[28:29], s[22:23]
	s_mov_b64 s[30:31], s[20:21]
	s_waitcnt vmcnt(0)
	v_cvt_f32_u32_e32 v214, v184
	v_lshlrev_b32_e32 v184, 16, v198
	v_and_b32_e32 v185, 0xffff0000, v198
	v_and_b32_e32 v215, 0xffff0000, v200
	v_mul_f32_e32 v214, 0x3b800000, v214
	v_fmamk_f32 v214, v214, 0x3a000000, v196
	v_rsq_f32_e32 v220, v214
	v_lshlrev_b32_e32 v214, 16, v200
	v_lshlrev_b32_e32 v200, 16, v201
	v_and_b32_e32 v201, 0xffff0000, v201
	v_mul_f32_e32 v124, v124, v220
	v_mul_f32_e32 v125, v125, v220
	v_mul_f32_e32 v126, v126, v220
	v_mul_f32_e32 v127, v127, v220
	v_mul_f32_e32 v120, v120, v220
	v_mul_f32_e32 v121, v121, v220
	v_mul_f32_e32 v122, v122, v220
	v_mul_f32_e32 v123, v123, v220
	v_mul_f32_e32 v124, 0xbfb8aa3b, v124
	v_mul_f32_e32 v125, 0xbfb8aa3b, v125
	v_mul_f32_e32 v126, 0xbfb8aa3b, v126
	v_mul_f32_e32 v127, 0xbfb8aa3b, v127
	v_mul_f32_e32 v120, 0xbfb8aa3b, v120
	v_mul_f32_e32 v121, 0xbfb8aa3b, v121
	v_mul_f32_e32 v122, 0xbfb8aa3b, v122
	v_mul_f32_e32 v123, 0xbfb8aa3b, v123
	v_exp_f32_e32 v124, v124
	v_exp_f32_e32 v125, v125
	v_exp_f32_e32 v126, v126
	v_exp_f32_e32 v127, v127
	v_exp_f32_e32 v120, v120
	v_exp_f32_e32 v121, v121
	v_exp_f32_e32 v122, v122
	v_exp_f32_e32 v123, v123
	v_mul_f32_e32 v112, v112, v220
	v_add_f32_e32 v124, 1.0, v124
	v_add_f32_e32 v125, 1.0, v125
	v_add_f32_e32 v126, 1.0, v126
	v_add_f32_e32 v127, 1.0, v127
	v_add_f32_e32 v216, 1.0, v120
	v_add_f32_e32 v217, 1.0, v121
	v_add_f32_e32 v218, 1.0, v122
	v_add_f32_e32 v219, 1.0, v123
	v_mul_f32_e32 v112, 0xbfb8aa3b, v112
	v_mul_f32_e32 v113, v113, v220
	v_rcp_f32_e32 v120, v124
; __device__ __forceinline__ float bf_lo(unsigned w) { return __uint_as_float(w << 16); }
; __device__ __forceinline__ float bf_hi(unsigned w) { return __uint_as_float(w & 0xffff0000u); }
; __device__ __forceinline__ float fast_sigmoid(float x) { return __builtin_amdgcn_rcpf(1.0f + __builtin_amdgcn_exp2f(-x * LOG2E)); }
; __device__ __forceinline__ float ss_fix(float raw) { return (float)__float_as_uint(raw) * (1.0f / 256.0f); }
;     __device__ __forceinline__ void operator()(const f32x4 (&acc)[2][2][4][2], const Unit& u, int wr, int wc, int fr, int fq) const {
;     ...
;             const int row = row0 + ai * HALF + m * 16; const size_t ro = (size_t)row * DM + col0;
;             float rs = 1.0f; if (MODE == 1) rs = __builtin_amdgcn_rsqf(ss_fix(rsb[sc]) * (1.0f / DM) + EPS);
;             float sq = 0.f;
; #pragma unroll
;             for (int bj = 0; bj < 2; ++bj) { const size_t off = ro + bj * HALF;
;                 f32x4 v0 = acc[ai][bj][m][0], v1 = acc[ai][bj][m][1];
;                 if (MODE == 1) { const u32x4 pw = pbuf[sc][bj];
;                     v0[0] = fast_sigmoid(rs * v0[0]) * bf_lo(pw.x); v0[1] = fast_sigmoid(rs * v0[1]) * bf_hi(pw.x); v0[2] = fast_sigmoid(rs * v0[2]) * bf_lo(pw.y); v0[3] = fast_sigmoid(rs * v0[3]) * bf_hi(pw.y);
;                     v1[0] = fast_sigmoid(rs * v1[0]) * bf_lo(pw.z); v1[1] = fast_sigmoid(rs * v1[1]) * bf_hi(pw.z); v1[2] = fast_sigmoid(rs * v1[2]) * bf_lo(pw.w); v1[3] = fast_sigmoid(rs * v1[3]) * bf_hi(pw.w); }
;                 f32x4 h0, h1;
;                 if (IN16) { const u32x4 hw = hraw[sc][bj]; h0 = (f32x4){bf_lo(hw.x), bf_hi(hw.x), bf_lo(hw.y), bf_hi(hw.y)}; h1 = (f32x4){bf_lo(hw.z), bf_hi(hw.z), bf_lo(hw.w), bf_hi(hw.w)}; }
;                 else { h0 = hbuf[sc][2 * bj]; h1 = hbuf[sc][2 * bj + 1]; }
;                 const f32x4 o0 = h0 + v0, o1 = h1 + v1;
;                 if (OUT32) { *(f32x4*)(hout + off) = o0; *(f32x4*)(hout + off + 4) = o1; }
;                 if (hb) { u32x4 w; w.x = pk_bf16(o0[0], o0[1]); w.y = pk_bf16(o0[2], o0[3]); w.z = pk_bf16(o1[0], o1[1]); w.w = pk_bf16(o1[2], o1[3]); *(u32x4*)(hb + off) = w; }
;                 sq += ((o0[0] * o0[0] + o0[1] * o0[1]) + (o0[2] * o0[2] + o0[3] * o0[3])) + ((o1[0] * o1[0] + o1[1] * o1[1]) + (o1[2] * o1[2] + o1[3] * o1[3])); }
	v_rcp_f32_e32 v121, v125
	v_rcp_f32_e32 v122, v126
	v_rcp_f32_e32 v123, v127
	v_rcp_f32_e32 v124, v216
	v_rcp_f32_e32 v125, v217
	v_rcp_f32_e32 v126, v218
	v_rcp_f32_e32 v127, v219
	v_exp_f32_e32 v112, v112
	v_mul_f32_e32 v113, 0xbfb8aa3b, v113
	v_exp_f32_e32 v113, v113
	v_lshlrev_b32_e32 v216, 16, v202
	v_and_b32_e32 v217, 0xffff0000, v202
	v_lshlrev_b32_e32 v218, 16, v204
	v_and_b32_e32 v219, 0xffff0000, v204
	v_lshlrev_b32_e32 v204, 16, v205
	v_and_b32_e32 v205, 0xffff0000, v205
	v_pk_fma_f32 v[120:121], v[120:121], v[184:185], v[216:217]
	v_pk_fma_f32 v[126:127], v[126:127], v[200:201], v[204:205]
	v_pk_fma_f32 v[124:125], v[124:125], v[214:215], v[218:219]
	v_lshl_add_u64 v[184:185], v[186:187], 2, s[4:5]
	v_add_f32_e32 v112, 1.0, v112
	global_store_dwordx4 v[184:185], v[124:127], off offset:16
	v_mul_f32_e32 v116, v116, v220
	v_mul_f32_e32 v117, v117, v220
	v_rcp_f32_e32 v124, v112
	v_add_f32_e32 v112, 1.0, v113
	v_rcp_f32_e32 v125, v112
	v_mul_f32_e32 v112, v114, v220
	v_mul_f32_e32 v118, v118, v220
	v_mul_f32_e32 v119, v119, v220
	v_mul_f32_e32 v112, 0xbfb8aa3b, v112
	v_mul_f32_e32 v113, v115, v220
	v_mul_f32_e32 v116, 0xbfb8aa3b, v116
	v_mul_f32_e32 v117, 0xbfb8aa3b, v117
	v_mul_f32_e32 v118, 0xbfb8aa3b, v118
	v_mul_f32_e32 v119, 0xbfb8aa3b, v119
	v_exp_f32_e32 v112, v112
	v_mul_f32_e32 v113, 0xbfb8aa3b, v113
	v_exp_f32_e32 v116, v116
	v_exp_f32_e32 v117, v117
	v_exp_f32_e32 v118, v118
	v_exp_f32_e32 v119, v119
	v_exp_f32_e32 v113, v113
	v_lshlrev_b32_e32 v198, 16, v199
	v_and_b32_e32 v199, 0xffff0000, v199
	v_lshlrev_b32_e32 v202, 16, v203
	v_and_b32_e32 v203, 0xffff0000, v203
	v_add_f32_e32 v112, 1.0, v112
	v_pk_fma_f32 v[122:123], v[122:123], v[198:199], v[202:203]
	v_add_f32_e32 v116, 1.0, v116
	v_add_f32_e32 v117, 1.0, v117
	v_add_f32_e32 v118, 1.0, v118
	v_add_f32_e32 v119, 1.0, v119
	v_rcp_f32_e32 v198, v112
	v_add_f32_e32 v112, 1.0, v113
	v_rcp_f32_e32 v116, v116
	v_rcp_f32_e32 v117, v117
	v_rcp_f32_e32 v118, v118
	v_rcp_f32_e32 v119, v119
	v_rcp_f32_e32 v199, v112
	global_store_dwordx4 v[184:185], v[120:123], off
	v_lshlrev_b32_e32 v200, 16, v213
	v_and_b32_e32 v201, 0xffff0000, v213
	v_lshlrev_b32_e32 v120, 16, v210
	v_and_b32_e32 v121, 0xffff0000, v210
	v_lshlrev_b32_e32 v122, 16, v211
	v_and_b32_e32 v123, 0xffff0000, v211
	v_lshlrev_b32_e32 v112, 16, v206
	v_and_b32_e32 v113, 0xffff0000, v206
	v_lshlrev_b32_e32 v114, 16, v207
	v_and_b32_e32 v115, 0xffff0000, v207
	v_lshlrev_b32_e32 v204, 16, v209
	v_and_b32_e32 v205, 0xffff0000, v209
	v_lshlrev_b32_e32 v126, 16, v212
	v_and_b32_e32 v127, 0xffff0000, v212
	v_lshlrev_b32_e32 v202, 16, v208
	v_and_b32_e32 v203, 0xffff0000, v208
	v_pk_fma_f32 v[114:115], v[118:119], v[122:123], v[114:115]
	v_pk_fma_f32 v[112:113], v[116:117], v[120:121], v[112:113]
	v_pk_fma_f32 v[118:119], v[198:199], v[200:201], v[204:205]
	v_pk_fma_f32 v[116:117], v[124:125], v[126:127], v[202:203]
	global_store_dwordx4 v[184:185], v[112:115], off offset:512
	global_store_dwordx4 v[184:185], v[116:119], off offset:528
	v_or_b32_e32 v198, 48, v178
	v_ashrrev_i32_e32 v199, 31, v198
	v_cvt_f32_u32_e32 v118, v197
	v_lshlrev_b64 v[112:113], 11, v[198:199]
	v_lshl_add_u64 v[198:199], v[198:199], 2, s[8:9]
	v_mul_f32_e32 v118, 0x3b800000, v118
	v_fmamk_f32 v118, v118, 0x3a000000, v196
	v_rsq_f32_e32 v197, v118
	global_load_dword v206, v[198:199], off
	v_lshl_add_u64 v[184:185], v[112:113], 0, v[176:177]
	v_lshlrev_b64 v[116:117], 1, v[184:185]
	v_mul_f32_e32 v104, v104, v197
	v_mul_f32_e32 v104, 0xbfb8aa3b, v104
	v_mul_f32_e32 v105, v105, v197
	v_exp_f32_e32 v104, v104
	v_mul_f32_e32 v105, 0xbfb8aa3b, v105
	v_exp_f32_e32 v105, v105
	v_mul_f32_e32 v108, v108, v197
	v_add_f32_e32 v104, 1.0, v104
	v_rcp_f32_e32 v200, v104
	v_add_f32_e32 v104, 1.0, v105
	v_rcp_f32_e32 v201, v104
	v_mul_f32_e32 v104, v106, v197
	v_mul_f32_e32 v109, v109, v197
	v_mul_f32_e32 v110, v110, v197
	v_mul_f32_e32 v111, v111, v197
	v_mul_f32_e32 v104, 0xbfb8aa3b, v104
	v_mul_f32_e32 v105, v107, v197
	v_mul_f32_e32 v108, 0xbfb8aa3b, v108
	v_mul_f32_e32 v109, 0xbfb8aa3b, v109
	v_mul_f32_e32 v110, 0xbfb8aa3b, v110
	v_mul_f32_e32 v111, 0xbfb8aa3b, v111
	v_exp_f32_e32 v104, v104
	v_mul_f32_e32 v105, 0xbfb8aa3b, v105
	v_exp_f32_e32 v108, v108
	v_exp_f32_e32 v109, v109
	v_exp_f32_e32 v110, v110
	v_exp_f32_e32 v111, v111
	v_exp_f32_e32 v105, v105
	v_add_f32_e32 v104, 1.0, v104
	v_mul_f32_e32 v96, v96, v197
	v_add_f32_e32 v108, 1.0, v108
	v_add_f32_e32 v109, 1.0, v109
	v_add_f32_e32 v110, 1.0, v110
	v_add_f32_e32 v111, 1.0, v111
	v_rcp_f32_e32 v204, v104
	v_add_f32_e32 v104, 1.0, v105
	v_mul_f32_e32 v96, 0xbfb8aa3b, v96
	v_mul_f32_e32 v97, v97, v197
	v_rcp_f32_e32 v108, v108
	v_rcp_f32_e32 v109, v109
	v_rcp_f32_e32 v110, v110
	v_rcp_f32_e32 v111, v111
	v_rcp_f32_e32 v205, v104
	v_exp_f32_e32 v96, v96
	v_mul_f32_e32 v97, 0xbfb8aa3b, v97
	v_exp_f32_e32 v97, v97
	v_lshl_add_u64 v[112:113], s[6:7], 0, v[116:117]
	global_load_dwordx4 v[120:123], v[112:113], off
	v_lshl_add_u64 v[112:113], s[10:11], 0, v[116:117]
	v_or_b32_e32 v116, 0x100, v116
	v_lshlrev_b32_e32 v198, 16, v156
	v_and_b32_e32 v199, 0xffff0000, v156
	v_lshlrev_b32_e32 v156, 16, v157
	v_and_b32_e32 v157, 0xffff0000, v157
	v_lshlrev_b32_e32 v202, 16, v158
	v_and_b32_e32 v203, 0xffff0000, v158
	v_lshlrev_b32_e32 v158, 16, v159
	v_and_b32_e32 v159, 0xffff0000, v159
	v_lshlrev_b32_e32 v104, 16, v152
	v_and_b32_e32 v105, 0xffff0000, v152
	v_lshlrev_b32_e32 v106, 16, v153
	v_and_b32_e32 v107, 0xffff0000, v153
	v_lshlrev_b32_e32 v152, 16, v154
	v_and_b32_e32 v153, 0xffff0000, v154
	v_lshlrev_b32_e32 v154, 16, v155
	v_and_b32_e32 v155, 0xffff0000, v155
	global_load_dwordx4 v[124:127], v[112:113], off
; __device__ __forceinline__ float bf_lo(unsigned w) { return __uint_as_float(w << 16); }
; __device__ __forceinline__ float bf_hi(unsigned w) { return __uint_as_float(w & 0xffff0000u); }
; __device__ __forceinline__ float fast_sigmoid(float x) { return __builtin_amdgcn_rcpf(1.0f + __builtin_amdgcn_exp2f(-x * LOG2E)); }
; __device__ __forceinline__ float ss_fix(float raw) { return (float)__float_as_uint(raw) * (1.0f / 256.0f); }
;     __device__ __forceinline__ void operator()(const f32x4 (&acc)[2][2][4][2], const Unit& u, int wr, int wc, int fr, int fq) const {
;     ...
;             const int row = row0 + ai * HALF + m * 16; const size_t ro = (size_t)row * DM + col0;
;             float rs = 1.0f; if (MODE == 1) rs = __builtin_amdgcn_rsqf(ss_fix(rsb[sc]) * (1.0f / DM) + EPS);
;             float sq = 0.f;
; #pragma unroll
;             for (int bj = 0; bj < 2; ++bj) { const size_t off = ro + bj * HALF;
;                 f32x4 v0 = acc[ai][bj][m][0], v1 = acc[ai][bj][m][1];
;                 if (MODE == 1) { const u32x4 pw = pbuf[sc][bj];
;                     v0[0] = fast_sigmoid(rs * v0[0]) * bf_lo(pw.x); v0[1] = fast_sigmoid(rs * v0[1]) * bf_hi(pw.x); v0[2] = fast_sigmoid(rs * v0[2]) * bf_lo(pw.y); v0[3] = fast_sigmoid(rs * v0[3]) * bf_hi(pw.y);
;                     v1[0] = fast_sigmoid(rs * v1[0]) * bf_lo(pw.z); v1[1] = fast_sigmoid(rs * v1[1]) * bf_hi(pw.z); v1[2] = fast_sigmoid(rs * v1[2]) * bf_lo(pw.w); v1[3] = fast_sigmoid(rs * v1[3]) * bf_hi(pw.w); }
;                 f32x4 h0, h1;
;                 if (IN16) { const u32x4 hw = hraw[sc][bj]; h0 = (f32x4){bf_lo(hw.x), bf_hi(hw.x), bf_lo(hw.y), bf_hi(hw.y)}; h1 = (f32x4){bf_lo(hw.z), bf_hi(hw.z), bf_lo(hw.w), bf_hi(hw.w)}; }
;                 else { h0 = hbuf[sc][2 * bj]; h1 = hbuf[sc][2 * bj + 1]; }
;                 const f32x4 o0 = h0 + v0, o1 = h1 + v1;
;                 if (OUT32) { *(f32x4*)(hout + off) = o0; *(f32x4*)(hout + off + 4) = o1; }
;                 if (hb) { u32x4 w; w.x = pk_bf16(o0[0], o0[1]); w.y = pk_bf16(o0[2], o0[3]); w.z = pk_bf16(o1[0], o1[1]); w.w = pk_bf16(o1[2], o1[3]); *(u32x4*)(hb + off) = w; }
;                 sq += ((o0[0] * o0[0] + o0[1] * o0[1]) + (o0[2] * o0[2] + o0[3] * o0[3])) + ((o1[0] * o1[0] + o1[1] * o1[1]) + (o1[2] * o1[2] + o1[3] * o1[3])); }
	v_lshl_add_u64 v[112:113], s[6:7], 0, v[116:117]
	v_lshl_add_u64 v[116:117], s[10:11], 0, v[116:117]
	v_pk_fma_f32 v[106:107], v[110:111], v[156:157], v[106:107]
	v_pk_fma_f32 v[104:105], v[108:109], v[198:199], v[104:105]
	v_pk_fma_f32 v[110:111], v[204:205], v[158:159], v[154:155]
	v_pk_fma_f32 v[108:109], v[200:201], v[202:203], v[152:153]
	v_lshl_add_u64 v[152:153], v[188:189], 2, s[4:5]
	v_add_f32_e32 v96, 1.0, v96
	global_load_dwordx4 v[112:115], v[112:113], off
	v_mul_f32_e32 v100, v100, v197
	global_load_dwordx4 v[116:119], v[116:117], off
	global_store_dwordx4 v[152:153], v[108:111], off offset:16
	v_mul_f32_e32 v101, v101, v197
	v_mul_f32_e32 v102, v102, v197
	v_rcp_f32_e32 v108, v96
	v_add_f32_e32 v96, 1.0, v97
	v_rcp_f32_e32 v109, v96
	v_mul_f32_e32 v96, v98, v197
	v_mul_f32_e32 v103, v103, v197
	v_mul_f32_e32 v96, 0xbfb8aa3b, v96
	v_mul_f32_e32 v97, v99, v197
	v_mul_f32_e32 v100, 0xbfb8aa3b, v100
	v_mul_f32_e32 v101, 0xbfb8aa3b, v101
	v_mul_f32_e32 v102, 0xbfb8aa3b, v102
	v_mul_f32_e32 v103, 0xbfb8aa3b, v103
	v_exp_f32_e32 v96, v96
	v_mul_f32_e32 v97, 0xbfb8aa3b, v97
	v_exp_f32_e32 v100, v100
	v_exp_f32_e32 v101, v101
	v_exp_f32_e32 v102, v102
	v_exp_f32_e32 v103, v103
	v_exp_f32_e32 v97, v97
	v_add_f32_e32 v96, 1.0, v96
	global_store_dwordx4 v[152:153], v[104:107], off
	v_add_f32_e32 v100, 1.0, v100
	v_add_f32_e32 v101, 1.0, v101
	v_lshlrev_b32_e32 v104, 16, v148
	v_and_b32_e32 v105, 0xffff0000, v148
	v_add_f32_e32 v102, 1.0, v102
	v_add_f32_e32 v103, 1.0, v103
	v_rcp_f32_e32 v148, v96
	v_add_f32_e32 v96, 1.0, v97
	v_rcp_f32_e32 v100, v100
	v_rcp_f32_e32 v101, v101
	v_rcp_f32_e32 v102, v102
	v_rcp_f32_e32 v103, v103
	v_lshlrev_b32_e32 v106, 16, v149
	v_and_b32_e32 v107, 0xffff0000, v149
	v_rcp_f32_e32 v149, v96
	v_lshlrev_b32_e32 v110, 16, v150
	v_and_b32_e32 v111, 0xffff0000, v150
	v_lshlrev_b32_e32 v150, 16, v151
	v_and_b32_e32 v151, 0xffff0000, v151
	v_lshlrev_b32_e32 v96, 16, v144
	v_and_b32_e32 v97, 0xffff0000, v144
	v_lshlrev_b32_e32 v98, 16, v145
	v_and_b32_e32 v99, 0xffff0000, v145
	v_lshlrev_b32_e32 v144, 16, v146
	v_and_b32_e32 v145, 0xffff0000, v146
	v_lshlrev_b32_e32 v146, 16, v147
	v_and_b32_e32 v147, 0xffff0000, v147
	v_pk_fma_f32 v[98:99], v[102:103], v[106:107], v[98:99]
	v_pk_fma_f32 v[96:97], v[100:101], v[104:105], v[96:97]
	v_pk_fma_f32 v[102:103], v[148:149], v[150:151], v[146:147]
	v_pk_fma_f32 v[100:101], v[108:109], v[110:111], v[144:145]
	global_store_dwordx4 v[152:153], v[96:99], off offset:512
	global_store_dwordx4 v[152:153], v[100:103], off offset:528
	v_lshl_add_u64 v[144:145], v[186:187], 0, s[14:15]
	v_lshlrev_b32_e32 v146, 16, v140
	v_cvt_f32_u32_e32 v102, v179
	v_lshlrev_b64 v[100:101], 1, v[144:145]
	v_lshl_add_u64 v[96:97], s[6:7], 0, v[100:101]
	global_load_dwordx4 v[104:107], v[96:97], off
	v_mul_f32_e32 v102, 0x3b800000, v102
	v_fmamk_f32 v102, v102, 0x3a000000, v196
	v_rsq_f32_e32 v154, v102
	v_lshl_add_u64 v[96:97], s[10:11], 0, v[100:101]
	v_or_b32_e32 v100, 0x100, v100
	global_load_dwordx4 v[108:111], v[96:97], off
	v_lshl_add_u64 v[96:97], s[6:7], 0, v[100:101]
	v_lshl_add_u64 v[100:101], s[10:11], 0, v[100:101]
	global_load_dwordx4 v[96:99], v[96:97], off
	s_nop 0
	global_load_dwordx4 v[100:103], v[100:101], off
	s_nop 0
	global_load_dword v155, v[180:181], off offset:512
	v_mul_f32_e32 v88, v88, v154
	v_mul_f32_e32 v88, 0xbfb8aa3b, v88
	v_mul_f32_e32 v89, v89, v154
	v_exp_f32_e32 v88, v88
	v_mul_f32_e32 v89, 0xbfb8aa3b, v89
	v_exp_f32_e32 v89, v89
	v_mul_f32_e32 v92, v92, v154
	v_add_f32_e32 v88, 1.0, v88
	v_rcp_f32_e32 v148, v88
	v_add_f32_e32 v88, 1.0, v89
	v_rcp_f32_e32 v149, v88
	v_mul_f32_e32 v88, v90, v154
	v_mul_f32_e32 v93, v93, v154
	v_mul_f32_e32 v94, v94, v154
	v_mul_f32_e32 v95, v95, v154
	v_mul_f32_e32 v88, 0xbfb8aa3b, v88
	v_mul_f32_e32 v89, v91, v154
	v_mul_f32_e32 v92, 0xbfb8aa3b, v92
	v_mul_f32_e32 v93, 0xbfb8aa3b, v93
	v_mul_f32_e32 v94, 0xbfb8aa3b, v94
	v_mul_f32_e32 v95, 0xbfb8aa3b, v95
	v_exp_f32_e32 v88, v88
	v_mul_f32_e32 v89, 0xbfb8aa3b, v89
	v_exp_f32_e32 v92, v92
	v_exp_f32_e32 v93, v93
	v_exp_f32_e32 v94, v94
	v_exp_f32_e32 v95, v95
	v_exp_f32_e32 v89, v89
	v_add_f32_e32 v88, 1.0, v88
	v_mul_f32_e32 v80, v80, v154
	v_add_f32_e32 v92, 1.0, v92
	v_add_f32_e32 v93, 1.0, v93
	v_add_f32_e32 v94, 1.0, v94
	v_add_f32_e32 v95, 1.0, v95
	v_rcp_f32_e32 v152, v88
	v_add_f32_e32 v88, 1.0, v89
	v_mul_f32_e32 v80, 0xbfb8aa3b, v80
	v_mul_f32_e32 v81, v81, v154
	v_rcp_f32_e32 v92, v92
	v_rcp_f32_e32 v93, v93
	v_rcp_f32_e32 v94, v94
	v_rcp_f32_e32 v95, v95
	v_rcp_f32_e32 v153, v88
	v_exp_f32_e32 v80, v80
	v_mul_f32_e32 v81, 0xbfb8aa3b, v81
	v_exp_f32_e32 v81, v81
	v_and_b32_e32 v147, 0xffff0000, v140
	v_lshlrev_b32_e32 v140, 16, v141
	v_and_b32_e32 v141, 0xffff0000, v141
	v_lshlrev_b32_e32 v150, 16, v142
	v_and_b32_e32 v151, 0xffff0000, v142
	v_lshlrev_b32_e32 v142, 16, v143
	v_and_b32_e32 v143, 0xffff0000, v143
	v_lshlrev_b32_e32 v88, 16, v136
	v_and_b32_e32 v89, 0xffff0000, v136
	v_lshlrev_b32_e32 v90, 16, v137
	v_and_b32_e32 v91, 0xffff0000, v137
	v_lshlrev_b32_e32 v136, 16, v138
	v_and_b32_e32 v137, 0xffff0000, v138
	v_lshlrev_b32_e32 v138, 16, v139
	v_and_b32_e32 v139, 0xffff0000, v139
	v_pk_fma_f32 v[90:91], v[94:95], v[140:141], v[90:91]
	v_pk_fma_f32 v[88:89], v[92:93], v[146:147], v[88:89]
	v_pk_fma_f32 v[94:95], v[152:153], v[142:143], v[138:139]
	v_pk_fma_f32 v[92:93], v[148:149], v[150:151], v[136:137]
	v_lshl_add_u64 v[136:137], v[182:183], 2, s[4:5]
	v_add_f32_e32 v80, 1.0, v80
	global_store_dwordx4 v[136:137], v[92:95], off offset:16
	v_mul_f32_e32 v84, v84, v154
	v_mul_f32_e32 v85, v85, v154
	v_rcp_f32_e32 v92, v80
	v_add_f32_e32 v80, 1.0, v81
; __device__ __forceinline__ float bf_lo(unsigned w) { return __uint_as_float(w << 16); }
; __device__ __forceinline__ float bf_hi(unsigned w) { return __uint_as_float(w & 0xffff0000u); }
; __device__ __forceinline__ float fast_sigmoid(float x) { return __builtin_amdgcn_rcpf(1.0f + __builtin_amdgcn_exp2f(-x * LOG2E)); }
; __device__ __forceinline__ float ss_fix(float raw) { return (float)__float_as_uint(raw) * (1.0f / 256.0f); }
;     __device__ __forceinline__ void operator()(const f32x4 (&acc)[2][2][4][2], const Unit& u, int wr, int wc, int fr, int fq) const {
;     ...
;             const int row = row0 + ai * HALF + m * 16; const size_t ro = (size_t)row * DM + col0;
;             float rs = 1.0f; if (MODE == 1) rs = __builtin_amdgcn_rsqf(ss_fix(rsb[sc]) * (1.0f / DM) + EPS);
;             float sq = 0.f;
; #pragma unroll
;             for (int bj = 0; bj < 2; ++bj) { const size_t off = ro + bj * HALF;
;                 f32x4 v0 = acc[ai][bj][m][0], v1 = acc[ai][bj][m][1];
;                 if (MODE == 1) { const u32x4 pw = pbuf[sc][bj];
;                     v0[0] = fast_sigmoid(rs * v0[0]) * bf_lo(pw.x); v0[1] = fast_sigmoid(rs * v0[1]) * bf_hi(pw.x); v0[2] = fast_sigmoid(rs * v0[2]) * bf_lo(pw.y); v0[3] = fast_sigmoid(rs * v0[3]) * bf_hi(pw.y);
;                     v1[0] = fast_sigmoid(rs * v1[0]) * bf_lo(pw.z); v1[1] = fast_sigmoid(rs * v1[1]) * bf_hi(pw.z); v1[2] = fast_sigmoid(rs * v1[2]) * bf_lo(pw.w); v1[3] = fast_sigmoid(rs * v1[3]) * bf_hi(pw.w); }
;                 f32x4 h0, h1;
;                 if (IN16) { const u32x4 hw = hraw[sc][bj]; h0 = (f32x4){bf_lo(hw.x), bf_hi(hw.x), bf_lo(hw.y), bf_hi(hw.y)}; h1 = (f32x4){bf_lo(hw.z), bf_hi(hw.z), bf_lo(hw.w), bf_hi(hw.w)}; }
;                 else { h0 = hbuf[sc][2 * bj]; h1 = hbuf[sc][2 * bj + 1]; }
;                 const f32x4 o0 = h0 + v0, o1 = h1 + v1;
;                 if (OUT32) { *(f32x4*)(hout + off) = o0; *(f32x4*)(hout + off + 4) = o1; }
;                 if (hb) { u32x4 w; w.x = pk_bf16(o0[0], o0[1]); w.y = pk_bf16(o0[2], o0[3]); w.z = pk_bf16(o1[0], o1[1]); w.w = pk_bf16(o1[2], o1[3]); *(u32x4*)(hb + off) = w; }
;                 sq += ((o0[0] * o0[0] + o0[1] * o0[1]) + (o0[2] * o0[2] + o0[3] * o0[3])) + ((o1[0] * o1[0] + o1[1] * o1[1]) + (o1[2] * o1[2] + o1[3] * o1[3])); }
	v_rcp_f32_e32 v93, v80
	v_mul_f32_e32 v80, v82, v154
	v_mul_f32_e32 v86, v86, v154
	v_mul_f32_e32 v87, v87, v154
	v_mul_f32_e32 v80, 0xbfb8aa3b, v80
	v_mul_f32_e32 v81, v83, v154
	v_mul_f32_e32 v84, 0xbfb8aa3b, v84
	v_mul_f32_e32 v85, 0xbfb8aa3b, v85
	v_mul_f32_e32 v86, 0xbfb8aa3b, v86
	v_mul_f32_e32 v87, 0xbfb8aa3b, v87
	v_exp_f32_e32 v80, v80
	v_mul_f32_e32 v81, 0xbfb8aa3b, v81
	v_exp_f32_e32 v84, v84
	v_exp_f32_e32 v85, v85
	v_exp_f32_e32 v86, v86
	v_exp_f32_e32 v87, v87
	v_exp_f32_e32 v81, v81
	v_add_f32_e32 v80, 1.0, v80
	global_store_dwordx4 v[136:137], v[88:91], off
	v_add_f32_e32 v84, 1.0, v84
	v_add_f32_e32 v85, 1.0, v85
	v_lshlrev_b32_e32 v88, 16, v132
	v_and_b32_e32 v89, 0xffff0000, v132
	v_add_f32_e32 v86, 1.0, v86
	v_add_f32_e32 v87, 1.0, v87
	v_rcp_f32_e32 v132, v80
	v_add_f32_e32 v80, 1.0, v81
	v_rcp_f32_e32 v84, v84
	v_rcp_f32_e32 v85, v85
	v_rcp_f32_e32 v86, v86
	v_rcp_f32_e32 v87, v87
	v_lshlrev_b32_e32 v90, 16, v133
	v_and_b32_e32 v91, 0xffff0000, v133
	v_rcp_f32_e32 v133, v80
	v_lshlrev_b32_e32 v94, 16, v134
	v_and_b32_e32 v95, 0xffff0000, v134
	v_lshlrev_b32_e32 v134, 16, v135
	v_and_b32_e32 v135, 0xffff0000, v135
	v_lshlrev_b32_e32 v80, 16, v128
	v_and_b32_e32 v81, 0xffff0000, v128
	v_lshlrev_b32_e32 v82, 16, v129
	v_and_b32_e32 v83, 0xffff0000, v129
	v_lshlrev_b32_e32 v128, 16, v130
	v_and_b32_e32 v129, 0xffff0000, v130
	v_lshlrev_b32_e32 v130, 16, v131
	v_and_b32_e32 v131, 0xffff0000, v131
	v_pk_fma_f32 v[82:83], v[86:87], v[90:91], v[82:83]
	v_pk_fma_f32 v[80:81], v[84:85], v[88:89], v[80:81]
	v_pk_fma_f32 v[86:87], v[132:133], v[134:135], v[130:131]
	v_pk_fma_f32 v[84:85], v[92:93], v[94:95], v[128:129]
	global_store_dwordx4 v[136:137], v[80:83], off offset:512
	global_store_dwordx4 v[136:137], v[84:87], off offset:528
	v_add_u32_e32 v128, 0x90, v178
	v_ashrrev_i32_e32 v129, 31, v128
	s_waitcnt vmcnt(0)
	v_cvt_f32_u32_e32 v86, v206
	v_lshlrev_b64 v[80:81], 11, v[128:129]
	v_lshl_add_u64 v[80:81], v[80:81], 0, v[176:177]
	v_lshlrev_b64 v[84:85], 1, v[80:81]
	v_mul_f32_e32 v86, 0x3b800000, v86
	v_fmamk_f32 v86, v86, 0x3a000000, v196
	v_rsq_f32_e32 v138, v86
	v_lshl_add_u64 v[80:81], s[6:7], 0, v[84:85]
	global_load_dwordx4 v[88:91], v[80:81], off
	v_mul_f32_e32 v72, v72, v138
	v_mul_f32_e32 v72, 0xbfb8aa3b, v72
	v_mul_f32_e32 v73, v73, v138
	v_exp_f32_e32 v72, v72
	v_mul_f32_e32 v73, 0xbfb8aa3b, v73
	v_exp_f32_e32 v73, v73
	v_lshl_add_u64 v[80:81], s[10:11], 0, v[84:85]
	v_or_b32_e32 v84, 0x100, v84
	global_load_dwordx4 v[92:95], v[80:81], off
	v_lshl_add_u64 v[80:81], s[6:7], 0, v[84:85]
	v_lshl_add_u64 v[84:85], s[10:11], 0, v[84:85]
	v_add_f32_e32 v72, 1.0, v72
	global_load_dwordx4 v[80:83], v[80:81], off
	s_nop 0
	global_load_dwordx4 v[84:87], v[84:85], off
	s_nop 0
	global_load_dword v139, v[180:181], off offset:576
	v_rcp_f32_e32 v132, v72
	v_add_f32_e32 v72, 1.0, v73
	v_rcp_f32_e32 v133, v72
	v_mul_f32_e32 v72, v74, v138
	v_mul_f32_e32 v76, v76, v138
	v_mul_f32_e32 v77, v77, v138
	v_mul_f32_e32 v78, v78, v138
	v_mul_f32_e32 v79, v79, v138
	v_mul_f32_e32 v72, 0xbfb8aa3b, v72
	v_mul_f32_e32 v73, v75, v138
	v_mul_f32_e32 v76, 0xbfb8aa3b, v76
	v_mul_f32_e32 v77, 0xbfb8aa3b, v77
	v_mul_f32_e32 v78, 0xbfb8aa3b, v78
	v_mul_f32_e32 v79, 0xbfb8aa3b, v79
	v_exp_f32_e32 v72, v72
	v_mul_f32_e32 v73, 0xbfb8aa3b, v73
	v_exp_f32_e32 v76, v76
	v_exp_f32_e32 v77, v77
	v_exp_f32_e32 v78, v78
	v_exp_f32_e32 v79, v79
	v_exp_f32_e32 v73, v73
	v_add_f32_e32 v72, 1.0, v72
	v_mul_f32_e32 v64, v64, v138
	v_add_f32_e32 v76, 1.0, v76
	v_add_f32_e32 v77, 1.0, v77
	v_add_f32_e32 v78, 1.0, v78
	v_add_f32_e32 v79, 1.0, v79
	v_rcp_f32_e32 v136, v72
	v_add_f32_e32 v72, 1.0, v73
	v_mul_f32_e32 v64, 0xbfb8aa3b, v64
	v_mul_f32_e32 v65, v65, v138
	v_rcp_f32_e32 v76, v76
	v_rcp_f32_e32 v77, v77
	v_rcp_f32_e32 v78, v78
	v_rcp_f32_e32 v79, v79
	v_rcp_f32_e32 v137, v72
	v_exp_f32_e32 v64, v64
	v_mul_f32_e32 v65, 0xbfb8aa3b, v65
	v_exp_f32_e32 v65, v65
	v_lshlrev_b32_e32 v130, 16, v124
	v_and_b32_e32 v131, 0xffff0000, v124
	v_lshlrev_b32_e32 v124, 16, v125
	v_and_b32_e32 v125, 0xffff0000, v125
	v_lshlrev_b32_e32 v134, 16, v126
	v_and_b32_e32 v135, 0xffff0000, v126
	v_lshlrev_b32_e32 v126, 16, v127
	v_and_b32_e32 v127, 0xffff0000, v127
	v_lshlrev_b32_e32 v72, 16, v120
	v_and_b32_e32 v73, 0xffff0000, v120
	v_lshlrev_b32_e32 v74, 16, v121
	v_and_b32_e32 v75, 0xffff0000, v121
	v_lshlrev_b32_e32 v120, 16, v122
	v_and_b32_e32 v121, 0xffff0000, v122
	v_lshlrev_b32_e32 v122, 16, v123
	v_and_b32_e32 v123, 0xffff0000, v123
	v_pk_fma_f32 v[74:75], v[78:79], v[124:125], v[74:75]
	v_pk_fma_f32 v[72:73], v[76:77], v[130:131], v[72:73]
	v_pk_fma_f32 v[78:79], v[136:137], v[126:127], v[122:123]
	v_pk_fma_f32 v[76:77], v[132:133], v[134:135], v[120:121]
	v_lshl_add_u64 v[120:121], v[184:185], 2, s[4:5]
	v_add_f32_e32 v64, 1.0, v64
	global_store_dwordx4 v[120:121], v[76:79], off offset:16
	v_mul_f32_e32 v68, v68, v138
	v_mul_f32_e32 v69, v69, v138
	v_rcp_f32_e32 v76, v64
	v_add_f32_e32 v64, 1.0, v65
	v_rcp_f32_e32 v77, v64
	v_mul_f32_e32 v64, v66, v138
	v_mul_f32_e32 v70, v70, v138
	v_mul_f32_e32 v71, v71, v138
	v_mul_f32_e32 v64, 0xbfb8aa3b, v64
	v_mul_f32_e32 v65, v67, v138
	v_mul_f32_e32 v68, 0xbfb8aa3b, v68
	v_mul_f32_e32 v69, 0xbfb8aa3b, v69
	v_mul_f32_e32 v70, 0xbfb8aa3b, v70
	v_mul_f32_e32 v71, 0xbfb8aa3b, v71
	v_exp_f32_e32 v64, v64
	v_mul_f32_e32 v65, 0xbfb8aa3b, v65
	v_exp_f32_e32 v68, v68
	v_exp_f32_e32 v69, v69
	v_exp_f32_e32 v70, v70
	v_exp_f32_e32 v71, v71
	v_exp_f32_e32 v65, v65
	v_add_f32_e32 v64, 1.0, v64
	global_store_dwordx4 v[120:121], v[72:75], off
	v_add_f32_e32 v68, 1.0, v68
	v_add_f32_e32 v69, 1.0, v69
	v_lshlrev_b32_e32 v72, 16, v116
; __device__ __forceinline__ float bf_lo(unsigned w) { return __uint_as_float(w << 16); }
; __device__ __forceinline__ float bf_hi(unsigned w) { return __uint_as_float(w & 0xffff0000u); }
; __device__ __forceinline__ float fast_sigmoid(float x) { return __builtin_amdgcn_rcpf(1.0f + __builtin_amdgcn_exp2f(-x * LOG2E)); }
; __device__ __forceinline__ float ss_fix(float raw) { return (float)__float_as_uint(raw) * (1.0f / 256.0f); }
;     __device__ __forceinline__ void operator()(const f32x4 (&acc)[2][2][4][2], const Unit& u, int wr, int wc, int fr, int fq) const {
;     ...
;             const int row = row0 + ai * HALF + m * 16; const size_t ro = (size_t)row * DM + col0;
;             float rs = 1.0f; if (MODE == 1) rs = __builtin_amdgcn_rsqf(ss_fix(rsb[sc]) * (1.0f / DM) + EPS);
;             float sq = 0.f;
; #pragma unroll
;             for (int bj = 0; bj < 2; ++bj) { const size_t off = ro + bj * HALF;
;                 f32x4 v0 = acc[ai][bj][m][0], v1 = acc[ai][bj][m][1];
;                 if (MODE == 1) { const u32x4 pw = pbuf[sc][bj];
;                     v0[0] = fast_sigmoid(rs * v0[0]) * bf_lo(pw.x); v0[1] = fast_sigmoid(rs * v0[1]) * bf_hi(pw.x); v0[2] = fast_sigmoid(rs * v0[2]) * bf_lo(pw.y); v0[3] = fast_sigmoid(rs * v0[3]) * bf_hi(pw.y);
;                     v1[0] = fast_sigmoid(rs * v1[0]) * bf_lo(pw.z); v1[1] = fast_sigmoid(rs * v1[1]) * bf_hi(pw.z); v1[2] = fast_sigmoid(rs * v1[2]) * bf_lo(pw.w); v1[3] = fast_sigmoid(rs * v1[3]) * bf_hi(pw.w); }
;                 f32x4 h0, h1;
;                 if (IN16) { const u32x4 hw = hraw[sc][bj]; h0 = (f32x4){bf_lo(hw.x), bf_hi(hw.x), bf_lo(hw.y), bf_hi(hw.y)}; h1 = (f32x4){bf_lo(hw.z), bf_hi(hw.z), bf_lo(hw.w), bf_hi(hw.w)}; }
;                 else { h0 = hbuf[sc][2 * bj]; h1 = hbuf[sc][2 * bj + 1]; }
;                 const f32x4 o0 = h0 + v0, o1 = h1 + v1;
;                 if (OUT32) { *(f32x4*)(hout + off) = o0; *(f32x4*)(hout + off + 4) = o1; }
;                 if (hb) { u32x4 w; w.x = pk_bf16(o0[0], o0[1]); w.y = pk_bf16(o0[2], o0[3]); w.z = pk_bf16(o1[0], o1[1]); w.w = pk_bf16(o1[2], o1[3]); *(u32x4*)(hb + off) = w; }
;                 sq += ((o0[0] * o0[0] + o0[1] * o0[1]) + (o0[2] * o0[2] + o0[3] * o0[3])) + ((o1[0] * o1[0] + o1[1] * o1[1]) + (o1[2] * o1[2] + o1[3] * o1[3])); }
	v_and_b32_e32 v73, 0xffff0000, v116
	v_add_f32_e32 v70, 1.0, v70
	v_add_f32_e32 v71, 1.0, v71
	v_rcp_f32_e32 v116, v64
	v_add_f32_e32 v64, 1.0, v65
	v_rcp_f32_e32 v68, v68
	v_rcp_f32_e32 v69, v69
	v_rcp_f32_e32 v70, v70
	v_rcp_f32_e32 v71, v71
	v_lshlrev_b32_e32 v74, 16, v117
	v_and_b32_e32 v75, 0xffff0000, v117
	v_rcp_f32_e32 v117, v64
	v_lshlrev_b32_e32 v78, 16, v118
	v_and_b32_e32 v79, 0xffff0000, v118
	v_lshlrev_b32_e32 v118, 16, v119
	v_and_b32_e32 v119, 0xffff0000, v119
	v_lshlrev_b32_e32 v64, 16, v112
	v_and_b32_e32 v65, 0xffff0000, v112
	v_lshlrev_b32_e32 v66, 16, v113
	v_and_b32_e32 v67, 0xffff0000, v113
	v_lshlrev_b32_e32 v112, 16, v114
	v_and_b32_e32 v113, 0xffff0000, v114
	v_lshlrev_b32_e32 v114, 16, v115
	v_and_b32_e32 v115, 0xffff0000, v115
	v_pk_fma_f32 v[66:67], v[70:71], v[74:75], v[66:67]
	v_pk_fma_f32 v[64:65], v[68:69], v[72:73], v[64:65]
	v_pk_fma_f32 v[70:71], v[116:117], v[118:119], v[114:115]
	v_pk_fma_f32 v[68:69], v[76:77], v[78:79], v[112:113]
	global_store_dwordx4 v[120:121], v[64:67], off offset:512
	global_store_dwordx4 v[120:121], v[68:71], off offset:528
	v_add_u32_e32 v114, 0xa0, v178
	v_ashrrev_i32_e32 v115, 31, v114
	v_cvt_f32_u32_e32 v70, v155
	v_lshlrev_b64 v[64:65], 11, v[114:115]
	v_lshl_add_u64 v[114:115], v[114:115], 2, s[8:9]
	v_mul_f32_e32 v70, 0x3b800000, v70
	v_fmamk_f32 v70, v70, 0x3a000000, v196
	v_rsq_f32_e32 v122, v70
	global_load_dword v123, v[114:115], off
	v_lshl_add_u64 v[112:113], v[64:65], 0, v[176:177]
	v_lshlrev_b64 v[68:69], 1, v[112:113]
	v_mul_f32_e32 v56, v56, v122
	v_mul_f32_e32 v56, 0xbfb8aa3b, v56
	v_mul_f32_e32 v57, v57, v122
	v_exp_f32_e32 v56, v56
	v_mul_f32_e32 v57, 0xbfb8aa3b, v57
	v_exp_f32_e32 v57, v57
	v_mul_f32_e32 v60, v60, v122
	v_add_f32_e32 v56, 1.0, v56
	v_rcp_f32_e32 v116, v56
	v_add_f32_e32 v56, 1.0, v57
	v_rcp_f32_e32 v117, v56
	v_mul_f32_e32 v56, v58, v122
	v_mul_f32_e32 v61, v61, v122
	v_mul_f32_e32 v62, v62, v122
	v_mul_f32_e32 v63, v63, v122
	v_mul_f32_e32 v56, 0xbfb8aa3b, v56
	v_mul_f32_e32 v57, v59, v122
	v_mul_f32_e32 v60, 0xbfb8aa3b, v60
	v_mul_f32_e32 v61, 0xbfb8aa3b, v61
	v_mul_f32_e32 v62, 0xbfb8aa3b, v62
	v_mul_f32_e32 v63, 0xbfb8aa3b, v63
	v_exp_f32_e32 v56, v56
	v_mul_f32_e32 v57, 0xbfb8aa3b, v57
	v_exp_f32_e32 v60, v60
	v_exp_f32_e32 v61, v61
	v_exp_f32_e32 v62, v62
	v_exp_f32_e32 v63, v63
	v_exp_f32_e32 v57, v57
	v_add_f32_e32 v56, 1.0, v56
	v_mul_f32_e32 v48, v48, v122
	v_add_f32_e32 v60, 1.0, v60
	v_add_f32_e32 v61, 1.0, v61
	v_add_f32_e32 v62, 1.0, v62
	v_add_f32_e32 v63, 1.0, v63
	v_rcp_f32_e32 v120, v56
	v_add_f32_e32 v56, 1.0, v57
	v_mul_f32_e32 v48, 0xbfb8aa3b, v48
	v_mul_f32_e32 v49, v49, v122
	v_rcp_f32_e32 v60, v60
	v_rcp_f32_e32 v61, v61
	v_rcp_f32_e32 v62, v62
	v_rcp_f32_e32 v63, v63
	v_rcp_f32_e32 v121, v56
	v_exp_f32_e32 v48, v48
	v_mul_f32_e32 v49, 0xbfb8aa3b, v49
	v_exp_f32_e32 v49, v49
	v_lshl_add_u64 v[64:65], s[6:7], 0, v[68:69]
	global_load_dwordx4 v[72:75], v[64:65], off
	v_lshl_add_u64 v[64:65], s[10:11], 0, v[68:69]
	v_or_b32_e32 v68, 0x100, v68
	v_lshlrev_b32_e32 v114, 16, v108
	v_and_b32_e32 v115, 0xffff0000, v108
	v_lshlrev_b32_e32 v108, 16, v109
	v_and_b32_e32 v109, 0xffff0000, v109
	v_lshlrev_b32_e32 v118, 16, v110
	v_and_b32_e32 v119, 0xffff0000, v110
	v_lshlrev_b32_e32 v110, 16, v111
	v_and_b32_e32 v111, 0xffff0000, v111
	v_lshlrev_b32_e32 v56, 16, v104
	v_and_b32_e32 v57, 0xffff0000, v104
	v_lshlrev_b32_e32 v58, 16, v105
	v_and_b32_e32 v59, 0xffff0000, v105
	v_lshlrev_b32_e32 v104, 16, v106
	v_and_b32_e32 v105, 0xffff0000, v106
	v_lshlrev_b32_e32 v106, 16, v107
	v_and_b32_e32 v107, 0xffff0000, v107
	global_load_dwordx4 v[76:79], v[64:65], off
	v_lshl_add_u64 v[64:65], s[6:7], 0, v[68:69]
	v_lshl_add_u64 v[68:69], s[10:11], 0, v[68:69]
	v_pk_fma_f32 v[58:59], v[62:63], v[108:109], v[58:59]
	v_pk_fma_f32 v[56:57], v[60:61], v[114:115], v[56:57]
	v_pk_fma_f32 v[62:63], v[120:121], v[110:111], v[106:107]
	v_pk_fma_f32 v[60:61], v[116:117], v[118:119], v[104:105]
	v_lshl_add_u64 v[104:105], v[144:145], 2, s[4:5]
	v_add_f32_e32 v48, 1.0, v48
	global_load_dwordx4 v[64:67], v[64:65], off
	v_mul_f32_e32 v52, v52, v122
	global_load_dwordx4 v[68:71], v[68:69], off
	global_store_dwordx4 v[104:105], v[60:63], off offset:16
	v_mul_f32_e32 v53, v53, v122
	v_mul_f32_e32 v54, v54, v122
	v_rcp_f32_e32 v60, v48
	v_add_f32_e32 v48, 1.0, v49
	v_rcp_f32_e32 v61, v48
	v_mul_f32_e32 v48, v50, v122
	v_mul_f32_e32 v55, v55, v122
	v_mul_f32_e32 v48, 0xbfb8aa3b, v48
	v_mul_f32_e32 v49, v51, v122
	v_mul_f32_e32 v52, 0xbfb8aa3b, v52
	v_mul_f32_e32 v53, 0xbfb8aa3b, v53
	v_mul_f32_e32 v54, 0xbfb8aa3b, v54
	v_mul_f32_e32 v55, 0xbfb8aa3b, v55
	v_exp_f32_e32 v48, v48
	v_mul_f32_e32 v49, 0xbfb8aa3b, v49
	v_exp_f32_e32 v52, v52
	v_exp_f32_e32 v53, v53
	v_exp_f32_e32 v54, v54
	v_exp_f32_e32 v55, v55
	v_exp_f32_e32 v49, v49
	v_add_f32_e32 v48, 1.0, v48
	global_store_dwordx4 v[104:105], v[56:59], off
	v_add_f32_e32 v52, 1.0, v52
	v_add_f32_e32 v53, 1.0, v53
	v_lshlrev_b32_e32 v56, 16, v100
	v_and_b32_e32 v57, 0xffff0000, v100
	v_add_f32_e32 v54, 1.0, v54
	v_add_f32_e32 v55, 1.0, v55
	v_rcp_f32_e32 v100, v48
	v_add_f32_e32 v48, 1.0, v49
	v_rcp_f32_e32 v52, v52
	v_rcp_f32_e32 v53, v53
	v_rcp_f32_e32 v54, v54
	v_rcp_f32_e32 v55, v55
	v_lshlrev_b32_e32 v58, 16, v101
	v_and_b32_e32 v59, 0xffff0000, v101
	v_rcp_f32_e32 v101, v48
	v_lshlrev_b32_e32 v62, 16, v102
	v_and_b32_e32 v63, 0xffff0000, v102
	v_lshlrev_b32_e32 v102, 16, v103
	v_and_b32_e32 v103, 0xffff0000, v103
	v_lshlrev_b32_e32 v48, 16, v96
	v_and_b32_e32 v49, 0xffff0000, v96
	v_lshlrev_b32_e32 v50, 16, v97
	v_and_b32_e32 v51, 0xffff0000, v97
	v_lshlrev_b32_e32 v96, 16, v98
	v_and_b32_e32 v97, 0xffff0000, v98
	v_lshlrev_b32_e32 v98, 16, v99
	v_and_b32_e32 v99, 0xffff0000, v99
	v_pk_fma_f32 v[50:51], v[54:55], v[58:59], v[50:51]
	v_pk_fma_f32 v[48:49], v[52:53], v[56:57], v[48:49]
	v_pk_fma_f32 v[54:55], v[100:101], v[102:103], v[98:99]
	v_add_u32_e32 v98, 0xb0, v178
	v_pk_fma_f32 v[52:53], v[60:61], v[62:63], v[96:97]
	global_store_dwordx4 v[104:105], v[48:51], off offset:512
	global_store_dwordx4 v[104:105], v[52:55], off offset:528
	v_ashrrev_i32_e32 v99, 31, v98
	v_lshlrev_b64 v[48:49], 11, v[98:99]
	v_lshl_add_u64 v[98:99], v[98:99], 2, s[8:9]
	global_load_dword v107, v[98:99], off
	s_waitcnt vmcnt(0)
; __device__ __forceinline__ float bf_lo(unsigned w) { return __uint_as_float(w << 16); }
; __device__ __forceinline__ float bf_hi(unsigned w) { return __uint_as_float(w & 0xffff0000u); }
; __device__ __forceinline__ float fast_sigmoid(float x) { return __builtin_amdgcn_rcpf(1.0f + __builtin_amdgcn_exp2f(-x * LOG2E)); }
; __device__ __forceinline__ float ss_fix(float raw) { return (float)__float_as_uint(raw) * (1.0f / 256.0f); }
;     __device__ __forceinline__ void operator()(const f32x4 (&acc)[2][2][4][2], const Unit& u, int wr, int wc, int fr, int fq) const {
;     ...
;             const int row = row0 + ai * HALF + m * 16; const size_t ro = (size_t)row * DM + col0;
;             float rs = 1.0f; if (MODE == 1) rs = __builtin_amdgcn_rsqf(ss_fix(rsb[sc]) * (1.0f / DM) + EPS);
;             float sq = 0.f;
; #pragma unroll
;             for (int bj = 0; bj < 2; ++bj) { const size_t off = ro + bj * HALF;
;                 f32x4 v0 = acc[ai][bj][m][0], v1 = acc[ai][bj][m][1];
;                 if (MODE == 1) { const u32x4 pw = pbuf[sc][bj];
;                     v0[0] = fast_sigmoid(rs * v0[0]) * bf_lo(pw.x); v0[1] = fast_sigmoid(rs * v0[1]) * bf_hi(pw.x); v0[2] = fast_sigmoid(rs * v0[2]) * bf_lo(pw.y); v0[3] = fast_sigmoid(rs * v0[3]) * bf_hi(pw.y);
;                     v1[0] = fast_sigmoid(rs * v1[0]) * bf_lo(pw.z); v1[1] = fast_sigmoid(rs * v1[1]) * bf_hi(pw.z); v1[2] = fast_sigmoid(rs * v1[2]) * bf_lo(pw.w); v1[3] = fast_sigmoid(rs * v1[3]) * bf_hi(pw.w); }
;                 f32x4 h0, h1;
;                 if (IN16) { const u32x4 hw = hraw[sc][bj]; h0 = (f32x4){bf_lo(hw.x), bf_hi(hw.x), bf_lo(hw.y), bf_hi(hw.y)}; h1 = (f32x4){bf_lo(hw.z), bf_hi(hw.z), bf_lo(hw.w), bf_hi(hw.w)}; }
;                 else { h0 = hbuf[sc][2 * bj]; h1 = hbuf[sc][2 * bj + 1]; }
;                 const f32x4 o0 = h0 + v0, o1 = h1 + v1;
;                 if (OUT32) { *(f32x4*)(hout + off) = o0; *(f32x4*)(hout + off + 4) = o1; }
;                 if (hb) { u32x4 w; w.x = pk_bf16(o0[0], o0[1]); w.y = pk_bf16(o0[2], o0[3]); w.z = pk_bf16(o1[0], o1[1]); w.w = pk_bf16(o1[2], o1[3]); *(u32x4*)(hb + off) = w; }
;                 sq += ((o0[0] * o0[0] + o0[1] * o0[1]) + (o0[2] * o0[2] + o0[3] * o0[3])) + ((o1[0] * o1[0] + o1[1] * o1[1]) + (o1[2] * o1[2] + o1[3] * o1[3])); }
	v_cvt_f32_u32_e32 v54, v139
	v_lshl_add_u64 v[96:97], v[48:49], 0, v[176:177]
	v_lshlrev_b64 v[52:53], 1, v[96:97]
	v_lshl_add_u64 v[48:49], s[6:7], 0, v[52:53]
	v_mul_f32_e32 v54, 0x3b800000, v54
	v_fmamk_f32 v54, v54, 0x3a000000, v196
	v_rsq_f32_e32 v106, v54
	global_load_dwordx4 v[56:59], v[48:49], off
	v_lshl_add_u64 v[48:49], s[10:11], 0, v[52:53]
	global_load_dwordx4 v[60:63], v[48:49], off
	v_mul_f32_e32 v40, v40, v106
	v_mul_f32_e32 v40, 0xbfb8aa3b, v40
	v_mul_f32_e32 v41, v41, v106
	v_exp_f32_e32 v40, v40
	v_mul_f32_e32 v41, 0xbfb8aa3b, v41
	v_exp_f32_e32 v41, v41
	v_mul_f32_e32 v44, v44, v106
	v_add_f32_e32 v40, 1.0, v40
	v_mul_f32_e32 v45, v45, v106
	v_rcp_f32_e32 v100, v40
	v_add_f32_e32 v40, 1.0, v41
	v_mul_f32_e32 v44, 0xbfb8aa3b, v44
	v_mul_f32_e32 v45, 0xbfb8aa3b, v45
	v_rcp_f32_e32 v101, v40
	v_mul_f32_e32 v40, v42, v106
	v_exp_f32_e32 v44, v44
	v_exp_f32_e32 v45, v45
	v_mul_f32_e32 v46, v46, v106
	v_mul_f32_e32 v47, v47, v106
	v_mul_f32_e32 v40, 0xbfb8aa3b, v40
	v_mul_f32_e32 v41, v43, v106
	v_mul_f32_e32 v46, 0xbfb8aa3b, v46
	v_mul_f32_e32 v47, 0xbfb8aa3b, v47
	v_exp_f32_e32 v40, v40
	v_mul_f32_e32 v41, 0xbfb8aa3b, v41
	v_exp_f32_e32 v46, v46
	v_exp_f32_e32 v47, v47
	v_exp_f32_e32 v41, v41
	v_add_f32_e32 v44, 1.0, v44
	v_add_f32_e32 v45, 1.0, v45
	v_rcp_f32_e32 v44, v44
	v_rcp_f32_e32 v45, v45
	v_add_f32_e32 v40, 1.0, v40
	v_mul_f32_e32 v32, v32, v106
	v_add_f32_e32 v46, 1.0, v46
	v_add_f32_e32 v47, 1.0, v47
	v_rcp_f32_e32 v104, v40
	v_add_f32_e32 v40, 1.0, v41
	v_mul_f32_e32 v32, 0xbfb8aa3b, v32
	v_mul_f32_e32 v33, v33, v106
	v_rcp_f32_e32 v46, v46
	v_rcp_f32_e32 v47, v47
	v_rcp_f32_e32 v105, v40
	v_mul_f32_e32 v38, v38, v106
	v_mul_f32_e32 v39, v39, v106
	v_exp_f32_e32 v32, v32
	v_mul_f32_e32 v33, 0xbfb8aa3b, v33
	v_lshlrev_b32_e32 v98, 16, v92
	v_and_b32_e32 v99, 0xffff0000, v92
	v_lshlrev_b32_e32 v102, 16, v94
	v_and_b32_e32 v103, 0xffff0000, v94
	v_lshlrev_b32_e32 v40, 16, v88
	v_and_b32_e32 v41, 0xffff0000, v88
	v_lshlrev_b32_e32 v42, 16, v89
	v_and_b32_e32 v43, 0xffff0000, v89
	v_lshlrev_b32_e32 v88, 16, v90
	v_and_b32_e32 v89, 0xffff0000, v90
	v_mul_f32_e32 v38, 0xbfb8aa3b, v38
	v_mul_f32_e32 v39, 0xbfb8aa3b, v39
	v_exp_f32_e32 v33, v33
	v_pk_fma_f32 v[40:41], v[44:45], v[98:99], v[40:41]
	v_pk_fma_f32 v[44:45], v[100:101], v[102:103], v[88:89]
	v_lshlrev_b64 v[88:89], 13, v[128:129]
	v_exp_f32_e32 v38, v38
	v_exp_f32_e32 v39, v39
	v_or_b32_e32 v52, 0x100, v52
	v_lshlrev_b32_e32 v92, 16, v93
	v_and_b32_e32 v93, 0xffff0000, v93
	v_lshlrev_b32_e32 v94, 16, v95
	v_and_b32_e32 v95, 0xffff0000, v95
	v_lshlrev_b32_e32 v90, 16, v91
	v_and_b32_e32 v91, 0xffff0000, v91
	v_lshl_add_u64 v[88:89], s[4:5], 0, v[88:89]
	v_lshl_add_u64 v[48:49], s[6:7], 0, v[52:53]
	v_lshl_add_u64 v[52:53], s[10:11], 0, v[52:53]
	v_pk_fma_f32 v[42:43], v[46:47], v[92:93], v[42:43]
	v_pk_fma_f32 v[46:47], v[104:105], v[94:95], v[90:91]
	v_lshl_add_u64 v[88:89], v[176:177], 2, v[88:89]
	v_mul_f32_e32 v36, v36, v106
	v_mul_f32_e32 v37, v37, v106
	v_add_f32_e32 v32, 1.0, v32
	global_load_dwordx4 v[48:51], v[48:49], off
	v_mul_f32_e32 v36, 0xbfb8aa3b, v36
	global_load_dwordx4 v[52:55], v[52:53], off
	v_mul_f32_e32 v37, 0xbfb8aa3b, v37
	global_store_dwordx4 v[88:89], v[44:47], off offset:16
	v_exp_f32_e32 v36, v36
	v_exp_f32_e32 v37, v37
	v_rcp_f32_e32 v44, v32
	v_add_f32_e32 v32, 1.0, v33
	v_add_f32_e32 v38, 1.0, v38
	v_add_f32_e32 v39, 1.0, v39
	v_rcp_f32_e32 v45, v32
	v_mul_f32_e32 v32, v34, v106
	v_rcp_f32_e32 v38, v38
	v_rcp_f32_e32 v39, v39
	v_mul_f32_e32 v32, 0xbfb8aa3b, v32
	v_mul_f32_e32 v33, v35, v106
	v_exp_f32_e32 v32, v32
	v_mul_f32_e32 v33, 0xbfb8aa3b, v33
	v_exp_f32_e32 v33, v33
	global_store_dwordx4 v[88:89], v[40:43], off
	v_add_f32_e32 v36, 1.0, v36
	v_add_f32_e32 v37, 1.0, v37
	v_lshlrev_b32_e32 v42, 16, v85
	v_and_b32_e32 v43, 0xffff0000, v85
	v_lshlrev_b32_e32 v34, 16, v81
	v_and_b32_e32 v35, 0xffff0000, v81
	v_rcp_f32_e32 v36, v36
	v_rcp_f32_e32 v37, v37
	v_pk_fma_f32 v[34:35], v[38:39], v[42:43], v[34:35]
	v_cvt_f32_u32_e32 v42, v123
	v_add_f32_e32 v32, 1.0, v32
	v_lshlrev_b32_e32 v40, 16, v84
	v_and_b32_e32 v41, 0xffff0000, v84
	v_rcp_f32_e32 v84, v32
	v_add_f32_e32 v32, 1.0, v33
	v_rcp_f32_e32 v85, v32
	v_lshlrev_b32_e32 v32, 16, v80
	v_and_b32_e32 v33, 0xffff0000, v80
	v_pk_fma_f32 v[32:33], v[36:37], v[40:41], v[32:33]
	v_mul_f32_e32 v40, 0x3b800000, v42
	v_lshlrev_b32_e32 v46, 16, v86
	v_and_b32_e32 v47, 0xffff0000, v86
	v_lshlrev_b32_e32 v80, 16, v82
	v_and_b32_e32 v81, 0xffff0000, v82
	v_fmamk_f32 v40, v40, 0x3a000000, v196
	v_pk_fma_f32 v[36:37], v[44:45], v[46:47], v[80:81]
	v_rsq_f32_e32 v80, v40
	v_lshlrev_b32_e32 v86, 16, v87
	v_and_b32_e32 v87, 0xffff0000, v87
	v_lshlrev_b32_e32 v82, 16, v83
	v_mul_f32_e32 v24, v24, v80
	v_mul_f32_e32 v24, 0xbfb8aa3b, v24
	v_mul_f32_e32 v25, v25, v80
	v_exp_f32_e32 v24, v24
	v_mul_f32_e32 v25, 0xbfb8aa3b, v25
	v_exp_f32_e32 v25, v25
	v_and_b32_e32 v83, 0xffff0000, v83
	v_add_f32_e32 v24, 1.0, v24
	v_pk_fma_f32 v[38:39], v[84:85], v[86:87], v[82:83]
	global_store_dwordx4 v[88:89], v[32:35], off offset:512
	global_store_dwordx4 v[88:89], v[36:39], off offset:528
	v_mul_f32_e32 v28, v28, v80
	v_mul_f32_e32 v29, v29, v80
	v_rcp_f32_e32 v36, v24
	v_add_f32_e32 v24, 1.0, v25
	v_rcp_f32_e32 v37, v24
	v_mul_f32_e32 v24, v26, v80
	v_mul_f32_e32 v30, v30, v80
	v_mul_f32_e32 v31, v31, v80
	v_mul_f32_e32 v24, 0xbfb8aa3b, v24
	v_mul_f32_e32 v25, v27, v80
	v_mul_f32_e32 v28, 0xbfb8aa3b, v28
	v_mul_f32_e32 v29, 0xbfb8aa3b, v29
	v_mul_f32_e32 v30, 0xbfb8aa3b, v30
	v_mul_f32_e32 v31, 0xbfb8aa3b, v31
	v_exp_f32_e32 v24, v24
	v_mul_f32_e32 v25, 0xbfb8aa3b, v25
	v_exp_f32_e32 v28, v28
; __device__ __forceinline__ float bf_lo(unsigned w) { return __uint_as_float(w << 16); }
; __device__ __forceinline__ float bf_hi(unsigned w) { return __uint_as_float(w & 0xffff0000u); }
; __device__ __forceinline__ float fast_sigmoid(float x) { return __builtin_amdgcn_rcpf(1.0f + __builtin_amdgcn_exp2f(-x * LOG2E)); }
; __device__ __forceinline__ float ss_fix(float raw) { return (float)__float_as_uint(raw) * (1.0f / 256.0f); }
;     __device__ __forceinline__ void operator()(const f32x4 (&acc)[2][2][4][2], const Unit& u, int wr, int wc, int fr, int fq) const {
;     ...
;             const int row = row0 + ai * HALF + m * 16; const size_t ro = (size_t)row * DM + col0;
;             float rs = 1.0f; if (MODE == 1) rs = __builtin_amdgcn_rsqf(ss_fix(rsb[sc]) * (1.0f / DM) + EPS);
;             float sq = 0.f;
; #pragma unroll
;             for (int bj = 0; bj < 2; ++bj) { const size_t off = ro + bj * HALF;
;                 f32x4 v0 = acc[ai][bj][m][0], v1 = acc[ai][bj][m][1];
;                 if (MODE == 1) { const u32x4 pw = pbuf[sc][bj];
;                     v0[0] = fast_sigmoid(rs * v0[0]) * bf_lo(pw.x); v0[1] = fast_sigmoid(rs * v0[1]) * bf_hi(pw.x); v0[2] = fast_sigmoid(rs * v0[2]) * bf_lo(pw.y); v0[3] = fast_sigmoid(rs * v0[3]) * bf_hi(pw.y);
;                     v1[0] = fast_sigmoid(rs * v1[0]) * bf_lo(pw.z); v1[1] = fast_sigmoid(rs * v1[1]) * bf_hi(pw.z); v1[2] = fast_sigmoid(rs * v1[2]) * bf_lo(pw.w); v1[3] = fast_sigmoid(rs * v1[3]) * bf_hi(pw.w); }
;                 f32x4 h0, h1;
;                 if (IN16) { const u32x4 hw = hraw[sc][bj]; h0 = (f32x4){bf_lo(hw.x), bf_hi(hw.x), bf_lo(hw.y), bf_hi(hw.y)}; h1 = (f32x4){bf_lo(hw.z), bf_hi(hw.z), bf_lo(hw.w), bf_hi(hw.w)}; }
;                 else { h0 = hbuf[sc][2 * bj]; h1 = hbuf[sc][2 * bj + 1]; }
;                 const f32x4 o0 = h0 + v0, o1 = h1 + v1;
;                 if (OUT32) { *(f32x4*)(hout + off) = o0; *(f32x4*)(hout + off + 4) = o1; }
;                 if (hb) { u32x4 w; w.x = pk_bf16(o0[0], o0[1]); w.y = pk_bf16(o0[2], o0[3]); w.z = pk_bf16(o1[0], o1[1]); w.w = pk_bf16(o1[2], o1[3]); *(u32x4*)(hb + off) = w; }
;                 sq += ((o0[0] * o0[0] + o0[1] * o0[1]) + (o0[2] * o0[2] + o0[3] * o0[3])) + ((o1[0] * o1[0] + o1[1] * o1[1]) + (o1[2] * o1[2] + o1[3] * o1[3])); }
	v_exp_f32_e32 v29, v29
	v_exp_f32_e32 v30, v30
	v_exp_f32_e32 v31, v31
	v_exp_f32_e32 v25, v25
	v_add_f32_e32 v24, 1.0, v24
	v_mul_f32_e32 v16, v16, v80
	v_add_f32_e32 v28, 1.0, v28
	v_add_f32_e32 v29, 1.0, v29
	v_add_f32_e32 v30, 1.0, v30
	v_add_f32_e32 v31, 1.0, v31
	v_rcp_f32_e32 v40, v24
	v_add_f32_e32 v24, 1.0, v25
	v_mul_f32_e32 v16, 0xbfb8aa3b, v16
	v_mul_f32_e32 v17, v17, v80
	v_rcp_f32_e32 v28, v28
	v_rcp_f32_e32 v29, v29
	v_rcp_f32_e32 v30, v30
	v_rcp_f32_e32 v31, v31
	v_rcp_f32_e32 v41, v24
	v_exp_f32_e32 v16, v16
	v_mul_f32_e32 v17, 0xbfb8aa3b, v17
	v_mul_f32_e32 v22, v22, v80
	v_mul_f32_e32 v23, v23, v80
	v_exp_f32_e32 v17, v17
	v_mul_f32_e32 v22, 0xbfb8aa3b, v22
	v_mul_f32_e32 v23, 0xbfb8aa3b, v23
	v_lshlrev_b32_e32 v32, 16, v76
	v_and_b32_e32 v33, 0xffff0000, v76
	v_lshlrev_b32_e32 v34, 16, v77
	v_and_b32_e32 v35, 0xffff0000, v77
	v_lshlrev_b32_e32 v38, 16, v78
	v_and_b32_e32 v39, 0xffff0000, v78
	v_lshlrev_b32_e32 v42, 16, v79
	v_and_b32_e32 v43, 0xffff0000, v79
	v_lshlrev_b32_e32 v24, 16, v72
	v_and_b32_e32 v25, 0xffff0000, v72
	v_lshlrev_b32_e32 v26, 16, v73
	v_and_b32_e32 v27, 0xffff0000, v73
	v_lshlrev_b32_e32 v44, 16, v74
	v_and_b32_e32 v45, 0xffff0000, v74
	v_lshlrev_b32_e32 v46, 16, v75
	v_and_b32_e32 v47, 0xffff0000, v75
	v_exp_f32_e32 v22, v22
	v_exp_f32_e32 v23, v23
	v_pk_fma_f32 v[26:27], v[30:31], v[34:35], v[26:27]
	v_pk_fma_f32 v[24:25], v[28:29], v[32:33], v[24:25]
	v_pk_fma_f32 v[30:31], v[40:41], v[42:43], v[46:47]
	v_pk_fma_f32 v[28:29], v[36:37], v[38:39], v[44:45]
	v_lshl_add_u64 v[32:33], v[112:113], 2, s[4:5]
	v_add_f32_e32 v16, 1.0, v16
	v_mul_f32_e32 v20, v20, v80
	v_mul_f32_e32 v21, v21, v80
	global_store_dwordx4 v[32:33], v[28:31], off offset:16
	v_mul_f32_e32 v20, 0xbfb8aa3b, v20
	v_mul_f32_e32 v21, 0xbfb8aa3b, v21
	v_rcp_f32_e32 v28, v16
	v_add_f32_e32 v16, 1.0, v17
	v_rcp_f32_e32 v29, v16
	v_mul_f32_e32 v16, v18, v80
	v_exp_f32_e32 v20, v20
	v_exp_f32_e32 v21, v21
	v_add_f32_e32 v22, 1.0, v22
	v_add_f32_e32 v23, 1.0, v23
	v_mul_f32_e32 v16, 0xbfb8aa3b, v16
	v_mul_f32_e32 v17, v19, v80
	v_rcp_f32_e32 v22, v22
	v_rcp_f32_e32 v23, v23
	v_exp_f32_e32 v16, v16
	v_mul_f32_e32 v17, 0xbfb8aa3b, v17
	v_exp_f32_e32 v17, v17
	global_store_dwordx4 v[32:33], v[24:27], off
	v_add_f32_e32 v20, 1.0, v20
	v_add_f32_e32 v21, 1.0, v21
	v_lshlrev_b32_e32 v26, 16, v69
	v_and_b32_e32 v27, 0xffff0000, v69
	v_lshlrev_b32_e32 v18, 16, v65
	v_and_b32_e32 v19, 0xffff0000, v65
	v_rcp_f32_e32 v20, v20
	v_rcp_f32_e32 v21, v21
	v_add_f32_e32 v16, 1.0, v16
	v_pk_fma_f32 v[18:19], v[22:23], v[26:27], v[18:19]
	v_cvt_f32_u32_e32 v26, v107
	v_rcp_f32_e32 v34, v16
	v_add_f32_e32 v16, 1.0, v17
	v_rcp_f32_e32 v35, v16
	v_lshlrev_b32_e32 v24, 16, v68
	v_and_b32_e32 v25, 0xffff0000, v68
	v_lshlrev_b32_e32 v16, 16, v64
	v_and_b32_e32 v17, 0xffff0000, v64
	v_pk_fma_f32 v[16:17], v[20:21], v[24:25], v[16:17]
	v_mul_f32_e32 v24, 0x3b800000, v26
	v_lshlrev_b32_e32 v36, 16, v71
	v_and_b32_e32 v37, 0xffff0000, v71
	v_lshlrev_b32_e32 v40, 16, v67
	v_and_b32_e32 v41, 0xffff0000, v67
	v_fmamk_f32 v24, v24, 0x3a000000, v196
	v_pk_fma_f32 v[22:23], v[34:35], v[36:37], v[40:41]
	v_rsq_f32_e32 v34, v24
	v_lshlrev_b32_e32 v30, 16, v70
	v_and_b32_e32 v31, 0xffff0000, v70
	v_lshlrev_b32_e32 v38, 16, v66
	v_mul_f32_e32 v8, v8, v34
	v_mul_f32_e32 v8, 0xbfb8aa3b, v8
	v_mul_f32_e32 v9, v9, v34
	v_exp_f32_e32 v8, v8
	v_mul_f32_e32 v9, 0xbfb8aa3b, v9
	v_exp_f32_e32 v9, v9
	v_and_b32_e32 v39, 0xffff0000, v66
	v_pk_fma_f32 v[20:21], v[28:29], v[30:31], v[38:39]
	v_add_f32_e32 v8, 1.0, v8
	global_store_dwordx4 v[32:33], v[16:19], off offset:512
	global_store_dwordx4 v[32:33], v[20:23], off offset:528
	v_mul_f32_e32 v12, v12, v34
	v_mul_f32_e32 v13, v13, v34
	v_rcp_f32_e32 v20, v8
	v_add_f32_e32 v8, 1.0, v9
	v_rcp_f32_e32 v21, v8
	v_mul_f32_e32 v8, v10, v34
	v_mul_f32_e32 v14, v14, v34
	v_mul_f32_e32 v15, v15, v34
	v_mul_f32_e32 v8, 0xbfb8aa3b, v8
	v_mul_f32_e32 v9, v11, v34
	v_mul_f32_e32 v12, 0xbfb8aa3b, v12
	v_mul_f32_e32 v13, 0xbfb8aa3b, v13
	v_mul_f32_e32 v14, 0xbfb8aa3b, v14
	v_mul_f32_e32 v15, 0xbfb8aa3b, v15
	v_exp_f32_e32 v8, v8
	v_mul_f32_e32 v9, 0xbfb8aa3b, v9
	v_exp_f32_e32 v12, v12
	v_exp_f32_e32 v13, v13
	v_exp_f32_e32 v14, v14
	v_exp_f32_e32 v15, v15
	v_exp_f32_e32 v9, v9
	v_add_f32_e32 v8, 1.0, v8
	v_mul_f32_e32 v0, v0, v34
	v_add_f32_e32 v12, 1.0, v12
	v_add_f32_e32 v13, 1.0, v13
	v_add_f32_e32 v14, 1.0, v14
	v_add_f32_e32 v15, 1.0, v15
	v_rcp_f32_e32 v24, v8
	v_add_f32_e32 v8, 1.0, v9
	v_mul_f32_e32 v0, 0xbfb8aa3b, v0
	v_mul_f32_e32 v1, v1, v34
	v_rcp_f32_e32 v12, v12
	v_rcp_f32_e32 v13, v13
	v_rcp_f32_e32 v14, v14
	v_rcp_f32_e32 v15, v15
	v_rcp_f32_e32 v25, v8
	v_exp_f32_e32 v0, v0
	v_mul_f32_e32 v1, 0xbfb8aa3b, v1
	v_exp_f32_e32 v1, v1
	s_waitcnt vmcnt(0)
; __device__ __forceinline__ float bf_lo(unsigned w) { return __uint_as_float(w << 16); }
; #define PG8_BAR __builtin_amdgcn_s_barrier()
; template <class Epi>
; __device__ __forceinline__ void gemm_phase(LAS unsigned char* lds, const Gemm g, const StaticOrder& S, const Epi& E, int wv) {
;     ...
;     PG8_WAIT_V(0);
;     if (wr == 0) PG8_BAR;
;     PG8_BAR;
;     __device__ __forceinline__ void operator()(const f32x4 (&acc)[2][2][4][2], const Unit& u, int wr, int wc, int fr, int fq) const {
;     ...
;             const int row = row0 + ai * HALF + m * 16; const size_t ro = (size_t)row * DM + col0;
;             float rs = 1.0f; if (MODE == 1) rs = __builtin_amdgcn_rsqf(ss_fix(rsb[sc]) * (1.0f / DM) + EPS);
;             float sq = 0.f;
; #pragma unroll
;             for (int bj = 0; bj < 2; ++bj) { const size_t off = ro + bj * HALF;
;                 f32x4 v0 = acc[ai][bj][m][0], v1 = acc[ai][bj][m][1];
;                 if (MODE == 1) { const u32x4 pw = pbuf[sc][bj];
;                     v0[0] = fast_sigmoid(rs * v0[0]) * bf_lo(pw.x); v0[1] = fast_sigmoid(rs * v0[1]) * bf_hi(pw.x); v0[2] = fast_sigmoid(rs * v0[2]) * bf_lo(pw.y); v0[3] = fast_sigmoid(rs * v0[3]) * bf_hi(pw.y);
;                     v1[0] = fast_sigmoid(rs * v1[0]) * bf_lo(pw.z); v1[1] = fast_sigmoid(rs * v1[1]) * bf_hi(pw.z); v1[2] = fast_sigmoid(rs * v1[2]) * bf_lo(pw.w); v1[3] = fast_sigmoid(rs * v1[3]) * bf_hi(pw.w); }
;                 f32x4 h0, h1;
;                 if (IN16) { const u32x4 hw = hraw[sc][bj]; h0 = (f32x4){bf_lo(hw.x), bf_hi(hw.x), bf_lo(hw.y), bf_hi(hw.y)}; h1 = (f32x4){bf_lo(hw.z), bf_hi(hw.z), bf_lo(hw.w), bf_hi(hw.w)}; }
;                 else { h0 = hbuf[sc][2 * bj]; h1 = hbuf[sc][2 * bj + 1]; }
;                 const f32x4 o0 = h0 + v0, o1 = h1 + v1;
;                 if (OUT32) { *(f32x4*)(hout + off) = o0; *(f32x4*)(hout + off + 4) = o1; }
;                 if (hb) { u32x4 w; w.x = pk_bf16(o0[0], o0[1]); w.y = pk_bf16(o0[2], o0[3]); w.z = pk_bf16(o1[0], o1[1]); w.w = pk_bf16(o1[2], o1[3]); *(u32x4*)(hb + off) = w; }
;                 sq += ((o0[0] * o0[0] + o0[1] * o0[1]) + (o0[2] * o0[2] + o0[3] * o0[3])) + ((o1[0] * o1[0] + o1[1] * o1[1]) + (o1[2] * o1[2] + o1[3] * o1[3])); }
;             if (ss_out) { sq += __shfl_xor(sq, 16); sq += __shfl_xor(sq, 32); if (fq == 0) atomicAdd((unsigned*)(ss_out + row), ss_enc(sq)); }
;             asm volatile("" ::: "memory"); }
	v_lshlrev_b32_e32 v16, 16, v60
	v_and_b32_e32 v17, 0xffff0000, v60
	v_lshlrev_b32_e32 v18, 16, v61
	v_and_b32_e32 v19, 0xffff0000, v61
	v_lshlrev_b32_e32 v22, 16, v62
	v_and_b32_e32 v23, 0xffff0000, v62
	v_lshlrev_b32_e32 v26, 16, v63
	v_and_b32_e32 v27, 0xffff0000, v63
	v_lshlrev_b32_e32 v8, 16, v56
	v_and_b32_e32 v9, 0xffff0000, v56
	v_lshlrev_b32_e32 v10, 16, v57
	v_and_b32_e32 v11, 0xffff0000, v57
	v_lshlrev_b32_e32 v28, 16, v58
	v_and_b32_e32 v29, 0xffff0000, v58
	v_lshlrev_b32_e32 v30, 16, v59
	v_and_b32_e32 v31, 0xffff0000, v59
	v_pk_fma_f32 v[10:11], v[14:15], v[18:19], v[10:11]
	v_pk_fma_f32 v[8:9], v[12:13], v[16:17], v[8:9]
	v_pk_fma_f32 v[14:15], v[24:25], v[26:27], v[30:31]
	v_pk_fma_f32 v[12:13], v[20:21], v[22:23], v[28:29]
	v_lshl_add_u64 v[16:17], v[96:97], 2, s[4:5]
	v_add_f32_e32 v0, 1.0, v0
	global_store_dwordx4 v[16:17], v[12:15], off offset:16
	v_mul_f32_e32 v4, v4, v34
	v_mul_f32_e32 v5, v5, v34
	v_rcp_f32_e32 v12, v0
	v_add_f32_e32 v0, 1.0, v1
	v_mul_f32_e32 v6, v6, v34
	v_mul_f32_e32 v7, v7, v34
	v_rcp_f32_e32 v13, v0
	v_mul_f32_e32 v0, v2, v34
	v_mul_f32_e32 v4, 0xbfb8aa3b, v4
	v_mul_f32_e32 v5, 0xbfb8aa3b, v5
	v_mul_f32_e32 v6, 0xbfb8aa3b, v6
	v_mul_f32_e32 v7, 0xbfb8aa3b, v7
	v_mul_f32_e32 v0, 0xbfb8aa3b, v0
	v_mul_f32_e32 v1, v3, v34
	v_exp_f32_e32 v4, v4
	v_exp_f32_e32 v5, v5
	v_exp_f32_e32 v6, v6
	v_exp_f32_e32 v7, v7
	v_exp_f32_e32 v0, v0
	v_mul_f32_e32 v1, 0xbfb8aa3b, v1
	v_exp_f32_e32 v1, v1
	v_add_f32_e32 v4, 1.0, v4
	v_add_f32_e32 v5, 1.0, v5
	v_add_f32_e32 v6, 1.0, v6
	v_add_f32_e32 v7, 1.0, v7
	v_add_f32_e32 v0, 1.0, v0
	v_rcp_f32_e32 v4, v4
	v_rcp_f32_e32 v5, v5
	v_rcp_f32_e32 v6, v6
	v_rcp_f32_e32 v7, v7
	v_rcp_f32_e32 v18, v0
	v_add_f32_e32 v0, 1.0, v1
	v_rcp_f32_e32 v19, v0
	global_store_dwordx4 v[16:17], v[8:11], off
	v_lshlrev_b32_e32 v0, 16, v48
	v_and_b32_e32 v1, 0xffff0000, v48
	v_lshlrev_b32_e32 v8, 16, v52
	v_and_b32_e32 v9, 0xffff0000, v52
	v_lshlrev_b32_e32 v10, 16, v53
	v_and_b32_e32 v11, 0xffff0000, v53
	v_lshlrev_b32_e32 v2, 16, v49
	v_and_b32_e32 v3, 0xffff0000, v49
	v_lshlrev_b32_e32 v14, 16, v54
	v_and_b32_e32 v15, 0xffff0000, v54
	v_lshlrev_b32_e32 v20, 16, v55
	v_and_b32_e32 v21, 0xffff0000, v55
	v_lshlrev_b32_e32 v22, 16, v50
	v_and_b32_e32 v23, 0xffff0000, v50
	v_lshlrev_b32_e32 v24, 16, v51
	v_and_b32_e32 v25, 0xffff0000, v51
	v_pk_fma_f32 v[2:3], v[6:7], v[10:11], v[2:3]
	v_pk_fma_f32 v[0:1], v[4:5], v[8:9], v[0:1]
	v_pk_fma_f32 v[6:7], v[18:19], v[20:21], v[24:25]
	v_pk_fma_f32 v[4:5], v[12:13], v[14:15], v[22:23]
	global_store_dwordx4 v[16:17], v[0:3], off offset:512
	global_store_dwordx4 v[16:17], v[4:7], off offset:528
	s_cbranch_vccz .LBB0_1846
	s_waitcnt vmcnt(0)
	s_cmpk_gt_u32 s33, 0xff
	s_cbranch_scc1 .LBB0_1857
	s_barrier
